# G1: 32 single-lane broadcasts per unit via v_readlane + SGPR operand instead of ds_bpermute round trips (waits re-derived); on top of conv DPP wave_sum
# baseline (speedup 1.0000x reference)
.LBB0_704:
	v_mov_b32_e32 v68, v109
	v_mov_b64_e32 v[2:3], s[8:9]
	v_add_u32_e32 v4, s33, v68
	v_mad_i64_i32 v[70:71], s[0:1], v4, s27, v[2:3]
	s_lshl_b32 s0, s10, 1
	s_mov_b32 s1, s11
	v_lshl_add_u64 v[30:31], v[70:71], 0, s[0:1]
	global_load_dwordx4 v[2:5], v[30:31], off offset:512
	global_load_dwordx4 v[6:9], v[30:31], off offset:528
	global_load_dwordx4 v[10:13], v[30:31], off offset:544
	global_load_dwordx4 v[14:17], v[30:31], off offset:560
	global_load_dwordx4 v[18:21], v[30:31], off offset:576
	global_load_dwordx4 v[22:25], v[30:31], off offset:592
	global_load_dwordx4 v[26:29], v[30:31], off offset:608
	s_nop 0
	global_load_dwordx4 v[30:33], v[30:31], off offset:624
	v_readlane_b32 s40, v239, 33
	global_load_dwordx4 v[34:37], v[70:71], off offset:1568
	s_lshl_b32 s0, s36, 7
	v_readlane_b32 s50, v239, 43
	v_readlane_b32 s51, v239, 44
	v_readlane_b32 s52, v239, 45
	v_readlane_b32 s53, v239, 46
	s_add_u32 s12, s50, s0
	v_mov_b32_e32 v123, s0
	s_addc_u32 s13, s51, 0
	s_nop 1
	global_load_dwordx4 v[38:41], v123, s[52:53]
	global_load_dwordx4 v[42:45], v123, s[50:51]
	global_load_dwordx4 v[46:49], v123, s[50:51] offset:512
	global_load_dwordx4 v[50:53], v123, s[50:51] offset:1024
	global_load_dwordx4 v[54:57], v123, s[50:51] offset:1536
	global_load_dwordx4 v[58:61], v123, s[50:51] offset:2048
	global_load_dwordx4 v[62:65], v123, s[50:51] offset:2560
	global_load_dwordx4 v[74:77], v123, s[50:51] offset:3072
	global_load_dwordx4 v[78:81], v123, s[50:51] offset:3584
	global_load_dwordx4 v[82:85], v110, s[12:13]
	global_load_dwordx4 v[86:89], v110, s[12:13] offset:512
	global_load_dwordx4 v[90:93], v[70:71], off offset:1584
	v_lshl_add_u32 v66, v68, 1, s17
	v_lshl_add_u64 v[70:71], v[70:71], 0, s[10:11]
	v_readlane_b32 s41, v239, 34
	v_readlane_b32 s42, v239, 35
	v_readlane_b32 s43, v239, 36
	v_readlane_b32 s44, v239, 37
	v_readlane_b32 s45, v239, 38
	v_readlane_b32 s46, v239, 39
	v_readlane_b32 s47, v239, 40
	v_readlane_b32 s48, v239, 41
	v_readlane_b32 s49, v239, 42
	v_readlane_b32 s54, v239, 47
	v_readlane_b32 s55, v239, 48
	v_ashrrev_i32_e32 v69, 31, v68
	s_waitcnt vmcnt(20)
	ds_write_b16 v66, v2
	ds_write_b16_d16_hi v66, v2 offset:128
	ds_write_b16 v66, v3 offset:256
	ds_write_b16_d16_hi v66, v3 offset:384
	ds_write_b16 v66, v4 offset:512
	ds_write_b16_d16_hi v66, v4 offset:640
	ds_write_b16 v66, v5 offset:768
	ds_write_b16_d16_hi v66, v5 offset:896
	s_waitcnt vmcnt(19)
	ds_write_b16 v66, v6 offset:1024
	ds_write_b16_d16_hi v66, v6 offset:1152
	ds_write_b16 v66, v7 offset:1280
	ds_write_b16_d16_hi v66, v7 offset:1408
	ds_write_b16 v66, v8 offset:1536
	ds_write_b16_d16_hi v66, v8 offset:1664
	ds_write_b16 v66, v9 offset:1792
	ds_write_b16_d16_hi v66, v9 offset:1920
	s_waitcnt vmcnt(18)
	ds_write_b16 v66, v10 offset:2048
	ds_write_b16_d16_hi v66, v10 offset:2176
	ds_write_b16 v66, v11 offset:2304
	ds_write_b16_d16_hi v66, v11 offset:2432
	ds_write_b16 v66, v12 offset:2560
	ds_write_b16_d16_hi v66, v12 offset:2688
	ds_write_b16 v66, v13 offset:2816
	ds_write_b16_d16_hi v66, v13 offset:2944
	s_waitcnt vmcnt(17)
	ds_write_b16 v66, v14 offset:3072
	ds_write_b16_d16_hi v66, v14 offset:3200
	ds_write_b16 v66, v15 offset:3328
	ds_write_b16_d16_hi v66, v15 offset:3456
	ds_write_b16 v66, v16 offset:3584
	ds_write_b16_d16_hi v66, v16 offset:3712
	ds_write_b16 v66, v17 offset:3840
	ds_write_b16_d16_hi v66, v17 offset:3968
	s_waitcnt vmcnt(16)
	ds_write_b16 v66, v18 offset:4096
	ds_write_b16_d16_hi v66, v18 offset:4224
	ds_write_b16 v66, v19 offset:4352
	ds_write_b16_d16_hi v66, v19 offset:4480
	ds_write_b16 v66, v20 offset:4608
	ds_write_b16_d16_hi v66, v20 offset:4736
	ds_write_b16 v66, v21 offset:4864
	ds_write_b16_d16_hi v66, v21 offset:4992
	s_waitcnt vmcnt(15)
	ds_write_b16 v66, v22 offset:5120
	ds_write_b16_d16_hi v66, v22 offset:5248
	ds_write_b16 v66, v23 offset:5376
	ds_write_b16_d16_hi v66, v23 offset:5504
	ds_write_b16 v66, v24 offset:5632
	ds_write_b16_d16_hi v66, v24 offset:5760
	ds_write_b16 v66, v25 offset:5888
	ds_write_b16_d16_hi v66, v25 offset:6016
	s_waitcnt vmcnt(14)
	ds_write_b16 v66, v26 offset:6144
	ds_write_b16_d16_hi v66, v26 offset:6272
	ds_write_b16 v66, v27 offset:6400
	ds_write_b16_d16_hi v66, v27 offset:6528
	ds_write_b16 v66, v28 offset:6656
	ds_write_b16_d16_hi v66, v28 offset:6784
	ds_write_b16 v66, v29 offset:6912
	ds_write_b16_d16_hi v66, v29 offset:7040
	s_waitcnt vmcnt(13)
	ds_write_b16 v66, v30 offset:7168
	ds_write_b16_d16_hi v66, v30 offset:7296
	ds_write_b16 v66, v31 offset:7424
	ds_write_b16_d16_hi v66, v31 offset:7552
	ds_write_b16 v66, v32 offset:7680
	ds_write_b16_d16_hi v66, v32 offset:7808
	ds_write_b16 v66, v33 offset:7936
	ds_write_b16_d16_hi v66, v33 offset:8064
	global_load_dwordx4 v[18:21], v110, s[12:13] offset:1024
	global_load_dwordx4 v[22:25], v110, s[12:13] offset:1536
	global_load_dwordx4 v[14:17], v[70:71], off offset:256
	global_load_dwordx4 v[10:13], v[70:71], off offset:272
	global_load_dwordx4 v[6:9], v[70:71], off offset:288
	global_load_dwordx4 v[2:5], v[70:71], off offset:304
	global_load_dwordx4 v[26:29], v110, s[12:13] offset:2048
	global_load_dwordx4 v[30:33], v110, s[12:13] offset:2560
	global_load_dwordx4 v[94:97], v110, s[12:13] offset:3072
	global_load_dwordx4 v[98:101], v110, s[12:13] offset:3584
	s_waitcnt vmcnt(22)
	v_lshlrev_b32_e32 v118, 16, v34
	v_and_b32_e32 v117, 0xffff0000, v34
	v_lshlrev_b32_e32 v120, 16, v36
	v_and_b32_e32 v119, 0xffff0000, v36
	s_waitcnt vmcnt(20)
	v_fma_f32 v36, v42, v118, v38
	v_lshlrev_b32_e32 v122, 16, v35
	s_waitcnt vmcnt(19)
	v_fmac_f32_e32 v36, v46, v117
	v_and_b32_e32 v121, 0xffff0000, v35
	s_waitcnt vmcnt(18)
	v_fmac_f32_e32 v36, v50, v122
	v_fma_f32 v38, v43, v118, v39
	s_waitcnt vmcnt(17)
	v_fmac_f32_e32 v36, v54, v121
	v_fmac_f32_e32 v38, v47, v117
	s_waitcnt vmcnt(16)
	v_fmac_f32_e32 v36, v58, v120
	v_fmac_f32_e32 v38, v51, v122
	v_and_b32_e32 v73, 0xffff0000, v37
	v_lshlrev_b32_e32 v72, 16, v37
	s_waitcnt vmcnt(14)
	v_mov_b32_e32 v34, v74
	s_waitcnt vmcnt(13)
	v_mov_b32_e32 v35, v78
	v_fmac_f32_e32 v36, v62, v119
	v_fmac_f32_e32 v38, v55, v121
	v_fma_f32 v39, v44, v118, v40
	v_pk_mul_f32 v[34:35], v[34:35], v[72:73]
	v_fmac_f32_e32 v38, v59, v120
	v_fmac_f32_e32 v39, v48, v117
	v_add_f32_e32 v34, v36, v34
	v_mov_b32_e32 v78, v75
	v_fmac_f32_e32 v38, v63, v119
	v_fmac_f32_e32 v39, v52, v122
	v_fmac_f32_e32 v41, v45, v118
	v_add_f32_e32 v36, v34, v35
	v_pk_mul_f32 v[34:35], v[78:79], v[72:73]
	v_fmac_f32_e32 v39, v56, v121
	v_fmac_f32_e32 v41, v49, v117
	v_add_f32_e32 v34, v34, v38
	v_fmac_f32_e32 v39, v60, v120
	v_fmac_f32_e32 v41, v53, v122
	v_add_f32_e32 v37, v35, v34
	v_mov_b32_e32 v34, v76
	v_mov_b32_e32 v35, v80
	v_fmac_f32_e32 v39, v64, v119
	v_fmac_f32_e32 v41, v57, v121
	v_pk_mul_f32 v[34:35], v[34:35], v[72:73]
	v_fmac_f32_e32 v41, v61, v120
	v_add_f32_e32 v34, v34, v39
	v_mov_b32_e32 v80, v77
	v_fmac_f32_e32 v41, v65, v119
	v_add_f32_e32 v38, v35, v34
	v_pk_mul_f32 v[34:35], v[80:81], v[72:73]
	s_waitcnt vmcnt(10)
	v_and_b32_e32 v75, 0xffff0000, v90
	v_add_f32_e32 v34, v34, v41
	v_add_f32_e32 v39, v35, v34
	v_lshlrev_b32_e32 v74, 16, v90
	v_mov_b32_e32 v34, v82
	v_mov_b32_e32 v35, v86
	v_pk_mul_f32 v[34:35], v[34:35], v[74:75]
	v_mov_b32_e32 v86, v83
	v_add_f32_e32 v34, v36, v34
	v_add_f32_e32 v36, v34, v35
	v_pk_mul_f32 v[34:35], v[86:87], v[74:75]
	v_and_b32_e32 v79, 0xffff0000, v91
	v_add_f32_e32 v34, v34, v37
	v_add_f32_e32 v37, v35, v34
	v_mov_b32_e32 v34, v84
	v_mov_b32_e32 v35, v88
	v_pk_mul_f32 v[34:35], v[34:35], v[74:75]
	v_mov_b32_e32 v88, v85
	v_add_f32_e32 v34, v34, v38
	v_add_f32_e32 v38, v35, v34
	v_pk_mul_f32 v[34:35], v[88:89], v[74:75]
	v_lshlrev_b32_e32 v78, 16, v91
	v_add_f32_e32 v34, v34, v39
	v_add_f32_e32 v39, v35, v34
	v_and_b32_e32 v81, 0xffff0000, v92
	v_lshlrev_b32_e32 v80, 16, v92
	v_and_b32_e32 v83, 0xffff0000, v93
	v_lshlrev_b32_e32 v82, 16, v93
	s_waitcnt vmcnt(9)
	v_mov_b32_e32 v34, v18
	s_waitcnt vmcnt(8)
	v_mov_b32_e32 v35, v22
	v_pk_mul_f32 v[34:35], v[34:35], v[78:79]
	v_mov_b32_e32 v22, v19
	v_add_f32_e32 v18, v36, v34
	v_add_f32_e32 v34, v18, v35
	v_pk_mul_f32 v[18:19], v[22:23], v[78:79]
	s_nop 0
	v_add_f32_e32 v18, v18, v37
	v_add_f32_e32 v22, v19, v18
	v_mov_b32_e32 v18, v20
	v_mov_b32_e32 v19, v24
	v_pk_mul_f32 v[18:19], v[18:19], v[78:79]
	v_mov_b32_e32 v24, v21
	v_add_f32_e32 v18, v18, v38
	v_add_f32_e32 v20, v19, v18
	v_pk_mul_f32 v[18:19], v[24:25], v[78:79]
	s_waitcnt vmcnt(0)
	v_mov_b32_e32 v21, v98
	v_add_f32_e32 v18, v18, v39
	v_add_f32_e32 v23, v19, v18
	v_mov_b32_e32 v18, v26
	v_mov_b32_e32 v19, v30
	v_pk_mul_f32 v[18:19], v[18:19], v[80:81]
	v_mov_b32_e32 v30, v27
	v_add_f32_e32 v18, v34, v18
	v_add_f32_e32 v24, v18, v19
	v_pk_mul_f32 v[18:19], v[30:31], v[80:81]
	v_mov_b32_e32 v98, v95
	v_add_f32_e32 v18, v18, v22
	v_add_f32_e32 v22, v19, v18
	v_mov_b32_e32 v18, v28
	v_mov_b32_e32 v19, v32
	v_pk_mul_f32 v[18:19], v[18:19], v[80:81]
	v_mov_b32_e32 v32, v29
	v_add_f32_e32 v18, v18, v20
	v_mov_b32_e32 v20, v94
	v_pk_mul_f32 v[20:21], v[20:21], v[82:83]
	s_nop 0
	v_add_f32_e32 v20, v24, v20
	v_add_f32_e32 v20, v20, v21
	v_mul_f32_e64 v21, |v20|, s28
	v_exp_f32_e32 v21, v21
	v_add_f32_e32 v24, v19, v18
	v_pk_mul_f32 v[18:19], v[32:33], v[80:81]
	v_add_f32_e32 v21, 1.0, v21
	v_cmp_gt_f32_e32 vcc, s29, v21
	v_add_f32_e32 v18, v18, v23
	v_add_f32_e32 v26, v19, v18
	v_cndmask_b32_e64 v25, 0, 32, vcc
	v_ldexp_f32 v21, v21, v25
	v_log_f32_e32 v25, v21
	v_min_f32_e32 v18, 0, v20
	v_pk_mul_f32 v[20:21], v[98:99], v[82:83]
	v_mov_b32_e32 v23, v100
	v_add_f32_e32 v20, v20, v22
	v_add_f32_e32 v21, v21, v20
	v_mul_f32_e64 v20, |v21|, s28
	v_exp_f32_e32 v20, v20
	v_mul_f32_e32 v19, 0x3f317217, v25
	v_fma_f32 v19, v25, s30, -v19
	v_fmac_f32_e32 v19, 0x3377d1cf, v25
	v_fmac_f32_e32 v19, 0x3f317217, v25
	v_cmp_lt_f32_e64 s[0:1], |v25|, s31
	v_add_f32_e32 v20, 1.0, v20
	v_mov_b32_e32 v100, v97
	v_cndmask_b32_e64 v19, v25, v19, s[0:1]
	v_cmp_gt_f32_e64 s[0:1], s29, v20
	s_nop 1
	v_cndmask_b32_e64 v22, 0, 32, s[0:1]
	v_ldexp_f32 v20, v20, v22
	v_mov_b32_e32 v22, v96
	v_pk_mul_f32 v[22:23], v[22:23], v[82:83]
	v_log_f32_e32 v25, v20
	v_add_f32_e32 v22, v22, v24
	v_add_f32_e32 v22, v23, v22
	v_mul_f32_e64 v23, |v22|, s28
	v_cndmask_b32_e32 v20, 0, v111, vcc
	v_exp_f32_e32 v23, v23
	v_sub_f32_e32 v20, v19, v20
	v_min_f32_e32 v19, 0, v21
	v_mul_f32_e32 v21, 0x3f317217, v25
	v_fma_f32 v21, v25, s30, -v21
	v_fmac_f32_e32 v21, 0x3377d1cf, v25
	v_fmac_f32_e32 v21, 0x3f317217, v25
	v_cmp_lt_f32_e64 vcc, |v25|, s31
	v_add_f32_e32 v23, 1.0, v23
	v_cndmask_b32_e64 v24, 0, v111, s[0:1]
	v_cndmask_b32_e32 v21, v25, v21, vcc
	v_cmp_gt_f32_e32 vcc, s29, v23
	v_sub_f32_e32 v21, v21, v24
	v_pk_add_f32 v[18:19], v[18:19], v[20:21] neg_lo:[0,1] neg_hi:[0,1]
	v_cndmask_b32_e64 v24, 0, 32, vcc
	v_ldexp_f32 v23, v23, v24
	v_pk_mul_f32 v[20:21], v[100:101], v[82:83]
	v_log_f32_e32 v23, v23
	v_add_f32_e32 v20, v20, v26
	v_add_f32_e32 v21, v21, v20
	v_mul_f32_e64 v20, |v21|, s28
	v_exp_f32_e32 v20, v20
	v_pk_mul_f32 v[70:71], v[18:19], s[6:7] op_sel_hi:[1,0]
	v_mul_f32_e32 v19, 0x3f317217, v23
	v_fma_f32 v19, v23, s30, -v19
	v_fmac_f32_e32 v19, 0x3377d1cf, v23
	v_fmac_f32_e32 v19, 0x3f317217, v23
	v_cmp_lt_f32_e64 s[0:1], |v23|, s31
	v_add_f32_e32 v20, 1.0, v20
	v_min_f32_e32 v18, 0, v22
	v_cndmask_b32_e64 v19, v23, v19, s[0:1]
	v_cmp_gt_f32_e64 s[0:1], s29, v20
	s_nop 1
	v_cndmask_b32_e64 v22, 0, 32, s[0:1]
	v_ldexp_f32 v20, v20, v22
	v_log_f32_e32 v22, v20
	v_cndmask_b32_e32 v20, 0, v111, vcc
	v_sub_f32_e32 v20, v19, v20
	v_min_f32_e32 v19, 0, v21
	v_mul_f32_e32 v21, 0x3f317217, v22
	v_fma_f32 v21, v22, s30, -v21
	v_fmac_f32_e32 v21, 0x3377d1cf, v22
	v_fmac_f32_e32 v21, 0x3f317217, v22
	v_cmp_lt_f32_e64 vcc, |v22|, s31
	s_nop 1
	v_cndmask_b32_e32 v21, v22, v21, vcc
	v_cndmask_b32_e64 v22, 0, v111, s[0:1]
	v_sub_f32_e32 v21, v21, v22
	v_pk_add_f32 v[18:19], v[18:19], v[20:21] neg_lo:[0,1] neg_hi:[0,1]
	s_nop 0
	v_pk_mul_f32 v[76:77], v[18:19], s[6:7] op_sel_hi:[1,0]
	global_load_dwordx4 v[18:21], v123, s[52:53] offset:16
	global_load_dwordx4 v[22:25], v123, s[50:51] offset:16
	global_load_dwordx4 v[26:29], v123, s[50:51] offset:3088
	global_load_dwordx4 v[30:33], v123, s[50:51] offset:3600
	global_load_dwordx4 v[34:37], v110, s[12:13] offset:16
	global_load_dwordx4 v[38:41], v110, s[12:13] offset:528
	global_load_dwordx4 v[42:45], v110, s[12:13] offset:1040
	global_load_dwordx4 v[46:49], v110, s[12:13] offset:1552
	global_load_dwordx4 v[50:53], v110, s[12:13] offset:2064
	global_load_dwordx4 v[54:57], v110, s[12:13] offset:2576
	global_load_dwordx4 v[58:61], v110, s[12:13] offset:3088
	global_load_dwordx4 v[62:65], v110, s[12:13] offset:3600
	global_load_dwordx4 v[84:87], v123, s[50:51] offset:528
	global_load_dwordx4 v[88:91], v123, s[50:51] offset:1040
	global_load_dwordx4 v[92:95], v123, s[50:51] offset:1552
	global_load_dwordx4 v[96:99], v123, s[50:51] offset:2064
	global_load_dwordx4 v[100:103], v123, s[50:51] offset:2576
	s_waitcnt vmcnt(15)
	v_fma_f32 v130, v22, v118, v18
	v_fma_f32 v20, v24, v118, v20
	s_waitcnt vmcnt(14)
	v_mov_b32_e32 v104, v26
	s_waitcnt vmcnt(13)
	v_mov_b32_e32 v105, v30
	v_fma_f32 v23, v23, v118, v19
	v_mov_b32_e32 v30, v27
	v_mov_b32_e32 v18, v28
	v_mov_b32_e32 v19, v32
	v_pk_mul_f32 v[26:27], v[104:105], v[72:73]
	s_waitcnt vmcnt(12)
	v_mov_b32_e32 v106, v34
	s_waitcnt vmcnt(11)
	v_mov_b32_e32 v107, v38
	s_waitcnt vmcnt(4)
	v_fmac_f32_e32 v130, v84, v117
	v_fmac_f32_e32 v20, v86, v117
	s_waitcnt vmcnt(3)
	v_fmac_f32_e32 v130, v88, v122
	v_fmac_f32_e32 v20, v90, v122
	s_waitcnt vmcnt(2)
	v_fmac_f32_e32 v130, v92, v121
	v_fmac_f32_e32 v20, v94, v121
	s_waitcnt vmcnt(1)
	v_fmac_f32_e32 v130, v96, v120
	v_fmac_f32_e32 v20, v98, v120
	s_waitcnt vmcnt(0)
	v_fmac_f32_e32 v130, v100, v119
	v_fmac_f32_e32 v23, v85, v117
	v_pk_mul_f32 v[18:19], v[18:19], v[72:73]
	v_fmac_f32_e32 v20, v102, v119
	v_add_f32_e32 v24, v130, v26
	v_mov_b32_e32 v38, v35
	v_pk_mul_f32 v[34:35], v[106:107], v[74:75]
	v_fmac_f32_e32 v23, v89, v122
	v_add_f32_e32 v18, v18, v20
	v_add_f32_e32 v20, v24, v27
	v_mov_b32_e32 v124, v42
	v_mov_b32_e32 v125, v46
	v_fmac_f32_e32 v23, v93, v121
	v_add_f32_e32 v20, v20, v34
	v_mov_b32_e32 v46, v43
	v_pk_mul_f32 v[42:43], v[124:125], v[78:79]
	v_fmac_f32_e32 v23, v97, v120
	v_add_f32_e32 v20, v20, v35
	v_mov_b32_e32 v126, v50
	v_mov_b32_e32 v127, v54
	v_pk_mul_f32 v[30:31], v[30:31], v[72:73]
	v_fmac_f32_e32 v23, v101, v119
	v_add_f32_e32 v20, v20, v42
	v_mov_b32_e32 v54, v51
	v_pk_mul_f32 v[50:51], v[126:127], v[80:81]
	v_add_f32_e32 v23, v30, v23
	v_add_f32_e32 v20, v20, v43
	v_mov_b32_e32 v128, v58
	v_mov_b32_e32 v129, v62
	v_pk_mul_f32 v[38:39], v[38:39], v[74:75]
	v_add_f32_e32 v23, v31, v23
	v_add_f32_e32 v20, v20, v50
	v_mov_b32_e32 v62, v59
	v_pk_mul_f32 v[58:59], v[128:129], v[82:83]
	v_add_f32_e32 v23, v38, v23
	v_add_f32_e32 v20, v20, v51
	v_pk_mul_f32 v[46:47], v[46:47], v[78:79]
	v_add_f32_e32 v23, v39, v23
	v_add_f32_e32 v20, v20, v58
	v_add_f32_e32 v23, v46, v23
	v_add_f32_e32 v20, v20, v59
	v_pk_mul_f32 v[54:55], v[54:55], v[80:81]
	v_add_f32_e32 v23, v47, v23
	v_mul_f32_e64 v24, |v20|, s28
	v_add_f32_e32 v23, v54, v23
	v_exp_f32_e32 v24, v24
	v_pk_mul_f32 v[62:63], v[62:63], v[82:83]
	v_add_f32_e32 v23, v55, v23
	v_add_f32_e32 v23, v62, v23
	v_add_f32_e32 v23, v63, v23
	v_mul_f32_e64 v26, |v23|, s28
	v_add_f32_e32 v27, v19, v18
	v_add_f32_e32 v19, 1.0, v24
	v_exp_f32_e32 v26, v26
	v_cmp_gt_f32_e32 vcc, s29, v19
	v_min_f32_e32 v18, 0, v20
	v_mov_b32_e32 v22, v36
	v_cndmask_b32_e64 v24, 0, 32, vcc
	v_ldexp_f32 v19, v19, v24
	v_log_f32_e32 v24, v19
	v_add_f32_e32 v20, 1.0, v26
	v_cmp_gt_f32_e64 s[0:1], s29, v20
	v_min_f32_e32 v19, 0, v23
	v_cndmask_b32_e32 v23, 0, v111, vcc
	v_cndmask_b32_e64 v26, 0, 32, s[0:1]
	v_ldexp_f32 v20, v20, v26
	v_mul_f32_e32 v26, 0x3f317217, v24
	v_fma_f32 v26, v24, s30, -v26
	v_fmac_f32_e32 v26, 0x3377d1cf, v24
	v_fmac_f32_e32 v26, 0x3f317217, v24
	v_cmp_lt_f32_e64 vcc, |v24|, s31
	v_log_f32_e32 v20, v20
	v_fmac_f32_e32 v21, v25, v118
	v_cndmask_b32_e32 v24, v24, v26, vcc
	v_sub_f32_e32 v26, v24, v23
	v_mov_b32_e32 v23, v40
	v_pk_mul_f32 v[22:23], v[22:23], v[74:75]
	v_mul_f32_e32 v28, 0x3f317217, v20
	v_add_f32_e32 v22, v22, v27
	v_add_f32_e32 v24, v23, v22
	v_mov_b32_e32 v22, v44
	v_mov_b32_e32 v23, v48
	v_pk_mul_f32 v[22:23], v[22:23], v[78:79]
	v_fma_f32 v28, v20, s30, -v28
	v_add_f32_e32 v22, v22, v24
	v_add_f32_e32 v24, v23, v22
	v_mov_b32_e32 v22, v52
	v_mov_b32_e32 v23, v56
	v_pk_mul_f32 v[22:23], v[22:23], v[80:81]
	v_fmac_f32_e32 v28, 0x3377d1cf, v20
	v_add_f32_e32 v22, v22, v24
	v_add_f32_e32 v24, v23, v22
	v_mov_b32_e32 v22, v60
	v_mov_b32_e32 v23, v64
	v_pk_mul_f32 v[22:23], v[22:23], v[82:83]
	v_fmac_f32_e32 v28, 0x3f317217, v20
	v_add_f32_e32 v22, v22, v24
	v_add_f32_e32 v22, v23, v22
	v_mul_f32_e64 v23, |v22|, s28
	v_exp_f32_e32 v23, v23
	v_cmp_lt_f32_e64 vcc, |v20|, s31
	v_cndmask_b32_e64 v24, 0, v111, s[0:1]
	v_fmac_f32_e32 v21, v87, v117
	v_cndmask_b32_e32 v20, v20, v28, vcc
	v_sub_f32_e32 v27, v20, v24
	v_add_f32_e32 v20, 1.0, v23
	v_fmac_f32_e32 v21, v91, v122
	v_cmp_gt_f32_e32 vcc, s29, v20
	v_fmac_f32_e32 v21, v95, v121
	v_pk_add_f32 v[18:19], v[18:19], v[26:27] neg_lo:[0,1] neg_hi:[0,1]
	v_cndmask_b32_e64 v23, 0, 32, vcc
	v_fmac_f32_e32 v21, v99, v120
	v_mov_b32_e32 v32, v29
	v_ldexp_f32 v20, v20, v23
	v_pk_mul_f32 v[84:85], v[18:19], s[6:7] op_sel_hi:[1,0]
	v_min_f32_e32 v18, 0, v22
	v_fmac_f32_e32 v21, v103, v119
	v_pk_mul_f32 v[22:23], v[32:33], v[72:73]
	v_log_f32_e32 v24, v20
	v_add_f32_e32 v20, v22, v21
	v_mov_b32_e32 v40, v37
	v_add_f32_e32 v22, v23, v20
	v_pk_mul_f32 v[20:21], v[40:41], v[74:75]
	v_mov_b32_e32 v48, v45
	v_add_f32_e32 v20, v20, v22
	v_add_f32_e32 v22, v21, v20
	v_pk_mul_f32 v[20:21], v[48:49], v[78:79]
	v_mov_b32_e32 v56, v53
	v_add_f32_e32 v20, v20, v22
	v_add_f32_e32 v22, v21, v20
	v_pk_mul_f32 v[20:21], v[56:57], v[80:81]
	v_mov_b32_e32 v64, v61
	v_add_f32_e32 v20, v20, v22
	v_add_f32_e32 v22, v21, v20
	v_pk_mul_f32 v[20:21], v[64:65], v[82:83]
	v_mul_f32_e32 v19, 0x3f317217, v24
	v_add_f32_e32 v20, v20, v22
	v_add_f32_e32 v21, v21, v20
	v_mul_f32_e64 v20, |v21|, s28
	v_exp_f32_e32 v20, v20
	v_fma_f32 v19, v24, s30, -v19
	v_fmac_f32_e32 v19, 0x3377d1cf, v24
	v_fmac_f32_e32 v19, 0x3f317217, v24
	v_cmp_lt_f32_e64 s[0:1], |v24|, s31
	v_add_f32_e32 v20, 1.0, v20
	s_nop 0
	v_cndmask_b32_e64 v19, v24, v19, s[0:1]
	v_cmp_gt_f32_e64 s[0:1], s29, v20
	s_nop 1
	v_cndmask_b32_e64 v22, 0, 32, s[0:1]
	v_ldexp_f32 v20, v20, v22
	v_log_f32_e32 v22, v20
	v_cndmask_b32_e32 v20, 0, v111, vcc
	v_sub_f32_e32 v20, v19, v20
	v_min_f32_e32 v19, 0, v21
	v_mul_f32_e32 v21, 0x3f317217, v22
	v_fma_f32 v21, v22, s30, -v21
	v_fmac_f32_e32 v21, 0x3377d1cf, v22
	v_fmac_f32_e32 v21, 0x3f317217, v22
	v_cmp_lt_f32_e64 vcc, |v22|, s31
	s_nop 1
	v_cndmask_b32_e32 v21, v22, v21, vcc
	v_cndmask_b32_e64 v22, 0, v111, s[0:1]
	v_sub_f32_e32 v21, v21, v22
	v_pk_add_f32 v[18:19], v[18:19], v[20:21] neg_lo:[0,1] neg_hi:[0,1]
	s_nop 0
	v_pk_mul_f32 v[86:87], v[18:19], s[6:7] op_sel_hi:[1,0]
	global_load_dwordx4 v[18:21], v123, s[52:53] offset:32
	global_load_dwordx4 v[22:25], v123, s[50:51] offset:32
	global_load_dwordx4 v[26:29], v123, s[50:51] offset:3104
	global_load_dwordx4 v[30:33], v123, s[50:51] offset:3616
	global_load_dwordx4 v[34:37], v110, s[12:13] offset:32
	global_load_dwordx4 v[38:41], v110, s[12:13] offset:544
	global_load_dwordx4 v[42:45], v110, s[12:13] offset:1056
	global_load_dwordx4 v[46:49], v110, s[12:13] offset:1568
	global_load_dwordx4 v[50:53], v110, s[12:13] offset:2080
	global_load_dwordx4 v[54:57], v110, s[12:13] offset:2592
	global_load_dwordx4 v[58:61], v110, s[12:13] offset:3104
	global_load_dwordx4 v[62:65], v110, s[12:13] offset:3616
	global_load_dwordx4 v[88:91], v123, s[50:51] offset:544
	global_load_dwordx4 v[92:95], v123, s[50:51] offset:1056
	global_load_dwordx4 v[96:99], v123, s[50:51] offset:1568
	global_load_dwordx4 v[100:103], v123, s[50:51] offset:2080
	global_load_dwordx4 v[104:107], v123, s[50:51] offset:2592
	s_waitcnt vmcnt(15)
	v_fma_f32 v134, v22, v118, v18
	v_fma_f32 v20, v24, v118, v20
	s_waitcnt vmcnt(14)
	v_mov_b32_e32 v124, v26
	s_waitcnt vmcnt(13)
	v_mov_b32_e32 v125, v30
	v_fma_f32 v23, v23, v118, v19
	v_mov_b32_e32 v30, v27
	v_mov_b32_e32 v18, v28
	v_mov_b32_e32 v19, v32
	v_pk_mul_f32 v[26:27], v[124:125], v[72:73]
	s_waitcnt vmcnt(12)
	v_mov_b32_e32 v126, v34
	s_waitcnt vmcnt(11)
	v_mov_b32_e32 v127, v38
	s_waitcnt vmcnt(4)
	v_fmac_f32_e32 v134, v88, v117
	v_fmac_f32_e32 v20, v90, v117
	s_waitcnt vmcnt(3)
	v_fmac_f32_e32 v134, v92, v122
	v_fmac_f32_e32 v20, v94, v122
	s_waitcnt vmcnt(2)
	v_fmac_f32_e32 v134, v96, v121
	v_fmac_f32_e32 v20, v98, v121
	s_waitcnt vmcnt(1)
	v_fmac_f32_e32 v134, v100, v120
	v_fmac_f32_e32 v20, v102, v120
	s_waitcnt vmcnt(0)
	v_fmac_f32_e32 v134, v104, v119
	v_fmac_f32_e32 v23, v89, v117
	v_pk_mul_f32 v[18:19], v[18:19], v[72:73]
	v_fmac_f32_e32 v20, v106, v119
	v_add_f32_e32 v24, v134, v26
	v_mov_b32_e32 v38, v35
	v_pk_mul_f32 v[34:35], v[126:127], v[74:75]
	v_fmac_f32_e32 v23, v93, v122
	v_add_f32_e32 v18, v18, v20
	v_add_f32_e32 v20, v24, v27
	v_mov_b32_e32 v128, v42
	v_mov_b32_e32 v129, v46
	v_fmac_f32_e32 v23, v97, v121
	v_add_f32_e32 v20, v20, v34
	v_mov_b32_e32 v46, v43
	v_pk_mul_f32 v[42:43], v[128:129], v[78:79]
	v_fmac_f32_e32 v23, v101, v120
	v_add_f32_e32 v20, v20, v35
	v_mov_b32_e32 v130, v50
	v_mov_b32_e32 v131, v54
	v_pk_mul_f32 v[30:31], v[30:31], v[72:73]
	v_fmac_f32_e32 v23, v105, v119
	v_add_f32_e32 v20, v20, v42
	v_mov_b32_e32 v54, v51
	v_pk_mul_f32 v[50:51], v[130:131], v[80:81]
	v_add_f32_e32 v23, v30, v23
	v_add_f32_e32 v20, v20, v43
	v_mov_b32_e32 v132, v58
	v_mov_b32_e32 v133, v62
	v_pk_mul_f32 v[38:39], v[38:39], v[74:75]
	v_add_f32_e32 v23, v31, v23
	v_add_f32_e32 v20, v20, v50
	v_mov_b32_e32 v62, v59
	v_pk_mul_f32 v[58:59], v[132:133], v[82:83]
	v_add_f32_e32 v23, v38, v23
	v_add_f32_e32 v20, v20, v51
	v_pk_mul_f32 v[46:47], v[46:47], v[78:79]
	v_add_f32_e32 v23, v39, v23
	v_add_f32_e32 v20, v20, v58
	v_add_f32_e32 v23, v46, v23
	v_add_f32_e32 v20, v20, v59
	v_pk_mul_f32 v[54:55], v[54:55], v[80:81]
	v_add_f32_e32 v23, v47, v23
	v_mul_f32_e64 v24, |v20|, s28
	v_add_f32_e32 v23, v54, v23
	v_exp_f32_e32 v24, v24
	v_pk_mul_f32 v[62:63], v[62:63], v[82:83]
	v_add_f32_e32 v23, v55, v23
	v_add_f32_e32 v23, v62, v23
	v_add_f32_e32 v23, v63, v23
	v_mul_f32_e64 v26, |v23|, s28
	v_add_f32_e32 v27, v19, v18
	v_add_f32_e32 v19, 1.0, v24
	v_exp_f32_e32 v26, v26
	v_cmp_gt_f32_e32 vcc, s29, v19
	v_min_f32_e32 v18, 0, v20
	v_mov_b32_e32 v22, v36
	v_cndmask_b32_e64 v24, 0, 32, vcc
	v_ldexp_f32 v19, v19, v24
	v_log_f32_e32 v24, v19
	v_add_f32_e32 v20, 1.0, v26
	v_cmp_gt_f32_e64 s[0:1], s29, v20
	v_min_f32_e32 v19, 0, v23
	v_cndmask_b32_e32 v23, 0, v111, vcc
	v_cndmask_b32_e64 v26, 0, 32, s[0:1]
	v_ldexp_f32 v20, v20, v26
	v_mul_f32_e32 v26, 0x3f317217, v24
	v_fma_f32 v26, v24, s30, -v26
	v_fmac_f32_e32 v26, 0x3377d1cf, v24
	v_fmac_f32_e32 v26, 0x3f317217, v24
	v_cmp_lt_f32_e64 vcc, |v24|, s31
	v_log_f32_e32 v20, v20
	v_fmac_f32_e32 v21, v25, v118
	v_cndmask_b32_e32 v24, v24, v26, vcc
	v_sub_f32_e32 v26, v24, v23
	v_mov_b32_e32 v23, v40
	v_pk_mul_f32 v[22:23], v[22:23], v[74:75]
	v_mul_f32_e32 v28, 0x3f317217, v20
	v_add_f32_e32 v22, v22, v27
	v_add_f32_e32 v24, v23, v22
	v_mov_b32_e32 v22, v44
	v_mov_b32_e32 v23, v48
	v_pk_mul_f32 v[22:23], v[22:23], v[78:79]
	v_fma_f32 v28, v20, s30, -v28
	v_add_f32_e32 v22, v22, v24
	v_add_f32_e32 v24, v23, v22
	v_mov_b32_e32 v22, v52
	v_mov_b32_e32 v23, v56
	v_pk_mul_f32 v[22:23], v[22:23], v[80:81]
	v_fmac_f32_e32 v28, 0x3377d1cf, v20
	v_add_f32_e32 v22, v22, v24
	v_add_f32_e32 v24, v23, v22
	v_mov_b32_e32 v22, v60
	v_mov_b32_e32 v23, v64
	v_pk_mul_f32 v[22:23], v[22:23], v[82:83]
	v_fmac_f32_e32 v28, 0x3f317217, v20
	v_add_f32_e32 v22, v22, v24
	v_add_f32_e32 v22, v23, v22
	v_mul_f32_e64 v23, |v22|, s28
	v_exp_f32_e32 v23, v23
	v_cmp_lt_f32_e64 vcc, |v20|, s31
	v_cndmask_b32_e64 v24, 0, v111, s[0:1]
	v_fmac_f32_e32 v21, v91, v117
	v_cndmask_b32_e32 v20, v20, v28, vcc
	v_sub_f32_e32 v27, v20, v24
	v_add_f32_e32 v20, 1.0, v23
	v_fmac_f32_e32 v21, v95, v122
	v_cmp_gt_f32_e32 vcc, s29, v20
	v_fmac_f32_e32 v21, v99, v121
	v_pk_add_f32 v[18:19], v[18:19], v[26:27] neg_lo:[0,1] neg_hi:[0,1]
	v_cndmask_b32_e64 v23, 0, 32, vcc
	v_fmac_f32_e32 v21, v103, v120
	v_mov_b32_e32 v32, v29
	v_ldexp_f32 v20, v20, v23
	v_pk_mul_f32 v[88:89], v[18:19], s[6:7] op_sel_hi:[1,0]
	v_min_f32_e32 v18, 0, v22
	v_fmac_f32_e32 v21, v107, v119
	v_pk_mul_f32 v[22:23], v[32:33], v[72:73]
	v_log_f32_e32 v24, v20
	v_add_f32_e32 v20, v22, v21
	v_mov_b32_e32 v40, v37
	v_add_f32_e32 v22, v23, v20
	v_pk_mul_f32 v[20:21], v[40:41], v[74:75]
	v_mov_b32_e32 v48, v45
	v_add_f32_e32 v20, v20, v22
	v_add_f32_e32 v22, v21, v20
	v_pk_mul_f32 v[20:21], v[48:49], v[78:79]
	v_mov_b32_e32 v56, v53
	v_add_f32_e32 v20, v20, v22
	v_add_f32_e32 v22, v21, v20
	v_pk_mul_f32 v[20:21], v[56:57], v[80:81]
	v_mov_b32_e32 v64, v61
	v_add_f32_e32 v20, v20, v22
	v_add_f32_e32 v22, v21, v20
	v_pk_mul_f32 v[20:21], v[64:65], v[82:83]
	v_mul_f32_e32 v19, 0x3f317217, v24
	v_add_f32_e32 v20, v20, v22
	v_add_f32_e32 v21, v21, v20
	v_mul_f32_e64 v20, |v21|, s28
	v_exp_f32_e32 v20, v20
	v_fma_f32 v19, v24, s30, -v19
	v_fmac_f32_e32 v19, 0x3377d1cf, v24
	v_fmac_f32_e32 v19, 0x3f317217, v24
	v_cmp_lt_f32_e64 s[0:1], |v24|, s31
	v_add_f32_e32 v20, 1.0, v20
	s_nop 0
	v_cndmask_b32_e64 v19, v24, v19, s[0:1]
	v_cmp_gt_f32_e64 s[0:1], s29, v20
	s_nop 1
	v_cndmask_b32_e64 v22, 0, 32, s[0:1]
	v_ldexp_f32 v20, v20, v22
	v_log_f32_e32 v22, v20
	v_cndmask_b32_e32 v20, 0, v111, vcc
	v_sub_f32_e32 v20, v19, v20
	v_min_f32_e32 v19, 0, v21
	v_mul_f32_e32 v21, 0x3f317217, v22
	v_fma_f32 v21, v22, s30, -v21
	v_fmac_f32_e32 v21, 0x3377d1cf, v22
	v_fmac_f32_e32 v21, 0x3f317217, v22
	v_cmp_lt_f32_e64 vcc, |v22|, s31
	s_nop 1
	v_cndmask_b32_e32 v21, v22, v21, vcc
	v_cndmask_b32_e64 v22, 0, v111, s[0:1]
	v_sub_f32_e32 v21, v21, v22
	v_pk_add_f32 v[18:19], v[18:19], v[20:21] neg_lo:[0,1] neg_hi:[0,1]
	s_nop 0
	v_pk_mul_f32 v[90:91], v[18:19], s[6:7] op_sel_hi:[1,0]
	global_load_dwordx4 v[18:21], v123, s[52:53] offset:48
	global_load_dwordx4 v[22:25], v123, s[50:51] offset:48
	global_load_dwordx4 v[26:29], v123, s[50:51] offset:3120
	global_load_dwordx4 v[30:33], v123, s[50:51] offset:3632
	global_load_dwordx4 v[34:37], v110, s[12:13] offset:48
	global_load_dwordx4 v[38:41], v110, s[12:13] offset:560
	global_load_dwordx4 v[42:45], v110, s[12:13] offset:1072
	global_load_dwordx4 v[46:49], v110, s[12:13] offset:1584
	global_load_dwordx4 v[50:53], v110, s[12:13] offset:2096
	global_load_dwordx4 v[54:57], v110, s[12:13] offset:2608
	global_load_dwordx4 v[58:61], v110, s[12:13] offset:3120
	global_load_dwordx4 v[62:65], v110, s[12:13] offset:3632
	global_load_dwordx4 v[92:95], v123, s[50:51] offset:560
	global_load_dwordx4 v[96:99], v123, s[50:51] offset:1072
	global_load_dwordx4 v[100:103], v123, s[50:51] offset:1584
	global_load_dwordx4 v[104:107], v123, s[50:51] offset:2096
	global_load_dwordx4 v[124:127], v123, s[50:51] offset:2608
	s_waitcnt vmcnt(15)
	v_fma_f32 v138, v22, v118, v18
	v_fma_f32 v20, v24, v118, v20
	s_waitcnt vmcnt(14)
	v_mov_b32_e32 v128, v26
	s_waitcnt vmcnt(13)
	v_mov_b32_e32 v129, v30
	v_fma_f32 v23, v23, v118, v19
	v_mov_b32_e32 v30, v27
	v_mov_b32_e32 v18, v28
	v_mov_b32_e32 v19, v32
	v_pk_mul_f32 v[26:27], v[128:129], v[72:73]
	s_waitcnt vmcnt(12)
	v_mov_b32_e32 v130, v34
	s_waitcnt vmcnt(11)
	v_mov_b32_e32 v131, v38
	s_waitcnt vmcnt(4)
	v_fmac_f32_e32 v138, v92, v117
	v_fmac_f32_e32 v20, v94, v117
	s_waitcnt vmcnt(3)
	v_fmac_f32_e32 v138, v96, v122
	v_fmac_f32_e32 v20, v98, v122
	s_waitcnt vmcnt(2)
	v_fmac_f32_e32 v138, v100, v121
	v_fmac_f32_e32 v20, v102, v121
	s_waitcnt vmcnt(1)
	v_fmac_f32_e32 v138, v104, v120
	v_fmac_f32_e32 v20, v106, v120
	s_waitcnt vmcnt(0)
	v_fmac_f32_e32 v138, v124, v119
	v_fmac_f32_e32 v23, v93, v117
	v_pk_mul_f32 v[18:19], v[18:19], v[72:73]
	v_fmac_f32_e32 v20, v126, v119
	v_add_f32_e32 v24, v138, v26
	v_mov_b32_e32 v38, v35
	v_pk_mul_f32 v[34:35], v[130:131], v[74:75]
	v_fmac_f32_e32 v23, v97, v122
	v_add_f32_e32 v18, v18, v20
	v_add_f32_e32 v20, v24, v27
	v_mov_b32_e32 v132, v42
	v_mov_b32_e32 v133, v46
	v_fmac_f32_e32 v23, v101, v121
	v_add_f32_e32 v20, v20, v34
	v_mov_b32_e32 v46, v43
	v_pk_mul_f32 v[42:43], v[132:133], v[78:79]
	v_fmac_f32_e32 v23, v105, v120
	v_add_f32_e32 v20, v20, v35
	v_mov_b32_e32 v134, v50
	v_mov_b32_e32 v135, v54
	v_pk_mul_f32 v[30:31], v[30:31], v[72:73]
	v_fmac_f32_e32 v23, v125, v119
	v_add_f32_e32 v20, v20, v42
	v_mov_b32_e32 v54, v51
	v_pk_mul_f32 v[50:51], v[134:135], v[80:81]
	v_add_f32_e32 v23, v30, v23
	v_add_f32_e32 v20, v20, v43
	v_mov_b32_e32 v136, v58
	v_mov_b32_e32 v137, v62
	v_pk_mul_f32 v[38:39], v[38:39], v[74:75]
	v_add_f32_e32 v23, v31, v23
	v_add_f32_e32 v20, v20, v50
	v_mov_b32_e32 v62, v59
	v_pk_mul_f32 v[58:59], v[136:137], v[82:83]
	v_add_f32_e32 v23, v38, v23
	v_add_f32_e32 v20, v20, v51
	v_pk_mul_f32 v[46:47], v[46:47], v[78:79]
	v_add_f32_e32 v23, v39, v23
	v_add_f32_e32 v20, v20, v58
	v_add_f32_e32 v23, v46, v23
	v_add_f32_e32 v20, v20, v59
	v_pk_mul_f32 v[54:55], v[54:55], v[80:81]
	v_add_f32_e32 v23, v47, v23
	v_mul_f32_e64 v24, |v20|, s28
	v_add_f32_e32 v23, v54, v23
	v_exp_f32_e32 v24, v24
	v_pk_mul_f32 v[62:63], v[62:63], v[82:83]
	v_add_f32_e32 v23, v55, v23
	v_add_f32_e32 v23, v62, v23
	v_add_f32_e32 v23, v63, v23
	v_mul_f32_e64 v26, |v23|, s28
	v_add_f32_e32 v27, v19, v18
	v_add_f32_e32 v19, 1.0, v24
	v_exp_f32_e32 v26, v26
	v_cmp_gt_f32_e32 vcc, s29, v19
	v_min_f32_e32 v18, 0, v20
	v_mov_b32_e32 v22, v36
	v_cndmask_b32_e64 v24, 0, 32, vcc
	v_ldexp_f32 v19, v19, v24
	v_log_f32_e32 v24, v19
	v_add_f32_e32 v20, 1.0, v26
	v_cmp_gt_f32_e64 s[0:1], s29, v20
	v_min_f32_e32 v19, 0, v23
	v_cndmask_b32_e32 v23, 0, v111, vcc
	v_cndmask_b32_e64 v26, 0, 32, s[0:1]
	v_ldexp_f32 v20, v20, v26
	v_mul_f32_e32 v26, 0x3f317217, v24
	v_fma_f32 v26, v24, s30, -v26
	v_fmac_f32_e32 v26, 0x3377d1cf, v24
	v_fmac_f32_e32 v26, 0x3f317217, v24
	v_cmp_lt_f32_e64 vcc, |v24|, s31
	v_log_f32_e32 v20, v20
	v_fmac_f32_e32 v21, v25, v118
	v_cndmask_b32_e32 v24, v24, v26, vcc
	v_sub_f32_e32 v26, v24, v23
	v_mov_b32_e32 v23, v40
	v_pk_mul_f32 v[22:23], v[22:23], v[74:75]
	v_mul_f32_e32 v28, 0x3f317217, v20
	v_add_f32_e32 v22, v22, v27
	v_add_f32_e32 v24, v23, v22
	v_mov_b32_e32 v22, v44
	v_mov_b32_e32 v23, v48
	v_pk_mul_f32 v[22:23], v[22:23], v[78:79]
	v_fma_f32 v28, v20, s30, -v28
	v_add_f32_e32 v22, v22, v24
	v_add_f32_e32 v24, v23, v22
	v_mov_b32_e32 v22, v52
	v_mov_b32_e32 v23, v56
	v_pk_mul_f32 v[22:23], v[22:23], v[80:81]
	v_fmac_f32_e32 v28, 0x3377d1cf, v20
	v_add_f32_e32 v22, v22, v24
	v_add_f32_e32 v24, v23, v22
	v_mov_b32_e32 v22, v60
	v_mov_b32_e32 v23, v64
	v_pk_mul_f32 v[22:23], v[22:23], v[82:83]
	v_fmac_f32_e32 v28, 0x3f317217, v20
	v_add_f32_e32 v22, v22, v24
	v_add_f32_e32 v22, v23, v22
	v_mul_f32_e64 v23, |v22|, s28
	v_exp_f32_e32 v23, v23
	v_cmp_lt_f32_e64 vcc, |v20|, s31
	v_cndmask_b32_e64 v24, 0, v111, s[0:1]
	v_fmac_f32_e32 v21, v95, v117
	v_cndmask_b32_e32 v20, v20, v28, vcc
	v_sub_f32_e32 v27, v20, v24
	v_add_f32_e32 v20, 1.0, v23
	v_fmac_f32_e32 v21, v99, v122
	v_cmp_gt_f32_e32 vcc, s29, v20
	v_fmac_f32_e32 v21, v103, v121
	v_pk_add_f32 v[18:19], v[18:19], v[26:27] neg_lo:[0,1] neg_hi:[0,1]
	v_cndmask_b32_e64 v23, 0, 32, vcc
	v_fmac_f32_e32 v21, v107, v120
	v_mov_b32_e32 v32, v29
	v_ldexp_f32 v20, v20, v23
	v_pk_mul_f32 v[92:93], v[18:19], s[6:7] op_sel_hi:[1,0]
	v_min_f32_e32 v18, 0, v22
	v_fmac_f32_e32 v21, v127, v119
	v_pk_mul_f32 v[22:23], v[32:33], v[72:73]
	v_log_f32_e32 v24, v20
	v_add_f32_e32 v20, v22, v21
	v_mov_b32_e32 v40, v37
	v_add_f32_e32 v22, v23, v20
	v_pk_mul_f32 v[20:21], v[40:41], v[74:75]
	v_mov_b32_e32 v48, v45
	v_add_f32_e32 v20, v20, v22
	v_add_f32_e32 v22, v21, v20
	v_pk_mul_f32 v[20:21], v[48:49], v[78:79]
	v_mov_b32_e32 v56, v53
	v_add_f32_e32 v20, v20, v22
	v_add_f32_e32 v22, v21, v20
	v_pk_mul_f32 v[20:21], v[56:57], v[80:81]
	v_mov_b32_e32 v64, v61
	v_add_f32_e32 v20, v20, v22
	v_add_f32_e32 v22, v21, v20
	v_pk_mul_f32 v[20:21], v[64:65], v[82:83]
	v_mul_f32_e32 v19, 0x3f317217, v24
	v_add_f32_e32 v20, v20, v22
	v_add_f32_e32 v21, v21, v20
	v_mul_f32_e64 v20, |v21|, s28
	v_exp_f32_e32 v20, v20
	v_fma_f32 v19, v24, s30, -v19
	v_fmac_f32_e32 v19, 0x3377d1cf, v24
	v_fmac_f32_e32 v19, 0x3f317217, v24
	v_cmp_lt_f32_e64 s[0:1], |v24|, s31
	v_add_f32_e32 v20, 1.0, v20
	s_nop 0
	v_cndmask_b32_e64 v19, v24, v19, s[0:1]
	v_cmp_gt_f32_e64 s[0:1], s29, v20
	s_nop 1
	v_cndmask_b32_e64 v22, 0, 32, s[0:1]
	v_ldexp_f32 v20, v20, v22
	v_log_f32_e32 v22, v20
	v_cndmask_b32_e32 v20, 0, v111, vcc
	v_sub_f32_e32 v20, v19, v20
	v_min_f32_e32 v19, 0, v21
	v_mul_f32_e32 v21, 0x3f317217, v22
	v_fma_f32 v21, v22, s30, -v21
	v_fmac_f32_e32 v21, 0x3377d1cf, v22
	v_fmac_f32_e32 v21, 0x3f317217, v22
	v_cmp_lt_f32_e64 vcc, |v22|, s31
	s_nop 1
	v_cndmask_b32_e32 v21, v22, v21, vcc
	v_cndmask_b32_e64 v22, 0, v111, s[0:1]
	v_sub_f32_e32 v21, v21, v22
	v_pk_add_f32 v[18:19], v[18:19], v[20:21] neg_lo:[0,1] neg_hi:[0,1]
	s_nop 0
	v_pk_mul_f32 v[94:95], v[18:19], s[6:7] op_sel_hi:[1,0]
	global_load_dwordx4 v[18:21], v123, s[52:53] offset:64
	global_load_dwordx4 v[22:25], v123, s[50:51] offset:64
	global_load_dwordx4 v[26:29], v123, s[50:51] offset:3136
	global_load_dwordx4 v[30:33], v123, s[50:51] offset:3648
	global_load_dwordx4 v[34:37], v110, s[12:13] offset:64
	global_load_dwordx4 v[38:41], v110, s[12:13] offset:576
	global_load_dwordx4 v[42:45], v110, s[12:13] offset:1088
	global_load_dwordx4 v[46:49], v110, s[12:13] offset:1600
	global_load_dwordx4 v[50:53], v110, s[12:13] offset:2112
	global_load_dwordx4 v[54:57], v110, s[12:13] offset:2624
	global_load_dwordx4 v[58:61], v110, s[12:13] offset:3136
	global_load_dwordx4 v[62:65], v110, s[12:13] offset:3648
	global_load_dwordx4 v[96:99], v123, s[50:51] offset:576
	global_load_dwordx4 v[100:103], v123, s[50:51] offset:1088
	global_load_dwordx4 v[104:107], v123, s[50:51] offset:1600
	global_load_dwordx4 v[124:127], v123, s[50:51] offset:2112
	global_load_dwordx4 v[128:131], v123, s[50:51] offset:2624
	s_waitcnt vmcnt(15)
	v_fma_f32 v142, v22, v118, v18
	v_fma_f32 v20, v24, v118, v20
	s_waitcnt vmcnt(14)
	v_mov_b32_e32 v132, v26
	s_waitcnt vmcnt(13)
	v_mov_b32_e32 v133, v30
	v_fma_f32 v23, v23, v118, v19
	v_mov_b32_e32 v30, v27
	v_mov_b32_e32 v18, v28
	v_mov_b32_e32 v19, v32
	v_pk_mul_f32 v[26:27], v[132:133], v[72:73]
	s_waitcnt vmcnt(12)
	v_mov_b32_e32 v134, v34
	s_waitcnt vmcnt(11)
	v_mov_b32_e32 v135, v38
	s_waitcnt vmcnt(4)
	v_fmac_f32_e32 v142, v96, v117
	v_fmac_f32_e32 v20, v98, v117
	s_waitcnt vmcnt(3)
	v_fmac_f32_e32 v142, v100, v122
	v_fmac_f32_e32 v20, v102, v122
	s_waitcnt vmcnt(2)
	v_fmac_f32_e32 v142, v104, v121
	v_fmac_f32_e32 v20, v106, v121
	s_waitcnt vmcnt(1)
	v_fmac_f32_e32 v142, v124, v120
	v_fmac_f32_e32 v20, v126, v120
	s_waitcnt vmcnt(0)
	v_fmac_f32_e32 v142, v128, v119
	v_fmac_f32_e32 v23, v97, v117
	v_pk_mul_f32 v[18:19], v[18:19], v[72:73]
	v_fmac_f32_e32 v20, v130, v119
	v_add_f32_e32 v24, v142, v26
	v_mov_b32_e32 v38, v35
	v_pk_mul_f32 v[34:35], v[134:135], v[74:75]
	v_fmac_f32_e32 v23, v101, v122
	v_add_f32_e32 v18, v18, v20
	v_add_f32_e32 v20, v24, v27
	v_mov_b32_e32 v136, v42
	v_mov_b32_e32 v137, v46
	v_fmac_f32_e32 v23, v105, v121
	v_add_f32_e32 v20, v20, v34
	v_mov_b32_e32 v46, v43
	v_pk_mul_f32 v[42:43], v[136:137], v[78:79]
	v_fmac_f32_e32 v23, v125, v120
	v_add_f32_e32 v20, v20, v35
	v_mov_b32_e32 v138, v50
	v_mov_b32_e32 v139, v54
	v_pk_mul_f32 v[30:31], v[30:31], v[72:73]
	v_fmac_f32_e32 v23, v129, v119
	v_add_f32_e32 v20, v20, v42
	v_mov_b32_e32 v54, v51
	v_pk_mul_f32 v[50:51], v[138:139], v[80:81]
	v_add_f32_e32 v23, v30, v23
	v_add_f32_e32 v20, v20, v43
	v_mov_b32_e32 v140, v58
	v_mov_b32_e32 v141, v62
	v_pk_mul_f32 v[38:39], v[38:39], v[74:75]
	v_add_f32_e32 v23, v31, v23
	v_add_f32_e32 v20, v20, v50
	v_mov_b32_e32 v62, v59
	v_pk_mul_f32 v[58:59], v[140:141], v[82:83]
	v_add_f32_e32 v23, v38, v23
	v_add_f32_e32 v20, v20, v51
	v_pk_mul_f32 v[46:47], v[46:47], v[78:79]
	v_add_f32_e32 v23, v39, v23
	v_add_f32_e32 v20, v20, v58
	v_add_f32_e32 v23, v46, v23
	v_add_f32_e32 v20, v20, v59
	v_pk_mul_f32 v[54:55], v[54:55], v[80:81]
	v_add_f32_e32 v23, v47, v23
	v_mul_f32_e64 v24, |v20|, s28
	v_add_f32_e32 v23, v54, v23
	v_exp_f32_e32 v24, v24
	v_pk_mul_f32 v[62:63], v[62:63], v[82:83]
	v_add_f32_e32 v23, v55, v23
	v_add_f32_e32 v23, v62, v23
	v_add_f32_e32 v23, v63, v23
	v_mul_f32_e64 v26, |v23|, s28
	v_add_f32_e32 v27, v19, v18
	v_add_f32_e32 v19, 1.0, v24
	v_exp_f32_e32 v26, v26
	v_cmp_gt_f32_e32 vcc, s29, v19
	v_min_f32_e32 v18, 0, v20
	v_mov_b32_e32 v22, v36
	v_cndmask_b32_e64 v24, 0, 32, vcc
	v_ldexp_f32 v19, v19, v24
	v_log_f32_e32 v24, v19
	v_add_f32_e32 v20, 1.0, v26
	v_cmp_gt_f32_e64 s[0:1], s29, v20
	v_min_f32_e32 v19, 0, v23
	v_cndmask_b32_e32 v23, 0, v111, vcc
	v_cndmask_b32_e64 v26, 0, 32, s[0:1]
	v_ldexp_f32 v20, v20, v26
	v_mul_f32_e32 v26, 0x3f317217, v24
	v_fma_f32 v26, v24, s30, -v26
	v_fmac_f32_e32 v26, 0x3377d1cf, v24
	v_fmac_f32_e32 v26, 0x3f317217, v24
	v_cmp_lt_f32_e64 vcc, |v24|, s31
	v_log_f32_e32 v20, v20
	v_fmac_f32_e32 v21, v25, v118
	v_cndmask_b32_e32 v24, v24, v26, vcc
	v_sub_f32_e32 v26, v24, v23
	v_mov_b32_e32 v23, v40
	v_pk_mul_f32 v[22:23], v[22:23], v[74:75]
	v_mul_f32_e32 v28, 0x3f317217, v20
	v_add_f32_e32 v22, v22, v27
	v_add_f32_e32 v24, v23, v22
	v_mov_b32_e32 v22, v44
	v_mov_b32_e32 v23, v48
	v_pk_mul_f32 v[22:23], v[22:23], v[78:79]
	v_fma_f32 v28, v20, s30, -v28
	v_add_f32_e32 v22, v22, v24
	v_add_f32_e32 v24, v23, v22
	v_mov_b32_e32 v22, v52
	v_mov_b32_e32 v23, v56
	v_pk_mul_f32 v[22:23], v[22:23], v[80:81]
	v_fmac_f32_e32 v28, 0x3377d1cf, v20
	v_add_f32_e32 v22, v22, v24
	v_add_f32_e32 v24, v23, v22
	v_mov_b32_e32 v22, v60
	v_mov_b32_e32 v23, v64
	v_pk_mul_f32 v[22:23], v[22:23], v[82:83]
	v_fmac_f32_e32 v28, 0x3f317217, v20
	v_add_f32_e32 v22, v22, v24
	v_add_f32_e32 v22, v23, v22
	v_mul_f32_e64 v23, |v22|, s28
	v_exp_f32_e32 v23, v23
	v_cmp_lt_f32_e64 vcc, |v20|, s31
	v_cndmask_b32_e64 v24, 0, v111, s[0:1]
	v_fmac_f32_e32 v21, v99, v117
	v_cndmask_b32_e32 v20, v20, v28, vcc
	v_sub_f32_e32 v27, v20, v24
	v_add_f32_e32 v20, 1.0, v23
	v_fmac_f32_e32 v21, v103, v122
	v_cmp_gt_f32_e32 vcc, s29, v20
	v_fmac_f32_e32 v21, v107, v121
	v_pk_add_f32 v[18:19], v[18:19], v[26:27] neg_lo:[0,1] neg_hi:[0,1]
	v_cndmask_b32_e64 v23, 0, 32, vcc
	v_fmac_f32_e32 v21, v127, v120
	v_mov_b32_e32 v32, v29
	v_ldexp_f32 v20, v20, v23
	v_pk_mul_f32 v[96:97], v[18:19], s[6:7] op_sel_hi:[1,0]
	v_min_f32_e32 v18, 0, v22
	v_fmac_f32_e32 v21, v131, v119
	v_pk_mul_f32 v[22:23], v[32:33], v[72:73]
	v_log_f32_e32 v24, v20
	v_add_f32_e32 v20, v22, v21
	v_mov_b32_e32 v40, v37
	v_add_f32_e32 v22, v23, v20
	v_pk_mul_f32 v[20:21], v[40:41], v[74:75]
	v_mov_b32_e32 v48, v45
	v_add_f32_e32 v20, v20, v22
	v_add_f32_e32 v22, v21, v20
	v_pk_mul_f32 v[20:21], v[48:49], v[78:79]
	v_mov_b32_e32 v56, v53
	v_add_f32_e32 v20, v20, v22
	v_add_f32_e32 v22, v21, v20
	v_pk_mul_f32 v[20:21], v[56:57], v[80:81]
	v_mov_b32_e32 v64, v61
	v_add_f32_e32 v20, v20, v22
	v_add_f32_e32 v22, v21, v20
	v_pk_mul_f32 v[20:21], v[64:65], v[82:83]
	v_mul_f32_e32 v19, 0x3f317217, v24
	v_add_f32_e32 v20, v20, v22
	v_add_f32_e32 v21, v21, v20
	v_mul_f32_e64 v20, |v21|, s28
	v_exp_f32_e32 v20, v20
	v_fma_f32 v19, v24, s30, -v19
	v_fmac_f32_e32 v19, 0x3377d1cf, v24
	v_fmac_f32_e32 v19, 0x3f317217, v24
	v_cmp_lt_f32_e64 s[0:1], |v24|, s31
	v_add_f32_e32 v20, 1.0, v20
	s_nop 0
	v_cndmask_b32_e64 v19, v24, v19, s[0:1]
	v_cmp_gt_f32_e64 s[0:1], s29, v20
	s_nop 1
	v_cndmask_b32_e64 v22, 0, 32, s[0:1]
	v_ldexp_f32 v20, v20, v22
	v_log_f32_e32 v22, v20
	v_cndmask_b32_e32 v20, 0, v111, vcc
	v_sub_f32_e32 v20, v19, v20
	v_min_f32_e32 v19, 0, v21
	v_mul_f32_e32 v21, 0x3f317217, v22
	v_fma_f32 v21, v22, s30, -v21
	v_fmac_f32_e32 v21, 0x3377d1cf, v22
	v_fmac_f32_e32 v21, 0x3f317217, v22
	v_cmp_lt_f32_e64 vcc, |v22|, s31
	s_nop 1
	v_cndmask_b32_e32 v21, v22, v21, vcc
	v_cndmask_b32_e64 v22, 0, v111, s[0:1]
	v_sub_f32_e32 v21, v21, v22
	v_pk_add_f32 v[18:19], v[18:19], v[20:21] neg_lo:[0,1] neg_hi:[0,1]
	s_nop 0
	v_pk_mul_f32 v[98:99], v[18:19], s[6:7] op_sel_hi:[1,0]
	global_load_dwordx4 v[18:21], v123, s[52:53] offset:80
	global_load_dwordx4 v[22:25], v123, s[50:51] offset:80
	global_load_dwordx4 v[26:29], v123, s[50:51] offset:3152
	global_load_dwordx4 v[30:33], v123, s[50:51] offset:3664
	global_load_dwordx4 v[34:37], v110, s[12:13] offset:80
	global_load_dwordx4 v[38:41], v110, s[12:13] offset:592
	global_load_dwordx4 v[42:45], v110, s[12:13] offset:1104
	global_load_dwordx4 v[46:49], v110, s[12:13] offset:1616
	global_load_dwordx4 v[50:53], v110, s[12:13] offset:2128
	global_load_dwordx4 v[54:57], v110, s[12:13] offset:2640
	global_load_dwordx4 v[58:61], v110, s[12:13] offset:3152
	global_load_dwordx4 v[62:65], v110, s[12:13] offset:3664
	global_load_dwordx4 v[100:103], v123, s[50:51] offset:592
	global_load_dwordx4 v[104:107], v123, s[50:51] offset:1104
	global_load_dwordx4 v[124:127], v123, s[50:51] offset:1616
	global_load_dwordx4 v[128:131], v123, s[50:51] offset:2128
	global_load_dwordx4 v[132:135], v123, s[50:51] offset:2640
	s_waitcnt vmcnt(15)
	v_fma_f32 v146, v22, v118, v18
	v_fma_f32 v20, v24, v118, v20
	s_waitcnt vmcnt(14)
	v_mov_b32_e32 v136, v26
	s_waitcnt vmcnt(13)
	v_mov_b32_e32 v137, v30
	v_fma_f32 v23, v23, v118, v19
	v_mov_b32_e32 v30, v27
	v_mov_b32_e32 v18, v28
	v_mov_b32_e32 v19, v32
	v_pk_mul_f32 v[26:27], v[136:137], v[72:73]
	s_waitcnt vmcnt(12)
	v_mov_b32_e32 v138, v34
	s_waitcnt vmcnt(11)
	v_mov_b32_e32 v139, v38
	s_waitcnt vmcnt(4)
	v_fmac_f32_e32 v146, v100, v117
	v_fmac_f32_e32 v20, v102, v117
	s_waitcnt vmcnt(3)
	v_fmac_f32_e32 v146, v104, v122
	v_fmac_f32_e32 v20, v106, v122
	s_waitcnt vmcnt(2)
	v_fmac_f32_e32 v146, v124, v121
	v_fmac_f32_e32 v20, v126, v121
	s_waitcnt vmcnt(1)
	v_fmac_f32_e32 v146, v128, v120
	v_fmac_f32_e32 v20, v130, v120
	s_waitcnt vmcnt(0)
	v_fmac_f32_e32 v146, v132, v119
	v_fmac_f32_e32 v23, v101, v117
	v_pk_mul_f32 v[18:19], v[18:19], v[72:73]
	v_fmac_f32_e32 v20, v134, v119
	v_add_f32_e32 v24, v146, v26
	v_mov_b32_e32 v38, v35
	v_pk_mul_f32 v[34:35], v[138:139], v[74:75]
	v_fmac_f32_e32 v23, v105, v122
	v_add_f32_e32 v18, v18, v20
	v_add_f32_e32 v20, v24, v27
	v_mov_b32_e32 v140, v42
	v_mov_b32_e32 v141, v46
	v_fmac_f32_e32 v23, v125, v121
	v_add_f32_e32 v20, v20, v34
	v_mov_b32_e32 v46, v43
	v_pk_mul_f32 v[42:43], v[140:141], v[78:79]
	v_fmac_f32_e32 v23, v129, v120
	v_add_f32_e32 v20, v20, v35
	v_mov_b32_e32 v142, v50
	v_mov_b32_e32 v143, v54
	v_pk_mul_f32 v[30:31], v[30:31], v[72:73]
	v_fmac_f32_e32 v23, v133, v119
	v_add_f32_e32 v20, v20, v42
	v_mov_b32_e32 v54, v51
	v_pk_mul_f32 v[50:51], v[142:143], v[80:81]
	v_add_f32_e32 v23, v30, v23
	v_add_f32_e32 v20, v20, v43
	v_mov_b32_e32 v144, v58
	v_mov_b32_e32 v145, v62
	v_pk_mul_f32 v[38:39], v[38:39], v[74:75]
	v_add_f32_e32 v23, v31, v23
	v_add_f32_e32 v20, v20, v50
	v_mov_b32_e32 v62, v59
	v_pk_mul_f32 v[58:59], v[144:145], v[82:83]
	v_add_f32_e32 v23, v38, v23
	v_add_f32_e32 v20, v20, v51
	v_pk_mul_f32 v[46:47], v[46:47], v[78:79]
	v_add_f32_e32 v23, v39, v23
	v_add_f32_e32 v20, v20, v58
	v_add_f32_e32 v23, v46, v23
	v_add_f32_e32 v20, v20, v59
	v_pk_mul_f32 v[54:55], v[54:55], v[80:81]
	v_add_f32_e32 v23, v47, v23
	v_mul_f32_e64 v24, |v20|, s28
	v_add_f32_e32 v23, v54, v23
	v_exp_f32_e32 v24, v24
	v_pk_mul_f32 v[62:63], v[62:63], v[82:83]
	v_add_f32_e32 v23, v55, v23
	v_add_f32_e32 v23, v62, v23
	v_add_f32_e32 v23, v63, v23
	v_mul_f32_e64 v26, |v23|, s28
	v_add_f32_e32 v27, v19, v18
	v_add_f32_e32 v19, 1.0, v24
	v_exp_f32_e32 v26, v26
	v_cmp_gt_f32_e32 vcc, s29, v19
	v_min_f32_e32 v18, 0, v20
	v_mov_b32_e32 v22, v36
	v_cndmask_b32_e64 v24, 0, 32, vcc
	v_ldexp_f32 v19, v19, v24
	v_log_f32_e32 v24, v19
	v_add_f32_e32 v20, 1.0, v26
	v_cmp_gt_f32_e64 s[0:1], s29, v20
	v_min_f32_e32 v19, 0, v23
	v_cndmask_b32_e32 v23, 0, v111, vcc
	v_cndmask_b32_e64 v26, 0, 32, s[0:1]
	v_ldexp_f32 v20, v20, v26
	v_mul_f32_e32 v26, 0x3f317217, v24
	v_fma_f32 v26, v24, s30, -v26
	v_fmac_f32_e32 v26, 0x3377d1cf, v24
	v_fmac_f32_e32 v26, 0x3f317217, v24
	v_cmp_lt_f32_e64 vcc, |v24|, s31
	v_log_f32_e32 v20, v20
	v_fmac_f32_e32 v21, v25, v118
	v_cndmask_b32_e32 v24, v24, v26, vcc
	v_sub_f32_e32 v26, v24, v23
	v_mov_b32_e32 v23, v40
	v_pk_mul_f32 v[22:23], v[22:23], v[74:75]
	v_mul_f32_e32 v28, 0x3f317217, v20
	v_add_f32_e32 v22, v22, v27
	v_add_f32_e32 v24, v23, v22
	v_mov_b32_e32 v22, v44
	v_mov_b32_e32 v23, v48
	v_pk_mul_f32 v[22:23], v[22:23], v[78:79]
	v_fma_f32 v28, v20, s30, -v28
	v_add_f32_e32 v22, v22, v24
	v_add_f32_e32 v24, v23, v22
	v_mov_b32_e32 v22, v52
	v_mov_b32_e32 v23, v56
	v_pk_mul_f32 v[22:23], v[22:23], v[80:81]
	v_fmac_f32_e32 v28, 0x3377d1cf, v20
	v_add_f32_e32 v22, v22, v24
	v_add_f32_e32 v24, v23, v22
	v_mov_b32_e32 v22, v60
	v_mov_b32_e32 v23, v64
	v_pk_mul_f32 v[22:23], v[22:23], v[82:83]
	v_fmac_f32_e32 v28, 0x3f317217, v20
	v_add_f32_e32 v22, v22, v24
	v_add_f32_e32 v22, v23, v22
	v_mul_f32_e64 v23, |v22|, s28
	v_exp_f32_e32 v23, v23
	v_cmp_lt_f32_e64 vcc, |v20|, s31
	v_cndmask_b32_e64 v24, 0, v111, s[0:1]
	v_fmac_f32_e32 v21, v103, v117
	v_cndmask_b32_e32 v20, v20, v28, vcc
	v_sub_f32_e32 v27, v20, v24
	v_add_f32_e32 v20, 1.0, v23
	v_fmac_f32_e32 v21, v107, v122
	v_cmp_gt_f32_e32 vcc, s29, v20
	v_fmac_f32_e32 v21, v127, v121
	v_pk_add_f32 v[18:19], v[18:19], v[26:27] neg_lo:[0,1] neg_hi:[0,1]
	v_cndmask_b32_e64 v23, 0, 32, vcc
	v_fmac_f32_e32 v21, v131, v120
	v_mov_b32_e32 v32, v29
	v_ldexp_f32 v20, v20, v23
	v_pk_mul_f32 v[100:101], v[18:19], s[6:7] op_sel_hi:[1,0]
	v_min_f32_e32 v18, 0, v22
	v_fmac_f32_e32 v21, v135, v119
	v_pk_mul_f32 v[22:23], v[32:33], v[72:73]
	v_log_f32_e32 v24, v20
	v_add_f32_e32 v20, v22, v21
	v_mov_b32_e32 v40, v37
	v_add_f32_e32 v22, v23, v20
	v_pk_mul_f32 v[20:21], v[40:41], v[74:75]
	v_mov_b32_e32 v48, v45
	v_add_f32_e32 v20, v20, v22
	v_add_f32_e32 v22, v21, v20
	v_pk_mul_f32 v[20:21], v[48:49], v[78:79]
	v_mov_b32_e32 v56, v53
	v_add_f32_e32 v20, v20, v22
	v_add_f32_e32 v22, v21, v20
	v_pk_mul_f32 v[20:21], v[56:57], v[80:81]
	v_mov_b32_e32 v64, v61
	v_add_f32_e32 v20, v20, v22
	v_add_f32_e32 v22, v21, v20
	v_pk_mul_f32 v[20:21], v[64:65], v[82:83]
	v_mul_f32_e32 v19, 0x3f317217, v24
	v_add_f32_e32 v20, v20, v22
	v_add_f32_e32 v21, v21, v20
	v_mul_f32_e64 v20, |v21|, s28
	v_exp_f32_e32 v20, v20
	v_fma_f32 v19, v24, s30, -v19
	v_fmac_f32_e32 v19, 0x3377d1cf, v24
	v_fmac_f32_e32 v19, 0x3f317217, v24
	v_cmp_lt_f32_e64 s[0:1], |v24|, s31
	v_add_f32_e32 v20, 1.0, v20
	s_nop 0
	v_cndmask_b32_e64 v19, v24, v19, s[0:1]
	v_cmp_gt_f32_e64 s[0:1], s29, v20
	s_nop 1
	v_cndmask_b32_e64 v22, 0, 32, s[0:1]
	v_ldexp_f32 v20, v20, v22
	v_log_f32_e32 v22, v20
	v_cndmask_b32_e32 v20, 0, v111, vcc
	v_sub_f32_e32 v20, v19, v20
	v_min_f32_e32 v19, 0, v21
	v_mul_f32_e32 v21, 0x3f317217, v22
	v_fma_f32 v21, v22, s30, -v21
	v_fmac_f32_e32 v21, 0x3377d1cf, v22
	v_fmac_f32_e32 v21, 0x3f317217, v22
	v_cmp_lt_f32_e64 vcc, |v22|, s31
	s_nop 1
	v_cndmask_b32_e32 v21, v22, v21, vcc
	v_cndmask_b32_e64 v22, 0, v111, s[0:1]
	v_sub_f32_e32 v21, v21, v22
	v_pk_add_f32 v[18:19], v[18:19], v[20:21] neg_lo:[0,1] neg_hi:[0,1]
	s_nop 0
	v_pk_mul_f32 v[102:103], v[18:19], s[6:7] op_sel_hi:[1,0]
	global_load_dwordx4 v[18:21], v123, s[52:53] offset:96
	global_load_dwordx4 v[22:25], v123, s[50:51] offset:96
	global_load_dwordx4 v[26:29], v123, s[50:51] offset:3168
	global_load_dwordx4 v[30:33], v123, s[50:51] offset:3680
	global_load_dwordx4 v[34:37], v110, s[12:13] offset:96
	global_load_dwordx4 v[38:41], v110, s[12:13] offset:608
	global_load_dwordx4 v[42:45], v110, s[12:13] offset:1120
	global_load_dwordx4 v[46:49], v110, s[12:13] offset:1632
	global_load_dwordx4 v[50:53], v110, s[12:13] offset:2144
	global_load_dwordx4 v[54:57], v110, s[12:13] offset:2656
	global_load_dwordx4 v[58:61], v110, s[12:13] offset:3168
	global_load_dwordx4 v[62:65], v110, s[12:13] offset:3680
	global_load_dwordx4 v[104:107], v123, s[50:51] offset:608
	global_load_dwordx4 v[124:127], v123, s[50:51] offset:1120
	global_load_dwordx4 v[128:131], v123, s[50:51] offset:1632
	global_load_dwordx4 v[132:135], v123, s[50:51] offset:2144
	global_load_dwordx4 v[136:139], v123, s[50:51] offset:2656
	s_waitcnt vmcnt(15)
	v_fma_f32 v150, v22, v118, v18
	v_fma_f32 v20, v24, v118, v20
	s_waitcnt vmcnt(14)
	v_mov_b32_e32 v140, v26
	s_waitcnt vmcnt(13)
	v_mov_b32_e32 v141, v30
	v_fma_f32 v23, v23, v118, v19
	v_mov_b32_e32 v30, v27
	v_mov_b32_e32 v18, v28
	v_mov_b32_e32 v19, v32
	v_pk_mul_f32 v[26:27], v[140:141], v[72:73]
	s_waitcnt vmcnt(12)
	v_mov_b32_e32 v142, v34
	s_waitcnt vmcnt(11)
	v_mov_b32_e32 v143, v38
	s_waitcnt vmcnt(4)
	v_fmac_f32_e32 v150, v104, v117
	v_fmac_f32_e32 v20, v106, v117
	s_waitcnt vmcnt(3)
	v_fmac_f32_e32 v150, v124, v122
	v_fmac_f32_e32 v20, v126, v122
	s_waitcnt vmcnt(2)
	v_fmac_f32_e32 v150, v128, v121
	v_fmac_f32_e32 v20, v130, v121
	s_waitcnt vmcnt(1)
	v_fmac_f32_e32 v150, v132, v120
	v_fmac_f32_e32 v20, v134, v120
	s_waitcnt vmcnt(0)
	v_fmac_f32_e32 v150, v136, v119
	v_fmac_f32_e32 v23, v105, v117
	v_pk_mul_f32 v[18:19], v[18:19], v[72:73]
	v_fmac_f32_e32 v20, v138, v119
	v_add_f32_e32 v24, v150, v26
	v_mov_b32_e32 v38, v35
	v_pk_mul_f32 v[34:35], v[142:143], v[74:75]
	v_fmac_f32_e32 v23, v125, v122
	v_add_f32_e32 v18, v18, v20
	v_add_f32_e32 v20, v24, v27
	v_mov_b32_e32 v144, v42
	v_mov_b32_e32 v145, v46
	v_fmac_f32_e32 v23, v129, v121
	v_add_f32_e32 v20, v20, v34
	v_mov_b32_e32 v46, v43
	v_pk_mul_f32 v[42:43], v[144:145], v[78:79]
	v_fmac_f32_e32 v23, v133, v120
	v_add_f32_e32 v20, v20, v35
	v_mov_b32_e32 v146, v50
	v_mov_b32_e32 v147, v54
	v_pk_mul_f32 v[30:31], v[30:31], v[72:73]
	v_fmac_f32_e32 v23, v137, v119
	v_add_f32_e32 v20, v20, v42
	v_mov_b32_e32 v54, v51
	v_pk_mul_f32 v[50:51], v[146:147], v[80:81]
	v_add_f32_e32 v23, v30, v23
	v_add_f32_e32 v20, v20, v43
	v_mov_b32_e32 v148, v58
	v_mov_b32_e32 v149, v62
	v_pk_mul_f32 v[38:39], v[38:39], v[74:75]
	v_add_f32_e32 v23, v31, v23
	v_add_f32_e32 v20, v20, v50
	v_mov_b32_e32 v62, v59
	v_pk_mul_f32 v[58:59], v[148:149], v[82:83]
	v_add_f32_e32 v23, v38, v23
	v_add_f32_e32 v20, v20, v51
	v_pk_mul_f32 v[46:47], v[46:47], v[78:79]
	v_add_f32_e32 v23, v39, v23
	v_add_f32_e32 v20, v20, v58
	v_add_f32_e32 v23, v46, v23
	v_add_f32_e32 v20, v20, v59
	v_pk_mul_f32 v[54:55], v[54:55], v[80:81]
	v_add_f32_e32 v23, v47, v23
	v_mul_f32_e64 v24, |v20|, s28
	v_add_f32_e32 v23, v54, v23
	v_exp_f32_e32 v24, v24
	v_pk_mul_f32 v[62:63], v[62:63], v[82:83]
	v_add_f32_e32 v23, v55, v23
	v_add_f32_e32 v23, v62, v23
	v_add_f32_e32 v23, v63, v23
	v_mul_f32_e64 v26, |v23|, s28
	v_add_f32_e32 v27, v19, v18
	v_add_f32_e32 v19, 1.0, v24
	v_exp_f32_e32 v26, v26
	v_cmp_gt_f32_e32 vcc, s29, v19
	v_min_f32_e32 v18, 0, v20
	v_mov_b32_e32 v22, v36
	v_cndmask_b32_e64 v24, 0, 32, vcc
	v_ldexp_f32 v19, v19, v24
	v_log_f32_e32 v24, v19
	v_add_f32_e32 v20, 1.0, v26
	v_cmp_gt_f32_e64 s[0:1], s29, v20
	v_min_f32_e32 v19, 0, v23
	v_cndmask_b32_e32 v23, 0, v111, vcc
	v_cndmask_b32_e64 v26, 0, 32, s[0:1]
	v_ldexp_f32 v20, v20, v26
	v_mul_f32_e32 v26, 0x3f317217, v24
	v_fma_f32 v26, v24, s30, -v26
	v_fmac_f32_e32 v26, 0x3377d1cf, v24
	v_fmac_f32_e32 v26, 0x3f317217, v24
	v_cmp_lt_f32_e64 vcc, |v24|, s31
	v_log_f32_e32 v20, v20
	v_fmac_f32_e32 v21, v25, v118
	v_cndmask_b32_e32 v24, v24, v26, vcc
	v_sub_f32_e32 v26, v24, v23
	v_mov_b32_e32 v23, v40
	v_pk_mul_f32 v[22:23], v[22:23], v[74:75]
	v_mul_f32_e32 v28, 0x3f317217, v20
	v_add_f32_e32 v22, v22, v27
	v_add_f32_e32 v24, v23, v22
	v_mov_b32_e32 v22, v44
	v_mov_b32_e32 v23, v48
	v_pk_mul_f32 v[22:23], v[22:23], v[78:79]
	v_fma_f32 v28, v20, s30, -v28
	v_add_f32_e32 v22, v22, v24
	v_add_f32_e32 v24, v23, v22
	v_mov_b32_e32 v22, v52
	v_mov_b32_e32 v23, v56
	v_pk_mul_f32 v[22:23], v[22:23], v[80:81]
	v_fmac_f32_e32 v28, 0x3377d1cf, v20
	v_add_f32_e32 v22, v22, v24
	v_add_f32_e32 v24, v23, v22
	v_mov_b32_e32 v22, v60
	v_mov_b32_e32 v23, v64
	v_pk_mul_f32 v[22:23], v[22:23], v[82:83]
	v_fmac_f32_e32 v28, 0x3f317217, v20
	v_add_f32_e32 v22, v22, v24
	v_add_f32_e32 v22, v23, v22
	v_mul_f32_e64 v23, |v22|, s28
	v_exp_f32_e32 v23, v23
	v_cmp_lt_f32_e64 vcc, |v20|, s31
	v_cndmask_b32_e64 v24, 0, v111, s[0:1]
	v_fmac_f32_e32 v21, v107, v117
	v_cndmask_b32_e32 v20, v20, v28, vcc
	v_sub_f32_e32 v27, v20, v24
	v_add_f32_e32 v20, 1.0, v23
	v_fmac_f32_e32 v21, v127, v122
	v_cmp_gt_f32_e32 vcc, s29, v20
	v_fmac_f32_e32 v21, v131, v121
	v_pk_add_f32 v[18:19], v[18:19], v[26:27] neg_lo:[0,1] neg_hi:[0,1]
	v_cndmask_b32_e64 v23, 0, 32, vcc
	v_fmac_f32_e32 v21, v135, v120
	v_mov_b32_e32 v32, v29
	v_ldexp_f32 v20, v20, v23
	v_pk_mul_f32 v[104:105], v[18:19], s[6:7] op_sel_hi:[1,0]
	v_min_f32_e32 v18, 0, v22
	v_fmac_f32_e32 v21, v139, v119
	v_pk_mul_f32 v[22:23], v[32:33], v[72:73]
	v_log_f32_e32 v24, v20
	v_add_f32_e32 v20, v22, v21
	v_mov_b32_e32 v40, v37
	v_add_f32_e32 v22, v23, v20
	v_pk_mul_f32 v[20:21], v[40:41], v[74:75]
	v_mov_b32_e32 v48, v45
	v_add_f32_e32 v20, v20, v22
	v_add_f32_e32 v22, v21, v20
	v_pk_mul_f32 v[20:21], v[48:49], v[78:79]
	v_mov_b32_e32 v56, v53
	v_add_f32_e32 v20, v20, v22
	v_add_f32_e32 v22, v21, v20
	v_pk_mul_f32 v[20:21], v[56:57], v[80:81]
	v_mov_b32_e32 v64, v61
	v_add_f32_e32 v20, v20, v22
	v_add_f32_e32 v22, v21, v20
	v_pk_mul_f32 v[20:21], v[64:65], v[82:83]
	v_mul_f32_e32 v19, 0x3f317217, v24
	v_add_f32_e32 v20, v20, v22
	v_add_f32_e32 v21, v21, v20
	v_mul_f32_e64 v20, |v21|, s28
	v_exp_f32_e32 v20, v20
	v_fma_f32 v19, v24, s30, -v19
	v_fmac_f32_e32 v19, 0x3377d1cf, v24
	v_fmac_f32_e32 v19, 0x3f317217, v24
	v_cmp_lt_f32_e64 s[0:1], |v24|, s31
	v_add_f32_e32 v20, 1.0, v20
	s_nop 0
	v_cndmask_b32_e64 v19, v24, v19, s[0:1]
	v_cmp_gt_f32_e64 s[0:1], s29, v20
	s_nop 1
	v_cndmask_b32_e64 v22, 0, 32, s[0:1]
	v_ldexp_f32 v20, v20, v22
	v_log_f32_e32 v22, v20
	v_cndmask_b32_e32 v20, 0, v111, vcc
	v_sub_f32_e32 v20, v19, v20
	v_min_f32_e32 v19, 0, v21
	v_mul_f32_e32 v21, 0x3f317217, v22
	v_fma_f32 v21, v22, s30, -v21
	v_fmac_f32_e32 v21, 0x3377d1cf, v22
	v_fmac_f32_e32 v21, 0x3f317217, v22
	v_cmp_lt_f32_e64 vcc, |v22|, s31
	s_nop 1
	v_cndmask_b32_e32 v21, v22, v21, vcc
	v_cndmask_b32_e64 v22, 0, v111, s[0:1]
	v_sub_f32_e32 v21, v21, v22
	v_pk_add_f32 v[18:19], v[18:19], v[20:21] neg_lo:[0,1] neg_hi:[0,1]
	s_nop 0
	v_pk_mul_f32 v[106:107], v[18:19], s[6:7] op_sel_hi:[1,0]
	global_load_dwordx4 v[18:21], v123, s[52:53] offset:112
	global_load_dwordx4 v[22:25], v123, s[50:51] offset:112
	global_load_dwordx4 v[26:29], v123, s[50:51] offset:3184
	global_load_dwordx4 v[30:33], v123, s[50:51] offset:3696
	global_load_dwordx4 v[34:37], v110, s[12:13] offset:112
	global_load_dwordx4 v[38:41], v110, s[12:13] offset:624
	global_load_dwordx4 v[42:45], v110, s[12:13] offset:1136
	global_load_dwordx4 v[46:49], v110, s[12:13] offset:1648
	global_load_dwordx4 v[50:53], v110, s[12:13] offset:2160
	global_load_dwordx4 v[54:57], v110, s[12:13] offset:2672
	global_load_dwordx4 v[58:61], v110, s[12:13] offset:3184
	global_load_dwordx4 v[62:65], v110, s[12:13] offset:3696
	global_load_dwordx4 v[124:127], v123, s[50:51] offset:624
	global_load_dwordx4 v[128:131], v123, s[50:51] offset:1136
	global_load_dwordx4 v[132:135], v123, s[50:51] offset:1648
	global_load_dwordx4 v[136:139], v123, s[50:51] offset:2160
	global_load_dwordx4 v[140:143], v123, s[50:51] offset:2672
	s_waitcnt vmcnt(15)
	v_fma_f32 v123, v22, v118, v18
	v_fma_f32 v20, v24, v118, v20
	s_waitcnt vmcnt(14)
	v_mov_b32_e32 v144, v26
	s_waitcnt vmcnt(13)
	v_mov_b32_e32 v145, v30
	v_fma_f32 v23, v23, v118, v19
	v_mov_b32_e32 v30, v27
	v_mov_b32_e32 v18, v28
	v_mov_b32_e32 v19, v32
	v_pk_mul_f32 v[26:27], v[144:145], v[72:73]
	s_waitcnt vmcnt(12)
	v_mov_b32_e32 v146, v34
	s_waitcnt vmcnt(11)
	v_mov_b32_e32 v147, v38
	s_waitcnt vmcnt(4)
	v_fmac_f32_e32 v123, v124, v117
	v_fmac_f32_e32 v20, v126, v117
	s_waitcnt vmcnt(3)
	v_fmac_f32_e32 v123, v128, v122
	v_fmac_f32_e32 v20, v130, v122
	s_waitcnt vmcnt(2)
	v_fmac_f32_e32 v123, v132, v121
	v_fmac_f32_e32 v20, v134, v121
	s_waitcnt vmcnt(1)
	v_fmac_f32_e32 v123, v136, v120
	v_fmac_f32_e32 v20, v138, v120
	s_waitcnt vmcnt(0)
	v_fmac_f32_e32 v123, v140, v119
	v_fmac_f32_e32 v23, v125, v117
	v_pk_mul_f32 v[18:19], v[18:19], v[72:73]
	v_fmac_f32_e32 v20, v142, v119
	v_add_f32_e32 v24, v123, v26
	v_mov_b32_e32 v38, v35
	v_pk_mul_f32 v[34:35], v[146:147], v[74:75]
	v_fmac_f32_e32 v23, v129, v122
	v_add_f32_e32 v18, v18, v20
	v_add_f32_e32 v20, v24, v27
	v_mov_b32_e32 v148, v42
	v_mov_b32_e32 v149, v46
	v_fmac_f32_e32 v23, v133, v121
	v_add_f32_e32 v20, v20, v34
	v_mov_b32_e32 v46, v43
	v_pk_mul_f32 v[42:43], v[148:149], v[78:79]
	v_fmac_f32_e32 v23, v137, v120
	v_add_f32_e32 v20, v20, v35
	v_mov_b32_e32 v150, v50
	v_mov_b32_e32 v151, v54
	v_pk_mul_f32 v[30:31], v[30:31], v[72:73]
	v_fmac_f32_e32 v23, v141, v119
	v_add_f32_e32 v20, v20, v42
	v_mov_b32_e32 v54, v51
	v_pk_mul_f32 v[50:51], v[150:151], v[80:81]
	v_add_f32_e32 v23, v30, v23
	v_add_f32_e32 v20, v20, v43
	v_mov_b32_e32 v152, v58
	v_mov_b32_e32 v153, v62
	v_pk_mul_f32 v[38:39], v[38:39], v[74:75]
	v_add_f32_e32 v23, v31, v23
	v_add_f32_e32 v20, v20, v50
	v_mov_b32_e32 v62, v59
	v_pk_mul_f32 v[58:59], v[152:153], v[82:83]
	v_add_f32_e32 v23, v38, v23
	v_add_f32_e32 v20, v20, v51
	v_pk_mul_f32 v[46:47], v[46:47], v[78:79]
	v_add_f32_e32 v23, v39, v23
	v_add_f32_e32 v20, v20, v58
	v_add_f32_e32 v23, v46, v23
	v_add_f32_e32 v20, v20, v59
	v_pk_mul_f32 v[54:55], v[54:55], v[80:81]
	v_add_f32_e32 v23, v47, v23
	v_mul_f32_e64 v24, |v20|, s28
	v_add_f32_e32 v23, v54, v23
	v_exp_f32_e32 v24, v24
	v_pk_mul_f32 v[62:63], v[62:63], v[82:83]
	v_add_f32_e32 v23, v55, v23
	v_add_f32_e32 v23, v62, v23
	v_add_f32_e32 v23, v63, v23
	v_mul_f32_e64 v26, |v23|, s28
	v_add_f32_e32 v27, v19, v18
	v_add_f32_e32 v19, 1.0, v24
	v_exp_f32_e32 v26, v26
	v_cmp_gt_f32_e32 vcc, s29, v19
	v_min_f32_e32 v18, 0, v20
	v_mov_b32_e32 v22, v36
	v_cndmask_b32_e64 v24, 0, 32, vcc
	v_ldexp_f32 v19, v19, v24
	v_log_f32_e32 v24, v19
	v_add_f32_e32 v20, 1.0, v26
	v_cmp_gt_f32_e64 s[0:1], s29, v20
	v_min_f32_e32 v19, 0, v23
	v_cndmask_b32_e32 v23, 0, v111, vcc
	v_cndmask_b32_e64 v26, 0, 32, s[0:1]
	v_ldexp_f32 v20, v20, v26
	v_mul_f32_e32 v26, 0x3f317217, v24
	v_fma_f32 v26, v24, s30, -v26
	v_fmac_f32_e32 v26, 0x3377d1cf, v24
	v_fmac_f32_e32 v26, 0x3f317217, v24
	v_cmp_lt_f32_e64 vcc, |v24|, s31
	v_log_f32_e32 v20, v20
	v_fmac_f32_e32 v21, v25, v118
	v_cndmask_b32_e32 v24, v24, v26, vcc
	v_sub_f32_e32 v26, v24, v23
	v_mov_b32_e32 v23, v40
	v_pk_mul_f32 v[22:23], v[22:23], v[74:75]
	v_mul_f32_e32 v28, 0x3f317217, v20
	v_add_f32_e32 v22, v22, v27
	v_add_f32_e32 v24, v23, v22
	v_mov_b32_e32 v22, v44
	v_mov_b32_e32 v23, v48
	v_pk_mul_f32 v[22:23], v[22:23], v[78:79]
	v_fma_f32 v28, v20, s30, -v28
	v_add_f32_e32 v22, v22, v24
	v_add_f32_e32 v24, v23, v22
	v_mov_b32_e32 v22, v52
	v_mov_b32_e32 v23, v56
	v_pk_mul_f32 v[22:23], v[22:23], v[80:81]
	v_fmac_f32_e32 v28, 0x3377d1cf, v20
	v_add_f32_e32 v22, v22, v24
	v_add_f32_e32 v24, v23, v22
	v_mov_b32_e32 v22, v60
	v_mov_b32_e32 v23, v64
	v_pk_mul_f32 v[22:23], v[22:23], v[82:83]
	v_fmac_f32_e32 v28, 0x3f317217, v20
	v_add_f32_e32 v22, v22, v24
	v_add_f32_e32 v22, v23, v22
	v_mul_f32_e64 v23, |v22|, s28
	v_exp_f32_e32 v23, v23
	v_cmp_lt_f32_e64 vcc, |v20|, s31
	v_cndmask_b32_e64 v24, 0, v111, s[0:1]
	v_fmac_f32_e32 v21, v127, v117
	v_cndmask_b32_e32 v20, v20, v28, vcc
	v_sub_f32_e32 v27, v20, v24
	v_add_f32_e32 v20, 1.0, v23
	v_cmp_gt_f32_e32 vcc, s29, v20
	v_fmac_f32_e32 v21, v131, v122
	v_fmac_f32_e32 v21, v135, v121
	v_cndmask_b32_e64 v23, 0, 32, vcc
	v_ldexp_f32 v20, v20, v23
	v_log_f32_e32 v24, v20
	v_min_f32_e32 v20, 0, v22
	v_fmac_f32_e32 v21, v139, v120
	v_mov_b32_e32 v32, v29
	v_mul_f32_e32 v22, 0x3f317217, v24
	v_pk_add_f32 v[18:19], v[18:19], v[26:27] neg_lo:[0,1] neg_hi:[0,1]
	v_fma_f32 v26, v24, s30, -v22
	v_fmac_f32_e32 v21, v143, v119
	v_pk_mul_f32 v[22:23], v[32:33], v[72:73]
	v_mov_b32_e32 v40, v37
	v_add_f32_e32 v21, v22, v21
	v_add_f32_e32 v21, v23, v21
	v_pk_mul_f32 v[22:23], v[40:41], v[74:75]
	v_mov_b32_e32 v48, v45
	v_add_f32_e32 v21, v22, v21
	v_add_f32_e32 v21, v23, v21
	v_pk_mul_f32 v[22:23], v[48:49], v[78:79]
	v_mov_b32_e32 v56, v53
	v_add_f32_e32 v21, v22, v21
	v_add_f32_e32 v21, v23, v21
	v_pk_mul_f32 v[22:23], v[56:57], v[80:81]
	v_mov_b32_e32 v64, v61
	v_add_f32_e32 v21, v22, v21
	v_add_f32_e32 v21, v23, v21
	v_pk_mul_f32 v[22:23], v[64:65], v[82:83]
	v_fmac_f32_e32 v26, 0x3377d1cf, v24
	v_add_f32_e32 v21, v22, v21
	v_add_f32_e32 v21, v23, v21
	v_mul_f32_e64 v22, |v21|, s28
	v_exp_f32_e32 v22, v22
	v_fmac_f32_e32 v26, 0x3f317217, v24
	v_cmp_lt_f32_e64 s[0:1], |v24|, s31
	v_min_f32_e32 v21, 0, v21
	v_add_f32_e32 v22, 1.0, v22
	v_cndmask_b32_e64 v23, v24, v26, s[0:1]
	v_cmp_gt_f32_e64 s[0:1], s29, v22
	v_pk_mul_f32 v[18:19], v[18:19], s[6:7] op_sel_hi:[1,0]
	s_nop 0
	v_cndmask_b32_e64 v24, 0, 32, s[0:1]
	v_ldexp_f32 v22, v22, v24
	v_log_f32_e32 v24, v22
	v_cndmask_b32_e32 v22, 0, v111, vcc
	v_sub_f32_e32 v22, v23, v22
	v_mul_f32_e32 v23, 0x3f317217, v24
	v_fma_f32 v23, v24, s30, -v23
	v_fmac_f32_e32 v23, 0x3377d1cf, v24
	v_fmac_f32_e32 v23, 0x3f317217, v24
	v_cmp_lt_f32_e64 vcc, |v24|, s31
	s_nop 1
	v_cndmask_b32_e32 v23, v24, v23, vcc
	v_cndmask_b32_e64 v24, 0, v111, s[0:1]
	v_sub_f32_e32 v23, v23, v24
	v_pk_add_f32 v[20:21], v[20:21], v[22:23] neg_lo:[0,1] neg_hi:[0,1]
	s_nop 0
	v_pk_mul_f32 v[20:21], v[20:21], s[6:7] op_sel_hi:[1,0]
	v_cmp_ne_u32_e32 vcc, 63, v113
	v_cmp_gt_u32_e64 s[0:1], 62, v113
	s_nop 0
	v_addc_co_u32_e32 v22, vcc, 0, v112, vcc
	v_lshlrev_b32_e32 v22, 2, v22
	ds_bpermute_b32 v23, v22, v70
	ds_bpermute_b32 v24, v22, v71
	ds_bpermute_b32 v25, v22, v76
	ds_bpermute_b32 v26, v22, v77
	ds_bpermute_b32 v27, v22, v84
	ds_bpermute_b32 v28, v22, v85
	ds_bpermute_b32 v29, v22, v86
	ds_bpermute_b32 v30, v22, v87
	ds_bpermute_b32 v31, v22, v88
	ds_bpermute_b32 v32, v22, v89
	ds_bpermute_b32 v33, v22, v90
	ds_bpermute_b32 v34, v22, v91
	ds_bpermute_b32 v35, v22, v92
	ds_bpermute_b32 v36, v22, v93
	ds_bpermute_b32 v37, v22, v94
	ds_bpermute_b32 v38, v22, v95
	ds_bpermute_b32 v39, v22, v96
	ds_bpermute_b32 v40, v22, v97
	ds_bpermute_b32 v41, v22, v98
	ds_bpermute_b32 v42, v22, v99
	ds_bpermute_b32 v43, v22, v100
	ds_bpermute_b32 v44, v22, v101
	ds_bpermute_b32 v45, v22, v102
	ds_bpermute_b32 v46, v22, v103
	ds_bpermute_b32 v47, v22, v104
	ds_bpermute_b32 v48, v22, v105
	ds_bpermute_b32 v49, v22, v106
	ds_bpermute_b32 v50, v22, v107
	ds_bpermute_b32 v51, v22, v18
	ds_bpermute_b32 v52, v22, v19
	ds_bpermute_b32 v53, v22, v20
	ds_bpermute_b32 v22, v22, v21
	v_cmp_gt_i32_e32 vcc, 63, v68
	s_waitcnt lgkmcnt(6)
	v_add_f32_e32 v48, v105, v48
	v_add_f32_e32 v23, v70, v23
	v_add_f32_e32 v24, v71, v24
	s_waitcnt lgkmcnt(0)
	v_add_f32_e32 v22, v21, v22
	v_add_f32_e32 v25, v76, v25
	v_add_f32_e32 v26, v77, v26
	v_add_f32_e32 v27, v84, v27
	v_add_f32_e32 v28, v85, v28
	v_add_f32_e32 v29, v86, v29
	v_add_f32_e32 v30, v87, v30
	v_add_f32_e32 v31, v88, v31
	v_add_f32_e32 v32, v89, v32
	v_add_f32_e32 v33, v90, v33
	v_add_f32_e32 v34, v91, v34
	v_add_f32_e32 v35, v92, v35
	v_add_f32_e32 v36, v93, v36
	v_add_f32_e32 v37, v94, v37
	v_add_f32_e32 v38, v95, v38
	v_add_f32_e32 v39, v96, v39
	v_add_f32_e32 v40, v97, v40
	v_add_f32_e32 v41, v98, v41
	v_add_f32_e32 v42, v99, v42
	v_add_f32_e32 v43, v100, v43
	v_add_f32_e32 v44, v101, v44
	v_add_f32_e32 v45, v102, v45
	v_add_f32_e32 v46, v103, v46
	v_add_f32_e32 v47, v104, v47
	v_add_f32_e32 v49, v106, v49
	v_add_f32_e32 v50, v107, v50
	v_add_f32_e32 v51, v18, v51
	v_add_f32_e32 v52, v19, v52
	v_add_f32_e32 v53, v20, v53
	v_cndmask_b32_e32 v21, v21, v22, vcc
	v_cndmask_b32_e32 v22, v105, v48, vcc
	v_cndmask_b32_e64 v48, 0, 2, s[0:1]
	v_cndmask_b32_e32 v23, v70, v23, vcc
	v_cndmask_b32_e32 v25, v76, v25, vcc
	v_cndmask_b32_e32 v26, v77, v26, vcc
	v_cndmask_b32_e32 v28, v85, v28, vcc
	v_cndmask_b32_e32 v29, v86, v29, vcc
	v_cndmask_b32_e32 v31, v88, v31, vcc
	v_cndmask_b32_e32 v32, v89, v32, vcc
	v_cndmask_b32_e32 v34, v91, v34, vcc
	v_cndmask_b32_e32 v35, v92, v35, vcc
	v_cndmask_b32_e32 v37, v94, v37, vcc
	v_cndmask_b32_e32 v38, v95, v38, vcc
	v_cndmask_b32_e32 v40, v97, v40, vcc
	v_cndmask_b32_e32 v41, v98, v41, vcc
	v_cndmask_b32_e32 v43, v100, v43, vcc
	v_cndmask_b32_e32 v44, v101, v44, vcc
	v_cndmask_b32_e32 v46, v103, v46, vcc
	v_cndmask_b32_e32 v47, v104, v47, vcc
	v_cndmask_b32_e32 v49, v106, v49, vcc
	v_cndmask_b32_e32 v50, v107, v50, vcc
	v_cndmask_b32_e32 v52, v19, v52, vcc
	v_cndmask_b32_e32 v53, v20, v53, vcc
	v_cndmask_b32_e32 v18, v18, v51, vcc
	v_cndmask_b32_e32 v45, v102, v45, vcc
	v_cndmask_b32_e32 v42, v99, v42, vcc
	v_cndmask_b32_e32 v39, v96, v39, vcc
	v_cndmask_b32_e32 v36, v93, v36, vcc
	v_cndmask_b32_e32 v33, v90, v33, vcc
	v_add_lshl_u32 v48, v48, v112, 2
	v_cndmask_b32_e32 v30, v87, v30, vcc
	v_cndmask_b32_e32 v27, v84, v27, vcc
	v_cndmask_b32_e32 v24, v71, v24, vcc
	v_cndmask_b32_e32 v54, v70, v23, vcc
	v_cndmask_b32_e32 v55, v76, v25, vcc
	v_cndmask_b32_e32 v57, v85, v28, vcc
	v_cndmask_b32_e32 v58, v86, v29, vcc
	v_cndmask_b32_e32 v59, v88, v31, vcc
	v_cndmask_b32_e32 v60, v89, v32, vcc
	v_cndmask_b32_e32 v61, v91, v34, vcc
	v_cndmask_b32_e32 v62, v92, v35, vcc
	v_cndmask_b32_e32 v63, v94, v37, vcc
	v_cndmask_b32_e32 v64, v95, v38, vcc
	v_cndmask_b32_e32 v65, v97, v40, vcc
	v_cndmask_b32_e32 v70, v98, v41, vcc
	v_cndmask_b32_e32 v72, v100, v43, vcc
	v_cndmask_b32_e32 v73, v101, v44, vcc
	v_cndmask_b32_e32 v74, v103, v46, vcc
	v_cndmask_b32_e32 v75, v104, v47, vcc
	v_cndmask_b32_e32 v76, v106, v49, vcc
	ds_bpermute_b32 v51, v48, v23
	ds_bpermute_b32 v71, v48, v24
	ds_bpermute_b32 v78, v48, v25
	ds_bpermute_b32 v79, v48, v26
	ds_bpermute_b32 v80, v48, v27
	ds_bpermute_b32 v81, v48, v28
	ds_bpermute_b32 v82, v48, v29
	ds_bpermute_b32 v83, v48, v30
	ds_bpermute_b32 v84, v48, v31
	ds_bpermute_b32 v85, v48, v32
	ds_bpermute_b32 v86, v48, v33
	ds_bpermute_b32 v87, v48, v34
	ds_bpermute_b32 v88, v48, v35
	ds_bpermute_b32 v89, v48, v36
	ds_bpermute_b32 v90, v48, v37
	ds_bpermute_b32 v91, v48, v38
	ds_bpermute_b32 v92, v48, v39
	ds_bpermute_b32 v93, v48, v40
	ds_bpermute_b32 v94, v48, v41
	ds_bpermute_b32 v95, v48, v42
	ds_bpermute_b32 v96, v48, v43
	ds_bpermute_b32 v97, v48, v44
	ds_bpermute_b32 v98, v48, v45
	ds_bpermute_b32 v99, v48, v46
	ds_bpermute_b32 v100, v48, v47
	ds_bpermute_b32 v101, v48, v22
	ds_bpermute_b32 v102, v48, v49
	ds_bpermute_b32 v103, v48, v50
	ds_bpermute_b32 v104, v48, v18
	ds_bpermute_b32 v105, v48, v52
	ds_bpermute_b32 v106, v48, v53
	ds_bpermute_b32 v48, v48, v21
	v_cndmask_b32_e32 v56, v77, v26, vcc
	v_cndmask_b32_e32 v77, v107, v50, vcc
	v_cndmask_b32_e32 v19, v19, v52, vcc
	v_cndmask_b32_e32 v20, v20, v53, vcc
	v_cmp_gt_i32_e32 vcc, 62, v68
	s_waitcnt lgkmcnt(0)
	v_add_f32_e32 v48, v21, v48
	v_cmp_gt_u32_e64 s[0:1], 60, v113
	v_add_f32_e32 v51, v23, v51
	v_add_f32_e32 v71, v24, v71
	v_add_f32_e32 v78, v25, v78
	v_add_f32_e32 v79, v26, v79
	v_add_f32_e32 v80, v27, v80
	v_add_f32_e32 v81, v28, v81
	v_add_f32_e32 v82, v29, v82
	v_add_f32_e32 v83, v30, v83
	v_add_f32_e32 v84, v31, v84
	v_add_f32_e32 v85, v32, v85
	v_add_f32_e32 v86, v33, v86
	v_add_f32_e32 v87, v34, v87
	v_add_f32_e32 v88, v35, v88
	v_add_f32_e32 v89, v36, v89
	v_add_f32_e32 v90, v37, v90
	v_add_f32_e32 v91, v38, v91
	v_add_f32_e32 v92, v39, v92
	v_add_f32_e32 v93, v40, v93
	v_add_f32_e32 v94, v41, v94
	v_add_f32_e32 v95, v42, v95
	v_add_f32_e32 v96, v43, v96
	v_add_f32_e32 v97, v44, v97
	v_add_f32_e32 v98, v45, v98
	v_add_f32_e32 v99, v46, v99
	v_add_f32_e32 v100, v47, v100
	v_add_f32_e32 v101, v22, v101
	v_add_f32_e32 v102, v49, v102
	v_add_f32_e32 v103, v50, v103
	v_add_f32_e32 v104, v18, v104
	v_add_f32_e32 v105, v52, v105
	v_add_f32_e32 v106, v53, v106
	v_cndmask_b32_e32 v21, v21, v48, vcc
	v_cndmask_b32_e64 v48, 0, 4, s[0:1]
	v_cndmask_b32_e32 v23, v23, v51, vcc
	v_cndmask_b32_e32 v25, v25, v78, vcc
	v_cndmask_b32_e32 v26, v26, v79, vcc
	v_cndmask_b32_e32 v28, v28, v81, vcc
	v_cndmask_b32_e32 v29, v29, v82, vcc
	v_cndmask_b32_e32 v31, v31, v84, vcc
	v_cndmask_b32_e32 v32, v32, v85, vcc
	v_cndmask_b32_e32 v34, v34, v87, vcc
	v_cndmask_b32_e32 v35, v35, v88, vcc
	v_cndmask_b32_e32 v37, v37, v90, vcc
	v_cndmask_b32_e32 v38, v38, v91, vcc
	v_cndmask_b32_e32 v40, v40, v93, vcc
	v_cndmask_b32_e32 v41, v41, v94, vcc
	v_cndmask_b32_e32 v43, v43, v96, vcc
	v_cndmask_b32_e32 v44, v44, v97, vcc
	v_cndmask_b32_e32 v46, v46, v99, vcc
	v_cndmask_b32_e32 v47, v47, v100, vcc
	v_cndmask_b32_e32 v49, v49, v102, vcc
	v_cndmask_b32_e32 v50, v50, v103, vcc
	v_cndmask_b32_e32 v52, v52, v105, vcc
	v_cndmask_b32_e32 v53, v53, v106, vcc
	v_cndmask_b32_e32 v18, v18, v104, vcc
	v_cndmask_b32_e32 v22, v22, v101, vcc
	v_cndmask_b32_e32 v45, v45, v98, vcc
	v_cndmask_b32_e32 v42, v42, v95, vcc
	v_cndmask_b32_e32 v39, v39, v92, vcc
	v_cndmask_b32_e32 v36, v36, v89, vcc
	v_cndmask_b32_e32 v33, v33, v86, vcc
	v_add_lshl_u32 v48, v48, v112, 2
	v_cndmask_b32_e32 v30, v30, v83, vcc
	v_cndmask_b32_e32 v27, v27, v80, vcc
	v_cndmask_b32_e32 v24, v24, v71, vcc
	v_cndmask_b32_e32 v20, v20, v106, vcc
	v_cndmask_b32_e32 v19, v19, v105, vcc
	v_cndmask_b32_e32 v77, v77, v103, vcc
	v_cndmask_b32_e32 v76, v76, v102, vcc
	v_cndmask_b32_e32 v75, v75, v100, vcc
	v_cndmask_b32_e32 v74, v74, v99, vcc
	v_cndmask_b32_e32 v73, v73, v97, vcc
	v_cndmask_b32_e32 v72, v72, v96, vcc
	v_cndmask_b32_e32 v70, v70, v94, vcc
	v_cndmask_b32_e32 v65, v65, v93, vcc
	v_cndmask_b32_e32 v64, v64, v91, vcc
	v_cndmask_b32_e32 v63, v63, v90, vcc
	v_cndmask_b32_e32 v62, v62, v88, vcc
	v_cndmask_b32_e32 v61, v61, v87, vcc
	v_cndmask_b32_e32 v60, v60, v85, vcc
	v_cndmask_b32_e32 v59, v59, v84, vcc
	v_cndmask_b32_e32 v58, v58, v82, vcc
	v_cndmask_b32_e32 v57, v57, v81, vcc
	v_cndmask_b32_e32 v56, v56, v79, vcc
	v_cndmask_b32_e32 v55, v55, v78, vcc
	v_cndmask_b32_e32 v51, v54, v51, vcc
	ds_bpermute_b32 v54, v48, v23
	ds_bpermute_b32 v71, v48, v24
	ds_bpermute_b32 v78, v48, v25
	ds_bpermute_b32 v79, v48, v26
	ds_bpermute_b32 v80, v48, v27
	ds_bpermute_b32 v81, v48, v28
	ds_bpermute_b32 v82, v48, v29
	ds_bpermute_b32 v83, v48, v30
	ds_bpermute_b32 v84, v48, v31
	ds_bpermute_b32 v85, v48, v32
	ds_bpermute_b32 v86, v48, v33
	ds_bpermute_b32 v87, v48, v34
	ds_bpermute_b32 v88, v48, v35
	ds_bpermute_b32 v89, v48, v36
	ds_bpermute_b32 v90, v48, v37
	ds_bpermute_b32 v91, v48, v38
	ds_bpermute_b32 v92, v48, v39
	ds_bpermute_b32 v93, v48, v40
	ds_bpermute_b32 v94, v48, v41
	ds_bpermute_b32 v95, v48, v42
	ds_bpermute_b32 v96, v48, v43
	ds_bpermute_b32 v97, v48, v44
	ds_bpermute_b32 v98, v48, v45
	ds_bpermute_b32 v99, v48, v46
	ds_bpermute_b32 v100, v48, v47
	ds_bpermute_b32 v101, v48, v22
	ds_bpermute_b32 v102, v48, v49
	ds_bpermute_b32 v103, v48, v50
	ds_bpermute_b32 v104, v48, v18
	ds_bpermute_b32 v105, v48, v52
	ds_bpermute_b32 v106, v48, v53
	ds_bpermute_b32 v48, v48, v21
	v_cmp_gt_i32_e32 vcc, 60, v68
	v_cmp_gt_u32_e64 s[0:1], 56, v113
	s_waitcnt lgkmcnt(14)
	v_add_f32_e32 v54, v23, v54
	v_add_f32_e32 v71, v24, v71
	s_waitcnt lgkmcnt(0)
	v_add_f32_e32 v48, v21, v48
	v_cndmask_b32_e32 v21, v21, v48, vcc
	v_cndmask_b32_e64 v48, 0, 8, s[0:1]
	v_cndmask_b32_e32 v23, v23, v54, vcc
	v_add_f32_e32 v78, v25, v78
	v_add_f32_e32 v79, v26, v79
	v_add_f32_e32 v81, v28, v81
	v_add_f32_e32 v82, v29, v82
	v_add_f32_e32 v84, v31, v84
	v_add_f32_e32 v85, v32, v85
	v_add_f32_e32 v87, v34, v87
	v_add_f32_e32 v88, v35, v88
	v_add_f32_e32 v90, v37, v90
	v_add_f32_e32 v91, v38, v91
	v_add_f32_e32 v93, v40, v93
	v_add_f32_e32 v94, v41, v94
	v_add_f32_e32 v96, v43, v96
	v_add_f32_e32 v97, v44, v97
	v_add_f32_e32 v99, v46, v99
	v_add_f32_e32 v100, v47, v100
	v_add_f32_e32 v102, v49, v102
	v_add_f32_e32 v103, v50, v103
	v_cndmask_b32_e32 v24, v24, v71, vcc
	v_add_lshl_u32 v48, v48, v112, 2
	v_cndmask_b32_e32 v51, v51, v54, vcc
	v_cndmask_b32_e32 v54, v55, v78, vcc
	v_cndmask_b32_e32 v55, v56, v79, vcc
	v_cndmask_b32_e32 v56, v57, v81, vcc
	v_cndmask_b32_e32 v57, v58, v82, vcc
	v_cndmask_b32_e32 v58, v59, v84, vcc
	v_cndmask_b32_e32 v59, v60, v85, vcc
	v_cndmask_b32_e32 v60, v61, v87, vcc
	v_cndmask_b32_e32 v61, v62, v88, vcc
	v_cndmask_b32_e32 v62, v63, v90, vcc
	v_cndmask_b32_e32 v63, v64, v91, vcc
	v_cndmask_b32_e32 v64, v65, v93, vcc
	v_cndmask_b32_e32 v65, v70, v94, vcc
	v_cndmask_b32_e32 v70, v72, v96, vcc
	v_cndmask_b32_e32 v72, v73, v97, vcc
	v_cndmask_b32_e32 v73, v74, v99, vcc
	v_cndmask_b32_e32 v74, v75, v100, vcc
	v_cndmask_b32_e32 v75, v76, v102, vcc
	v_cndmask_b32_e32 v76, v77, v103, vcc
	ds_bpermute_b32 v71, v48, v23
	ds_bpermute_b32 v77, v48, v24
	v_add_f32_e32 v80, v27, v80
	v_cndmask_b32_e32 v25, v25, v78, vcc
	v_cndmask_b32_e32 v28, v28, v81, vcc
	v_cndmask_b32_e32 v29, v29, v82, vcc
	v_cndmask_b32_e32 v27, v27, v80, vcc
	v_cndmask_b32_e32 v26, v26, v79, vcc
	s_waitcnt lgkmcnt(1)
	v_add_f32_e32 v23, v23, v71
	s_waitcnt lgkmcnt(0)
	v_add_f32_e32 v71, v24, v77
	ds_bpermute_b32 v77, v48, v25
	ds_bpermute_b32 v79, v48, v27
	ds_bpermute_b32 v80, v48, v28
	ds_bpermute_b32 v81, v48, v29
	v_add_f32_e32 v86, v33, v86
	v_cndmask_b32_e32 v31, v31, v84, vcc
	v_cndmask_b32_e32 v32, v32, v85, vcc
	v_cndmask_b32_e32 v34, v34, v87, vcc
	v_cndmask_b32_e32 v33, v33, v86, vcc
	s_waitcnt lgkmcnt(3)
	v_add_f32_e32 v25, v25, v77
	s_waitcnt lgkmcnt(2)
	v_add_f32_e32 v77, v27, v79
	s_waitcnt lgkmcnt(1)
	v_add_f32_e32 v28, v28, v80
	s_waitcnt lgkmcnt(0)
	v_add_f32_e32 v29, v29, v81
	ds_bpermute_b32 v79, v48, v31
	ds_bpermute_b32 v80, v48, v32
	ds_bpermute_b32 v81, v48, v33
	ds_bpermute_b32 v82, v48, v34
	v_add_f32_e32 v89, v36, v89
	v_add_f32_e32 v92, v39, v92
	v_cndmask_b32_e32 v35, v35, v88, vcc
	v_cndmask_b32_e32 v37, v37, v90, vcc
	v_cndmask_b32_e32 v39, v39, v92, vcc
	v_cndmask_b32_e32 v36, v36, v89, vcc
	s_waitcnt lgkmcnt(3)
	v_add_f32_e32 v31, v31, v79
	s_waitcnt lgkmcnt(2)
	v_add_f32_e32 v32, v32, v80
	s_waitcnt lgkmcnt(1)
	v_add_f32_e32 v79, v33, v81
	s_waitcnt lgkmcnt(0)
	v_add_f32_e32 v34, v34, v82
	ds_bpermute_b32 v80, v48, v35
	ds_bpermute_b32 v81, v48, v36
	ds_bpermute_b32 v82, v48, v37
	ds_bpermute_b32 v84, v48, v39
	v_add_f32_e32 v95, v42, v95
	v_add_f32_e32 v83, v30, v83
	v_cndmask_b32_e32 v38, v38, v91, vcc
	v_cndmask_b32_e32 v40, v40, v93, vcc
	v_cndmask_b32_e32 v43, v43, v96, vcc
	v_cndmask_b32_e32 v44, v44, v97, vcc
	v_cndmask_b32_e32 v42, v42, v95, vcc
	v_cndmask_b32_e32 v30, v30, v83, vcc
	ds_bpermute_b32 v83, v48, v38
	s_waitcnt lgkmcnt(4)
	v_add_f32_e32 v35, v35, v80
	s_waitcnt lgkmcnt(3)
	v_add_f32_e32 v80, v36, v81
	s_waitcnt lgkmcnt(2)
	v_add_f32_e32 v37, v37, v82
	s_waitcnt lgkmcnt(1)
	v_add_f32_e32 v81, v39, v84
	ds_bpermute_b32 v82, v48, v40
	ds_bpermute_b32 v84, v48, v42
	ds_bpermute_b32 v85, v48, v43
	ds_bpermute_b32 v86, v48, v44
	v_add_f32_e32 v101, v22, v101
	v_cndmask_b32_e32 v41, v41, v94, vcc
	v_cndmask_b32_e32 v46, v46, v99, vcc
	v_cndmask_b32_e32 v47, v47, v100, vcc
	v_cndmask_b32_e32 v49, v49, v102, vcc
	v_cndmask_b32_e32 v22, v22, v101, vcc
	ds_bpermute_b32 v78, v48, v26
	s_waitcnt lgkmcnt(5)
	v_add_f32_e32 v38, v38, v83
	ds_bpermute_b32 v83, v48, v41
	s_waitcnt lgkmcnt(5)
	v_add_f32_e32 v40, v40, v82
	s_waitcnt lgkmcnt(4)
	v_add_f32_e32 v82, v42, v84
	s_waitcnt lgkmcnt(3)
	v_add_f32_e32 v43, v43, v85
	s_waitcnt lgkmcnt(2)
	v_add_f32_e32 v44, v44, v86
	ds_bpermute_b32 v84, v48, v46
	ds_bpermute_b32 v85, v48, v47
	ds_bpermute_b32 v86, v48, v22
	ds_bpermute_b32 v87, v48, v49
	v_add_f32_e32 v98, v45, v98
	v_add_f32_e32 v104, v18, v104
	v_add_f32_e32 v105, v52, v105
	v_add_f32_e32 v106, v53, v106
	v_cndmask_b32_e32 v50, v50, v103, vcc
	v_cndmask_b32_e32 v52, v52, v105, vcc
	v_cndmask_b32_e32 v53, v53, v106, vcc
	v_cndmask_b32_e32 v18, v18, v104, vcc
	v_cndmask_b32_e32 v45, v45, v98, vcc
	s_waitcnt lgkmcnt(5)
	v_add_f32_e32 v26, v26, v78
	ds_bpermute_b32 v78, v48, v30
	s_waitcnt lgkmcnt(5)
	v_add_f32_e32 v41, v41, v83
	ds_bpermute_b32 v83, v48, v45
	s_waitcnt lgkmcnt(5)
	v_add_f32_e32 v46, v46, v84
	s_waitcnt lgkmcnt(4)
	v_add_f32_e32 v47, v47, v85
	s_waitcnt lgkmcnt(3)
	v_add_f32_e32 v84, v22, v86
	s_waitcnt lgkmcnt(2)
	v_add_f32_e32 v49, v49, v87
	ds_bpermute_b32 v85, v48, v50
	ds_bpermute_b32 v86, v48, v18
	ds_bpermute_b32 v87, v48, v52
	ds_bpermute_b32 v88, v48, v53
	ds_bpermute_b32 v48, v48, v21
	v_cndmask_b32_e32 v19, v19, v105, vcc
	v_cndmask_b32_e32 v20, v20, v106, vcc
	s_waitcnt lgkmcnt(4)
	v_add_f32_e32 v50, v50, v85
	v_cmp_gt_i32_e32 vcc, 56, v68
	v_lshrrev_b32_e32 v255, 2, v115
	s_nop 0
	v_readfirstlane_b32 s101, v255
	s_nop 3
	s_waitcnt lgkmcnt(0)
	v_add_f32_e32 v48, v21, v48
	v_cmp_gt_u32_e64 s[0:1], 48, v113
	v_cndmask_b32_e32 v21, v21, v48, vcc
	v_cndmask_b32_e32 v48, v76, v50, vcc
	v_cndmask_b32_e64 v50, 0, 16, s[0:1]
	v_cndmask_b32_e32 v47, v74, v47, vcc
	v_cndmask_b32_e32 v40, v64, v40, vcc
	v_cndmask_b32_e32 v31, v58, v31, vcc
	v_cndmask_b32_e32 v23, v51, v23, vcc
	v_add_lshl_u32 v50, v50, v112, 2
	v_add_f32_e32 v52, v52, v87
	v_cndmask_b32_e32 v22, v22, v84, vcc
	v_cndmask_b32_e32 v44, v72, v44, vcc
	v_cndmask_b32_e32 v33, v33, v79, vcc
	v_cndmask_b32_e32 v32, v59, v32, vcc
	ds_bpermute_b32 v51, v50, v23
	v_cndmask_b32_e32 v24, v24, v71, vcc
	ds_bpermute_b32 v59, v50, v31
	ds_bpermute_b32 v72, v50, v40
	ds_bpermute_b32 v79, v50, v47
	v_cndmask_b32_e32 v19, v19, v52, vcc
	v_cndmask_b32_e32 v36, v36, v80, vcc
	ds_bpermute_b32 v52, v50, v24
	ds_bpermute_b32 v80, v50, v22
	v_cndmask_b32_e32 v28, v56, v28, vcc
	v_add_f32_e32 v78, v30, v78
	v_add_f32_e32 v83, v45, v83
	v_add_f32_e32 v85, v18, v86
	v_add_f32_e32 v53, v53, v88
	v_cndmask_b32_e32 v46, v73, v46, vcc
	v_cndmask_b32_e32 v43, v70, v43, vcc
	v_cndmask_b32_e32 v41, v65, v41, vcc
	v_cndmask_b32_e32 v29, v57, v29, vcc
	v_cndmask_b32_e32 v27, v27, v77, vcc
	v_cndmask_b32_e32 v26, v55, v26, vcc
	v_cndmask_b32_e32 v25, v54, v25, vcc
	ds_bpermute_b32 v56, v50, v28
	ds_bpermute_b32 v76, v50, v44
	v_cndmask_b32_e32 v20, v20, v53, vcc
	v_cndmask_b32_e32 v18, v18, v85, vcc
	v_cndmask_b32_e32 v49, v75, v49, vcc
	v_cndmask_b32_e32 v45, v45, v83, vcc
	v_cndmask_b32_e32 v42, v42, v82, vcc
	v_cndmask_b32_e32 v39, v39, v81, vcc
	v_cndmask_b32_e32 v38, v63, v38, vcc
	v_cndmask_b32_e32 v37, v62, v37, vcc
	v_cndmask_b32_e32 v35, v61, v35, vcc
	v_cndmask_b32_e32 v34, v60, v34, vcc
	v_cndmask_b32_e32 v30, v30, v78, vcc
	s_waitcnt lgkmcnt(7)
	v_add_f32_e32 v51, v23, v51
	ds_bpermute_b32 v53, v50, v25
	v_cmp_gt_i32_e32 vcc, 48, v68
	ds_bpermute_b32 v54, v50, v26
	ds_bpermute_b32 v55, v50, v27
	ds_bpermute_b32 v57, v50, v29
	ds_bpermute_b32 v60, v50, v32
	s_waitcnt lgkmcnt(11)
	v_add_f32_e32 v59, v31, v59
	ds_bpermute_b32 v73, v50, v41
	s_waitcnt lgkmcnt(11)
	v_add_f32_e32 v72, v40, v72
	ds_bpermute_b32 v75, v50, v43
	ds_bpermute_b32 v78, v50, v46
	s_waitcnt lgkmcnt(12)
	v_add_f32_e32 v79, v47, v79
	v_cndmask_b32_e32 v51, v23, v51, vcc
	s_waitcnt lgkmcnt(11)
	v_add_f32_e32 v52, v24, v52
	ds_bpermute_b32 v58, v50, v30
	ds_bpermute_b32 v61, v50, v33
	v_cndmask_b32_e32 v59, v31, v59, vcc
	v_cndmask_b32_e32 v72, v40, v72, vcc
	ds_bpermute_b32 v77, v50, v45
	v_cndmask_b32_e32 v79, v47, v79, vcc
	ds_bpermute_b32 v82, v50, v48
	s_waitcnt lgkmcnt(14)
	v_add_f32_e32 v80, v22, v80
	v_cndmask_b32_e32 v88, v23, v51, vcc
	v_cndmask_b32_e32 v93, v31, v59, vcc
	v_cndmask_b32_e32 v31, v40, v72, vcc
	v_cndmask_b32_e32 v23, v47, v79, vcc
	v_cndmask_b32_e32 v40, v22, v80, vcc
	v_cndmask_b32_e32 v47, v24, v52, vcc
	ds_bpermute_b32 v22, v114, v51
	ds_bpermute_b32 v24, v114, v47
	s_waitcnt lgkmcnt(15)
	v_add_f32_e32 v56, v28, v56
	s_waitcnt lgkmcnt(14)
	v_add_f32_e32 v76, v44, v76
	s_waitcnt lgkmcnt(13)
	v_add_f32_e32 v53, v25, v53
	s_waitcnt lgkmcnt(12)
	v_add_f32_e32 v54, v26, v54
	s_waitcnt lgkmcnt(11)
	v_add_f32_e32 v55, v27, v55
	v_cndmask_b32_e32 v56, v28, v56, vcc
	s_waitcnt lgkmcnt(10)
	v_add_f32_e32 v57, v29, v57
	ds_bpermute_b32 v62, v50, v34
	s_waitcnt lgkmcnt(10)
	v_add_f32_e32 v60, v32, v60
	ds_bpermute_b32 v63, v50, v35
	s_waitcnt lgkmcnt(10)
	v_add_f32_e32 v73, v41, v73
	s_waitcnt lgkmcnt(9)
	v_add_f32_e32 v75, v43, v75
	v_cndmask_b32_e32 v76, v44, v76, vcc
	s_waitcnt lgkmcnt(8)
	v_add_f32_e32 v78, v46, v78
	ds_bpermute_b32 v81, v50, v49
	v_cndmask_b32_e32 v53, v25, v53, vcc
	v_cndmask_b32_e32 v54, v26, v54, vcc
	v_cndmask_b32_e32 v57, v29, v57, vcc
	s_waitcnt lgkmcnt(8)
	v_add_f32_e32 v58, v30, v58
	v_cndmask_b32_e32 v60, v32, v60, vcc
	s_waitcnt lgkmcnt(7)
	v_add_f32_e32 v61, v33, v61
	v_cndmask_b32_e32 v73, v41, v73, vcc
	v_cndmask_b32_e32 v75, v43, v75, vcc
	s_waitcnt lgkmcnt(6)
	v_add_f32_e32 v77, v45, v77
	v_cndmask_b32_e32 v78, v46, v78, vcc
	s_waitcnt lgkmcnt(5)
	v_add_f32_e32 v82, v48, v82
	v_cndmask_b32_e32 v90, v28, v56, vcc
	v_cndmask_b32_e32 v28, v44, v76, vcc
	v_cndmask_b32_e32 v44, v27, v55, vcc
	ds_bpermute_b32 v64, v50, v36
	ds_bpermute_b32 v65, v50, v37
	ds_bpermute_b32 v70, v50, v38
	ds_bpermute_b32 v71, v50, v39
	ds_bpermute_b32 v74, v50, v42
	ds_bpermute_b32 v83, v50, v18
	ds_bpermute_b32 v84, v50, v19
	v_cndmask_b32_e32 v82, v48, v82, vcc
	ds_bpermute_b32 v85, v50, v20
	ds_bpermute_b32 v50, v50, v21
	v_cndmask_b32_e32 v86, v26, v54, vcc
	v_cndmask_b32_e32 v89, v29, v57, vcc
	v_cndmask_b32_e32 v92, v32, v60, vcc
	v_cndmask_b32_e32 v32, v41, v73, vcc
	v_cndmask_b32_e32 v29, v46, v78, vcc
	v_cndmask_b32_e32 v26, v43, v75, vcc
	v_cndmask_b32_e32 v41, v45, v77, vcc
	v_cndmask_b32_e32 v43, v33, v61, vcc
	v_cndmask_b32_e32 v45, v30, v58, vcc
	s_waitcnt lgkmcnt(13)
	v_add_f32_e32 v46, v51, v22
	ds_bpermute_b32 v22, v114, v53
	ds_bpermute_b32 v27, v114, v44
	ds_bpermute_b32 v30, v114, v56
	ds_bpermute_b32 v33, v114, v57
	v_cndmask_b32_e32 v87, v25, v53, vcc
	v_cndmask_b32_e32 v25, v48, v82, vcc
	s_waitcnt lgkmcnt(15)
	v_add_f32_e32 v48, v47, v24
	ds_bpermute_b32 v24, v114, v54
	s_waitcnt lgkmcnt(15)
	v_add_f32_e32 v62, v34, v62
	s_waitcnt lgkmcnt(15)
	v_add_f32_e32 v63, v35, v63
	s_waitcnt lgkmcnt(14)
	v_add_f32_e32 v81, v49, v81
	v_cndmask_b32_e32 v62, v34, v62, vcc
	v_cndmask_b32_e32 v63, v35, v63, vcc
	v_cndmask_b32_e32 v81, v49, v81, vcc
	s_waitcnt lgkmcnt(5)
	v_add_f32_e32 v50, v21, v50
	v_cndmask_b32_e32 v91, v34, v62, vcc
	v_cndmask_b32_e32 v34, v35, v63, vcc
	v_cndmask_b32_e32 v35, v49, v81, vcc
	s_waitcnt lgkmcnt(4)
	v_add_f32_e32 v49, v53, v22
	s_waitcnt lgkmcnt(3)
	v_add_f32_e32 v51, v44, v27
	s_waitcnt lgkmcnt(2)
	v_add_f32_e32 v52, v56, v30
	s_waitcnt lgkmcnt(1)
	v_add_f32_e32 v53, v57, v33
	ds_bpermute_b32 v22, v114, v45
	ds_bpermute_b32 v27, v114, v60
	ds_bpermute_b32 v30, v114, v43
	ds_bpermute_b32 v33, v114, v62
	v_cndmask_b32_e32 v21, v21, v50, vcc
	s_waitcnt lgkmcnt(4)
	v_add_f32_e32 v50, v54, v24
	ds_bpermute_b32 v24, v114, v59
	v_add_f32_e32 v65, v37, v65
	v_add_f32_e32 v70, v38, v70
	v_add_f32_e32 v71, v39, v71
	v_add_f32_e32 v64, v36, v64
	v_cndmask_b32_e32 v65, v37, v65, vcc
	v_cndmask_b32_e32 v70, v38, v70, vcc
	v_cndmask_b32_e32 v39, v39, v71, vcc
	v_cndmask_b32_e32 v36, v36, v64, vcc
	s_waitcnt lgkmcnt(4)
	v_add_f32_e32 v54, v45, v22
	s_waitcnt lgkmcnt(3)
	v_add_f32_e32 v56, v60, v27
	s_waitcnt lgkmcnt(2)
	v_add_f32_e32 v57, v43, v30
	s_waitcnt lgkmcnt(1)
	v_add_f32_e32 v58, v62, v33
	ds_bpermute_b32 v22, v114, v63
	ds_bpermute_b32 v27, v114, v65
	ds_bpermute_b32 v30, v114, v70
	ds_bpermute_b32 v33, v114, v39
	s_waitcnt lgkmcnt(4)
	v_add_f32_e32 v55, v59, v24
	ds_bpermute_b32 v24, v114, v36
	v_add_f32_e32 v74, v42, v74
	v_cndmask_b32_e32 v42, v42, v74, vcc
	s_waitcnt lgkmcnt(4)
	v_add_f32_e32 v59, v63, v22
	s_waitcnt lgkmcnt(3)
	v_add_f32_e32 v61, v65, v27
	s_waitcnt lgkmcnt(2)
	v_add_f32_e32 v62, v70, v30
	s_waitcnt lgkmcnt(1)
	v_add_f32_e32 v30, v39, v33
	ds_bpermute_b32 v22, v114, v72
	ds_bpermute_b32 v27, v114, v42
	ds_bpermute_b32 v33, v114, v75
	ds_bpermute_b32 v63, v114, v76
	s_waitcnt lgkmcnt(4)
	v_add_f32_e32 v60, v36, v24
	ds_bpermute_b32 v24, v114, v73
	v_cndmask_b32_e32 v38, v38, v70, vcc
	s_waitcnt lgkmcnt(4)
	v_add_f32_e32 v64, v72, v22
	s_waitcnt lgkmcnt(3)
	v_add_f32_e32 v70, v42, v27
	s_waitcnt lgkmcnt(2)
	v_add_f32_e32 v27, v75, v33
	s_waitcnt lgkmcnt(1)
	v_add_f32_e32 v33, v76, v63
	ds_bpermute_b32 v22, v114, v41
	ds_bpermute_b32 v63, v114, v79
	ds_bpermute_b32 v72, v114, v81
	v_cndmask_b32_e32 v37, v37, v65, vcc
	s_waitcnt lgkmcnt(3)
	v_add_f32_e32 v65, v73, v24
	ds_bpermute_b32 v24, v114, v78
	ds_bpermute_b32 v71, v114, v40
	s_lshl_b32 s1, s38, 3
	v_add_f32_e32 v83, v18, v83
	v_add_f32_e32 v84, v19, v84
	v_add_f32_e32 v85, v20, v85
	s_or_b32 s1, s36, s1
	v_cndmask_b32_e32 v84, v19, v84, vcc
	v_cndmask_b32_e32 v85, v20, v85, vcc
	v_cndmask_b32_e32 v18, v18, v83, vcc
	s_or_b32 s2, s1, 4
	v_cndmask_b32_e32 v20, v20, v85, vcc
	v_cndmask_b32_e32 v19, v19, v84, vcc
	s_waitcnt lgkmcnt(4)
	v_add_f32_e32 v73, v41, v22
	s_waitcnt lgkmcnt(3)
	v_add_f32_e32 v22, v79, v63
	s_waitcnt lgkmcnt(2)
	v_add_f32_e32 v63, v81, v72
	ds_bpermute_b32 v72, v114, v18
	ds_bpermute_b32 v75, v114, v84
	ds_bpermute_b32 v76, v114, v85
	ds_bpermute_b32 v77, v114, v21
	v_cmp_gt_i32_e32 vcc, 32, v68
	s_sub_i32 s0, 0x103, s14
	s_mul_hi_i32 s1, s2, 0x104
	s_mulk_i32 s2, 0x104
	s_waitcnt lgkmcnt(5)
	v_add_f32_e32 v74, v78, v24
	s_waitcnt lgkmcnt(4)
	v_add_f32_e32 v24, v40, v71
	ds_bpermute_b32 v71, v114, v82
	v_cndmask_b32_e32 v46, v88, v46, vcc
	s_add_u32 s12, s2, s37
	v_cndmask_b32_e32 v22, v23, v22, vcc
	v_cndmask_b32_e32 v23, v40, v24, vcc
	v_cndmask_b32_e32 v40, v43, v57, vcc
	v_cndmask_b32_e32 v43, v90, v52, vcc
	s_addc_u32 s13, s1, 0
	v_readlane_b32 s98, v46, s101
	s_lshl_b64 s[12:13], s[12:13], 13
	s_add_u32 s12, s19, s12
	s_waitcnt lgkmcnt(4)
	v_add_f32_e32 v72, v18, v72
	s_waitcnt lgkmcnt(3)
	v_add_f32_e32 v75, v84, v75
	s_waitcnt lgkmcnt(2)
	v_add_f32_e32 v76, v85, v76
	s_waitcnt lgkmcnt(1)
	v_add_f32_e32 v77, v21, v77
	v_cndmask_b32_e32 v26, v26, v27, vcc
	v_cndmask_b32_e32 v27, v28, v33, vcc
	v_cndmask_b32_e32 v33, v42, v70, vcc
	v_cndmask_b32_e32 v42, v44, v51, vcc
	v_cndmask_b32_e32 v47, v47, v48, vcc
	v_cndmask_b32_e32 v48, v87, v49, vcc
	v_cndmask_b32_e32 v49, v86, v50, vcc
	s_addc_u32 s13, s22, s13
	v_lshlrev_b64 v[50:51], 7, v[68:69]
	s_waitcnt lgkmcnt(0)
	v_add_f32_e32 v71, v82, v71
	v_cndmask_b32_e32 v18, v18, v72, vcc
	v_cndmask_b32_e32 v19, v19, v75, vcc
	v_cndmask_b32_e32 v20, v20, v76, vcc
	v_cndmask_b32_e32 v21, v21, v77, vcc
	v_cndmask_b32_e32 v24, v35, v63, vcc
	v_cndmask_b32_e32 v34, v34, v59, vcc
	v_cndmask_b32_e32 v35, v36, v60, vcc
	v_cndmask_b32_e32 v36, v37, v61, vcc
	v_cndmask_b32_e32 v37, v38, v62, vcc
	v_lshl_add_u64 v[50:51], s[12:13], 0, v[50:51]
	v_cndmask_b32_e32 v25, v25, v71, vcc
	v_cndmask_b32_e32 v28, v41, v73, vcc
	v_cndmask_b32_e32 v29, v29, v74, vcc
	v_cndmask_b32_e32 v30, v39, v30, vcc
	v_cndmask_b32_e32 v31, v31, v64, vcc
	v_cndmask_b32_e32 v32, v32, v65, vcc
	v_cndmask_b32_e32 v38, v93, v55, vcc
	v_cndmask_b32_e32 v39, v92, v56, vcc
	v_cndmask_b32_e32 v41, v91, v58, vcc
	v_cndmask_b32_e32 v44, v89, v53, vcc
	v_cndmask_b32_e32 v45, v45, v54, vcc
	global_store_dwordx4 v[50:51], v[46:49], off
	global_store_dwordx4 v[50:51], v[42:45], off offset:16
	global_store_dwordx4 v[50:51], v[38:41], off offset:32
	global_store_dwordx4 v[50:51], v[34:37], off offset:48
	global_store_dwordx4 v[50:51], v[30:33], off offset:64
	global_store_dwordx4 v[50:51], v[26:29], off offset:80
	global_store_dwordx4 v[50:51], v[22:25], off offset:96
	v_sub_f32_e32 v52, s98, v46
	global_store_dwordx4 v[50:51], v[18:21], off offset:112
	v_readlane_b32 s98, v47, s101
	v_mul_f32_e32 v52, 0x3fb8aa3b, v52
	v_exp_f32_e32 v52, v52
	v_lshlrev_b32_e32 v51, 16, v14
	v_and_b32_e32 v14, 0xffff0000, v14
	v_sub_f32_e32 v50, s98, v47
	v_mul_f32_e32 v51, v52, v51
	v_mul_f32_e32 v50, 0x3fb8aa3b, v50
	v_bfe_u32 v52, v51, 16, 1
	v_exp_f32_e32 v50, v50
	v_add3_u32 v51, v51, v52, s34
	ds_write_b16_d16_hi v66, v51 offset:8192
	v_readlane_b32 s98, v48, s101
	v_mul_f32_e32 v14, v50, v14
	v_bfe_u32 v50, v14, 16, 1
	v_add3_u32 v14, v14, v50, s34
	ds_write_b16_d16_hi v66, v14 offset:8320
	v_sub_f32_e32 v50, s98, v48
	v_readlane_b32 s98, v49, s101
	v_mul_f32_e32 v50, 0x3fb8aa3b, v50
	v_exp_f32_e32 v50, v50
	v_lshlrev_b32_e32 v51, 16, v15
	v_and_b32_e32 v15, 0xffff0000, v15
	v_sub_f32_e32 v14, s98, v49
	v_mul_f32_e32 v50, v50, v51
	v_mul_f32_e32 v14, 0x3fb8aa3b, v14
	v_bfe_u32 v51, v50, 16, 1
	v_exp_f32_e32 v14, v14
	v_add3_u32 v50, v50, v51, s34
	ds_write_b16_d16_hi v66, v50 offset:8448
	v_readlane_b32 s98, v42, s101
	v_mul_f32_e32 v14, v14, v15
	v_bfe_u32 v15, v14, 16, 1
	v_add3_u32 v14, v14, v15, s34
	ds_write_b16_d16_hi v66, v14 offset:8576
	v_sub_f32_e32 v15, s98, v42
	v_readlane_b32 s98, v43, s101
	v_mul_f32_e32 v15, 0x3fb8aa3b, v15
	v_exp_f32_e32 v15, v15
	v_lshlrev_b32_e32 v50, 16, v16
	v_and_b32_e32 v16, 0xffff0000, v16
	v_sub_f32_e32 v14, s98, v43
	v_mul_f32_e32 v15, v15, v50
	v_mul_f32_e32 v14, 0x3fb8aa3b, v14
	v_bfe_u32 v50, v15, 16, 1
	v_exp_f32_e32 v14, v14
	v_add3_u32 v15, v15, v50, s34
	ds_write_b16_d16_hi v66, v15 offset:8704
	v_readlane_b32 s98, v44, s101
	v_mul_f32_e32 v14, v14, v16
	v_bfe_u32 v16, v14, 16, 1
	v_add3_u32 v14, v14, v16, s34
	ds_write_b16_d16_hi v66, v14 offset:8832
	v_sub_f32_e32 v15, s98, v44
	v_readlane_b32 s98, v45, s101
	v_mul_f32_e32 v15, 0x3fb8aa3b, v15
	v_exp_f32_e32 v15, v15
	v_lshlrev_b32_e32 v16, 16, v17
	s_add_u32 s0, s2, s0
	v_sub_f32_e32 v14, s98, v45
	v_mul_f32_e32 v15, v15, v16
	v_mul_f32_e32 v14, 0x3fb8aa3b, v14
	v_bfe_u32 v16, v15, 16, 1
	v_exp_f32_e32 v14, v14
	v_add3_u32 v15, v15, v16, s34
	ds_write_b16_d16_hi v66, v15 offset:8960
	v_readlane_b32 s98, v38, s101
	v_and_b32_e32 v16, 0xffff0000, v17
	v_mul_f32_e32 v14, v14, v16
	v_bfe_u32 v16, v14, 16, 1
	v_add3_u32 v14, v14, v16, s34
	v_sub_f32_e32 v15, s98, v38
	ds_write_b16_d16_hi v66, v14 offset:9088
	v_readlane_b32 s98, v39, s101
	v_mul_f32_e32 v15, 0x3fb8aa3b, v15
	v_exp_f32_e32 v15, v15
	v_lshlrev_b32_e32 v16, 16, v10
	v_and_b32_e32 v10, 0xffff0000, v10
	v_sub_f32_e32 v14, s98, v39
	v_mul_f32_e32 v15, v15, v16
	v_mul_f32_e32 v14, 0x3fb8aa3b, v14
	v_bfe_u32 v16, v15, 16, 1
	v_exp_f32_e32 v14, v14
	v_add3_u32 v15, v15, v16, s34
	ds_write_b16_d16_hi v66, v15 offset:9216
	v_readlane_b32 s98, v40, s101
	v_mul_f32_e32 v10, v14, v10
	v_bfe_u32 v14, v10, 16, 1
	v_add3_u32 v10, v10, v14, s34
	ds_write_b16_d16_hi v66, v10 offset:9344
	v_sub_f32_e32 v14, s98, v40
	v_readlane_b32 s98, v41, s101
	v_mul_f32_e32 v14, 0x3fb8aa3b, v14
	v_exp_f32_e32 v14, v14
	v_lshlrev_b32_e32 v15, 16, v11
	v_and_b32_e32 v11, 0xffff0000, v11
	v_sub_f32_e32 v10, s98, v41
	v_mul_f32_e32 v14, v14, v15
	v_mul_f32_e32 v10, 0x3fb8aa3b, v10
	v_bfe_u32 v15, v14, 16, 1
	v_exp_f32_e32 v10, v10
	v_add3_u32 v14, v14, v15, s34
	ds_write_b16_d16_hi v66, v14 offset:9472
	v_readlane_b32 s98, v34, s101
	v_mul_f32_e32 v10, v10, v11
	v_bfe_u32 v11, v10, 16, 1
	v_add3_u32 v10, v10, v11, s34
	ds_write_b16_d16_hi v66, v10 offset:9600
	v_sub_f32_e32 v11, s98, v34
	v_readlane_b32 s98, v35, s101
	v_mul_f32_e32 v11, 0x3fb8aa3b, v11
	v_exp_f32_e32 v11, v11
	v_lshlrev_b32_e32 v14, 16, v12
	v_and_b32_e32 v12, 0xffff0000, v12
	v_sub_f32_e32 v10, s98, v35
	v_mul_f32_e32 v11, v11, v14
	v_mul_f32_e32 v10, 0x3fb8aa3b, v10
	v_bfe_u32 v14, v11, 16, 1
	v_exp_f32_e32 v10, v10
	v_add3_u32 v11, v11, v14, s34
	ds_write_b16_d16_hi v66, v11 offset:9728
	v_readlane_b32 s98, v36, s101
	v_mul_f32_e32 v10, v10, v12
	v_bfe_u32 v12, v10, 16, 1
	v_add3_u32 v10, v10, v12, s34
	ds_write_b16_d16_hi v66, v10 offset:9856
	v_sub_f32_e32 v11, s98, v36
	v_readlane_b32 s98, v37, s101
	v_mul_f32_e32 v11, 0x3fb8aa3b, v11
	v_exp_f32_e32 v11, v11
	v_lshlrev_b32_e32 v12, 16, v13
	s_addc_u32 s1, s1, 0
	v_sub_f32_e32 v10, s98, v37
	v_mul_f32_e32 v11, v11, v12
	v_mul_f32_e32 v10, 0x3fb8aa3b, v10
	v_bfe_u32 v12, v11, 16, 1
	v_exp_f32_e32 v10, v10
	v_add3_u32 v11, v11, v12, s34
	ds_write_b16_d16_hi v66, v11 offset:9984
	v_readlane_b32 s98, v30, s101
	v_and_b32_e32 v12, 0xffff0000, v13
	v_mul_f32_e32 v10, v10, v12
	v_bfe_u32 v12, v10, 16, 1
	v_add3_u32 v10, v10, v12, s34
	v_sub_f32_e32 v11, s98, v30
	ds_write_b16_d16_hi v66, v10 offset:10112
	v_readlane_b32 s98, v31, s101
	v_mul_f32_e32 v11, 0x3fb8aa3b, v11
	v_exp_f32_e32 v11, v11
	v_lshlrev_b32_e32 v12, 16, v6
	v_and_b32_e32 v6, 0xffff0000, v6
	v_sub_f32_e32 v10, s98, v31
	v_mul_f32_e32 v11, v11, v12
	v_mul_f32_e32 v10, 0x3fb8aa3b, v10
	v_bfe_u32 v12, v11, 16, 1
	v_exp_f32_e32 v10, v10
	v_add3_u32 v11, v11, v12, s34
	ds_write_b16_d16_hi v66, v11 offset:10240
	v_readlane_b32 s98, v32, s101
	v_mul_f32_e32 v6, v10, v6
	v_bfe_u32 v10, v6, 16, 1
	v_add3_u32 v6, v6, v10, s34
	ds_write_b16_d16_hi v66, v6 offset:10368
	v_sub_f32_e32 v10, s98, v32
	v_readlane_b32 s98, v33, s101
	v_mul_f32_e32 v10, 0x3fb8aa3b, v10
	v_exp_f32_e32 v10, v10
	v_lshlrev_b32_e32 v11, 16, v7
	v_and_b32_e32 v7, 0xffff0000, v7
	v_sub_f32_e32 v6, s98, v33
	v_mul_f32_e32 v10, v10, v11
	v_mul_f32_e32 v6, 0x3fb8aa3b, v6
	v_bfe_u32 v11, v10, 16, 1
	v_exp_f32_e32 v6, v6
	v_add3_u32 v10, v10, v11, s34
	ds_write_b16_d16_hi v66, v10 offset:10496
	v_readlane_b32 s98, v26, s101
	v_mul_f32_e32 v6, v6, v7
	v_bfe_u32 v7, v6, 16, 1
	v_add3_u32 v6, v6, v7, s34
	ds_write_b16_d16_hi v66, v6 offset:10624
	v_sub_f32_e32 v7, s98, v26
	v_readlane_b32 s98, v27, s101
	v_mul_f32_e32 v7, 0x3fb8aa3b, v7
	v_exp_f32_e32 v7, v7
	v_lshlrev_b32_e32 v10, 16, v8
	v_and_b32_e32 v8, 0xffff0000, v8
	v_sub_f32_e32 v6, s98, v27
	v_mul_f32_e32 v7, v7, v10
	v_mul_f32_e32 v6, 0x3fb8aa3b, v6
	v_bfe_u32 v10, v7, 16, 1
	v_exp_f32_e32 v6, v6
	v_add3_u32 v7, v7, v10, s34
	ds_write_b16_d16_hi v66, v7 offset:10752
	v_readlane_b32 s98, v28, s101
	v_mul_f32_e32 v6, v6, v8
	v_bfe_u32 v8, v6, 16, 1
	v_add3_u32 v6, v6, v8, s34
	ds_write_b16_d16_hi v66, v6 offset:10880
	v_sub_f32_e32 v7, s98, v28
	v_readlane_b32 s98, v29, s101
	v_mul_f32_e32 v7, 0x3fb8aa3b, v7
	v_exp_f32_e32 v7, v7
	v_lshlrev_b32_e32 v8, 16, v9
	v_cmp_eq_u32_e32 vcc, 0, v68
	v_sub_f32_e32 v6, s98, v29
	v_mul_f32_e32 v7, v7, v8
	v_mul_f32_e32 v6, 0x3fb8aa3b, v6
	v_bfe_u32 v8, v7, 16, 1
	v_exp_f32_e32 v6, v6
	v_add3_u32 v7, v7, v8, s34
	ds_write_b16_d16_hi v66, v7 offset:11008
	v_readlane_b32 s98, v22, s101
	v_and_b32_e32 v8, 0xffff0000, v9
	v_mul_f32_e32 v6, v6, v8
	v_bfe_u32 v8, v6, 16, 1
	v_add3_u32 v6, v6, v8, s34
	v_sub_f32_e32 v7, s98, v22
	ds_write_b16_d16_hi v66, v6 offset:11136
	v_readlane_b32 s98, v23, s101
	v_mul_f32_e32 v7, 0x3fb8aa3b, v7
	v_exp_f32_e32 v7, v7
	v_lshlrev_b32_e32 v8, 16, v2
	v_and_b32_e32 v2, 0xffff0000, v2
	v_sub_f32_e32 v6, s98, v23
	v_mul_f32_e32 v7, v7, v8
	v_mul_f32_e32 v6, 0x3fb8aa3b, v6
	v_bfe_u32 v8, v7, 16, 1
	v_exp_f32_e32 v6, v6
	v_add3_u32 v7, v7, v8, s34
	ds_write_b16_d16_hi v66, v7 offset:11264
	v_readlane_b32 s98, v24, s101
	v_mul_f32_e32 v2, v6, v2
	v_bfe_u32 v6, v2, 16, 1
	v_add3_u32 v2, v2, v6, s34
	ds_write_b16_d16_hi v66, v2 offset:11392
	v_sub_f32_e32 v6, s98, v24
	v_readlane_b32 s98, v25, s101
	v_mul_f32_e32 v6, 0x3fb8aa3b, v6
	v_exp_f32_e32 v6, v6
	v_lshlrev_b32_e32 v7, 16, v3
	v_and_b32_e32 v3, 0xffff0000, v3
	v_sub_f32_e32 v2, s98, v25
	v_mul_f32_e32 v6, v6, v7
	v_mul_f32_e32 v2, 0x3fb8aa3b, v2
	v_bfe_u32 v7, v6, 16, 1
	v_exp_f32_e32 v2, v2
	v_add3_u32 v6, v6, v7, s34
	ds_write_b16_d16_hi v66, v6 offset:11520
	v_readlane_b32 s98, v18, s101
	v_mul_f32_e32 v2, v2, v3
	v_bfe_u32 v3, v2, 16, 1
	v_add3_u32 v2, v2, v3, s34
	ds_write_b16_d16_hi v66, v2 offset:11648
	v_sub_f32_e32 v3, s98, v18
	v_readlane_b32 s98, v19, s101
	v_mul_f32_e32 v3, 0x3fb8aa3b, v3
	v_exp_f32_e32 v3, v3
	v_lshlrev_b32_e32 v6, 16, v4
	v_and_b32_e32 v4, 0xffff0000, v4
	v_sub_f32_e32 v2, s98, v19
	v_mul_f32_e32 v3, v3, v6
	v_mul_f32_e32 v2, 0x3fb8aa3b, v2
	v_bfe_u32 v6, v3, 16, 1
	v_exp_f32_e32 v2, v2
	v_add3_u32 v3, v3, v6, s34
	ds_write_b16_d16_hi v66, v3 offset:11776
	v_readlane_b32 s98, v20, s101
	v_mul_f32_e32 v2, v2, v4
	v_bfe_u32 v4, v2, 16, 1
	v_add3_u32 v2, v2, v4, s34
	v_readlane_b32 s99, v21, s101
	v_sub_f32_e32 v3, s98, v20
	v_mul_f32_e32 v3, 0x3fb8aa3b, v3
	v_exp_f32_e32 v3, v3
	ds_write_b16_d16_hi v66, v2 offset:11904
	v_sub_f32_e32 v4, s99, v21
	v_lshlrev_b32_e32 v2, 16, v5
	v_mul_f32_e32 v4, 0x3fb8aa3b, v4
	v_mul_f32_e32 v2, v3, v2
	v_exp_f32_e32 v4, v4
	v_bfe_u32 v3, v2, 16, 1
	v_add3_u32 v2, v2, v3, s34
	ds_write_b16_d16_hi v66, v2 offset:12032
	v_and_b32_e32 v2, 0xffff0000, v5
	v_mul_f32_e32 v2, v4, v2
	v_bfe_u32 v3, v2, 16, 1
	v_add3_u32 v2, v2, v3, s34
	ds_write_b16_d16_hi v66, v2 offset:12160
	s_and_saveexec_b64 s[12:13], vcc
	s_cbranch_execz .LBB0_706
	v_mul_f32_e32 v2, 0x3fb8aa3b, v46
	v_mul_f32_e32 v3, 0x3fb8aa3b, v47
	v_mul_f32_e32 v4, 0x3fb8aa3b, v48
	v_mul_f32_e32 v5, 0x3fb8aa3b, v49
	v_exp_f32_e32 v2, v2
	v_exp_f32_e32 v3, v3
	v_exp_f32_e32 v4, v4
	v_exp_f32_e32 v5, v5
	v_mul_f32_e32 v6, 0x3fb8aa3b, v42
	v_mul_f32_e32 v7, 0x3fb8aa3b, v43
	v_mul_f32_e32 v8, 0x3fb8aa3b, v44
	v_mul_f32_e32 v9, 0x3fb8aa3b, v45
	s_lshl_b64 s[14:15], s[0:1], 7
	v_exp_f32_e32 v6, v6
	v_exp_f32_e32 v7, v7
	v_exp_f32_e32 v8, v8
	v_exp_f32_e32 v9, v9
	v_mul_f32_e32 v10, 0x3fb8aa3b, v38
	v_mul_f32_e32 v11, 0x3fb8aa3b, v39
	v_mul_f32_e32 v12, 0x3fb8aa3b, v40
	v_mul_f32_e32 v13, 0x3fb8aa3b, v41
	s_add_u32 s14, s23, s14
	v_exp_f32_e32 v10, v10
	v_exp_f32_e32 v11, v11
	v_exp_f32_e32 v12, v12
	v_exp_f32_e32 v13, v13
	v_mul_f32_e32 v14, 0x3fb8aa3b, v34
	v_mul_f32_e32 v15, 0x3fb8aa3b, v35
	v_mul_f32_e32 v16, 0x3fb8aa3b, v36
	v_mul_f32_e32 v17, 0x3fb8aa3b, v37
	s_addc_u32 s15, s24, s15
	v_exp_f32_e32 v14, v14
	v_exp_f32_e32 v15, v15
	v_exp_f32_e32 v16, v16
	v_exp_f32_e32 v17, v17
	global_store_dwordx4 v67, v[2:5], s[14:15]
	global_store_dwordx4 v67, v[6:9], s[14:15] offset:16
	global_store_dwordx4 v67, v[10:13], s[14:15] offset:32
	global_store_dwordx4 v67, v[14:17], s[14:15] offset:48
	v_mul_f32_e32 v2, 0x3fb8aa3b, v30
	v_mul_f32_e32 v3, 0x3fb8aa3b, v31
	v_mul_f32_e32 v4, 0x3fb8aa3b, v32
	v_mul_f32_e32 v5, 0x3fb8aa3b, v33
	v_exp_f32_e32 v2, v2
	v_exp_f32_e32 v3, v3
	v_exp_f32_e32 v4, v4
	v_exp_f32_e32 v5, v5
	v_mul_f32_e32 v6, 0x3fb8aa3b, v26
	v_mul_f32_e32 v7, 0x3fb8aa3b, v27
	v_mul_f32_e32 v8, 0x3fb8aa3b, v28
	v_mul_f32_e32 v9, 0x3fb8aa3b, v29
	v_exp_f32_e32 v6, v6
	v_exp_f32_e32 v7, v7
	v_exp_f32_e32 v8, v8
	v_exp_f32_e32 v9, v9
	v_mul_f32_e32 v10, 0x3fb8aa3b, v22
	v_mul_f32_e32 v11, 0x3fb8aa3b, v23
	v_mul_f32_e32 v12, 0x3fb8aa3b, v24
	v_mul_f32_e32 v13, 0x3fb8aa3b, v25
	v_exp_f32_e32 v10, v10
	v_exp_f32_e32 v11, v11
	v_exp_f32_e32 v12, v12
	v_exp_f32_e32 v13, v13
	v_mul_f32_e32 v14, 0x3fb8aa3b, v18
	v_mul_f32_e32 v15, 0x3fb8aa3b, v19
	v_mul_f32_e32 v16, 0x3fb8aa3b, v20
	v_mul_f32_e32 v17, 0x3fb8aa3b, v21
	v_exp_f32_e32 v14, v14
	v_exp_f32_e32 v15, v15
	v_exp_f32_e32 v16, v16
	v_exp_f32_e32 v17, v17
	global_store_dwordx4 v67, v[2:5], s[14:15] offset:64
	global_store_dwordx4 v67, v[6:9], s[14:15] offset:80
	global_store_dwordx4 v67, v[10:13], s[14:15] offset:96
	global_store_dwordx4 v67, v[14:17], s[14:15] offset:112

.LBB0_707:
	v_mov_b32_e32 v68, v109
	v_mov_b64_e32 v[2:3], s[8:9]
	v_add_u32_e32 v4, s33, v68
	v_mad_i64_i32 v[70:71], s[0:1], v4, s27, v[2:3]
	s_lshl_b32 s0, s10, 1
	s_mov_b32 s1, s11
	v_lshl_add_u64 v[30:31], v[70:71], 0, s[0:1]
	global_load_dwordx4 v[2:5], v[30:31], off offset:512
	global_load_dwordx4 v[6:9], v[30:31], off offset:528
	global_load_dwordx4 v[10:13], v[30:31], off offset:544
	global_load_dwordx4 v[14:17], v[30:31], off offset:560
	global_load_dwordx4 v[18:21], v[30:31], off offset:576
	global_load_dwordx4 v[22:25], v[30:31], off offset:592
	global_load_dwordx4 v[26:29], v[30:31], off offset:608
	s_nop 0
	global_load_dwordx4 v[30:33], v[30:31], off offset:624
	v_readlane_b32 s40, v239, 33
	global_load_dwordx4 v[34:37], v[70:71], off offset:1536
	s_lshl_b32 s0, s36, 7
	v_readlane_b32 s46, v239, 39
	v_readlane_b32 s47, v239, 40
	v_readlane_b32 s48, v239, 41
	v_readlane_b32 s49, v239, 42
	s_add_u32 s12, s46, s0
	v_mov_b32_e32 v123, s0
	s_addc_u32 s13, s47, 0
	s_nop 1
	global_load_dwordx4 v[38:41], v123, s[48:49]
	global_load_dwordx4 v[42:45], v123, s[46:47]
	global_load_dwordx4 v[46:49], v123, s[46:47] offset:512
	global_load_dwordx4 v[50:53], v123, s[46:47] offset:1024
	global_load_dwordx4 v[54:57], v123, s[46:47] offset:1536
	global_load_dwordx4 v[58:61], v123, s[46:47] offset:2048
	global_load_dwordx4 v[62:65], v123, s[46:47] offset:2560
	global_load_dwordx4 v[74:77], v123, s[46:47] offset:3072
	global_load_dwordx4 v[78:81], v123, s[46:47] offset:3584
	global_load_dwordx4 v[82:85], v110, s[12:13]
	global_load_dwordx4 v[86:89], v110, s[12:13] offset:512
	global_load_dwordx4 v[90:93], v[70:71], off offset:1552
	v_lshl_add_u32 v66, v68, 1, s17
	v_lshl_add_u64 v[70:71], v[70:71], 0, s[10:11]
	v_readlane_b32 s41, v239, 34
	v_readlane_b32 s42, v239, 35
	v_readlane_b32 s43, v239, 36
	v_readlane_b32 s44, v239, 37
	v_readlane_b32 s45, v239, 38
	v_readlane_b32 s50, v239, 43
	v_readlane_b32 s51, v239, 44
	v_readlane_b32 s52, v239, 45
	v_readlane_b32 s53, v239, 46
	v_readlane_b32 s54, v239, 47
	v_readlane_b32 s55, v239, 48
	v_ashrrev_i32_e32 v69, 31, v68
	s_waitcnt vmcnt(20)
	ds_write_b16 v66, v2
	ds_write_b16_d16_hi v66, v2 offset:128
	ds_write_b16 v66, v3 offset:256
	ds_write_b16_d16_hi v66, v3 offset:384
	ds_write_b16 v66, v4 offset:512
	ds_write_b16_d16_hi v66, v4 offset:640
	ds_write_b16 v66, v5 offset:768
	ds_write_b16_d16_hi v66, v5 offset:896
	s_waitcnt vmcnt(19)
	ds_write_b16 v66, v6 offset:1024
	ds_write_b16_d16_hi v66, v6 offset:1152
	ds_write_b16 v66, v7 offset:1280
	ds_write_b16_d16_hi v66, v7 offset:1408
	ds_write_b16 v66, v8 offset:1536
	ds_write_b16_d16_hi v66, v8 offset:1664
	ds_write_b16 v66, v9 offset:1792
	ds_write_b16_d16_hi v66, v9 offset:1920
	s_waitcnt vmcnt(18)
	ds_write_b16 v66, v10 offset:2048
	ds_write_b16_d16_hi v66, v10 offset:2176
	ds_write_b16 v66, v11 offset:2304
	ds_write_b16_d16_hi v66, v11 offset:2432
	ds_write_b16 v66, v12 offset:2560
	ds_write_b16_d16_hi v66, v12 offset:2688
	ds_write_b16 v66, v13 offset:2816
	ds_write_b16_d16_hi v66, v13 offset:2944
	s_waitcnt vmcnt(17)
	ds_write_b16 v66, v14 offset:3072
	ds_write_b16_d16_hi v66, v14 offset:3200
	ds_write_b16 v66, v15 offset:3328
	ds_write_b16_d16_hi v66, v15 offset:3456
	ds_write_b16 v66, v16 offset:3584
	ds_write_b16_d16_hi v66, v16 offset:3712
	ds_write_b16 v66, v17 offset:3840
	ds_write_b16_d16_hi v66, v17 offset:3968
	s_waitcnt vmcnt(16)
	ds_write_b16 v66, v18 offset:4096
	ds_write_b16_d16_hi v66, v18 offset:4224
	ds_write_b16 v66, v19 offset:4352
	ds_write_b16_d16_hi v66, v19 offset:4480
	ds_write_b16 v66, v20 offset:4608
	ds_write_b16_d16_hi v66, v20 offset:4736
	ds_write_b16 v66, v21 offset:4864
	ds_write_b16_d16_hi v66, v21 offset:4992
	s_waitcnt vmcnt(15)
	ds_write_b16 v66, v22 offset:5120
	ds_write_b16_d16_hi v66, v22 offset:5248
	ds_write_b16 v66, v23 offset:5376
	ds_write_b16_d16_hi v66, v23 offset:5504
	ds_write_b16 v66, v24 offset:5632
	ds_write_b16_d16_hi v66, v24 offset:5760
	ds_write_b16 v66, v25 offset:5888
	ds_write_b16_d16_hi v66, v25 offset:6016
	s_waitcnt vmcnt(14)
	ds_write_b16 v66, v26 offset:6144
	ds_write_b16_d16_hi v66, v26 offset:6272
	ds_write_b16 v66, v27 offset:6400
	ds_write_b16_d16_hi v66, v27 offset:6528
	ds_write_b16 v66, v28 offset:6656
	ds_write_b16_d16_hi v66, v28 offset:6784
	ds_write_b16 v66, v29 offset:6912
	ds_write_b16_d16_hi v66, v29 offset:7040
	s_waitcnt vmcnt(13)
	ds_write_b16 v66, v30 offset:7168
	ds_write_b16_d16_hi v66, v30 offset:7296
	ds_write_b16 v66, v31 offset:7424
	ds_write_b16_d16_hi v66, v31 offset:7552
	ds_write_b16 v66, v32 offset:7680
	ds_write_b16_d16_hi v66, v32 offset:7808
	ds_write_b16 v66, v33 offset:7936
	ds_write_b16_d16_hi v66, v33 offset:8064
	global_load_dwordx4 v[18:21], v110, s[12:13] offset:1024
	global_load_dwordx4 v[22:25], v110, s[12:13] offset:1536
	global_load_dwordx4 v[14:17], v[70:71], off offset:256
	global_load_dwordx4 v[10:13], v[70:71], off offset:272
	global_load_dwordx4 v[6:9], v[70:71], off offset:288
	global_load_dwordx4 v[2:5], v[70:71], off offset:304
	global_load_dwordx4 v[26:29], v110, s[12:13] offset:2048
	global_load_dwordx4 v[30:33], v110, s[12:13] offset:2560
	global_load_dwordx4 v[94:97], v110, s[12:13] offset:3072
	global_load_dwordx4 v[98:101], v110, s[12:13] offset:3584
	s_waitcnt vmcnt(22)
	v_lshlrev_b32_e32 v118, 16, v34
	v_and_b32_e32 v117, 0xffff0000, v34
	v_lshlrev_b32_e32 v120, 16, v36
	v_and_b32_e32 v119, 0xffff0000, v36
	s_waitcnt vmcnt(20)
	v_fma_f32 v36, v42, v118, v38
	v_lshlrev_b32_e32 v122, 16, v35
	s_waitcnt vmcnt(19)
	v_fmac_f32_e32 v36, v46, v117
	v_and_b32_e32 v121, 0xffff0000, v35
	s_waitcnt vmcnt(18)
	v_fmac_f32_e32 v36, v50, v122
	v_fma_f32 v38, v43, v118, v39
	s_waitcnt vmcnt(17)
	v_fmac_f32_e32 v36, v54, v121
	v_fmac_f32_e32 v38, v47, v117
	s_waitcnt vmcnt(16)
	v_fmac_f32_e32 v36, v58, v120
	v_fmac_f32_e32 v38, v51, v122
	v_and_b32_e32 v73, 0xffff0000, v37
	v_lshlrev_b32_e32 v72, 16, v37
	s_waitcnt vmcnt(14)
	v_mov_b32_e32 v34, v74
	s_waitcnt vmcnt(13)
	v_mov_b32_e32 v35, v78
	v_fmac_f32_e32 v36, v62, v119
	v_fmac_f32_e32 v38, v55, v121
	v_fma_f32 v39, v44, v118, v40
	v_pk_mul_f32 v[34:35], v[34:35], v[72:73]
	v_fmac_f32_e32 v38, v59, v120
	v_fmac_f32_e32 v39, v48, v117
	v_add_f32_e32 v34, v36, v34
	v_mov_b32_e32 v78, v75
	v_fmac_f32_e32 v38, v63, v119
	v_fmac_f32_e32 v39, v52, v122
	v_fmac_f32_e32 v41, v45, v118
	v_add_f32_e32 v36, v34, v35
	v_pk_mul_f32 v[34:35], v[78:79], v[72:73]
	v_fmac_f32_e32 v39, v56, v121
	v_fmac_f32_e32 v41, v49, v117
	v_add_f32_e32 v34, v34, v38
	v_fmac_f32_e32 v39, v60, v120
	v_fmac_f32_e32 v41, v53, v122
	v_add_f32_e32 v37, v35, v34
	v_mov_b32_e32 v34, v76
	v_mov_b32_e32 v35, v80
	v_fmac_f32_e32 v39, v64, v119
	v_fmac_f32_e32 v41, v57, v121
	v_pk_mul_f32 v[34:35], v[34:35], v[72:73]
	v_fmac_f32_e32 v41, v61, v120
	v_add_f32_e32 v34, v34, v39
	v_mov_b32_e32 v80, v77
	v_fmac_f32_e32 v41, v65, v119
	v_add_f32_e32 v38, v35, v34
	v_pk_mul_f32 v[34:35], v[80:81], v[72:73]
	s_waitcnt vmcnt(10)
	v_and_b32_e32 v75, 0xffff0000, v90
	v_add_f32_e32 v34, v34, v41
	v_add_f32_e32 v39, v35, v34
	v_lshlrev_b32_e32 v74, 16, v90
	v_mov_b32_e32 v34, v82
	v_mov_b32_e32 v35, v86
	v_pk_mul_f32 v[34:35], v[34:35], v[74:75]
	v_mov_b32_e32 v86, v83
	v_add_f32_e32 v34, v36, v34
	v_add_f32_e32 v36, v34, v35
	v_pk_mul_f32 v[34:35], v[86:87], v[74:75]
	v_and_b32_e32 v79, 0xffff0000, v91
	v_add_f32_e32 v34, v34, v37
	v_add_f32_e32 v37, v35, v34
	v_mov_b32_e32 v34, v84
	v_mov_b32_e32 v35, v88
	v_pk_mul_f32 v[34:35], v[34:35], v[74:75]
	v_mov_b32_e32 v88, v85
	v_add_f32_e32 v34, v34, v38
	v_add_f32_e32 v38, v35, v34
	v_pk_mul_f32 v[34:35], v[88:89], v[74:75]
	v_lshlrev_b32_e32 v78, 16, v91
	v_add_f32_e32 v34, v34, v39
	v_add_f32_e32 v39, v35, v34
	v_and_b32_e32 v81, 0xffff0000, v92
	v_lshlrev_b32_e32 v80, 16, v92
	v_and_b32_e32 v83, 0xffff0000, v93
	v_lshlrev_b32_e32 v82, 16, v93
	s_waitcnt vmcnt(9)
	v_mov_b32_e32 v34, v18
	s_waitcnt vmcnt(8)
	v_mov_b32_e32 v35, v22
	v_pk_mul_f32 v[34:35], v[34:35], v[78:79]
	v_mov_b32_e32 v22, v19
	v_add_f32_e32 v18, v36, v34
	v_add_f32_e32 v34, v18, v35
	v_pk_mul_f32 v[18:19], v[22:23], v[78:79]
	s_nop 0
	v_add_f32_e32 v18, v18, v37
	v_add_f32_e32 v22, v19, v18
	v_mov_b32_e32 v18, v20
	v_mov_b32_e32 v19, v24
	v_pk_mul_f32 v[18:19], v[18:19], v[78:79]
	v_mov_b32_e32 v24, v21
	v_add_f32_e32 v18, v18, v38
	v_add_f32_e32 v20, v19, v18
	v_pk_mul_f32 v[18:19], v[24:25], v[78:79]
	s_waitcnt vmcnt(0)
	v_mov_b32_e32 v21, v98
	v_add_f32_e32 v18, v18, v39
	v_add_f32_e32 v23, v19, v18
	v_mov_b32_e32 v18, v26
	v_mov_b32_e32 v19, v30
	v_pk_mul_f32 v[18:19], v[18:19], v[80:81]
	v_mov_b32_e32 v30, v27
	v_add_f32_e32 v18, v34, v18
	v_add_f32_e32 v24, v18, v19
	v_pk_mul_f32 v[18:19], v[30:31], v[80:81]
	v_mov_b32_e32 v98, v95
	v_add_f32_e32 v18, v18, v22
	v_add_f32_e32 v22, v19, v18
	v_mov_b32_e32 v18, v28
	v_mov_b32_e32 v19, v32
	v_pk_mul_f32 v[18:19], v[18:19], v[80:81]
	v_mov_b32_e32 v32, v29
	v_add_f32_e32 v18, v18, v20
	v_mov_b32_e32 v20, v94
	v_pk_mul_f32 v[20:21], v[20:21], v[82:83]
	s_nop 0
	v_add_f32_e32 v20, v24, v20
	v_add_f32_e32 v20, v20, v21
	v_mul_f32_e64 v21, |v20|, s28
	v_exp_f32_e32 v21, v21
	v_add_f32_e32 v24, v19, v18
	v_pk_mul_f32 v[18:19], v[32:33], v[80:81]
	v_add_f32_e32 v21, 1.0, v21
	v_cmp_gt_f32_e32 vcc, s29, v21
	v_add_f32_e32 v18, v18, v23
	v_add_f32_e32 v26, v19, v18
	v_cndmask_b32_e64 v25, 0, 32, vcc
	v_ldexp_f32 v21, v21, v25
	v_log_f32_e32 v25, v21
	v_min_f32_e32 v18, 0, v20
	v_pk_mul_f32 v[20:21], v[98:99], v[82:83]
	v_mov_b32_e32 v23, v100
	v_add_f32_e32 v20, v20, v22
	v_add_f32_e32 v21, v21, v20
	v_mul_f32_e64 v20, |v21|, s28
	v_exp_f32_e32 v20, v20
	v_mul_f32_e32 v19, 0x3f317217, v25
	v_fma_f32 v19, v25, s30, -v19
	v_fmac_f32_e32 v19, 0x3377d1cf, v25
	v_fmac_f32_e32 v19, 0x3f317217, v25
	v_cmp_lt_f32_e64 s[0:1], |v25|, s31
	v_add_f32_e32 v20, 1.0, v20
	v_mov_b32_e32 v100, v97
	v_cndmask_b32_e64 v19, v25, v19, s[0:1]
	v_cmp_gt_f32_e64 s[0:1], s29, v20
	s_nop 1
	v_cndmask_b32_e64 v22, 0, 32, s[0:1]
	v_ldexp_f32 v20, v20, v22
	v_mov_b32_e32 v22, v96
	v_pk_mul_f32 v[22:23], v[22:23], v[82:83]
	v_log_f32_e32 v25, v20
	v_add_f32_e32 v22, v22, v24
	v_add_f32_e32 v22, v23, v22
	v_mul_f32_e64 v23, |v22|, s28
	v_cndmask_b32_e32 v20, 0, v111, vcc
	v_exp_f32_e32 v23, v23
	v_sub_f32_e32 v20, v19, v20
	v_min_f32_e32 v19, 0, v21
	v_mul_f32_e32 v21, 0x3f317217, v25
	v_fma_f32 v21, v25, s30, -v21
	v_fmac_f32_e32 v21, 0x3377d1cf, v25
	v_fmac_f32_e32 v21, 0x3f317217, v25
	v_cmp_lt_f32_e64 vcc, |v25|, s31
	v_add_f32_e32 v23, 1.0, v23
	v_cndmask_b32_e64 v24, 0, v111, s[0:1]
	v_cndmask_b32_e32 v21, v25, v21, vcc
	v_cmp_gt_f32_e32 vcc, s29, v23
	v_sub_f32_e32 v21, v21, v24
	v_pk_add_f32 v[18:19], v[18:19], v[20:21] neg_lo:[0,1] neg_hi:[0,1]
	v_cndmask_b32_e64 v24, 0, 32, vcc
	v_ldexp_f32 v23, v23, v24
	v_pk_mul_f32 v[20:21], v[100:101], v[82:83]
	v_log_f32_e32 v23, v23
	v_add_f32_e32 v20, v20, v26
	v_add_f32_e32 v21, v21, v20
	v_mul_f32_e64 v20, |v21|, s28
	v_exp_f32_e32 v20, v20
	v_pk_mul_f32 v[70:71], v[18:19], s[6:7] op_sel_hi:[1,0]
	v_mul_f32_e32 v19, 0x3f317217, v23
	v_fma_f32 v19, v23, s30, -v19
	v_fmac_f32_e32 v19, 0x3377d1cf, v23
	v_fmac_f32_e32 v19, 0x3f317217, v23
	v_cmp_lt_f32_e64 s[0:1], |v23|, s31
	v_add_f32_e32 v20, 1.0, v20
	v_min_f32_e32 v18, 0, v22
	v_cndmask_b32_e64 v19, v23, v19, s[0:1]
	v_cmp_gt_f32_e64 s[0:1], s29, v20
	s_nop 1
	v_cndmask_b32_e64 v22, 0, 32, s[0:1]
	v_ldexp_f32 v20, v20, v22
	v_log_f32_e32 v22, v20
	v_cndmask_b32_e32 v20, 0, v111, vcc
	v_sub_f32_e32 v20, v19, v20
	v_min_f32_e32 v19, 0, v21
	v_mul_f32_e32 v21, 0x3f317217, v22
	v_fma_f32 v21, v22, s30, -v21
	v_fmac_f32_e32 v21, 0x3377d1cf, v22
	v_fmac_f32_e32 v21, 0x3f317217, v22
	v_cmp_lt_f32_e64 vcc, |v22|, s31
	s_nop 1
	v_cndmask_b32_e32 v21, v22, v21, vcc
	v_cndmask_b32_e64 v22, 0, v111, s[0:1]
	v_sub_f32_e32 v21, v21, v22
	v_pk_add_f32 v[18:19], v[18:19], v[20:21] neg_lo:[0,1] neg_hi:[0,1]
	s_nop 0
	v_pk_mul_f32 v[76:77], v[18:19], s[6:7] op_sel_hi:[1,0]
	global_load_dwordx4 v[18:21], v123, s[48:49] offset:16
	global_load_dwordx4 v[22:25], v123, s[46:47] offset:16
	global_load_dwordx4 v[26:29], v123, s[46:47] offset:3088
	global_load_dwordx4 v[30:33], v123, s[46:47] offset:3600
	global_load_dwordx4 v[34:37], v110, s[12:13] offset:16
	global_load_dwordx4 v[38:41], v110, s[12:13] offset:528
	global_load_dwordx4 v[42:45], v110, s[12:13] offset:1040
	global_load_dwordx4 v[46:49], v110, s[12:13] offset:1552
	global_load_dwordx4 v[50:53], v110, s[12:13] offset:2064
	global_load_dwordx4 v[54:57], v110, s[12:13] offset:2576
	global_load_dwordx4 v[58:61], v110, s[12:13] offset:3088
	global_load_dwordx4 v[62:65], v110, s[12:13] offset:3600
	global_load_dwordx4 v[84:87], v123, s[46:47] offset:528
	global_load_dwordx4 v[88:91], v123, s[46:47] offset:1040
	global_load_dwordx4 v[92:95], v123, s[46:47] offset:1552
	global_load_dwordx4 v[96:99], v123, s[46:47] offset:2064
	global_load_dwordx4 v[100:103], v123, s[46:47] offset:2576
	s_waitcnt vmcnt(15)
	v_fma_f32 v130, v22, v118, v18
	v_fma_f32 v20, v24, v118, v20
	s_waitcnt vmcnt(14)
	v_mov_b32_e32 v104, v26
	s_waitcnt vmcnt(13)
	v_mov_b32_e32 v105, v30
	v_fma_f32 v23, v23, v118, v19
	v_mov_b32_e32 v30, v27
	v_mov_b32_e32 v18, v28
	v_mov_b32_e32 v19, v32
	v_pk_mul_f32 v[26:27], v[104:105], v[72:73]
	s_waitcnt vmcnt(12)
	v_mov_b32_e32 v106, v34
	s_waitcnt vmcnt(11)
	v_mov_b32_e32 v107, v38
	s_waitcnt vmcnt(4)
	v_fmac_f32_e32 v130, v84, v117
	v_fmac_f32_e32 v20, v86, v117
	s_waitcnt vmcnt(3)
	v_fmac_f32_e32 v130, v88, v122
	v_fmac_f32_e32 v20, v90, v122
	s_waitcnt vmcnt(2)
	v_fmac_f32_e32 v130, v92, v121
	v_fmac_f32_e32 v20, v94, v121
	s_waitcnt vmcnt(1)
	v_fmac_f32_e32 v130, v96, v120
	v_fmac_f32_e32 v20, v98, v120
	s_waitcnt vmcnt(0)
	v_fmac_f32_e32 v130, v100, v119
	v_fmac_f32_e32 v23, v85, v117
	v_pk_mul_f32 v[18:19], v[18:19], v[72:73]
	v_fmac_f32_e32 v20, v102, v119
	v_add_f32_e32 v24, v130, v26
	v_mov_b32_e32 v38, v35
	v_pk_mul_f32 v[34:35], v[106:107], v[74:75]
	v_fmac_f32_e32 v23, v89, v122
	v_add_f32_e32 v18, v18, v20
	v_add_f32_e32 v20, v24, v27
	v_mov_b32_e32 v124, v42
	v_mov_b32_e32 v125, v46
	v_fmac_f32_e32 v23, v93, v121
	v_add_f32_e32 v20, v20, v34
	v_mov_b32_e32 v46, v43
	v_pk_mul_f32 v[42:43], v[124:125], v[78:79]
	v_fmac_f32_e32 v23, v97, v120
	v_add_f32_e32 v20, v20, v35
	v_mov_b32_e32 v126, v50
	v_mov_b32_e32 v127, v54
	v_pk_mul_f32 v[30:31], v[30:31], v[72:73]
	v_fmac_f32_e32 v23, v101, v119
	v_add_f32_e32 v20, v20, v42
	v_mov_b32_e32 v54, v51
	v_pk_mul_f32 v[50:51], v[126:127], v[80:81]
	v_add_f32_e32 v23, v30, v23
	v_add_f32_e32 v20, v20, v43
	v_mov_b32_e32 v128, v58
	v_mov_b32_e32 v129, v62
	v_pk_mul_f32 v[38:39], v[38:39], v[74:75]
	v_add_f32_e32 v23, v31, v23
	v_add_f32_e32 v20, v20, v50
	v_mov_b32_e32 v62, v59
	v_pk_mul_f32 v[58:59], v[128:129], v[82:83]
	v_add_f32_e32 v23, v38, v23
	v_add_f32_e32 v20, v20, v51
	v_pk_mul_f32 v[46:47], v[46:47], v[78:79]
	v_add_f32_e32 v23, v39, v23
	v_add_f32_e32 v20, v20, v58
	v_add_f32_e32 v23, v46, v23
	v_add_f32_e32 v20, v20, v59
	v_pk_mul_f32 v[54:55], v[54:55], v[80:81]
	v_add_f32_e32 v23, v47, v23
	v_mul_f32_e64 v24, |v20|, s28
	v_add_f32_e32 v23, v54, v23
	v_exp_f32_e32 v24, v24
	v_pk_mul_f32 v[62:63], v[62:63], v[82:83]
	v_add_f32_e32 v23, v55, v23
	v_add_f32_e32 v23, v62, v23
	v_add_f32_e32 v23, v63, v23
	v_mul_f32_e64 v26, |v23|, s28
	v_add_f32_e32 v27, v19, v18
	v_add_f32_e32 v19, 1.0, v24
	v_exp_f32_e32 v26, v26
	v_cmp_gt_f32_e32 vcc, s29, v19
	v_min_f32_e32 v18, 0, v20
	v_mov_b32_e32 v22, v36
	v_cndmask_b32_e64 v24, 0, 32, vcc
	v_ldexp_f32 v19, v19, v24
	v_log_f32_e32 v24, v19
	v_add_f32_e32 v20, 1.0, v26
	v_cmp_gt_f32_e64 s[0:1], s29, v20
	v_min_f32_e32 v19, 0, v23
	v_cndmask_b32_e32 v23, 0, v111, vcc
	v_cndmask_b32_e64 v26, 0, 32, s[0:1]
	v_ldexp_f32 v20, v20, v26
	v_mul_f32_e32 v26, 0x3f317217, v24
	v_fma_f32 v26, v24, s30, -v26
	v_fmac_f32_e32 v26, 0x3377d1cf, v24
	v_fmac_f32_e32 v26, 0x3f317217, v24
	v_cmp_lt_f32_e64 vcc, |v24|, s31
	v_log_f32_e32 v20, v20
	v_fmac_f32_e32 v21, v25, v118
	v_cndmask_b32_e32 v24, v24, v26, vcc
	v_sub_f32_e32 v26, v24, v23
	v_mov_b32_e32 v23, v40
	v_pk_mul_f32 v[22:23], v[22:23], v[74:75]
	v_mul_f32_e32 v28, 0x3f317217, v20
	v_add_f32_e32 v22, v22, v27
	v_add_f32_e32 v24, v23, v22
	v_mov_b32_e32 v22, v44
	v_mov_b32_e32 v23, v48
	v_pk_mul_f32 v[22:23], v[22:23], v[78:79]
	v_fma_f32 v28, v20, s30, -v28
	v_add_f32_e32 v22, v22, v24
	v_add_f32_e32 v24, v23, v22
	v_mov_b32_e32 v22, v52
	v_mov_b32_e32 v23, v56
	v_pk_mul_f32 v[22:23], v[22:23], v[80:81]
	v_fmac_f32_e32 v28, 0x3377d1cf, v20
	v_add_f32_e32 v22, v22, v24
	v_add_f32_e32 v24, v23, v22
	v_mov_b32_e32 v22, v60
	v_mov_b32_e32 v23, v64
	v_pk_mul_f32 v[22:23], v[22:23], v[82:83]
	v_fmac_f32_e32 v28, 0x3f317217, v20
	v_add_f32_e32 v22, v22, v24
	v_add_f32_e32 v22, v23, v22
	v_mul_f32_e64 v23, |v22|, s28
	v_exp_f32_e32 v23, v23
	v_cmp_lt_f32_e64 vcc, |v20|, s31
	v_cndmask_b32_e64 v24, 0, v111, s[0:1]
	v_fmac_f32_e32 v21, v87, v117
	v_cndmask_b32_e32 v20, v20, v28, vcc
	v_sub_f32_e32 v27, v20, v24
	v_add_f32_e32 v20, 1.0, v23
	v_fmac_f32_e32 v21, v91, v122
	v_cmp_gt_f32_e32 vcc, s29, v20
	v_fmac_f32_e32 v21, v95, v121
	v_pk_add_f32 v[18:19], v[18:19], v[26:27] neg_lo:[0,1] neg_hi:[0,1]
	v_cndmask_b32_e64 v23, 0, 32, vcc
	v_fmac_f32_e32 v21, v99, v120
	v_mov_b32_e32 v32, v29
	v_ldexp_f32 v20, v20, v23
	v_pk_mul_f32 v[84:85], v[18:19], s[6:7] op_sel_hi:[1,0]
	v_min_f32_e32 v18, 0, v22
	v_fmac_f32_e32 v21, v103, v119
	v_pk_mul_f32 v[22:23], v[32:33], v[72:73]
	v_log_f32_e32 v24, v20
	v_add_f32_e32 v20, v22, v21
	v_mov_b32_e32 v40, v37
	v_add_f32_e32 v22, v23, v20
	v_pk_mul_f32 v[20:21], v[40:41], v[74:75]
	v_mov_b32_e32 v48, v45
	v_add_f32_e32 v20, v20, v22
	v_add_f32_e32 v22, v21, v20
	v_pk_mul_f32 v[20:21], v[48:49], v[78:79]
	v_mov_b32_e32 v56, v53
	v_add_f32_e32 v20, v20, v22
	v_add_f32_e32 v22, v21, v20
	v_pk_mul_f32 v[20:21], v[56:57], v[80:81]
	v_mov_b32_e32 v64, v61
	v_add_f32_e32 v20, v20, v22
	v_add_f32_e32 v22, v21, v20
	v_pk_mul_f32 v[20:21], v[64:65], v[82:83]
	v_mul_f32_e32 v19, 0x3f317217, v24
	v_add_f32_e32 v20, v20, v22
	v_add_f32_e32 v21, v21, v20
	v_mul_f32_e64 v20, |v21|, s28
	v_exp_f32_e32 v20, v20
	v_fma_f32 v19, v24, s30, -v19
	v_fmac_f32_e32 v19, 0x3377d1cf, v24
	v_fmac_f32_e32 v19, 0x3f317217, v24
	v_cmp_lt_f32_e64 s[0:1], |v24|, s31
	v_add_f32_e32 v20, 1.0, v20
	s_nop 0
	v_cndmask_b32_e64 v19, v24, v19, s[0:1]
	v_cmp_gt_f32_e64 s[0:1], s29, v20
	s_nop 1
	v_cndmask_b32_e64 v22, 0, 32, s[0:1]
	v_ldexp_f32 v20, v20, v22
	v_log_f32_e32 v22, v20
	v_cndmask_b32_e32 v20, 0, v111, vcc
	v_sub_f32_e32 v20, v19, v20
	v_min_f32_e32 v19, 0, v21
	v_mul_f32_e32 v21, 0x3f317217, v22
	v_fma_f32 v21, v22, s30, -v21
	v_fmac_f32_e32 v21, 0x3377d1cf, v22
	v_fmac_f32_e32 v21, 0x3f317217, v22
	v_cmp_lt_f32_e64 vcc, |v22|, s31
	s_nop 1
	v_cndmask_b32_e32 v21, v22, v21, vcc
	v_cndmask_b32_e64 v22, 0, v111, s[0:1]
	v_sub_f32_e32 v21, v21, v22
	v_pk_add_f32 v[18:19], v[18:19], v[20:21] neg_lo:[0,1] neg_hi:[0,1]
	s_nop 0
	v_pk_mul_f32 v[86:87], v[18:19], s[6:7] op_sel_hi:[1,0]
	global_load_dwordx4 v[18:21], v123, s[48:49] offset:32
	global_load_dwordx4 v[22:25], v123, s[46:47] offset:32
	global_load_dwordx4 v[26:29], v123, s[46:47] offset:3104
	global_load_dwordx4 v[30:33], v123, s[46:47] offset:3616
	global_load_dwordx4 v[34:37], v110, s[12:13] offset:32
	global_load_dwordx4 v[38:41], v110, s[12:13] offset:544
	global_load_dwordx4 v[42:45], v110, s[12:13] offset:1056
	global_load_dwordx4 v[46:49], v110, s[12:13] offset:1568
	global_load_dwordx4 v[50:53], v110, s[12:13] offset:2080
	global_load_dwordx4 v[54:57], v110, s[12:13] offset:2592
	global_load_dwordx4 v[58:61], v110, s[12:13] offset:3104
	global_load_dwordx4 v[62:65], v110, s[12:13] offset:3616
	global_load_dwordx4 v[88:91], v123, s[46:47] offset:544
	global_load_dwordx4 v[92:95], v123, s[46:47] offset:1056
	global_load_dwordx4 v[96:99], v123, s[46:47] offset:1568
	global_load_dwordx4 v[100:103], v123, s[46:47] offset:2080
	global_load_dwordx4 v[104:107], v123, s[46:47] offset:2592
	s_waitcnt vmcnt(15)
	v_fma_f32 v134, v22, v118, v18
	v_fma_f32 v20, v24, v118, v20
	s_waitcnt vmcnt(14)
	v_mov_b32_e32 v124, v26
	s_waitcnt vmcnt(13)
	v_mov_b32_e32 v125, v30
	v_fma_f32 v23, v23, v118, v19
	v_mov_b32_e32 v30, v27
	v_mov_b32_e32 v18, v28
	v_mov_b32_e32 v19, v32
	v_pk_mul_f32 v[26:27], v[124:125], v[72:73]
	s_waitcnt vmcnt(12)
	v_mov_b32_e32 v126, v34
	s_waitcnt vmcnt(11)
	v_mov_b32_e32 v127, v38
	s_waitcnt vmcnt(4)
	v_fmac_f32_e32 v134, v88, v117
	v_fmac_f32_e32 v20, v90, v117
	s_waitcnt vmcnt(3)
	v_fmac_f32_e32 v134, v92, v122
	v_fmac_f32_e32 v20, v94, v122
	s_waitcnt vmcnt(2)
	v_fmac_f32_e32 v134, v96, v121
	v_fmac_f32_e32 v20, v98, v121
	s_waitcnt vmcnt(1)
	v_fmac_f32_e32 v134, v100, v120
	v_fmac_f32_e32 v20, v102, v120
	s_waitcnt vmcnt(0)
	v_fmac_f32_e32 v134, v104, v119
	v_fmac_f32_e32 v23, v89, v117
	v_pk_mul_f32 v[18:19], v[18:19], v[72:73]
	v_fmac_f32_e32 v20, v106, v119
	v_add_f32_e32 v24, v134, v26
	v_mov_b32_e32 v38, v35
	v_pk_mul_f32 v[34:35], v[126:127], v[74:75]
	v_fmac_f32_e32 v23, v93, v122
	v_add_f32_e32 v18, v18, v20
	v_add_f32_e32 v20, v24, v27
	v_mov_b32_e32 v128, v42
	v_mov_b32_e32 v129, v46
	v_fmac_f32_e32 v23, v97, v121
	v_add_f32_e32 v20, v20, v34
	v_mov_b32_e32 v46, v43
	v_pk_mul_f32 v[42:43], v[128:129], v[78:79]
	v_fmac_f32_e32 v23, v101, v120
	v_add_f32_e32 v20, v20, v35
	v_mov_b32_e32 v130, v50
	v_mov_b32_e32 v131, v54
	v_pk_mul_f32 v[30:31], v[30:31], v[72:73]
	v_fmac_f32_e32 v23, v105, v119
	v_add_f32_e32 v20, v20, v42
	v_mov_b32_e32 v54, v51
	v_pk_mul_f32 v[50:51], v[130:131], v[80:81]
	v_add_f32_e32 v23, v30, v23
	v_add_f32_e32 v20, v20, v43
	v_mov_b32_e32 v132, v58
	v_mov_b32_e32 v133, v62
	v_pk_mul_f32 v[38:39], v[38:39], v[74:75]
	v_add_f32_e32 v23, v31, v23
	v_add_f32_e32 v20, v20, v50
	v_mov_b32_e32 v62, v59
	v_pk_mul_f32 v[58:59], v[132:133], v[82:83]
	v_add_f32_e32 v23, v38, v23
	v_add_f32_e32 v20, v20, v51
	v_pk_mul_f32 v[46:47], v[46:47], v[78:79]
	v_add_f32_e32 v23, v39, v23
	v_add_f32_e32 v20, v20, v58
	v_add_f32_e32 v23, v46, v23
	v_add_f32_e32 v20, v20, v59
	v_pk_mul_f32 v[54:55], v[54:55], v[80:81]
	v_add_f32_e32 v23, v47, v23
	v_mul_f32_e64 v24, |v20|, s28
	v_add_f32_e32 v23, v54, v23
	v_exp_f32_e32 v24, v24
	v_pk_mul_f32 v[62:63], v[62:63], v[82:83]
	v_add_f32_e32 v23, v55, v23
	v_add_f32_e32 v23, v62, v23
	v_add_f32_e32 v23, v63, v23
	v_mul_f32_e64 v26, |v23|, s28
	v_add_f32_e32 v27, v19, v18
	v_add_f32_e32 v19, 1.0, v24
	v_exp_f32_e32 v26, v26
	v_cmp_gt_f32_e32 vcc, s29, v19
	v_min_f32_e32 v18, 0, v20
	v_mov_b32_e32 v22, v36
	v_cndmask_b32_e64 v24, 0, 32, vcc
	v_ldexp_f32 v19, v19, v24
	v_log_f32_e32 v24, v19
	v_add_f32_e32 v20, 1.0, v26
	v_cmp_gt_f32_e64 s[0:1], s29, v20
	v_min_f32_e32 v19, 0, v23
	v_cndmask_b32_e32 v23, 0, v111, vcc
	v_cndmask_b32_e64 v26, 0, 32, s[0:1]
	v_ldexp_f32 v20, v20, v26
	v_mul_f32_e32 v26, 0x3f317217, v24
	v_fma_f32 v26, v24, s30, -v26
	v_fmac_f32_e32 v26, 0x3377d1cf, v24
	v_fmac_f32_e32 v26, 0x3f317217, v24
	v_cmp_lt_f32_e64 vcc, |v24|, s31
	v_log_f32_e32 v20, v20
	v_fmac_f32_e32 v21, v25, v118
	v_cndmask_b32_e32 v24, v24, v26, vcc
	v_sub_f32_e32 v26, v24, v23
	v_mov_b32_e32 v23, v40
	v_pk_mul_f32 v[22:23], v[22:23], v[74:75]
	v_mul_f32_e32 v28, 0x3f317217, v20
	v_add_f32_e32 v22, v22, v27
	v_add_f32_e32 v24, v23, v22
	v_mov_b32_e32 v22, v44
	v_mov_b32_e32 v23, v48
	v_pk_mul_f32 v[22:23], v[22:23], v[78:79]
	v_fma_f32 v28, v20, s30, -v28
	v_add_f32_e32 v22, v22, v24
	v_add_f32_e32 v24, v23, v22
	v_mov_b32_e32 v22, v52
	v_mov_b32_e32 v23, v56
	v_pk_mul_f32 v[22:23], v[22:23], v[80:81]
	v_fmac_f32_e32 v28, 0x3377d1cf, v20
	v_add_f32_e32 v22, v22, v24
	v_add_f32_e32 v24, v23, v22
	v_mov_b32_e32 v22, v60
	v_mov_b32_e32 v23, v64
	v_pk_mul_f32 v[22:23], v[22:23], v[82:83]
	v_fmac_f32_e32 v28, 0x3f317217, v20
	v_add_f32_e32 v22, v22, v24
	v_add_f32_e32 v22, v23, v22
	v_mul_f32_e64 v23, |v22|, s28
	v_exp_f32_e32 v23, v23
	v_cmp_lt_f32_e64 vcc, |v20|, s31
	v_cndmask_b32_e64 v24, 0, v111, s[0:1]
	v_fmac_f32_e32 v21, v91, v117
	v_cndmask_b32_e32 v20, v20, v28, vcc
	v_sub_f32_e32 v27, v20, v24
	v_add_f32_e32 v20, 1.0, v23
	v_fmac_f32_e32 v21, v95, v122
	v_cmp_gt_f32_e32 vcc, s29, v20
	v_fmac_f32_e32 v21, v99, v121
	v_pk_add_f32 v[18:19], v[18:19], v[26:27] neg_lo:[0,1] neg_hi:[0,1]
	v_cndmask_b32_e64 v23, 0, 32, vcc
	v_fmac_f32_e32 v21, v103, v120
	v_mov_b32_e32 v32, v29
	v_ldexp_f32 v20, v20, v23
	v_pk_mul_f32 v[88:89], v[18:19], s[6:7] op_sel_hi:[1,0]
	v_min_f32_e32 v18, 0, v22
	v_fmac_f32_e32 v21, v107, v119
	v_pk_mul_f32 v[22:23], v[32:33], v[72:73]
	v_log_f32_e32 v24, v20
	v_add_f32_e32 v20, v22, v21
	v_mov_b32_e32 v40, v37
	v_add_f32_e32 v22, v23, v20
	v_pk_mul_f32 v[20:21], v[40:41], v[74:75]
	v_mov_b32_e32 v48, v45
	v_add_f32_e32 v20, v20, v22
	v_add_f32_e32 v22, v21, v20
	v_pk_mul_f32 v[20:21], v[48:49], v[78:79]
	v_mov_b32_e32 v56, v53
	v_add_f32_e32 v20, v20, v22
	v_add_f32_e32 v22, v21, v20
	v_pk_mul_f32 v[20:21], v[56:57], v[80:81]
	v_mov_b32_e32 v64, v61
	v_add_f32_e32 v20, v20, v22
	v_add_f32_e32 v22, v21, v20
	v_pk_mul_f32 v[20:21], v[64:65], v[82:83]
	v_mul_f32_e32 v19, 0x3f317217, v24
	v_add_f32_e32 v20, v20, v22
	v_add_f32_e32 v21, v21, v20
	v_mul_f32_e64 v20, |v21|, s28
	v_exp_f32_e32 v20, v20
	v_fma_f32 v19, v24, s30, -v19
	v_fmac_f32_e32 v19, 0x3377d1cf, v24
	v_fmac_f32_e32 v19, 0x3f317217, v24
	v_cmp_lt_f32_e64 s[0:1], |v24|, s31
	v_add_f32_e32 v20, 1.0, v20
	s_nop 0
	v_cndmask_b32_e64 v19, v24, v19, s[0:1]
	v_cmp_gt_f32_e64 s[0:1], s29, v20
	s_nop 1
	v_cndmask_b32_e64 v22, 0, 32, s[0:1]
	v_ldexp_f32 v20, v20, v22
	v_log_f32_e32 v22, v20
	v_cndmask_b32_e32 v20, 0, v111, vcc
	v_sub_f32_e32 v20, v19, v20
	v_min_f32_e32 v19, 0, v21
	v_mul_f32_e32 v21, 0x3f317217, v22
	v_fma_f32 v21, v22, s30, -v21
	v_fmac_f32_e32 v21, 0x3377d1cf, v22
	v_fmac_f32_e32 v21, 0x3f317217, v22
	v_cmp_lt_f32_e64 vcc, |v22|, s31
	s_nop 1
	v_cndmask_b32_e32 v21, v22, v21, vcc
	v_cndmask_b32_e64 v22, 0, v111, s[0:1]
	v_sub_f32_e32 v21, v21, v22
	v_pk_add_f32 v[18:19], v[18:19], v[20:21] neg_lo:[0,1] neg_hi:[0,1]
	s_nop 0
	v_pk_mul_f32 v[90:91], v[18:19], s[6:7] op_sel_hi:[1,0]
	global_load_dwordx4 v[18:21], v123, s[48:49] offset:48
	global_load_dwordx4 v[22:25], v123, s[46:47] offset:48
	global_load_dwordx4 v[26:29], v123, s[46:47] offset:3120
	global_load_dwordx4 v[30:33], v123, s[46:47] offset:3632
	global_load_dwordx4 v[34:37], v110, s[12:13] offset:48
	global_load_dwordx4 v[38:41], v110, s[12:13] offset:560
	global_load_dwordx4 v[42:45], v110, s[12:13] offset:1072
	global_load_dwordx4 v[46:49], v110, s[12:13] offset:1584
	global_load_dwordx4 v[50:53], v110, s[12:13] offset:2096
	global_load_dwordx4 v[54:57], v110, s[12:13] offset:2608
	global_load_dwordx4 v[58:61], v110, s[12:13] offset:3120
	global_load_dwordx4 v[62:65], v110, s[12:13] offset:3632
	global_load_dwordx4 v[92:95], v123, s[46:47] offset:560
	global_load_dwordx4 v[96:99], v123, s[46:47] offset:1072
	global_load_dwordx4 v[100:103], v123, s[46:47] offset:1584
	global_load_dwordx4 v[104:107], v123, s[46:47] offset:2096
	global_load_dwordx4 v[124:127], v123, s[46:47] offset:2608
	s_waitcnt vmcnt(15)
	v_fma_f32 v138, v22, v118, v18
	v_fma_f32 v20, v24, v118, v20
	s_waitcnt vmcnt(14)
	v_mov_b32_e32 v128, v26
	s_waitcnt vmcnt(13)
	v_mov_b32_e32 v129, v30
	v_fma_f32 v23, v23, v118, v19
	v_mov_b32_e32 v30, v27
	v_mov_b32_e32 v18, v28
	v_mov_b32_e32 v19, v32
	v_pk_mul_f32 v[26:27], v[128:129], v[72:73]
	s_waitcnt vmcnt(12)
	v_mov_b32_e32 v130, v34
	s_waitcnt vmcnt(11)
	v_mov_b32_e32 v131, v38
	s_waitcnt vmcnt(4)
	v_fmac_f32_e32 v138, v92, v117
	v_fmac_f32_e32 v20, v94, v117
	s_waitcnt vmcnt(3)
	v_fmac_f32_e32 v138, v96, v122
	v_fmac_f32_e32 v20, v98, v122
	s_waitcnt vmcnt(2)
	v_fmac_f32_e32 v138, v100, v121
	v_fmac_f32_e32 v20, v102, v121
	s_waitcnt vmcnt(1)
	v_fmac_f32_e32 v138, v104, v120
	v_fmac_f32_e32 v20, v106, v120
	s_waitcnt vmcnt(0)
	v_fmac_f32_e32 v138, v124, v119
	v_fmac_f32_e32 v23, v93, v117
	v_pk_mul_f32 v[18:19], v[18:19], v[72:73]
	v_fmac_f32_e32 v20, v126, v119
	v_add_f32_e32 v24, v138, v26
	v_mov_b32_e32 v38, v35
	v_pk_mul_f32 v[34:35], v[130:131], v[74:75]
	v_fmac_f32_e32 v23, v97, v122
	v_add_f32_e32 v18, v18, v20
	v_add_f32_e32 v20, v24, v27
	v_mov_b32_e32 v132, v42
	v_mov_b32_e32 v133, v46
	v_fmac_f32_e32 v23, v101, v121
	v_add_f32_e32 v20, v20, v34
	v_mov_b32_e32 v46, v43
	v_pk_mul_f32 v[42:43], v[132:133], v[78:79]
	v_fmac_f32_e32 v23, v105, v120
	v_add_f32_e32 v20, v20, v35
	v_mov_b32_e32 v134, v50
	v_mov_b32_e32 v135, v54
	v_pk_mul_f32 v[30:31], v[30:31], v[72:73]
	v_fmac_f32_e32 v23, v125, v119
	v_add_f32_e32 v20, v20, v42
	v_mov_b32_e32 v54, v51
	v_pk_mul_f32 v[50:51], v[134:135], v[80:81]
	v_add_f32_e32 v23, v30, v23
	v_add_f32_e32 v20, v20, v43
	v_mov_b32_e32 v136, v58
	v_mov_b32_e32 v137, v62
	v_pk_mul_f32 v[38:39], v[38:39], v[74:75]
	v_add_f32_e32 v23, v31, v23
	v_add_f32_e32 v20, v20, v50
	v_mov_b32_e32 v62, v59
	v_pk_mul_f32 v[58:59], v[136:137], v[82:83]
	v_add_f32_e32 v23, v38, v23
	v_add_f32_e32 v20, v20, v51
	v_pk_mul_f32 v[46:47], v[46:47], v[78:79]
	v_add_f32_e32 v23, v39, v23
	v_add_f32_e32 v20, v20, v58
	v_add_f32_e32 v23, v46, v23
	v_add_f32_e32 v20, v20, v59
	v_pk_mul_f32 v[54:55], v[54:55], v[80:81]
	v_add_f32_e32 v23, v47, v23
	v_mul_f32_e64 v24, |v20|, s28
	v_add_f32_e32 v23, v54, v23
	v_exp_f32_e32 v24, v24
	v_pk_mul_f32 v[62:63], v[62:63], v[82:83]
	v_add_f32_e32 v23, v55, v23
	v_add_f32_e32 v23, v62, v23
	v_add_f32_e32 v23, v63, v23
	v_mul_f32_e64 v26, |v23|, s28
	v_add_f32_e32 v27, v19, v18
	v_add_f32_e32 v19, 1.0, v24
	v_exp_f32_e32 v26, v26
	v_cmp_gt_f32_e32 vcc, s29, v19
	v_min_f32_e32 v18, 0, v20
	v_mov_b32_e32 v22, v36
	v_cndmask_b32_e64 v24, 0, 32, vcc
	v_ldexp_f32 v19, v19, v24
	v_log_f32_e32 v24, v19
	v_add_f32_e32 v20, 1.0, v26
	v_cmp_gt_f32_e64 s[0:1], s29, v20
	v_min_f32_e32 v19, 0, v23
	v_cndmask_b32_e32 v23, 0, v111, vcc
	v_cndmask_b32_e64 v26, 0, 32, s[0:1]
	v_ldexp_f32 v20, v20, v26
	v_mul_f32_e32 v26, 0x3f317217, v24
	v_fma_f32 v26, v24, s30, -v26
	v_fmac_f32_e32 v26, 0x3377d1cf, v24
	v_fmac_f32_e32 v26, 0x3f317217, v24
	v_cmp_lt_f32_e64 vcc, |v24|, s31
	v_log_f32_e32 v20, v20
	v_fmac_f32_e32 v21, v25, v118
	v_cndmask_b32_e32 v24, v24, v26, vcc
	v_sub_f32_e32 v26, v24, v23
	v_mov_b32_e32 v23, v40
	v_pk_mul_f32 v[22:23], v[22:23], v[74:75]
	v_mul_f32_e32 v28, 0x3f317217, v20
	v_add_f32_e32 v22, v22, v27
	v_add_f32_e32 v24, v23, v22
	v_mov_b32_e32 v22, v44
	v_mov_b32_e32 v23, v48
	v_pk_mul_f32 v[22:23], v[22:23], v[78:79]
	v_fma_f32 v28, v20, s30, -v28
	v_add_f32_e32 v22, v22, v24
	v_add_f32_e32 v24, v23, v22
	v_mov_b32_e32 v22, v52
	v_mov_b32_e32 v23, v56
	v_pk_mul_f32 v[22:23], v[22:23], v[80:81]
	v_fmac_f32_e32 v28, 0x3377d1cf, v20
	v_add_f32_e32 v22, v22, v24
	v_add_f32_e32 v24, v23, v22
	v_mov_b32_e32 v22, v60
	v_mov_b32_e32 v23, v64
	v_pk_mul_f32 v[22:23], v[22:23], v[82:83]
	v_fmac_f32_e32 v28, 0x3f317217, v20
	v_add_f32_e32 v22, v22, v24
	v_add_f32_e32 v22, v23, v22
	v_mul_f32_e64 v23, |v22|, s28
	v_exp_f32_e32 v23, v23
	v_cmp_lt_f32_e64 vcc, |v20|, s31
	v_cndmask_b32_e64 v24, 0, v111, s[0:1]
	v_fmac_f32_e32 v21, v95, v117
	v_cndmask_b32_e32 v20, v20, v28, vcc
	v_sub_f32_e32 v27, v20, v24
	v_add_f32_e32 v20, 1.0, v23
	v_fmac_f32_e32 v21, v99, v122
	v_cmp_gt_f32_e32 vcc, s29, v20
	v_fmac_f32_e32 v21, v103, v121
	v_pk_add_f32 v[18:19], v[18:19], v[26:27] neg_lo:[0,1] neg_hi:[0,1]
	v_cndmask_b32_e64 v23, 0, 32, vcc
	v_fmac_f32_e32 v21, v107, v120
	v_mov_b32_e32 v32, v29
	v_ldexp_f32 v20, v20, v23
	v_pk_mul_f32 v[92:93], v[18:19], s[6:7] op_sel_hi:[1,0]
	v_min_f32_e32 v18, 0, v22
	v_fmac_f32_e32 v21, v127, v119
	v_pk_mul_f32 v[22:23], v[32:33], v[72:73]
	v_log_f32_e32 v24, v20
	v_add_f32_e32 v20, v22, v21
	v_mov_b32_e32 v40, v37
	v_add_f32_e32 v22, v23, v20
	v_pk_mul_f32 v[20:21], v[40:41], v[74:75]
	v_mov_b32_e32 v48, v45
	v_add_f32_e32 v20, v20, v22
	v_add_f32_e32 v22, v21, v20
	v_pk_mul_f32 v[20:21], v[48:49], v[78:79]
	v_mov_b32_e32 v56, v53
	v_add_f32_e32 v20, v20, v22
	v_add_f32_e32 v22, v21, v20
	v_pk_mul_f32 v[20:21], v[56:57], v[80:81]
	v_mov_b32_e32 v64, v61
	v_add_f32_e32 v20, v20, v22
	v_add_f32_e32 v22, v21, v20
	v_pk_mul_f32 v[20:21], v[64:65], v[82:83]
	v_mul_f32_e32 v19, 0x3f317217, v24
	v_add_f32_e32 v20, v20, v22
	v_add_f32_e32 v21, v21, v20
	v_mul_f32_e64 v20, |v21|, s28
	v_exp_f32_e32 v20, v20
	v_fma_f32 v19, v24, s30, -v19
	v_fmac_f32_e32 v19, 0x3377d1cf, v24
	v_fmac_f32_e32 v19, 0x3f317217, v24
	v_cmp_lt_f32_e64 s[0:1], |v24|, s31
	v_add_f32_e32 v20, 1.0, v20
	s_nop 0
	v_cndmask_b32_e64 v19, v24, v19, s[0:1]
	v_cmp_gt_f32_e64 s[0:1], s29, v20
	s_nop 1
	v_cndmask_b32_e64 v22, 0, 32, s[0:1]
	v_ldexp_f32 v20, v20, v22
	v_log_f32_e32 v22, v20
	v_cndmask_b32_e32 v20, 0, v111, vcc
	v_sub_f32_e32 v20, v19, v20
	v_min_f32_e32 v19, 0, v21
	v_mul_f32_e32 v21, 0x3f317217, v22
	v_fma_f32 v21, v22, s30, -v21
	v_fmac_f32_e32 v21, 0x3377d1cf, v22
	v_fmac_f32_e32 v21, 0x3f317217, v22
	v_cmp_lt_f32_e64 vcc, |v22|, s31
	s_nop 1
	v_cndmask_b32_e32 v21, v22, v21, vcc
	v_cndmask_b32_e64 v22, 0, v111, s[0:1]
	v_sub_f32_e32 v21, v21, v22
	v_pk_add_f32 v[18:19], v[18:19], v[20:21] neg_lo:[0,1] neg_hi:[0,1]
	s_nop 0
	v_pk_mul_f32 v[94:95], v[18:19], s[6:7] op_sel_hi:[1,0]
	global_load_dwordx4 v[18:21], v123, s[48:49] offset:64
	global_load_dwordx4 v[22:25], v123, s[46:47] offset:64
	global_load_dwordx4 v[26:29], v123, s[46:47] offset:3136
	global_load_dwordx4 v[30:33], v123, s[46:47] offset:3648
	global_load_dwordx4 v[34:37], v110, s[12:13] offset:64
	global_load_dwordx4 v[38:41], v110, s[12:13] offset:576
	global_load_dwordx4 v[42:45], v110, s[12:13] offset:1088
	global_load_dwordx4 v[46:49], v110, s[12:13] offset:1600
	global_load_dwordx4 v[50:53], v110, s[12:13] offset:2112
	global_load_dwordx4 v[54:57], v110, s[12:13] offset:2624
	global_load_dwordx4 v[58:61], v110, s[12:13] offset:3136
	global_load_dwordx4 v[62:65], v110, s[12:13] offset:3648
	global_load_dwordx4 v[96:99], v123, s[46:47] offset:576
	global_load_dwordx4 v[100:103], v123, s[46:47] offset:1088
	global_load_dwordx4 v[104:107], v123, s[46:47] offset:1600
	global_load_dwordx4 v[124:127], v123, s[46:47] offset:2112
	global_load_dwordx4 v[128:131], v123, s[46:47] offset:2624
	s_waitcnt vmcnt(15)
	v_fma_f32 v142, v22, v118, v18
	v_fma_f32 v20, v24, v118, v20
	s_waitcnt vmcnt(14)
	v_mov_b32_e32 v132, v26
	s_waitcnt vmcnt(13)
	v_mov_b32_e32 v133, v30
	v_fma_f32 v23, v23, v118, v19
	v_mov_b32_e32 v30, v27
	v_mov_b32_e32 v18, v28
	v_mov_b32_e32 v19, v32
	v_pk_mul_f32 v[26:27], v[132:133], v[72:73]
	s_waitcnt vmcnt(12)
	v_mov_b32_e32 v134, v34
	s_waitcnt vmcnt(11)
	v_mov_b32_e32 v135, v38
	s_waitcnt vmcnt(4)
	v_fmac_f32_e32 v142, v96, v117
	v_fmac_f32_e32 v20, v98, v117
	s_waitcnt vmcnt(3)
	v_fmac_f32_e32 v142, v100, v122
	v_fmac_f32_e32 v20, v102, v122
	s_waitcnt vmcnt(2)
	v_fmac_f32_e32 v142, v104, v121
	v_fmac_f32_e32 v20, v106, v121
	s_waitcnt vmcnt(1)
	v_fmac_f32_e32 v142, v124, v120
	v_fmac_f32_e32 v20, v126, v120
	s_waitcnt vmcnt(0)
	v_fmac_f32_e32 v142, v128, v119
	v_fmac_f32_e32 v23, v97, v117
	v_pk_mul_f32 v[18:19], v[18:19], v[72:73]
	v_fmac_f32_e32 v20, v130, v119
	v_add_f32_e32 v24, v142, v26
	v_mov_b32_e32 v38, v35
	v_pk_mul_f32 v[34:35], v[134:135], v[74:75]
	v_fmac_f32_e32 v23, v101, v122
	v_add_f32_e32 v18, v18, v20
	v_add_f32_e32 v20, v24, v27
	v_mov_b32_e32 v136, v42
	v_mov_b32_e32 v137, v46
	v_fmac_f32_e32 v23, v105, v121
	v_add_f32_e32 v20, v20, v34
	v_mov_b32_e32 v46, v43
	v_pk_mul_f32 v[42:43], v[136:137], v[78:79]
	v_fmac_f32_e32 v23, v125, v120
	v_add_f32_e32 v20, v20, v35
	v_mov_b32_e32 v138, v50
	v_mov_b32_e32 v139, v54
	v_pk_mul_f32 v[30:31], v[30:31], v[72:73]
	v_fmac_f32_e32 v23, v129, v119
	v_add_f32_e32 v20, v20, v42
	v_mov_b32_e32 v54, v51
	v_pk_mul_f32 v[50:51], v[138:139], v[80:81]
	v_add_f32_e32 v23, v30, v23
	v_add_f32_e32 v20, v20, v43
	v_mov_b32_e32 v140, v58
	v_mov_b32_e32 v141, v62
	v_pk_mul_f32 v[38:39], v[38:39], v[74:75]
	v_add_f32_e32 v23, v31, v23
	v_add_f32_e32 v20, v20, v50
	v_mov_b32_e32 v62, v59
	v_pk_mul_f32 v[58:59], v[140:141], v[82:83]
	v_add_f32_e32 v23, v38, v23
	v_add_f32_e32 v20, v20, v51
	v_pk_mul_f32 v[46:47], v[46:47], v[78:79]
	v_add_f32_e32 v23, v39, v23
	v_add_f32_e32 v20, v20, v58
	v_add_f32_e32 v23, v46, v23
	v_add_f32_e32 v20, v20, v59
	v_pk_mul_f32 v[54:55], v[54:55], v[80:81]
	v_add_f32_e32 v23, v47, v23
	v_mul_f32_e64 v24, |v20|, s28
	v_add_f32_e32 v23, v54, v23
	v_exp_f32_e32 v24, v24
	v_pk_mul_f32 v[62:63], v[62:63], v[82:83]
	v_add_f32_e32 v23, v55, v23
	v_add_f32_e32 v23, v62, v23
	v_add_f32_e32 v23, v63, v23
	v_mul_f32_e64 v26, |v23|, s28
	v_add_f32_e32 v27, v19, v18
	v_add_f32_e32 v19, 1.0, v24
	v_exp_f32_e32 v26, v26
	v_cmp_gt_f32_e32 vcc, s29, v19
	v_min_f32_e32 v18, 0, v20
	v_mov_b32_e32 v22, v36
	v_cndmask_b32_e64 v24, 0, 32, vcc
	v_ldexp_f32 v19, v19, v24
	v_log_f32_e32 v24, v19
	v_add_f32_e32 v20, 1.0, v26
	v_cmp_gt_f32_e64 s[0:1], s29, v20
	v_min_f32_e32 v19, 0, v23
	v_cndmask_b32_e32 v23, 0, v111, vcc
	v_cndmask_b32_e64 v26, 0, 32, s[0:1]
	v_ldexp_f32 v20, v20, v26
	v_mul_f32_e32 v26, 0x3f317217, v24
	v_fma_f32 v26, v24, s30, -v26
	v_fmac_f32_e32 v26, 0x3377d1cf, v24
	v_fmac_f32_e32 v26, 0x3f317217, v24
	v_cmp_lt_f32_e64 vcc, |v24|, s31
	v_log_f32_e32 v20, v20
	v_fmac_f32_e32 v21, v25, v118
	v_cndmask_b32_e32 v24, v24, v26, vcc
	v_sub_f32_e32 v26, v24, v23
	v_mov_b32_e32 v23, v40
	v_pk_mul_f32 v[22:23], v[22:23], v[74:75]
	v_mul_f32_e32 v28, 0x3f317217, v20
	v_add_f32_e32 v22, v22, v27
	v_add_f32_e32 v24, v23, v22
	v_mov_b32_e32 v22, v44
	v_mov_b32_e32 v23, v48
	v_pk_mul_f32 v[22:23], v[22:23], v[78:79]
	v_fma_f32 v28, v20, s30, -v28
	v_add_f32_e32 v22, v22, v24
	v_add_f32_e32 v24, v23, v22
	v_mov_b32_e32 v22, v52
	v_mov_b32_e32 v23, v56
	v_pk_mul_f32 v[22:23], v[22:23], v[80:81]
	v_fmac_f32_e32 v28, 0x3377d1cf, v20
	v_add_f32_e32 v22, v22, v24
	v_add_f32_e32 v24, v23, v22
	v_mov_b32_e32 v22, v60
	v_mov_b32_e32 v23, v64
	v_pk_mul_f32 v[22:23], v[22:23], v[82:83]
	v_fmac_f32_e32 v28, 0x3f317217, v20
	v_add_f32_e32 v22, v22, v24
	v_add_f32_e32 v22, v23, v22
	v_mul_f32_e64 v23, |v22|, s28
	v_exp_f32_e32 v23, v23
	v_cmp_lt_f32_e64 vcc, |v20|, s31
	v_cndmask_b32_e64 v24, 0, v111, s[0:1]
	v_fmac_f32_e32 v21, v99, v117
	v_cndmask_b32_e32 v20, v20, v28, vcc
	v_sub_f32_e32 v27, v20, v24
	v_add_f32_e32 v20, 1.0, v23
	v_fmac_f32_e32 v21, v103, v122
	v_cmp_gt_f32_e32 vcc, s29, v20
	v_fmac_f32_e32 v21, v107, v121
	v_pk_add_f32 v[18:19], v[18:19], v[26:27] neg_lo:[0,1] neg_hi:[0,1]
	v_cndmask_b32_e64 v23, 0, 32, vcc
	v_fmac_f32_e32 v21, v127, v120
	v_mov_b32_e32 v32, v29
	v_ldexp_f32 v20, v20, v23
	v_pk_mul_f32 v[96:97], v[18:19], s[6:7] op_sel_hi:[1,0]
	v_min_f32_e32 v18, 0, v22
	v_fmac_f32_e32 v21, v131, v119
	v_pk_mul_f32 v[22:23], v[32:33], v[72:73]
	v_log_f32_e32 v24, v20
	v_add_f32_e32 v20, v22, v21
	v_mov_b32_e32 v40, v37
	v_add_f32_e32 v22, v23, v20
	v_pk_mul_f32 v[20:21], v[40:41], v[74:75]
	v_mov_b32_e32 v48, v45
	v_add_f32_e32 v20, v20, v22
	v_add_f32_e32 v22, v21, v20
	v_pk_mul_f32 v[20:21], v[48:49], v[78:79]
	v_mov_b32_e32 v56, v53
	v_add_f32_e32 v20, v20, v22
	v_add_f32_e32 v22, v21, v20
	v_pk_mul_f32 v[20:21], v[56:57], v[80:81]
	v_mov_b32_e32 v64, v61
	v_add_f32_e32 v20, v20, v22
	v_add_f32_e32 v22, v21, v20
	v_pk_mul_f32 v[20:21], v[64:65], v[82:83]
	v_mul_f32_e32 v19, 0x3f317217, v24
	v_add_f32_e32 v20, v20, v22
	v_add_f32_e32 v21, v21, v20
	v_mul_f32_e64 v20, |v21|, s28
	v_exp_f32_e32 v20, v20
	v_fma_f32 v19, v24, s30, -v19
	v_fmac_f32_e32 v19, 0x3377d1cf, v24
	v_fmac_f32_e32 v19, 0x3f317217, v24
	v_cmp_lt_f32_e64 s[0:1], |v24|, s31
	v_add_f32_e32 v20, 1.0, v20
	s_nop 0
	v_cndmask_b32_e64 v19, v24, v19, s[0:1]
	v_cmp_gt_f32_e64 s[0:1], s29, v20
	s_nop 1
	v_cndmask_b32_e64 v22, 0, 32, s[0:1]
	v_ldexp_f32 v20, v20, v22
	v_log_f32_e32 v22, v20
	v_cndmask_b32_e32 v20, 0, v111, vcc
	v_sub_f32_e32 v20, v19, v20
	v_min_f32_e32 v19, 0, v21
	v_mul_f32_e32 v21, 0x3f317217, v22
	v_fma_f32 v21, v22, s30, -v21
	v_fmac_f32_e32 v21, 0x3377d1cf, v22
	v_fmac_f32_e32 v21, 0x3f317217, v22
	v_cmp_lt_f32_e64 vcc, |v22|, s31
	s_nop 1
	v_cndmask_b32_e32 v21, v22, v21, vcc
	v_cndmask_b32_e64 v22, 0, v111, s[0:1]
	v_sub_f32_e32 v21, v21, v22
	v_pk_add_f32 v[18:19], v[18:19], v[20:21] neg_lo:[0,1] neg_hi:[0,1]
	s_nop 0
	v_pk_mul_f32 v[98:99], v[18:19], s[6:7] op_sel_hi:[1,0]
	global_load_dwordx4 v[18:21], v123, s[48:49] offset:80
	global_load_dwordx4 v[22:25], v123, s[46:47] offset:80
	global_load_dwordx4 v[26:29], v123, s[46:47] offset:3152
	global_load_dwordx4 v[30:33], v123, s[46:47] offset:3664
	global_load_dwordx4 v[34:37], v110, s[12:13] offset:80
	global_load_dwordx4 v[38:41], v110, s[12:13] offset:592
	global_load_dwordx4 v[42:45], v110, s[12:13] offset:1104
	global_load_dwordx4 v[46:49], v110, s[12:13] offset:1616
	global_load_dwordx4 v[50:53], v110, s[12:13] offset:2128
	global_load_dwordx4 v[54:57], v110, s[12:13] offset:2640
	global_load_dwordx4 v[58:61], v110, s[12:13] offset:3152
	global_load_dwordx4 v[62:65], v110, s[12:13] offset:3664
	global_load_dwordx4 v[100:103], v123, s[46:47] offset:592
	global_load_dwordx4 v[104:107], v123, s[46:47] offset:1104
	global_load_dwordx4 v[124:127], v123, s[46:47] offset:1616
	global_load_dwordx4 v[128:131], v123, s[46:47] offset:2128
	global_load_dwordx4 v[132:135], v123, s[46:47] offset:2640
	s_waitcnt vmcnt(15)
	v_fma_f32 v146, v22, v118, v18
	v_fma_f32 v20, v24, v118, v20
	s_waitcnt vmcnt(14)
	v_mov_b32_e32 v136, v26
	s_waitcnt vmcnt(13)
	v_mov_b32_e32 v137, v30
	v_fma_f32 v23, v23, v118, v19
	v_mov_b32_e32 v30, v27
	v_mov_b32_e32 v18, v28
	v_mov_b32_e32 v19, v32
	v_pk_mul_f32 v[26:27], v[136:137], v[72:73]
	s_waitcnt vmcnt(12)
	v_mov_b32_e32 v138, v34
	s_waitcnt vmcnt(11)
	v_mov_b32_e32 v139, v38
	s_waitcnt vmcnt(4)
	v_fmac_f32_e32 v146, v100, v117
	v_fmac_f32_e32 v20, v102, v117
	s_waitcnt vmcnt(3)
	v_fmac_f32_e32 v146, v104, v122
	v_fmac_f32_e32 v20, v106, v122
	s_waitcnt vmcnt(2)
	v_fmac_f32_e32 v146, v124, v121
	v_fmac_f32_e32 v20, v126, v121
	s_waitcnt vmcnt(1)
	v_fmac_f32_e32 v146, v128, v120
	v_fmac_f32_e32 v20, v130, v120
	s_waitcnt vmcnt(0)
	v_fmac_f32_e32 v146, v132, v119
	v_fmac_f32_e32 v23, v101, v117
	v_pk_mul_f32 v[18:19], v[18:19], v[72:73]
	v_fmac_f32_e32 v20, v134, v119
	v_add_f32_e32 v24, v146, v26
	v_mov_b32_e32 v38, v35
	v_pk_mul_f32 v[34:35], v[138:139], v[74:75]
	v_fmac_f32_e32 v23, v105, v122
	v_add_f32_e32 v18, v18, v20
	v_add_f32_e32 v20, v24, v27
	v_mov_b32_e32 v140, v42
	v_mov_b32_e32 v141, v46
	v_fmac_f32_e32 v23, v125, v121
	v_add_f32_e32 v20, v20, v34
	v_mov_b32_e32 v46, v43
	v_pk_mul_f32 v[42:43], v[140:141], v[78:79]
	v_fmac_f32_e32 v23, v129, v120
	v_add_f32_e32 v20, v20, v35
	v_mov_b32_e32 v142, v50
	v_mov_b32_e32 v143, v54
	v_pk_mul_f32 v[30:31], v[30:31], v[72:73]
	v_fmac_f32_e32 v23, v133, v119
	v_add_f32_e32 v20, v20, v42
	v_mov_b32_e32 v54, v51
	v_pk_mul_f32 v[50:51], v[142:143], v[80:81]
	v_add_f32_e32 v23, v30, v23
	v_add_f32_e32 v20, v20, v43
	v_mov_b32_e32 v144, v58
	v_mov_b32_e32 v145, v62
	v_pk_mul_f32 v[38:39], v[38:39], v[74:75]
	v_add_f32_e32 v23, v31, v23
	v_add_f32_e32 v20, v20, v50
	v_mov_b32_e32 v62, v59
	v_pk_mul_f32 v[58:59], v[144:145], v[82:83]
	v_add_f32_e32 v23, v38, v23
	v_add_f32_e32 v20, v20, v51
	v_pk_mul_f32 v[46:47], v[46:47], v[78:79]
	v_add_f32_e32 v23, v39, v23
	v_add_f32_e32 v20, v20, v58
	v_add_f32_e32 v23, v46, v23
	v_add_f32_e32 v20, v20, v59
	v_pk_mul_f32 v[54:55], v[54:55], v[80:81]
	v_add_f32_e32 v23, v47, v23
	v_mul_f32_e64 v24, |v20|, s28
	v_add_f32_e32 v23, v54, v23
	v_exp_f32_e32 v24, v24
	v_pk_mul_f32 v[62:63], v[62:63], v[82:83]
	v_add_f32_e32 v23, v55, v23
	v_add_f32_e32 v23, v62, v23
	v_add_f32_e32 v23, v63, v23
	v_mul_f32_e64 v26, |v23|, s28
	v_add_f32_e32 v27, v19, v18
	v_add_f32_e32 v19, 1.0, v24
	v_exp_f32_e32 v26, v26
	v_cmp_gt_f32_e32 vcc, s29, v19
	v_min_f32_e32 v18, 0, v20
	v_mov_b32_e32 v22, v36
	v_cndmask_b32_e64 v24, 0, 32, vcc
	v_ldexp_f32 v19, v19, v24
	v_log_f32_e32 v24, v19
	v_add_f32_e32 v20, 1.0, v26
	v_cmp_gt_f32_e64 s[0:1], s29, v20
	v_min_f32_e32 v19, 0, v23
	v_cndmask_b32_e32 v23, 0, v111, vcc
	v_cndmask_b32_e64 v26, 0, 32, s[0:1]
	v_ldexp_f32 v20, v20, v26
	v_mul_f32_e32 v26, 0x3f317217, v24
	v_fma_f32 v26, v24, s30, -v26
	v_fmac_f32_e32 v26, 0x3377d1cf, v24
	v_fmac_f32_e32 v26, 0x3f317217, v24
	v_cmp_lt_f32_e64 vcc, |v24|, s31
	v_log_f32_e32 v20, v20
	v_fmac_f32_e32 v21, v25, v118
	v_cndmask_b32_e32 v24, v24, v26, vcc
	v_sub_f32_e32 v26, v24, v23
	v_mov_b32_e32 v23, v40
	v_pk_mul_f32 v[22:23], v[22:23], v[74:75]
	v_mul_f32_e32 v28, 0x3f317217, v20
	v_add_f32_e32 v22, v22, v27
	v_add_f32_e32 v24, v23, v22
	v_mov_b32_e32 v22, v44
	v_mov_b32_e32 v23, v48
	v_pk_mul_f32 v[22:23], v[22:23], v[78:79]
	v_fma_f32 v28, v20, s30, -v28
	v_add_f32_e32 v22, v22, v24
	v_add_f32_e32 v24, v23, v22
	v_mov_b32_e32 v22, v52
	v_mov_b32_e32 v23, v56
	v_pk_mul_f32 v[22:23], v[22:23], v[80:81]
	v_fmac_f32_e32 v28, 0x3377d1cf, v20
	v_add_f32_e32 v22, v22, v24
	v_add_f32_e32 v24, v23, v22
	v_mov_b32_e32 v22, v60
	v_mov_b32_e32 v23, v64
	v_pk_mul_f32 v[22:23], v[22:23], v[82:83]
	v_fmac_f32_e32 v28, 0x3f317217, v20
	v_add_f32_e32 v22, v22, v24
	v_add_f32_e32 v22, v23, v22
	v_mul_f32_e64 v23, |v22|, s28
	v_exp_f32_e32 v23, v23
	v_cmp_lt_f32_e64 vcc, |v20|, s31
	v_cndmask_b32_e64 v24, 0, v111, s[0:1]
	v_fmac_f32_e32 v21, v103, v117
	v_cndmask_b32_e32 v20, v20, v28, vcc
	v_sub_f32_e32 v27, v20, v24
	v_add_f32_e32 v20, 1.0, v23
	v_fmac_f32_e32 v21, v107, v122
	v_cmp_gt_f32_e32 vcc, s29, v20
	v_fmac_f32_e32 v21, v127, v121
	v_pk_add_f32 v[18:19], v[18:19], v[26:27] neg_lo:[0,1] neg_hi:[0,1]
	v_cndmask_b32_e64 v23, 0, 32, vcc
	v_fmac_f32_e32 v21, v131, v120
	v_mov_b32_e32 v32, v29
	v_ldexp_f32 v20, v20, v23
	v_pk_mul_f32 v[100:101], v[18:19], s[6:7] op_sel_hi:[1,0]
	v_min_f32_e32 v18, 0, v22
	v_fmac_f32_e32 v21, v135, v119
	v_pk_mul_f32 v[22:23], v[32:33], v[72:73]
	v_log_f32_e32 v24, v20
	v_add_f32_e32 v20, v22, v21
	v_mov_b32_e32 v40, v37
	v_add_f32_e32 v22, v23, v20
	v_pk_mul_f32 v[20:21], v[40:41], v[74:75]
	v_mov_b32_e32 v48, v45
	v_add_f32_e32 v20, v20, v22
	v_add_f32_e32 v22, v21, v20
	v_pk_mul_f32 v[20:21], v[48:49], v[78:79]
	v_mov_b32_e32 v56, v53
	v_add_f32_e32 v20, v20, v22
	v_add_f32_e32 v22, v21, v20
	v_pk_mul_f32 v[20:21], v[56:57], v[80:81]
	v_mov_b32_e32 v64, v61
	v_add_f32_e32 v20, v20, v22
	v_add_f32_e32 v22, v21, v20
	v_pk_mul_f32 v[20:21], v[64:65], v[82:83]
	v_mul_f32_e32 v19, 0x3f317217, v24
	v_add_f32_e32 v20, v20, v22
	v_add_f32_e32 v21, v21, v20
	v_mul_f32_e64 v20, |v21|, s28
	v_exp_f32_e32 v20, v20
	v_fma_f32 v19, v24, s30, -v19
	v_fmac_f32_e32 v19, 0x3377d1cf, v24
	v_fmac_f32_e32 v19, 0x3f317217, v24
	v_cmp_lt_f32_e64 s[0:1], |v24|, s31
	v_add_f32_e32 v20, 1.0, v20
	s_nop 0
	v_cndmask_b32_e64 v19, v24, v19, s[0:1]
	v_cmp_gt_f32_e64 s[0:1], s29, v20
	s_nop 1
	v_cndmask_b32_e64 v22, 0, 32, s[0:1]
	v_ldexp_f32 v20, v20, v22
	v_log_f32_e32 v22, v20
	v_cndmask_b32_e32 v20, 0, v111, vcc
	v_sub_f32_e32 v20, v19, v20
	v_min_f32_e32 v19, 0, v21
	v_mul_f32_e32 v21, 0x3f317217, v22
	v_fma_f32 v21, v22, s30, -v21
	v_fmac_f32_e32 v21, 0x3377d1cf, v22
	v_fmac_f32_e32 v21, 0x3f317217, v22
	v_cmp_lt_f32_e64 vcc, |v22|, s31
	s_nop 1
	v_cndmask_b32_e32 v21, v22, v21, vcc
	v_cndmask_b32_e64 v22, 0, v111, s[0:1]
	v_sub_f32_e32 v21, v21, v22
	v_pk_add_f32 v[18:19], v[18:19], v[20:21] neg_lo:[0,1] neg_hi:[0,1]
	s_nop 0
	v_pk_mul_f32 v[102:103], v[18:19], s[6:7] op_sel_hi:[1,0]
	global_load_dwordx4 v[18:21], v123, s[48:49] offset:96
	global_load_dwordx4 v[22:25], v123, s[46:47] offset:96
	global_load_dwordx4 v[26:29], v123, s[46:47] offset:3168
	global_load_dwordx4 v[30:33], v123, s[46:47] offset:3680
	global_load_dwordx4 v[34:37], v110, s[12:13] offset:96
	global_load_dwordx4 v[38:41], v110, s[12:13] offset:608
	global_load_dwordx4 v[42:45], v110, s[12:13] offset:1120
	global_load_dwordx4 v[46:49], v110, s[12:13] offset:1632
	global_load_dwordx4 v[50:53], v110, s[12:13] offset:2144
	global_load_dwordx4 v[54:57], v110, s[12:13] offset:2656
	global_load_dwordx4 v[58:61], v110, s[12:13] offset:3168
	global_load_dwordx4 v[62:65], v110, s[12:13] offset:3680
	global_load_dwordx4 v[104:107], v123, s[46:47] offset:608
	global_load_dwordx4 v[124:127], v123, s[46:47] offset:1120
	global_load_dwordx4 v[128:131], v123, s[46:47] offset:1632
	global_load_dwordx4 v[132:135], v123, s[46:47] offset:2144
	global_load_dwordx4 v[136:139], v123, s[46:47] offset:2656
	s_waitcnt vmcnt(15)
	v_fma_f32 v150, v22, v118, v18
	v_fma_f32 v20, v24, v118, v20
	s_waitcnt vmcnt(14)
	v_mov_b32_e32 v140, v26
	s_waitcnt vmcnt(13)
	v_mov_b32_e32 v141, v30
	v_fma_f32 v23, v23, v118, v19
	v_mov_b32_e32 v30, v27
	v_mov_b32_e32 v18, v28
	v_mov_b32_e32 v19, v32
	v_pk_mul_f32 v[26:27], v[140:141], v[72:73]
	s_waitcnt vmcnt(12)
	v_mov_b32_e32 v142, v34
	s_waitcnt vmcnt(11)
	v_mov_b32_e32 v143, v38
	s_waitcnt vmcnt(4)
	v_fmac_f32_e32 v150, v104, v117
	v_fmac_f32_e32 v20, v106, v117
	s_waitcnt vmcnt(3)
	v_fmac_f32_e32 v150, v124, v122
	v_fmac_f32_e32 v20, v126, v122
	s_waitcnt vmcnt(2)
	v_fmac_f32_e32 v150, v128, v121
	v_fmac_f32_e32 v20, v130, v121
	s_waitcnt vmcnt(1)
	v_fmac_f32_e32 v150, v132, v120
	v_fmac_f32_e32 v20, v134, v120
	s_waitcnt vmcnt(0)
	v_fmac_f32_e32 v150, v136, v119
	v_fmac_f32_e32 v23, v105, v117
	v_pk_mul_f32 v[18:19], v[18:19], v[72:73]
	v_fmac_f32_e32 v20, v138, v119
	v_add_f32_e32 v24, v150, v26
	v_mov_b32_e32 v38, v35
	v_pk_mul_f32 v[34:35], v[142:143], v[74:75]
	v_fmac_f32_e32 v23, v125, v122
	v_add_f32_e32 v18, v18, v20
	v_add_f32_e32 v20, v24, v27
	v_mov_b32_e32 v144, v42
	v_mov_b32_e32 v145, v46
	v_fmac_f32_e32 v23, v129, v121
	v_add_f32_e32 v20, v20, v34
	v_mov_b32_e32 v46, v43
	v_pk_mul_f32 v[42:43], v[144:145], v[78:79]
	v_fmac_f32_e32 v23, v133, v120
	v_add_f32_e32 v20, v20, v35
	v_mov_b32_e32 v146, v50
	v_mov_b32_e32 v147, v54
	v_pk_mul_f32 v[30:31], v[30:31], v[72:73]
	v_fmac_f32_e32 v23, v137, v119
	v_add_f32_e32 v20, v20, v42
	v_mov_b32_e32 v54, v51
	v_pk_mul_f32 v[50:51], v[146:147], v[80:81]
	v_add_f32_e32 v23, v30, v23
	v_add_f32_e32 v20, v20, v43
	v_mov_b32_e32 v148, v58
	v_mov_b32_e32 v149, v62
	v_pk_mul_f32 v[38:39], v[38:39], v[74:75]
	v_add_f32_e32 v23, v31, v23
	v_add_f32_e32 v20, v20, v50
	v_mov_b32_e32 v62, v59
	v_pk_mul_f32 v[58:59], v[148:149], v[82:83]
	v_add_f32_e32 v23, v38, v23
	v_add_f32_e32 v20, v20, v51
	v_pk_mul_f32 v[46:47], v[46:47], v[78:79]
	v_add_f32_e32 v23, v39, v23
	v_add_f32_e32 v20, v20, v58
	v_add_f32_e32 v23, v46, v23
	v_add_f32_e32 v20, v20, v59
	v_pk_mul_f32 v[54:55], v[54:55], v[80:81]
	v_add_f32_e32 v23, v47, v23
	v_mul_f32_e64 v24, |v20|, s28
	v_add_f32_e32 v23, v54, v23
	v_exp_f32_e32 v24, v24
	v_pk_mul_f32 v[62:63], v[62:63], v[82:83]
	v_add_f32_e32 v23, v55, v23
	v_add_f32_e32 v23, v62, v23
	v_add_f32_e32 v23, v63, v23
	v_mul_f32_e64 v26, |v23|, s28
	v_add_f32_e32 v27, v19, v18
	v_add_f32_e32 v19, 1.0, v24
	v_exp_f32_e32 v26, v26
	v_cmp_gt_f32_e32 vcc, s29, v19
	v_min_f32_e32 v18, 0, v20
	v_mov_b32_e32 v22, v36
	v_cndmask_b32_e64 v24, 0, 32, vcc
	v_ldexp_f32 v19, v19, v24
	v_log_f32_e32 v24, v19
	v_add_f32_e32 v20, 1.0, v26
	v_cmp_gt_f32_e64 s[0:1], s29, v20
	v_min_f32_e32 v19, 0, v23
	v_cndmask_b32_e32 v23, 0, v111, vcc
	v_cndmask_b32_e64 v26, 0, 32, s[0:1]
	v_ldexp_f32 v20, v20, v26
	v_mul_f32_e32 v26, 0x3f317217, v24
	v_fma_f32 v26, v24, s30, -v26
	v_fmac_f32_e32 v26, 0x3377d1cf, v24
	v_fmac_f32_e32 v26, 0x3f317217, v24
	v_cmp_lt_f32_e64 vcc, |v24|, s31
	v_log_f32_e32 v20, v20
	v_fmac_f32_e32 v21, v25, v118
	v_cndmask_b32_e32 v24, v24, v26, vcc
	v_sub_f32_e32 v26, v24, v23
	v_mov_b32_e32 v23, v40
	v_pk_mul_f32 v[22:23], v[22:23], v[74:75]
	v_mul_f32_e32 v28, 0x3f317217, v20
	v_add_f32_e32 v22, v22, v27
	v_add_f32_e32 v24, v23, v22
	v_mov_b32_e32 v22, v44
	v_mov_b32_e32 v23, v48
	v_pk_mul_f32 v[22:23], v[22:23], v[78:79]
	v_fma_f32 v28, v20, s30, -v28
	v_add_f32_e32 v22, v22, v24
	v_add_f32_e32 v24, v23, v22
	v_mov_b32_e32 v22, v52
	v_mov_b32_e32 v23, v56
	v_pk_mul_f32 v[22:23], v[22:23], v[80:81]
	v_fmac_f32_e32 v28, 0x3377d1cf, v20
	v_add_f32_e32 v22, v22, v24
	v_add_f32_e32 v24, v23, v22
	v_mov_b32_e32 v22, v60
	v_mov_b32_e32 v23, v64
	v_pk_mul_f32 v[22:23], v[22:23], v[82:83]
	v_fmac_f32_e32 v28, 0x3f317217, v20
	v_add_f32_e32 v22, v22, v24
	v_add_f32_e32 v22, v23, v22
	v_mul_f32_e64 v23, |v22|, s28
	v_exp_f32_e32 v23, v23
	v_cmp_lt_f32_e64 vcc, |v20|, s31
	v_cndmask_b32_e64 v24, 0, v111, s[0:1]
	v_fmac_f32_e32 v21, v107, v117
	v_cndmask_b32_e32 v20, v20, v28, vcc
	v_sub_f32_e32 v27, v20, v24
	v_add_f32_e32 v20, 1.0, v23
	v_fmac_f32_e32 v21, v127, v122
	v_cmp_gt_f32_e32 vcc, s29, v20
	v_fmac_f32_e32 v21, v131, v121
	v_pk_add_f32 v[18:19], v[18:19], v[26:27] neg_lo:[0,1] neg_hi:[0,1]
	v_cndmask_b32_e64 v23, 0, 32, vcc
	v_fmac_f32_e32 v21, v135, v120
	v_mov_b32_e32 v32, v29
	v_ldexp_f32 v20, v20, v23
	v_pk_mul_f32 v[104:105], v[18:19], s[6:7] op_sel_hi:[1,0]
	v_min_f32_e32 v18, 0, v22
	v_fmac_f32_e32 v21, v139, v119
	v_pk_mul_f32 v[22:23], v[32:33], v[72:73]
	v_log_f32_e32 v24, v20
	v_add_f32_e32 v20, v22, v21
	v_mov_b32_e32 v40, v37
	v_add_f32_e32 v22, v23, v20
	v_pk_mul_f32 v[20:21], v[40:41], v[74:75]
	v_mov_b32_e32 v48, v45
	v_add_f32_e32 v20, v20, v22
	v_add_f32_e32 v22, v21, v20
	v_pk_mul_f32 v[20:21], v[48:49], v[78:79]
	v_mov_b32_e32 v56, v53
	v_add_f32_e32 v20, v20, v22
	v_add_f32_e32 v22, v21, v20
	v_pk_mul_f32 v[20:21], v[56:57], v[80:81]
	v_mov_b32_e32 v64, v61
	v_add_f32_e32 v20, v20, v22
	v_add_f32_e32 v22, v21, v20
	v_pk_mul_f32 v[20:21], v[64:65], v[82:83]
	v_mul_f32_e32 v19, 0x3f317217, v24
	v_add_f32_e32 v20, v20, v22
	v_add_f32_e32 v21, v21, v20
	v_mul_f32_e64 v20, |v21|, s28
	v_exp_f32_e32 v20, v20
	v_fma_f32 v19, v24, s30, -v19
	v_fmac_f32_e32 v19, 0x3377d1cf, v24
	v_fmac_f32_e32 v19, 0x3f317217, v24
	v_cmp_lt_f32_e64 s[0:1], |v24|, s31
	v_add_f32_e32 v20, 1.0, v20
	s_nop 0
	v_cndmask_b32_e64 v19, v24, v19, s[0:1]
	v_cmp_gt_f32_e64 s[0:1], s29, v20
	s_nop 1
	v_cndmask_b32_e64 v22, 0, 32, s[0:1]
	v_ldexp_f32 v20, v20, v22
	v_log_f32_e32 v22, v20
	v_cndmask_b32_e32 v20, 0, v111, vcc
	v_sub_f32_e32 v20, v19, v20
	v_min_f32_e32 v19, 0, v21
	v_mul_f32_e32 v21, 0x3f317217, v22
	v_fma_f32 v21, v22, s30, -v21
	v_fmac_f32_e32 v21, 0x3377d1cf, v22
	v_fmac_f32_e32 v21, 0x3f317217, v22
	v_cmp_lt_f32_e64 vcc, |v22|, s31
	s_nop 1
	v_cndmask_b32_e32 v21, v22, v21, vcc
	v_cndmask_b32_e64 v22, 0, v111, s[0:1]
	v_sub_f32_e32 v21, v21, v22
	v_pk_add_f32 v[18:19], v[18:19], v[20:21] neg_lo:[0,1] neg_hi:[0,1]
	s_nop 0
	v_pk_mul_f32 v[106:107], v[18:19], s[6:7] op_sel_hi:[1,0]
	global_load_dwordx4 v[18:21], v123, s[48:49] offset:112
	global_load_dwordx4 v[22:25], v123, s[46:47] offset:112
	global_load_dwordx4 v[26:29], v123, s[46:47] offset:3184
	global_load_dwordx4 v[30:33], v123, s[46:47] offset:3696
	global_load_dwordx4 v[34:37], v110, s[12:13] offset:112
	global_load_dwordx4 v[38:41], v110, s[12:13] offset:624
	global_load_dwordx4 v[42:45], v110, s[12:13] offset:1136
	global_load_dwordx4 v[46:49], v110, s[12:13] offset:1648
	global_load_dwordx4 v[50:53], v110, s[12:13] offset:2160
	global_load_dwordx4 v[54:57], v110, s[12:13] offset:2672
	global_load_dwordx4 v[58:61], v110, s[12:13] offset:3184
	global_load_dwordx4 v[62:65], v110, s[12:13] offset:3696
	global_load_dwordx4 v[124:127], v123, s[46:47] offset:624
	global_load_dwordx4 v[128:131], v123, s[46:47] offset:1136
	global_load_dwordx4 v[132:135], v123, s[46:47] offset:1648
	global_load_dwordx4 v[136:139], v123, s[46:47] offset:2160
	global_load_dwordx4 v[140:143], v123, s[46:47] offset:2672
	s_waitcnt vmcnt(15)
	v_fma_f32 v123, v22, v118, v18
	v_fma_f32 v20, v24, v118, v20
	s_waitcnt vmcnt(14)
	v_mov_b32_e32 v144, v26
	s_waitcnt vmcnt(13)
	v_mov_b32_e32 v145, v30
	v_fma_f32 v23, v23, v118, v19
	v_mov_b32_e32 v30, v27
	v_mov_b32_e32 v18, v28
	v_mov_b32_e32 v19, v32
	v_pk_mul_f32 v[26:27], v[144:145], v[72:73]
	s_waitcnt vmcnt(12)
	v_mov_b32_e32 v146, v34
	s_waitcnt vmcnt(11)
	v_mov_b32_e32 v147, v38
	s_waitcnt vmcnt(4)
	v_fmac_f32_e32 v123, v124, v117
	v_fmac_f32_e32 v20, v126, v117
	s_waitcnt vmcnt(3)
	v_fmac_f32_e32 v123, v128, v122
	v_fmac_f32_e32 v20, v130, v122
	s_waitcnt vmcnt(2)
	v_fmac_f32_e32 v123, v132, v121
	v_fmac_f32_e32 v20, v134, v121
	s_waitcnt vmcnt(1)
	v_fmac_f32_e32 v123, v136, v120
	v_fmac_f32_e32 v20, v138, v120
	s_waitcnt vmcnt(0)
	v_fmac_f32_e32 v123, v140, v119
	v_fmac_f32_e32 v23, v125, v117
	v_pk_mul_f32 v[18:19], v[18:19], v[72:73]
	v_fmac_f32_e32 v20, v142, v119
	v_add_f32_e32 v24, v123, v26
	v_mov_b32_e32 v38, v35
	v_pk_mul_f32 v[34:35], v[146:147], v[74:75]
	v_fmac_f32_e32 v23, v129, v122
	v_add_f32_e32 v18, v18, v20
	v_add_f32_e32 v20, v24, v27
	v_mov_b32_e32 v148, v42
	v_mov_b32_e32 v149, v46
	v_fmac_f32_e32 v23, v133, v121
	v_add_f32_e32 v20, v20, v34
	v_mov_b32_e32 v46, v43
	v_pk_mul_f32 v[42:43], v[148:149], v[78:79]
	v_fmac_f32_e32 v23, v137, v120
	v_add_f32_e32 v20, v20, v35
	v_mov_b32_e32 v150, v50
	v_mov_b32_e32 v151, v54
	v_pk_mul_f32 v[30:31], v[30:31], v[72:73]
	v_fmac_f32_e32 v23, v141, v119
	v_add_f32_e32 v20, v20, v42
	v_mov_b32_e32 v54, v51
	v_pk_mul_f32 v[50:51], v[150:151], v[80:81]
	v_add_f32_e32 v23, v30, v23
	v_add_f32_e32 v20, v20, v43
	v_mov_b32_e32 v152, v58
	v_mov_b32_e32 v153, v62
	v_pk_mul_f32 v[38:39], v[38:39], v[74:75]
	v_add_f32_e32 v23, v31, v23
	v_add_f32_e32 v20, v20, v50
	v_mov_b32_e32 v62, v59
	v_pk_mul_f32 v[58:59], v[152:153], v[82:83]
	v_add_f32_e32 v23, v38, v23
	v_add_f32_e32 v20, v20, v51
	v_pk_mul_f32 v[46:47], v[46:47], v[78:79]
	v_add_f32_e32 v23, v39, v23
	v_add_f32_e32 v20, v20, v58
	v_add_f32_e32 v23, v46, v23
	v_add_f32_e32 v20, v20, v59
	v_pk_mul_f32 v[54:55], v[54:55], v[80:81]
	v_add_f32_e32 v23, v47, v23
	v_mul_f32_e64 v24, |v20|, s28
	v_add_f32_e32 v23, v54, v23
	v_exp_f32_e32 v24, v24
	v_pk_mul_f32 v[62:63], v[62:63], v[82:83]
	v_add_f32_e32 v23, v55, v23
	v_add_f32_e32 v23, v62, v23
	v_add_f32_e32 v23, v63, v23
	v_mul_f32_e64 v26, |v23|, s28
	v_add_f32_e32 v27, v19, v18
	v_add_f32_e32 v19, 1.0, v24
	v_exp_f32_e32 v26, v26
	v_cmp_gt_f32_e32 vcc, s29, v19
	v_min_f32_e32 v18, 0, v20
	v_mov_b32_e32 v22, v36
	v_cndmask_b32_e64 v24, 0, 32, vcc
	v_ldexp_f32 v19, v19, v24
	v_log_f32_e32 v24, v19
	v_add_f32_e32 v20, 1.0, v26
	v_cmp_gt_f32_e64 s[0:1], s29, v20
	v_min_f32_e32 v19, 0, v23
	v_cndmask_b32_e32 v23, 0, v111, vcc
	v_cndmask_b32_e64 v26, 0, 32, s[0:1]
	v_ldexp_f32 v20, v20, v26
	v_mul_f32_e32 v26, 0x3f317217, v24
	v_fma_f32 v26, v24, s30, -v26
	v_fmac_f32_e32 v26, 0x3377d1cf, v24
	v_fmac_f32_e32 v26, 0x3f317217, v24
	v_cmp_lt_f32_e64 vcc, |v24|, s31
	v_log_f32_e32 v20, v20
	v_fmac_f32_e32 v21, v25, v118
	v_cndmask_b32_e32 v24, v24, v26, vcc
	v_sub_f32_e32 v26, v24, v23
	v_mov_b32_e32 v23, v40
	v_pk_mul_f32 v[22:23], v[22:23], v[74:75]
	v_mul_f32_e32 v28, 0x3f317217, v20
	v_add_f32_e32 v22, v22, v27
	v_add_f32_e32 v24, v23, v22
	v_mov_b32_e32 v22, v44
	v_mov_b32_e32 v23, v48
	v_pk_mul_f32 v[22:23], v[22:23], v[78:79]
	v_fma_f32 v28, v20, s30, -v28
	v_add_f32_e32 v22, v22, v24
	v_add_f32_e32 v24, v23, v22
	v_mov_b32_e32 v22, v52
	v_mov_b32_e32 v23, v56
	v_pk_mul_f32 v[22:23], v[22:23], v[80:81]
	v_fmac_f32_e32 v28, 0x3377d1cf, v20
	v_add_f32_e32 v22, v22, v24
	v_add_f32_e32 v24, v23, v22
	v_mov_b32_e32 v22, v60
	v_mov_b32_e32 v23, v64
	v_pk_mul_f32 v[22:23], v[22:23], v[82:83]
	v_fmac_f32_e32 v28, 0x3f317217, v20
	v_add_f32_e32 v22, v22, v24
	v_add_f32_e32 v24, v23, v22
	v_mul_f32_e64 v22, |v24|, s28
	v_exp_f32_e32 v22, v22
	v_cmp_lt_f32_e64 vcc, |v20|, s31
	v_cndmask_b32_e64 v23, 0, v111, s[0:1]
	v_fmac_f32_e32 v21, v127, v117
	v_cndmask_b32_e32 v20, v20, v28, vcc
	v_sub_f32_e32 v27, v20, v23
	v_add_f32_e32 v20, 1.0, v22
	v_fmac_f32_e32 v21, v131, v122
	v_cmp_gt_f32_e32 vcc, s29, v20
	v_fmac_f32_e32 v21, v135, v121
	v_pk_add_f32 v[18:19], v[18:19], v[26:27] neg_lo:[0,1] neg_hi:[0,1]
	v_cndmask_b32_e64 v22, 0, 32, vcc
	v_fmac_f32_e32 v21, v139, v120
	v_mov_b32_e32 v32, v29
	v_ldexp_f32 v20, v20, v22
	v_pk_mul_f32 v[22:23], v[18:19], s[6:7] op_sel_hi:[1,0]
	v_min_f32_e32 v18, 0, v24
	v_fmac_f32_e32 v21, v143, v119
	v_pk_mul_f32 v[24:25], v[32:33], v[72:73]
	v_log_f32_e32 v28, v20
	v_add_f32_e32 v20, v24, v21
	v_mov_b32_e32 v40, v37
	v_add_f32_e32 v24, v25, v20
	v_pk_mul_f32 v[20:21], v[40:41], v[74:75]
	v_mov_b32_e32 v48, v45
	v_add_f32_e32 v20, v20, v24
	v_add_f32_e32 v24, v21, v20
	v_pk_mul_f32 v[20:21], v[48:49], v[78:79]
	v_mov_b32_e32 v56, v53
	v_add_f32_e32 v20, v20, v24
	v_add_f32_e32 v24, v21, v20
	v_pk_mul_f32 v[20:21], v[56:57], v[80:81]
	v_mov_b32_e32 v64, v61
	v_add_f32_e32 v20, v20, v24
	v_add_f32_e32 v24, v21, v20
	v_pk_mul_f32 v[20:21], v[64:65], v[82:83]
	v_mul_f32_e32 v19, 0x3f317217, v28
	v_add_f32_e32 v20, v20, v24
	v_add_f32_e32 v21, v21, v20
	v_mul_f32_e64 v20, |v21|, s28
	v_exp_f32_e32 v20, v20
	v_fma_f32 v19, v28, s30, -v19
	v_fmac_f32_e32 v19, 0x3377d1cf, v28
	v_fmac_f32_e32 v19, 0x3f317217, v28
	v_cmp_lt_f32_e64 s[0:1], |v28|, s31
	v_add_f32_e32 v20, 1.0, v20
	s_nop 0
	v_cndmask_b32_e64 v19, v28, v19, s[0:1]
	v_cmp_gt_f32_e64 s[0:1], s29, v20
	s_nop 1
	v_cndmask_b32_e64 v24, 0, 32, s[0:1]
	v_ldexp_f32 v20, v20, v24
	v_log_f32_e32 v24, v20
	v_cndmask_b32_e32 v20, 0, v111, vcc
	v_sub_f32_e32 v20, v19, v20
	v_min_f32_e32 v19, 0, v21
	v_mul_f32_e32 v21, 0x3f317217, v24
	v_fma_f32 v21, v24, s30, -v21
	v_fmac_f32_e32 v21, 0x3377d1cf, v24
	v_fmac_f32_e32 v21, 0x3f317217, v24
	v_cmp_lt_f32_e64 vcc, |v24|, s31
	s_nop 1
	v_cndmask_b32_e32 v21, v24, v21, vcc
	v_cndmask_b32_e64 v24, 0, v111, s[0:1]
	v_sub_f32_e32 v21, v21, v24
	v_pk_add_f32 v[18:19], v[18:19], v[20:21] neg_lo:[0,1] neg_hi:[0,1]
	s_nop 0
	v_pk_mul_f32 v[20:21], v[18:19], s[6:7] op_sel_hi:[1,0]
	v_and_b32_e32 v18, 64, v112
	v_add_u32_e32 v19, -1, v112
	v_cmp_lt_i32_e32 vcc, v19, v18
	s_nop 1
	v_cndmask_b32_e32 v19, v19, v112, vcc
	v_lshlrev_b32_e32 v19, 2, v19
	ds_bpermute_b32 v24, v19, v70
	ds_bpermute_b32 v25, v19, v71
	ds_bpermute_b32 v26, v19, v76
	ds_bpermute_b32 v27, v19, v77
	ds_bpermute_b32 v28, v19, v84
	ds_bpermute_b32 v29, v19, v85
	ds_bpermute_b32 v30, v19, v86
	ds_bpermute_b32 v31, v19, v87
	ds_bpermute_b32 v32, v19, v88
	ds_bpermute_b32 v33, v19, v89
	ds_bpermute_b32 v34, v19, v90
	ds_bpermute_b32 v35, v19, v91
	ds_bpermute_b32 v36, v19, v92
	ds_bpermute_b32 v37, v19, v93
	ds_bpermute_b32 v38, v19, v94
	ds_bpermute_b32 v39, v19, v95
	ds_bpermute_b32 v40, v19, v96
	ds_bpermute_b32 v41, v19, v97
	ds_bpermute_b32 v42, v19, v98
	ds_bpermute_b32 v43, v19, v99
	ds_bpermute_b32 v44, v19, v100
	ds_bpermute_b32 v45, v19, v101
	ds_bpermute_b32 v46, v19, v102
	ds_bpermute_b32 v47, v19, v103
	ds_bpermute_b32 v48, v19, v104
	ds_bpermute_b32 v49, v19, v105
	ds_bpermute_b32 v50, v19, v106
	ds_bpermute_b32 v51, v19, v107
	ds_bpermute_b32 v52, v19, v22
	ds_bpermute_b32 v53, v19, v23
	ds_bpermute_b32 v54, v19, v20
	ds_bpermute_b32 v19, v19, v21
	v_cmp_gt_i32_e32 vcc, 1, v68
	s_waitcnt lgkmcnt(6)
	v_add_f32_e32 v49, v105, v49
	s_waitcnt lgkmcnt(3)
	v_add_f32_e32 v52, v22, v52
	v_add_f32_e32 v24, v70, v24
	s_waitcnt lgkmcnt(0)
	v_add_f32_e32 v19, v21, v19
	v_cndmask_b32_e32 v19, v19, v21, vcc
	v_cndmask_b32_e32 v21, v52, v22, vcc
	v_cndmask_b32_e32 v22, v49, v105, vcc
	v_add_u32_e32 v49, -2, v112
	v_cmp_lt_i32_e64 s[0:1], v49, v18
	v_add_f32_e32 v25, v71, v25
	v_add_f32_e32 v26, v76, v26
	v_add_f32_e32 v27, v77, v27
	v_add_f32_e32 v28, v84, v28
	v_add_f32_e32 v29, v85, v29
	v_add_f32_e32 v30, v86, v30
	v_add_f32_e32 v31, v87, v31
	v_add_f32_e32 v32, v88, v32
	v_add_f32_e32 v33, v89, v33
	v_add_f32_e32 v34, v90, v34
	v_add_f32_e32 v35, v91, v35
	v_add_f32_e32 v36, v92, v36
	v_add_f32_e32 v37, v93, v37
	v_add_f32_e32 v38, v94, v38
	v_add_f32_e32 v39, v95, v39
	v_add_f32_e32 v40, v96, v40
	v_add_f32_e32 v41, v97, v41
	v_add_f32_e32 v42, v98, v42
	v_add_f32_e32 v43, v99, v43
	v_add_f32_e32 v44, v100, v44
	v_add_f32_e32 v45, v101, v45
	v_add_f32_e32 v46, v102, v46
	v_add_f32_e32 v47, v103, v47
	v_add_f32_e32 v48, v104, v48
	v_add_f32_e32 v50, v106, v50
	v_add_f32_e32 v51, v107, v51
	v_add_f32_e32 v53, v23, v53
	v_add_f32_e32 v54, v20, v54
	v_cndmask_b32_e64 v49, v49, v112, s[0:1]
	v_cndmask_b32_e32 v24, v24, v70, vcc
	v_cndmask_b32_e32 v26, v26, v76, vcc
	v_cndmask_b32_e32 v27, v27, v77, vcc
	v_cndmask_b32_e32 v29, v29, v85, vcc
	v_cndmask_b32_e32 v30, v30, v86, vcc
	v_cndmask_b32_e32 v32, v32, v88, vcc
	v_cndmask_b32_e32 v33, v33, v89, vcc
	v_cndmask_b32_e32 v35, v35, v91, vcc
	v_cndmask_b32_e32 v36, v36, v92, vcc
	v_cndmask_b32_e32 v38, v38, v94, vcc
	v_cndmask_b32_e32 v39, v39, v95, vcc
	v_cndmask_b32_e32 v41, v41, v97, vcc
	v_cndmask_b32_e32 v42, v42, v98, vcc
	v_cndmask_b32_e32 v44, v44, v100, vcc
	v_cndmask_b32_e32 v45, v45, v101, vcc
	v_cndmask_b32_e32 v47, v47, v103, vcc
	v_cndmask_b32_e32 v48, v48, v104, vcc
	v_cndmask_b32_e32 v50, v50, v106, vcc
	v_cndmask_b32_e32 v51, v51, v107, vcc
	v_cndmask_b32_e32 v53, v53, v23, vcc
	v_cndmask_b32_e32 v54, v54, v20, vcc
	v_cndmask_b32_e32 v46, v46, v102, vcc
	v_cndmask_b32_e32 v43, v43, v99, vcc
	v_cndmask_b32_e32 v40, v40, v96, vcc
	v_cndmask_b32_e32 v37, v37, v93, vcc
	v_cndmask_b32_e32 v34, v34, v90, vcc
	v_lshlrev_b32_e32 v49, 2, v49
	v_cndmask_b32_e32 v31, v31, v87, vcc
	v_cndmask_b32_e32 v28, v28, v84, vcc
	v_cndmask_b32_e32 v25, v25, v71, vcc
	v_cndmask_b32_e32 v55, v24, v70, vcc
	v_cndmask_b32_e32 v56, v26, v76, vcc
	v_cndmask_b32_e32 v57, v27, v77, vcc
	v_cndmask_b32_e32 v58, v29, v85, vcc
	v_cndmask_b32_e32 v59, v30, v86, vcc
	v_cndmask_b32_e32 v60, v32, v88, vcc
	v_cndmask_b32_e32 v61, v33, v89, vcc
	v_cndmask_b32_e32 v62, v35, v91, vcc
	v_cndmask_b32_e32 v63, v36, v92, vcc
	v_cndmask_b32_e32 v64, v38, v94, vcc
	v_cndmask_b32_e32 v65, v39, v95, vcc
	v_cndmask_b32_e32 v70, v41, v97, vcc
	v_cndmask_b32_e32 v72, v42, v98, vcc
	v_cndmask_b32_e32 v73, v44, v100, vcc
	v_cndmask_b32_e32 v74, v45, v101, vcc
	v_cndmask_b32_e32 v75, v47, v103, vcc
	v_cndmask_b32_e32 v76, v48, v104, vcc
	v_cndmask_b32_e32 v77, v50, v106, vcc
	v_cndmask_b32_e32 v78, v51, v107, vcc
	ds_bpermute_b32 v52, v49, v24
	ds_bpermute_b32 v71, v49, v25
	ds_bpermute_b32 v79, v49, v26
	ds_bpermute_b32 v80, v49, v27
	ds_bpermute_b32 v81, v49, v28
	ds_bpermute_b32 v82, v49, v29
	ds_bpermute_b32 v83, v49, v30
	ds_bpermute_b32 v84, v49, v31
	ds_bpermute_b32 v85, v49, v32
	ds_bpermute_b32 v86, v49, v33
	ds_bpermute_b32 v87, v49, v34
	ds_bpermute_b32 v88, v49, v35
	ds_bpermute_b32 v89, v49, v36
	ds_bpermute_b32 v90, v49, v37
	ds_bpermute_b32 v91, v49, v38
	ds_bpermute_b32 v92, v49, v39
	ds_bpermute_b32 v93, v49, v40
	ds_bpermute_b32 v94, v49, v41
	ds_bpermute_b32 v95, v49, v42
	ds_bpermute_b32 v96, v49, v43
	ds_bpermute_b32 v97, v49, v44
	ds_bpermute_b32 v98, v49, v45
	ds_bpermute_b32 v99, v49, v46
	ds_bpermute_b32 v100, v49, v47
	ds_bpermute_b32 v101, v49, v48
	ds_bpermute_b32 v102, v49, v22
	ds_bpermute_b32 v103, v49, v50
	ds_bpermute_b32 v104, v49, v51
	ds_bpermute_b32 v105, v49, v21
	ds_bpermute_b32 v106, v49, v53
	ds_bpermute_b32 v107, v49, v54
	ds_bpermute_b32 v49, v49, v19
	v_cndmask_b32_e32 v23, v53, v23, vcc
	v_cndmask_b32_e32 v20, v54, v20, vcc
	v_cmp_gt_i32_e32 vcc, 2, v68
	s_waitcnt lgkmcnt(14)
	v_add_f32_e32 v52, v24, v52
	s_waitcnt lgkmcnt(0)
	v_add_f32_e32 v49, v19, v49
	v_cndmask_b32_e32 v19, v49, v19, vcc
	v_add_u32_e32 v49, -4, v112
	v_cmp_lt_i32_e64 s[0:1], v49, v18
	v_add_f32_e32 v71, v25, v71
	v_add_f32_e32 v79, v26, v79
	v_add_f32_e32 v80, v27, v80
	v_add_f32_e32 v81, v28, v81
	v_add_f32_e32 v82, v29, v82
	v_add_f32_e32 v83, v30, v83
	v_add_f32_e32 v84, v31, v84
	v_add_f32_e32 v85, v32, v85
	v_add_f32_e32 v86, v33, v86
	v_add_f32_e32 v87, v34, v87
	v_add_f32_e32 v88, v35, v88
	v_add_f32_e32 v89, v36, v89
	v_add_f32_e32 v90, v37, v90
	v_add_f32_e32 v91, v38, v91
	v_add_f32_e32 v92, v39, v92
	v_add_f32_e32 v93, v40, v93
	v_add_f32_e32 v94, v41, v94
	v_add_f32_e32 v95, v42, v95
	v_add_f32_e32 v96, v43, v96
	v_add_f32_e32 v97, v44, v97
	v_add_f32_e32 v98, v45, v98
	v_add_f32_e32 v99, v46, v99
	v_add_f32_e32 v100, v47, v100
	v_add_f32_e32 v101, v48, v101
	v_add_f32_e32 v102, v22, v102
	v_add_f32_e32 v103, v50, v103
	v_add_f32_e32 v104, v51, v104
	v_add_f32_e32 v105, v21, v105
	v_add_f32_e32 v106, v53, v106
	v_add_f32_e32 v107, v54, v107
	v_cndmask_b32_e64 v49, v49, v112, s[0:1]
	v_cndmask_b32_e32 v24, v52, v24, vcc
	v_cndmask_b32_e32 v26, v79, v26, vcc
	v_cndmask_b32_e32 v27, v80, v27, vcc
	v_cndmask_b32_e32 v29, v82, v29, vcc
	v_cndmask_b32_e32 v30, v83, v30, vcc
	v_cndmask_b32_e32 v32, v85, v32, vcc
	v_cndmask_b32_e32 v33, v86, v33, vcc
	v_cndmask_b32_e32 v35, v88, v35, vcc
	v_cndmask_b32_e32 v36, v89, v36, vcc
	v_cndmask_b32_e32 v38, v91, v38, vcc
	v_cndmask_b32_e32 v39, v92, v39, vcc
	v_cndmask_b32_e32 v41, v94, v41, vcc
	v_cndmask_b32_e32 v42, v95, v42, vcc
	v_cndmask_b32_e32 v44, v97, v44, vcc
	v_cndmask_b32_e32 v45, v98, v45, vcc
	v_cndmask_b32_e32 v47, v100, v47, vcc
	v_cndmask_b32_e32 v48, v101, v48, vcc
	v_cndmask_b32_e32 v50, v103, v50, vcc
	v_cndmask_b32_e32 v51, v104, v51, vcc
	v_cndmask_b32_e32 v53, v106, v53, vcc
	v_cndmask_b32_e32 v54, v107, v54, vcc
	v_cndmask_b32_e32 v21, v105, v21, vcc
	v_cndmask_b32_e32 v22, v102, v22, vcc
	v_cndmask_b32_e32 v46, v99, v46, vcc
	v_cndmask_b32_e32 v43, v96, v43, vcc
	v_cndmask_b32_e32 v40, v93, v40, vcc
	v_cndmask_b32_e32 v37, v90, v37, vcc
	v_cndmask_b32_e32 v34, v87, v34, vcc
	v_lshlrev_b32_e32 v49, 2, v49
	v_cndmask_b32_e32 v31, v84, v31, vcc
	v_cndmask_b32_e32 v28, v81, v28, vcc
	v_cndmask_b32_e32 v25, v71, v25, vcc
	v_cndmask_b32_e32 v20, v107, v20, vcc
	v_cndmask_b32_e32 v23, v106, v23, vcc
	v_cndmask_b32_e32 v78, v104, v78, vcc
	v_cndmask_b32_e32 v77, v103, v77, vcc
	v_cndmask_b32_e32 v76, v101, v76, vcc
	v_cndmask_b32_e32 v75, v100, v75, vcc
	v_cndmask_b32_e32 v74, v98, v74, vcc
	v_cndmask_b32_e32 v73, v97, v73, vcc
	v_cndmask_b32_e32 v72, v95, v72, vcc
	v_cndmask_b32_e32 v70, v94, v70, vcc
	v_cndmask_b32_e32 v65, v92, v65, vcc
	v_cndmask_b32_e32 v64, v91, v64, vcc
	v_cndmask_b32_e32 v63, v89, v63, vcc
	v_cndmask_b32_e32 v62, v88, v62, vcc
	v_cndmask_b32_e32 v61, v86, v61, vcc
	v_cndmask_b32_e32 v60, v85, v60, vcc
	v_cndmask_b32_e32 v59, v83, v59, vcc
	v_cndmask_b32_e32 v58, v82, v58, vcc
	v_cndmask_b32_e32 v57, v80, v57, vcc
	v_cndmask_b32_e32 v56, v79, v56, vcc
	v_cndmask_b32_e32 v52, v52, v55, vcc
	ds_bpermute_b32 v55, v49, v24
	ds_bpermute_b32 v71, v49, v25
	ds_bpermute_b32 v79, v49, v26
	ds_bpermute_b32 v80, v49, v27
	ds_bpermute_b32 v81, v49, v28
	ds_bpermute_b32 v82, v49, v29
	ds_bpermute_b32 v83, v49, v30
	ds_bpermute_b32 v84, v49, v31
	ds_bpermute_b32 v85, v49, v32
	ds_bpermute_b32 v86, v49, v33
	ds_bpermute_b32 v87, v49, v34
	ds_bpermute_b32 v88, v49, v35
	ds_bpermute_b32 v89, v49, v36
	ds_bpermute_b32 v90, v49, v37
	ds_bpermute_b32 v91, v49, v38
	ds_bpermute_b32 v92, v49, v39
	ds_bpermute_b32 v93, v49, v40
	ds_bpermute_b32 v94, v49, v41
	ds_bpermute_b32 v95, v49, v42
	ds_bpermute_b32 v96, v49, v43
	ds_bpermute_b32 v97, v49, v44
	ds_bpermute_b32 v98, v49, v45
	ds_bpermute_b32 v99, v49, v46
	ds_bpermute_b32 v100, v49, v47
	ds_bpermute_b32 v101, v49, v48
	ds_bpermute_b32 v102, v49, v22
	ds_bpermute_b32 v103, v49, v50
	ds_bpermute_b32 v104, v49, v51
	ds_bpermute_b32 v105, v49, v21
	ds_bpermute_b32 v106, v49, v53
	ds_bpermute_b32 v107, v49, v54
	ds_bpermute_b32 v49, v49, v19
	v_cmp_gt_i32_e32 vcc, 4, v68
	s_waitcnt lgkmcnt(14)
	v_add_f32_e32 v55, v24, v55
	v_add_f32_e32 v71, v25, v71
	v_cndmask_b32_e32 v24, v55, v24, vcc
	s_waitcnt lgkmcnt(0)
	v_add_f32_e32 v49, v19, v49
	v_cndmask_b32_e32 v19, v49, v19, vcc
	v_add_u32_e32 v49, -8, v112
	v_cmp_lt_i32_e64 s[0:1], v49, v18
	v_add_f32_e32 v79, v26, v79
	v_add_f32_e32 v80, v27, v80
	v_cndmask_b32_e64 v49, v49, v112, s[0:1]
	v_add_f32_e32 v82, v29, v82
	v_add_f32_e32 v83, v30, v83
	v_add_f32_e32 v85, v32, v85
	v_add_f32_e32 v86, v33, v86
	v_add_f32_e32 v88, v35, v88
	v_add_f32_e32 v89, v36, v89
	v_add_f32_e32 v91, v38, v91
	v_add_f32_e32 v92, v39, v92
	v_add_f32_e32 v94, v41, v94
	v_add_f32_e32 v95, v42, v95
	v_add_f32_e32 v97, v44, v97
	v_add_f32_e32 v98, v45, v98
	v_add_f32_e32 v100, v47, v100
	v_add_f32_e32 v101, v48, v101
	v_add_f32_e32 v103, v50, v103
	v_add_f32_e32 v104, v51, v104
	v_cndmask_b32_e32 v25, v71, v25, vcc
	v_lshlrev_b32_e32 v49, 2, v49
	v_cndmask_b32_e32 v52, v55, v52, vcc
	v_cndmask_b32_e32 v55, v79, v56, vcc
	v_cndmask_b32_e32 v56, v80, v57, vcc
	v_cndmask_b32_e32 v57, v82, v58, vcc
	v_cndmask_b32_e32 v58, v83, v59, vcc
	v_cndmask_b32_e32 v59, v85, v60, vcc
	v_cndmask_b32_e32 v60, v86, v61, vcc
	v_cndmask_b32_e32 v61, v88, v62, vcc
	v_cndmask_b32_e32 v62, v89, v63, vcc
	v_cndmask_b32_e32 v63, v91, v64, vcc
	v_cndmask_b32_e32 v64, v92, v65, vcc
	v_cndmask_b32_e32 v65, v94, v70, vcc
	v_cndmask_b32_e32 v70, v95, v72, vcc
	v_cndmask_b32_e32 v72, v97, v73, vcc
	v_cndmask_b32_e32 v73, v98, v74, vcc
	v_cndmask_b32_e32 v74, v100, v75, vcc
	v_cndmask_b32_e32 v75, v101, v76, vcc
	v_cndmask_b32_e32 v76, v103, v77, vcc
	v_cndmask_b32_e32 v77, v104, v78, vcc
	ds_bpermute_b32 v71, v49, v24
	ds_bpermute_b32 v78, v49, v25
	v_add_f32_e32 v81, v28, v81
	v_cndmask_b32_e32 v26, v79, v26, vcc
	v_cndmask_b32_e32 v29, v82, v29, vcc
	v_cndmask_b32_e32 v30, v83, v30, vcc
	v_cndmask_b32_e32 v28, v81, v28, vcc
	v_cndmask_b32_e32 v27, v80, v27, vcc
	s_waitcnt lgkmcnt(1)
	v_add_f32_e32 v24, v24, v71
	s_waitcnt lgkmcnt(0)
	v_add_f32_e32 v71, v25, v78
	ds_bpermute_b32 v78, v49, v26
	ds_bpermute_b32 v80, v49, v28
	ds_bpermute_b32 v81, v49, v29
	ds_bpermute_b32 v82, v49, v30
	v_add_f32_e32 v87, v34, v87
	v_cndmask_b32_e32 v32, v85, v32, vcc
	v_cndmask_b32_e32 v33, v86, v33, vcc
	v_cndmask_b32_e32 v35, v88, v35, vcc
	v_cndmask_b32_e32 v34, v87, v34, vcc
	s_waitcnt lgkmcnt(3)
	v_add_f32_e32 v26, v26, v78
	s_waitcnt lgkmcnt(2)
	v_add_f32_e32 v78, v28, v80
	s_waitcnt lgkmcnt(1)
	v_add_f32_e32 v29, v29, v81
	s_waitcnt lgkmcnt(0)
	v_add_f32_e32 v30, v30, v82
	ds_bpermute_b32 v80, v49, v32
	ds_bpermute_b32 v81, v49, v33
	ds_bpermute_b32 v82, v49, v34
	ds_bpermute_b32 v83, v49, v35
	v_add_f32_e32 v90, v37, v90
	v_add_f32_e32 v93, v40, v93
	v_cndmask_b32_e32 v36, v89, v36, vcc
	v_cndmask_b32_e32 v38, v91, v38, vcc
	v_cndmask_b32_e32 v40, v93, v40, vcc
	v_cndmask_b32_e32 v37, v90, v37, vcc
	s_waitcnt lgkmcnt(3)
	v_add_f32_e32 v32, v32, v80
	s_waitcnt lgkmcnt(2)
	v_add_f32_e32 v33, v33, v81
	s_waitcnt lgkmcnt(1)
	v_add_f32_e32 v80, v34, v82
	s_waitcnt lgkmcnt(0)
	v_add_f32_e32 v35, v35, v83
	ds_bpermute_b32 v81, v49, v36
	ds_bpermute_b32 v82, v49, v37
	ds_bpermute_b32 v83, v49, v38
	ds_bpermute_b32 v85, v49, v40
	v_add_f32_e32 v96, v43, v96
	v_add_f32_e32 v84, v31, v84
	v_cndmask_b32_e32 v39, v92, v39, vcc
	v_cndmask_b32_e32 v41, v94, v41, vcc
	v_cndmask_b32_e32 v44, v97, v44, vcc
	v_cndmask_b32_e32 v45, v98, v45, vcc
	v_cndmask_b32_e32 v43, v96, v43, vcc
	v_cndmask_b32_e32 v31, v84, v31, vcc
	ds_bpermute_b32 v84, v49, v39
	s_waitcnt lgkmcnt(4)
	v_add_f32_e32 v36, v36, v81
	s_waitcnt lgkmcnt(3)
	v_add_f32_e32 v81, v37, v82
	s_waitcnt lgkmcnt(2)
	v_add_f32_e32 v38, v38, v83
	s_waitcnt lgkmcnt(1)
	v_add_f32_e32 v82, v40, v85
	ds_bpermute_b32 v83, v49, v41
	ds_bpermute_b32 v85, v49, v43
	ds_bpermute_b32 v86, v49, v44
	ds_bpermute_b32 v87, v49, v45
	v_add_f32_e32 v102, v22, v102
	v_cndmask_b32_e32 v42, v95, v42, vcc
	v_cndmask_b32_e32 v47, v100, v47, vcc
	v_cndmask_b32_e32 v48, v101, v48, vcc
	v_cndmask_b32_e32 v50, v103, v50, vcc
	v_cndmask_b32_e32 v22, v102, v22, vcc
	ds_bpermute_b32 v79, v49, v27
	s_waitcnt lgkmcnt(5)
	v_add_f32_e32 v39, v39, v84
	ds_bpermute_b32 v84, v49, v42
	s_waitcnt lgkmcnt(5)
	v_add_f32_e32 v41, v41, v83
	s_waitcnt lgkmcnt(4)
	v_add_f32_e32 v83, v43, v85
	s_waitcnt lgkmcnt(3)
	v_add_f32_e32 v44, v44, v86
	s_waitcnt lgkmcnt(2)
	v_add_f32_e32 v45, v45, v87
	ds_bpermute_b32 v85, v49, v47
	ds_bpermute_b32 v86, v49, v48
	ds_bpermute_b32 v87, v49, v22
	ds_bpermute_b32 v88, v49, v50
	v_add_f32_e32 v99, v46, v99
	v_add_f32_e32 v105, v21, v105
	v_add_f32_e32 v106, v53, v106
	v_add_f32_e32 v107, v54, v107
	v_cndmask_b32_e32 v51, v104, v51, vcc
	v_cndmask_b32_e32 v53, v106, v53, vcc
	v_cndmask_b32_e32 v54, v107, v54, vcc
	v_cndmask_b32_e32 v21, v105, v21, vcc
	v_cndmask_b32_e32 v46, v99, v46, vcc
	s_waitcnt lgkmcnt(5)
	v_add_f32_e32 v27, v27, v79
	ds_bpermute_b32 v79, v49, v31
	s_waitcnt lgkmcnt(5)
	v_add_f32_e32 v42, v42, v84
	ds_bpermute_b32 v84, v49, v46
	s_waitcnt lgkmcnt(5)
	v_add_f32_e32 v47, v47, v85
	s_waitcnt lgkmcnt(4)
	v_add_f32_e32 v48, v48, v86
	s_waitcnt lgkmcnt(3)
	v_add_f32_e32 v85, v22, v87
	s_waitcnt lgkmcnt(2)
	v_add_f32_e32 v50, v50, v88
	ds_bpermute_b32 v86, v49, v51
	ds_bpermute_b32 v87, v49, v21
	ds_bpermute_b32 v88, v49, v53
	ds_bpermute_b32 v89, v49, v54
	ds_bpermute_b32 v49, v49, v19
	v_cndmask_b32_e32 v23, v106, v23, vcc
	v_cndmask_b32_e32 v20, v107, v20, vcc
	s_waitcnt lgkmcnt(4)
	v_add_f32_e32 v51, v51, v86
	v_cmp_gt_i32_e32 vcc, 8, v68
	s_waitcnt lgkmcnt(0)
	v_add_f32_e32 v49, v19, v49
	v_add_f32_e32 v79, v31, v79
	v_cndmask_b32_e32 v19, v49, v19, vcc
	v_cndmask_b32_e32 v49, v51, v77, vcc
	v_add_u32_e32 v51, -16, v112
	v_cmp_lt_i32_e64 s[0:1], v51, v18
	v_add_f32_e32 v84, v46, v84
	v_add_f32_e32 v86, v21, v87
	v_cndmask_b32_e64 v51, v51, v112, s[0:1]
	v_add_f32_e32 v53, v53, v88
	v_add_f32_e32 v54, v54, v89
	v_cndmask_b32_e32 v41, v41, v65, vcc
	v_cndmask_b32_e32 v33, v33, v60, vcc
	v_lshlrev_b32_e32 v51, 2, v51
	v_cndmask_b32_e32 v20, v54, v20, vcc
	v_cndmask_b32_e32 v23, v53, v23, vcc
	v_cndmask_b32_e32 v21, v86, v21, vcc
	v_cndmask_b32_e32 v50, v50, v76, vcc
	v_cndmask_b32_e32 v22, v85, v22, vcc
	v_cndmask_b32_e32 v48, v48, v75, vcc
	v_cndmask_b32_e32 v47, v47, v74, vcc
	v_cndmask_b32_e32 v46, v84, v46, vcc
	v_cndmask_b32_e32 v45, v45, v73, vcc
	v_cndmask_b32_e32 v44, v44, v72, vcc
	v_cndmask_b32_e32 v43, v83, v43, vcc
	v_cndmask_b32_e32 v42, v42, v70, vcc
	v_cndmask_b32_e32 v40, v82, v40, vcc
	v_cndmask_b32_e32 v39, v39, v64, vcc
	v_cndmask_b32_e32 v38, v38, v63, vcc
	v_cndmask_b32_e32 v37, v81, v37, vcc
	v_cndmask_b32_e32 v36, v36, v62, vcc
	v_cndmask_b32_e32 v35, v35, v61, vcc
	v_cndmask_b32_e32 v34, v80, v34, vcc
	v_cndmask_b32_e32 v32, v32, v59, vcc
	v_cndmask_b32_e32 v31, v79, v31, vcc
	v_cndmask_b32_e32 v30, v30, v58, vcc
	v_cndmask_b32_e32 v29, v29, v57, vcc
	v_cndmask_b32_e32 v28, v78, v28, vcc
	v_cndmask_b32_e32 v24, v24, v52, vcc
	v_cndmask_b32_e32 v27, v27, v56, vcc
	v_cndmask_b32_e32 v26, v26, v55, vcc
	v_cndmask_b32_e32 v25, v71, v25, vcc
	ds_bpermute_b32 v61, v51, v33
	ds_bpermute_b32 v73, v51, v41
	ds_bpermute_b32 v52, v51, v24
	ds_bpermute_b32 v53, v51, v25
	ds_bpermute_b32 v54, v51, v26
	ds_bpermute_b32 v55, v51, v27
	ds_bpermute_b32 v56, v51, v28
	ds_bpermute_b32 v57, v51, v29
	ds_bpermute_b32 v58, v51, v30
	ds_bpermute_b32 v59, v51, v31
	ds_bpermute_b32 v60, v51, v32
	ds_bpermute_b32 v62, v51, v34
	ds_bpermute_b32 v63, v51, v35
	ds_bpermute_b32 v64, v51, v36
	ds_bpermute_b32 v65, v51, v37
	ds_bpermute_b32 v70, v51, v38
	ds_bpermute_b32 v71, v51, v39
	ds_bpermute_b32 v72, v51, v40
	ds_bpermute_b32 v74, v51, v42
	ds_bpermute_b32 v75, v51, v43
	ds_bpermute_b32 v76, v51, v44
	ds_bpermute_b32 v77, v51, v45
	ds_bpermute_b32 v78, v51, v46
	ds_bpermute_b32 v79, v51, v47
	ds_bpermute_b32 v80, v51, v48
	ds_bpermute_b32 v81, v51, v22
	ds_bpermute_b32 v82, v51, v50
	ds_bpermute_b32 v83, v51, v49
	ds_bpermute_b32 v84, v51, v21
	ds_bpermute_b32 v85, v51, v23
	ds_bpermute_b32 v86, v51, v20
	ds_bpermute_b32 v51, v51, v19
	v_cmp_gt_i32_e32 vcc, 16, v68
	s_waitcnt lgkmcnt(14)
	v_add_f32_e32 v61, v33, v61
	v_add_f32_e32 v73, v41, v73
	v_cndmask_b32_e32 v61, v61, v33, vcc
	v_cndmask_b32_e32 v73, v73, v41, vcc
	s_waitcnt lgkmcnt(3)
	v_add_f32_e32 v84, v21, v84
	s_waitcnt lgkmcnt(0)
	v_add_f32_e32 v51, v19, v51
	v_cndmask_b32_e32 v93, v61, v33, vcc
	v_cndmask_b32_e32 v33, v73, v41, vcc
	v_cndmask_b32_e32 v41, v51, v19, vcc
	v_cndmask_b32_e32 v19, v84, v21, vcc
	v_subrev_u32_e32 v21, 32, v112
	v_add_f32_e32 v57, v29, v57
	v_add_f32_e32 v79, v47, v79
	v_cmp_lt_i32_e64 s[0:1], v21, v18
	v_add_f32_e32 v52, v24, v52
	v_add_f32_e32 v53, v25, v53
	v_cndmask_b32_e32 v57, v57, v29, vcc
	v_add_f32_e32 v60, v32, v60
	v_add_f32_e32 v74, v42, v74
	v_cndmask_b32_e32 v79, v79, v47, vcc
	v_cndmask_b32_e64 v18, v21, v112, s[0:1]
	v_cndmask_b32_e32 v52, v52, v24, vcc
	v_cndmask_b32_e32 v60, v60, v32, vcc
	v_cndmask_b32_e32 v74, v74, v42, vcc
	v_add_f32_e32 v81, v22, v81
	v_cndmask_b32_e32 v91, v57, v29, vcc
	v_cndmask_b32_e32 v29, v79, v47, vcc
	v_cndmask_b32_e32 v47, v53, v25, vcc
	v_lshlrev_b32_e32 v18, 2, v18
	v_cndmask_b32_e32 v94, v60, v32, vcc
	v_cndmask_b32_e32 v32, v74, v42, vcc
	v_cndmask_b32_e32 v42, v81, v22, vcc
	ds_bpermute_b32 v21, v18, v52
	ds_bpermute_b32 v22, v18, v47
	v_add_f32_e32 v63, v35, v63
	v_add_f32_e32 v64, v36, v64
	v_add_f32_e32 v80, v48, v80
	v_add_f32_e32 v54, v26, v54
	v_add_f32_e32 v55, v27, v55
	v_add_f32_e32 v56, v28, v56
	v_add_f32_e32 v58, v30, v58
	v_cndmask_b32_e32 v63, v63, v35, vcc
	v_cndmask_b32_e32 v64, v64, v36, vcc
	v_cndmask_b32_e32 v80, v80, v48, vcc
	v_add_f32_e32 v82, v50, v82
	v_add_f32_e32 v83, v49, v83
	v_cndmask_b32_e32 v54, v54, v26, vcc
	v_cndmask_b32_e32 v55, v55, v27, vcc
	v_cndmask_b32_e32 v58, v58, v30, vcc
	v_cndmask_b32_e32 v82, v82, v50, vcc
	v_cndmask_b32_e32 v83, v83, v49, vcc
	v_cndmask_b32_e32 v92, v63, v35, vcc
	v_cndmask_b32_e32 v35, v64, v36, vcc
	v_cndmask_b32_e32 v36, v80, v48, vcc
	v_cndmask_b32_e32 v48, v56, v28, vcc
	v_cndmask_b32_e32 v89, v52, v24, vcc
	v_cndmask_b32_e32 v90, v58, v30, vcc
	v_cndmask_b32_e32 v30, v83, v49, vcc
	v_cndmask_b32_e32 v24, v82, v50, vcc
	s_waitcnt lgkmcnt(1)
	v_add_f32_e32 v49, v52, v21
	s_waitcnt lgkmcnt(0)
	v_add_f32_e32 v50, v47, v22
	ds_bpermute_b32 v21, v18, v54
	ds_bpermute_b32 v22, v18, v55
	ds_bpermute_b32 v25, v18, v48
	v_add_f32_e32 v76, v44, v76
	v_add_f32_e32 v59, v31, v59
	v_cndmask_b32_e32 v76, v76, v44, vcc
	v_add_f32_e32 v78, v46, v78
	v_cndmask_b32_e32 v88, v54, v26, vcc
	v_cndmask_b32_e32 v26, v76, v44, vcc
	v_cndmask_b32_e32 v44, v78, v46, vcc
	v_cndmask_b32_e32 v46, v59, v31, vcc
	ds_bpermute_b32 v28, v18, v57
	ds_bpermute_b32 v31, v18, v58
	s_waitcnt lgkmcnt(4)
	v_add_f32_e32 v51, v54, v21
	s_waitcnt lgkmcnt(3)
	v_add_f32_e32 v52, v55, v22
	s_waitcnt lgkmcnt(2)
	v_add_f32_e32 v53, v48, v25
	ds_bpermute_b32 v21, v18, v46
	ds_bpermute_b32 v22, v18, v60
	ds_bpermute_b32 v25, v18, v61
	v_add_f32_e32 v77, v45, v77
	v_add_f32_e32 v62, v34, v62
	v_add_f32_e32 v65, v37, v65
	v_add_f32_e32 v70, v38, v70
	v_cndmask_b32_e32 v77, v77, v45, vcc
	v_cndmask_b32_e32 v70, v70, v38, vcc
	v_cndmask_b32_e32 v87, v55, v27, vcc
	v_cndmask_b32_e32 v27, v77, v45, vcc
	v_cndmask_b32_e32 v37, v65, v37, vcc
	v_cndmask_b32_e32 v45, v62, v34, vcc
	s_waitcnt lgkmcnt(4)
	v_add_f32_e32 v54, v57, v28
	s_waitcnt lgkmcnt(3)
	v_add_f32_e32 v55, v58, v31
	ds_bpermute_b32 v28, v18, v45
	s_waitcnt lgkmcnt(3)
	v_add_f32_e32 v56, v46, v21
	s_waitcnt lgkmcnt(2)
	v_add_f32_e32 v57, v60, v22
	s_waitcnt lgkmcnt(1)
	v_add_f32_e32 v58, v61, v25
	ds_bpermute_b32 v21, v18, v64
	ds_bpermute_b32 v22, v18, v37
	ds_bpermute_b32 v25, v18, v70
	v_add_f32_e32 v71, v39, v71
	v_add_f32_e32 v75, v43, v75
	v_cndmask_b32_e32 v71, v71, v39, vcc
	v_cndmask_b32_e32 v43, v75, v43, vcc
	ds_bpermute_b32 v31, v18, v63
	s_waitcnt lgkmcnt(4)
	v_add_f32_e32 v59, v45, v28
	ds_bpermute_b32 v28, v18, v71
	s_waitcnt lgkmcnt(4)
	v_add_f32_e32 v34, v64, v21
	s_waitcnt lgkmcnt(3)
	v_add_f32_e32 v61, v37, v22
	s_waitcnt lgkmcnt(2)
	v_add_f32_e32 v62, v70, v25
	ds_bpermute_b32 v21, v18, v73
	ds_bpermute_b32 v22, v18, v74
	ds_bpermute_b32 v25, v18, v43
	v_add_f32_e32 v72, v40, v72
	v_cndmask_b32_e32 v39, v71, v39, vcc
	v_cndmask_b32_e32 v38, v70, v38, vcc
	v_cndmask_b32_e32 v40, v72, v40, vcc
	s_waitcnt lgkmcnt(4)
	v_add_f32_e32 v60, v63, v31
	s_waitcnt lgkmcnt(3)
	v_add_f32_e32 v63, v71, v28
	ds_bpermute_b32 v28, v18, v76
	s_waitcnt lgkmcnt(3)
	v_add_f32_e32 v65, v73, v21
	s_waitcnt lgkmcnt(2)
	v_add_f32_e32 v70, v74, v22
	s_waitcnt lgkmcnt(1)
	v_add_f32_e32 v71, v43, v25
	ds_bpermute_b32 v21, v18, v44
	ds_bpermute_b32 v22, v18, v79
	ds_bpermute_b32 v25, v18, v80
	ds_bpermute_b32 v72, v18, v42
	ds_bpermute_b32 v73, v18, v82
	ds_bpermute_b32 v64, v18, v77
	v_add_f32_e32 v85, v23, v85
	v_cndmask_b32_e32 v85, v85, v23, vcc
	v_add_f32_e32 v86, v20, v86
	v_cndmask_b32_e32 v86, v86, v20, vcc
	ds_bpermute_b32 v31, v18, v40
	s_waitcnt lgkmcnt(7)
	v_add_f32_e32 v28, v76, v28
	s_waitcnt lgkmcnt(6)
	v_add_f32_e32 v74, v44, v21
	s_waitcnt lgkmcnt(5)
	v_add_f32_e32 v75, v79, v22
	s_waitcnt lgkmcnt(4)
	v_add_f32_e32 v22, v80, v25
	s_waitcnt lgkmcnt(3)
	v_add_f32_e32 v25, v42, v72
	s_waitcnt lgkmcnt(2)
	v_add_f32_e32 v72, v82, v73
	ds_bpermute_b32 v21, v18, v83
	ds_bpermute_b32 v73, v18, v19
	ds_bpermute_b32 v76, v18, v85
	s_waitcnt lgkmcnt(4)
	v_add_f32_e32 v64, v77, v64
	ds_bpermute_b32 v77, v18, v86
	ds_bpermute_b32 v18, v18, v41
	s_lshl_b32 s0, s38, 3
	s_or_b32 s0, s36, s0
	v_cndmask_b32_e32 v20, v86, v20, vcc
	v_cndmask_b32_e32 v23, v85, v23, vcc
	s_waitcnt lgkmcnt(5)
	v_add_f32_e32 v31, v40, v31
	s_waitcnt lgkmcnt(4)
	v_add_f32_e32 v78, v83, v21
	s_waitcnt lgkmcnt(3)
	v_add_f32_e32 v21, v19, v73
	s_waitcnt lgkmcnt(2)
	v_add_f32_e32 v73, v85, v76
	v_cmp_gt_i32_e32 vcc, 32, v68
	s_mul_hi_i32 s1, s0, 0x104
	s_mulk_i32 s0, 0x104
	s_waitcnt lgkmcnt(1)
	v_add_f32_e32 v76, v86, v77
	s_waitcnt lgkmcnt(0)
	v_add_f32_e32 v77, v41, v18
	v_cndmask_b32_e32 v18, v21, v19, vcc
	v_cndmask_b32_e32 v19, v73, v23, vcc
	v_cndmask_b32_e32 v23, v25, v42, vcc
	v_cndmask_b32_e32 v25, v78, v30, vcc
	v_cndmask_b32_e32 v30, v31, v40, vcc
	v_cndmask_b32_e32 v40, v59, v45, vcc
	v_cndmask_b32_e32 v45, v56, v46, vcc
	v_cndmask_b32_e32 v46, v49, v89, vcc
	v_cndmask_b32_e32 v49, v52, v87, vcc
	s_add_u32 s12, s0, s37
	v_lshl_or_b32 v52, v112, 2, v116
	v_lshrrev_b32_e32 v255, 2, v52
	s_nop 0
	v_readfirstlane_b32 s101, v255
	s_nop 3
	v_cndmask_b32_e32 v42, v53, v48, vcc
	s_addc_u32 s13, s1, 0
	v_readlane_b32 s98, v46, s101
	s_lshl_b64 s[0:1], s[12:13], 13
	s_add_u32 s14, s19, s0
	v_cndmask_b32_e32 v47, v50, v47, vcc
	v_cndmask_b32_e32 v48, v51, v88, vcc
	s_addc_u32 s15, s22, s1
	v_lshlrev_b64 v[50:51], 7, v[68:69]
	v_cndmask_b32_e32 v20, v76, v20, vcc
	v_cndmask_b32_e32 v21, v77, v41, vcc
	v_cndmask_b32_e32 v22, v22, v36, vcc
	v_cndmask_b32_e32 v34, v34, v35, vcc
	v_cndmask_b32_e32 v35, v61, v37, vcc
	v_cndmask_b32_e32 v36, v62, v38, vcc
	v_cndmask_b32_e32 v37, v63, v39, vcc
	v_lshl_add_u64 v[50:51], s[14:15], 0, v[50:51]
	v_cndmask_b32_e32 v24, v72, v24, vcc
	v_cndmask_b32_e32 v26, v28, v26, vcc
	v_cndmask_b32_e32 v27, v64, v27, vcc
	v_cndmask_b32_e32 v28, v74, v44, vcc
	v_cndmask_b32_e32 v29, v75, v29, vcc
	v_cndmask_b32_e32 v31, v65, v33, vcc
	v_cndmask_b32_e32 v32, v70, v32, vcc
	v_cndmask_b32_e32 v33, v71, v43, vcc
	v_cndmask_b32_e32 v38, v57, v94, vcc
	v_cndmask_b32_e32 v39, v58, v93, vcc
	v_cndmask_b32_e32 v41, v60, v92, vcc
	v_cndmask_b32_e32 v43, v54, v91, vcc
	v_cndmask_b32_e32 v44, v55, v90, vcc
	global_store_dwordx4 v[50:51], v[46:49], off
	global_store_dwordx4 v[50:51], v[42:45], off offset:16
	global_store_dwordx4 v[50:51], v[38:41], off offset:32
	global_store_dwordx4 v[50:51], v[34:37], off offset:48
	global_store_dwordx4 v[50:51], v[30:33], off offset:64
	global_store_dwordx4 v[50:51], v[26:29], off offset:80
	global_store_dwordx4 v[50:51], v[22:25], off offset:96
	v_sub_f32_e32 v53, s98, v46
	global_store_dwordx4 v[50:51], v[18:21], off offset:112
	v_readlane_b32 s98, v47, s101
	v_mul_f32_e32 v53, 0x3fb8aa3b, v53
	v_exp_f32_e32 v53, v53
	v_lshlrev_b32_e32 v51, 16, v14
	v_and_b32_e32 v14, 0xffff0000, v14
	v_sub_f32_e32 v50, s98, v47
	v_mul_f32_e32 v51, v53, v51
	v_mul_f32_e32 v50, 0x3fb8aa3b, v50
	v_bfe_u32 v53, v51, 16, 1
	v_exp_f32_e32 v50, v50
	v_add3_u32 v51, v51, v53, s34
	ds_write_b16_d16_hi v66, v51 offset:8192
	v_readlane_b32 s98, v48, s101
	v_mul_f32_e32 v14, v50, v14
	v_bfe_u32 v50, v14, 16, 1
	v_add3_u32 v14, v14, v50, s34
	ds_write_b16_d16_hi v66, v14 offset:8320
	v_sub_f32_e32 v50, s98, v48
	v_readlane_b32 s98, v49, s101
	v_mul_f32_e32 v50, 0x3fb8aa3b, v50
	v_exp_f32_e32 v50, v50
	v_lshlrev_b32_e32 v51, 16, v15
	v_and_b32_e32 v15, 0xffff0000, v15
	v_sub_f32_e32 v14, s98, v49
	v_mul_f32_e32 v50, v50, v51
	v_mul_f32_e32 v14, 0x3fb8aa3b, v14
	v_bfe_u32 v51, v50, 16, 1
	v_exp_f32_e32 v14, v14
	v_add3_u32 v50, v50, v51, s34
	ds_write_b16_d16_hi v66, v50 offset:8448
	v_readlane_b32 s98, v42, s101
	v_mul_f32_e32 v14, v14, v15
	v_bfe_u32 v15, v14, 16, 1
	v_add3_u32 v14, v14, v15, s34
	ds_write_b16_d16_hi v66, v14 offset:8576
	v_sub_f32_e32 v15, s98, v42
	v_readlane_b32 s98, v43, s101
	v_mul_f32_e32 v15, 0x3fb8aa3b, v15
	v_exp_f32_e32 v15, v15
	v_lshlrev_b32_e32 v50, 16, v16
	v_and_b32_e32 v16, 0xffff0000, v16
	v_sub_f32_e32 v14, s98, v43
	v_mul_f32_e32 v15, v15, v50
	v_mul_f32_e32 v14, 0x3fb8aa3b, v14
	v_bfe_u32 v50, v15, 16, 1
	v_exp_f32_e32 v14, v14
	v_add3_u32 v15, v15, v50, s34
	ds_write_b16_d16_hi v66, v15 offset:8704
	v_readlane_b32 s98, v44, s101
	v_mul_f32_e32 v14, v14, v16
	v_bfe_u32 v16, v14, 16, 1
	v_add3_u32 v14, v14, v16, s34
	ds_write_b16_d16_hi v66, v14 offset:8832
	v_sub_f32_e32 v15, s98, v44
	v_readlane_b32 s98, v45, s101
	v_mul_f32_e32 v15, 0x3fb8aa3b, v15
	v_exp_f32_e32 v15, v15
	v_lshlrev_b32_e32 v16, 16, v17
	v_cmp_eq_u32_e32 vcc, 63, v68
	v_sub_f32_e32 v14, s98, v45
	v_mul_f32_e32 v15, v15, v16
	v_mul_f32_e32 v14, 0x3fb8aa3b, v14
	v_bfe_u32 v16, v15, 16, 1
	v_exp_f32_e32 v14, v14
	v_add3_u32 v15, v15, v16, s34
	ds_write_b16_d16_hi v66, v15 offset:8960
	v_readlane_b32 s98, v38, s101
	v_and_b32_e32 v16, 0xffff0000, v17
	v_mul_f32_e32 v14, v14, v16
	v_bfe_u32 v16, v14, 16, 1
	v_add3_u32 v14, v14, v16, s34
	v_sub_f32_e32 v15, s98, v38
	ds_write_b16_d16_hi v66, v14 offset:9088
	v_readlane_b32 s98, v39, s101
	v_mul_f32_e32 v15, 0x3fb8aa3b, v15
	v_exp_f32_e32 v15, v15
	v_lshlrev_b32_e32 v16, 16, v10
	v_and_b32_e32 v10, 0xffff0000, v10
	v_sub_f32_e32 v14, s98, v39
	v_mul_f32_e32 v15, v15, v16
	v_mul_f32_e32 v14, 0x3fb8aa3b, v14
	v_bfe_u32 v16, v15, 16, 1
	v_exp_f32_e32 v14, v14
	v_add3_u32 v15, v15, v16, s34
	ds_write_b16_d16_hi v66, v15 offset:9216
	v_readlane_b32 s98, v40, s101
	v_mul_f32_e32 v10, v14, v10
	v_bfe_u32 v14, v10, 16, 1
	v_add3_u32 v10, v10, v14, s34
	ds_write_b16_d16_hi v66, v10 offset:9344
	v_sub_f32_e32 v14, s98, v40
	v_readlane_b32 s98, v41, s101
	v_mul_f32_e32 v14, 0x3fb8aa3b, v14
	v_exp_f32_e32 v14, v14
	v_lshlrev_b32_e32 v15, 16, v11
	v_and_b32_e32 v11, 0xffff0000, v11
	v_sub_f32_e32 v10, s98, v41
	v_mul_f32_e32 v14, v14, v15
	v_mul_f32_e32 v10, 0x3fb8aa3b, v10
	v_bfe_u32 v15, v14, 16, 1
	v_exp_f32_e32 v10, v10
	v_add3_u32 v14, v14, v15, s34
	ds_write_b16_d16_hi v66, v14 offset:9472
	v_readlane_b32 s98, v34, s101
	v_mul_f32_e32 v10, v10, v11
	v_bfe_u32 v11, v10, 16, 1
	v_add3_u32 v10, v10, v11, s34
	ds_write_b16_d16_hi v66, v10 offset:9600
	v_sub_f32_e32 v11, s98, v34
	v_readlane_b32 s98, v35, s101
	v_mul_f32_e32 v11, 0x3fb8aa3b, v11
	v_exp_f32_e32 v11, v11
	v_lshlrev_b32_e32 v14, 16, v12
	v_and_b32_e32 v12, 0xffff0000, v12
	v_sub_f32_e32 v10, s98, v35
	v_mul_f32_e32 v11, v11, v14
	v_mul_f32_e32 v10, 0x3fb8aa3b, v10
	v_bfe_u32 v14, v11, 16, 1
	v_exp_f32_e32 v10, v10
	v_add3_u32 v11, v11, v14, s34
	ds_write_b16_d16_hi v66, v11 offset:9728
	v_readlane_b32 s98, v36, s101
	v_mul_f32_e32 v10, v10, v12
	v_bfe_u32 v12, v10, 16, 1
	v_add3_u32 v10, v10, v12, s34
	ds_write_b16_d16_hi v66, v10 offset:9856
	v_sub_f32_e32 v11, s98, v36
	v_readlane_b32 s98, v37, s101
	v_mul_f32_e32 v11, 0x3fb8aa3b, v11
	v_exp_f32_e32 v11, v11
	v_lshlrev_b32_e32 v12, 16, v13
	v_sub_f32_e32 v10, s98, v37
	v_mul_f32_e32 v11, v11, v12
	v_mul_f32_e32 v10, 0x3fb8aa3b, v10
	v_bfe_u32 v12, v11, 16, 1
	v_exp_f32_e32 v10, v10
	v_add3_u32 v11, v11, v12, s34
	ds_write_b16_d16_hi v66, v11 offset:9984
	v_readlane_b32 s98, v30, s101
	v_and_b32_e32 v12, 0xffff0000, v13
	v_mul_f32_e32 v10, v10, v12
	v_bfe_u32 v12, v10, 16, 1
	v_add3_u32 v10, v10, v12, s34
	v_sub_f32_e32 v11, s98, v30
	ds_write_b16_d16_hi v66, v10 offset:10112
	v_readlane_b32 s98, v31, s101
	v_mul_f32_e32 v11, 0x3fb8aa3b, v11
	v_exp_f32_e32 v11, v11
	v_lshlrev_b32_e32 v12, 16, v6
	v_and_b32_e32 v6, 0xffff0000, v6
	v_sub_f32_e32 v10, s98, v31
	v_mul_f32_e32 v11, v11, v12
	v_mul_f32_e32 v10, 0x3fb8aa3b, v10
	v_bfe_u32 v12, v11, 16, 1
	v_exp_f32_e32 v10, v10
	v_add3_u32 v11, v11, v12, s34
	ds_write_b16_d16_hi v66, v11 offset:10240
	v_readlane_b32 s98, v32, s101
	v_mul_f32_e32 v6, v10, v6
	v_bfe_u32 v10, v6, 16, 1
	v_add3_u32 v6, v6, v10, s34
	ds_write_b16_d16_hi v66, v6 offset:10368
	v_sub_f32_e32 v10, s98, v32
	v_readlane_b32 s98, v33, s101
	v_mul_f32_e32 v10, 0x3fb8aa3b, v10
	v_exp_f32_e32 v10, v10
	v_lshlrev_b32_e32 v11, 16, v7
	v_and_b32_e32 v7, 0xffff0000, v7
	v_sub_f32_e32 v6, s98, v33
	v_mul_f32_e32 v10, v10, v11
	v_mul_f32_e32 v6, 0x3fb8aa3b, v6
	v_bfe_u32 v11, v10, 16, 1
	v_exp_f32_e32 v6, v6
	v_add3_u32 v10, v10, v11, s34
	ds_write_b16_d16_hi v66, v10 offset:10496
	v_readlane_b32 s98, v26, s101
	v_mul_f32_e32 v6, v6, v7
	v_bfe_u32 v7, v6, 16, 1
	v_add3_u32 v6, v6, v7, s34
	ds_write_b16_d16_hi v66, v6 offset:10624
	v_sub_f32_e32 v7, s98, v26
	v_readlane_b32 s98, v27, s101
	v_mul_f32_e32 v7, 0x3fb8aa3b, v7
	v_exp_f32_e32 v7, v7
	v_lshlrev_b32_e32 v10, 16, v8
	v_and_b32_e32 v8, 0xffff0000, v8
	v_sub_f32_e32 v6, s98, v27
	v_mul_f32_e32 v7, v7, v10
	v_mul_f32_e32 v6, 0x3fb8aa3b, v6
	v_bfe_u32 v10, v7, 16, 1
	v_exp_f32_e32 v6, v6
	v_add3_u32 v7, v7, v10, s34
	ds_write_b16_d16_hi v66, v7 offset:10752
	v_readlane_b32 s98, v28, s101
	v_mul_f32_e32 v6, v6, v8
	v_bfe_u32 v8, v6, 16, 1
	v_add3_u32 v6, v6, v8, s34
	ds_write_b16_d16_hi v66, v6 offset:10880
	v_sub_f32_e32 v7, s98, v28
	v_readlane_b32 s98, v29, s101
	v_mul_f32_e32 v7, 0x3fb8aa3b, v7
	v_exp_f32_e32 v7, v7
	v_lshlrev_b32_e32 v8, 16, v9
	v_sub_f32_e32 v6, s98, v29
	v_mul_f32_e32 v7, v7, v8
	v_mul_f32_e32 v6, 0x3fb8aa3b, v6
	v_bfe_u32 v8, v7, 16, 1
	v_exp_f32_e32 v6, v6
	v_add3_u32 v7, v7, v8, s34
	ds_write_b16_d16_hi v66, v7 offset:11008
	v_readlane_b32 s98, v22, s101
	v_and_b32_e32 v8, 0xffff0000, v9
	v_mul_f32_e32 v6, v6, v8
	v_bfe_u32 v8, v6, 16, 1
	v_add3_u32 v6, v6, v8, s34
	v_sub_f32_e32 v7, s98, v22
	ds_write_b16_d16_hi v66, v6 offset:11136
	v_readlane_b32 s98, v23, s101
	v_mul_f32_e32 v7, 0x3fb8aa3b, v7
	v_exp_f32_e32 v7, v7
	v_lshlrev_b32_e32 v8, 16, v2
	v_and_b32_e32 v2, 0xffff0000, v2
	v_sub_f32_e32 v6, s98, v23
	v_mul_f32_e32 v7, v7, v8
	v_mul_f32_e32 v6, 0x3fb8aa3b, v6
	v_bfe_u32 v8, v7, 16, 1
	v_exp_f32_e32 v6, v6
	v_add3_u32 v7, v7, v8, s34
	ds_write_b16_d16_hi v66, v7 offset:11264
	v_readlane_b32 s98, v24, s101
	v_mul_f32_e32 v2, v6, v2
	v_bfe_u32 v6, v2, 16, 1
	v_add3_u32 v2, v2, v6, s34
	ds_write_b16_d16_hi v66, v2 offset:11392
	v_sub_f32_e32 v6, s98, v24
	v_readlane_b32 s98, v25, s101
	v_mul_f32_e32 v6, 0x3fb8aa3b, v6
	v_exp_f32_e32 v6, v6
	v_lshlrev_b32_e32 v7, 16, v3
	v_and_b32_e32 v3, 0xffff0000, v3
	v_sub_f32_e32 v2, s98, v25
	v_mul_f32_e32 v6, v6, v7
	v_mul_f32_e32 v2, 0x3fb8aa3b, v2
	v_bfe_u32 v7, v6, 16, 1
	v_exp_f32_e32 v2, v2
	v_add3_u32 v6, v6, v7, s34
	ds_write_b16_d16_hi v66, v6 offset:11520
	v_readlane_b32 s98, v18, s101
	v_mul_f32_e32 v2, v2, v3
	v_bfe_u32 v3, v2, 16, 1
	v_add3_u32 v2, v2, v3, s34
	ds_write_b16_d16_hi v66, v2 offset:11648
	v_sub_f32_e32 v3, s98, v18
	v_readlane_b32 s98, v19, s101
	v_mul_f32_e32 v3, 0x3fb8aa3b, v3
	v_exp_f32_e32 v3, v3
	v_lshlrev_b32_e32 v6, 16, v4
	v_and_b32_e32 v4, 0xffff0000, v4
	v_sub_f32_e32 v2, s98, v19
	v_mul_f32_e32 v3, v3, v6
	v_mul_f32_e32 v2, 0x3fb8aa3b, v2
	v_bfe_u32 v6, v3, 16, 1
	v_exp_f32_e32 v2, v2
	v_add3_u32 v3, v3, v6, s34
	ds_write_b16_d16_hi v66, v3 offset:11776
	v_readlane_b32 s98, v20, s101
	v_mul_f32_e32 v2, v2, v4
	v_bfe_u32 v4, v2, 16, 1
	v_add3_u32 v2, v2, v4, s34
	v_readlane_b32 s99, v21, s101
	v_sub_f32_e32 v3, s98, v20
	v_mul_f32_e32 v3, 0x3fb8aa3b, v3
	v_exp_f32_e32 v3, v3
	ds_write_b16_d16_hi v66, v2 offset:11904
	v_sub_f32_e32 v4, s99, v21
	v_lshlrev_b32_e32 v2, 16, v5
	v_mul_f32_e32 v4, 0x3fb8aa3b, v4
	v_mul_f32_e32 v2, v3, v2
	v_exp_f32_e32 v4, v4
	v_bfe_u32 v3, v2, 16, 1
	v_add3_u32 v2, v2, v3, s34
	ds_write_b16_d16_hi v66, v2 offset:12032
	v_and_b32_e32 v2, 0xffff0000, v5
	v_mul_f32_e32 v2, v4, v2
	v_bfe_u32 v3, v2, 16, 1
	v_add3_u32 v2, v2, v3, s34
	ds_write_b16_d16_hi v66, v2 offset:12160
	s_and_saveexec_b64 s[14:15], vcc
	s_cbranch_execz .LBB0_700
	v_mul_f32_e32 v2, 0x3fb8aa3b, v46
	v_mul_f32_e32 v3, 0x3fb8aa3b, v47
	v_mul_f32_e32 v4, 0x3fb8aa3b, v48
	v_mul_f32_e32 v5, 0x3fb8aa3b, v49
	v_exp_f32_e32 v2, v2
	v_exp_f32_e32 v3, v3
	v_exp_f32_e32 v4, v4
	v_exp_f32_e32 v5, v5
	v_mul_f32_e32 v6, 0x3fb8aa3b, v42
	v_mul_f32_e32 v7, 0x3fb8aa3b, v43
	v_mul_f32_e32 v8, 0x3fb8aa3b, v44
	v_mul_f32_e32 v9, 0x3fb8aa3b, v45
	s_lshl_b64 s[12:13], s[12:13], 7
	v_exp_f32_e32 v6, v6
	v_exp_f32_e32 v7, v7
	v_exp_f32_e32 v8, v8
	v_exp_f32_e32 v9, v9
	v_mul_f32_e32 v10, 0x3fb8aa3b, v38
	v_mul_f32_e32 v11, 0x3fb8aa3b, v39
	v_mul_f32_e32 v12, 0x3fb8aa3b, v40
	v_mul_f32_e32 v13, 0x3fb8aa3b, v41
	s_add_u32 s12, s23, s12
	v_exp_f32_e32 v10, v10
	v_exp_f32_e32 v11, v11
	v_exp_f32_e32 v12, v12
	v_exp_f32_e32 v13, v13
	v_mul_f32_e32 v14, 0x3fb8aa3b, v34
	v_mul_f32_e32 v15, 0x3fb8aa3b, v35
	v_mul_f32_e32 v16, 0x3fb8aa3b, v36
	v_mul_f32_e32 v17, 0x3fb8aa3b, v37
	s_addc_u32 s13, s24, s13
	v_exp_f32_e32 v14, v14
	v_exp_f32_e32 v15, v15
	v_exp_f32_e32 v16, v16
	v_exp_f32_e32 v17, v17
	global_store_dwordx4 v67, v[2:5], s[12:13]
	global_store_dwordx4 v67, v[6:9], s[12:13] offset:16
	global_store_dwordx4 v67, v[10:13], s[12:13] offset:32
	global_store_dwordx4 v67, v[14:17], s[12:13] offset:48
	v_mul_f32_e32 v2, 0x3fb8aa3b, v30
	v_mul_f32_e32 v3, 0x3fb8aa3b, v31
	v_mul_f32_e32 v4, 0x3fb8aa3b, v32
	v_mul_f32_e32 v5, 0x3fb8aa3b, v33
	v_exp_f32_e32 v2, v2
	v_exp_f32_e32 v3, v3
	v_exp_f32_e32 v4, v4
	v_exp_f32_e32 v5, v5
	v_mul_f32_e32 v6, 0x3fb8aa3b, v26
	v_mul_f32_e32 v7, 0x3fb8aa3b, v27
	v_mul_f32_e32 v8, 0x3fb8aa3b, v28
	v_mul_f32_e32 v9, 0x3fb8aa3b, v29
	v_exp_f32_e32 v6, v6
	v_exp_f32_e32 v7, v7
	v_exp_f32_e32 v8, v8
	v_exp_f32_e32 v9, v9
	v_mul_f32_e32 v10, 0x3fb8aa3b, v22
	v_mul_f32_e32 v11, 0x3fb8aa3b, v23
	v_mul_f32_e32 v12, 0x3fb8aa3b, v24
	v_mul_f32_e32 v13, 0x3fb8aa3b, v25
	v_exp_f32_e32 v10, v10
	v_exp_f32_e32 v11, v11
	v_exp_f32_e32 v12, v12
	v_exp_f32_e32 v13, v13
	v_mul_f32_e32 v14, 0x3fb8aa3b, v18
	v_mul_f32_e32 v15, 0x3fb8aa3b, v19
	v_mul_f32_e32 v16, 0x3fb8aa3b, v20
	v_mul_f32_e32 v17, 0x3fb8aa3b, v21
	v_exp_f32_e32 v14, v14
	v_exp_f32_e32 v15, v15
	v_exp_f32_e32 v16, v16
	v_exp_f32_e32 v17, v17
	global_store_dwordx4 v67, v[2:5], s[12:13] offset:64
	global_store_dwordx4 v67, v[6:9], s[12:13] offset:80
	global_store_dwordx4 v67, v[10:13], s[12:13] offset:96
	global_store_dwordx4 v67, v[14:17], s[12:13] offset:112
	s_branch .LBB0_700

.LBB0_712:
	s_mul_hi_u32 s0, s31, s29
	s_mul_i32 s0, s0, s18
	s_sub_i32 s0, s31, s0
	s_sub_i32 s1, s0, s18
	s_cmp_ge_u32 s0, s18
	s_cselect_b32 s0, s1, s0
	s_sub_i32 s1, s0, s18
	s_cmp_ge_u32 s0, s18
	s_cselect_b32 s0, s1, s0
	s_cmp_lg_u32 s0, s16
	s_cbranch_scc1 .LBB0_711
	s_bfe_u32 s35, s34, 0x20003
	s_lshr_b32 s37, s34, 5
	s_lshl_b32 s1, s37, 8
	s_lshl_b32 s2, s35, 6
	s_bfe_u32 s36, s34, 0x20001
	s_or_b32 s33, s1, s2
	s_and_b32 s0, s34, 1
	s_add_i32 s33, s33, 0x8000
	s_lshl_b32 s6, s36, 6
	s_cmp_eq_u32 s0, 0
	s_mov_b64 s[0:1], -1
	s_cbranch_scc1 .LBB0_717
	v_mov_b32_e32 v68, v109
	v_mov_b64_e32 v[2:3], s[22:23]
	v_add_u32_e32 v4, s33, v68
	v_mad_i64_i32 v[70:71], s[0:1], v4, s24, v[2:3]
	s_lshl_b32 s0, s6, 1
	s_mov_b32 s1, s7
	v_lshl_add_u64 v[30:31], v[70:71], 0, s[0:1]
	global_load_dwordx4 v[2:5], v[30:31], off offset:512
	global_load_dwordx4 v[6:9], v[30:31], off offset:528
	global_load_dwordx4 v[10:13], v[30:31], off offset:544
	global_load_dwordx4 v[14:17], v[30:31], off offset:560
	global_load_dwordx4 v[18:21], v[30:31], off offset:576
	global_load_dwordx4 v[22:25], v[30:31], off offset:592
	global_load_dwordx4 v[26:29], v[30:31], off offset:608
	s_nop 0
	global_load_dwordx4 v[30:33], v[30:31], off offset:624
	v_readlane_b32 s40, v239, 33
	global_load_dwordx4 v[34:37], v[70:71], off offset:1568
	v_readlane_b32 s44, v239, 37
	v_readlane_b32 s45, v239, 38
	v_readlane_b32 s46, v239, 39
	v_readlane_b32 s47, v239, 40
	v_readlane_b32 s48, v239, 41
	v_readlane_b32 s49, v239, 42
	v_readlane_b32 s50, v239, 43
	v_readlane_b32 s51, v239, 44
	v_readlane_b32 s52, v239, 45
	v_readlane_b32 s53, v239, 46
	v_readlane_b32 s54, v239, 47
	v_readlane_b32 s55, v239, 48
	s_mov_b64 s[44:45], s[48:49]
	s_lshl_b32 s0, s36, 7
	s_mov_b64 s[46:47], s[50:51]
	s_mov_b64 s[48:49], s[52:53]
	s_add_u32 s8, s46, s0
	v_mov_b32_e32 v123, s0
	s_addc_u32 s9, s47, 0
	global_load_dwordx4 v[38:41], v123, s[48:49]
	global_load_dwordx4 v[42:45], v123, s[46:47]
	global_load_dwordx4 v[46:49], v123, s[46:47] offset:512
	global_load_dwordx4 v[50:53], v123, s[46:47] offset:1024
	global_load_dwordx4 v[54:57], v123, s[46:47] offset:1536
	global_load_dwordx4 v[58:61], v123, s[46:47] offset:2048
	global_load_dwordx4 v[62:65], v123, s[46:47] offset:2560
	global_load_dwordx4 v[74:77], v123, s[46:47] offset:3072
	global_load_dwordx4 v[78:81], v123, s[46:47] offset:3584
	global_load_dwordx4 v[82:85], v111, s[8:9]
	global_load_dwordx4 v[86:89], v111, s[8:9] offset:512
	global_load_dwordx4 v[90:93], v[70:71], off offset:1584
	v_lshl_add_u32 v66, v68, 1, s17
	v_lshl_add_u64 v[70:71], v[70:71], 0, s[6:7]
	v_readlane_b32 s41, v239, 34
	v_readlane_b32 s42, v239, 35
	v_readlane_b32 s43, v239, 36
	s_mov_b64 s[50:51], s[54:55]
	v_ashrrev_i32_e32 v69, 31, v68
	s_waitcnt vmcnt(20)
	ds_write_b16 v66, v2
	ds_write_b16_d16_hi v66, v2 offset:128
	ds_write_b16 v66, v3 offset:256
	ds_write_b16_d16_hi v66, v3 offset:384
	ds_write_b16 v66, v4 offset:512
	ds_write_b16_d16_hi v66, v4 offset:640
	ds_write_b16 v66, v5 offset:768
	ds_write_b16_d16_hi v66, v5 offset:896
	s_waitcnt vmcnt(19)
	ds_write_b16 v66, v6 offset:1024
	ds_write_b16_d16_hi v66, v6 offset:1152
	ds_write_b16 v66, v7 offset:1280
	ds_write_b16_d16_hi v66, v7 offset:1408
	ds_write_b16 v66, v8 offset:1536
	ds_write_b16_d16_hi v66, v8 offset:1664
	ds_write_b16 v66, v9 offset:1792
	ds_write_b16_d16_hi v66, v9 offset:1920
	s_waitcnt vmcnt(18)
	ds_write_b16 v66, v10 offset:2048
	ds_write_b16_d16_hi v66, v10 offset:2176
	ds_write_b16 v66, v11 offset:2304
	ds_write_b16_d16_hi v66, v11 offset:2432
	ds_write_b16 v66, v12 offset:2560
	ds_write_b16_d16_hi v66, v12 offset:2688
	ds_write_b16 v66, v13 offset:2816
	ds_write_b16_d16_hi v66, v13 offset:2944
	s_waitcnt vmcnt(17)
	ds_write_b16 v66, v14 offset:3072
	ds_write_b16_d16_hi v66, v14 offset:3200
	ds_write_b16 v66, v15 offset:3328
	ds_write_b16_d16_hi v66, v15 offset:3456
	ds_write_b16 v66, v16 offset:3584
	ds_write_b16_d16_hi v66, v16 offset:3712
	ds_write_b16 v66, v17 offset:3840
	ds_write_b16_d16_hi v66, v17 offset:3968
	s_waitcnt vmcnt(16)
	ds_write_b16 v66, v18 offset:4096
	ds_write_b16_d16_hi v66, v18 offset:4224
	ds_write_b16 v66, v19 offset:4352
	ds_write_b16_d16_hi v66, v19 offset:4480
	ds_write_b16 v66, v20 offset:4608
	ds_write_b16_d16_hi v66, v20 offset:4736
	ds_write_b16 v66, v21 offset:4864
	ds_write_b16_d16_hi v66, v21 offset:4992
	s_waitcnt vmcnt(15)
	ds_write_b16 v66, v22 offset:5120
	ds_write_b16_d16_hi v66, v22 offset:5248
	ds_write_b16 v66, v23 offset:5376
	ds_write_b16_d16_hi v66, v23 offset:5504
	ds_write_b16 v66, v24 offset:5632
	ds_write_b16_d16_hi v66, v24 offset:5760
	ds_write_b16 v66, v25 offset:5888
	ds_write_b16_d16_hi v66, v25 offset:6016
	s_waitcnt vmcnt(14)
	ds_write_b16 v66, v26 offset:6144
	ds_write_b16_d16_hi v66, v26 offset:6272
	ds_write_b16 v66, v27 offset:6400
	ds_write_b16_d16_hi v66, v27 offset:6528
	ds_write_b16 v66, v28 offset:6656
	ds_write_b16_d16_hi v66, v28 offset:6784
	ds_write_b16 v66, v29 offset:6912
	ds_write_b16_d16_hi v66, v29 offset:7040
	s_waitcnt vmcnt(13)
	ds_write_b16 v66, v30 offset:7168
	ds_write_b16_d16_hi v66, v30 offset:7296
	ds_write_b16 v66, v31 offset:7424
	ds_write_b16_d16_hi v66, v31 offset:7552
	ds_write_b16 v66, v32 offset:7680
	ds_write_b16_d16_hi v66, v32 offset:7808
	ds_write_b16 v66, v33 offset:7936
	ds_write_b16_d16_hi v66, v33 offset:8064
	global_load_dwordx4 v[18:21], v111, s[8:9] offset:1024
	global_load_dwordx4 v[22:25], v111, s[8:9] offset:1536
	global_load_dwordx4 v[14:17], v[70:71], off offset:256
	global_load_dwordx4 v[10:13], v[70:71], off offset:272
	global_load_dwordx4 v[6:9], v[70:71], off offset:288
	global_load_dwordx4 v[2:5], v[70:71], off offset:304
	global_load_dwordx4 v[26:29], v111, s[8:9] offset:2048
	global_load_dwordx4 v[30:33], v111, s[8:9] offset:2560
	global_load_dwordx4 v[94:97], v111, s[8:9] offset:3072
	global_load_dwordx4 v[98:101], v111, s[8:9] offset:3584
	s_waitcnt vmcnt(22)
	v_lshlrev_b32_e32 v118, 16, v34
	v_and_b32_e32 v117, 0xffff0000, v34
	v_lshlrev_b32_e32 v120, 16, v36
	v_and_b32_e32 v119, 0xffff0000, v36
	v_lshlrev_b32_e32 v122, 16, v35
	v_and_b32_e32 v121, 0xffff0000, v35
	v_and_b32_e32 v73, 0xffff0000, v37
	v_lshlrev_b32_e32 v72, 16, v37
	s_waitcnt vmcnt(20)
	v_fma_f32 v36, v42, v118, v38
	s_waitcnt vmcnt(19)
	v_fmac_f32_e32 v36, v46, v117
	s_waitcnt vmcnt(18)
	v_fmac_f32_e32 v36, v50, v122
	v_fma_f32 v38, v43, v118, v39
	s_waitcnt vmcnt(17)
	v_fmac_f32_e32 v36, v54, v121
	v_fmac_f32_e32 v38, v47, v117
	s_waitcnt vmcnt(16)
	v_fmac_f32_e32 v36, v58, v120
	v_fmac_f32_e32 v38, v51, v122
	s_waitcnt vmcnt(14)
	v_mov_b32_e32 v34, v74
	s_waitcnt vmcnt(13)
	v_mov_b32_e32 v35, v78
	v_fmac_f32_e32 v36, v62, v119
	v_fmac_f32_e32 v38, v55, v121
	v_fma_f32 v39, v44, v118, v40
	v_pk_mul_f32 v[34:35], v[34:35], v[72:73]
	v_fmac_f32_e32 v38, v59, v120
	v_fmac_f32_e32 v39, v48, v117
	v_add_f32_e32 v34, v36, v34
	v_mov_b32_e32 v78, v75
	v_fmac_f32_e32 v38, v63, v119
	v_fmac_f32_e32 v39, v52, v122
	v_fmac_f32_e32 v41, v45, v118
	v_add_f32_e32 v36, v34, v35
	v_pk_mul_f32 v[34:35], v[78:79], v[72:73]
	v_fmac_f32_e32 v39, v56, v121
	v_fmac_f32_e32 v41, v49, v117
	v_add_f32_e32 v34, v34, v38
	v_fmac_f32_e32 v39, v60, v120
	v_fmac_f32_e32 v41, v53, v122
	v_add_f32_e32 v37, v35, v34
	v_mov_b32_e32 v34, v76
	v_mov_b32_e32 v35, v80
	v_fmac_f32_e32 v39, v64, v119
	v_fmac_f32_e32 v41, v57, v121
	v_pk_mul_f32 v[34:35], v[34:35], v[72:73]
	v_fmac_f32_e32 v41, v61, v120
	v_add_f32_e32 v34, v34, v39
	v_mov_b32_e32 v80, v77
	v_fmac_f32_e32 v41, v65, v119
	v_add_f32_e32 v38, v35, v34
	v_pk_mul_f32 v[34:35], v[80:81], v[72:73]
	s_waitcnt vmcnt(10)
	v_and_b32_e32 v75, 0xffff0000, v90
	v_add_f32_e32 v34, v34, v41
	v_add_f32_e32 v39, v35, v34
	v_lshlrev_b32_e32 v74, 16, v90
	v_mov_b32_e32 v34, v82
	v_mov_b32_e32 v35, v86
	v_pk_mul_f32 v[34:35], v[34:35], v[74:75]
	v_mov_b32_e32 v86, v83
	v_add_f32_e32 v34, v36, v34
	v_add_f32_e32 v36, v34, v35
	v_pk_mul_f32 v[34:35], v[86:87], v[74:75]
	v_and_b32_e32 v79, 0xffff0000, v91
	v_add_f32_e32 v34, v34, v37
	v_add_f32_e32 v37, v35, v34
	v_mov_b32_e32 v34, v84
	v_mov_b32_e32 v35, v88
	v_pk_mul_f32 v[34:35], v[34:35], v[74:75]
	v_mov_b32_e32 v88, v85
	v_add_f32_e32 v34, v34, v38
	v_add_f32_e32 v38, v35, v34
	v_pk_mul_f32 v[34:35], v[88:89], v[74:75]
	v_lshlrev_b32_e32 v78, 16, v91
	v_add_f32_e32 v34, v34, v39
	v_add_f32_e32 v39, v35, v34
	v_and_b32_e32 v81, 0xffff0000, v92
	v_lshlrev_b32_e32 v80, 16, v92
	v_and_b32_e32 v83, 0xffff0000, v93
	v_lshlrev_b32_e32 v82, 16, v93
	s_waitcnt vmcnt(9)
	v_mov_b32_e32 v34, v18
	s_waitcnt vmcnt(8)
	v_mov_b32_e32 v35, v22
	v_pk_mul_f32 v[34:35], v[34:35], v[78:79]
	v_mov_b32_e32 v22, v19
	v_add_f32_e32 v18, v36, v34
	v_add_f32_e32 v34, v18, v35
	v_pk_mul_f32 v[18:19], v[22:23], v[78:79]
	s_nop 0
	v_add_f32_e32 v18, v18, v37
	v_add_f32_e32 v22, v19, v18
	v_mov_b32_e32 v18, v20
	v_mov_b32_e32 v19, v24
	v_pk_mul_f32 v[18:19], v[18:19], v[78:79]
	v_mov_b32_e32 v24, v21
	v_add_f32_e32 v18, v18, v38
	v_add_f32_e32 v20, v19, v18
	v_pk_mul_f32 v[18:19], v[24:25], v[78:79]
	s_waitcnt vmcnt(0)
	v_mov_b32_e32 v21, v98
	v_add_f32_e32 v18, v18, v39
	v_add_f32_e32 v23, v19, v18
	v_mov_b32_e32 v18, v26
	v_mov_b32_e32 v19, v30
	v_pk_mul_f32 v[18:19], v[18:19], v[80:81]
	v_mov_b32_e32 v30, v27
	v_add_f32_e32 v18, v34, v18
	v_add_f32_e32 v24, v18, v19
	v_pk_mul_f32 v[18:19], v[30:31], v[80:81]
	v_mov_b32_e32 v98, v95
	v_add_f32_e32 v18, v18, v22
	v_add_f32_e32 v22, v19, v18
	v_mov_b32_e32 v18, v28
	v_mov_b32_e32 v19, v32
	v_pk_mul_f32 v[18:19], v[18:19], v[80:81]
	v_mov_b32_e32 v32, v29
	v_add_f32_e32 v18, v18, v20
	v_mov_b32_e32 v20, v94
	v_pk_mul_f32 v[20:21], v[20:21], v[82:83]
	s_nop 0
	v_add_f32_e32 v20, v24, v20
	v_add_f32_e32 v20, v20, v21
	v_mul_f32_e64 v21, |v20|, s25
	v_exp_f32_e32 v21, v21
	v_add_f32_e32 v24, v19, v18
	v_pk_mul_f32 v[18:19], v[32:33], v[80:81]
	v_add_f32_e32 v21, 1.0, v21
	v_cmp_gt_f32_e32 vcc, s26, v21
	v_add_f32_e32 v18, v18, v23
	v_add_f32_e32 v26, v19, v18
	v_cndmask_b32_e64 v25, 0, 32, vcc
	v_ldexp_f32 v21, v21, v25
	v_log_f32_e32 v25, v21
	v_min_f32_e32 v18, 0, v20
	v_pk_mul_f32 v[20:21], v[98:99], v[82:83]
	v_mov_b32_e32 v23, v100
	v_add_f32_e32 v20, v20, v22
	v_add_f32_e32 v21, v21, v20
	v_mul_f32_e64 v20, |v21|, s25
	v_exp_f32_e32 v20, v20
	v_mul_f32_e32 v19, 0x3f317217, v25
	v_fma_f32 v19, v25, s27, -v19
	v_fmac_f32_e32 v19, 0x3377d1cf, v25
	v_fmac_f32_e32 v19, 0x3f317217, v25
	v_cmp_lt_f32_e64 s[0:1], |v25|, s28
	v_add_f32_e32 v20, 1.0, v20
	v_mov_b32_e32 v100, v97
	v_cndmask_b32_e64 v19, v25, v19, s[0:1]
	v_cmp_gt_f32_e64 s[0:1], s26, v20
	s_nop 1
	v_cndmask_b32_e64 v22, 0, 32, s[0:1]
	v_ldexp_f32 v20, v20, v22
	v_mov_b32_e32 v22, v96
	v_pk_mul_f32 v[22:23], v[22:23], v[82:83]
	v_log_f32_e32 v25, v20
	v_add_f32_e32 v22, v22, v24
	v_add_f32_e32 v22, v23, v22
	v_mul_f32_e64 v23, |v22|, s25
	v_cndmask_b32_e32 v20, 0, v112, vcc
	v_exp_f32_e32 v23, v23
	v_sub_f32_e32 v20, v19, v20
	v_min_f32_e32 v19, 0, v21
	v_mul_f32_e32 v21, 0x3f317217, v25
	v_fma_f32 v21, v25, s27, -v21
	v_fmac_f32_e32 v21, 0x3377d1cf, v25
	v_fmac_f32_e32 v21, 0x3f317217, v25
	v_cmp_lt_f32_e64 vcc, |v25|, s28
	v_add_f32_e32 v23, 1.0, v23
	v_cndmask_b32_e64 v24, 0, v112, s[0:1]
	v_cndmask_b32_e32 v21, v25, v21, vcc
	v_cmp_gt_f32_e32 vcc, s26, v23
	v_sub_f32_e32 v21, v21, v24
	v_pk_add_f32 v[18:19], v[18:19], v[20:21] neg_lo:[0,1] neg_hi:[0,1]
	v_cndmask_b32_e64 v24, 0, 32, vcc
	v_ldexp_f32 v23, v23, v24
	v_pk_mul_f32 v[20:21], v[100:101], v[82:83]
	v_log_f32_e32 v23, v23
	v_add_f32_e32 v20, v20, v26
	v_add_f32_e32 v21, v21, v20
	v_mul_f32_e64 v20, |v21|, s25
	v_exp_f32_e32 v20, v20
	v_pk_mul_f32 v[70:71], v[18:19], s[4:5] op_sel_hi:[1,0]
	v_mul_f32_e32 v19, 0x3f317217, v23
	v_fma_f32 v19, v23, s27, -v19
	v_fmac_f32_e32 v19, 0x3377d1cf, v23
	v_fmac_f32_e32 v19, 0x3f317217, v23
	v_cmp_lt_f32_e64 s[0:1], |v23|, s28
	v_add_f32_e32 v20, 1.0, v20
	v_min_f32_e32 v18, 0, v22
	v_cndmask_b32_e64 v19, v23, v19, s[0:1]
	v_cmp_gt_f32_e64 s[0:1], s26, v20
	s_nop 1
	v_cndmask_b32_e64 v22, 0, 32, s[0:1]
	v_ldexp_f32 v20, v20, v22
	v_log_f32_e32 v22, v20
	v_cndmask_b32_e32 v20, 0, v112, vcc
	v_sub_f32_e32 v20, v19, v20
	v_min_f32_e32 v19, 0, v21
	v_mul_f32_e32 v21, 0x3f317217, v22
	v_fma_f32 v21, v22, s27, -v21
	v_fmac_f32_e32 v21, 0x3377d1cf, v22
	v_fmac_f32_e32 v21, 0x3f317217, v22
	v_cmp_lt_f32_e64 vcc, |v22|, s28
	s_nop 1
	v_cndmask_b32_e32 v21, v22, v21, vcc
	v_cndmask_b32_e64 v22, 0, v112, s[0:1]
	v_sub_f32_e32 v21, v21, v22
	v_pk_add_f32 v[18:19], v[18:19], v[20:21] neg_lo:[0,1] neg_hi:[0,1]
	s_nop 0
	v_pk_mul_f32 v[76:77], v[18:19], s[4:5] op_sel_hi:[1,0]
	global_load_dwordx4 v[18:21], v123, s[48:49] offset:16
	global_load_dwordx4 v[22:25], v123, s[46:47] offset:16
	global_load_dwordx4 v[26:29], v123, s[46:47] offset:3088
	global_load_dwordx4 v[30:33], v123, s[46:47] offset:3600
	global_load_dwordx4 v[34:37], v111, s[8:9] offset:16
	global_load_dwordx4 v[38:41], v111, s[8:9] offset:528
	global_load_dwordx4 v[42:45], v111, s[8:9] offset:1040
	global_load_dwordx4 v[46:49], v111, s[8:9] offset:1552
	global_load_dwordx4 v[50:53], v111, s[8:9] offset:2064
	global_load_dwordx4 v[54:57], v111, s[8:9] offset:2576
	global_load_dwordx4 v[58:61], v111, s[8:9] offset:3088
	global_load_dwordx4 v[62:65], v111, s[8:9] offset:3600
	global_load_dwordx4 v[84:87], v123, s[46:47] offset:528
	global_load_dwordx4 v[88:91], v123, s[46:47] offset:1040
	global_load_dwordx4 v[92:95], v123, s[46:47] offset:1552
	global_load_dwordx4 v[96:99], v123, s[46:47] offset:2064
	global_load_dwordx4 v[100:103], v123, s[46:47] offset:2576
	s_waitcnt vmcnt(15)
	v_fma_f32 v130, v22, v118, v18
	v_fma_f32 v20, v24, v118, v20
	s_waitcnt vmcnt(14)
	v_mov_b32_e32 v104, v26
	s_waitcnt vmcnt(13)
	v_mov_b32_e32 v105, v30
	v_fma_f32 v23, v23, v118, v19
	v_mov_b32_e32 v30, v27
	v_mov_b32_e32 v18, v28
	v_mov_b32_e32 v19, v32
	v_pk_mul_f32 v[26:27], v[104:105], v[72:73]
	s_waitcnt vmcnt(12)
	v_mov_b32_e32 v106, v34
	s_waitcnt vmcnt(11)
	v_mov_b32_e32 v107, v38
	s_waitcnt vmcnt(4)
	v_fmac_f32_e32 v130, v84, v117
	v_fmac_f32_e32 v20, v86, v117
	s_waitcnt vmcnt(3)
	v_fmac_f32_e32 v130, v88, v122
	v_fmac_f32_e32 v20, v90, v122
	s_waitcnt vmcnt(2)
	v_fmac_f32_e32 v130, v92, v121
	v_fmac_f32_e32 v20, v94, v121
	s_waitcnt vmcnt(1)
	v_fmac_f32_e32 v130, v96, v120
	v_fmac_f32_e32 v20, v98, v120
	s_waitcnt vmcnt(0)
	v_fmac_f32_e32 v130, v100, v119
	v_fmac_f32_e32 v23, v85, v117
	v_pk_mul_f32 v[18:19], v[18:19], v[72:73]
	v_fmac_f32_e32 v20, v102, v119
	v_add_f32_e32 v24, v130, v26
	v_mov_b32_e32 v38, v35
	v_pk_mul_f32 v[34:35], v[106:107], v[74:75]
	v_fmac_f32_e32 v23, v89, v122
	v_add_f32_e32 v18, v18, v20
	v_add_f32_e32 v20, v24, v27
	v_mov_b32_e32 v124, v42
	v_mov_b32_e32 v125, v46
	v_fmac_f32_e32 v23, v93, v121
	v_add_f32_e32 v20, v20, v34
	v_mov_b32_e32 v46, v43
	v_pk_mul_f32 v[42:43], v[124:125], v[78:79]
	v_fmac_f32_e32 v23, v97, v120
	v_add_f32_e32 v20, v20, v35
	v_mov_b32_e32 v126, v50
	v_mov_b32_e32 v127, v54
	v_pk_mul_f32 v[30:31], v[30:31], v[72:73]
	v_fmac_f32_e32 v23, v101, v119
	v_add_f32_e32 v20, v20, v42
	v_mov_b32_e32 v54, v51
	v_pk_mul_f32 v[50:51], v[126:127], v[80:81]
	v_add_f32_e32 v23, v30, v23
	v_add_f32_e32 v20, v20, v43
	v_mov_b32_e32 v128, v58
	v_mov_b32_e32 v129, v62
	v_pk_mul_f32 v[38:39], v[38:39], v[74:75]
	v_add_f32_e32 v23, v31, v23
	v_add_f32_e32 v20, v20, v50
	v_mov_b32_e32 v62, v59
	v_pk_mul_f32 v[58:59], v[128:129], v[82:83]
	v_add_f32_e32 v23, v38, v23
	v_add_f32_e32 v20, v20, v51
	v_pk_mul_f32 v[46:47], v[46:47], v[78:79]
	v_add_f32_e32 v23, v39, v23
	v_add_f32_e32 v20, v20, v58
	v_add_f32_e32 v23, v46, v23
	v_add_f32_e32 v20, v20, v59
	v_pk_mul_f32 v[54:55], v[54:55], v[80:81]
	v_add_f32_e32 v23, v47, v23
	v_mul_f32_e64 v24, |v20|, s25
	v_add_f32_e32 v23, v54, v23
	v_exp_f32_e32 v24, v24
	v_pk_mul_f32 v[62:63], v[62:63], v[82:83]
	v_add_f32_e32 v23, v55, v23
	v_add_f32_e32 v23, v62, v23
	v_add_f32_e32 v23, v63, v23
	v_mul_f32_e64 v26, |v23|, s25
	v_add_f32_e32 v27, v19, v18
	v_add_f32_e32 v19, 1.0, v24
	v_exp_f32_e32 v26, v26
	v_cmp_gt_f32_e32 vcc, s26, v19
	v_min_f32_e32 v18, 0, v20
	v_mov_b32_e32 v22, v36
	v_cndmask_b32_e64 v24, 0, 32, vcc
	v_ldexp_f32 v19, v19, v24
	v_log_f32_e32 v24, v19
	v_add_f32_e32 v20, 1.0, v26
	v_cmp_gt_f32_e64 s[0:1], s26, v20
	v_min_f32_e32 v19, 0, v23
	v_cndmask_b32_e32 v23, 0, v112, vcc
	v_cndmask_b32_e64 v26, 0, 32, s[0:1]
	v_ldexp_f32 v20, v20, v26
	v_mul_f32_e32 v26, 0x3f317217, v24
	v_fma_f32 v26, v24, s27, -v26
	v_fmac_f32_e32 v26, 0x3377d1cf, v24
	v_fmac_f32_e32 v26, 0x3f317217, v24
	v_cmp_lt_f32_e64 vcc, |v24|, s28
	v_log_f32_e32 v20, v20
	v_fmac_f32_e32 v21, v25, v118
	v_cndmask_b32_e32 v24, v24, v26, vcc
	v_sub_f32_e32 v26, v24, v23
	v_mov_b32_e32 v23, v40
	v_pk_mul_f32 v[22:23], v[22:23], v[74:75]
	v_mul_f32_e32 v28, 0x3f317217, v20
	v_add_f32_e32 v22, v22, v27
	v_add_f32_e32 v24, v23, v22
	v_mov_b32_e32 v22, v44
	v_mov_b32_e32 v23, v48
	v_pk_mul_f32 v[22:23], v[22:23], v[78:79]
	v_fma_f32 v28, v20, s27, -v28
	v_add_f32_e32 v22, v22, v24
	v_add_f32_e32 v24, v23, v22
	v_mov_b32_e32 v22, v52
	v_mov_b32_e32 v23, v56
	v_pk_mul_f32 v[22:23], v[22:23], v[80:81]
	v_fmac_f32_e32 v28, 0x3377d1cf, v20
	v_add_f32_e32 v22, v22, v24
	v_add_f32_e32 v24, v23, v22
	v_mov_b32_e32 v22, v60
	v_mov_b32_e32 v23, v64
	v_pk_mul_f32 v[22:23], v[22:23], v[82:83]
	v_fmac_f32_e32 v28, 0x3f317217, v20
	v_add_f32_e32 v22, v22, v24
	v_add_f32_e32 v22, v23, v22
	v_mul_f32_e64 v23, |v22|, s25
	v_exp_f32_e32 v23, v23
	v_cmp_lt_f32_e64 vcc, |v20|, s28
	v_cndmask_b32_e64 v24, 0, v112, s[0:1]
	v_fmac_f32_e32 v21, v87, v117
	v_cndmask_b32_e32 v20, v20, v28, vcc
	v_sub_f32_e32 v27, v20, v24
	v_add_f32_e32 v20, 1.0, v23
	v_fmac_f32_e32 v21, v91, v122
	v_cmp_gt_f32_e32 vcc, s26, v20
	v_fmac_f32_e32 v21, v95, v121
	v_pk_add_f32 v[18:19], v[18:19], v[26:27] neg_lo:[0,1] neg_hi:[0,1]
	v_cndmask_b32_e64 v23, 0, 32, vcc
	v_fmac_f32_e32 v21, v99, v120
	v_mov_b32_e32 v32, v29
	v_ldexp_f32 v20, v20, v23
	v_pk_mul_f32 v[84:85], v[18:19], s[4:5] op_sel_hi:[1,0]
	v_min_f32_e32 v18, 0, v22
	v_fmac_f32_e32 v21, v103, v119
	v_pk_mul_f32 v[22:23], v[32:33], v[72:73]
	v_log_f32_e32 v24, v20
	v_add_f32_e32 v20, v22, v21
	v_mov_b32_e32 v40, v37
	v_add_f32_e32 v22, v23, v20
	v_pk_mul_f32 v[20:21], v[40:41], v[74:75]
	v_mov_b32_e32 v48, v45
	v_add_f32_e32 v20, v20, v22
	v_add_f32_e32 v22, v21, v20
	v_pk_mul_f32 v[20:21], v[48:49], v[78:79]
	v_mov_b32_e32 v56, v53
	v_add_f32_e32 v20, v20, v22
	v_add_f32_e32 v22, v21, v20
	v_pk_mul_f32 v[20:21], v[56:57], v[80:81]
	v_mov_b32_e32 v64, v61
	v_add_f32_e32 v20, v20, v22
	v_add_f32_e32 v22, v21, v20
	v_pk_mul_f32 v[20:21], v[64:65], v[82:83]
	v_mul_f32_e32 v19, 0x3f317217, v24
	v_add_f32_e32 v20, v20, v22
	v_add_f32_e32 v21, v21, v20
	v_mul_f32_e64 v20, |v21|, s25
	v_exp_f32_e32 v20, v20
	v_fma_f32 v19, v24, s27, -v19
	v_fmac_f32_e32 v19, 0x3377d1cf, v24
	v_fmac_f32_e32 v19, 0x3f317217, v24
	v_cmp_lt_f32_e64 s[0:1], |v24|, s28
	v_add_f32_e32 v20, 1.0, v20
	s_nop 0
	v_cndmask_b32_e64 v19, v24, v19, s[0:1]
	v_cmp_gt_f32_e64 s[0:1], s26, v20
	s_nop 1
	v_cndmask_b32_e64 v22, 0, 32, s[0:1]
	v_ldexp_f32 v20, v20, v22
	v_log_f32_e32 v22, v20
	v_cndmask_b32_e32 v20, 0, v112, vcc
	v_sub_f32_e32 v20, v19, v20
	v_min_f32_e32 v19, 0, v21
	v_mul_f32_e32 v21, 0x3f317217, v22
	v_fma_f32 v21, v22, s27, -v21
	v_fmac_f32_e32 v21, 0x3377d1cf, v22
	v_fmac_f32_e32 v21, 0x3f317217, v22
	v_cmp_lt_f32_e64 vcc, |v22|, s28
	s_nop 1
	v_cndmask_b32_e32 v21, v22, v21, vcc
	v_cndmask_b32_e64 v22, 0, v112, s[0:1]
	v_sub_f32_e32 v21, v21, v22
	v_pk_add_f32 v[18:19], v[18:19], v[20:21] neg_lo:[0,1] neg_hi:[0,1]
	s_nop 0
	v_pk_mul_f32 v[86:87], v[18:19], s[4:5] op_sel_hi:[1,0]
	global_load_dwordx4 v[18:21], v123, s[48:49] offset:32
	global_load_dwordx4 v[22:25], v123, s[46:47] offset:32
	global_load_dwordx4 v[26:29], v123, s[46:47] offset:3104
	global_load_dwordx4 v[30:33], v123, s[46:47] offset:3616
	global_load_dwordx4 v[34:37], v111, s[8:9] offset:32
	global_load_dwordx4 v[38:41], v111, s[8:9] offset:544
	global_load_dwordx4 v[42:45], v111, s[8:9] offset:1056
	global_load_dwordx4 v[46:49], v111, s[8:9] offset:1568
	global_load_dwordx4 v[50:53], v111, s[8:9] offset:2080
	global_load_dwordx4 v[54:57], v111, s[8:9] offset:2592
	global_load_dwordx4 v[58:61], v111, s[8:9] offset:3104
	global_load_dwordx4 v[62:65], v111, s[8:9] offset:3616
	global_load_dwordx4 v[88:91], v123, s[46:47] offset:544
	global_load_dwordx4 v[92:95], v123, s[46:47] offset:1056
	global_load_dwordx4 v[96:99], v123, s[46:47] offset:1568
	global_load_dwordx4 v[100:103], v123, s[46:47] offset:2080
	global_load_dwordx4 v[104:107], v123, s[46:47] offset:2592
	s_waitcnt vmcnt(15)
	v_fma_f32 v134, v22, v118, v18
	v_fma_f32 v20, v24, v118, v20
	s_waitcnt vmcnt(14)
	v_mov_b32_e32 v124, v26
	s_waitcnt vmcnt(13)
	v_mov_b32_e32 v125, v30
	v_fma_f32 v23, v23, v118, v19
	v_mov_b32_e32 v30, v27
	v_mov_b32_e32 v18, v28
	v_mov_b32_e32 v19, v32
	v_pk_mul_f32 v[26:27], v[124:125], v[72:73]
	s_waitcnt vmcnt(12)
	v_mov_b32_e32 v126, v34
	s_waitcnt vmcnt(11)
	v_mov_b32_e32 v127, v38
	s_waitcnt vmcnt(4)
	v_fmac_f32_e32 v134, v88, v117
	v_fmac_f32_e32 v20, v90, v117
	s_waitcnt vmcnt(3)
	v_fmac_f32_e32 v134, v92, v122
	v_fmac_f32_e32 v20, v94, v122
	s_waitcnt vmcnt(2)
	v_fmac_f32_e32 v134, v96, v121
	v_fmac_f32_e32 v20, v98, v121
	s_waitcnt vmcnt(1)
	v_fmac_f32_e32 v134, v100, v120
	v_fmac_f32_e32 v20, v102, v120
	s_waitcnt vmcnt(0)
	v_fmac_f32_e32 v134, v104, v119
	v_fmac_f32_e32 v23, v89, v117
	v_pk_mul_f32 v[18:19], v[18:19], v[72:73]
	v_fmac_f32_e32 v20, v106, v119
	v_add_f32_e32 v24, v134, v26
	v_mov_b32_e32 v38, v35
	v_pk_mul_f32 v[34:35], v[126:127], v[74:75]
	v_fmac_f32_e32 v23, v93, v122
	v_add_f32_e32 v18, v18, v20
	v_add_f32_e32 v20, v24, v27
	v_mov_b32_e32 v128, v42
	v_mov_b32_e32 v129, v46
	v_fmac_f32_e32 v23, v97, v121
	v_add_f32_e32 v20, v20, v34
	v_mov_b32_e32 v46, v43
	v_pk_mul_f32 v[42:43], v[128:129], v[78:79]
	v_fmac_f32_e32 v23, v101, v120
	v_add_f32_e32 v20, v20, v35
	v_mov_b32_e32 v130, v50
	v_mov_b32_e32 v131, v54
	v_pk_mul_f32 v[30:31], v[30:31], v[72:73]
	v_fmac_f32_e32 v23, v105, v119
	v_add_f32_e32 v20, v20, v42
	v_mov_b32_e32 v54, v51
	v_pk_mul_f32 v[50:51], v[130:131], v[80:81]
	v_add_f32_e32 v23, v30, v23
	v_add_f32_e32 v20, v20, v43
	v_mov_b32_e32 v132, v58
	v_mov_b32_e32 v133, v62
	v_pk_mul_f32 v[38:39], v[38:39], v[74:75]
	v_add_f32_e32 v23, v31, v23
	v_add_f32_e32 v20, v20, v50
	v_mov_b32_e32 v62, v59
	v_pk_mul_f32 v[58:59], v[132:133], v[82:83]
	v_add_f32_e32 v23, v38, v23
	v_add_f32_e32 v20, v20, v51
	v_pk_mul_f32 v[46:47], v[46:47], v[78:79]
	v_add_f32_e32 v23, v39, v23
	v_add_f32_e32 v20, v20, v58
	v_add_f32_e32 v23, v46, v23
	v_add_f32_e32 v20, v20, v59
	v_pk_mul_f32 v[54:55], v[54:55], v[80:81]
	v_add_f32_e32 v23, v47, v23
	v_mul_f32_e64 v24, |v20|, s25
	v_add_f32_e32 v23, v54, v23
	v_exp_f32_e32 v24, v24
	v_pk_mul_f32 v[62:63], v[62:63], v[82:83]
	v_add_f32_e32 v23, v55, v23
	v_add_f32_e32 v23, v62, v23
	v_add_f32_e32 v23, v63, v23
	v_mul_f32_e64 v26, |v23|, s25
	v_add_f32_e32 v27, v19, v18
	v_add_f32_e32 v19, 1.0, v24
	v_exp_f32_e32 v26, v26
	v_cmp_gt_f32_e32 vcc, s26, v19
	v_min_f32_e32 v18, 0, v20
	v_mov_b32_e32 v22, v36
	v_cndmask_b32_e64 v24, 0, 32, vcc
	v_ldexp_f32 v19, v19, v24
	v_log_f32_e32 v24, v19
	v_add_f32_e32 v20, 1.0, v26
	v_cmp_gt_f32_e64 s[0:1], s26, v20
	v_min_f32_e32 v19, 0, v23
	v_cndmask_b32_e32 v23, 0, v112, vcc
	v_cndmask_b32_e64 v26, 0, 32, s[0:1]
	v_ldexp_f32 v20, v20, v26
	v_mul_f32_e32 v26, 0x3f317217, v24
	v_fma_f32 v26, v24, s27, -v26
	v_fmac_f32_e32 v26, 0x3377d1cf, v24
	v_fmac_f32_e32 v26, 0x3f317217, v24
	v_cmp_lt_f32_e64 vcc, |v24|, s28
	v_log_f32_e32 v20, v20
	v_fmac_f32_e32 v21, v25, v118
	v_cndmask_b32_e32 v24, v24, v26, vcc
	v_sub_f32_e32 v26, v24, v23
	v_mov_b32_e32 v23, v40
	v_pk_mul_f32 v[22:23], v[22:23], v[74:75]
	v_mul_f32_e32 v28, 0x3f317217, v20
	v_add_f32_e32 v22, v22, v27
	v_add_f32_e32 v24, v23, v22
	v_mov_b32_e32 v22, v44
	v_mov_b32_e32 v23, v48
	v_pk_mul_f32 v[22:23], v[22:23], v[78:79]
	v_fma_f32 v28, v20, s27, -v28
	v_add_f32_e32 v22, v22, v24
	v_add_f32_e32 v24, v23, v22
	v_mov_b32_e32 v22, v52
	v_mov_b32_e32 v23, v56
	v_pk_mul_f32 v[22:23], v[22:23], v[80:81]
	v_fmac_f32_e32 v28, 0x3377d1cf, v20
	v_add_f32_e32 v22, v22, v24
	v_add_f32_e32 v24, v23, v22
	v_mov_b32_e32 v22, v60
	v_mov_b32_e32 v23, v64
	v_pk_mul_f32 v[22:23], v[22:23], v[82:83]
	v_fmac_f32_e32 v28, 0x3f317217, v20
	v_add_f32_e32 v22, v22, v24
	v_add_f32_e32 v22, v23, v22
	v_mul_f32_e64 v23, |v22|, s25
	v_exp_f32_e32 v23, v23
	v_cmp_lt_f32_e64 vcc, |v20|, s28
	v_cndmask_b32_e64 v24, 0, v112, s[0:1]
	v_fmac_f32_e32 v21, v91, v117
	v_cndmask_b32_e32 v20, v20, v28, vcc
	v_sub_f32_e32 v27, v20, v24
	v_add_f32_e32 v20, 1.0, v23
	v_fmac_f32_e32 v21, v95, v122
	v_cmp_gt_f32_e32 vcc, s26, v20
	v_fmac_f32_e32 v21, v99, v121
	v_pk_add_f32 v[18:19], v[18:19], v[26:27] neg_lo:[0,1] neg_hi:[0,1]
	v_cndmask_b32_e64 v23, 0, 32, vcc
	v_fmac_f32_e32 v21, v103, v120
	v_mov_b32_e32 v32, v29
	v_ldexp_f32 v20, v20, v23
	v_pk_mul_f32 v[88:89], v[18:19], s[4:5] op_sel_hi:[1,0]
	v_min_f32_e32 v18, 0, v22
	v_fmac_f32_e32 v21, v107, v119
	v_pk_mul_f32 v[22:23], v[32:33], v[72:73]
	v_log_f32_e32 v24, v20
	v_add_f32_e32 v20, v22, v21
	v_mov_b32_e32 v40, v37
	v_add_f32_e32 v22, v23, v20
	v_pk_mul_f32 v[20:21], v[40:41], v[74:75]
	v_mov_b32_e32 v48, v45
	v_add_f32_e32 v20, v20, v22
	v_add_f32_e32 v22, v21, v20
	v_pk_mul_f32 v[20:21], v[48:49], v[78:79]
	v_mov_b32_e32 v56, v53
	v_add_f32_e32 v20, v20, v22
	v_add_f32_e32 v22, v21, v20
	v_pk_mul_f32 v[20:21], v[56:57], v[80:81]
	v_mov_b32_e32 v64, v61
	v_add_f32_e32 v20, v20, v22
	v_add_f32_e32 v22, v21, v20
	v_pk_mul_f32 v[20:21], v[64:65], v[82:83]
	v_mul_f32_e32 v19, 0x3f317217, v24
	v_add_f32_e32 v20, v20, v22
	v_add_f32_e32 v21, v21, v20
	v_mul_f32_e64 v20, |v21|, s25
	v_exp_f32_e32 v20, v20
	v_fma_f32 v19, v24, s27, -v19
	v_fmac_f32_e32 v19, 0x3377d1cf, v24
	v_fmac_f32_e32 v19, 0x3f317217, v24
	v_cmp_lt_f32_e64 s[0:1], |v24|, s28
	v_add_f32_e32 v20, 1.0, v20
	s_nop 0
	v_cndmask_b32_e64 v19, v24, v19, s[0:1]
	v_cmp_gt_f32_e64 s[0:1], s26, v20
	s_nop 1
	v_cndmask_b32_e64 v22, 0, 32, s[0:1]
	v_ldexp_f32 v20, v20, v22
	v_log_f32_e32 v22, v20
	v_cndmask_b32_e32 v20, 0, v112, vcc
	v_sub_f32_e32 v20, v19, v20
	v_min_f32_e32 v19, 0, v21
	v_mul_f32_e32 v21, 0x3f317217, v22
	v_fma_f32 v21, v22, s27, -v21
	v_fmac_f32_e32 v21, 0x3377d1cf, v22
	v_fmac_f32_e32 v21, 0x3f317217, v22
	v_cmp_lt_f32_e64 vcc, |v22|, s28
	s_nop 1
	v_cndmask_b32_e32 v21, v22, v21, vcc
	v_cndmask_b32_e64 v22, 0, v112, s[0:1]
	v_sub_f32_e32 v21, v21, v22
	v_pk_add_f32 v[18:19], v[18:19], v[20:21] neg_lo:[0,1] neg_hi:[0,1]
	s_nop 0
	v_pk_mul_f32 v[90:91], v[18:19], s[4:5] op_sel_hi:[1,0]
	global_load_dwordx4 v[18:21], v123, s[48:49] offset:48
	global_load_dwordx4 v[22:25], v123, s[46:47] offset:48
	global_load_dwordx4 v[26:29], v123, s[46:47] offset:3120
	global_load_dwordx4 v[30:33], v123, s[46:47] offset:3632
	global_load_dwordx4 v[34:37], v111, s[8:9] offset:48
	global_load_dwordx4 v[38:41], v111, s[8:9] offset:560
	global_load_dwordx4 v[42:45], v111, s[8:9] offset:1072
	global_load_dwordx4 v[46:49], v111, s[8:9] offset:1584
	global_load_dwordx4 v[50:53], v111, s[8:9] offset:2096
	global_load_dwordx4 v[54:57], v111, s[8:9] offset:2608
	global_load_dwordx4 v[58:61], v111, s[8:9] offset:3120
	global_load_dwordx4 v[62:65], v111, s[8:9] offset:3632
	global_load_dwordx4 v[92:95], v123, s[46:47] offset:560
	global_load_dwordx4 v[96:99], v123, s[46:47] offset:1072
	global_load_dwordx4 v[100:103], v123, s[46:47] offset:1584
	global_load_dwordx4 v[104:107], v123, s[46:47] offset:2096
	global_load_dwordx4 v[124:127], v123, s[46:47] offset:2608
	s_waitcnt vmcnt(15)
	v_fma_f32 v138, v22, v118, v18
	v_fma_f32 v20, v24, v118, v20
	s_waitcnt vmcnt(14)
	v_mov_b32_e32 v128, v26
	s_waitcnt vmcnt(13)
	v_mov_b32_e32 v129, v30
	v_fma_f32 v23, v23, v118, v19
	v_mov_b32_e32 v30, v27
	v_mov_b32_e32 v18, v28
	v_mov_b32_e32 v19, v32
	v_pk_mul_f32 v[26:27], v[128:129], v[72:73]
	s_waitcnt vmcnt(12)
	v_mov_b32_e32 v130, v34
	s_waitcnt vmcnt(11)
	v_mov_b32_e32 v131, v38
	s_waitcnt vmcnt(4)
	v_fmac_f32_e32 v138, v92, v117
	v_fmac_f32_e32 v20, v94, v117
	s_waitcnt vmcnt(3)
	v_fmac_f32_e32 v138, v96, v122
	v_fmac_f32_e32 v20, v98, v122
	s_waitcnt vmcnt(2)
	v_fmac_f32_e32 v138, v100, v121
	v_fmac_f32_e32 v20, v102, v121
	s_waitcnt vmcnt(1)
	v_fmac_f32_e32 v138, v104, v120
	v_fmac_f32_e32 v20, v106, v120
	s_waitcnt vmcnt(0)
	v_fmac_f32_e32 v138, v124, v119
	v_fmac_f32_e32 v23, v93, v117
	v_pk_mul_f32 v[18:19], v[18:19], v[72:73]
	v_fmac_f32_e32 v20, v126, v119
	v_add_f32_e32 v24, v138, v26
	v_mov_b32_e32 v38, v35
	v_pk_mul_f32 v[34:35], v[130:131], v[74:75]
	v_fmac_f32_e32 v23, v97, v122
	v_add_f32_e32 v18, v18, v20
	v_add_f32_e32 v20, v24, v27
	v_mov_b32_e32 v132, v42
	v_mov_b32_e32 v133, v46
	v_fmac_f32_e32 v23, v101, v121
	v_add_f32_e32 v20, v20, v34
	v_mov_b32_e32 v46, v43
	v_pk_mul_f32 v[42:43], v[132:133], v[78:79]
	v_fmac_f32_e32 v23, v105, v120
	v_add_f32_e32 v20, v20, v35
	v_mov_b32_e32 v134, v50
	v_mov_b32_e32 v135, v54
	v_pk_mul_f32 v[30:31], v[30:31], v[72:73]
	v_fmac_f32_e32 v23, v125, v119
	v_add_f32_e32 v20, v20, v42
	v_mov_b32_e32 v54, v51
	v_pk_mul_f32 v[50:51], v[134:135], v[80:81]
	v_add_f32_e32 v23, v30, v23
	v_add_f32_e32 v20, v20, v43
	v_mov_b32_e32 v136, v58
	v_mov_b32_e32 v137, v62
	v_pk_mul_f32 v[38:39], v[38:39], v[74:75]
	v_add_f32_e32 v23, v31, v23
	v_add_f32_e32 v20, v20, v50
	v_mov_b32_e32 v62, v59
	v_pk_mul_f32 v[58:59], v[136:137], v[82:83]
	v_add_f32_e32 v23, v38, v23
	v_add_f32_e32 v20, v20, v51
	v_pk_mul_f32 v[46:47], v[46:47], v[78:79]
	v_add_f32_e32 v23, v39, v23
	v_add_f32_e32 v20, v20, v58
	v_add_f32_e32 v23, v46, v23
	v_add_f32_e32 v20, v20, v59
	v_pk_mul_f32 v[54:55], v[54:55], v[80:81]
	v_add_f32_e32 v23, v47, v23
	v_mul_f32_e64 v24, |v20|, s25
	v_add_f32_e32 v23, v54, v23
	v_exp_f32_e32 v24, v24
	v_pk_mul_f32 v[62:63], v[62:63], v[82:83]
	v_add_f32_e32 v23, v55, v23
	v_add_f32_e32 v23, v62, v23
	v_add_f32_e32 v23, v63, v23
	v_mul_f32_e64 v26, |v23|, s25
	v_add_f32_e32 v27, v19, v18
	v_add_f32_e32 v19, 1.0, v24
	v_exp_f32_e32 v26, v26
	v_cmp_gt_f32_e32 vcc, s26, v19
	v_min_f32_e32 v18, 0, v20
	v_mov_b32_e32 v22, v36
	v_cndmask_b32_e64 v24, 0, 32, vcc
	v_ldexp_f32 v19, v19, v24
	v_log_f32_e32 v24, v19
	v_add_f32_e32 v20, 1.0, v26
	v_cmp_gt_f32_e64 s[0:1], s26, v20
	v_min_f32_e32 v19, 0, v23
	v_cndmask_b32_e32 v23, 0, v112, vcc
	v_cndmask_b32_e64 v26, 0, 32, s[0:1]
	v_ldexp_f32 v20, v20, v26
	v_mul_f32_e32 v26, 0x3f317217, v24
	v_fma_f32 v26, v24, s27, -v26
	v_fmac_f32_e32 v26, 0x3377d1cf, v24
	v_fmac_f32_e32 v26, 0x3f317217, v24
	v_cmp_lt_f32_e64 vcc, |v24|, s28
	v_log_f32_e32 v20, v20
	v_fmac_f32_e32 v21, v25, v118
	v_cndmask_b32_e32 v24, v24, v26, vcc
	v_sub_f32_e32 v26, v24, v23
	v_mov_b32_e32 v23, v40
	v_pk_mul_f32 v[22:23], v[22:23], v[74:75]
	v_mul_f32_e32 v28, 0x3f317217, v20
	v_add_f32_e32 v22, v22, v27
	v_add_f32_e32 v24, v23, v22
	v_mov_b32_e32 v22, v44
	v_mov_b32_e32 v23, v48
	v_pk_mul_f32 v[22:23], v[22:23], v[78:79]
	v_fma_f32 v28, v20, s27, -v28
	v_add_f32_e32 v22, v22, v24
	v_add_f32_e32 v24, v23, v22
	v_mov_b32_e32 v22, v52
	v_mov_b32_e32 v23, v56
	v_pk_mul_f32 v[22:23], v[22:23], v[80:81]
	v_fmac_f32_e32 v28, 0x3377d1cf, v20
	v_add_f32_e32 v22, v22, v24
	v_add_f32_e32 v24, v23, v22
	v_mov_b32_e32 v22, v60
	v_mov_b32_e32 v23, v64
	v_pk_mul_f32 v[22:23], v[22:23], v[82:83]
	v_fmac_f32_e32 v28, 0x3f317217, v20
	v_add_f32_e32 v22, v22, v24
	v_add_f32_e32 v22, v23, v22
	v_mul_f32_e64 v23, |v22|, s25
	v_exp_f32_e32 v23, v23
	v_cmp_lt_f32_e64 vcc, |v20|, s28
	v_cndmask_b32_e64 v24, 0, v112, s[0:1]
	v_fmac_f32_e32 v21, v95, v117
	v_cndmask_b32_e32 v20, v20, v28, vcc
	v_sub_f32_e32 v27, v20, v24
	v_add_f32_e32 v20, 1.0, v23
	v_fmac_f32_e32 v21, v99, v122
	v_cmp_gt_f32_e32 vcc, s26, v20
	v_fmac_f32_e32 v21, v103, v121
	v_pk_add_f32 v[18:19], v[18:19], v[26:27] neg_lo:[0,1] neg_hi:[0,1]
	v_cndmask_b32_e64 v23, 0, 32, vcc
	v_fmac_f32_e32 v21, v107, v120
	v_mov_b32_e32 v32, v29
	v_ldexp_f32 v20, v20, v23
	v_pk_mul_f32 v[92:93], v[18:19], s[4:5] op_sel_hi:[1,0]
	v_min_f32_e32 v18, 0, v22
	v_fmac_f32_e32 v21, v127, v119
	v_pk_mul_f32 v[22:23], v[32:33], v[72:73]
	v_log_f32_e32 v24, v20
	v_add_f32_e32 v20, v22, v21
	v_mov_b32_e32 v40, v37
	v_add_f32_e32 v22, v23, v20
	v_pk_mul_f32 v[20:21], v[40:41], v[74:75]
	v_mov_b32_e32 v48, v45
	v_add_f32_e32 v20, v20, v22
	v_add_f32_e32 v22, v21, v20
	v_pk_mul_f32 v[20:21], v[48:49], v[78:79]
	v_mov_b32_e32 v56, v53
	v_add_f32_e32 v20, v20, v22
	v_add_f32_e32 v22, v21, v20
	v_pk_mul_f32 v[20:21], v[56:57], v[80:81]
	v_mov_b32_e32 v64, v61
	v_add_f32_e32 v20, v20, v22
	v_add_f32_e32 v22, v21, v20
	v_pk_mul_f32 v[20:21], v[64:65], v[82:83]
	v_mul_f32_e32 v19, 0x3f317217, v24
	v_add_f32_e32 v20, v20, v22
	v_add_f32_e32 v21, v21, v20
	v_mul_f32_e64 v20, |v21|, s25
	v_exp_f32_e32 v20, v20
	v_fma_f32 v19, v24, s27, -v19
	v_fmac_f32_e32 v19, 0x3377d1cf, v24
	v_fmac_f32_e32 v19, 0x3f317217, v24
	v_cmp_lt_f32_e64 s[0:1], |v24|, s28
	v_add_f32_e32 v20, 1.0, v20
	s_nop 0
	v_cndmask_b32_e64 v19, v24, v19, s[0:1]
	v_cmp_gt_f32_e64 s[0:1], s26, v20
	s_nop 1
	v_cndmask_b32_e64 v22, 0, 32, s[0:1]
	v_ldexp_f32 v20, v20, v22
	v_log_f32_e32 v22, v20
	v_cndmask_b32_e32 v20, 0, v112, vcc
	v_sub_f32_e32 v20, v19, v20
	v_min_f32_e32 v19, 0, v21
	v_mul_f32_e32 v21, 0x3f317217, v22
	v_fma_f32 v21, v22, s27, -v21
	v_fmac_f32_e32 v21, 0x3377d1cf, v22
	v_fmac_f32_e32 v21, 0x3f317217, v22
	v_cmp_lt_f32_e64 vcc, |v22|, s28
	s_nop 1
	v_cndmask_b32_e32 v21, v22, v21, vcc
	v_cndmask_b32_e64 v22, 0, v112, s[0:1]
	v_sub_f32_e32 v21, v21, v22
	v_pk_add_f32 v[18:19], v[18:19], v[20:21] neg_lo:[0,1] neg_hi:[0,1]
	s_nop 0
	v_pk_mul_f32 v[94:95], v[18:19], s[4:5] op_sel_hi:[1,0]
	global_load_dwordx4 v[18:21], v123, s[48:49] offset:64
	global_load_dwordx4 v[22:25], v123, s[46:47] offset:64
	global_load_dwordx4 v[26:29], v123, s[46:47] offset:3136
	global_load_dwordx4 v[30:33], v123, s[46:47] offset:3648
	global_load_dwordx4 v[34:37], v111, s[8:9] offset:64
	global_load_dwordx4 v[38:41], v111, s[8:9] offset:576
	global_load_dwordx4 v[42:45], v111, s[8:9] offset:1088
	global_load_dwordx4 v[46:49], v111, s[8:9] offset:1600
	global_load_dwordx4 v[50:53], v111, s[8:9] offset:2112
	global_load_dwordx4 v[54:57], v111, s[8:9] offset:2624
	global_load_dwordx4 v[58:61], v111, s[8:9] offset:3136
	global_load_dwordx4 v[62:65], v111, s[8:9] offset:3648
	global_load_dwordx4 v[96:99], v123, s[46:47] offset:576
	global_load_dwordx4 v[100:103], v123, s[46:47] offset:1088
	global_load_dwordx4 v[104:107], v123, s[46:47] offset:1600
	global_load_dwordx4 v[124:127], v123, s[46:47] offset:2112
	global_load_dwordx4 v[128:131], v123, s[46:47] offset:2624
	s_waitcnt vmcnt(15)
	v_fma_f32 v142, v22, v118, v18
	v_fma_f32 v20, v24, v118, v20
	s_waitcnt vmcnt(14)
	v_mov_b32_e32 v132, v26
	s_waitcnt vmcnt(13)
	v_mov_b32_e32 v133, v30
	v_fma_f32 v23, v23, v118, v19
	v_mov_b32_e32 v30, v27
	v_mov_b32_e32 v18, v28
	v_mov_b32_e32 v19, v32
	v_pk_mul_f32 v[26:27], v[132:133], v[72:73]
	s_waitcnt vmcnt(12)
	v_mov_b32_e32 v134, v34
	s_waitcnt vmcnt(11)
	v_mov_b32_e32 v135, v38
	s_waitcnt vmcnt(4)
	v_fmac_f32_e32 v142, v96, v117
	v_fmac_f32_e32 v20, v98, v117
	s_waitcnt vmcnt(3)
	v_fmac_f32_e32 v142, v100, v122
	v_fmac_f32_e32 v20, v102, v122
	s_waitcnt vmcnt(2)
	v_fmac_f32_e32 v142, v104, v121
	v_fmac_f32_e32 v20, v106, v121
	s_waitcnt vmcnt(1)
	v_fmac_f32_e32 v142, v124, v120
	v_fmac_f32_e32 v20, v126, v120
	s_waitcnt vmcnt(0)
	v_fmac_f32_e32 v142, v128, v119
	v_fmac_f32_e32 v23, v97, v117
	v_pk_mul_f32 v[18:19], v[18:19], v[72:73]
	v_fmac_f32_e32 v20, v130, v119
	v_add_f32_e32 v24, v142, v26
	v_mov_b32_e32 v38, v35
	v_pk_mul_f32 v[34:35], v[134:135], v[74:75]
	v_fmac_f32_e32 v23, v101, v122
	v_add_f32_e32 v18, v18, v20
	v_add_f32_e32 v20, v24, v27
	v_mov_b32_e32 v136, v42
	v_mov_b32_e32 v137, v46
	v_fmac_f32_e32 v23, v105, v121
	v_add_f32_e32 v20, v20, v34
	v_mov_b32_e32 v46, v43
	v_pk_mul_f32 v[42:43], v[136:137], v[78:79]
	v_fmac_f32_e32 v23, v125, v120
	v_add_f32_e32 v20, v20, v35
	v_mov_b32_e32 v138, v50
	v_mov_b32_e32 v139, v54
	v_pk_mul_f32 v[30:31], v[30:31], v[72:73]
	v_fmac_f32_e32 v23, v129, v119
	v_add_f32_e32 v20, v20, v42
	v_mov_b32_e32 v54, v51
	v_pk_mul_f32 v[50:51], v[138:139], v[80:81]
	v_add_f32_e32 v23, v30, v23
	v_add_f32_e32 v20, v20, v43
	v_mov_b32_e32 v140, v58
	v_mov_b32_e32 v141, v62
	v_pk_mul_f32 v[38:39], v[38:39], v[74:75]
	v_add_f32_e32 v23, v31, v23
	v_add_f32_e32 v20, v20, v50
	v_mov_b32_e32 v62, v59
	v_pk_mul_f32 v[58:59], v[140:141], v[82:83]
	v_add_f32_e32 v23, v38, v23
	v_add_f32_e32 v20, v20, v51
	v_pk_mul_f32 v[46:47], v[46:47], v[78:79]
	v_add_f32_e32 v23, v39, v23
	v_add_f32_e32 v20, v20, v58
	v_add_f32_e32 v23, v46, v23
	v_add_f32_e32 v20, v20, v59
	v_pk_mul_f32 v[54:55], v[54:55], v[80:81]
	v_add_f32_e32 v23, v47, v23
	v_mul_f32_e64 v24, |v20|, s25
	v_add_f32_e32 v23, v54, v23
	v_exp_f32_e32 v24, v24
	v_pk_mul_f32 v[62:63], v[62:63], v[82:83]
	v_add_f32_e32 v23, v55, v23
	v_add_f32_e32 v23, v62, v23
	v_add_f32_e32 v23, v63, v23
	v_mul_f32_e64 v26, |v23|, s25
	v_add_f32_e32 v27, v19, v18
	v_add_f32_e32 v19, 1.0, v24
	v_exp_f32_e32 v26, v26
	v_cmp_gt_f32_e32 vcc, s26, v19
	v_min_f32_e32 v18, 0, v20
	v_mov_b32_e32 v22, v36
	v_cndmask_b32_e64 v24, 0, 32, vcc
	v_ldexp_f32 v19, v19, v24
	v_log_f32_e32 v24, v19
	v_add_f32_e32 v20, 1.0, v26
	v_cmp_gt_f32_e64 s[0:1], s26, v20
	v_min_f32_e32 v19, 0, v23
	v_cndmask_b32_e32 v23, 0, v112, vcc
	v_cndmask_b32_e64 v26, 0, 32, s[0:1]
	v_ldexp_f32 v20, v20, v26
	v_mul_f32_e32 v26, 0x3f317217, v24
	v_fma_f32 v26, v24, s27, -v26
	v_fmac_f32_e32 v26, 0x3377d1cf, v24
	v_fmac_f32_e32 v26, 0x3f317217, v24
	v_cmp_lt_f32_e64 vcc, |v24|, s28
	v_log_f32_e32 v20, v20
	v_fmac_f32_e32 v21, v25, v118
	v_cndmask_b32_e32 v24, v24, v26, vcc
	v_sub_f32_e32 v26, v24, v23
	v_mov_b32_e32 v23, v40
	v_pk_mul_f32 v[22:23], v[22:23], v[74:75]
	v_mul_f32_e32 v28, 0x3f317217, v20
	v_add_f32_e32 v22, v22, v27
	v_add_f32_e32 v24, v23, v22
	v_mov_b32_e32 v22, v44
	v_mov_b32_e32 v23, v48
	v_pk_mul_f32 v[22:23], v[22:23], v[78:79]
	v_fma_f32 v28, v20, s27, -v28
	v_add_f32_e32 v22, v22, v24
	v_add_f32_e32 v24, v23, v22
	v_mov_b32_e32 v22, v52
	v_mov_b32_e32 v23, v56
	v_pk_mul_f32 v[22:23], v[22:23], v[80:81]
	v_fmac_f32_e32 v28, 0x3377d1cf, v20
	v_add_f32_e32 v22, v22, v24
	v_add_f32_e32 v24, v23, v22
	v_mov_b32_e32 v22, v60
	v_mov_b32_e32 v23, v64
	v_pk_mul_f32 v[22:23], v[22:23], v[82:83]
	v_fmac_f32_e32 v28, 0x3f317217, v20
	v_add_f32_e32 v22, v22, v24
	v_add_f32_e32 v22, v23, v22
	v_mul_f32_e64 v23, |v22|, s25
	v_exp_f32_e32 v23, v23
	v_cmp_lt_f32_e64 vcc, |v20|, s28
	v_cndmask_b32_e64 v24, 0, v112, s[0:1]
	v_fmac_f32_e32 v21, v99, v117
	v_cndmask_b32_e32 v20, v20, v28, vcc
	v_sub_f32_e32 v27, v20, v24
	v_add_f32_e32 v20, 1.0, v23
	v_fmac_f32_e32 v21, v103, v122
	v_cmp_gt_f32_e32 vcc, s26, v20
	v_fmac_f32_e32 v21, v107, v121
	v_pk_add_f32 v[18:19], v[18:19], v[26:27] neg_lo:[0,1] neg_hi:[0,1]
	v_cndmask_b32_e64 v23, 0, 32, vcc
	v_fmac_f32_e32 v21, v127, v120
	v_mov_b32_e32 v32, v29
	v_ldexp_f32 v20, v20, v23
	v_pk_mul_f32 v[96:97], v[18:19], s[4:5] op_sel_hi:[1,0]
	v_min_f32_e32 v18, 0, v22
	v_fmac_f32_e32 v21, v131, v119
	v_pk_mul_f32 v[22:23], v[32:33], v[72:73]
	v_log_f32_e32 v24, v20
	v_add_f32_e32 v20, v22, v21
	v_mov_b32_e32 v40, v37
	v_add_f32_e32 v22, v23, v20
	v_pk_mul_f32 v[20:21], v[40:41], v[74:75]
	v_mov_b32_e32 v48, v45
	v_add_f32_e32 v20, v20, v22
	v_add_f32_e32 v22, v21, v20
	v_pk_mul_f32 v[20:21], v[48:49], v[78:79]
	v_mov_b32_e32 v56, v53
	v_add_f32_e32 v20, v20, v22
	v_add_f32_e32 v22, v21, v20
	v_pk_mul_f32 v[20:21], v[56:57], v[80:81]
	v_mov_b32_e32 v64, v61
	v_add_f32_e32 v20, v20, v22
	v_add_f32_e32 v22, v21, v20
	v_pk_mul_f32 v[20:21], v[64:65], v[82:83]
	v_mul_f32_e32 v19, 0x3f317217, v24
	v_add_f32_e32 v20, v20, v22
	v_add_f32_e32 v21, v21, v20
	v_mul_f32_e64 v20, |v21|, s25
	v_exp_f32_e32 v20, v20
	v_fma_f32 v19, v24, s27, -v19
	v_fmac_f32_e32 v19, 0x3377d1cf, v24
	v_fmac_f32_e32 v19, 0x3f317217, v24
	v_cmp_lt_f32_e64 s[0:1], |v24|, s28
	v_add_f32_e32 v20, 1.0, v20
	s_nop 0
	v_cndmask_b32_e64 v19, v24, v19, s[0:1]
	v_cmp_gt_f32_e64 s[0:1], s26, v20
	s_nop 1
	v_cndmask_b32_e64 v22, 0, 32, s[0:1]
	v_ldexp_f32 v20, v20, v22
	v_log_f32_e32 v22, v20
	v_cndmask_b32_e32 v20, 0, v112, vcc
	v_sub_f32_e32 v20, v19, v20
	v_min_f32_e32 v19, 0, v21
	v_mul_f32_e32 v21, 0x3f317217, v22
	v_fma_f32 v21, v22, s27, -v21
	v_fmac_f32_e32 v21, 0x3377d1cf, v22
	v_fmac_f32_e32 v21, 0x3f317217, v22
	v_cmp_lt_f32_e64 vcc, |v22|, s28
	s_nop 1
	v_cndmask_b32_e32 v21, v22, v21, vcc
	v_cndmask_b32_e64 v22, 0, v112, s[0:1]
	v_sub_f32_e32 v21, v21, v22
	v_pk_add_f32 v[18:19], v[18:19], v[20:21] neg_lo:[0,1] neg_hi:[0,1]
	s_nop 0
	v_pk_mul_f32 v[98:99], v[18:19], s[4:5] op_sel_hi:[1,0]
	global_load_dwordx4 v[18:21], v123, s[48:49] offset:80
	global_load_dwordx4 v[22:25], v123, s[46:47] offset:80
	global_load_dwordx4 v[26:29], v123, s[46:47] offset:3152
	global_load_dwordx4 v[30:33], v123, s[46:47] offset:3664
	global_load_dwordx4 v[34:37], v111, s[8:9] offset:80
	global_load_dwordx4 v[38:41], v111, s[8:9] offset:592
	global_load_dwordx4 v[42:45], v111, s[8:9] offset:1104
	global_load_dwordx4 v[46:49], v111, s[8:9] offset:1616
	global_load_dwordx4 v[50:53], v111, s[8:9] offset:2128
	global_load_dwordx4 v[54:57], v111, s[8:9] offset:2640
	global_load_dwordx4 v[58:61], v111, s[8:9] offset:3152
	global_load_dwordx4 v[62:65], v111, s[8:9] offset:3664
	global_load_dwordx4 v[100:103], v123, s[46:47] offset:592
	global_load_dwordx4 v[104:107], v123, s[46:47] offset:1104
	global_load_dwordx4 v[124:127], v123, s[46:47] offset:1616
	global_load_dwordx4 v[128:131], v123, s[46:47] offset:2128
	global_load_dwordx4 v[132:135], v123, s[46:47] offset:2640
	s_waitcnt vmcnt(15)
	v_fma_f32 v146, v22, v118, v18
	v_fma_f32 v20, v24, v118, v20
	s_waitcnt vmcnt(14)
	v_mov_b32_e32 v136, v26
	s_waitcnt vmcnt(13)
	v_mov_b32_e32 v137, v30
	v_fma_f32 v23, v23, v118, v19
	v_mov_b32_e32 v30, v27
	v_mov_b32_e32 v18, v28
	v_mov_b32_e32 v19, v32
	v_pk_mul_f32 v[26:27], v[136:137], v[72:73]
	s_waitcnt vmcnt(12)
	v_mov_b32_e32 v138, v34
	s_waitcnt vmcnt(11)
	v_mov_b32_e32 v139, v38
	s_waitcnt vmcnt(4)
	v_fmac_f32_e32 v146, v100, v117
	v_fmac_f32_e32 v20, v102, v117
	s_waitcnt vmcnt(3)
	v_fmac_f32_e32 v146, v104, v122
	v_fmac_f32_e32 v20, v106, v122
	s_waitcnt vmcnt(2)
	v_fmac_f32_e32 v146, v124, v121
	v_fmac_f32_e32 v20, v126, v121
	s_waitcnt vmcnt(1)
	v_fmac_f32_e32 v146, v128, v120
	v_fmac_f32_e32 v20, v130, v120
	s_waitcnt vmcnt(0)
	v_fmac_f32_e32 v146, v132, v119
	v_fmac_f32_e32 v23, v101, v117
	v_pk_mul_f32 v[18:19], v[18:19], v[72:73]
	v_fmac_f32_e32 v20, v134, v119
	v_add_f32_e32 v24, v146, v26
	v_mov_b32_e32 v38, v35
	v_pk_mul_f32 v[34:35], v[138:139], v[74:75]
	v_fmac_f32_e32 v23, v105, v122
	v_add_f32_e32 v18, v18, v20
	v_add_f32_e32 v20, v24, v27
	v_mov_b32_e32 v140, v42
	v_mov_b32_e32 v141, v46
	v_fmac_f32_e32 v23, v125, v121
	v_add_f32_e32 v20, v20, v34
	v_mov_b32_e32 v46, v43
	v_pk_mul_f32 v[42:43], v[140:141], v[78:79]
	v_fmac_f32_e32 v23, v129, v120
	v_add_f32_e32 v20, v20, v35
	v_mov_b32_e32 v142, v50
	v_mov_b32_e32 v143, v54
	v_pk_mul_f32 v[30:31], v[30:31], v[72:73]
	v_fmac_f32_e32 v23, v133, v119
	v_add_f32_e32 v20, v20, v42
	v_mov_b32_e32 v54, v51
	v_pk_mul_f32 v[50:51], v[142:143], v[80:81]
	v_add_f32_e32 v23, v30, v23
	v_add_f32_e32 v20, v20, v43
	v_mov_b32_e32 v144, v58
	v_mov_b32_e32 v145, v62
	v_pk_mul_f32 v[38:39], v[38:39], v[74:75]
	v_add_f32_e32 v23, v31, v23
	v_add_f32_e32 v20, v20, v50
	v_mov_b32_e32 v62, v59
	v_pk_mul_f32 v[58:59], v[144:145], v[82:83]
	v_add_f32_e32 v23, v38, v23
	v_add_f32_e32 v20, v20, v51
	v_pk_mul_f32 v[46:47], v[46:47], v[78:79]
	v_add_f32_e32 v23, v39, v23
	v_add_f32_e32 v20, v20, v58
	v_add_f32_e32 v23, v46, v23
	v_add_f32_e32 v20, v20, v59
	v_pk_mul_f32 v[54:55], v[54:55], v[80:81]
	v_add_f32_e32 v23, v47, v23
	v_mul_f32_e64 v24, |v20|, s25
	v_add_f32_e32 v23, v54, v23
	v_exp_f32_e32 v24, v24
	v_pk_mul_f32 v[62:63], v[62:63], v[82:83]
	v_add_f32_e32 v23, v55, v23
	v_add_f32_e32 v23, v62, v23
	v_add_f32_e32 v23, v63, v23
	v_mul_f32_e64 v26, |v23|, s25
	v_add_f32_e32 v27, v19, v18
	v_add_f32_e32 v19, 1.0, v24
	v_exp_f32_e32 v26, v26
	v_cmp_gt_f32_e32 vcc, s26, v19
	v_min_f32_e32 v18, 0, v20
	v_mov_b32_e32 v22, v36
	v_cndmask_b32_e64 v24, 0, 32, vcc
	v_ldexp_f32 v19, v19, v24
	v_log_f32_e32 v24, v19
	v_add_f32_e32 v20, 1.0, v26
	v_cmp_gt_f32_e64 s[0:1], s26, v20
	v_min_f32_e32 v19, 0, v23
	v_cndmask_b32_e32 v23, 0, v112, vcc
	v_cndmask_b32_e64 v26, 0, 32, s[0:1]
	v_ldexp_f32 v20, v20, v26
	v_mul_f32_e32 v26, 0x3f317217, v24
	v_fma_f32 v26, v24, s27, -v26
	v_fmac_f32_e32 v26, 0x3377d1cf, v24
	v_fmac_f32_e32 v26, 0x3f317217, v24
	v_cmp_lt_f32_e64 vcc, |v24|, s28
	v_log_f32_e32 v20, v20
	v_fmac_f32_e32 v21, v25, v118
	v_cndmask_b32_e32 v24, v24, v26, vcc
	v_sub_f32_e32 v26, v24, v23
	v_mov_b32_e32 v23, v40
	v_pk_mul_f32 v[22:23], v[22:23], v[74:75]
	v_mul_f32_e32 v28, 0x3f317217, v20
	v_add_f32_e32 v22, v22, v27
	v_add_f32_e32 v24, v23, v22
	v_mov_b32_e32 v22, v44
	v_mov_b32_e32 v23, v48
	v_pk_mul_f32 v[22:23], v[22:23], v[78:79]
	v_fma_f32 v28, v20, s27, -v28
	v_add_f32_e32 v22, v22, v24
	v_add_f32_e32 v24, v23, v22
	v_mov_b32_e32 v22, v52
	v_mov_b32_e32 v23, v56
	v_pk_mul_f32 v[22:23], v[22:23], v[80:81]
	v_fmac_f32_e32 v28, 0x3377d1cf, v20
	v_add_f32_e32 v22, v22, v24
	v_add_f32_e32 v24, v23, v22
	v_mov_b32_e32 v22, v60
	v_mov_b32_e32 v23, v64
	v_pk_mul_f32 v[22:23], v[22:23], v[82:83]
	v_fmac_f32_e32 v28, 0x3f317217, v20
	v_add_f32_e32 v22, v22, v24
	v_add_f32_e32 v22, v23, v22
	v_mul_f32_e64 v23, |v22|, s25
	v_exp_f32_e32 v23, v23
	v_cmp_lt_f32_e64 vcc, |v20|, s28
	v_cndmask_b32_e64 v24, 0, v112, s[0:1]
	v_fmac_f32_e32 v21, v103, v117
	v_cndmask_b32_e32 v20, v20, v28, vcc
	v_sub_f32_e32 v27, v20, v24
	v_add_f32_e32 v20, 1.0, v23
	v_fmac_f32_e32 v21, v107, v122
	v_cmp_gt_f32_e32 vcc, s26, v20
	v_fmac_f32_e32 v21, v127, v121
	v_pk_add_f32 v[18:19], v[18:19], v[26:27] neg_lo:[0,1] neg_hi:[0,1]
	v_cndmask_b32_e64 v23, 0, 32, vcc
	v_fmac_f32_e32 v21, v131, v120
	v_mov_b32_e32 v32, v29
	v_ldexp_f32 v20, v20, v23
	v_pk_mul_f32 v[100:101], v[18:19], s[4:5] op_sel_hi:[1,0]
	v_min_f32_e32 v18, 0, v22
	v_fmac_f32_e32 v21, v135, v119
	v_pk_mul_f32 v[22:23], v[32:33], v[72:73]
	v_log_f32_e32 v24, v20
	v_add_f32_e32 v20, v22, v21
	v_mov_b32_e32 v40, v37
	v_add_f32_e32 v22, v23, v20
	v_pk_mul_f32 v[20:21], v[40:41], v[74:75]
	v_mov_b32_e32 v48, v45
	v_add_f32_e32 v20, v20, v22
	v_add_f32_e32 v22, v21, v20
	v_pk_mul_f32 v[20:21], v[48:49], v[78:79]
	v_mov_b32_e32 v56, v53
	v_add_f32_e32 v20, v20, v22
	v_add_f32_e32 v22, v21, v20
	v_pk_mul_f32 v[20:21], v[56:57], v[80:81]
	v_mov_b32_e32 v64, v61
	v_add_f32_e32 v20, v20, v22
	v_add_f32_e32 v22, v21, v20
	v_pk_mul_f32 v[20:21], v[64:65], v[82:83]
	v_mul_f32_e32 v19, 0x3f317217, v24
	v_add_f32_e32 v20, v20, v22
	v_add_f32_e32 v21, v21, v20
	v_mul_f32_e64 v20, |v21|, s25
	v_exp_f32_e32 v20, v20
	v_fma_f32 v19, v24, s27, -v19
	v_fmac_f32_e32 v19, 0x3377d1cf, v24
	v_fmac_f32_e32 v19, 0x3f317217, v24
	v_cmp_lt_f32_e64 s[0:1], |v24|, s28
	v_add_f32_e32 v20, 1.0, v20
	s_nop 0
	v_cndmask_b32_e64 v19, v24, v19, s[0:1]
	v_cmp_gt_f32_e64 s[0:1], s26, v20
	s_nop 1
	v_cndmask_b32_e64 v22, 0, 32, s[0:1]
	v_ldexp_f32 v20, v20, v22
	v_log_f32_e32 v22, v20
	v_cndmask_b32_e32 v20, 0, v112, vcc
	v_sub_f32_e32 v20, v19, v20
	v_min_f32_e32 v19, 0, v21
	v_mul_f32_e32 v21, 0x3f317217, v22
	v_fma_f32 v21, v22, s27, -v21
	v_fmac_f32_e32 v21, 0x3377d1cf, v22
	v_fmac_f32_e32 v21, 0x3f317217, v22
	v_cmp_lt_f32_e64 vcc, |v22|, s28
	s_nop 1
	v_cndmask_b32_e32 v21, v22, v21, vcc
	v_cndmask_b32_e64 v22, 0, v112, s[0:1]
	v_sub_f32_e32 v21, v21, v22
	v_pk_add_f32 v[18:19], v[18:19], v[20:21] neg_lo:[0,1] neg_hi:[0,1]
	s_nop 0
	v_pk_mul_f32 v[102:103], v[18:19], s[4:5] op_sel_hi:[1,0]
	global_load_dwordx4 v[18:21], v123, s[48:49] offset:96
	global_load_dwordx4 v[22:25], v123, s[46:47] offset:96
	global_load_dwordx4 v[26:29], v123, s[46:47] offset:3168
	global_load_dwordx4 v[30:33], v123, s[46:47] offset:3680
	global_load_dwordx4 v[34:37], v111, s[8:9] offset:96
	global_load_dwordx4 v[38:41], v111, s[8:9] offset:608
	global_load_dwordx4 v[42:45], v111, s[8:9] offset:1120
	global_load_dwordx4 v[46:49], v111, s[8:9] offset:1632
	global_load_dwordx4 v[50:53], v111, s[8:9] offset:2144
	global_load_dwordx4 v[54:57], v111, s[8:9] offset:2656
	global_load_dwordx4 v[58:61], v111, s[8:9] offset:3168
	global_load_dwordx4 v[62:65], v111, s[8:9] offset:3680
	global_load_dwordx4 v[104:107], v123, s[46:47] offset:608
	global_load_dwordx4 v[124:127], v123, s[46:47] offset:1120
	global_load_dwordx4 v[128:131], v123, s[46:47] offset:1632
	global_load_dwordx4 v[132:135], v123, s[46:47] offset:2144
	global_load_dwordx4 v[136:139], v123, s[46:47] offset:2656
	s_waitcnt vmcnt(15)
	v_fma_f32 v150, v22, v118, v18
	v_fma_f32 v20, v24, v118, v20
	s_waitcnt vmcnt(14)
	v_mov_b32_e32 v140, v26
	s_waitcnt vmcnt(13)
	v_mov_b32_e32 v141, v30
	v_fma_f32 v23, v23, v118, v19
	v_mov_b32_e32 v30, v27
	v_mov_b32_e32 v18, v28
	v_mov_b32_e32 v19, v32
	v_pk_mul_f32 v[26:27], v[140:141], v[72:73]
	s_waitcnt vmcnt(12)
	v_mov_b32_e32 v142, v34
	s_waitcnt vmcnt(11)
	v_mov_b32_e32 v143, v38
	s_waitcnt vmcnt(4)
	v_fmac_f32_e32 v150, v104, v117
	v_fmac_f32_e32 v20, v106, v117
	s_waitcnt vmcnt(3)
	v_fmac_f32_e32 v150, v124, v122
	v_fmac_f32_e32 v20, v126, v122
	s_waitcnt vmcnt(2)
	v_fmac_f32_e32 v150, v128, v121
	v_fmac_f32_e32 v20, v130, v121
	s_waitcnt vmcnt(1)
	v_fmac_f32_e32 v150, v132, v120
	v_fmac_f32_e32 v20, v134, v120
	s_waitcnt vmcnt(0)
	v_fmac_f32_e32 v150, v136, v119
	v_fmac_f32_e32 v23, v105, v117
	v_pk_mul_f32 v[18:19], v[18:19], v[72:73]
	v_fmac_f32_e32 v20, v138, v119
	v_add_f32_e32 v24, v150, v26
	v_mov_b32_e32 v38, v35
	v_pk_mul_f32 v[34:35], v[142:143], v[74:75]
	v_fmac_f32_e32 v23, v125, v122
	v_add_f32_e32 v18, v18, v20
	v_add_f32_e32 v20, v24, v27
	v_mov_b32_e32 v144, v42
	v_mov_b32_e32 v145, v46
	v_fmac_f32_e32 v23, v129, v121
	v_add_f32_e32 v20, v20, v34
	v_mov_b32_e32 v46, v43
	v_pk_mul_f32 v[42:43], v[144:145], v[78:79]
	v_fmac_f32_e32 v23, v133, v120
	v_add_f32_e32 v20, v20, v35
	v_mov_b32_e32 v146, v50
	v_mov_b32_e32 v147, v54
	v_pk_mul_f32 v[30:31], v[30:31], v[72:73]
	v_fmac_f32_e32 v23, v137, v119
	v_add_f32_e32 v20, v20, v42
	v_mov_b32_e32 v54, v51
	v_pk_mul_f32 v[50:51], v[146:147], v[80:81]
	v_add_f32_e32 v23, v30, v23
	v_add_f32_e32 v20, v20, v43
	v_mov_b32_e32 v148, v58
	v_mov_b32_e32 v149, v62
	v_pk_mul_f32 v[38:39], v[38:39], v[74:75]
	v_add_f32_e32 v23, v31, v23
	v_add_f32_e32 v20, v20, v50
	v_mov_b32_e32 v62, v59
	v_pk_mul_f32 v[58:59], v[148:149], v[82:83]
	v_add_f32_e32 v23, v38, v23
	v_add_f32_e32 v20, v20, v51
	v_pk_mul_f32 v[46:47], v[46:47], v[78:79]
	v_add_f32_e32 v23, v39, v23
	v_add_f32_e32 v20, v20, v58
	v_add_f32_e32 v23, v46, v23
	v_add_f32_e32 v20, v20, v59
	v_pk_mul_f32 v[54:55], v[54:55], v[80:81]
	v_add_f32_e32 v23, v47, v23
	v_mul_f32_e64 v24, |v20|, s25
	v_add_f32_e32 v23, v54, v23
	v_exp_f32_e32 v24, v24
	v_pk_mul_f32 v[62:63], v[62:63], v[82:83]
	v_add_f32_e32 v23, v55, v23
	v_add_f32_e32 v23, v62, v23
	v_add_f32_e32 v23, v63, v23
	v_mul_f32_e64 v26, |v23|, s25
	v_add_f32_e32 v27, v19, v18
	v_add_f32_e32 v19, 1.0, v24
	v_exp_f32_e32 v26, v26
	v_cmp_gt_f32_e32 vcc, s26, v19
	v_min_f32_e32 v18, 0, v20
	v_mov_b32_e32 v22, v36
	v_cndmask_b32_e64 v24, 0, 32, vcc
	v_ldexp_f32 v19, v19, v24
	v_log_f32_e32 v24, v19
	v_add_f32_e32 v20, 1.0, v26
	v_cmp_gt_f32_e64 s[0:1], s26, v20
	v_min_f32_e32 v19, 0, v23
	v_cndmask_b32_e32 v23, 0, v112, vcc
	v_cndmask_b32_e64 v26, 0, 32, s[0:1]
	v_ldexp_f32 v20, v20, v26
	v_mul_f32_e32 v26, 0x3f317217, v24
	v_fma_f32 v26, v24, s27, -v26
	v_fmac_f32_e32 v26, 0x3377d1cf, v24
	v_fmac_f32_e32 v26, 0x3f317217, v24
	v_cmp_lt_f32_e64 vcc, |v24|, s28
	v_log_f32_e32 v20, v20
	v_fmac_f32_e32 v21, v25, v118
	v_cndmask_b32_e32 v24, v24, v26, vcc
	v_sub_f32_e32 v26, v24, v23
	v_mov_b32_e32 v23, v40
	v_pk_mul_f32 v[22:23], v[22:23], v[74:75]
	v_mul_f32_e32 v28, 0x3f317217, v20
	v_add_f32_e32 v22, v22, v27
	v_add_f32_e32 v24, v23, v22
	v_mov_b32_e32 v22, v44
	v_mov_b32_e32 v23, v48
	v_pk_mul_f32 v[22:23], v[22:23], v[78:79]
	v_fma_f32 v28, v20, s27, -v28
	v_add_f32_e32 v22, v22, v24
	v_add_f32_e32 v24, v23, v22
	v_mov_b32_e32 v22, v52
	v_mov_b32_e32 v23, v56
	v_pk_mul_f32 v[22:23], v[22:23], v[80:81]
	v_fmac_f32_e32 v28, 0x3377d1cf, v20
	v_add_f32_e32 v22, v22, v24
	v_add_f32_e32 v24, v23, v22
	v_mov_b32_e32 v22, v60
	v_mov_b32_e32 v23, v64
	v_pk_mul_f32 v[22:23], v[22:23], v[82:83]
	v_fmac_f32_e32 v28, 0x3f317217, v20
	v_add_f32_e32 v22, v22, v24
	v_add_f32_e32 v22, v23, v22
	v_mul_f32_e64 v23, |v22|, s25
	v_exp_f32_e32 v23, v23
	v_cmp_lt_f32_e64 vcc, |v20|, s28
	v_cndmask_b32_e64 v24, 0, v112, s[0:1]
	v_fmac_f32_e32 v21, v107, v117
	v_cndmask_b32_e32 v20, v20, v28, vcc
	v_sub_f32_e32 v27, v20, v24
	v_add_f32_e32 v20, 1.0, v23
	v_fmac_f32_e32 v21, v127, v122
	v_cmp_gt_f32_e32 vcc, s26, v20
	v_fmac_f32_e32 v21, v131, v121
	v_pk_add_f32 v[18:19], v[18:19], v[26:27] neg_lo:[0,1] neg_hi:[0,1]
	v_cndmask_b32_e64 v23, 0, 32, vcc
	v_fmac_f32_e32 v21, v135, v120
	v_mov_b32_e32 v32, v29
	v_ldexp_f32 v20, v20, v23
	v_pk_mul_f32 v[104:105], v[18:19], s[4:5] op_sel_hi:[1,0]
	v_min_f32_e32 v18, 0, v22
	v_fmac_f32_e32 v21, v139, v119
	v_pk_mul_f32 v[22:23], v[32:33], v[72:73]
	v_log_f32_e32 v24, v20
	v_add_f32_e32 v20, v22, v21
	v_mov_b32_e32 v40, v37
	v_add_f32_e32 v22, v23, v20
	v_pk_mul_f32 v[20:21], v[40:41], v[74:75]
	v_mov_b32_e32 v48, v45
	v_add_f32_e32 v20, v20, v22
	v_add_f32_e32 v22, v21, v20
	v_pk_mul_f32 v[20:21], v[48:49], v[78:79]
	v_mov_b32_e32 v56, v53
	v_add_f32_e32 v20, v20, v22
	v_add_f32_e32 v22, v21, v20
	v_pk_mul_f32 v[20:21], v[56:57], v[80:81]
	v_mov_b32_e32 v64, v61
	v_add_f32_e32 v20, v20, v22
	v_add_f32_e32 v22, v21, v20
	v_pk_mul_f32 v[20:21], v[64:65], v[82:83]
	v_mul_f32_e32 v19, 0x3f317217, v24
	v_add_f32_e32 v20, v20, v22
	v_add_f32_e32 v21, v21, v20
	v_mul_f32_e64 v20, |v21|, s25
	v_exp_f32_e32 v20, v20
	v_fma_f32 v19, v24, s27, -v19
	v_fmac_f32_e32 v19, 0x3377d1cf, v24
	v_fmac_f32_e32 v19, 0x3f317217, v24
	v_cmp_lt_f32_e64 s[0:1], |v24|, s28
	v_add_f32_e32 v20, 1.0, v20
	s_nop 0
	v_cndmask_b32_e64 v19, v24, v19, s[0:1]
	v_cmp_gt_f32_e64 s[0:1], s26, v20
	s_nop 1
	v_cndmask_b32_e64 v22, 0, 32, s[0:1]
	v_ldexp_f32 v20, v20, v22
	v_log_f32_e32 v22, v20
	v_cndmask_b32_e32 v20, 0, v112, vcc
	v_sub_f32_e32 v20, v19, v20
	v_min_f32_e32 v19, 0, v21
	v_mul_f32_e32 v21, 0x3f317217, v22
	v_fma_f32 v21, v22, s27, -v21
	v_fmac_f32_e32 v21, 0x3377d1cf, v22
	v_fmac_f32_e32 v21, 0x3f317217, v22
	v_cmp_lt_f32_e64 vcc, |v22|, s28
	s_nop 1
	v_cndmask_b32_e32 v21, v22, v21, vcc
	v_cndmask_b32_e64 v22, 0, v112, s[0:1]
	v_sub_f32_e32 v21, v21, v22
	v_pk_add_f32 v[18:19], v[18:19], v[20:21] neg_lo:[0,1] neg_hi:[0,1]
	s_nop 0
	v_pk_mul_f32 v[106:107], v[18:19], s[4:5] op_sel_hi:[1,0]
	global_load_dwordx4 v[18:21], v123, s[48:49] offset:112
	global_load_dwordx4 v[22:25], v123, s[46:47] offset:112
	global_load_dwordx4 v[26:29], v123, s[46:47] offset:3184
	global_load_dwordx4 v[30:33], v123, s[46:47] offset:3696
	global_load_dwordx4 v[34:37], v111, s[8:9] offset:112
	global_load_dwordx4 v[38:41], v111, s[8:9] offset:624
	global_load_dwordx4 v[42:45], v111, s[8:9] offset:1136
	global_load_dwordx4 v[46:49], v111, s[8:9] offset:1648
	global_load_dwordx4 v[50:53], v111, s[8:9] offset:2160
	global_load_dwordx4 v[54:57], v111, s[8:9] offset:2672
	global_load_dwordx4 v[58:61], v111, s[8:9] offset:3184
	global_load_dwordx4 v[62:65], v111, s[8:9] offset:3696
	global_load_dwordx4 v[124:127], v123, s[46:47] offset:624
	global_load_dwordx4 v[128:131], v123, s[46:47] offset:1136
	global_load_dwordx4 v[132:135], v123, s[46:47] offset:1648
	global_load_dwordx4 v[136:139], v123, s[46:47] offset:2160
	global_load_dwordx4 v[140:143], v123, s[46:47] offset:2672
	s_waitcnt vmcnt(15)
	v_fma_f32 v123, v22, v118, v18
	v_fma_f32 v20, v24, v118, v20
	s_waitcnt vmcnt(14)
	v_mov_b32_e32 v144, v26
	s_waitcnt vmcnt(13)
	v_mov_b32_e32 v145, v30
	v_fma_f32 v23, v23, v118, v19
	v_mov_b32_e32 v30, v27
	v_mov_b32_e32 v18, v28
	v_mov_b32_e32 v19, v32
	v_pk_mul_f32 v[26:27], v[144:145], v[72:73]
	s_waitcnt vmcnt(12)
	v_mov_b32_e32 v146, v34
	s_waitcnt vmcnt(11)
	v_mov_b32_e32 v147, v38
	s_waitcnt vmcnt(4)
	v_fmac_f32_e32 v123, v124, v117
	v_fmac_f32_e32 v20, v126, v117
	s_waitcnt vmcnt(3)
	v_fmac_f32_e32 v123, v128, v122
	v_fmac_f32_e32 v20, v130, v122
	s_waitcnt vmcnt(2)
	v_fmac_f32_e32 v123, v132, v121
	v_fmac_f32_e32 v20, v134, v121
	s_waitcnt vmcnt(1)
	v_fmac_f32_e32 v123, v136, v120
	v_fmac_f32_e32 v20, v138, v120
	s_waitcnt vmcnt(0)
	v_fmac_f32_e32 v123, v140, v119
	v_fmac_f32_e32 v23, v125, v117
	v_pk_mul_f32 v[18:19], v[18:19], v[72:73]
	v_fmac_f32_e32 v20, v142, v119
	v_add_f32_e32 v24, v123, v26
	v_mov_b32_e32 v38, v35
	v_pk_mul_f32 v[34:35], v[146:147], v[74:75]
	v_fmac_f32_e32 v23, v129, v122
	v_add_f32_e32 v18, v18, v20
	v_add_f32_e32 v20, v24, v27
	v_mov_b32_e32 v148, v42
	v_mov_b32_e32 v149, v46
	v_fmac_f32_e32 v23, v133, v121
	v_add_f32_e32 v20, v20, v34
	v_mov_b32_e32 v46, v43
	v_pk_mul_f32 v[42:43], v[148:149], v[78:79]
	v_fmac_f32_e32 v23, v137, v120
	v_add_f32_e32 v20, v20, v35
	v_mov_b32_e32 v150, v50
	v_mov_b32_e32 v151, v54
	v_pk_mul_f32 v[30:31], v[30:31], v[72:73]
	v_fmac_f32_e32 v23, v141, v119
	v_add_f32_e32 v20, v20, v42
	v_mov_b32_e32 v54, v51
	v_pk_mul_f32 v[50:51], v[150:151], v[80:81]
	v_add_f32_e32 v23, v30, v23
	v_add_f32_e32 v20, v20, v43
	v_mov_b32_e32 v152, v58
	v_mov_b32_e32 v153, v62
	v_pk_mul_f32 v[38:39], v[38:39], v[74:75]
	v_add_f32_e32 v23, v31, v23
	v_add_f32_e32 v20, v20, v50
	v_mov_b32_e32 v62, v59
	v_pk_mul_f32 v[58:59], v[152:153], v[82:83]
	v_add_f32_e32 v23, v38, v23
	v_add_f32_e32 v20, v20, v51
	v_pk_mul_f32 v[46:47], v[46:47], v[78:79]
	v_add_f32_e32 v23, v39, v23
	v_add_f32_e32 v20, v20, v58
	v_add_f32_e32 v23, v46, v23
	v_add_f32_e32 v20, v20, v59
	v_pk_mul_f32 v[54:55], v[54:55], v[80:81]
	v_add_f32_e32 v23, v47, v23
	v_mul_f32_e64 v24, |v20|, s25
	v_add_f32_e32 v23, v54, v23
	v_exp_f32_e32 v24, v24
	v_pk_mul_f32 v[62:63], v[62:63], v[82:83]
	v_add_f32_e32 v23, v55, v23
	v_add_f32_e32 v23, v62, v23
	v_add_f32_e32 v23, v63, v23
	v_mul_f32_e64 v26, |v23|, s25
	v_add_f32_e32 v27, v19, v18
	v_add_f32_e32 v19, 1.0, v24
	v_exp_f32_e32 v26, v26
	v_cmp_gt_f32_e32 vcc, s26, v19
	v_min_f32_e32 v18, 0, v20
	v_mov_b32_e32 v22, v36
	v_cndmask_b32_e64 v24, 0, 32, vcc
	v_ldexp_f32 v19, v19, v24
	v_log_f32_e32 v24, v19
	v_add_f32_e32 v20, 1.0, v26
	v_cmp_gt_f32_e64 s[0:1], s26, v20
	v_min_f32_e32 v19, 0, v23
	v_cndmask_b32_e32 v23, 0, v112, vcc
	v_cndmask_b32_e64 v26, 0, 32, s[0:1]
	v_ldexp_f32 v20, v20, v26
	v_mul_f32_e32 v26, 0x3f317217, v24
	v_fma_f32 v26, v24, s27, -v26
	v_fmac_f32_e32 v26, 0x3377d1cf, v24
	v_fmac_f32_e32 v26, 0x3f317217, v24
	v_cmp_lt_f32_e64 vcc, |v24|, s28
	v_log_f32_e32 v20, v20
	v_fmac_f32_e32 v21, v25, v118
	v_cndmask_b32_e32 v24, v24, v26, vcc
	v_sub_f32_e32 v26, v24, v23
	v_mov_b32_e32 v23, v40
	v_pk_mul_f32 v[22:23], v[22:23], v[74:75]
	v_mul_f32_e32 v28, 0x3f317217, v20
	v_add_f32_e32 v22, v22, v27
	v_add_f32_e32 v24, v23, v22
	v_mov_b32_e32 v22, v44
	v_mov_b32_e32 v23, v48
	v_pk_mul_f32 v[22:23], v[22:23], v[78:79]
	v_fma_f32 v28, v20, s27, -v28
	v_add_f32_e32 v22, v22, v24
	v_add_f32_e32 v24, v23, v22
	v_mov_b32_e32 v22, v52
	v_mov_b32_e32 v23, v56
	v_pk_mul_f32 v[22:23], v[22:23], v[80:81]
	v_fmac_f32_e32 v28, 0x3377d1cf, v20
	v_add_f32_e32 v22, v22, v24
	v_add_f32_e32 v24, v23, v22
	v_mov_b32_e32 v22, v60
	v_mov_b32_e32 v23, v64
	v_pk_mul_f32 v[22:23], v[22:23], v[82:83]
	v_fmac_f32_e32 v28, 0x3f317217, v20
	v_add_f32_e32 v22, v22, v24
	v_add_f32_e32 v22, v23, v22
	v_mul_f32_e64 v23, |v22|, s25
	v_exp_f32_e32 v23, v23
	v_cmp_lt_f32_e64 vcc, |v20|, s28
	v_cndmask_b32_e64 v24, 0, v112, s[0:1]
	v_fmac_f32_e32 v21, v127, v117
	v_cndmask_b32_e32 v20, v20, v28, vcc
	v_sub_f32_e32 v27, v20, v24
	v_add_f32_e32 v20, 1.0, v23
	v_cmp_gt_f32_e32 vcc, s26, v20
	v_fmac_f32_e32 v21, v131, v122
	v_fmac_f32_e32 v21, v135, v121
	v_cndmask_b32_e64 v23, 0, 32, vcc
	v_ldexp_f32 v20, v20, v23
	v_log_f32_e32 v24, v20
	v_min_f32_e32 v20, 0, v22
	v_fmac_f32_e32 v21, v139, v120
	v_mov_b32_e32 v32, v29
	v_mul_f32_e32 v22, 0x3f317217, v24
	v_pk_add_f32 v[18:19], v[18:19], v[26:27] neg_lo:[0,1] neg_hi:[0,1]
	v_fma_f32 v26, v24, s27, -v22
	v_fmac_f32_e32 v21, v143, v119
	v_pk_mul_f32 v[22:23], v[32:33], v[72:73]
	v_mov_b32_e32 v40, v37
	v_add_f32_e32 v21, v22, v21
	v_add_f32_e32 v21, v23, v21
	v_pk_mul_f32 v[22:23], v[40:41], v[74:75]
	v_mov_b32_e32 v48, v45
	v_add_f32_e32 v21, v22, v21
	v_add_f32_e32 v21, v23, v21
	v_pk_mul_f32 v[22:23], v[48:49], v[78:79]
	v_mov_b32_e32 v56, v53
	v_add_f32_e32 v21, v22, v21
	v_add_f32_e32 v21, v23, v21
	v_pk_mul_f32 v[22:23], v[56:57], v[80:81]
	v_mov_b32_e32 v64, v61
	v_add_f32_e32 v21, v22, v21
	v_add_f32_e32 v21, v23, v21
	v_pk_mul_f32 v[22:23], v[64:65], v[82:83]
	v_fmac_f32_e32 v26, 0x3377d1cf, v24
	v_add_f32_e32 v21, v22, v21
	v_add_f32_e32 v21, v23, v21
	v_mul_f32_e64 v22, |v21|, s25
	v_exp_f32_e32 v22, v22
	v_fmac_f32_e32 v26, 0x3f317217, v24
	v_cmp_lt_f32_e64 s[0:1], |v24|, s28
	v_min_f32_e32 v21, 0, v21
	v_add_f32_e32 v22, 1.0, v22
	v_cndmask_b32_e64 v23, v24, v26, s[0:1]
	v_cmp_gt_f32_e64 s[0:1], s26, v22
	v_pk_mul_f32 v[18:19], v[18:19], s[4:5] op_sel_hi:[1,0]
	s_nop 0
	v_cndmask_b32_e64 v24, 0, 32, s[0:1]
	v_ldexp_f32 v22, v22, v24
	v_log_f32_e32 v24, v22
	v_cndmask_b32_e32 v22, 0, v112, vcc
	v_sub_f32_e32 v22, v23, v22
	v_mul_f32_e32 v23, 0x3f317217, v24
	v_fma_f32 v23, v24, s27, -v23
	v_fmac_f32_e32 v23, 0x3377d1cf, v24
	v_fmac_f32_e32 v23, 0x3f317217, v24
	v_cmp_lt_f32_e64 vcc, |v24|, s28
	s_nop 1
	v_cndmask_b32_e32 v23, v24, v23, vcc
	v_cndmask_b32_e64 v24, 0, v112, s[0:1]
	v_sub_f32_e32 v23, v23, v24
	v_pk_add_f32 v[20:21], v[20:21], v[22:23] neg_lo:[0,1] neg_hi:[0,1]
	s_nop 0
	v_pk_mul_f32 v[20:21], v[20:21], s[4:5] op_sel_hi:[1,0]
	v_cmp_ne_u32_e32 vcc, 63, v113
	v_cmp_gt_u32_e64 s[0:1], 62, v113
	s_nop 0
	v_addc_co_u32_e32 v22, vcc, 0, v110, vcc
	v_lshlrev_b32_e32 v22, 2, v22
	ds_bpermute_b32 v23, v22, v70
	ds_bpermute_b32 v24, v22, v71
	ds_bpermute_b32 v25, v22, v76
	ds_bpermute_b32 v26, v22, v77
	ds_bpermute_b32 v27, v22, v84
	ds_bpermute_b32 v28, v22, v85
	ds_bpermute_b32 v29, v22, v86
	ds_bpermute_b32 v30, v22, v87
	ds_bpermute_b32 v31, v22, v88
	ds_bpermute_b32 v32, v22, v89
	ds_bpermute_b32 v33, v22, v90
	ds_bpermute_b32 v34, v22, v91
	ds_bpermute_b32 v35, v22, v92
	ds_bpermute_b32 v36, v22, v93
	ds_bpermute_b32 v37, v22, v94
	ds_bpermute_b32 v38, v22, v95
	ds_bpermute_b32 v39, v22, v96
	ds_bpermute_b32 v40, v22, v97
	ds_bpermute_b32 v41, v22, v98
	ds_bpermute_b32 v42, v22, v99
	ds_bpermute_b32 v43, v22, v100
	ds_bpermute_b32 v44, v22, v101
	ds_bpermute_b32 v45, v22, v102
	ds_bpermute_b32 v46, v22, v103
	ds_bpermute_b32 v47, v22, v104
	ds_bpermute_b32 v48, v22, v105
	ds_bpermute_b32 v49, v22, v106
	ds_bpermute_b32 v50, v22, v107
	ds_bpermute_b32 v51, v22, v18
	ds_bpermute_b32 v52, v22, v19
	ds_bpermute_b32 v53, v22, v20
	ds_bpermute_b32 v22, v22, v21
	v_cmp_gt_i32_e32 vcc, 63, v68
	s_waitcnt lgkmcnt(6)
	v_add_f32_e32 v48, v105, v48
	v_add_f32_e32 v23, v70, v23
	v_add_f32_e32 v24, v71, v24
	s_waitcnt lgkmcnt(0)
	v_add_f32_e32 v22, v21, v22
	v_add_f32_e32 v25, v76, v25
	v_add_f32_e32 v26, v77, v26
	v_add_f32_e32 v27, v84, v27
	v_add_f32_e32 v28, v85, v28
	v_add_f32_e32 v29, v86, v29
	v_add_f32_e32 v30, v87, v30
	v_add_f32_e32 v31, v88, v31
	v_add_f32_e32 v32, v89, v32
	v_add_f32_e32 v33, v90, v33
	v_add_f32_e32 v34, v91, v34
	v_add_f32_e32 v35, v92, v35
	v_add_f32_e32 v36, v93, v36
	v_add_f32_e32 v37, v94, v37
	v_add_f32_e32 v38, v95, v38
	v_add_f32_e32 v39, v96, v39
	v_add_f32_e32 v40, v97, v40
	v_add_f32_e32 v41, v98, v41
	v_add_f32_e32 v42, v99, v42
	v_add_f32_e32 v43, v100, v43
	v_add_f32_e32 v44, v101, v44
	v_add_f32_e32 v45, v102, v45
	v_add_f32_e32 v46, v103, v46
	v_add_f32_e32 v47, v104, v47
	v_add_f32_e32 v49, v106, v49
	v_add_f32_e32 v50, v107, v50
	v_add_f32_e32 v51, v18, v51
	v_add_f32_e32 v52, v19, v52
	v_add_f32_e32 v53, v20, v53
	v_cndmask_b32_e32 v21, v21, v22, vcc
	v_cndmask_b32_e32 v22, v105, v48, vcc
	v_cndmask_b32_e64 v48, 0, 2, s[0:1]
	v_cndmask_b32_e32 v23, v70, v23, vcc
	v_cndmask_b32_e32 v25, v76, v25, vcc
	v_cndmask_b32_e32 v26, v77, v26, vcc
	v_cndmask_b32_e32 v28, v85, v28, vcc
	v_cndmask_b32_e32 v29, v86, v29, vcc
	v_cndmask_b32_e32 v31, v88, v31, vcc
	v_cndmask_b32_e32 v32, v89, v32, vcc
	v_cndmask_b32_e32 v34, v91, v34, vcc
	v_cndmask_b32_e32 v35, v92, v35, vcc
	v_cndmask_b32_e32 v37, v94, v37, vcc
	v_cndmask_b32_e32 v38, v95, v38, vcc
	v_cndmask_b32_e32 v40, v97, v40, vcc
	v_cndmask_b32_e32 v41, v98, v41, vcc
	v_cndmask_b32_e32 v43, v100, v43, vcc
	v_cndmask_b32_e32 v44, v101, v44, vcc
	v_cndmask_b32_e32 v46, v103, v46, vcc
	v_cndmask_b32_e32 v47, v104, v47, vcc
	v_cndmask_b32_e32 v49, v106, v49, vcc
	v_cndmask_b32_e32 v50, v107, v50, vcc
	v_cndmask_b32_e32 v52, v19, v52, vcc
	v_cndmask_b32_e32 v53, v20, v53, vcc
	v_cndmask_b32_e32 v18, v18, v51, vcc
	v_cndmask_b32_e32 v45, v102, v45, vcc
	v_cndmask_b32_e32 v42, v99, v42, vcc
	v_cndmask_b32_e32 v39, v96, v39, vcc
	v_cndmask_b32_e32 v36, v93, v36, vcc
	v_cndmask_b32_e32 v33, v90, v33, vcc
	v_add_lshl_u32 v48, v48, v110, 2
	v_cndmask_b32_e32 v30, v87, v30, vcc
	v_cndmask_b32_e32 v27, v84, v27, vcc
	v_cndmask_b32_e32 v24, v71, v24, vcc
	v_cndmask_b32_e32 v54, v70, v23, vcc
	v_cndmask_b32_e32 v55, v76, v25, vcc
	v_cndmask_b32_e32 v57, v85, v28, vcc
	v_cndmask_b32_e32 v58, v86, v29, vcc
	v_cndmask_b32_e32 v59, v88, v31, vcc
	v_cndmask_b32_e32 v60, v89, v32, vcc
	v_cndmask_b32_e32 v61, v91, v34, vcc
	v_cndmask_b32_e32 v62, v92, v35, vcc
	v_cndmask_b32_e32 v63, v94, v37, vcc
	v_cndmask_b32_e32 v64, v95, v38, vcc
	v_cndmask_b32_e32 v65, v97, v40, vcc
	v_cndmask_b32_e32 v70, v98, v41, vcc
	v_cndmask_b32_e32 v72, v100, v43, vcc
	v_cndmask_b32_e32 v73, v101, v44, vcc
	v_cndmask_b32_e32 v74, v103, v46, vcc
	v_cndmask_b32_e32 v75, v104, v47, vcc
	v_cndmask_b32_e32 v76, v106, v49, vcc
	ds_bpermute_b32 v51, v48, v23
	ds_bpermute_b32 v71, v48, v24
	ds_bpermute_b32 v78, v48, v25
	ds_bpermute_b32 v79, v48, v26
	ds_bpermute_b32 v80, v48, v27
	ds_bpermute_b32 v81, v48, v28
	ds_bpermute_b32 v82, v48, v29
	ds_bpermute_b32 v83, v48, v30
	ds_bpermute_b32 v84, v48, v31
	ds_bpermute_b32 v85, v48, v32
	ds_bpermute_b32 v86, v48, v33
	ds_bpermute_b32 v87, v48, v34
	ds_bpermute_b32 v88, v48, v35
	ds_bpermute_b32 v89, v48, v36
	ds_bpermute_b32 v90, v48, v37
	ds_bpermute_b32 v91, v48, v38
	ds_bpermute_b32 v92, v48, v39
	ds_bpermute_b32 v93, v48, v40
	ds_bpermute_b32 v94, v48, v41
	ds_bpermute_b32 v95, v48, v42
	ds_bpermute_b32 v96, v48, v43
	ds_bpermute_b32 v97, v48, v44
	ds_bpermute_b32 v98, v48, v45
	ds_bpermute_b32 v99, v48, v46
	ds_bpermute_b32 v100, v48, v47
	ds_bpermute_b32 v101, v48, v22
	ds_bpermute_b32 v102, v48, v49
	ds_bpermute_b32 v103, v48, v50
	ds_bpermute_b32 v104, v48, v18
	ds_bpermute_b32 v105, v48, v52
	ds_bpermute_b32 v106, v48, v53
	ds_bpermute_b32 v48, v48, v21
	v_cndmask_b32_e32 v56, v77, v26, vcc
	v_cndmask_b32_e32 v77, v107, v50, vcc
	v_cndmask_b32_e32 v19, v19, v52, vcc
	v_cndmask_b32_e32 v20, v20, v53, vcc
	v_cmp_gt_i32_e32 vcc, 62, v68
	s_waitcnt lgkmcnt(0)
	v_add_f32_e32 v48, v21, v48
	v_cmp_gt_u32_e64 s[0:1], 60, v113
	v_add_f32_e32 v51, v23, v51
	v_add_f32_e32 v71, v24, v71
	v_add_f32_e32 v78, v25, v78
	v_add_f32_e32 v79, v26, v79
	v_add_f32_e32 v80, v27, v80
	v_add_f32_e32 v81, v28, v81
	v_add_f32_e32 v82, v29, v82
	v_add_f32_e32 v83, v30, v83
	v_add_f32_e32 v84, v31, v84
	v_add_f32_e32 v85, v32, v85
	v_add_f32_e32 v86, v33, v86
	v_add_f32_e32 v87, v34, v87
	v_add_f32_e32 v88, v35, v88
	v_add_f32_e32 v89, v36, v89
	v_add_f32_e32 v90, v37, v90
	v_add_f32_e32 v91, v38, v91
	v_add_f32_e32 v92, v39, v92
	v_add_f32_e32 v93, v40, v93
	v_add_f32_e32 v94, v41, v94
	v_add_f32_e32 v95, v42, v95
	v_add_f32_e32 v96, v43, v96
	v_add_f32_e32 v97, v44, v97
	v_add_f32_e32 v98, v45, v98
	v_add_f32_e32 v99, v46, v99
	v_add_f32_e32 v100, v47, v100
	v_add_f32_e32 v101, v22, v101
	v_add_f32_e32 v102, v49, v102
	v_add_f32_e32 v103, v50, v103
	v_add_f32_e32 v104, v18, v104
	v_add_f32_e32 v105, v52, v105
	v_add_f32_e32 v106, v53, v106
	v_cndmask_b32_e32 v21, v21, v48, vcc
	v_cndmask_b32_e64 v48, 0, 4, s[0:1]
	v_cndmask_b32_e32 v23, v23, v51, vcc
	v_cndmask_b32_e32 v25, v25, v78, vcc
	v_cndmask_b32_e32 v26, v26, v79, vcc
	v_cndmask_b32_e32 v28, v28, v81, vcc
	v_cndmask_b32_e32 v29, v29, v82, vcc
	v_cndmask_b32_e32 v31, v31, v84, vcc
	v_cndmask_b32_e32 v32, v32, v85, vcc
	v_cndmask_b32_e32 v34, v34, v87, vcc
	v_cndmask_b32_e32 v35, v35, v88, vcc
	v_cndmask_b32_e32 v37, v37, v90, vcc
	v_cndmask_b32_e32 v38, v38, v91, vcc
	v_cndmask_b32_e32 v40, v40, v93, vcc
	v_cndmask_b32_e32 v41, v41, v94, vcc
	v_cndmask_b32_e32 v43, v43, v96, vcc
	v_cndmask_b32_e32 v44, v44, v97, vcc
	v_cndmask_b32_e32 v46, v46, v99, vcc
	v_cndmask_b32_e32 v47, v47, v100, vcc
	v_cndmask_b32_e32 v49, v49, v102, vcc
	v_cndmask_b32_e32 v50, v50, v103, vcc
	v_cndmask_b32_e32 v52, v52, v105, vcc
	v_cndmask_b32_e32 v53, v53, v106, vcc
	v_cndmask_b32_e32 v18, v18, v104, vcc
	v_cndmask_b32_e32 v22, v22, v101, vcc
	v_cndmask_b32_e32 v45, v45, v98, vcc
	v_cndmask_b32_e32 v42, v42, v95, vcc
	v_cndmask_b32_e32 v39, v39, v92, vcc
	v_cndmask_b32_e32 v36, v36, v89, vcc
	v_cndmask_b32_e32 v33, v33, v86, vcc
	v_add_lshl_u32 v48, v48, v110, 2
	v_cndmask_b32_e32 v30, v30, v83, vcc
	v_cndmask_b32_e32 v27, v27, v80, vcc
	v_cndmask_b32_e32 v24, v24, v71, vcc
	v_cndmask_b32_e32 v20, v20, v106, vcc
	v_cndmask_b32_e32 v19, v19, v105, vcc
	v_cndmask_b32_e32 v77, v77, v103, vcc
	v_cndmask_b32_e32 v76, v76, v102, vcc
	v_cndmask_b32_e32 v75, v75, v100, vcc
	v_cndmask_b32_e32 v74, v74, v99, vcc
	v_cndmask_b32_e32 v73, v73, v97, vcc
	v_cndmask_b32_e32 v72, v72, v96, vcc
	v_cndmask_b32_e32 v70, v70, v94, vcc
	v_cndmask_b32_e32 v65, v65, v93, vcc
	v_cndmask_b32_e32 v64, v64, v91, vcc
	v_cndmask_b32_e32 v63, v63, v90, vcc
	v_cndmask_b32_e32 v62, v62, v88, vcc
	v_cndmask_b32_e32 v61, v61, v87, vcc
	v_cndmask_b32_e32 v60, v60, v85, vcc
	v_cndmask_b32_e32 v59, v59, v84, vcc
	v_cndmask_b32_e32 v58, v58, v82, vcc
	v_cndmask_b32_e32 v57, v57, v81, vcc
	v_cndmask_b32_e32 v56, v56, v79, vcc
	v_cndmask_b32_e32 v55, v55, v78, vcc
	v_cndmask_b32_e32 v51, v54, v51, vcc
	ds_bpermute_b32 v54, v48, v23
	ds_bpermute_b32 v71, v48, v24
	ds_bpermute_b32 v78, v48, v25
	ds_bpermute_b32 v79, v48, v26
	ds_bpermute_b32 v80, v48, v27
	ds_bpermute_b32 v81, v48, v28
	ds_bpermute_b32 v82, v48, v29
	ds_bpermute_b32 v83, v48, v30
	ds_bpermute_b32 v84, v48, v31
	ds_bpermute_b32 v85, v48, v32
	ds_bpermute_b32 v86, v48, v33
	ds_bpermute_b32 v87, v48, v34
	ds_bpermute_b32 v88, v48, v35
	ds_bpermute_b32 v89, v48, v36
	ds_bpermute_b32 v90, v48, v37
	ds_bpermute_b32 v91, v48, v38
	ds_bpermute_b32 v92, v48, v39
	ds_bpermute_b32 v93, v48, v40
	ds_bpermute_b32 v94, v48, v41
	ds_bpermute_b32 v95, v48, v42
	ds_bpermute_b32 v96, v48, v43
	ds_bpermute_b32 v97, v48, v44
	ds_bpermute_b32 v98, v48, v45
	ds_bpermute_b32 v99, v48, v46
	ds_bpermute_b32 v100, v48, v47
	ds_bpermute_b32 v101, v48, v22
	ds_bpermute_b32 v102, v48, v49
	ds_bpermute_b32 v103, v48, v50
	ds_bpermute_b32 v104, v48, v18
	ds_bpermute_b32 v105, v48, v52
	ds_bpermute_b32 v106, v48, v53
	ds_bpermute_b32 v48, v48, v21
	v_cmp_gt_i32_e32 vcc, 60, v68
	v_cmp_gt_u32_e64 s[0:1], 56, v113
	s_waitcnt lgkmcnt(14)
	v_add_f32_e32 v54, v23, v54
	v_add_f32_e32 v71, v24, v71
	s_waitcnt lgkmcnt(0)
	v_add_f32_e32 v48, v21, v48
	v_cndmask_b32_e32 v21, v21, v48, vcc
	v_cndmask_b32_e64 v48, 0, 8, s[0:1]
	v_cndmask_b32_e32 v23, v23, v54, vcc
	v_add_f32_e32 v78, v25, v78
	v_add_f32_e32 v79, v26, v79
	v_add_f32_e32 v81, v28, v81
	v_add_f32_e32 v82, v29, v82
	v_add_f32_e32 v84, v31, v84
	v_add_f32_e32 v85, v32, v85
	v_add_f32_e32 v87, v34, v87
	v_add_f32_e32 v88, v35, v88
	v_add_f32_e32 v90, v37, v90
	v_add_f32_e32 v91, v38, v91
	v_add_f32_e32 v93, v40, v93
	v_add_f32_e32 v94, v41, v94
	v_add_f32_e32 v96, v43, v96
	v_add_f32_e32 v97, v44, v97
	v_add_f32_e32 v99, v46, v99
	v_add_f32_e32 v100, v47, v100
	v_add_f32_e32 v102, v49, v102
	v_add_f32_e32 v103, v50, v103
	v_cndmask_b32_e32 v24, v24, v71, vcc
	v_add_lshl_u32 v48, v48, v110, 2
	v_cndmask_b32_e32 v51, v51, v54, vcc
	v_cndmask_b32_e32 v54, v55, v78, vcc
	v_cndmask_b32_e32 v55, v56, v79, vcc
	v_cndmask_b32_e32 v56, v57, v81, vcc
	v_cndmask_b32_e32 v57, v58, v82, vcc
	v_cndmask_b32_e32 v58, v59, v84, vcc
	v_cndmask_b32_e32 v59, v60, v85, vcc
	v_cndmask_b32_e32 v60, v61, v87, vcc
	v_cndmask_b32_e32 v61, v62, v88, vcc
	v_cndmask_b32_e32 v62, v63, v90, vcc
	v_cndmask_b32_e32 v63, v64, v91, vcc
	v_cndmask_b32_e32 v64, v65, v93, vcc
	v_cndmask_b32_e32 v65, v70, v94, vcc
	v_cndmask_b32_e32 v70, v72, v96, vcc
	v_cndmask_b32_e32 v72, v73, v97, vcc
	v_cndmask_b32_e32 v73, v74, v99, vcc
	v_cndmask_b32_e32 v74, v75, v100, vcc
	v_cndmask_b32_e32 v75, v76, v102, vcc
	v_cndmask_b32_e32 v76, v77, v103, vcc
	ds_bpermute_b32 v71, v48, v23
	ds_bpermute_b32 v77, v48, v24
	v_add_f32_e32 v80, v27, v80
	v_cndmask_b32_e32 v25, v25, v78, vcc
	v_cndmask_b32_e32 v28, v28, v81, vcc
	v_cndmask_b32_e32 v29, v29, v82, vcc
	v_cndmask_b32_e32 v27, v27, v80, vcc
	v_cndmask_b32_e32 v26, v26, v79, vcc
	s_waitcnt lgkmcnt(1)
	v_add_f32_e32 v23, v23, v71
	s_waitcnt lgkmcnt(0)
	v_add_f32_e32 v71, v24, v77
	ds_bpermute_b32 v77, v48, v25
	ds_bpermute_b32 v79, v48, v27
	ds_bpermute_b32 v80, v48, v28
	ds_bpermute_b32 v81, v48, v29
	v_add_f32_e32 v86, v33, v86
	v_cndmask_b32_e32 v31, v31, v84, vcc
	v_cndmask_b32_e32 v32, v32, v85, vcc
	v_cndmask_b32_e32 v34, v34, v87, vcc
	v_cndmask_b32_e32 v33, v33, v86, vcc
	s_waitcnt lgkmcnt(3)
	v_add_f32_e32 v25, v25, v77
	s_waitcnt lgkmcnt(2)
	v_add_f32_e32 v77, v27, v79
	s_waitcnt lgkmcnt(1)
	v_add_f32_e32 v28, v28, v80
	s_waitcnt lgkmcnt(0)
	v_add_f32_e32 v29, v29, v81
	ds_bpermute_b32 v79, v48, v31
	ds_bpermute_b32 v80, v48, v32
	ds_bpermute_b32 v81, v48, v33
	ds_bpermute_b32 v82, v48, v34
	v_add_f32_e32 v89, v36, v89
	v_add_f32_e32 v92, v39, v92
	v_cndmask_b32_e32 v35, v35, v88, vcc
	v_cndmask_b32_e32 v37, v37, v90, vcc
	v_cndmask_b32_e32 v39, v39, v92, vcc
	v_cndmask_b32_e32 v36, v36, v89, vcc
	s_waitcnt lgkmcnt(3)
	v_add_f32_e32 v31, v31, v79
	s_waitcnt lgkmcnt(2)
	v_add_f32_e32 v32, v32, v80
	s_waitcnt lgkmcnt(1)
	v_add_f32_e32 v79, v33, v81
	s_waitcnt lgkmcnt(0)
	v_add_f32_e32 v34, v34, v82
	ds_bpermute_b32 v80, v48, v35
	ds_bpermute_b32 v81, v48, v36
	ds_bpermute_b32 v82, v48, v37
	ds_bpermute_b32 v84, v48, v39
	v_add_f32_e32 v95, v42, v95
	v_add_f32_e32 v83, v30, v83
	v_cndmask_b32_e32 v38, v38, v91, vcc
	v_cndmask_b32_e32 v40, v40, v93, vcc
	v_cndmask_b32_e32 v43, v43, v96, vcc
	v_cndmask_b32_e32 v44, v44, v97, vcc
	v_cndmask_b32_e32 v42, v42, v95, vcc
	v_cndmask_b32_e32 v30, v30, v83, vcc
	ds_bpermute_b32 v83, v48, v38
	s_waitcnt lgkmcnt(4)
	v_add_f32_e32 v35, v35, v80
	s_waitcnt lgkmcnt(3)
	v_add_f32_e32 v80, v36, v81
	s_waitcnt lgkmcnt(2)
	v_add_f32_e32 v37, v37, v82
	s_waitcnt lgkmcnt(1)
	v_add_f32_e32 v81, v39, v84
	ds_bpermute_b32 v82, v48, v40
	ds_bpermute_b32 v84, v48, v42
	ds_bpermute_b32 v85, v48, v43
	ds_bpermute_b32 v86, v48, v44
	v_add_f32_e32 v101, v22, v101
	v_cndmask_b32_e32 v41, v41, v94, vcc
	v_cndmask_b32_e32 v46, v46, v99, vcc
	v_cndmask_b32_e32 v47, v47, v100, vcc
	v_cndmask_b32_e32 v49, v49, v102, vcc
	v_cndmask_b32_e32 v22, v22, v101, vcc
	ds_bpermute_b32 v78, v48, v26
	s_waitcnt lgkmcnt(5)
	v_add_f32_e32 v38, v38, v83
	ds_bpermute_b32 v83, v48, v41
	s_waitcnt lgkmcnt(5)
	v_add_f32_e32 v40, v40, v82
	s_waitcnt lgkmcnt(4)
	v_add_f32_e32 v82, v42, v84
	s_waitcnt lgkmcnt(3)
	v_add_f32_e32 v43, v43, v85
	s_waitcnt lgkmcnt(2)
	v_add_f32_e32 v44, v44, v86
	ds_bpermute_b32 v84, v48, v46
	ds_bpermute_b32 v85, v48, v47
	ds_bpermute_b32 v86, v48, v22
	ds_bpermute_b32 v87, v48, v49
	v_add_f32_e32 v98, v45, v98
	v_add_f32_e32 v104, v18, v104
	v_add_f32_e32 v105, v52, v105
	v_add_f32_e32 v106, v53, v106
	v_cndmask_b32_e32 v50, v50, v103, vcc
	v_cndmask_b32_e32 v52, v52, v105, vcc
	v_cndmask_b32_e32 v53, v53, v106, vcc
	v_cndmask_b32_e32 v18, v18, v104, vcc
	v_cndmask_b32_e32 v45, v45, v98, vcc
	s_waitcnt lgkmcnt(5)
	v_add_f32_e32 v26, v26, v78
	ds_bpermute_b32 v78, v48, v30
	s_waitcnt lgkmcnt(5)
	v_add_f32_e32 v41, v41, v83
	ds_bpermute_b32 v83, v48, v45
	s_waitcnt lgkmcnt(5)
	v_add_f32_e32 v46, v46, v84
	s_waitcnt lgkmcnt(4)
	v_add_f32_e32 v47, v47, v85
	s_waitcnt lgkmcnt(3)
	v_add_f32_e32 v84, v22, v86
	s_waitcnt lgkmcnt(2)
	v_add_f32_e32 v49, v49, v87
	ds_bpermute_b32 v85, v48, v50
	ds_bpermute_b32 v86, v48, v18
	ds_bpermute_b32 v87, v48, v52
	ds_bpermute_b32 v88, v48, v53
	ds_bpermute_b32 v48, v48, v21
	v_cndmask_b32_e32 v19, v19, v105, vcc
	v_cndmask_b32_e32 v20, v20, v106, vcc
	s_waitcnt lgkmcnt(4)
	v_add_f32_e32 v50, v50, v85
	v_cmp_gt_i32_e32 vcc, 56, v68
	v_lshrrev_b32_e32 v255, 2, v115
	s_nop 0
	v_readfirstlane_b32 s101, v255
	s_nop 3
	s_waitcnt lgkmcnt(0)
	v_add_f32_e32 v48, v21, v48
	v_cmp_gt_u32_e64 s[0:1], 48, v113
	v_cndmask_b32_e32 v21, v21, v48, vcc
	v_cndmask_b32_e32 v48, v76, v50, vcc
	v_cndmask_b32_e64 v50, 0, 16, s[0:1]
	v_cndmask_b32_e32 v47, v74, v47, vcc
	v_cndmask_b32_e32 v40, v64, v40, vcc
	v_cndmask_b32_e32 v31, v58, v31, vcc
	v_cndmask_b32_e32 v23, v51, v23, vcc
	v_add_lshl_u32 v50, v50, v110, 2
	v_add_f32_e32 v52, v52, v87
	v_cndmask_b32_e32 v22, v22, v84, vcc
	v_cndmask_b32_e32 v44, v72, v44, vcc
	v_cndmask_b32_e32 v33, v33, v79, vcc
	v_cndmask_b32_e32 v32, v59, v32, vcc
	ds_bpermute_b32 v51, v50, v23
	v_cndmask_b32_e32 v24, v24, v71, vcc
	ds_bpermute_b32 v59, v50, v31
	ds_bpermute_b32 v72, v50, v40
	ds_bpermute_b32 v79, v50, v47
	v_cndmask_b32_e32 v19, v19, v52, vcc
	v_cndmask_b32_e32 v36, v36, v80, vcc
	ds_bpermute_b32 v52, v50, v24
	ds_bpermute_b32 v80, v50, v22
	v_cndmask_b32_e32 v28, v56, v28, vcc
	v_add_f32_e32 v78, v30, v78
	v_add_f32_e32 v83, v45, v83
	v_add_f32_e32 v85, v18, v86
	v_add_f32_e32 v53, v53, v88
	v_cndmask_b32_e32 v46, v73, v46, vcc
	v_cndmask_b32_e32 v43, v70, v43, vcc
	v_cndmask_b32_e32 v41, v65, v41, vcc
	v_cndmask_b32_e32 v29, v57, v29, vcc
	v_cndmask_b32_e32 v27, v27, v77, vcc
	v_cndmask_b32_e32 v26, v55, v26, vcc
	v_cndmask_b32_e32 v25, v54, v25, vcc
	ds_bpermute_b32 v56, v50, v28
	ds_bpermute_b32 v76, v50, v44
	v_cndmask_b32_e32 v20, v20, v53, vcc
	v_cndmask_b32_e32 v18, v18, v85, vcc
	v_cndmask_b32_e32 v49, v75, v49, vcc
	v_cndmask_b32_e32 v45, v45, v83, vcc
	v_cndmask_b32_e32 v42, v42, v82, vcc
	v_cndmask_b32_e32 v39, v39, v81, vcc
	v_cndmask_b32_e32 v38, v63, v38, vcc
	v_cndmask_b32_e32 v37, v62, v37, vcc
	v_cndmask_b32_e32 v35, v61, v35, vcc
	v_cndmask_b32_e32 v34, v60, v34, vcc
	v_cndmask_b32_e32 v30, v30, v78, vcc
	s_waitcnt lgkmcnt(7)
	v_add_f32_e32 v51, v23, v51
	ds_bpermute_b32 v53, v50, v25
	v_cmp_gt_i32_e32 vcc, 48, v68
	ds_bpermute_b32 v54, v50, v26
	ds_bpermute_b32 v55, v50, v27
	ds_bpermute_b32 v57, v50, v29
	ds_bpermute_b32 v60, v50, v32
	s_waitcnt lgkmcnt(11)
	v_add_f32_e32 v59, v31, v59
	ds_bpermute_b32 v73, v50, v41
	s_waitcnt lgkmcnt(11)
	v_add_f32_e32 v72, v40, v72
	ds_bpermute_b32 v75, v50, v43
	ds_bpermute_b32 v78, v50, v46
	s_waitcnt lgkmcnt(12)
	v_add_f32_e32 v79, v47, v79
	v_cndmask_b32_e32 v51, v23, v51, vcc
	s_waitcnt lgkmcnt(11)
	v_add_f32_e32 v52, v24, v52
	ds_bpermute_b32 v58, v50, v30
	ds_bpermute_b32 v61, v50, v33
	v_cndmask_b32_e32 v59, v31, v59, vcc
	v_cndmask_b32_e32 v72, v40, v72, vcc
	ds_bpermute_b32 v77, v50, v45
	v_cndmask_b32_e32 v79, v47, v79, vcc
	ds_bpermute_b32 v82, v50, v48
	s_waitcnt lgkmcnt(14)
	v_add_f32_e32 v80, v22, v80
	v_cndmask_b32_e32 v88, v23, v51, vcc
	v_cndmask_b32_e32 v93, v31, v59, vcc
	v_cndmask_b32_e32 v31, v40, v72, vcc
	v_cndmask_b32_e32 v23, v47, v79, vcc
	v_cndmask_b32_e32 v40, v22, v80, vcc
	v_cndmask_b32_e32 v47, v24, v52, vcc
	ds_bpermute_b32 v22, v114, v51
	ds_bpermute_b32 v24, v114, v47
	s_waitcnt lgkmcnt(15)
	v_add_f32_e32 v56, v28, v56
	s_waitcnt lgkmcnt(14)
	v_add_f32_e32 v76, v44, v76
	s_waitcnt lgkmcnt(13)
	v_add_f32_e32 v53, v25, v53
	s_waitcnt lgkmcnt(12)
	v_add_f32_e32 v54, v26, v54
	s_waitcnt lgkmcnt(11)
	v_add_f32_e32 v55, v27, v55
	v_cndmask_b32_e32 v56, v28, v56, vcc
	s_waitcnt lgkmcnt(10)
	v_add_f32_e32 v57, v29, v57
	ds_bpermute_b32 v62, v50, v34
	s_waitcnt lgkmcnt(10)
	v_add_f32_e32 v60, v32, v60
	ds_bpermute_b32 v63, v50, v35
	s_waitcnt lgkmcnt(10)
	v_add_f32_e32 v73, v41, v73
	s_waitcnt lgkmcnt(9)
	v_add_f32_e32 v75, v43, v75
	v_cndmask_b32_e32 v76, v44, v76, vcc
	s_waitcnt lgkmcnt(8)
	v_add_f32_e32 v78, v46, v78
	ds_bpermute_b32 v81, v50, v49
	v_cndmask_b32_e32 v53, v25, v53, vcc
	v_cndmask_b32_e32 v54, v26, v54, vcc
	v_cndmask_b32_e32 v57, v29, v57, vcc
	s_waitcnt lgkmcnt(8)
	v_add_f32_e32 v58, v30, v58
	v_cndmask_b32_e32 v60, v32, v60, vcc
	s_waitcnt lgkmcnt(7)
	v_add_f32_e32 v61, v33, v61
	v_cndmask_b32_e32 v73, v41, v73, vcc
	v_cndmask_b32_e32 v75, v43, v75, vcc
	s_waitcnt lgkmcnt(6)
	v_add_f32_e32 v77, v45, v77
	v_cndmask_b32_e32 v78, v46, v78, vcc
	s_waitcnt lgkmcnt(5)
	v_add_f32_e32 v82, v48, v82
	v_cndmask_b32_e32 v90, v28, v56, vcc
	v_cndmask_b32_e32 v28, v44, v76, vcc
	v_cndmask_b32_e32 v44, v27, v55, vcc
	ds_bpermute_b32 v64, v50, v36
	ds_bpermute_b32 v65, v50, v37
	ds_bpermute_b32 v70, v50, v38
	ds_bpermute_b32 v71, v50, v39
	ds_bpermute_b32 v74, v50, v42
	ds_bpermute_b32 v83, v50, v18
	ds_bpermute_b32 v84, v50, v19
	v_cndmask_b32_e32 v82, v48, v82, vcc
	ds_bpermute_b32 v85, v50, v20
	ds_bpermute_b32 v50, v50, v21
	v_cndmask_b32_e32 v86, v26, v54, vcc
	v_cndmask_b32_e32 v89, v29, v57, vcc
	v_cndmask_b32_e32 v92, v32, v60, vcc
	v_cndmask_b32_e32 v32, v41, v73, vcc
	v_cndmask_b32_e32 v29, v46, v78, vcc
	v_cndmask_b32_e32 v26, v43, v75, vcc
	v_cndmask_b32_e32 v41, v45, v77, vcc
	v_cndmask_b32_e32 v43, v33, v61, vcc
	v_cndmask_b32_e32 v45, v30, v58, vcc
	s_waitcnt lgkmcnt(13)
	v_add_f32_e32 v46, v51, v22
	ds_bpermute_b32 v22, v114, v53
	ds_bpermute_b32 v27, v114, v44
	ds_bpermute_b32 v30, v114, v56
	ds_bpermute_b32 v33, v114, v57
	v_cndmask_b32_e32 v87, v25, v53, vcc
	v_cndmask_b32_e32 v25, v48, v82, vcc
	s_waitcnt lgkmcnt(15)
	v_add_f32_e32 v48, v47, v24
	ds_bpermute_b32 v24, v114, v54
	s_waitcnt lgkmcnt(15)
	v_add_f32_e32 v62, v34, v62
	s_waitcnt lgkmcnt(15)
	v_add_f32_e32 v63, v35, v63
	s_waitcnt lgkmcnt(14)
	v_add_f32_e32 v81, v49, v81
	v_cndmask_b32_e32 v62, v34, v62, vcc
	v_cndmask_b32_e32 v63, v35, v63, vcc
	v_cndmask_b32_e32 v81, v49, v81, vcc
	s_waitcnt lgkmcnt(5)
	v_add_f32_e32 v50, v21, v50
	v_cndmask_b32_e32 v91, v34, v62, vcc
	v_cndmask_b32_e32 v34, v35, v63, vcc
	v_cndmask_b32_e32 v35, v49, v81, vcc
	s_waitcnt lgkmcnt(4)
	v_add_f32_e32 v49, v53, v22
	s_waitcnt lgkmcnt(3)
	v_add_f32_e32 v51, v44, v27
	s_waitcnt lgkmcnt(2)
	v_add_f32_e32 v52, v56, v30
	s_waitcnt lgkmcnt(1)
	v_add_f32_e32 v53, v57, v33
	ds_bpermute_b32 v22, v114, v45
	ds_bpermute_b32 v27, v114, v60
	ds_bpermute_b32 v30, v114, v43
	ds_bpermute_b32 v33, v114, v62
	v_cndmask_b32_e32 v21, v21, v50, vcc
	s_waitcnt lgkmcnt(4)
	v_add_f32_e32 v50, v54, v24
	ds_bpermute_b32 v24, v114, v59
	v_add_f32_e32 v65, v37, v65
	v_add_f32_e32 v70, v38, v70
	v_add_f32_e32 v71, v39, v71
	v_add_f32_e32 v64, v36, v64
	v_cndmask_b32_e32 v65, v37, v65, vcc
	v_cndmask_b32_e32 v70, v38, v70, vcc
	v_cndmask_b32_e32 v39, v39, v71, vcc
	v_cndmask_b32_e32 v36, v36, v64, vcc
	s_waitcnt lgkmcnt(4)
	v_add_f32_e32 v54, v45, v22
	s_waitcnt lgkmcnt(3)
	v_add_f32_e32 v56, v60, v27
	s_waitcnt lgkmcnt(2)
	v_add_f32_e32 v57, v43, v30
	s_waitcnt lgkmcnt(1)
	v_add_f32_e32 v58, v62, v33
	ds_bpermute_b32 v22, v114, v63
	ds_bpermute_b32 v27, v114, v65
	ds_bpermute_b32 v30, v114, v70
	ds_bpermute_b32 v33, v114, v39
	s_waitcnt lgkmcnt(4)
	v_add_f32_e32 v55, v59, v24
	ds_bpermute_b32 v24, v114, v36
	v_add_f32_e32 v74, v42, v74
	v_cndmask_b32_e32 v42, v42, v74, vcc
	s_waitcnt lgkmcnt(4)
	v_add_f32_e32 v59, v63, v22
	s_waitcnt lgkmcnt(3)
	v_add_f32_e32 v61, v65, v27
	s_waitcnt lgkmcnt(2)
	v_add_f32_e32 v62, v70, v30
	s_waitcnt lgkmcnt(1)
	v_add_f32_e32 v30, v39, v33
	ds_bpermute_b32 v22, v114, v72
	ds_bpermute_b32 v27, v114, v42
	ds_bpermute_b32 v33, v114, v75
	ds_bpermute_b32 v63, v114, v76
	s_waitcnt lgkmcnt(4)
	v_add_f32_e32 v60, v36, v24
	ds_bpermute_b32 v24, v114, v73
	v_cndmask_b32_e32 v38, v38, v70, vcc
	s_waitcnt lgkmcnt(4)
	v_add_f32_e32 v64, v72, v22
	s_waitcnt lgkmcnt(3)
	v_add_f32_e32 v70, v42, v27
	s_waitcnt lgkmcnt(2)
	v_add_f32_e32 v27, v75, v33
	s_waitcnt lgkmcnt(1)
	v_add_f32_e32 v33, v76, v63
	ds_bpermute_b32 v22, v114, v41
	ds_bpermute_b32 v63, v114, v79
	ds_bpermute_b32 v72, v114, v81
	v_cndmask_b32_e32 v37, v37, v65, vcc
	s_waitcnt lgkmcnt(3)
	v_add_f32_e32 v65, v73, v24
	ds_bpermute_b32 v24, v114, v78
	ds_bpermute_b32 v71, v114, v40
	v_add_f32_e32 v83, v18, v83
	v_add_f32_e32 v84, v19, v84
	v_add_f32_e32 v85, v20, v85
	s_lshl_b32 s0, s37, 3
	v_cndmask_b32_e32 v84, v19, v84, vcc
	v_cndmask_b32_e32 v85, v20, v85, vcc
	v_cndmask_b32_e32 v18, v18, v83, vcc
	s_or_b32 s0, s36, s0
	v_cndmask_b32_e32 v20, v20, v85, vcc
	v_cndmask_b32_e32 v19, v19, v84, vcc
	s_waitcnt lgkmcnt(4)
	v_add_f32_e32 v73, v41, v22
	s_waitcnt lgkmcnt(3)
	v_add_f32_e32 v22, v79, v63
	s_waitcnt lgkmcnt(2)
	v_add_f32_e32 v63, v81, v72
	ds_bpermute_b32 v72, v114, v18
	ds_bpermute_b32 v75, v114, v84
	ds_bpermute_b32 v76, v114, v85
	ds_bpermute_b32 v77, v114, v21
	v_cmp_gt_i32_e32 vcc, 32, v68
	s_mulk_i32 s0, 0x104
	s_waitcnt lgkmcnt(5)
	v_add_f32_e32 v74, v78, v24
	s_waitcnt lgkmcnt(4)
	v_add_f32_e32 v24, v40, v71
	ds_bpermute_b32 v71, v114, v82
	v_cndmask_b32_e32 v46, v88, v46, vcc
	s_or_b32 s0, s0, s35
	v_cndmask_b32_e32 v22, v23, v22, vcc
	v_cndmask_b32_e32 v23, v40, v24, vcc
	v_cndmask_b32_e32 v40, v43, v57, vcc
	v_cndmask_b32_e32 v43, v90, v52, vcc
	s_addk_i32 s0, 0x410
	s_mov_b32 s1, s7
	v_readlane_b32 s98, v46, s101
	s_lshl_b64 s[8:9], s[0:1], 13
	s_add_u32 s8, s5, s8
	s_waitcnt lgkmcnt(4)
	v_add_f32_e32 v72, v18, v72
	s_waitcnt lgkmcnt(3)
	v_add_f32_e32 v75, v84, v75
	s_waitcnt lgkmcnt(2)
	v_add_f32_e32 v76, v85, v76
	s_waitcnt lgkmcnt(1)
	v_add_f32_e32 v77, v21, v77
	v_cndmask_b32_e32 v26, v26, v27, vcc
	v_cndmask_b32_e32 v27, v28, v33, vcc
	v_cndmask_b32_e32 v33, v42, v70, vcc
	v_cndmask_b32_e32 v42, v44, v51, vcc
	v_cndmask_b32_e32 v47, v47, v48, vcc
	v_cndmask_b32_e32 v48, v87, v49, vcc
	v_cndmask_b32_e32 v49, v86, v50, vcc
	s_addc_u32 s9, s12, s9
	v_lshlrev_b64 v[50:51], 7, v[68:69]
	s_waitcnt lgkmcnt(0)
	v_add_f32_e32 v71, v82, v71
	v_cndmask_b32_e32 v18, v18, v72, vcc
	v_cndmask_b32_e32 v19, v19, v75, vcc
	v_cndmask_b32_e32 v20, v20, v76, vcc
	v_cndmask_b32_e32 v21, v21, v77, vcc
	v_cndmask_b32_e32 v24, v35, v63, vcc
	v_cndmask_b32_e32 v34, v34, v59, vcc
	v_cndmask_b32_e32 v35, v36, v60, vcc
	v_cndmask_b32_e32 v36, v37, v61, vcc
	v_cndmask_b32_e32 v37, v38, v62, vcc
	v_lshl_add_u64 v[50:51], s[8:9], 0, v[50:51]
	v_cndmask_b32_e32 v25, v25, v71, vcc
	v_cndmask_b32_e32 v28, v41, v73, vcc
	v_cndmask_b32_e32 v29, v29, v74, vcc
	v_cndmask_b32_e32 v30, v39, v30, vcc
	v_cndmask_b32_e32 v31, v31, v64, vcc
	v_cndmask_b32_e32 v32, v32, v65, vcc
	v_cndmask_b32_e32 v38, v93, v55, vcc
	v_cndmask_b32_e32 v39, v92, v56, vcc
	v_cndmask_b32_e32 v41, v91, v58, vcc
	v_cndmask_b32_e32 v44, v89, v53, vcc
	v_cndmask_b32_e32 v45, v45, v54, vcc
	global_store_dwordx4 v[50:51], v[46:49], off
	global_store_dwordx4 v[50:51], v[42:45], off offset:16
	global_store_dwordx4 v[50:51], v[38:41], off offset:32
	global_store_dwordx4 v[50:51], v[34:37], off offset:48
	global_store_dwordx4 v[50:51], v[30:33], off offset:64
	global_store_dwordx4 v[50:51], v[26:29], off offset:80
	global_store_dwordx4 v[50:51], v[22:25], off offset:96
	v_sub_f32_e32 v52, s98, v46
	global_store_dwordx4 v[50:51], v[18:21], off offset:112
	v_readlane_b32 s98, v47, s101
	v_mul_f32_e32 v52, 0x3fb8aa3b, v52
	v_exp_f32_e32 v52, v52
	v_lshlrev_b32_e32 v51, 16, v14
	v_and_b32_e32 v14, 0xffff0000, v14
	v_sub_f32_e32 v50, s98, v47
	v_mul_f32_e32 v51, v52, v51
	v_mul_f32_e32 v50, 0x3fb8aa3b, v50
	v_bfe_u32 v52, v51, 16, 1
	v_exp_f32_e32 v50, v50
	v_add3_u32 v51, v51, v52, s30
	ds_write_b16_d16_hi v66, v51 offset:8192
	v_readlane_b32 s98, v48, s101
	v_mul_f32_e32 v14, v50, v14
	v_bfe_u32 v50, v14, 16, 1
	v_add3_u32 v14, v14, v50, s30
	ds_write_b16_d16_hi v66, v14 offset:8320
	v_sub_f32_e32 v50, s98, v48
	v_readlane_b32 s98, v49, s101
	v_mul_f32_e32 v50, 0x3fb8aa3b, v50
	v_exp_f32_e32 v50, v50
	v_lshlrev_b32_e32 v51, 16, v15
	v_and_b32_e32 v15, 0xffff0000, v15
	v_sub_f32_e32 v14, s98, v49
	v_mul_f32_e32 v50, v50, v51
	v_mul_f32_e32 v14, 0x3fb8aa3b, v14
	v_bfe_u32 v51, v50, 16, 1
	v_exp_f32_e32 v14, v14
	v_add3_u32 v50, v50, v51, s30
	ds_write_b16_d16_hi v66, v50 offset:8448
	v_readlane_b32 s98, v42, s101
	v_mul_f32_e32 v14, v14, v15
	v_bfe_u32 v15, v14, 16, 1
	v_add3_u32 v14, v14, v15, s30
	ds_write_b16_d16_hi v66, v14 offset:8576
	v_sub_f32_e32 v15, s98, v42
	v_readlane_b32 s98, v43, s101
	v_mul_f32_e32 v15, 0x3fb8aa3b, v15
	v_exp_f32_e32 v15, v15
	v_lshlrev_b32_e32 v50, 16, v16
	v_and_b32_e32 v16, 0xffff0000, v16
	v_sub_f32_e32 v14, s98, v43
	v_mul_f32_e32 v15, v15, v50
	v_mul_f32_e32 v14, 0x3fb8aa3b, v14
	v_bfe_u32 v50, v15, 16, 1
	v_exp_f32_e32 v14, v14
	v_add3_u32 v15, v15, v50, s30
	ds_write_b16_d16_hi v66, v15 offset:8704
	v_readlane_b32 s98, v44, s101
	v_mul_f32_e32 v14, v14, v16
	v_bfe_u32 v16, v14, 16, 1
	v_add3_u32 v14, v14, v16, s30
	ds_write_b16_d16_hi v66, v14 offset:8832
	v_sub_f32_e32 v15, s98, v44
	v_readlane_b32 s98, v45, s101
	v_mul_f32_e32 v15, 0x3fb8aa3b, v15
	v_exp_f32_e32 v15, v15
	v_lshlrev_b32_e32 v16, 16, v17
	s_xor_b32 s0, s0, 3
	v_sub_f32_e32 v14, s98, v45
	v_mul_f32_e32 v15, v15, v16
	v_mul_f32_e32 v14, 0x3fb8aa3b, v14
	v_bfe_u32 v16, v15, 16, 1
	v_exp_f32_e32 v14, v14
	v_add3_u32 v15, v15, v16, s30
	ds_write_b16_d16_hi v66, v15 offset:8960
	v_readlane_b32 s98, v38, s101
	v_and_b32_e32 v16, 0xffff0000, v17
	v_mul_f32_e32 v14, v14, v16
	v_bfe_u32 v16, v14, 16, 1
	v_add3_u32 v14, v14, v16, s30
	v_sub_f32_e32 v15, s98, v38
	ds_write_b16_d16_hi v66, v14 offset:9088
	v_readlane_b32 s98, v39, s101
	v_mul_f32_e32 v15, 0x3fb8aa3b, v15
	v_exp_f32_e32 v15, v15
	v_lshlrev_b32_e32 v16, 16, v10
	v_and_b32_e32 v10, 0xffff0000, v10
	v_sub_f32_e32 v14, s98, v39
	v_mul_f32_e32 v15, v15, v16
	v_mul_f32_e32 v14, 0x3fb8aa3b, v14
	v_bfe_u32 v16, v15, 16, 1
	v_exp_f32_e32 v14, v14
	v_add3_u32 v15, v15, v16, s30
	ds_write_b16_d16_hi v66, v15 offset:9216
	v_readlane_b32 s98, v40, s101
	v_mul_f32_e32 v10, v14, v10
	v_bfe_u32 v14, v10, 16, 1
	v_add3_u32 v10, v10, v14, s30
	ds_write_b16_d16_hi v66, v10 offset:9344
	v_sub_f32_e32 v14, s98, v40
	v_readlane_b32 s98, v41, s101
	v_mul_f32_e32 v14, 0x3fb8aa3b, v14
	v_exp_f32_e32 v14, v14
	v_lshlrev_b32_e32 v15, 16, v11
	v_and_b32_e32 v11, 0xffff0000, v11
	v_sub_f32_e32 v10, s98, v41
	v_mul_f32_e32 v14, v14, v15
	v_mul_f32_e32 v10, 0x3fb8aa3b, v10
	v_bfe_u32 v15, v14, 16, 1
	v_exp_f32_e32 v10, v10
	v_add3_u32 v14, v14, v15, s30
	ds_write_b16_d16_hi v66, v14 offset:9472
	v_readlane_b32 s98, v34, s101
	v_mul_f32_e32 v10, v10, v11
	v_bfe_u32 v11, v10, 16, 1
	v_add3_u32 v10, v10, v11, s30
	ds_write_b16_d16_hi v66, v10 offset:9600
	v_sub_f32_e32 v11, s98, v34
	v_readlane_b32 s98, v35, s101
	v_mul_f32_e32 v11, 0x3fb8aa3b, v11
	v_exp_f32_e32 v11, v11
	v_lshlrev_b32_e32 v14, 16, v12
	v_and_b32_e32 v12, 0xffff0000, v12
	v_sub_f32_e32 v10, s98, v35
	v_mul_f32_e32 v11, v11, v14
	v_mul_f32_e32 v10, 0x3fb8aa3b, v10
	v_bfe_u32 v14, v11, 16, 1
	v_exp_f32_e32 v10, v10
	v_add3_u32 v11, v11, v14, s30
	ds_write_b16_d16_hi v66, v11 offset:9728
	v_readlane_b32 s98, v36, s101
	v_mul_f32_e32 v10, v10, v12
	v_bfe_u32 v12, v10, 16, 1
	v_add3_u32 v10, v10, v12, s30
	ds_write_b16_d16_hi v66, v10 offset:9856
	v_sub_f32_e32 v11, s98, v36
	v_readlane_b32 s98, v37, s101
	v_mul_f32_e32 v11, 0x3fb8aa3b, v11
	v_exp_f32_e32 v11, v11
	v_lshlrev_b32_e32 v12, 16, v13
	v_cmp_eq_u32_e32 vcc, 0, v68
	v_sub_f32_e32 v10, s98, v37
	v_mul_f32_e32 v11, v11, v12
	v_mul_f32_e32 v10, 0x3fb8aa3b, v10
	v_bfe_u32 v12, v11, 16, 1
	v_exp_f32_e32 v10, v10
	v_add3_u32 v11, v11, v12, s30
	ds_write_b16_d16_hi v66, v11 offset:9984
	v_readlane_b32 s98, v30, s101
	v_and_b32_e32 v12, 0xffff0000, v13
	v_mul_f32_e32 v10, v10, v12
	v_bfe_u32 v12, v10, 16, 1
	v_add3_u32 v10, v10, v12, s30
	v_sub_f32_e32 v11, s98, v30
	ds_write_b16_d16_hi v66, v10 offset:10112
	v_readlane_b32 s98, v31, s101
	v_mul_f32_e32 v11, 0x3fb8aa3b, v11
	v_exp_f32_e32 v11, v11
	v_lshlrev_b32_e32 v12, 16, v6
	v_and_b32_e32 v6, 0xffff0000, v6
	v_sub_f32_e32 v10, s98, v31
	v_mul_f32_e32 v11, v11, v12
	v_mul_f32_e32 v10, 0x3fb8aa3b, v10
	v_bfe_u32 v12, v11, 16, 1
	v_exp_f32_e32 v10, v10
	v_add3_u32 v11, v11, v12, s30
	ds_write_b16_d16_hi v66, v11 offset:10240
	v_readlane_b32 s98, v32, s101
	v_mul_f32_e32 v6, v10, v6
	v_bfe_u32 v10, v6, 16, 1
	v_add3_u32 v6, v6, v10, s30
	ds_write_b16_d16_hi v66, v6 offset:10368
	v_sub_f32_e32 v10, s98, v32
	v_readlane_b32 s98, v33, s101
	v_mul_f32_e32 v10, 0x3fb8aa3b, v10
	v_exp_f32_e32 v10, v10
	v_lshlrev_b32_e32 v11, 16, v7
	v_and_b32_e32 v7, 0xffff0000, v7
	v_sub_f32_e32 v6, s98, v33
	v_mul_f32_e32 v10, v10, v11
	v_mul_f32_e32 v6, 0x3fb8aa3b, v6
	v_bfe_u32 v11, v10, 16, 1
	v_exp_f32_e32 v6, v6
	v_add3_u32 v10, v10, v11, s30
	ds_write_b16_d16_hi v66, v10 offset:10496
	v_readlane_b32 s98, v26, s101
	v_mul_f32_e32 v6, v6, v7
	v_bfe_u32 v7, v6, 16, 1
	v_add3_u32 v6, v6, v7, s30
	ds_write_b16_d16_hi v66, v6 offset:10624
	v_sub_f32_e32 v7, s98, v26
	v_readlane_b32 s98, v27, s101
	v_mul_f32_e32 v7, 0x3fb8aa3b, v7
	v_exp_f32_e32 v7, v7
	v_lshlrev_b32_e32 v10, 16, v8
	v_and_b32_e32 v8, 0xffff0000, v8
	v_sub_f32_e32 v6, s98, v27
	v_mul_f32_e32 v7, v7, v10
	v_mul_f32_e32 v6, 0x3fb8aa3b, v6
	v_bfe_u32 v10, v7, 16, 1
	v_exp_f32_e32 v6, v6
	v_add3_u32 v7, v7, v10, s30
	ds_write_b16_d16_hi v66, v7 offset:10752
	v_readlane_b32 s98, v28, s101
	v_mul_f32_e32 v6, v6, v8
	v_bfe_u32 v8, v6, 16, 1
	v_add3_u32 v6, v6, v8, s30
	ds_write_b16_d16_hi v66, v6 offset:10880
	v_sub_f32_e32 v7, s98, v28
	v_readlane_b32 s98, v29, s101
	v_mul_f32_e32 v7, 0x3fb8aa3b, v7
	v_exp_f32_e32 v7, v7
	v_lshlrev_b32_e32 v8, 16, v9
	v_sub_f32_e32 v6, s98, v29
	v_mul_f32_e32 v7, v7, v8
	v_mul_f32_e32 v6, 0x3fb8aa3b, v6
	v_bfe_u32 v8, v7, 16, 1
	v_exp_f32_e32 v6, v6
	v_add3_u32 v7, v7, v8, s30
	ds_write_b16_d16_hi v66, v7 offset:11008
	v_readlane_b32 s98, v22, s101
	v_and_b32_e32 v8, 0xffff0000, v9
	v_mul_f32_e32 v6, v6, v8
	v_bfe_u32 v8, v6, 16, 1
	v_add3_u32 v6, v6, v8, s30
	v_sub_f32_e32 v7, s98, v22
	ds_write_b16_d16_hi v66, v6 offset:11136
	v_readlane_b32 s98, v23, s101
	v_mul_f32_e32 v7, 0x3fb8aa3b, v7
	v_exp_f32_e32 v7, v7
	v_lshlrev_b32_e32 v8, 16, v2
	v_and_b32_e32 v2, 0xffff0000, v2
	v_sub_f32_e32 v6, s98, v23
	v_mul_f32_e32 v7, v7, v8
	v_mul_f32_e32 v6, 0x3fb8aa3b, v6
	v_bfe_u32 v8, v7, 16, 1
	v_exp_f32_e32 v6, v6
	v_add3_u32 v7, v7, v8, s30
	ds_write_b16_d16_hi v66, v7 offset:11264
	v_readlane_b32 s98, v24, s101
	v_mul_f32_e32 v2, v6, v2
	v_bfe_u32 v6, v2, 16, 1
	v_add3_u32 v2, v2, v6, s30
	ds_write_b16_d16_hi v66, v2 offset:11392
	v_sub_f32_e32 v6, s98, v24
	v_readlane_b32 s98, v25, s101
	v_mul_f32_e32 v6, 0x3fb8aa3b, v6
	v_exp_f32_e32 v6, v6
	v_lshlrev_b32_e32 v7, 16, v3
	v_and_b32_e32 v3, 0xffff0000, v3
	v_sub_f32_e32 v2, s98, v25
	v_mul_f32_e32 v6, v6, v7
	v_mul_f32_e32 v2, 0x3fb8aa3b, v2
	v_bfe_u32 v7, v6, 16, 1
	v_exp_f32_e32 v2, v2
	v_add3_u32 v6, v6, v7, s30
	ds_write_b16_d16_hi v66, v6 offset:11520
	v_readlane_b32 s98, v18, s101
	v_mul_f32_e32 v2, v2, v3
	v_bfe_u32 v3, v2, 16, 1
	v_add3_u32 v2, v2, v3, s30
	ds_write_b16_d16_hi v66, v2 offset:11648
	v_sub_f32_e32 v3, s98, v18
	v_readlane_b32 s98, v19, s101
	v_mul_f32_e32 v3, 0x3fb8aa3b, v3
	v_exp_f32_e32 v3, v3
	v_lshlrev_b32_e32 v6, 16, v4
	v_and_b32_e32 v4, 0xffff0000, v4
	v_sub_f32_e32 v2, s98, v19
	v_mul_f32_e32 v3, v3, v6
	v_mul_f32_e32 v2, 0x3fb8aa3b, v2
	v_bfe_u32 v6, v3, 16, 1
	v_exp_f32_e32 v2, v2
	v_add3_u32 v3, v3, v6, s30
	ds_write_b16_d16_hi v66, v3 offset:11776
	v_readlane_b32 s98, v20, s101
	v_mul_f32_e32 v2, v2, v4
	v_bfe_u32 v4, v2, 16, 1
	v_add3_u32 v2, v2, v4, s30
	v_readlane_b32 s99, v21, s101
	v_sub_f32_e32 v3, s98, v20
	v_mul_f32_e32 v3, 0x3fb8aa3b, v3
	v_exp_f32_e32 v3, v3
	ds_write_b16_d16_hi v66, v2 offset:11904
	v_sub_f32_e32 v4, s99, v21
	v_lshlrev_b32_e32 v2, 16, v5
	v_mul_f32_e32 v4, 0x3fb8aa3b, v4
	v_mul_f32_e32 v2, v3, v2
	v_exp_f32_e32 v4, v4
	v_bfe_u32 v3, v2, 16, 1
	v_add3_u32 v2, v2, v3, s30
	ds_write_b16_d16_hi v66, v2 offset:12032
	v_and_b32_e32 v2, 0xffff0000, v5
	v_mul_f32_e32 v2, v4, v2
	v_bfe_u32 v3, v2, 16, 1
	v_add3_u32 v2, v2, v3, s30
	ds_write_b16_d16_hi v66, v2 offset:12160
	s_and_saveexec_b64 s[8:9], vcc
	s_cbranch_execz .LBB0_716
	v_mul_f32_e32 v2, 0x3fb8aa3b, v46
	v_mul_f32_e32 v3, 0x3fb8aa3b, v47
	v_mul_f32_e32 v4, 0x3fb8aa3b, v48
	v_mul_f32_e32 v5, 0x3fb8aa3b, v49
	v_exp_f32_e32 v2, v2
	v_exp_f32_e32 v3, v3
	v_exp_f32_e32 v4, v4
	v_exp_f32_e32 v5, v5
	v_mul_f32_e32 v6, 0x3fb8aa3b, v42
	v_mul_f32_e32 v7, 0x3fb8aa3b, v43
	v_mul_f32_e32 v8, 0x3fb8aa3b, v44
	v_mul_f32_e32 v9, 0x3fb8aa3b, v45
	s_lshl_b64 s[10:11], s[0:1], 7
	v_exp_f32_e32 v6, v6
	v_exp_f32_e32 v7, v7
	v_exp_f32_e32 v8, v8
	v_exp_f32_e32 v9, v9
	v_mul_f32_e32 v10, 0x3fb8aa3b, v38
	v_mul_f32_e32 v11, 0x3fb8aa3b, v39
	v_mul_f32_e32 v12, 0x3fb8aa3b, v40
	v_mul_f32_e32 v13, 0x3fb8aa3b, v41
	s_add_u32 s10, s13, s10
	v_exp_f32_e32 v10, v10
	v_exp_f32_e32 v11, v11
	v_exp_f32_e32 v12, v12
	v_exp_f32_e32 v13, v13
	v_mul_f32_e32 v14, 0x3fb8aa3b, v34
	v_mul_f32_e32 v15, 0x3fb8aa3b, v35
	v_mul_f32_e32 v16, 0x3fb8aa3b, v36
	v_mul_f32_e32 v17, 0x3fb8aa3b, v37
	s_addc_u32 s11, s14, s11
	v_exp_f32_e32 v14, v14
	v_exp_f32_e32 v15, v15
	v_exp_f32_e32 v16, v16
	v_exp_f32_e32 v17, v17
	global_store_dwordx4 v67, v[2:5], s[10:11]
	global_store_dwordx4 v67, v[6:9], s[10:11] offset:16
	global_store_dwordx4 v67, v[10:13], s[10:11] offset:32
	global_store_dwordx4 v67, v[14:17], s[10:11] offset:48
	v_mul_f32_e32 v2, 0x3fb8aa3b, v30
	v_mul_f32_e32 v3, 0x3fb8aa3b, v31
	v_mul_f32_e32 v4, 0x3fb8aa3b, v32
	v_mul_f32_e32 v5, 0x3fb8aa3b, v33
	v_exp_f32_e32 v2, v2
	v_exp_f32_e32 v3, v3
	v_exp_f32_e32 v4, v4
	v_exp_f32_e32 v5, v5
	v_mul_f32_e32 v6, 0x3fb8aa3b, v26
	v_mul_f32_e32 v7, 0x3fb8aa3b, v27
	v_mul_f32_e32 v8, 0x3fb8aa3b, v28
	v_mul_f32_e32 v9, 0x3fb8aa3b, v29
	v_exp_f32_e32 v6, v6
	v_exp_f32_e32 v7, v7
	v_exp_f32_e32 v8, v8
	v_exp_f32_e32 v9, v9
	v_mul_f32_e32 v10, 0x3fb8aa3b, v22
	v_mul_f32_e32 v11, 0x3fb8aa3b, v23
	v_mul_f32_e32 v12, 0x3fb8aa3b, v24
	v_mul_f32_e32 v13, 0x3fb8aa3b, v25
	v_exp_f32_e32 v10, v10
	v_exp_f32_e32 v11, v11
	v_exp_f32_e32 v12, v12
	v_exp_f32_e32 v13, v13
	v_mul_f32_e32 v14, 0x3fb8aa3b, v18
	v_mul_f32_e32 v15, 0x3fb8aa3b, v19
	v_mul_f32_e32 v16, 0x3fb8aa3b, v20
	v_mul_f32_e32 v17, 0x3fb8aa3b, v21
	v_exp_f32_e32 v14, v14
	v_exp_f32_e32 v15, v15
	v_exp_f32_e32 v16, v16
	v_exp_f32_e32 v17, v17
	global_store_dwordx4 v67, v[2:5], s[10:11] offset:64
	global_store_dwordx4 v67, v[6:9], s[10:11] offset:80
	global_store_dwordx4 v67, v[10:13], s[10:11] offset:96
	global_store_dwordx4 v67, v[14:17], s[10:11] offset:112

.LBB0_717:
	s_and_b64 vcc, exec, s[0:1]
	s_cbranch_vccz .LBB0_711
	v_mov_b32_e32 v68, v109
	v_mov_b64_e32 v[2:3], s[22:23]
	v_add_u32_e32 v4, s33, v68
	v_mad_i64_i32 v[70:71], s[0:1], v4, s24, v[2:3]
	s_lshl_b32 s0, s6, 1
	s_mov_b32 s1, s7
	v_lshl_add_u64 v[30:31], v[70:71], 0, s[0:1]
	global_load_dwordx4 v[2:5], v[30:31], off offset:512
	global_load_dwordx4 v[6:9], v[30:31], off offset:528
	global_load_dwordx4 v[10:13], v[30:31], off offset:544
	global_load_dwordx4 v[14:17], v[30:31], off offset:560
	global_load_dwordx4 v[18:21], v[30:31], off offset:576
	global_load_dwordx4 v[22:25], v[30:31], off offset:592
	global_load_dwordx4 v[26:29], v[30:31], off offset:608
	s_nop 0
	global_load_dwordx4 v[30:33], v[30:31], off offset:624
	v_readlane_b32 s40, v239, 33
	global_load_dwordx4 v[34:37], v[70:71], off offset:1536
	v_readlane_b32 s42, v239, 35
	v_readlane_b32 s43, v239, 36
	v_readlane_b32 s46, v239, 39
	v_readlane_b32 s47, v239, 40
	s_lshl_b32 s0, s36, 7
	v_readlane_b32 s44, v239, 37
	v_readlane_b32 s45, v239, 38
	v_readlane_b32 s48, v239, 41
	v_readlane_b32 s49, v239, 42
	v_readlane_b32 s50, v239, 43
	v_readlane_b32 s51, v239, 44
	s_mov_b64 s[42:43], s[46:47]
	v_readlane_b32 s52, v239, 45
	v_readlane_b32 s53, v239, 46
	v_readlane_b32 s54, v239, 47
	v_readlane_b32 s55, v239, 48
	s_mov_b64 s[44:45], s[48:49]
	s_add_u32 s8, s42, s0
	v_mov_b32_e32 v123, s0
	s_addc_u32 s9, s43, 0
	global_load_dwordx4 v[38:41], v123, s[44:45]
	global_load_dwordx4 v[42:45], v123, s[42:43]
	global_load_dwordx4 v[46:49], v123, s[42:43] offset:512
	global_load_dwordx4 v[50:53], v123, s[42:43] offset:1024
	global_load_dwordx4 v[54:57], v123, s[42:43] offset:1536
	global_load_dwordx4 v[58:61], v123, s[42:43] offset:2048
	global_load_dwordx4 v[62:65], v123, s[42:43] offset:2560
	global_load_dwordx4 v[74:77], v123, s[42:43] offset:3072
	global_load_dwordx4 v[78:81], v123, s[42:43] offset:3584
	global_load_dwordx4 v[82:85], v111, s[8:9]
	global_load_dwordx4 v[86:89], v111, s[8:9] offset:512
	global_load_dwordx4 v[90:93], v[70:71], off offset:1552
	v_lshl_add_u32 v66, v68, 1, s17
	v_lshl_add_u64 v[70:71], v[70:71], 0, s[6:7]
	v_readlane_b32 s41, v239, 34
	s_mov_b64 s[46:47], s[50:51]
	s_mov_b64 s[48:49], s[52:53]
	s_mov_b64 s[50:51], s[54:55]
	v_ashrrev_i32_e32 v69, 31, v68
	s_waitcnt vmcnt(20)
	ds_write_b16 v66, v2
	ds_write_b16_d16_hi v66, v2 offset:128
	ds_write_b16 v66, v3 offset:256
	ds_write_b16_d16_hi v66, v3 offset:384
	ds_write_b16 v66, v4 offset:512
	ds_write_b16_d16_hi v66, v4 offset:640
	ds_write_b16 v66, v5 offset:768
	ds_write_b16_d16_hi v66, v5 offset:896
	s_waitcnt vmcnt(19)
	ds_write_b16 v66, v6 offset:1024
	ds_write_b16_d16_hi v66, v6 offset:1152
	ds_write_b16 v66, v7 offset:1280
	ds_write_b16_d16_hi v66, v7 offset:1408
	ds_write_b16 v66, v8 offset:1536
	ds_write_b16_d16_hi v66, v8 offset:1664
	ds_write_b16 v66, v9 offset:1792
	ds_write_b16_d16_hi v66, v9 offset:1920
	s_waitcnt vmcnt(18)
	ds_write_b16 v66, v10 offset:2048
	ds_write_b16_d16_hi v66, v10 offset:2176
	ds_write_b16 v66, v11 offset:2304
	ds_write_b16_d16_hi v66, v11 offset:2432
	ds_write_b16 v66, v12 offset:2560
	ds_write_b16_d16_hi v66, v12 offset:2688
	ds_write_b16 v66, v13 offset:2816
	ds_write_b16_d16_hi v66, v13 offset:2944
	s_waitcnt vmcnt(17)
	ds_write_b16 v66, v14 offset:3072
	ds_write_b16_d16_hi v66, v14 offset:3200
	ds_write_b16 v66, v15 offset:3328
	ds_write_b16_d16_hi v66, v15 offset:3456
	ds_write_b16 v66, v16 offset:3584
	ds_write_b16_d16_hi v66, v16 offset:3712
	ds_write_b16 v66, v17 offset:3840
	ds_write_b16_d16_hi v66, v17 offset:3968
	s_waitcnt vmcnt(16)
	ds_write_b16 v66, v18 offset:4096
	ds_write_b16_d16_hi v66, v18 offset:4224
	ds_write_b16 v66, v19 offset:4352
	ds_write_b16_d16_hi v66, v19 offset:4480
	ds_write_b16 v66, v20 offset:4608
	ds_write_b16_d16_hi v66, v20 offset:4736
	ds_write_b16 v66, v21 offset:4864
	ds_write_b16_d16_hi v66, v21 offset:4992
	s_waitcnt vmcnt(15)
	ds_write_b16 v66, v22 offset:5120
	ds_write_b16_d16_hi v66, v22 offset:5248
	ds_write_b16 v66, v23 offset:5376
	ds_write_b16_d16_hi v66, v23 offset:5504
	ds_write_b16 v66, v24 offset:5632
	ds_write_b16_d16_hi v66, v24 offset:5760
	ds_write_b16 v66, v25 offset:5888
	ds_write_b16_d16_hi v66, v25 offset:6016
	s_waitcnt vmcnt(14)
	ds_write_b16 v66, v26 offset:6144
	ds_write_b16_d16_hi v66, v26 offset:6272
	ds_write_b16 v66, v27 offset:6400
	ds_write_b16_d16_hi v66, v27 offset:6528
	ds_write_b16 v66, v28 offset:6656
	ds_write_b16_d16_hi v66, v28 offset:6784
	ds_write_b16 v66, v29 offset:6912
	ds_write_b16_d16_hi v66, v29 offset:7040
	s_waitcnt vmcnt(13)
	ds_write_b16 v66, v30 offset:7168
	ds_write_b16_d16_hi v66, v30 offset:7296
	ds_write_b16 v66, v31 offset:7424
	ds_write_b16_d16_hi v66, v31 offset:7552
	ds_write_b16 v66, v32 offset:7680
	ds_write_b16_d16_hi v66, v32 offset:7808
	ds_write_b16 v66, v33 offset:7936
	ds_write_b16_d16_hi v66, v33 offset:8064
	global_load_dwordx4 v[18:21], v111, s[8:9] offset:1024
	global_load_dwordx4 v[22:25], v111, s[8:9] offset:1536
	global_load_dwordx4 v[14:17], v[70:71], off offset:256
	global_load_dwordx4 v[10:13], v[70:71], off offset:272
	global_load_dwordx4 v[6:9], v[70:71], off offset:288
	global_load_dwordx4 v[2:5], v[70:71], off offset:304
	global_load_dwordx4 v[26:29], v111, s[8:9] offset:2048
	global_load_dwordx4 v[30:33], v111, s[8:9] offset:2560
	global_load_dwordx4 v[94:97], v111, s[8:9] offset:3072
	global_load_dwordx4 v[98:101], v111, s[8:9] offset:3584
	s_waitcnt vmcnt(22)
	v_lshlrev_b32_e32 v118, 16, v34
	v_and_b32_e32 v117, 0xffff0000, v34
	v_lshlrev_b32_e32 v120, 16, v36
	v_and_b32_e32 v119, 0xffff0000, v36
	v_lshlrev_b32_e32 v122, 16, v35
	v_and_b32_e32 v121, 0xffff0000, v35
	v_and_b32_e32 v73, 0xffff0000, v37
	v_lshlrev_b32_e32 v72, 16, v37
	s_waitcnt vmcnt(20)
	v_fma_f32 v36, v42, v118, v38
	s_waitcnt vmcnt(19)
	v_fmac_f32_e32 v36, v46, v117
	s_waitcnt vmcnt(18)
	v_fmac_f32_e32 v36, v50, v122
	v_fma_f32 v38, v43, v118, v39
	s_waitcnt vmcnt(17)
	v_fmac_f32_e32 v36, v54, v121
	v_fmac_f32_e32 v38, v47, v117
	s_waitcnt vmcnt(16)
	v_fmac_f32_e32 v36, v58, v120
	v_fmac_f32_e32 v38, v51, v122
	s_waitcnt vmcnt(14)
	v_mov_b32_e32 v34, v74
	s_waitcnt vmcnt(13)
	v_mov_b32_e32 v35, v78
	v_fmac_f32_e32 v36, v62, v119
	v_fmac_f32_e32 v38, v55, v121
	v_fma_f32 v39, v44, v118, v40
	v_pk_mul_f32 v[34:35], v[34:35], v[72:73]
	v_fmac_f32_e32 v38, v59, v120
	v_fmac_f32_e32 v39, v48, v117
	v_add_f32_e32 v34, v36, v34
	v_mov_b32_e32 v78, v75
	v_fmac_f32_e32 v38, v63, v119
	v_fmac_f32_e32 v39, v52, v122
	v_fmac_f32_e32 v41, v45, v118
	v_add_f32_e32 v36, v34, v35
	v_pk_mul_f32 v[34:35], v[78:79], v[72:73]
	v_fmac_f32_e32 v39, v56, v121
	v_fmac_f32_e32 v41, v49, v117
	v_add_f32_e32 v34, v34, v38
	v_fmac_f32_e32 v39, v60, v120
	v_fmac_f32_e32 v41, v53, v122
	v_add_f32_e32 v37, v35, v34
	v_mov_b32_e32 v34, v76
	v_mov_b32_e32 v35, v80
	v_fmac_f32_e32 v39, v64, v119
	v_fmac_f32_e32 v41, v57, v121
	v_pk_mul_f32 v[34:35], v[34:35], v[72:73]
	v_fmac_f32_e32 v41, v61, v120
	v_add_f32_e32 v34, v34, v39
	v_mov_b32_e32 v80, v77
	v_fmac_f32_e32 v41, v65, v119
	v_add_f32_e32 v38, v35, v34
	v_pk_mul_f32 v[34:35], v[80:81], v[72:73]
	s_waitcnt vmcnt(10)
	v_and_b32_e32 v75, 0xffff0000, v90
	v_add_f32_e32 v34, v34, v41
	v_add_f32_e32 v39, v35, v34
	v_lshlrev_b32_e32 v74, 16, v90
	v_mov_b32_e32 v34, v82
	v_mov_b32_e32 v35, v86
	v_pk_mul_f32 v[34:35], v[34:35], v[74:75]
	v_mov_b32_e32 v86, v83
	v_add_f32_e32 v34, v36, v34
	v_add_f32_e32 v36, v34, v35
	v_pk_mul_f32 v[34:35], v[86:87], v[74:75]
	v_and_b32_e32 v79, 0xffff0000, v91
	v_add_f32_e32 v34, v34, v37
	v_add_f32_e32 v37, v35, v34
	v_mov_b32_e32 v34, v84
	v_mov_b32_e32 v35, v88
	v_pk_mul_f32 v[34:35], v[34:35], v[74:75]
	v_mov_b32_e32 v88, v85
	v_add_f32_e32 v34, v34, v38
	v_add_f32_e32 v38, v35, v34
	v_pk_mul_f32 v[34:35], v[88:89], v[74:75]
	v_lshlrev_b32_e32 v78, 16, v91
	v_add_f32_e32 v34, v34, v39
	v_add_f32_e32 v39, v35, v34
	v_and_b32_e32 v81, 0xffff0000, v92
	v_lshlrev_b32_e32 v80, 16, v92
	v_and_b32_e32 v83, 0xffff0000, v93
	s_waitcnt vmcnt(9)
	v_mov_b32_e32 v34, v18
	s_waitcnt vmcnt(8)
	v_mov_b32_e32 v35, v22
	v_pk_mul_f32 v[34:35], v[34:35], v[78:79]
	v_mov_b32_e32 v22, v19
	v_add_f32_e32 v18, v36, v34
	v_add_f32_e32 v34, v18, v35
	v_pk_mul_f32 v[18:19], v[22:23], v[78:79]
	v_lshlrev_b32_e32 v82, 16, v93
	v_add_f32_e32 v18, v18, v37
	v_add_f32_e32 v22, v19, v18
	v_mov_b32_e32 v18, v20
	v_mov_b32_e32 v19, v24
	v_pk_mul_f32 v[18:19], v[18:19], v[78:79]
	v_mov_b32_e32 v24, v21
	v_add_f32_e32 v18, v18, v38
	v_add_f32_e32 v20, v19, v18
	v_pk_mul_f32 v[18:19], v[24:25], v[78:79]
	s_waitcnt vmcnt(0)
	v_mov_b32_e32 v21, v98
	v_add_f32_e32 v18, v18, v39
	v_add_f32_e32 v23, v19, v18
	v_mov_b32_e32 v18, v26
	v_mov_b32_e32 v19, v30
	v_pk_mul_f32 v[18:19], v[18:19], v[80:81]
	v_mov_b32_e32 v30, v27
	v_add_f32_e32 v18, v34, v18
	v_add_f32_e32 v24, v18, v19
	v_pk_mul_f32 v[18:19], v[30:31], v[80:81]
	v_mov_b32_e32 v98, v95
	v_add_f32_e32 v18, v18, v22
	v_add_f32_e32 v22, v19, v18
	v_mov_b32_e32 v18, v28
	v_mov_b32_e32 v19, v32
	v_pk_mul_f32 v[18:19], v[18:19], v[80:81]
	v_mov_b32_e32 v32, v29
	v_add_f32_e32 v18, v18, v20
	v_mov_b32_e32 v20, v94
	v_pk_mul_f32 v[20:21], v[20:21], v[82:83]
	s_nop 0
	v_add_f32_e32 v20, v24, v20
	v_add_f32_e32 v20, v20, v21
	v_mul_f32_e64 v21, |v20|, s25
	v_exp_f32_e32 v21, v21
	v_add_f32_e32 v24, v19, v18
	v_pk_mul_f32 v[18:19], v[32:33], v[80:81]
	v_add_f32_e32 v21, 1.0, v21
	v_cmp_gt_f32_e32 vcc, s26, v21
	v_add_f32_e32 v18, v18, v23
	v_add_f32_e32 v26, v19, v18
	v_cndmask_b32_e64 v25, 0, 32, vcc
	v_ldexp_f32 v21, v21, v25
	v_log_f32_e32 v25, v21
	v_min_f32_e32 v18, 0, v20
	v_pk_mul_f32 v[20:21], v[98:99], v[82:83]
	v_mov_b32_e32 v23, v100
	v_add_f32_e32 v20, v20, v22
	v_add_f32_e32 v21, v21, v20
	v_mul_f32_e64 v20, |v21|, s25
	v_exp_f32_e32 v20, v20
	v_mul_f32_e32 v19, 0x3f317217, v25
	v_fma_f32 v19, v25, s27, -v19
	v_fmac_f32_e32 v19, 0x3377d1cf, v25
	v_fmac_f32_e32 v19, 0x3f317217, v25
	v_cmp_lt_f32_e64 s[0:1], |v25|, s28
	v_add_f32_e32 v20, 1.0, v20
	v_mov_b32_e32 v100, v97
	v_cndmask_b32_e64 v19, v25, v19, s[0:1]
	v_cmp_gt_f32_e64 s[0:1], s26, v20
	s_nop 1
	v_cndmask_b32_e64 v22, 0, 32, s[0:1]
	v_ldexp_f32 v20, v20, v22
	v_mov_b32_e32 v22, v96
	v_pk_mul_f32 v[22:23], v[22:23], v[82:83]
	v_log_f32_e32 v25, v20
	v_add_f32_e32 v22, v22, v24
	v_add_f32_e32 v22, v23, v22
	v_mul_f32_e64 v23, |v22|, s25
	v_cndmask_b32_e32 v20, 0, v112, vcc
	v_exp_f32_e32 v23, v23
	v_sub_f32_e32 v20, v19, v20
	v_min_f32_e32 v19, 0, v21
	v_mul_f32_e32 v21, 0x3f317217, v25
	v_fma_f32 v21, v25, s27, -v21
	v_fmac_f32_e32 v21, 0x3377d1cf, v25
	v_fmac_f32_e32 v21, 0x3f317217, v25
	v_cmp_lt_f32_e64 vcc, |v25|, s28
	v_add_f32_e32 v23, 1.0, v23
	v_cndmask_b32_e64 v24, 0, v112, s[0:1]
	v_cndmask_b32_e32 v21, v25, v21, vcc
	v_cmp_gt_f32_e32 vcc, s26, v23
	v_sub_f32_e32 v21, v21, v24
	v_pk_add_f32 v[18:19], v[18:19], v[20:21] neg_lo:[0,1] neg_hi:[0,1]
	v_cndmask_b32_e64 v24, 0, 32, vcc
	v_ldexp_f32 v23, v23, v24
	v_pk_mul_f32 v[20:21], v[100:101], v[82:83]
	v_log_f32_e32 v23, v23
	v_add_f32_e32 v20, v20, v26
	v_add_f32_e32 v21, v21, v20
	v_mul_f32_e64 v20, |v21|, s25
	v_exp_f32_e32 v20, v20
	v_pk_mul_f32 v[70:71], v[18:19], s[4:5] op_sel_hi:[1,0]
	v_mul_f32_e32 v19, 0x3f317217, v23
	v_fma_f32 v19, v23, s27, -v19
	v_fmac_f32_e32 v19, 0x3377d1cf, v23
	v_fmac_f32_e32 v19, 0x3f317217, v23
	v_cmp_lt_f32_e64 s[0:1], |v23|, s28
	v_add_f32_e32 v20, 1.0, v20
	v_min_f32_e32 v18, 0, v22
	v_cndmask_b32_e64 v19, v23, v19, s[0:1]
	v_cmp_gt_f32_e64 s[0:1], s26, v20
	s_nop 1
	v_cndmask_b32_e64 v22, 0, 32, s[0:1]
	v_ldexp_f32 v20, v20, v22
	v_log_f32_e32 v22, v20
	v_cndmask_b32_e32 v20, 0, v112, vcc
	v_sub_f32_e32 v20, v19, v20
	v_min_f32_e32 v19, 0, v21
	v_mul_f32_e32 v21, 0x3f317217, v22
	v_fma_f32 v21, v22, s27, -v21
	v_fmac_f32_e32 v21, 0x3377d1cf, v22
	v_fmac_f32_e32 v21, 0x3f317217, v22
	v_cmp_lt_f32_e64 vcc, |v22|, s28
	s_nop 1
	v_cndmask_b32_e32 v21, v22, v21, vcc
	v_cndmask_b32_e64 v22, 0, v112, s[0:1]
	v_sub_f32_e32 v21, v21, v22
	v_pk_add_f32 v[18:19], v[18:19], v[20:21] neg_lo:[0,1] neg_hi:[0,1]
	s_nop 0
	v_pk_mul_f32 v[76:77], v[18:19], s[4:5] op_sel_hi:[1,0]
	global_load_dwordx4 v[18:21], v123, s[44:45] offset:16
	global_load_dwordx4 v[22:25], v123, s[42:43] offset:16
	global_load_dwordx4 v[26:29], v123, s[42:43] offset:3088
	global_load_dwordx4 v[30:33], v123, s[42:43] offset:3600
	global_load_dwordx4 v[34:37], v111, s[8:9] offset:16
	global_load_dwordx4 v[38:41], v111, s[8:9] offset:528
	global_load_dwordx4 v[42:45], v111, s[8:9] offset:1040
	global_load_dwordx4 v[46:49], v111, s[8:9] offset:1552
	global_load_dwordx4 v[50:53], v111, s[8:9] offset:2064
	global_load_dwordx4 v[54:57], v111, s[8:9] offset:2576
	global_load_dwordx4 v[58:61], v111, s[8:9] offset:3088
	global_load_dwordx4 v[62:65], v111, s[8:9] offset:3600
	global_load_dwordx4 v[84:87], v123, s[42:43] offset:528
	global_load_dwordx4 v[88:91], v123, s[42:43] offset:1040
	global_load_dwordx4 v[92:95], v123, s[42:43] offset:1552
	global_load_dwordx4 v[96:99], v123, s[42:43] offset:2064
	global_load_dwordx4 v[100:103], v123, s[42:43] offset:2576
	s_waitcnt vmcnt(15)
	v_fma_f32 v130, v22, v118, v18
	v_fma_f32 v20, v24, v118, v20
	s_waitcnt vmcnt(14)
	v_mov_b32_e32 v104, v26
	s_waitcnt vmcnt(13)
	v_mov_b32_e32 v105, v30
	v_fma_f32 v23, v23, v118, v19
	v_mov_b32_e32 v30, v27
	v_mov_b32_e32 v18, v28
	v_mov_b32_e32 v19, v32
	v_pk_mul_f32 v[26:27], v[104:105], v[72:73]
	s_waitcnt vmcnt(12)
	v_mov_b32_e32 v106, v34
	s_waitcnt vmcnt(11)
	v_mov_b32_e32 v107, v38
	s_waitcnt vmcnt(4)
	v_fmac_f32_e32 v130, v84, v117
	v_fmac_f32_e32 v20, v86, v117
	s_waitcnt vmcnt(3)
	v_fmac_f32_e32 v130, v88, v122
	v_fmac_f32_e32 v20, v90, v122
	s_waitcnt vmcnt(2)
	v_fmac_f32_e32 v130, v92, v121
	v_fmac_f32_e32 v20, v94, v121
	s_waitcnt vmcnt(1)
	v_fmac_f32_e32 v130, v96, v120
	v_fmac_f32_e32 v20, v98, v120
	s_waitcnt vmcnt(0)
	v_fmac_f32_e32 v130, v100, v119
	v_fmac_f32_e32 v23, v85, v117
	v_pk_mul_f32 v[18:19], v[18:19], v[72:73]
	v_fmac_f32_e32 v20, v102, v119
	v_add_f32_e32 v24, v130, v26
	v_mov_b32_e32 v38, v35
	v_pk_mul_f32 v[34:35], v[106:107], v[74:75]
	v_fmac_f32_e32 v23, v89, v122
	v_add_f32_e32 v18, v18, v20
	v_add_f32_e32 v20, v24, v27
	v_mov_b32_e32 v124, v42
	v_mov_b32_e32 v125, v46
	v_fmac_f32_e32 v23, v93, v121
	v_add_f32_e32 v20, v20, v34
	v_mov_b32_e32 v46, v43
	v_pk_mul_f32 v[42:43], v[124:125], v[78:79]
	v_fmac_f32_e32 v23, v97, v120
	v_add_f32_e32 v20, v20, v35
	v_mov_b32_e32 v126, v50
	v_mov_b32_e32 v127, v54
	v_pk_mul_f32 v[30:31], v[30:31], v[72:73]
	v_fmac_f32_e32 v23, v101, v119
	v_add_f32_e32 v20, v20, v42
	v_mov_b32_e32 v54, v51
	v_pk_mul_f32 v[50:51], v[126:127], v[80:81]
	v_add_f32_e32 v23, v30, v23
	v_add_f32_e32 v20, v20, v43
	v_mov_b32_e32 v128, v58
	v_mov_b32_e32 v129, v62
	v_pk_mul_f32 v[38:39], v[38:39], v[74:75]
	v_add_f32_e32 v23, v31, v23
	v_add_f32_e32 v20, v20, v50
	v_mov_b32_e32 v62, v59
	v_pk_mul_f32 v[58:59], v[128:129], v[82:83]
	v_add_f32_e32 v23, v38, v23
	v_add_f32_e32 v20, v20, v51
	v_pk_mul_f32 v[46:47], v[46:47], v[78:79]
	v_add_f32_e32 v23, v39, v23
	v_add_f32_e32 v20, v20, v58
	v_add_f32_e32 v23, v46, v23
	v_add_f32_e32 v20, v20, v59
	v_pk_mul_f32 v[54:55], v[54:55], v[80:81]
	v_add_f32_e32 v23, v47, v23
	v_mul_f32_e64 v24, |v20|, s25
	v_add_f32_e32 v23, v54, v23
	v_exp_f32_e32 v24, v24
	v_pk_mul_f32 v[62:63], v[62:63], v[82:83]
	v_add_f32_e32 v23, v55, v23
	v_add_f32_e32 v23, v62, v23
	v_add_f32_e32 v23, v63, v23
	v_mul_f32_e64 v26, |v23|, s25
	v_add_f32_e32 v27, v19, v18
	v_add_f32_e32 v19, 1.0, v24
	v_exp_f32_e32 v26, v26
	v_cmp_gt_f32_e32 vcc, s26, v19
	v_min_f32_e32 v18, 0, v20
	v_mov_b32_e32 v22, v36
	v_cndmask_b32_e64 v24, 0, 32, vcc
	v_ldexp_f32 v19, v19, v24
	v_log_f32_e32 v24, v19
	v_add_f32_e32 v20, 1.0, v26
	v_cmp_gt_f32_e64 s[0:1], s26, v20
	v_min_f32_e32 v19, 0, v23
	v_cndmask_b32_e32 v23, 0, v112, vcc
	v_cndmask_b32_e64 v26, 0, 32, s[0:1]
	v_ldexp_f32 v20, v20, v26
	v_mul_f32_e32 v26, 0x3f317217, v24
	v_fma_f32 v26, v24, s27, -v26
	v_fmac_f32_e32 v26, 0x3377d1cf, v24
	v_fmac_f32_e32 v26, 0x3f317217, v24
	v_cmp_lt_f32_e64 vcc, |v24|, s28
	v_log_f32_e32 v20, v20
	v_fmac_f32_e32 v21, v25, v118
	v_cndmask_b32_e32 v24, v24, v26, vcc
	v_sub_f32_e32 v26, v24, v23
	v_mov_b32_e32 v23, v40
	v_pk_mul_f32 v[22:23], v[22:23], v[74:75]
	v_mul_f32_e32 v28, 0x3f317217, v20
	v_add_f32_e32 v22, v22, v27
	v_add_f32_e32 v24, v23, v22
	v_mov_b32_e32 v22, v44
	v_mov_b32_e32 v23, v48
	v_pk_mul_f32 v[22:23], v[22:23], v[78:79]
	v_fma_f32 v28, v20, s27, -v28
	v_add_f32_e32 v22, v22, v24
	v_add_f32_e32 v24, v23, v22
	v_mov_b32_e32 v22, v52
	v_mov_b32_e32 v23, v56
	v_pk_mul_f32 v[22:23], v[22:23], v[80:81]
	v_fmac_f32_e32 v28, 0x3377d1cf, v20
	v_add_f32_e32 v22, v22, v24
	v_add_f32_e32 v24, v23, v22
	v_mov_b32_e32 v22, v60
	v_mov_b32_e32 v23, v64
	v_pk_mul_f32 v[22:23], v[22:23], v[82:83]
	v_fmac_f32_e32 v28, 0x3f317217, v20
	v_add_f32_e32 v22, v22, v24
	v_add_f32_e32 v22, v23, v22
	v_mul_f32_e64 v23, |v22|, s25
	v_exp_f32_e32 v23, v23
	v_cmp_lt_f32_e64 vcc, |v20|, s28
	v_cndmask_b32_e64 v24, 0, v112, s[0:1]
	v_fmac_f32_e32 v21, v87, v117
	v_cndmask_b32_e32 v20, v20, v28, vcc
	v_sub_f32_e32 v27, v20, v24
	v_add_f32_e32 v20, 1.0, v23
	v_fmac_f32_e32 v21, v91, v122
	v_cmp_gt_f32_e32 vcc, s26, v20
	v_fmac_f32_e32 v21, v95, v121
	v_pk_add_f32 v[18:19], v[18:19], v[26:27] neg_lo:[0,1] neg_hi:[0,1]
	v_cndmask_b32_e64 v23, 0, 32, vcc
	v_fmac_f32_e32 v21, v99, v120
	v_mov_b32_e32 v32, v29
	v_ldexp_f32 v20, v20, v23
	v_pk_mul_f32 v[84:85], v[18:19], s[4:5] op_sel_hi:[1,0]
	v_min_f32_e32 v18, 0, v22
	v_fmac_f32_e32 v21, v103, v119
	v_pk_mul_f32 v[22:23], v[32:33], v[72:73]
	v_log_f32_e32 v24, v20
	v_add_f32_e32 v20, v22, v21
	v_mov_b32_e32 v40, v37
	v_add_f32_e32 v22, v23, v20
	v_pk_mul_f32 v[20:21], v[40:41], v[74:75]
	v_mov_b32_e32 v48, v45
	v_add_f32_e32 v20, v20, v22
	v_add_f32_e32 v22, v21, v20
	v_pk_mul_f32 v[20:21], v[48:49], v[78:79]
	v_mov_b32_e32 v56, v53
	v_add_f32_e32 v20, v20, v22
	v_add_f32_e32 v22, v21, v20
	v_pk_mul_f32 v[20:21], v[56:57], v[80:81]
	v_mov_b32_e32 v64, v61
	v_add_f32_e32 v20, v20, v22
	v_add_f32_e32 v22, v21, v20
	v_pk_mul_f32 v[20:21], v[64:65], v[82:83]
	v_mul_f32_e32 v19, 0x3f317217, v24
	v_add_f32_e32 v20, v20, v22
	v_add_f32_e32 v21, v21, v20
	v_mul_f32_e64 v20, |v21|, s25
	v_exp_f32_e32 v20, v20
	v_fma_f32 v19, v24, s27, -v19
	v_fmac_f32_e32 v19, 0x3377d1cf, v24
	v_fmac_f32_e32 v19, 0x3f317217, v24
	v_cmp_lt_f32_e64 s[0:1], |v24|, s28
	v_add_f32_e32 v20, 1.0, v20
	s_nop 0
	v_cndmask_b32_e64 v19, v24, v19, s[0:1]
	v_cmp_gt_f32_e64 s[0:1], s26, v20
	s_nop 1
	v_cndmask_b32_e64 v22, 0, 32, s[0:1]
	v_ldexp_f32 v20, v20, v22
	v_log_f32_e32 v22, v20
	v_cndmask_b32_e32 v20, 0, v112, vcc
	v_sub_f32_e32 v20, v19, v20
	v_min_f32_e32 v19, 0, v21
	v_mul_f32_e32 v21, 0x3f317217, v22
	v_fma_f32 v21, v22, s27, -v21
	v_fmac_f32_e32 v21, 0x3377d1cf, v22
	v_fmac_f32_e32 v21, 0x3f317217, v22
	v_cmp_lt_f32_e64 vcc, |v22|, s28
	s_nop 1
	v_cndmask_b32_e32 v21, v22, v21, vcc
	v_cndmask_b32_e64 v22, 0, v112, s[0:1]
	v_sub_f32_e32 v21, v21, v22
	v_pk_add_f32 v[18:19], v[18:19], v[20:21] neg_lo:[0,1] neg_hi:[0,1]
	s_nop 0
	v_pk_mul_f32 v[86:87], v[18:19], s[4:5] op_sel_hi:[1,0]
	global_load_dwordx4 v[18:21], v123, s[44:45] offset:32
	global_load_dwordx4 v[22:25], v123, s[42:43] offset:32
	global_load_dwordx4 v[26:29], v123, s[42:43] offset:3104
	global_load_dwordx4 v[30:33], v123, s[42:43] offset:3616
	global_load_dwordx4 v[34:37], v111, s[8:9] offset:32
	global_load_dwordx4 v[38:41], v111, s[8:9] offset:544
	global_load_dwordx4 v[42:45], v111, s[8:9] offset:1056
	global_load_dwordx4 v[46:49], v111, s[8:9] offset:1568
	global_load_dwordx4 v[50:53], v111, s[8:9] offset:2080
	global_load_dwordx4 v[54:57], v111, s[8:9] offset:2592
	global_load_dwordx4 v[58:61], v111, s[8:9] offset:3104
	global_load_dwordx4 v[62:65], v111, s[8:9] offset:3616
	global_load_dwordx4 v[88:91], v123, s[42:43] offset:544
	global_load_dwordx4 v[92:95], v123, s[42:43] offset:1056
	global_load_dwordx4 v[96:99], v123, s[42:43] offset:1568
	global_load_dwordx4 v[100:103], v123, s[42:43] offset:2080
	global_load_dwordx4 v[104:107], v123, s[42:43] offset:2592
	s_waitcnt vmcnt(15)
	v_fma_f32 v134, v22, v118, v18
	v_fma_f32 v20, v24, v118, v20
	s_waitcnt vmcnt(14)
	v_mov_b32_e32 v124, v26
	s_waitcnt vmcnt(13)
	v_mov_b32_e32 v125, v30
	v_fma_f32 v23, v23, v118, v19
	v_mov_b32_e32 v30, v27
	v_mov_b32_e32 v18, v28
	v_mov_b32_e32 v19, v32
	v_pk_mul_f32 v[26:27], v[124:125], v[72:73]
	s_waitcnt vmcnt(12)
	v_mov_b32_e32 v126, v34
	s_waitcnt vmcnt(11)
	v_mov_b32_e32 v127, v38
	s_waitcnt vmcnt(4)
	v_fmac_f32_e32 v134, v88, v117
	v_fmac_f32_e32 v20, v90, v117
	s_waitcnt vmcnt(3)
	v_fmac_f32_e32 v134, v92, v122
	v_fmac_f32_e32 v20, v94, v122
	s_waitcnt vmcnt(2)
	v_fmac_f32_e32 v134, v96, v121
	v_fmac_f32_e32 v20, v98, v121
	s_waitcnt vmcnt(1)
	v_fmac_f32_e32 v134, v100, v120
	v_fmac_f32_e32 v20, v102, v120
	s_waitcnt vmcnt(0)
	v_fmac_f32_e32 v134, v104, v119
	v_fmac_f32_e32 v23, v89, v117
	v_pk_mul_f32 v[18:19], v[18:19], v[72:73]
	v_fmac_f32_e32 v20, v106, v119
	v_add_f32_e32 v24, v134, v26
	v_mov_b32_e32 v38, v35
	v_pk_mul_f32 v[34:35], v[126:127], v[74:75]
	v_fmac_f32_e32 v23, v93, v122
	v_add_f32_e32 v18, v18, v20
	v_add_f32_e32 v20, v24, v27
	v_mov_b32_e32 v128, v42
	v_mov_b32_e32 v129, v46
	v_fmac_f32_e32 v23, v97, v121
	v_add_f32_e32 v20, v20, v34
	v_mov_b32_e32 v46, v43
	v_pk_mul_f32 v[42:43], v[128:129], v[78:79]
	v_fmac_f32_e32 v23, v101, v120
	v_add_f32_e32 v20, v20, v35
	v_mov_b32_e32 v130, v50
	v_mov_b32_e32 v131, v54
	v_pk_mul_f32 v[30:31], v[30:31], v[72:73]
	v_fmac_f32_e32 v23, v105, v119
	v_add_f32_e32 v20, v20, v42
	v_mov_b32_e32 v54, v51
	v_pk_mul_f32 v[50:51], v[130:131], v[80:81]
	v_add_f32_e32 v23, v30, v23
	v_add_f32_e32 v20, v20, v43
	v_mov_b32_e32 v132, v58
	v_mov_b32_e32 v133, v62
	v_pk_mul_f32 v[38:39], v[38:39], v[74:75]
	v_add_f32_e32 v23, v31, v23
	v_add_f32_e32 v20, v20, v50
	v_mov_b32_e32 v62, v59
	v_pk_mul_f32 v[58:59], v[132:133], v[82:83]
	v_add_f32_e32 v23, v38, v23
	v_add_f32_e32 v20, v20, v51
	v_pk_mul_f32 v[46:47], v[46:47], v[78:79]
	v_add_f32_e32 v23, v39, v23
	v_add_f32_e32 v20, v20, v58
	v_add_f32_e32 v23, v46, v23
	v_add_f32_e32 v20, v20, v59
	v_pk_mul_f32 v[54:55], v[54:55], v[80:81]
	v_add_f32_e32 v23, v47, v23
	v_mul_f32_e64 v24, |v20|, s25
	v_add_f32_e32 v23, v54, v23
	v_exp_f32_e32 v24, v24
	v_pk_mul_f32 v[62:63], v[62:63], v[82:83]
	v_add_f32_e32 v23, v55, v23
	v_add_f32_e32 v23, v62, v23
	v_add_f32_e32 v23, v63, v23
	v_mul_f32_e64 v26, |v23|, s25
	v_add_f32_e32 v27, v19, v18
	v_add_f32_e32 v19, 1.0, v24
	v_exp_f32_e32 v26, v26
	v_cmp_gt_f32_e32 vcc, s26, v19
	v_min_f32_e32 v18, 0, v20
	v_mov_b32_e32 v22, v36
	v_cndmask_b32_e64 v24, 0, 32, vcc
	v_ldexp_f32 v19, v19, v24
	v_log_f32_e32 v24, v19
	v_add_f32_e32 v20, 1.0, v26
	v_cmp_gt_f32_e64 s[0:1], s26, v20
	v_min_f32_e32 v19, 0, v23
	v_cndmask_b32_e32 v23, 0, v112, vcc
	v_cndmask_b32_e64 v26, 0, 32, s[0:1]
	v_ldexp_f32 v20, v20, v26
	v_mul_f32_e32 v26, 0x3f317217, v24
	v_fma_f32 v26, v24, s27, -v26
	v_fmac_f32_e32 v26, 0x3377d1cf, v24
	v_fmac_f32_e32 v26, 0x3f317217, v24
	v_cmp_lt_f32_e64 vcc, |v24|, s28
	v_log_f32_e32 v20, v20
	v_fmac_f32_e32 v21, v25, v118
	v_cndmask_b32_e32 v24, v24, v26, vcc
	v_sub_f32_e32 v26, v24, v23
	v_mov_b32_e32 v23, v40
	v_pk_mul_f32 v[22:23], v[22:23], v[74:75]
	v_mul_f32_e32 v28, 0x3f317217, v20
	v_add_f32_e32 v22, v22, v27
	v_add_f32_e32 v24, v23, v22
	v_mov_b32_e32 v22, v44
	v_mov_b32_e32 v23, v48
	v_pk_mul_f32 v[22:23], v[22:23], v[78:79]
	v_fma_f32 v28, v20, s27, -v28
	v_add_f32_e32 v22, v22, v24
	v_add_f32_e32 v24, v23, v22
	v_mov_b32_e32 v22, v52
	v_mov_b32_e32 v23, v56
	v_pk_mul_f32 v[22:23], v[22:23], v[80:81]
	v_fmac_f32_e32 v28, 0x3377d1cf, v20
	v_add_f32_e32 v22, v22, v24
	v_add_f32_e32 v24, v23, v22
	v_mov_b32_e32 v22, v60
	v_mov_b32_e32 v23, v64
	v_pk_mul_f32 v[22:23], v[22:23], v[82:83]
	v_fmac_f32_e32 v28, 0x3f317217, v20
	v_add_f32_e32 v22, v22, v24
	v_add_f32_e32 v22, v23, v22
	v_mul_f32_e64 v23, |v22|, s25
	v_exp_f32_e32 v23, v23
	v_cmp_lt_f32_e64 vcc, |v20|, s28
	v_cndmask_b32_e64 v24, 0, v112, s[0:1]
	v_fmac_f32_e32 v21, v91, v117
	v_cndmask_b32_e32 v20, v20, v28, vcc
	v_sub_f32_e32 v27, v20, v24
	v_add_f32_e32 v20, 1.0, v23
	v_fmac_f32_e32 v21, v95, v122
	v_cmp_gt_f32_e32 vcc, s26, v20
	v_fmac_f32_e32 v21, v99, v121
	v_pk_add_f32 v[18:19], v[18:19], v[26:27] neg_lo:[0,1] neg_hi:[0,1]
	v_cndmask_b32_e64 v23, 0, 32, vcc
	v_fmac_f32_e32 v21, v103, v120
	v_mov_b32_e32 v32, v29
	v_ldexp_f32 v20, v20, v23
	v_pk_mul_f32 v[88:89], v[18:19], s[4:5] op_sel_hi:[1,0]
	v_min_f32_e32 v18, 0, v22
	v_fmac_f32_e32 v21, v107, v119
	v_pk_mul_f32 v[22:23], v[32:33], v[72:73]
	v_log_f32_e32 v24, v20
	v_add_f32_e32 v20, v22, v21
	v_mov_b32_e32 v40, v37
	v_add_f32_e32 v22, v23, v20
	v_pk_mul_f32 v[20:21], v[40:41], v[74:75]
	v_mov_b32_e32 v48, v45
	v_add_f32_e32 v20, v20, v22
	v_add_f32_e32 v22, v21, v20
	v_pk_mul_f32 v[20:21], v[48:49], v[78:79]
	v_mov_b32_e32 v56, v53
	v_add_f32_e32 v20, v20, v22
	v_add_f32_e32 v22, v21, v20
	v_pk_mul_f32 v[20:21], v[56:57], v[80:81]
	v_mov_b32_e32 v64, v61
	v_add_f32_e32 v20, v20, v22
	v_add_f32_e32 v22, v21, v20
	v_pk_mul_f32 v[20:21], v[64:65], v[82:83]
	v_mul_f32_e32 v19, 0x3f317217, v24
	v_add_f32_e32 v20, v20, v22
	v_add_f32_e32 v21, v21, v20
	v_mul_f32_e64 v20, |v21|, s25
	v_exp_f32_e32 v20, v20
	v_fma_f32 v19, v24, s27, -v19
	v_fmac_f32_e32 v19, 0x3377d1cf, v24
	v_fmac_f32_e32 v19, 0x3f317217, v24
	v_cmp_lt_f32_e64 s[0:1], |v24|, s28
	v_add_f32_e32 v20, 1.0, v20
	s_nop 0
	v_cndmask_b32_e64 v19, v24, v19, s[0:1]
	v_cmp_gt_f32_e64 s[0:1], s26, v20
	s_nop 1
	v_cndmask_b32_e64 v22, 0, 32, s[0:1]
	v_ldexp_f32 v20, v20, v22
	v_log_f32_e32 v22, v20
	v_cndmask_b32_e32 v20, 0, v112, vcc
	v_sub_f32_e32 v20, v19, v20
	v_min_f32_e32 v19, 0, v21
	v_mul_f32_e32 v21, 0x3f317217, v22
	v_fma_f32 v21, v22, s27, -v21
	v_fmac_f32_e32 v21, 0x3377d1cf, v22
	v_fmac_f32_e32 v21, 0x3f317217, v22
	v_cmp_lt_f32_e64 vcc, |v22|, s28
	s_nop 1
	v_cndmask_b32_e32 v21, v22, v21, vcc
	v_cndmask_b32_e64 v22, 0, v112, s[0:1]
	v_sub_f32_e32 v21, v21, v22
	v_pk_add_f32 v[18:19], v[18:19], v[20:21] neg_lo:[0,1] neg_hi:[0,1]
	s_nop 0
	v_pk_mul_f32 v[90:91], v[18:19], s[4:5] op_sel_hi:[1,0]
	global_load_dwordx4 v[18:21], v123, s[44:45] offset:48
	global_load_dwordx4 v[22:25], v123, s[42:43] offset:48
	global_load_dwordx4 v[26:29], v123, s[42:43] offset:3120
	global_load_dwordx4 v[30:33], v123, s[42:43] offset:3632
	global_load_dwordx4 v[34:37], v111, s[8:9] offset:48
	global_load_dwordx4 v[38:41], v111, s[8:9] offset:560
	global_load_dwordx4 v[42:45], v111, s[8:9] offset:1072
	global_load_dwordx4 v[46:49], v111, s[8:9] offset:1584
	global_load_dwordx4 v[50:53], v111, s[8:9] offset:2096
	global_load_dwordx4 v[54:57], v111, s[8:9] offset:2608
	global_load_dwordx4 v[58:61], v111, s[8:9] offset:3120
	global_load_dwordx4 v[62:65], v111, s[8:9] offset:3632
	global_load_dwordx4 v[92:95], v123, s[42:43] offset:560
	global_load_dwordx4 v[96:99], v123, s[42:43] offset:1072
	global_load_dwordx4 v[100:103], v123, s[42:43] offset:1584
	global_load_dwordx4 v[104:107], v123, s[42:43] offset:2096
	global_load_dwordx4 v[124:127], v123, s[42:43] offset:2608
	s_waitcnt vmcnt(15)
	v_fma_f32 v138, v22, v118, v18
	v_fma_f32 v20, v24, v118, v20
	s_waitcnt vmcnt(14)
	v_mov_b32_e32 v128, v26
	s_waitcnt vmcnt(13)
	v_mov_b32_e32 v129, v30
	v_fma_f32 v23, v23, v118, v19
	v_mov_b32_e32 v30, v27
	v_mov_b32_e32 v18, v28
	v_mov_b32_e32 v19, v32
	v_pk_mul_f32 v[26:27], v[128:129], v[72:73]
	s_waitcnt vmcnt(12)
	v_mov_b32_e32 v130, v34
	s_waitcnt vmcnt(11)
	v_mov_b32_e32 v131, v38
	s_waitcnt vmcnt(4)
	v_fmac_f32_e32 v138, v92, v117
	v_fmac_f32_e32 v20, v94, v117
	s_waitcnt vmcnt(3)
	v_fmac_f32_e32 v138, v96, v122
	v_fmac_f32_e32 v20, v98, v122
	s_waitcnt vmcnt(2)
	v_fmac_f32_e32 v138, v100, v121
	v_fmac_f32_e32 v20, v102, v121
	s_waitcnt vmcnt(1)
	v_fmac_f32_e32 v138, v104, v120
	v_fmac_f32_e32 v20, v106, v120
	s_waitcnt vmcnt(0)
	v_fmac_f32_e32 v138, v124, v119
	v_fmac_f32_e32 v23, v93, v117
	v_pk_mul_f32 v[18:19], v[18:19], v[72:73]
	v_fmac_f32_e32 v20, v126, v119
	v_add_f32_e32 v24, v138, v26
	v_mov_b32_e32 v38, v35
	v_pk_mul_f32 v[34:35], v[130:131], v[74:75]
	v_fmac_f32_e32 v23, v97, v122
	v_add_f32_e32 v18, v18, v20
	v_add_f32_e32 v20, v24, v27
	v_mov_b32_e32 v132, v42
	v_mov_b32_e32 v133, v46
	v_fmac_f32_e32 v23, v101, v121
	v_add_f32_e32 v20, v20, v34
	v_mov_b32_e32 v46, v43
	v_pk_mul_f32 v[42:43], v[132:133], v[78:79]
	v_fmac_f32_e32 v23, v105, v120
	v_add_f32_e32 v20, v20, v35
	v_mov_b32_e32 v134, v50
	v_mov_b32_e32 v135, v54
	v_pk_mul_f32 v[30:31], v[30:31], v[72:73]
	v_fmac_f32_e32 v23, v125, v119
	v_add_f32_e32 v20, v20, v42
	v_mov_b32_e32 v54, v51
	v_pk_mul_f32 v[50:51], v[134:135], v[80:81]
	v_add_f32_e32 v23, v30, v23
	v_add_f32_e32 v20, v20, v43
	v_mov_b32_e32 v136, v58
	v_mov_b32_e32 v137, v62
	v_pk_mul_f32 v[38:39], v[38:39], v[74:75]
	v_add_f32_e32 v23, v31, v23
	v_add_f32_e32 v20, v20, v50
	v_mov_b32_e32 v62, v59
	v_pk_mul_f32 v[58:59], v[136:137], v[82:83]
	v_add_f32_e32 v23, v38, v23
	v_add_f32_e32 v20, v20, v51
	v_pk_mul_f32 v[46:47], v[46:47], v[78:79]
	v_add_f32_e32 v23, v39, v23
	v_add_f32_e32 v20, v20, v58
	v_add_f32_e32 v23, v46, v23
	v_add_f32_e32 v20, v20, v59
	v_pk_mul_f32 v[54:55], v[54:55], v[80:81]
	v_add_f32_e32 v23, v47, v23
	v_mul_f32_e64 v24, |v20|, s25
	v_add_f32_e32 v23, v54, v23
	v_exp_f32_e32 v24, v24
	v_pk_mul_f32 v[62:63], v[62:63], v[82:83]
	v_add_f32_e32 v23, v55, v23
	v_add_f32_e32 v23, v62, v23
	v_add_f32_e32 v23, v63, v23
	v_mul_f32_e64 v26, |v23|, s25
	v_add_f32_e32 v27, v19, v18
	v_add_f32_e32 v19, 1.0, v24
	v_exp_f32_e32 v26, v26
	v_cmp_gt_f32_e32 vcc, s26, v19
	v_min_f32_e32 v18, 0, v20
	v_mov_b32_e32 v22, v36
	v_cndmask_b32_e64 v24, 0, 32, vcc
	v_ldexp_f32 v19, v19, v24
	v_log_f32_e32 v24, v19
	v_add_f32_e32 v20, 1.0, v26
	v_cmp_gt_f32_e64 s[0:1], s26, v20
	v_min_f32_e32 v19, 0, v23
	v_cndmask_b32_e32 v23, 0, v112, vcc
	v_cndmask_b32_e64 v26, 0, 32, s[0:1]
	v_ldexp_f32 v20, v20, v26
	v_mul_f32_e32 v26, 0x3f317217, v24
	v_fma_f32 v26, v24, s27, -v26
	v_fmac_f32_e32 v26, 0x3377d1cf, v24
	v_fmac_f32_e32 v26, 0x3f317217, v24
	v_cmp_lt_f32_e64 vcc, |v24|, s28
	v_log_f32_e32 v20, v20
	v_fmac_f32_e32 v21, v25, v118
	v_cndmask_b32_e32 v24, v24, v26, vcc
	v_sub_f32_e32 v26, v24, v23
	v_mov_b32_e32 v23, v40
	v_pk_mul_f32 v[22:23], v[22:23], v[74:75]
	v_mul_f32_e32 v28, 0x3f317217, v20
	v_add_f32_e32 v22, v22, v27
	v_add_f32_e32 v24, v23, v22
	v_mov_b32_e32 v22, v44
	v_mov_b32_e32 v23, v48
	v_pk_mul_f32 v[22:23], v[22:23], v[78:79]
	v_fma_f32 v28, v20, s27, -v28
	v_add_f32_e32 v22, v22, v24
	v_add_f32_e32 v24, v23, v22
	v_mov_b32_e32 v22, v52
	v_mov_b32_e32 v23, v56
	v_pk_mul_f32 v[22:23], v[22:23], v[80:81]
	v_fmac_f32_e32 v28, 0x3377d1cf, v20
	v_add_f32_e32 v22, v22, v24
	v_add_f32_e32 v24, v23, v22
	v_mov_b32_e32 v22, v60
	v_mov_b32_e32 v23, v64
	v_pk_mul_f32 v[22:23], v[22:23], v[82:83]
	v_fmac_f32_e32 v28, 0x3f317217, v20
	v_add_f32_e32 v22, v22, v24
	v_add_f32_e32 v22, v23, v22
	v_mul_f32_e64 v23, |v22|, s25
	v_exp_f32_e32 v23, v23
	v_cmp_lt_f32_e64 vcc, |v20|, s28
	v_cndmask_b32_e64 v24, 0, v112, s[0:1]
	v_fmac_f32_e32 v21, v95, v117
	v_cndmask_b32_e32 v20, v20, v28, vcc
	v_sub_f32_e32 v27, v20, v24
	v_add_f32_e32 v20, 1.0, v23
	v_fmac_f32_e32 v21, v99, v122
	v_cmp_gt_f32_e32 vcc, s26, v20
	v_fmac_f32_e32 v21, v103, v121
	v_pk_add_f32 v[18:19], v[18:19], v[26:27] neg_lo:[0,1] neg_hi:[0,1]
	v_cndmask_b32_e64 v23, 0, 32, vcc
	v_fmac_f32_e32 v21, v107, v120
	v_mov_b32_e32 v32, v29
	v_ldexp_f32 v20, v20, v23
	v_pk_mul_f32 v[92:93], v[18:19], s[4:5] op_sel_hi:[1,0]
	v_min_f32_e32 v18, 0, v22
	v_fmac_f32_e32 v21, v127, v119
	v_pk_mul_f32 v[22:23], v[32:33], v[72:73]
	v_log_f32_e32 v24, v20
	v_add_f32_e32 v20, v22, v21
	v_mov_b32_e32 v40, v37
	v_add_f32_e32 v22, v23, v20
	v_pk_mul_f32 v[20:21], v[40:41], v[74:75]
	v_mov_b32_e32 v48, v45
	v_add_f32_e32 v20, v20, v22
	v_add_f32_e32 v22, v21, v20
	v_pk_mul_f32 v[20:21], v[48:49], v[78:79]
	v_mov_b32_e32 v56, v53
	v_add_f32_e32 v20, v20, v22
	v_add_f32_e32 v22, v21, v20
	v_pk_mul_f32 v[20:21], v[56:57], v[80:81]
	v_mov_b32_e32 v64, v61
	v_add_f32_e32 v20, v20, v22
	v_add_f32_e32 v22, v21, v20
	v_pk_mul_f32 v[20:21], v[64:65], v[82:83]
	v_mul_f32_e32 v19, 0x3f317217, v24
	v_add_f32_e32 v20, v20, v22
	v_add_f32_e32 v21, v21, v20
	v_mul_f32_e64 v20, |v21|, s25
	v_exp_f32_e32 v20, v20
	v_fma_f32 v19, v24, s27, -v19
	v_fmac_f32_e32 v19, 0x3377d1cf, v24
	v_fmac_f32_e32 v19, 0x3f317217, v24
	v_cmp_lt_f32_e64 s[0:1], |v24|, s28
	v_add_f32_e32 v20, 1.0, v20
	s_nop 0
	v_cndmask_b32_e64 v19, v24, v19, s[0:1]
	v_cmp_gt_f32_e64 s[0:1], s26, v20
	s_nop 1
	v_cndmask_b32_e64 v22, 0, 32, s[0:1]
	v_ldexp_f32 v20, v20, v22
	v_log_f32_e32 v22, v20
	v_cndmask_b32_e32 v20, 0, v112, vcc
	v_sub_f32_e32 v20, v19, v20
	v_min_f32_e32 v19, 0, v21
	v_mul_f32_e32 v21, 0x3f317217, v22
	v_fma_f32 v21, v22, s27, -v21
	v_fmac_f32_e32 v21, 0x3377d1cf, v22
	v_fmac_f32_e32 v21, 0x3f317217, v22
	v_cmp_lt_f32_e64 vcc, |v22|, s28
	s_nop 1
	v_cndmask_b32_e32 v21, v22, v21, vcc
	v_cndmask_b32_e64 v22, 0, v112, s[0:1]
	v_sub_f32_e32 v21, v21, v22
	v_pk_add_f32 v[18:19], v[18:19], v[20:21] neg_lo:[0,1] neg_hi:[0,1]
	s_nop 0
	v_pk_mul_f32 v[94:95], v[18:19], s[4:5] op_sel_hi:[1,0]
	global_load_dwordx4 v[18:21], v123, s[44:45] offset:64
	global_load_dwordx4 v[22:25], v123, s[42:43] offset:64
	global_load_dwordx4 v[26:29], v123, s[42:43] offset:3136
	global_load_dwordx4 v[30:33], v123, s[42:43] offset:3648
	global_load_dwordx4 v[34:37], v111, s[8:9] offset:64
	global_load_dwordx4 v[38:41], v111, s[8:9] offset:576
	global_load_dwordx4 v[42:45], v111, s[8:9] offset:1088
	global_load_dwordx4 v[46:49], v111, s[8:9] offset:1600
	global_load_dwordx4 v[50:53], v111, s[8:9] offset:2112
	global_load_dwordx4 v[54:57], v111, s[8:9] offset:2624
	global_load_dwordx4 v[58:61], v111, s[8:9] offset:3136
	global_load_dwordx4 v[62:65], v111, s[8:9] offset:3648
	global_load_dwordx4 v[96:99], v123, s[42:43] offset:576
	global_load_dwordx4 v[100:103], v123, s[42:43] offset:1088
	global_load_dwordx4 v[104:107], v123, s[42:43] offset:1600
	global_load_dwordx4 v[124:127], v123, s[42:43] offset:2112
	global_load_dwordx4 v[128:131], v123, s[42:43] offset:2624
	s_waitcnt vmcnt(15)
	v_fma_f32 v142, v22, v118, v18
	v_fma_f32 v20, v24, v118, v20
	s_waitcnt vmcnt(14)
	v_mov_b32_e32 v132, v26
	s_waitcnt vmcnt(13)
	v_mov_b32_e32 v133, v30
	v_fma_f32 v23, v23, v118, v19
	v_mov_b32_e32 v30, v27
	v_mov_b32_e32 v18, v28
	v_mov_b32_e32 v19, v32
	v_pk_mul_f32 v[26:27], v[132:133], v[72:73]
	s_waitcnt vmcnt(12)
	v_mov_b32_e32 v134, v34
	s_waitcnt vmcnt(11)
	v_mov_b32_e32 v135, v38
	s_waitcnt vmcnt(4)
	v_fmac_f32_e32 v142, v96, v117
	v_fmac_f32_e32 v20, v98, v117
	s_waitcnt vmcnt(3)
	v_fmac_f32_e32 v142, v100, v122
	v_fmac_f32_e32 v20, v102, v122
	s_waitcnt vmcnt(2)
	v_fmac_f32_e32 v142, v104, v121
	v_fmac_f32_e32 v20, v106, v121
	s_waitcnt vmcnt(1)
	v_fmac_f32_e32 v142, v124, v120
	v_fmac_f32_e32 v20, v126, v120
	s_waitcnt vmcnt(0)
	v_fmac_f32_e32 v142, v128, v119
	v_fmac_f32_e32 v23, v97, v117
	v_pk_mul_f32 v[18:19], v[18:19], v[72:73]
	v_fmac_f32_e32 v20, v130, v119
	v_add_f32_e32 v24, v142, v26
	v_mov_b32_e32 v38, v35
	v_pk_mul_f32 v[34:35], v[134:135], v[74:75]
	v_fmac_f32_e32 v23, v101, v122
	v_add_f32_e32 v18, v18, v20
	v_add_f32_e32 v20, v24, v27
	v_mov_b32_e32 v136, v42
	v_mov_b32_e32 v137, v46
	v_fmac_f32_e32 v23, v105, v121
	v_add_f32_e32 v20, v20, v34
	v_mov_b32_e32 v46, v43
	v_pk_mul_f32 v[42:43], v[136:137], v[78:79]
	v_fmac_f32_e32 v23, v125, v120
	v_add_f32_e32 v20, v20, v35
	v_mov_b32_e32 v138, v50
	v_mov_b32_e32 v139, v54
	v_pk_mul_f32 v[30:31], v[30:31], v[72:73]
	v_fmac_f32_e32 v23, v129, v119
	v_add_f32_e32 v20, v20, v42
	v_mov_b32_e32 v54, v51
	v_pk_mul_f32 v[50:51], v[138:139], v[80:81]
	v_add_f32_e32 v23, v30, v23
	v_add_f32_e32 v20, v20, v43
	v_mov_b32_e32 v140, v58
	v_mov_b32_e32 v141, v62
	v_pk_mul_f32 v[38:39], v[38:39], v[74:75]
	v_add_f32_e32 v23, v31, v23
	v_add_f32_e32 v20, v20, v50
	v_mov_b32_e32 v62, v59
	v_pk_mul_f32 v[58:59], v[140:141], v[82:83]
	v_add_f32_e32 v23, v38, v23
	v_add_f32_e32 v20, v20, v51
	v_pk_mul_f32 v[46:47], v[46:47], v[78:79]
	v_add_f32_e32 v23, v39, v23
	v_add_f32_e32 v20, v20, v58
	v_add_f32_e32 v23, v46, v23
	v_add_f32_e32 v20, v20, v59
	v_pk_mul_f32 v[54:55], v[54:55], v[80:81]
	v_add_f32_e32 v23, v47, v23
	v_mul_f32_e64 v24, |v20|, s25
	v_add_f32_e32 v23, v54, v23
	v_exp_f32_e32 v24, v24
	v_pk_mul_f32 v[62:63], v[62:63], v[82:83]
	v_add_f32_e32 v23, v55, v23
	v_add_f32_e32 v23, v62, v23
	v_add_f32_e32 v23, v63, v23
	v_mul_f32_e64 v26, |v23|, s25
	v_add_f32_e32 v27, v19, v18
	v_add_f32_e32 v19, 1.0, v24
	v_exp_f32_e32 v26, v26
	v_cmp_gt_f32_e32 vcc, s26, v19
	v_min_f32_e32 v18, 0, v20
	v_mov_b32_e32 v22, v36
	v_cndmask_b32_e64 v24, 0, 32, vcc
	v_ldexp_f32 v19, v19, v24
	v_log_f32_e32 v24, v19
	v_add_f32_e32 v20, 1.0, v26
	v_cmp_gt_f32_e64 s[0:1], s26, v20
	v_min_f32_e32 v19, 0, v23
	v_cndmask_b32_e32 v23, 0, v112, vcc
	v_cndmask_b32_e64 v26, 0, 32, s[0:1]
	v_ldexp_f32 v20, v20, v26
	v_mul_f32_e32 v26, 0x3f317217, v24
	v_fma_f32 v26, v24, s27, -v26
	v_fmac_f32_e32 v26, 0x3377d1cf, v24
	v_fmac_f32_e32 v26, 0x3f317217, v24
	v_cmp_lt_f32_e64 vcc, |v24|, s28
	v_log_f32_e32 v20, v20
	v_fmac_f32_e32 v21, v25, v118
	v_cndmask_b32_e32 v24, v24, v26, vcc
	v_sub_f32_e32 v26, v24, v23
	v_mov_b32_e32 v23, v40
	v_pk_mul_f32 v[22:23], v[22:23], v[74:75]
	v_mul_f32_e32 v28, 0x3f317217, v20
	v_add_f32_e32 v22, v22, v27
	v_add_f32_e32 v24, v23, v22
	v_mov_b32_e32 v22, v44
	v_mov_b32_e32 v23, v48
	v_pk_mul_f32 v[22:23], v[22:23], v[78:79]
	v_fma_f32 v28, v20, s27, -v28
	v_add_f32_e32 v22, v22, v24
	v_add_f32_e32 v24, v23, v22
	v_mov_b32_e32 v22, v52
	v_mov_b32_e32 v23, v56
	v_pk_mul_f32 v[22:23], v[22:23], v[80:81]
	v_fmac_f32_e32 v28, 0x3377d1cf, v20
	v_add_f32_e32 v22, v22, v24
	v_add_f32_e32 v24, v23, v22
	v_mov_b32_e32 v22, v60
	v_mov_b32_e32 v23, v64
	v_pk_mul_f32 v[22:23], v[22:23], v[82:83]
	v_fmac_f32_e32 v28, 0x3f317217, v20
	v_add_f32_e32 v22, v22, v24
	v_add_f32_e32 v22, v23, v22
	v_mul_f32_e64 v23, |v22|, s25
	v_exp_f32_e32 v23, v23
	v_cmp_lt_f32_e64 vcc, |v20|, s28
	v_cndmask_b32_e64 v24, 0, v112, s[0:1]
	v_fmac_f32_e32 v21, v99, v117
	v_cndmask_b32_e32 v20, v20, v28, vcc
	v_sub_f32_e32 v27, v20, v24
	v_add_f32_e32 v20, 1.0, v23
	v_fmac_f32_e32 v21, v103, v122
	v_cmp_gt_f32_e32 vcc, s26, v20
	v_fmac_f32_e32 v21, v107, v121
	v_pk_add_f32 v[18:19], v[18:19], v[26:27] neg_lo:[0,1] neg_hi:[0,1]
	v_cndmask_b32_e64 v23, 0, 32, vcc
	v_fmac_f32_e32 v21, v127, v120
	v_mov_b32_e32 v32, v29
	v_ldexp_f32 v20, v20, v23
	v_pk_mul_f32 v[96:97], v[18:19], s[4:5] op_sel_hi:[1,0]
	v_min_f32_e32 v18, 0, v22
	v_fmac_f32_e32 v21, v131, v119
	v_pk_mul_f32 v[22:23], v[32:33], v[72:73]
	v_log_f32_e32 v24, v20
	v_add_f32_e32 v20, v22, v21
	v_mov_b32_e32 v40, v37
	v_add_f32_e32 v22, v23, v20
	v_pk_mul_f32 v[20:21], v[40:41], v[74:75]
	v_mov_b32_e32 v48, v45
	v_add_f32_e32 v20, v20, v22
	v_add_f32_e32 v22, v21, v20
	v_pk_mul_f32 v[20:21], v[48:49], v[78:79]
	v_mov_b32_e32 v56, v53
	v_add_f32_e32 v20, v20, v22
	v_add_f32_e32 v22, v21, v20
	v_pk_mul_f32 v[20:21], v[56:57], v[80:81]
	v_mov_b32_e32 v64, v61
	v_add_f32_e32 v20, v20, v22
	v_add_f32_e32 v22, v21, v20
	v_pk_mul_f32 v[20:21], v[64:65], v[82:83]
	v_mul_f32_e32 v19, 0x3f317217, v24
	v_add_f32_e32 v20, v20, v22
	v_add_f32_e32 v21, v21, v20
	v_mul_f32_e64 v20, |v21|, s25
	v_exp_f32_e32 v20, v20
	v_fma_f32 v19, v24, s27, -v19
	v_fmac_f32_e32 v19, 0x3377d1cf, v24
	v_fmac_f32_e32 v19, 0x3f317217, v24
	v_cmp_lt_f32_e64 s[0:1], |v24|, s28
	v_add_f32_e32 v20, 1.0, v20
	s_nop 0
	v_cndmask_b32_e64 v19, v24, v19, s[0:1]
	v_cmp_gt_f32_e64 s[0:1], s26, v20
	s_nop 1
	v_cndmask_b32_e64 v22, 0, 32, s[0:1]
	v_ldexp_f32 v20, v20, v22
	v_log_f32_e32 v22, v20
	v_cndmask_b32_e32 v20, 0, v112, vcc
	v_sub_f32_e32 v20, v19, v20
	v_min_f32_e32 v19, 0, v21
	v_mul_f32_e32 v21, 0x3f317217, v22
	v_fma_f32 v21, v22, s27, -v21
	v_fmac_f32_e32 v21, 0x3377d1cf, v22
	v_fmac_f32_e32 v21, 0x3f317217, v22
	v_cmp_lt_f32_e64 vcc, |v22|, s28
	s_nop 1
	v_cndmask_b32_e32 v21, v22, v21, vcc
	v_cndmask_b32_e64 v22, 0, v112, s[0:1]
	v_sub_f32_e32 v21, v21, v22
	v_pk_add_f32 v[18:19], v[18:19], v[20:21] neg_lo:[0,1] neg_hi:[0,1]
	s_nop 0
	v_pk_mul_f32 v[98:99], v[18:19], s[4:5] op_sel_hi:[1,0]
	global_load_dwordx4 v[18:21], v123, s[44:45] offset:80
	global_load_dwordx4 v[22:25], v123, s[42:43] offset:80
	global_load_dwordx4 v[26:29], v123, s[42:43] offset:3152
	global_load_dwordx4 v[30:33], v123, s[42:43] offset:3664
	global_load_dwordx4 v[34:37], v111, s[8:9] offset:80
	global_load_dwordx4 v[38:41], v111, s[8:9] offset:592
	global_load_dwordx4 v[42:45], v111, s[8:9] offset:1104
	global_load_dwordx4 v[46:49], v111, s[8:9] offset:1616
	global_load_dwordx4 v[50:53], v111, s[8:9] offset:2128
	global_load_dwordx4 v[54:57], v111, s[8:9] offset:2640
	global_load_dwordx4 v[58:61], v111, s[8:9] offset:3152
	global_load_dwordx4 v[62:65], v111, s[8:9] offset:3664
	global_load_dwordx4 v[100:103], v123, s[42:43] offset:592
	global_load_dwordx4 v[104:107], v123, s[42:43] offset:1104
	global_load_dwordx4 v[124:127], v123, s[42:43] offset:1616
	global_load_dwordx4 v[128:131], v123, s[42:43] offset:2128
	global_load_dwordx4 v[132:135], v123, s[42:43] offset:2640
	s_waitcnt vmcnt(15)
	v_fma_f32 v146, v22, v118, v18
	v_fma_f32 v20, v24, v118, v20
	s_waitcnt vmcnt(14)
	v_mov_b32_e32 v136, v26
	s_waitcnt vmcnt(13)
	v_mov_b32_e32 v137, v30
	v_fma_f32 v23, v23, v118, v19
	v_mov_b32_e32 v30, v27
	v_mov_b32_e32 v18, v28
	v_mov_b32_e32 v19, v32
	v_pk_mul_f32 v[26:27], v[136:137], v[72:73]
	s_waitcnt vmcnt(12)
	v_mov_b32_e32 v138, v34
	s_waitcnt vmcnt(11)
	v_mov_b32_e32 v139, v38
	s_waitcnt vmcnt(4)
	v_fmac_f32_e32 v146, v100, v117
	v_fmac_f32_e32 v20, v102, v117
	s_waitcnt vmcnt(3)
	v_fmac_f32_e32 v146, v104, v122
	v_fmac_f32_e32 v20, v106, v122
	s_waitcnt vmcnt(2)
	v_fmac_f32_e32 v146, v124, v121
	v_fmac_f32_e32 v20, v126, v121
	s_waitcnt vmcnt(1)
	v_fmac_f32_e32 v146, v128, v120
	v_fmac_f32_e32 v20, v130, v120
	s_waitcnt vmcnt(0)
	v_fmac_f32_e32 v146, v132, v119
	v_fmac_f32_e32 v23, v101, v117
	v_pk_mul_f32 v[18:19], v[18:19], v[72:73]
	v_fmac_f32_e32 v20, v134, v119
	v_add_f32_e32 v24, v146, v26
	v_mov_b32_e32 v38, v35
	v_pk_mul_f32 v[34:35], v[138:139], v[74:75]
	v_fmac_f32_e32 v23, v105, v122
	v_add_f32_e32 v18, v18, v20
	v_add_f32_e32 v20, v24, v27
	v_mov_b32_e32 v140, v42
	v_mov_b32_e32 v141, v46
	v_fmac_f32_e32 v23, v125, v121
	v_add_f32_e32 v20, v20, v34
	v_mov_b32_e32 v46, v43
	v_pk_mul_f32 v[42:43], v[140:141], v[78:79]
	v_fmac_f32_e32 v23, v129, v120
	v_add_f32_e32 v20, v20, v35
	v_mov_b32_e32 v142, v50
	v_mov_b32_e32 v143, v54
	v_pk_mul_f32 v[30:31], v[30:31], v[72:73]
	v_fmac_f32_e32 v23, v133, v119
	v_add_f32_e32 v20, v20, v42
	v_mov_b32_e32 v54, v51
	v_pk_mul_f32 v[50:51], v[142:143], v[80:81]
	v_add_f32_e32 v23, v30, v23
	v_add_f32_e32 v20, v20, v43
	v_mov_b32_e32 v144, v58
	v_mov_b32_e32 v145, v62
	v_pk_mul_f32 v[38:39], v[38:39], v[74:75]
	v_add_f32_e32 v23, v31, v23
	v_add_f32_e32 v20, v20, v50
	v_mov_b32_e32 v62, v59
	v_pk_mul_f32 v[58:59], v[144:145], v[82:83]
	v_add_f32_e32 v23, v38, v23
	v_add_f32_e32 v20, v20, v51
	v_pk_mul_f32 v[46:47], v[46:47], v[78:79]
	v_add_f32_e32 v23, v39, v23
	v_add_f32_e32 v20, v20, v58
	v_add_f32_e32 v23, v46, v23
	v_add_f32_e32 v20, v20, v59
	v_pk_mul_f32 v[54:55], v[54:55], v[80:81]
	v_add_f32_e32 v23, v47, v23
	v_mul_f32_e64 v24, |v20|, s25
	v_add_f32_e32 v23, v54, v23
	v_exp_f32_e32 v24, v24
	v_pk_mul_f32 v[62:63], v[62:63], v[82:83]
	v_add_f32_e32 v23, v55, v23
	v_add_f32_e32 v23, v62, v23
	v_add_f32_e32 v23, v63, v23
	v_mul_f32_e64 v26, |v23|, s25
	v_add_f32_e32 v27, v19, v18
	v_add_f32_e32 v19, 1.0, v24
	v_exp_f32_e32 v26, v26
	v_cmp_gt_f32_e32 vcc, s26, v19
	v_min_f32_e32 v18, 0, v20
	v_mov_b32_e32 v22, v36
	v_cndmask_b32_e64 v24, 0, 32, vcc
	v_ldexp_f32 v19, v19, v24
	v_log_f32_e32 v24, v19
	v_add_f32_e32 v20, 1.0, v26
	v_cmp_gt_f32_e64 s[0:1], s26, v20
	v_min_f32_e32 v19, 0, v23
	v_cndmask_b32_e32 v23, 0, v112, vcc
	v_cndmask_b32_e64 v26, 0, 32, s[0:1]
	v_ldexp_f32 v20, v20, v26
	v_mul_f32_e32 v26, 0x3f317217, v24
	v_fma_f32 v26, v24, s27, -v26
	v_fmac_f32_e32 v26, 0x3377d1cf, v24
	v_fmac_f32_e32 v26, 0x3f317217, v24
	v_cmp_lt_f32_e64 vcc, |v24|, s28
	v_log_f32_e32 v20, v20
	v_fmac_f32_e32 v21, v25, v118
	v_cndmask_b32_e32 v24, v24, v26, vcc
	v_sub_f32_e32 v26, v24, v23
	v_mov_b32_e32 v23, v40
	v_pk_mul_f32 v[22:23], v[22:23], v[74:75]
	v_mul_f32_e32 v28, 0x3f317217, v20
	v_add_f32_e32 v22, v22, v27
	v_add_f32_e32 v24, v23, v22
	v_mov_b32_e32 v22, v44
	v_mov_b32_e32 v23, v48
	v_pk_mul_f32 v[22:23], v[22:23], v[78:79]
	v_fma_f32 v28, v20, s27, -v28
	v_add_f32_e32 v22, v22, v24
	v_add_f32_e32 v24, v23, v22
	v_mov_b32_e32 v22, v52
	v_mov_b32_e32 v23, v56
	v_pk_mul_f32 v[22:23], v[22:23], v[80:81]
	v_fmac_f32_e32 v28, 0x3377d1cf, v20
	v_add_f32_e32 v22, v22, v24
	v_add_f32_e32 v24, v23, v22
	v_mov_b32_e32 v22, v60
	v_mov_b32_e32 v23, v64
	v_pk_mul_f32 v[22:23], v[22:23], v[82:83]
	v_fmac_f32_e32 v28, 0x3f317217, v20
	v_add_f32_e32 v22, v22, v24
	v_add_f32_e32 v22, v23, v22
	v_mul_f32_e64 v23, |v22|, s25
	v_exp_f32_e32 v23, v23
	v_cmp_lt_f32_e64 vcc, |v20|, s28
	v_cndmask_b32_e64 v24, 0, v112, s[0:1]
	v_fmac_f32_e32 v21, v103, v117
	v_cndmask_b32_e32 v20, v20, v28, vcc
	v_sub_f32_e32 v27, v20, v24
	v_add_f32_e32 v20, 1.0, v23
	v_fmac_f32_e32 v21, v107, v122
	v_cmp_gt_f32_e32 vcc, s26, v20
	v_fmac_f32_e32 v21, v127, v121
	v_pk_add_f32 v[18:19], v[18:19], v[26:27] neg_lo:[0,1] neg_hi:[0,1]
	v_cndmask_b32_e64 v23, 0, 32, vcc
	v_fmac_f32_e32 v21, v131, v120
	v_mov_b32_e32 v32, v29
	v_ldexp_f32 v20, v20, v23
	v_pk_mul_f32 v[100:101], v[18:19], s[4:5] op_sel_hi:[1,0]
	v_min_f32_e32 v18, 0, v22
	v_fmac_f32_e32 v21, v135, v119
	v_pk_mul_f32 v[22:23], v[32:33], v[72:73]
	v_log_f32_e32 v24, v20
	v_add_f32_e32 v20, v22, v21
	v_mov_b32_e32 v40, v37
	v_add_f32_e32 v22, v23, v20
	v_pk_mul_f32 v[20:21], v[40:41], v[74:75]
	v_mov_b32_e32 v48, v45
	v_add_f32_e32 v20, v20, v22
	v_add_f32_e32 v22, v21, v20
	v_pk_mul_f32 v[20:21], v[48:49], v[78:79]
	v_mov_b32_e32 v56, v53
	v_add_f32_e32 v20, v20, v22
	v_add_f32_e32 v22, v21, v20
	v_pk_mul_f32 v[20:21], v[56:57], v[80:81]
	v_mov_b32_e32 v64, v61
	v_add_f32_e32 v20, v20, v22
	v_add_f32_e32 v22, v21, v20
	v_pk_mul_f32 v[20:21], v[64:65], v[82:83]
	v_mul_f32_e32 v19, 0x3f317217, v24
	v_add_f32_e32 v20, v20, v22
	v_add_f32_e32 v21, v21, v20
	v_mul_f32_e64 v20, |v21|, s25
	v_exp_f32_e32 v20, v20
	v_fma_f32 v19, v24, s27, -v19
	v_fmac_f32_e32 v19, 0x3377d1cf, v24
	v_fmac_f32_e32 v19, 0x3f317217, v24
	v_cmp_lt_f32_e64 s[0:1], |v24|, s28
	v_add_f32_e32 v20, 1.0, v20
	s_nop 0
	v_cndmask_b32_e64 v19, v24, v19, s[0:1]
	v_cmp_gt_f32_e64 s[0:1], s26, v20
	s_nop 1
	v_cndmask_b32_e64 v22, 0, 32, s[0:1]
	v_ldexp_f32 v20, v20, v22
	v_log_f32_e32 v22, v20
	v_cndmask_b32_e32 v20, 0, v112, vcc
	v_sub_f32_e32 v20, v19, v20
	v_min_f32_e32 v19, 0, v21
	v_mul_f32_e32 v21, 0x3f317217, v22
	v_fma_f32 v21, v22, s27, -v21
	v_fmac_f32_e32 v21, 0x3377d1cf, v22
	v_fmac_f32_e32 v21, 0x3f317217, v22
	v_cmp_lt_f32_e64 vcc, |v22|, s28
	s_nop 1
	v_cndmask_b32_e32 v21, v22, v21, vcc
	v_cndmask_b32_e64 v22, 0, v112, s[0:1]
	v_sub_f32_e32 v21, v21, v22
	v_pk_add_f32 v[18:19], v[18:19], v[20:21] neg_lo:[0,1] neg_hi:[0,1]
	s_nop 0
	v_pk_mul_f32 v[102:103], v[18:19], s[4:5] op_sel_hi:[1,0]
	global_load_dwordx4 v[18:21], v123, s[44:45] offset:96
	global_load_dwordx4 v[22:25], v123, s[42:43] offset:96
	global_load_dwordx4 v[26:29], v123, s[42:43] offset:3168
	global_load_dwordx4 v[30:33], v123, s[42:43] offset:3680
	global_load_dwordx4 v[34:37], v111, s[8:9] offset:96
	global_load_dwordx4 v[38:41], v111, s[8:9] offset:608
	global_load_dwordx4 v[42:45], v111, s[8:9] offset:1120
	global_load_dwordx4 v[46:49], v111, s[8:9] offset:1632
	global_load_dwordx4 v[50:53], v111, s[8:9] offset:2144
	global_load_dwordx4 v[54:57], v111, s[8:9] offset:2656
	global_load_dwordx4 v[58:61], v111, s[8:9] offset:3168
	global_load_dwordx4 v[62:65], v111, s[8:9] offset:3680
	global_load_dwordx4 v[104:107], v123, s[42:43] offset:608
	global_load_dwordx4 v[124:127], v123, s[42:43] offset:1120
	global_load_dwordx4 v[128:131], v123, s[42:43] offset:1632
	global_load_dwordx4 v[132:135], v123, s[42:43] offset:2144
	global_load_dwordx4 v[136:139], v123, s[42:43] offset:2656
	s_waitcnt vmcnt(15)
	v_fma_f32 v150, v22, v118, v18
	v_fma_f32 v20, v24, v118, v20
	s_waitcnt vmcnt(14)
	v_mov_b32_e32 v140, v26
	s_waitcnt vmcnt(13)
	v_mov_b32_e32 v141, v30
	v_fma_f32 v23, v23, v118, v19
	v_mov_b32_e32 v30, v27
	v_mov_b32_e32 v18, v28
	v_mov_b32_e32 v19, v32
	v_pk_mul_f32 v[26:27], v[140:141], v[72:73]
	s_waitcnt vmcnt(12)
	v_mov_b32_e32 v142, v34
	s_waitcnt vmcnt(11)
	v_mov_b32_e32 v143, v38
	s_waitcnt vmcnt(4)
	v_fmac_f32_e32 v150, v104, v117
	v_fmac_f32_e32 v20, v106, v117
	s_waitcnt vmcnt(3)
	v_fmac_f32_e32 v150, v124, v122
	v_fmac_f32_e32 v20, v126, v122
	s_waitcnt vmcnt(2)
	v_fmac_f32_e32 v150, v128, v121
	v_fmac_f32_e32 v20, v130, v121
	s_waitcnt vmcnt(1)
	v_fmac_f32_e32 v150, v132, v120
	v_fmac_f32_e32 v20, v134, v120
	s_waitcnt vmcnt(0)
	v_fmac_f32_e32 v150, v136, v119
	v_fmac_f32_e32 v23, v105, v117
	v_pk_mul_f32 v[18:19], v[18:19], v[72:73]
	v_fmac_f32_e32 v20, v138, v119
	v_add_f32_e32 v24, v150, v26
	v_mov_b32_e32 v38, v35
	v_pk_mul_f32 v[34:35], v[142:143], v[74:75]
	v_fmac_f32_e32 v23, v125, v122
	v_add_f32_e32 v18, v18, v20
	v_add_f32_e32 v20, v24, v27
	v_mov_b32_e32 v144, v42
	v_mov_b32_e32 v145, v46
	v_fmac_f32_e32 v23, v129, v121
	v_add_f32_e32 v20, v20, v34
	v_mov_b32_e32 v46, v43
	v_pk_mul_f32 v[42:43], v[144:145], v[78:79]
	v_fmac_f32_e32 v23, v133, v120
	v_add_f32_e32 v20, v20, v35
	v_mov_b32_e32 v146, v50
	v_mov_b32_e32 v147, v54
	v_pk_mul_f32 v[30:31], v[30:31], v[72:73]
	v_fmac_f32_e32 v23, v137, v119
	v_add_f32_e32 v20, v20, v42
	v_mov_b32_e32 v54, v51
	v_pk_mul_f32 v[50:51], v[146:147], v[80:81]
	v_add_f32_e32 v23, v30, v23
	v_add_f32_e32 v20, v20, v43
	v_mov_b32_e32 v148, v58
	v_mov_b32_e32 v149, v62
	v_pk_mul_f32 v[38:39], v[38:39], v[74:75]
	v_add_f32_e32 v23, v31, v23
	v_add_f32_e32 v20, v20, v50
	v_mov_b32_e32 v62, v59
	v_pk_mul_f32 v[58:59], v[148:149], v[82:83]
	v_add_f32_e32 v23, v38, v23
	v_add_f32_e32 v20, v20, v51
	v_pk_mul_f32 v[46:47], v[46:47], v[78:79]
	v_add_f32_e32 v23, v39, v23
	v_add_f32_e32 v20, v20, v58
	v_add_f32_e32 v23, v46, v23
	v_add_f32_e32 v20, v20, v59
	v_pk_mul_f32 v[54:55], v[54:55], v[80:81]
	v_add_f32_e32 v23, v47, v23
	v_mul_f32_e64 v24, |v20|, s25
	v_add_f32_e32 v23, v54, v23
	v_exp_f32_e32 v24, v24
	v_pk_mul_f32 v[62:63], v[62:63], v[82:83]
	v_add_f32_e32 v23, v55, v23
	v_add_f32_e32 v23, v62, v23
	v_add_f32_e32 v23, v63, v23
	v_mul_f32_e64 v26, |v23|, s25
	v_add_f32_e32 v27, v19, v18
	v_add_f32_e32 v19, 1.0, v24
	v_exp_f32_e32 v26, v26
	v_cmp_gt_f32_e32 vcc, s26, v19
	v_min_f32_e32 v18, 0, v20
	v_mov_b32_e32 v22, v36
	v_cndmask_b32_e64 v24, 0, 32, vcc
	v_ldexp_f32 v19, v19, v24
	v_log_f32_e32 v24, v19
	v_add_f32_e32 v20, 1.0, v26
	v_cmp_gt_f32_e64 s[0:1], s26, v20
	v_min_f32_e32 v19, 0, v23
	v_cndmask_b32_e32 v23, 0, v112, vcc
	v_cndmask_b32_e64 v26, 0, 32, s[0:1]
	v_ldexp_f32 v20, v20, v26
	v_mul_f32_e32 v26, 0x3f317217, v24
	v_fma_f32 v26, v24, s27, -v26
	v_fmac_f32_e32 v26, 0x3377d1cf, v24
	v_fmac_f32_e32 v26, 0x3f317217, v24
	v_cmp_lt_f32_e64 vcc, |v24|, s28
	v_log_f32_e32 v20, v20
	v_fmac_f32_e32 v21, v25, v118
	v_cndmask_b32_e32 v24, v24, v26, vcc
	v_sub_f32_e32 v26, v24, v23
	v_mov_b32_e32 v23, v40
	v_pk_mul_f32 v[22:23], v[22:23], v[74:75]
	v_mul_f32_e32 v28, 0x3f317217, v20
	v_add_f32_e32 v22, v22, v27
	v_add_f32_e32 v24, v23, v22
	v_mov_b32_e32 v22, v44
	v_mov_b32_e32 v23, v48
	v_pk_mul_f32 v[22:23], v[22:23], v[78:79]
	v_fma_f32 v28, v20, s27, -v28
	v_add_f32_e32 v22, v22, v24
	v_add_f32_e32 v24, v23, v22
	v_mov_b32_e32 v22, v52
	v_mov_b32_e32 v23, v56
	v_pk_mul_f32 v[22:23], v[22:23], v[80:81]
	v_fmac_f32_e32 v28, 0x3377d1cf, v20
	v_add_f32_e32 v22, v22, v24
	v_add_f32_e32 v24, v23, v22
	v_mov_b32_e32 v22, v60
	v_mov_b32_e32 v23, v64
	v_pk_mul_f32 v[22:23], v[22:23], v[82:83]
	v_fmac_f32_e32 v28, 0x3f317217, v20
	v_add_f32_e32 v22, v22, v24
	v_add_f32_e32 v22, v23, v22
	v_mul_f32_e64 v23, |v22|, s25
	v_exp_f32_e32 v23, v23
	v_cmp_lt_f32_e64 vcc, |v20|, s28
	v_cndmask_b32_e64 v24, 0, v112, s[0:1]
	v_fmac_f32_e32 v21, v107, v117
	v_cndmask_b32_e32 v20, v20, v28, vcc
	v_sub_f32_e32 v27, v20, v24
	v_add_f32_e32 v20, 1.0, v23
	v_fmac_f32_e32 v21, v127, v122
	v_cmp_gt_f32_e32 vcc, s26, v20
	v_fmac_f32_e32 v21, v131, v121
	v_pk_add_f32 v[18:19], v[18:19], v[26:27] neg_lo:[0,1] neg_hi:[0,1]
	v_cndmask_b32_e64 v23, 0, 32, vcc
	v_fmac_f32_e32 v21, v135, v120
	v_mov_b32_e32 v32, v29
	v_ldexp_f32 v20, v20, v23
	v_pk_mul_f32 v[104:105], v[18:19], s[4:5] op_sel_hi:[1,0]
	v_min_f32_e32 v18, 0, v22
	v_fmac_f32_e32 v21, v139, v119
	v_pk_mul_f32 v[22:23], v[32:33], v[72:73]
	v_log_f32_e32 v24, v20
	v_add_f32_e32 v20, v22, v21
	v_mov_b32_e32 v40, v37
	v_add_f32_e32 v22, v23, v20
	v_pk_mul_f32 v[20:21], v[40:41], v[74:75]
	v_mov_b32_e32 v48, v45
	v_add_f32_e32 v20, v20, v22
	v_add_f32_e32 v22, v21, v20
	v_pk_mul_f32 v[20:21], v[48:49], v[78:79]
	v_mov_b32_e32 v56, v53
	v_add_f32_e32 v20, v20, v22
	v_add_f32_e32 v22, v21, v20
	v_pk_mul_f32 v[20:21], v[56:57], v[80:81]
	v_mov_b32_e32 v64, v61
	v_add_f32_e32 v20, v20, v22
	v_add_f32_e32 v22, v21, v20
	v_pk_mul_f32 v[20:21], v[64:65], v[82:83]
	v_mul_f32_e32 v19, 0x3f317217, v24
	v_add_f32_e32 v20, v20, v22
	v_add_f32_e32 v21, v21, v20
	v_mul_f32_e64 v20, |v21|, s25
	v_exp_f32_e32 v20, v20
	v_fma_f32 v19, v24, s27, -v19
	v_fmac_f32_e32 v19, 0x3377d1cf, v24
	v_fmac_f32_e32 v19, 0x3f317217, v24
	v_cmp_lt_f32_e64 s[0:1], |v24|, s28
	v_add_f32_e32 v20, 1.0, v20
	s_nop 0
	v_cndmask_b32_e64 v19, v24, v19, s[0:1]
	v_cmp_gt_f32_e64 s[0:1], s26, v20
	s_nop 1
	v_cndmask_b32_e64 v22, 0, 32, s[0:1]
	v_ldexp_f32 v20, v20, v22
	v_log_f32_e32 v22, v20
	v_cndmask_b32_e32 v20, 0, v112, vcc
	v_sub_f32_e32 v20, v19, v20
	v_min_f32_e32 v19, 0, v21
	v_mul_f32_e32 v21, 0x3f317217, v22
	v_fma_f32 v21, v22, s27, -v21
	v_fmac_f32_e32 v21, 0x3377d1cf, v22
	v_fmac_f32_e32 v21, 0x3f317217, v22
	v_cmp_lt_f32_e64 vcc, |v22|, s28
	s_nop 1
	v_cndmask_b32_e32 v21, v22, v21, vcc
	v_cndmask_b32_e64 v22, 0, v112, s[0:1]
	v_sub_f32_e32 v21, v21, v22
	v_pk_add_f32 v[18:19], v[18:19], v[20:21] neg_lo:[0,1] neg_hi:[0,1]
	s_nop 0
	v_pk_mul_f32 v[106:107], v[18:19], s[4:5] op_sel_hi:[1,0]
	global_load_dwordx4 v[18:21], v123, s[44:45] offset:112
	global_load_dwordx4 v[22:25], v123, s[42:43] offset:112
	global_load_dwordx4 v[26:29], v123, s[42:43] offset:3184
	global_load_dwordx4 v[30:33], v123, s[42:43] offset:3696
	global_load_dwordx4 v[34:37], v111, s[8:9] offset:112
	global_load_dwordx4 v[38:41], v111, s[8:9] offset:624
	global_load_dwordx4 v[42:45], v111, s[8:9] offset:1136
	global_load_dwordx4 v[46:49], v111, s[8:9] offset:1648
	global_load_dwordx4 v[50:53], v111, s[8:9] offset:2160
	global_load_dwordx4 v[54:57], v111, s[8:9] offset:2672
	global_load_dwordx4 v[58:61], v111, s[8:9] offset:3184
	global_load_dwordx4 v[62:65], v111, s[8:9] offset:3696
	global_load_dwordx4 v[124:127], v123, s[42:43] offset:624
	global_load_dwordx4 v[128:131], v123, s[42:43] offset:1136
	global_load_dwordx4 v[132:135], v123, s[42:43] offset:1648
	global_load_dwordx4 v[136:139], v123, s[42:43] offset:2160
	global_load_dwordx4 v[140:143], v123, s[42:43] offset:2672
	s_waitcnt vmcnt(15)
	v_fma_f32 v123, v22, v118, v18
	v_fma_f32 v20, v24, v118, v20
	s_waitcnt vmcnt(14)
	v_mov_b32_e32 v144, v26
	s_waitcnt vmcnt(13)
	v_mov_b32_e32 v145, v30
	v_fma_f32 v23, v23, v118, v19
	v_mov_b32_e32 v30, v27
	v_mov_b32_e32 v18, v28
	v_mov_b32_e32 v19, v32
	v_pk_mul_f32 v[26:27], v[144:145], v[72:73]
	s_waitcnt vmcnt(12)
	v_mov_b32_e32 v146, v34
	s_waitcnt vmcnt(11)
	v_mov_b32_e32 v147, v38
	s_waitcnt vmcnt(4)
	v_fmac_f32_e32 v123, v124, v117
	v_fmac_f32_e32 v20, v126, v117
	s_waitcnt vmcnt(3)
	v_fmac_f32_e32 v123, v128, v122
	v_fmac_f32_e32 v20, v130, v122
	s_waitcnt vmcnt(2)
	v_fmac_f32_e32 v123, v132, v121
	v_fmac_f32_e32 v20, v134, v121
	s_waitcnt vmcnt(1)
	v_fmac_f32_e32 v123, v136, v120
	v_fmac_f32_e32 v20, v138, v120
	s_waitcnt vmcnt(0)
	v_fmac_f32_e32 v123, v140, v119
	v_fmac_f32_e32 v23, v125, v117
	v_pk_mul_f32 v[18:19], v[18:19], v[72:73]
	v_fmac_f32_e32 v20, v142, v119
	v_add_f32_e32 v24, v123, v26
	v_mov_b32_e32 v38, v35
	v_pk_mul_f32 v[34:35], v[146:147], v[74:75]
	v_fmac_f32_e32 v23, v129, v122
	v_add_f32_e32 v18, v18, v20
	v_add_f32_e32 v20, v24, v27
	v_mov_b32_e32 v148, v42
	v_mov_b32_e32 v149, v46
	v_fmac_f32_e32 v23, v133, v121
	v_add_f32_e32 v20, v20, v34
	v_mov_b32_e32 v46, v43
	v_pk_mul_f32 v[42:43], v[148:149], v[78:79]
	v_fmac_f32_e32 v23, v137, v120
	v_add_f32_e32 v20, v20, v35
	v_mov_b32_e32 v150, v50
	v_mov_b32_e32 v151, v54
	v_pk_mul_f32 v[30:31], v[30:31], v[72:73]
	v_fmac_f32_e32 v23, v141, v119
	v_add_f32_e32 v20, v20, v42
	v_mov_b32_e32 v54, v51
	v_pk_mul_f32 v[50:51], v[150:151], v[80:81]
	v_add_f32_e32 v23, v30, v23
	v_add_f32_e32 v20, v20, v43
	v_mov_b32_e32 v152, v58
	v_mov_b32_e32 v153, v62
	v_pk_mul_f32 v[38:39], v[38:39], v[74:75]
	v_add_f32_e32 v23, v31, v23
	v_add_f32_e32 v20, v20, v50
	v_mov_b32_e32 v62, v59
	v_pk_mul_f32 v[58:59], v[152:153], v[82:83]
	v_add_f32_e32 v23, v38, v23
	v_add_f32_e32 v20, v20, v51
	v_pk_mul_f32 v[46:47], v[46:47], v[78:79]
	v_add_f32_e32 v23, v39, v23
	v_add_f32_e32 v20, v20, v58
	v_add_f32_e32 v23, v46, v23
	v_add_f32_e32 v20, v20, v59
	v_pk_mul_f32 v[54:55], v[54:55], v[80:81]
	v_add_f32_e32 v23, v47, v23
	v_mul_f32_e64 v24, |v20|, s25
	v_add_f32_e32 v23, v54, v23
	v_exp_f32_e32 v24, v24
	v_pk_mul_f32 v[62:63], v[62:63], v[82:83]
	v_add_f32_e32 v23, v55, v23
	v_add_f32_e32 v23, v62, v23
	v_add_f32_e32 v23, v63, v23
	v_mul_f32_e64 v26, |v23|, s25
	v_add_f32_e32 v27, v19, v18
	v_add_f32_e32 v19, 1.0, v24
	v_exp_f32_e32 v26, v26
	v_cmp_gt_f32_e32 vcc, s26, v19
	v_min_f32_e32 v18, 0, v20
	v_mov_b32_e32 v22, v36
	v_cndmask_b32_e64 v24, 0, 32, vcc
	v_ldexp_f32 v19, v19, v24
	v_log_f32_e32 v24, v19
	v_add_f32_e32 v20, 1.0, v26
	v_cmp_gt_f32_e64 s[0:1], s26, v20
	v_min_f32_e32 v19, 0, v23
	v_cndmask_b32_e32 v23, 0, v112, vcc
	v_cndmask_b32_e64 v26, 0, 32, s[0:1]
	v_ldexp_f32 v20, v20, v26
	v_mul_f32_e32 v26, 0x3f317217, v24
	v_fma_f32 v26, v24, s27, -v26
	v_fmac_f32_e32 v26, 0x3377d1cf, v24
	v_fmac_f32_e32 v26, 0x3f317217, v24
	v_cmp_lt_f32_e64 vcc, |v24|, s28
	v_log_f32_e32 v20, v20
	v_fmac_f32_e32 v21, v25, v118
	v_cndmask_b32_e32 v24, v24, v26, vcc
	v_sub_f32_e32 v26, v24, v23
	v_mov_b32_e32 v23, v40
	v_pk_mul_f32 v[22:23], v[22:23], v[74:75]
	v_mul_f32_e32 v28, 0x3f317217, v20
	v_add_f32_e32 v22, v22, v27
	v_add_f32_e32 v24, v23, v22
	v_mov_b32_e32 v22, v44
	v_mov_b32_e32 v23, v48
	v_pk_mul_f32 v[22:23], v[22:23], v[78:79]
	v_fma_f32 v28, v20, s27, -v28
	v_add_f32_e32 v22, v22, v24
	v_add_f32_e32 v24, v23, v22
	v_mov_b32_e32 v22, v52
	v_mov_b32_e32 v23, v56
	v_pk_mul_f32 v[22:23], v[22:23], v[80:81]
	v_fmac_f32_e32 v28, 0x3377d1cf, v20
	v_add_f32_e32 v22, v22, v24
	v_add_f32_e32 v24, v23, v22
	v_mov_b32_e32 v22, v60
	v_mov_b32_e32 v23, v64
	v_pk_mul_f32 v[22:23], v[22:23], v[82:83]
	v_fmac_f32_e32 v28, 0x3f317217, v20
	v_add_f32_e32 v22, v22, v24
	v_add_f32_e32 v24, v23, v22
	v_mul_f32_e64 v22, |v24|, s25
	v_exp_f32_e32 v22, v22
	v_cmp_lt_f32_e64 vcc, |v20|, s28
	v_cndmask_b32_e64 v23, 0, v112, s[0:1]
	v_fmac_f32_e32 v21, v127, v117
	v_cndmask_b32_e32 v20, v20, v28, vcc
	v_sub_f32_e32 v27, v20, v23
	v_add_f32_e32 v20, 1.0, v22
	v_fmac_f32_e32 v21, v131, v122
	v_cmp_gt_f32_e32 vcc, s26, v20
	v_fmac_f32_e32 v21, v135, v121
	v_pk_add_f32 v[18:19], v[18:19], v[26:27] neg_lo:[0,1] neg_hi:[0,1]
	v_cndmask_b32_e64 v22, 0, 32, vcc
	v_fmac_f32_e32 v21, v139, v120
	v_mov_b32_e32 v32, v29
	v_ldexp_f32 v20, v20, v22
	v_pk_mul_f32 v[22:23], v[18:19], s[4:5] op_sel_hi:[1,0]
	v_min_f32_e32 v18, 0, v24
	v_fmac_f32_e32 v21, v143, v119
	v_pk_mul_f32 v[24:25], v[32:33], v[72:73]
	v_log_f32_e32 v28, v20
	v_add_f32_e32 v20, v24, v21
	v_mov_b32_e32 v40, v37
	v_add_f32_e32 v24, v25, v20
	v_pk_mul_f32 v[20:21], v[40:41], v[74:75]
	v_mov_b32_e32 v48, v45
	v_add_f32_e32 v20, v20, v24
	v_add_f32_e32 v24, v21, v20
	v_pk_mul_f32 v[20:21], v[48:49], v[78:79]
	v_mov_b32_e32 v56, v53
	v_add_f32_e32 v20, v20, v24
	v_add_f32_e32 v24, v21, v20
	v_pk_mul_f32 v[20:21], v[56:57], v[80:81]
	v_mov_b32_e32 v64, v61
	v_add_f32_e32 v20, v20, v24
	v_add_f32_e32 v24, v21, v20
	v_pk_mul_f32 v[20:21], v[64:65], v[82:83]
	v_mul_f32_e32 v19, 0x3f317217, v28
	v_add_f32_e32 v20, v20, v24
	v_add_f32_e32 v21, v21, v20
	v_mul_f32_e64 v20, |v21|, s25
	v_exp_f32_e32 v20, v20
	v_fma_f32 v19, v28, s27, -v19
	v_fmac_f32_e32 v19, 0x3377d1cf, v28
	v_fmac_f32_e32 v19, 0x3f317217, v28
	v_cmp_lt_f32_e64 s[0:1], |v28|, s28
	v_add_f32_e32 v20, 1.0, v20
	s_nop 0
	v_cndmask_b32_e64 v19, v28, v19, s[0:1]
	v_cmp_gt_f32_e64 s[0:1], s26, v20
	s_nop 1
	v_cndmask_b32_e64 v24, 0, 32, s[0:1]
	v_ldexp_f32 v20, v20, v24
	v_log_f32_e32 v24, v20
	v_cndmask_b32_e32 v20, 0, v112, vcc
	v_sub_f32_e32 v20, v19, v20
	v_min_f32_e32 v19, 0, v21
	v_mul_f32_e32 v21, 0x3f317217, v24
	v_fma_f32 v21, v24, s27, -v21
	v_fmac_f32_e32 v21, 0x3377d1cf, v24
	v_fmac_f32_e32 v21, 0x3f317217, v24
	v_cmp_lt_f32_e64 vcc, |v24|, s28
	s_nop 1
	v_cndmask_b32_e32 v21, v24, v21, vcc
	v_cndmask_b32_e64 v24, 0, v112, s[0:1]
	v_sub_f32_e32 v21, v21, v24
	v_pk_add_f32 v[18:19], v[18:19], v[20:21] neg_lo:[0,1] neg_hi:[0,1]
	s_nop 0
	v_pk_mul_f32 v[20:21], v[18:19], s[4:5] op_sel_hi:[1,0]
	v_and_b32_e32 v18, 64, v110
	v_add_u32_e32 v19, -1, v110
	v_cmp_lt_i32_e32 vcc, v19, v18
	s_nop 1
	v_cndmask_b32_e32 v19, v19, v110, vcc
	v_lshlrev_b32_e32 v19, 2, v19
	ds_bpermute_b32 v24, v19, v70
	ds_bpermute_b32 v25, v19, v71
	ds_bpermute_b32 v26, v19, v76
	ds_bpermute_b32 v27, v19, v77
	ds_bpermute_b32 v28, v19, v84
	ds_bpermute_b32 v29, v19, v85
	ds_bpermute_b32 v30, v19, v86
	ds_bpermute_b32 v31, v19, v87
	ds_bpermute_b32 v32, v19, v88
	ds_bpermute_b32 v33, v19, v89
	ds_bpermute_b32 v34, v19, v90
	ds_bpermute_b32 v35, v19, v91
	ds_bpermute_b32 v36, v19, v92
	ds_bpermute_b32 v37, v19, v93
	ds_bpermute_b32 v38, v19, v94
	ds_bpermute_b32 v39, v19, v95
	ds_bpermute_b32 v40, v19, v96
	ds_bpermute_b32 v41, v19, v97
	ds_bpermute_b32 v42, v19, v98
	ds_bpermute_b32 v43, v19, v99
	ds_bpermute_b32 v44, v19, v100
	ds_bpermute_b32 v45, v19, v101
	ds_bpermute_b32 v46, v19, v102
	ds_bpermute_b32 v47, v19, v103
	ds_bpermute_b32 v48, v19, v104
	ds_bpermute_b32 v49, v19, v105
	ds_bpermute_b32 v50, v19, v106
	ds_bpermute_b32 v51, v19, v107
	ds_bpermute_b32 v52, v19, v22
	ds_bpermute_b32 v53, v19, v23
	ds_bpermute_b32 v54, v19, v20
	ds_bpermute_b32 v19, v19, v21
	v_cmp_gt_i32_e32 vcc, 1, v68
	s_waitcnt lgkmcnt(6)
	v_add_f32_e32 v49, v105, v49
	s_waitcnt lgkmcnt(3)
	v_add_f32_e32 v52, v22, v52
	v_add_f32_e32 v24, v70, v24
	s_waitcnt lgkmcnt(0)
	v_add_f32_e32 v19, v21, v19
	v_cndmask_b32_e32 v19, v19, v21, vcc
	v_cndmask_b32_e32 v21, v52, v22, vcc
	v_cndmask_b32_e32 v22, v49, v105, vcc
	v_add_u32_e32 v49, -2, v110
	v_cmp_lt_i32_e64 s[0:1], v49, v18
	v_add_f32_e32 v25, v71, v25
	v_add_f32_e32 v26, v76, v26
	v_add_f32_e32 v27, v77, v27
	v_add_f32_e32 v28, v84, v28
	v_add_f32_e32 v29, v85, v29
	v_add_f32_e32 v30, v86, v30
	v_add_f32_e32 v31, v87, v31
	v_add_f32_e32 v32, v88, v32
	v_add_f32_e32 v33, v89, v33
	v_add_f32_e32 v34, v90, v34
	v_add_f32_e32 v35, v91, v35
	v_add_f32_e32 v36, v92, v36
	v_add_f32_e32 v37, v93, v37
	v_add_f32_e32 v38, v94, v38
	v_add_f32_e32 v39, v95, v39
	v_add_f32_e32 v40, v96, v40
	v_add_f32_e32 v41, v97, v41
	v_add_f32_e32 v42, v98, v42
	v_add_f32_e32 v43, v99, v43
	v_add_f32_e32 v44, v100, v44
	v_add_f32_e32 v45, v101, v45
	v_add_f32_e32 v46, v102, v46
	v_add_f32_e32 v47, v103, v47
	v_add_f32_e32 v48, v104, v48
	v_add_f32_e32 v50, v106, v50
	v_add_f32_e32 v51, v107, v51
	v_add_f32_e32 v53, v23, v53
	v_add_f32_e32 v54, v20, v54
	v_cndmask_b32_e64 v49, v49, v110, s[0:1]
	v_cndmask_b32_e32 v24, v24, v70, vcc
	v_cndmask_b32_e32 v26, v26, v76, vcc
	v_cndmask_b32_e32 v27, v27, v77, vcc
	v_cndmask_b32_e32 v29, v29, v85, vcc
	v_cndmask_b32_e32 v30, v30, v86, vcc
	v_cndmask_b32_e32 v32, v32, v88, vcc
	v_cndmask_b32_e32 v33, v33, v89, vcc
	v_cndmask_b32_e32 v35, v35, v91, vcc
	v_cndmask_b32_e32 v36, v36, v92, vcc
	v_cndmask_b32_e32 v38, v38, v94, vcc
	v_cndmask_b32_e32 v39, v39, v95, vcc
	v_cndmask_b32_e32 v41, v41, v97, vcc
	v_cndmask_b32_e32 v42, v42, v98, vcc
	v_cndmask_b32_e32 v44, v44, v100, vcc
	v_cndmask_b32_e32 v45, v45, v101, vcc
	v_cndmask_b32_e32 v47, v47, v103, vcc
	v_cndmask_b32_e32 v48, v48, v104, vcc
	v_cndmask_b32_e32 v50, v50, v106, vcc
	v_cndmask_b32_e32 v51, v51, v107, vcc
	v_cndmask_b32_e32 v53, v53, v23, vcc
	v_cndmask_b32_e32 v54, v54, v20, vcc
	v_cndmask_b32_e32 v46, v46, v102, vcc
	v_cndmask_b32_e32 v43, v43, v99, vcc
	v_cndmask_b32_e32 v40, v40, v96, vcc
	v_cndmask_b32_e32 v37, v37, v93, vcc
	v_cndmask_b32_e32 v34, v34, v90, vcc
	v_lshlrev_b32_e32 v49, 2, v49
	v_cndmask_b32_e32 v31, v31, v87, vcc
	v_cndmask_b32_e32 v28, v28, v84, vcc
	v_cndmask_b32_e32 v25, v25, v71, vcc
	v_cndmask_b32_e32 v55, v24, v70, vcc
	v_cndmask_b32_e32 v56, v26, v76, vcc
	v_cndmask_b32_e32 v57, v27, v77, vcc
	v_cndmask_b32_e32 v58, v29, v85, vcc
	v_cndmask_b32_e32 v59, v30, v86, vcc
	v_cndmask_b32_e32 v60, v32, v88, vcc
	v_cndmask_b32_e32 v61, v33, v89, vcc
	v_cndmask_b32_e32 v62, v35, v91, vcc
	v_cndmask_b32_e32 v63, v36, v92, vcc
	v_cndmask_b32_e32 v64, v38, v94, vcc
	v_cndmask_b32_e32 v65, v39, v95, vcc
	v_cndmask_b32_e32 v70, v41, v97, vcc
	v_cndmask_b32_e32 v72, v42, v98, vcc
	v_cndmask_b32_e32 v73, v44, v100, vcc
	v_cndmask_b32_e32 v74, v45, v101, vcc
	v_cndmask_b32_e32 v75, v47, v103, vcc
	v_cndmask_b32_e32 v76, v48, v104, vcc
	v_cndmask_b32_e32 v77, v50, v106, vcc
	v_cndmask_b32_e32 v78, v51, v107, vcc
	ds_bpermute_b32 v52, v49, v24
	ds_bpermute_b32 v71, v49, v25
	ds_bpermute_b32 v79, v49, v26
	ds_bpermute_b32 v80, v49, v27
	ds_bpermute_b32 v81, v49, v28
	ds_bpermute_b32 v82, v49, v29
	ds_bpermute_b32 v83, v49, v30
	ds_bpermute_b32 v84, v49, v31
	ds_bpermute_b32 v85, v49, v32
	ds_bpermute_b32 v86, v49, v33
	ds_bpermute_b32 v87, v49, v34
	ds_bpermute_b32 v88, v49, v35
	ds_bpermute_b32 v89, v49, v36
	ds_bpermute_b32 v90, v49, v37
	ds_bpermute_b32 v91, v49, v38
	ds_bpermute_b32 v92, v49, v39
	ds_bpermute_b32 v93, v49, v40
	ds_bpermute_b32 v94, v49, v41
	ds_bpermute_b32 v95, v49, v42
	ds_bpermute_b32 v96, v49, v43
	ds_bpermute_b32 v97, v49, v44
	ds_bpermute_b32 v98, v49, v45
	ds_bpermute_b32 v99, v49, v46
	ds_bpermute_b32 v100, v49, v47
	ds_bpermute_b32 v101, v49, v48
	ds_bpermute_b32 v102, v49, v22
	ds_bpermute_b32 v103, v49, v50
	ds_bpermute_b32 v104, v49, v51
	ds_bpermute_b32 v105, v49, v21
	ds_bpermute_b32 v106, v49, v53
	ds_bpermute_b32 v107, v49, v54
	ds_bpermute_b32 v49, v49, v19
	v_cndmask_b32_e32 v23, v53, v23, vcc
	v_cndmask_b32_e32 v20, v54, v20, vcc
	v_cmp_gt_i32_e32 vcc, 2, v68
	s_waitcnt lgkmcnt(14)
	v_add_f32_e32 v52, v24, v52
	s_waitcnt lgkmcnt(0)
	v_add_f32_e32 v49, v19, v49
	v_cndmask_b32_e32 v19, v49, v19, vcc
	v_add_u32_e32 v49, -4, v110
	v_cmp_lt_i32_e64 s[0:1], v49, v18
	v_add_f32_e32 v71, v25, v71
	v_add_f32_e32 v79, v26, v79
	v_add_f32_e32 v80, v27, v80
	v_add_f32_e32 v81, v28, v81
	v_add_f32_e32 v82, v29, v82
	v_add_f32_e32 v83, v30, v83
	v_add_f32_e32 v84, v31, v84
	v_add_f32_e32 v85, v32, v85
	v_add_f32_e32 v86, v33, v86
	v_add_f32_e32 v87, v34, v87
	v_add_f32_e32 v88, v35, v88
	v_add_f32_e32 v89, v36, v89
	v_add_f32_e32 v90, v37, v90
	v_add_f32_e32 v91, v38, v91
	v_add_f32_e32 v92, v39, v92
	v_add_f32_e32 v93, v40, v93
	v_add_f32_e32 v94, v41, v94
	v_add_f32_e32 v95, v42, v95
	v_add_f32_e32 v96, v43, v96
	v_add_f32_e32 v97, v44, v97
	v_add_f32_e32 v98, v45, v98
	v_add_f32_e32 v99, v46, v99
	v_add_f32_e32 v100, v47, v100
	v_add_f32_e32 v101, v48, v101
	v_add_f32_e32 v102, v22, v102
	v_add_f32_e32 v103, v50, v103
	v_add_f32_e32 v104, v51, v104
	v_add_f32_e32 v105, v21, v105
	v_add_f32_e32 v106, v53, v106
	v_add_f32_e32 v107, v54, v107
	v_cndmask_b32_e64 v49, v49, v110, s[0:1]
	v_cndmask_b32_e32 v24, v52, v24, vcc
	v_cndmask_b32_e32 v26, v79, v26, vcc
	v_cndmask_b32_e32 v27, v80, v27, vcc
	v_cndmask_b32_e32 v29, v82, v29, vcc
	v_cndmask_b32_e32 v30, v83, v30, vcc
	v_cndmask_b32_e32 v32, v85, v32, vcc
	v_cndmask_b32_e32 v33, v86, v33, vcc
	v_cndmask_b32_e32 v35, v88, v35, vcc
	v_cndmask_b32_e32 v36, v89, v36, vcc
	v_cndmask_b32_e32 v38, v91, v38, vcc
	v_cndmask_b32_e32 v39, v92, v39, vcc
	v_cndmask_b32_e32 v41, v94, v41, vcc
	v_cndmask_b32_e32 v42, v95, v42, vcc
	v_cndmask_b32_e32 v44, v97, v44, vcc
	v_cndmask_b32_e32 v45, v98, v45, vcc
	v_cndmask_b32_e32 v47, v100, v47, vcc
	v_cndmask_b32_e32 v48, v101, v48, vcc
	v_cndmask_b32_e32 v50, v103, v50, vcc
	v_cndmask_b32_e32 v51, v104, v51, vcc
	v_cndmask_b32_e32 v53, v106, v53, vcc
	v_cndmask_b32_e32 v54, v107, v54, vcc
	v_cndmask_b32_e32 v21, v105, v21, vcc
	v_cndmask_b32_e32 v22, v102, v22, vcc
	v_cndmask_b32_e32 v46, v99, v46, vcc
	v_cndmask_b32_e32 v43, v96, v43, vcc
	v_cndmask_b32_e32 v40, v93, v40, vcc
	v_cndmask_b32_e32 v37, v90, v37, vcc
	v_cndmask_b32_e32 v34, v87, v34, vcc
	v_lshlrev_b32_e32 v49, 2, v49
	v_cndmask_b32_e32 v31, v84, v31, vcc
	v_cndmask_b32_e32 v28, v81, v28, vcc
	v_cndmask_b32_e32 v25, v71, v25, vcc
	v_cndmask_b32_e32 v20, v107, v20, vcc
	v_cndmask_b32_e32 v23, v106, v23, vcc
	v_cndmask_b32_e32 v78, v104, v78, vcc
	v_cndmask_b32_e32 v77, v103, v77, vcc
	v_cndmask_b32_e32 v76, v101, v76, vcc
	v_cndmask_b32_e32 v75, v100, v75, vcc
	v_cndmask_b32_e32 v74, v98, v74, vcc
	v_cndmask_b32_e32 v73, v97, v73, vcc
	v_cndmask_b32_e32 v72, v95, v72, vcc
	v_cndmask_b32_e32 v70, v94, v70, vcc
	v_cndmask_b32_e32 v65, v92, v65, vcc
	v_cndmask_b32_e32 v64, v91, v64, vcc
	v_cndmask_b32_e32 v63, v89, v63, vcc
	v_cndmask_b32_e32 v62, v88, v62, vcc
	v_cndmask_b32_e32 v61, v86, v61, vcc
	v_cndmask_b32_e32 v60, v85, v60, vcc
	v_cndmask_b32_e32 v59, v83, v59, vcc
	v_cndmask_b32_e32 v58, v82, v58, vcc
	v_cndmask_b32_e32 v57, v80, v57, vcc
	v_cndmask_b32_e32 v56, v79, v56, vcc
	v_cndmask_b32_e32 v52, v52, v55, vcc
	ds_bpermute_b32 v55, v49, v24
	ds_bpermute_b32 v71, v49, v25
	ds_bpermute_b32 v79, v49, v26
	ds_bpermute_b32 v80, v49, v27
	ds_bpermute_b32 v81, v49, v28
	ds_bpermute_b32 v82, v49, v29
	ds_bpermute_b32 v83, v49, v30
	ds_bpermute_b32 v84, v49, v31
	ds_bpermute_b32 v85, v49, v32
	ds_bpermute_b32 v86, v49, v33
	ds_bpermute_b32 v87, v49, v34
	ds_bpermute_b32 v88, v49, v35
	ds_bpermute_b32 v89, v49, v36
	ds_bpermute_b32 v90, v49, v37
	ds_bpermute_b32 v91, v49, v38
	ds_bpermute_b32 v92, v49, v39
	ds_bpermute_b32 v93, v49, v40
	ds_bpermute_b32 v94, v49, v41
	ds_bpermute_b32 v95, v49, v42
	ds_bpermute_b32 v96, v49, v43
	ds_bpermute_b32 v97, v49, v44
	ds_bpermute_b32 v98, v49, v45
	ds_bpermute_b32 v99, v49, v46
	ds_bpermute_b32 v100, v49, v47
	ds_bpermute_b32 v101, v49, v48
	ds_bpermute_b32 v102, v49, v22
	ds_bpermute_b32 v103, v49, v50
	ds_bpermute_b32 v104, v49, v51
	ds_bpermute_b32 v105, v49, v21
	ds_bpermute_b32 v106, v49, v53
	ds_bpermute_b32 v107, v49, v54
	ds_bpermute_b32 v49, v49, v19
	v_cmp_gt_i32_e32 vcc, 4, v68
	s_waitcnt lgkmcnt(14)
	v_add_f32_e32 v55, v24, v55
	v_add_f32_e32 v71, v25, v71
	v_cndmask_b32_e32 v24, v55, v24, vcc
	s_waitcnt lgkmcnt(0)
	v_add_f32_e32 v49, v19, v49
	v_cndmask_b32_e32 v19, v49, v19, vcc
	v_add_u32_e32 v49, -8, v110
	v_cmp_lt_i32_e64 s[0:1], v49, v18
	v_add_f32_e32 v79, v26, v79
	v_add_f32_e32 v80, v27, v80
	v_cndmask_b32_e64 v49, v49, v110, s[0:1]
	v_add_f32_e32 v82, v29, v82
	v_add_f32_e32 v83, v30, v83
	v_add_f32_e32 v85, v32, v85
	v_add_f32_e32 v86, v33, v86
	v_add_f32_e32 v88, v35, v88
	v_add_f32_e32 v89, v36, v89
	v_add_f32_e32 v91, v38, v91
	v_add_f32_e32 v92, v39, v92
	v_add_f32_e32 v94, v41, v94
	v_add_f32_e32 v95, v42, v95
	v_add_f32_e32 v97, v44, v97
	v_add_f32_e32 v98, v45, v98
	v_add_f32_e32 v100, v47, v100
	v_add_f32_e32 v101, v48, v101
	v_add_f32_e32 v103, v50, v103
	v_add_f32_e32 v104, v51, v104
	v_cndmask_b32_e32 v25, v71, v25, vcc
	v_lshlrev_b32_e32 v49, 2, v49
	v_cndmask_b32_e32 v52, v55, v52, vcc
	v_cndmask_b32_e32 v55, v79, v56, vcc
	v_cndmask_b32_e32 v56, v80, v57, vcc
	v_cndmask_b32_e32 v57, v82, v58, vcc
	v_cndmask_b32_e32 v58, v83, v59, vcc
	v_cndmask_b32_e32 v59, v85, v60, vcc
	v_cndmask_b32_e32 v60, v86, v61, vcc
	v_cndmask_b32_e32 v61, v88, v62, vcc
	v_cndmask_b32_e32 v62, v89, v63, vcc
	v_cndmask_b32_e32 v63, v91, v64, vcc
	v_cndmask_b32_e32 v64, v92, v65, vcc
	v_cndmask_b32_e32 v65, v94, v70, vcc
	v_cndmask_b32_e32 v70, v95, v72, vcc
	v_cndmask_b32_e32 v72, v97, v73, vcc
	v_cndmask_b32_e32 v73, v98, v74, vcc
	v_cndmask_b32_e32 v74, v100, v75, vcc
	v_cndmask_b32_e32 v75, v101, v76, vcc
	v_cndmask_b32_e32 v76, v103, v77, vcc
	v_cndmask_b32_e32 v77, v104, v78, vcc
	ds_bpermute_b32 v71, v49, v24
	ds_bpermute_b32 v78, v49, v25
	v_add_f32_e32 v81, v28, v81
	v_cndmask_b32_e32 v26, v79, v26, vcc
	v_cndmask_b32_e32 v29, v82, v29, vcc
	v_cndmask_b32_e32 v30, v83, v30, vcc
	v_cndmask_b32_e32 v28, v81, v28, vcc
	v_cndmask_b32_e32 v27, v80, v27, vcc
	s_waitcnt lgkmcnt(1)
	v_add_f32_e32 v24, v24, v71
	s_waitcnt lgkmcnt(0)
	v_add_f32_e32 v71, v25, v78
	ds_bpermute_b32 v78, v49, v26
	ds_bpermute_b32 v80, v49, v28
	ds_bpermute_b32 v81, v49, v29
	ds_bpermute_b32 v82, v49, v30
	v_add_f32_e32 v87, v34, v87
	v_cndmask_b32_e32 v32, v85, v32, vcc
	v_cndmask_b32_e32 v33, v86, v33, vcc
	v_cndmask_b32_e32 v35, v88, v35, vcc
	v_cndmask_b32_e32 v34, v87, v34, vcc
	s_waitcnt lgkmcnt(3)
	v_add_f32_e32 v26, v26, v78
	s_waitcnt lgkmcnt(2)
	v_add_f32_e32 v78, v28, v80
	s_waitcnt lgkmcnt(1)
	v_add_f32_e32 v29, v29, v81
	s_waitcnt lgkmcnt(0)
	v_add_f32_e32 v30, v30, v82
	ds_bpermute_b32 v80, v49, v32
	ds_bpermute_b32 v81, v49, v33
	ds_bpermute_b32 v82, v49, v34
	ds_bpermute_b32 v83, v49, v35
	v_add_f32_e32 v90, v37, v90
	v_add_f32_e32 v93, v40, v93
	v_cndmask_b32_e32 v36, v89, v36, vcc
	v_cndmask_b32_e32 v38, v91, v38, vcc
	v_cndmask_b32_e32 v40, v93, v40, vcc
	v_cndmask_b32_e32 v37, v90, v37, vcc
	s_waitcnt lgkmcnt(3)
	v_add_f32_e32 v32, v32, v80
	s_waitcnt lgkmcnt(2)
	v_add_f32_e32 v33, v33, v81
	s_waitcnt lgkmcnt(1)
	v_add_f32_e32 v80, v34, v82
	s_waitcnt lgkmcnt(0)
	v_add_f32_e32 v35, v35, v83
	ds_bpermute_b32 v81, v49, v36
	ds_bpermute_b32 v82, v49, v37
	ds_bpermute_b32 v83, v49, v38
	ds_bpermute_b32 v85, v49, v40
	v_add_f32_e32 v96, v43, v96
	v_add_f32_e32 v84, v31, v84
	v_cndmask_b32_e32 v39, v92, v39, vcc
	v_cndmask_b32_e32 v41, v94, v41, vcc
	v_cndmask_b32_e32 v44, v97, v44, vcc
	v_cndmask_b32_e32 v45, v98, v45, vcc
	v_cndmask_b32_e32 v43, v96, v43, vcc
	v_cndmask_b32_e32 v31, v84, v31, vcc
	ds_bpermute_b32 v84, v49, v39
	s_waitcnt lgkmcnt(4)
	v_add_f32_e32 v36, v36, v81
	s_waitcnt lgkmcnt(3)
	v_add_f32_e32 v81, v37, v82
	s_waitcnt lgkmcnt(2)
	v_add_f32_e32 v38, v38, v83
	s_waitcnt lgkmcnt(1)
	v_add_f32_e32 v82, v40, v85
	ds_bpermute_b32 v83, v49, v41
	ds_bpermute_b32 v85, v49, v43
	ds_bpermute_b32 v86, v49, v44
	ds_bpermute_b32 v87, v49, v45
	v_add_f32_e32 v102, v22, v102
	v_cndmask_b32_e32 v42, v95, v42, vcc
	v_cndmask_b32_e32 v47, v100, v47, vcc
	v_cndmask_b32_e32 v48, v101, v48, vcc
	v_cndmask_b32_e32 v50, v103, v50, vcc
	v_cndmask_b32_e32 v22, v102, v22, vcc
	ds_bpermute_b32 v79, v49, v27
	s_waitcnt lgkmcnt(5)
	v_add_f32_e32 v39, v39, v84
	ds_bpermute_b32 v84, v49, v42
	s_waitcnt lgkmcnt(5)
	v_add_f32_e32 v41, v41, v83
	s_waitcnt lgkmcnt(4)
	v_add_f32_e32 v83, v43, v85
	s_waitcnt lgkmcnt(3)
	v_add_f32_e32 v44, v44, v86
	s_waitcnt lgkmcnt(2)
	v_add_f32_e32 v45, v45, v87
	ds_bpermute_b32 v85, v49, v47
	ds_bpermute_b32 v86, v49, v48
	ds_bpermute_b32 v87, v49, v22
	ds_bpermute_b32 v88, v49, v50
	v_add_f32_e32 v99, v46, v99
	v_add_f32_e32 v105, v21, v105
	v_add_f32_e32 v106, v53, v106
	v_add_f32_e32 v107, v54, v107
	v_cndmask_b32_e32 v51, v104, v51, vcc
	v_cndmask_b32_e32 v53, v106, v53, vcc
	v_cndmask_b32_e32 v54, v107, v54, vcc
	v_cndmask_b32_e32 v21, v105, v21, vcc
	v_cndmask_b32_e32 v46, v99, v46, vcc
	s_waitcnt lgkmcnt(5)
	v_add_f32_e32 v27, v27, v79
	ds_bpermute_b32 v79, v49, v31
	s_waitcnt lgkmcnt(5)
	v_add_f32_e32 v42, v42, v84
	ds_bpermute_b32 v84, v49, v46
	s_waitcnt lgkmcnt(5)
	v_add_f32_e32 v47, v47, v85
	s_waitcnt lgkmcnt(4)
	v_add_f32_e32 v48, v48, v86
	s_waitcnt lgkmcnt(3)
	v_add_f32_e32 v85, v22, v87
	s_waitcnt lgkmcnt(2)
	v_add_f32_e32 v50, v50, v88
	ds_bpermute_b32 v86, v49, v51
	ds_bpermute_b32 v87, v49, v21
	ds_bpermute_b32 v88, v49, v53
	ds_bpermute_b32 v89, v49, v54
	ds_bpermute_b32 v49, v49, v19
	v_cndmask_b32_e32 v23, v106, v23, vcc
	v_cndmask_b32_e32 v20, v107, v20, vcc
	s_waitcnt lgkmcnt(4)
	v_add_f32_e32 v51, v51, v86
	v_cmp_gt_i32_e32 vcc, 8, v68
	s_waitcnt lgkmcnt(0)
	v_add_f32_e32 v49, v19, v49
	v_add_f32_e32 v79, v31, v79
	v_cndmask_b32_e32 v19, v49, v19, vcc
	v_cndmask_b32_e32 v49, v51, v77, vcc
	v_add_u32_e32 v51, -16, v110
	v_cmp_lt_i32_e64 s[0:1], v51, v18
	v_add_f32_e32 v84, v46, v84
	v_add_f32_e32 v86, v21, v87
	v_cndmask_b32_e64 v51, v51, v110, s[0:1]
	v_add_f32_e32 v53, v53, v88
	v_add_f32_e32 v54, v54, v89
	v_cndmask_b32_e32 v41, v41, v65, vcc
	v_cndmask_b32_e32 v33, v33, v60, vcc
	v_lshlrev_b32_e32 v51, 2, v51
	v_cndmask_b32_e32 v20, v54, v20, vcc
	v_cndmask_b32_e32 v23, v53, v23, vcc
	v_cndmask_b32_e32 v21, v86, v21, vcc
	v_cndmask_b32_e32 v50, v50, v76, vcc
	v_cndmask_b32_e32 v22, v85, v22, vcc
	v_cndmask_b32_e32 v48, v48, v75, vcc
	v_cndmask_b32_e32 v47, v47, v74, vcc
	v_cndmask_b32_e32 v46, v84, v46, vcc
	v_cndmask_b32_e32 v45, v45, v73, vcc
	v_cndmask_b32_e32 v44, v44, v72, vcc
	v_cndmask_b32_e32 v43, v83, v43, vcc
	v_cndmask_b32_e32 v42, v42, v70, vcc
	v_cndmask_b32_e32 v40, v82, v40, vcc
	v_cndmask_b32_e32 v39, v39, v64, vcc
	v_cndmask_b32_e32 v38, v38, v63, vcc
	v_cndmask_b32_e32 v37, v81, v37, vcc
	v_cndmask_b32_e32 v36, v36, v62, vcc
	v_cndmask_b32_e32 v35, v35, v61, vcc
	v_cndmask_b32_e32 v34, v80, v34, vcc
	v_cndmask_b32_e32 v32, v32, v59, vcc
	v_cndmask_b32_e32 v31, v79, v31, vcc
	v_cndmask_b32_e32 v30, v30, v58, vcc
	v_cndmask_b32_e32 v29, v29, v57, vcc
	v_cndmask_b32_e32 v28, v78, v28, vcc
	v_cndmask_b32_e32 v24, v24, v52, vcc
	v_cndmask_b32_e32 v27, v27, v56, vcc
	v_cndmask_b32_e32 v26, v26, v55, vcc
	v_cndmask_b32_e32 v25, v71, v25, vcc
	ds_bpermute_b32 v61, v51, v33
	ds_bpermute_b32 v73, v51, v41
	ds_bpermute_b32 v52, v51, v24
	ds_bpermute_b32 v53, v51, v25
	ds_bpermute_b32 v54, v51, v26
	ds_bpermute_b32 v55, v51, v27
	ds_bpermute_b32 v56, v51, v28
	ds_bpermute_b32 v57, v51, v29
	ds_bpermute_b32 v58, v51, v30
	ds_bpermute_b32 v59, v51, v31
	ds_bpermute_b32 v60, v51, v32
	ds_bpermute_b32 v62, v51, v34
	ds_bpermute_b32 v63, v51, v35
	ds_bpermute_b32 v64, v51, v36
	ds_bpermute_b32 v65, v51, v37
	ds_bpermute_b32 v70, v51, v38
	ds_bpermute_b32 v71, v51, v39
	ds_bpermute_b32 v72, v51, v40
	ds_bpermute_b32 v74, v51, v42
	ds_bpermute_b32 v75, v51, v43
	ds_bpermute_b32 v76, v51, v44
	ds_bpermute_b32 v77, v51, v45
	ds_bpermute_b32 v78, v51, v46
	ds_bpermute_b32 v79, v51, v47
	ds_bpermute_b32 v80, v51, v48
	ds_bpermute_b32 v81, v51, v22
	ds_bpermute_b32 v82, v51, v50
	ds_bpermute_b32 v83, v51, v49
	ds_bpermute_b32 v84, v51, v21
	ds_bpermute_b32 v85, v51, v23
	ds_bpermute_b32 v86, v51, v20
	ds_bpermute_b32 v51, v51, v19
	v_cmp_gt_i32_e32 vcc, 16, v68
	s_waitcnt lgkmcnt(14)
	v_add_f32_e32 v61, v33, v61
	v_add_f32_e32 v73, v41, v73
	v_cndmask_b32_e32 v61, v61, v33, vcc
	v_cndmask_b32_e32 v73, v73, v41, vcc
	s_waitcnt lgkmcnt(3)
	v_add_f32_e32 v84, v21, v84
	s_waitcnt lgkmcnt(0)
	v_add_f32_e32 v51, v19, v51
	v_cndmask_b32_e32 v93, v61, v33, vcc
	v_cndmask_b32_e32 v33, v73, v41, vcc
	v_cndmask_b32_e32 v41, v51, v19, vcc
	v_cndmask_b32_e32 v19, v84, v21, vcc
	v_subrev_u32_e32 v21, 32, v110
	v_add_f32_e32 v57, v29, v57
	v_add_f32_e32 v79, v47, v79
	v_cmp_lt_i32_e64 s[0:1], v21, v18
	v_add_f32_e32 v52, v24, v52
	v_add_f32_e32 v53, v25, v53
	v_cndmask_b32_e32 v57, v57, v29, vcc
	v_add_f32_e32 v60, v32, v60
	v_add_f32_e32 v74, v42, v74
	v_cndmask_b32_e32 v79, v79, v47, vcc
	v_cndmask_b32_e64 v18, v21, v110, s[0:1]
	v_cndmask_b32_e32 v52, v52, v24, vcc
	v_cndmask_b32_e32 v60, v60, v32, vcc
	v_cndmask_b32_e32 v74, v74, v42, vcc
	v_add_f32_e32 v81, v22, v81
	v_cndmask_b32_e32 v91, v57, v29, vcc
	v_cndmask_b32_e32 v29, v79, v47, vcc
	v_cndmask_b32_e32 v47, v53, v25, vcc
	v_lshlrev_b32_e32 v18, 2, v18
	v_cndmask_b32_e32 v94, v60, v32, vcc
	v_cndmask_b32_e32 v32, v74, v42, vcc
	v_cndmask_b32_e32 v42, v81, v22, vcc
	ds_bpermute_b32 v21, v18, v52
	ds_bpermute_b32 v22, v18, v47
	v_add_f32_e32 v63, v35, v63
	v_add_f32_e32 v64, v36, v64
	v_add_f32_e32 v80, v48, v80
	v_add_f32_e32 v54, v26, v54
	v_add_f32_e32 v55, v27, v55
	v_add_f32_e32 v56, v28, v56
	v_add_f32_e32 v58, v30, v58
	v_cndmask_b32_e32 v63, v63, v35, vcc
	v_cndmask_b32_e32 v64, v64, v36, vcc
	v_cndmask_b32_e32 v80, v80, v48, vcc
	v_add_f32_e32 v82, v50, v82
	v_add_f32_e32 v83, v49, v83
	v_cndmask_b32_e32 v54, v54, v26, vcc
	v_cndmask_b32_e32 v55, v55, v27, vcc
	v_cndmask_b32_e32 v58, v58, v30, vcc
	v_cndmask_b32_e32 v82, v82, v50, vcc
	v_cndmask_b32_e32 v83, v83, v49, vcc
	v_cndmask_b32_e32 v92, v63, v35, vcc
	v_cndmask_b32_e32 v35, v64, v36, vcc
	v_cndmask_b32_e32 v36, v80, v48, vcc
	v_cndmask_b32_e32 v48, v56, v28, vcc
	v_cndmask_b32_e32 v89, v52, v24, vcc
	v_cndmask_b32_e32 v90, v58, v30, vcc
	v_cndmask_b32_e32 v30, v83, v49, vcc
	v_cndmask_b32_e32 v24, v82, v50, vcc
	s_waitcnt lgkmcnt(1)
	v_add_f32_e32 v49, v52, v21
	s_waitcnt lgkmcnt(0)
	v_add_f32_e32 v50, v47, v22
	ds_bpermute_b32 v21, v18, v54
	ds_bpermute_b32 v22, v18, v55
	ds_bpermute_b32 v25, v18, v48
	v_add_f32_e32 v76, v44, v76
	v_add_f32_e32 v59, v31, v59
	v_cndmask_b32_e32 v76, v76, v44, vcc
	v_add_f32_e32 v78, v46, v78
	v_cndmask_b32_e32 v88, v54, v26, vcc
	v_cndmask_b32_e32 v26, v76, v44, vcc
	v_cndmask_b32_e32 v44, v78, v46, vcc
	v_cndmask_b32_e32 v46, v59, v31, vcc
	ds_bpermute_b32 v28, v18, v57
	ds_bpermute_b32 v31, v18, v58
	s_waitcnt lgkmcnt(4)
	v_add_f32_e32 v51, v54, v21
	s_waitcnt lgkmcnt(3)
	v_add_f32_e32 v52, v55, v22
	s_waitcnt lgkmcnt(2)
	v_add_f32_e32 v53, v48, v25
	ds_bpermute_b32 v21, v18, v46
	ds_bpermute_b32 v22, v18, v60
	ds_bpermute_b32 v25, v18, v61
	v_add_f32_e32 v77, v45, v77
	v_add_f32_e32 v62, v34, v62
	v_add_f32_e32 v65, v37, v65
	v_add_f32_e32 v70, v38, v70
	v_cndmask_b32_e32 v77, v77, v45, vcc
	v_cndmask_b32_e32 v70, v70, v38, vcc
	v_cndmask_b32_e32 v87, v55, v27, vcc
	v_cndmask_b32_e32 v27, v77, v45, vcc
	v_cndmask_b32_e32 v37, v65, v37, vcc
	v_cndmask_b32_e32 v45, v62, v34, vcc
	s_waitcnt lgkmcnt(4)
	v_add_f32_e32 v54, v57, v28
	s_waitcnt lgkmcnt(3)
	v_add_f32_e32 v55, v58, v31
	ds_bpermute_b32 v28, v18, v45
	s_waitcnt lgkmcnt(3)
	v_add_f32_e32 v56, v46, v21
	s_waitcnt lgkmcnt(2)
	v_add_f32_e32 v57, v60, v22
	s_waitcnt lgkmcnt(1)
	v_add_f32_e32 v58, v61, v25
	ds_bpermute_b32 v21, v18, v64
	ds_bpermute_b32 v22, v18, v37
	ds_bpermute_b32 v25, v18, v70
	v_add_f32_e32 v71, v39, v71
	v_add_f32_e32 v75, v43, v75
	v_cndmask_b32_e32 v71, v71, v39, vcc
	v_cndmask_b32_e32 v43, v75, v43, vcc
	ds_bpermute_b32 v31, v18, v63
	s_waitcnt lgkmcnt(4)
	v_add_f32_e32 v59, v45, v28
	ds_bpermute_b32 v28, v18, v71
	s_waitcnt lgkmcnt(4)
	v_add_f32_e32 v34, v64, v21
	s_waitcnt lgkmcnt(3)
	v_add_f32_e32 v61, v37, v22
	s_waitcnt lgkmcnt(2)
	v_add_f32_e32 v62, v70, v25
	ds_bpermute_b32 v21, v18, v73
	ds_bpermute_b32 v22, v18, v74
	ds_bpermute_b32 v25, v18, v43
	v_add_f32_e32 v72, v40, v72
	v_cndmask_b32_e32 v39, v71, v39, vcc
	v_cndmask_b32_e32 v38, v70, v38, vcc
	v_cndmask_b32_e32 v40, v72, v40, vcc
	s_waitcnt lgkmcnt(4)
	v_add_f32_e32 v60, v63, v31
	s_waitcnt lgkmcnt(3)
	v_add_f32_e32 v63, v71, v28
	ds_bpermute_b32 v28, v18, v76
	s_waitcnt lgkmcnt(3)
	v_add_f32_e32 v65, v73, v21
	s_waitcnt lgkmcnt(2)
	v_add_f32_e32 v70, v74, v22
	s_waitcnt lgkmcnt(1)
	v_add_f32_e32 v71, v43, v25
	ds_bpermute_b32 v21, v18, v44
	ds_bpermute_b32 v22, v18, v79
	ds_bpermute_b32 v25, v18, v80
	ds_bpermute_b32 v72, v18, v42
	ds_bpermute_b32 v73, v18, v82
	ds_bpermute_b32 v64, v18, v77
	v_add_f32_e32 v85, v23, v85
	v_cndmask_b32_e32 v85, v85, v23, vcc
	v_add_f32_e32 v86, v20, v86
	v_cndmask_b32_e32 v86, v86, v20, vcc
	ds_bpermute_b32 v31, v18, v40
	s_waitcnt lgkmcnt(7)
	v_add_f32_e32 v28, v76, v28
	s_waitcnt lgkmcnt(6)
	v_add_f32_e32 v74, v44, v21
	s_waitcnt lgkmcnt(5)
	v_add_f32_e32 v75, v79, v22
	s_waitcnt lgkmcnt(4)
	v_add_f32_e32 v22, v80, v25
	s_waitcnt lgkmcnt(3)
	v_add_f32_e32 v25, v42, v72
	s_waitcnt lgkmcnt(2)
	v_add_f32_e32 v72, v82, v73
	ds_bpermute_b32 v21, v18, v83
	ds_bpermute_b32 v73, v18, v19
	ds_bpermute_b32 v76, v18, v85
	s_waitcnt lgkmcnt(4)
	v_add_f32_e32 v64, v77, v64
	ds_bpermute_b32 v77, v18, v86
	ds_bpermute_b32 v18, v18, v41
	s_lshl_b32 s0, s37, 3
	v_cndmask_b32_e32 v20, v86, v20, vcc
	v_cndmask_b32_e32 v23, v85, v23, vcc
	s_waitcnt lgkmcnt(5)
	v_add_f32_e32 v31, v40, v31
	s_waitcnt lgkmcnt(4)
	v_add_f32_e32 v78, v83, v21
	s_waitcnt lgkmcnt(3)
	v_add_f32_e32 v21, v19, v73
	s_waitcnt lgkmcnt(2)
	v_add_f32_e32 v73, v85, v76
	v_cmp_gt_i32_e32 vcc, 32, v68
	s_or_b32 s0, s36, s0
	s_waitcnt lgkmcnt(1)
	v_add_f32_e32 v76, v86, v77
	s_waitcnt lgkmcnt(0)
	v_add_f32_e32 v77, v41, v18
	v_cndmask_b32_e32 v18, v21, v19, vcc
	v_cndmask_b32_e32 v19, v73, v23, vcc
	v_cndmask_b32_e32 v23, v25, v42, vcc
	v_cndmask_b32_e32 v25, v78, v30, vcc
	v_cndmask_b32_e32 v30, v31, v40, vcc
	v_cndmask_b32_e32 v40, v59, v45, vcc
	v_cndmask_b32_e32 v45, v56, v46, vcc
	v_cndmask_b32_e32 v46, v49, v89, vcc
	v_cndmask_b32_e32 v49, v52, v87, vcc
	s_mulk_i32 s0, 0x104
	v_lshl_or_b32 v52, v110, 2, v116
	v_lshrrev_b32_e32 v255, 2, v52
	s_nop 0
	v_readfirstlane_b32 s101, v255
	s_nop 3
	v_cndmask_b32_e32 v42, v53, v48, vcc
	s_or_b32 s6, s0, s35
	v_readlane_b32 s98, v46, s101
	s_lshl_b64 s[0:1], s[6:7], 13
	s_add_u32 s8, s5, s0
	v_cndmask_b32_e32 v47, v50, v47, vcc
	v_cndmask_b32_e32 v48, v51, v88, vcc
	s_addc_u32 s9, s12, s1
	v_lshlrev_b64 v[50:51], 7, v[68:69]
	v_cndmask_b32_e32 v20, v76, v20, vcc
	v_cndmask_b32_e32 v21, v77, v41, vcc
	v_cndmask_b32_e32 v22, v22, v36, vcc
	v_cndmask_b32_e32 v34, v34, v35, vcc
	v_cndmask_b32_e32 v35, v61, v37, vcc
	v_cndmask_b32_e32 v36, v62, v38, vcc
	v_cndmask_b32_e32 v37, v63, v39, vcc
	v_lshl_add_u64 v[50:51], s[8:9], 0, v[50:51]
	v_cndmask_b32_e32 v24, v72, v24, vcc
	v_cndmask_b32_e32 v26, v28, v26, vcc
	v_cndmask_b32_e32 v27, v64, v27, vcc
	v_cndmask_b32_e32 v28, v74, v44, vcc
	v_cndmask_b32_e32 v29, v75, v29, vcc
	v_cndmask_b32_e32 v31, v65, v33, vcc
	v_cndmask_b32_e32 v32, v70, v32, vcc
	v_cndmask_b32_e32 v33, v71, v43, vcc
	v_cndmask_b32_e32 v38, v57, v94, vcc
	v_cndmask_b32_e32 v39, v58, v93, vcc
	v_cndmask_b32_e32 v41, v60, v92, vcc
	v_cndmask_b32_e32 v43, v54, v91, vcc
	v_cndmask_b32_e32 v44, v55, v90, vcc
	global_store_dwordx4 v[50:51], v[46:49], off
	global_store_dwordx4 v[50:51], v[42:45], off offset:16
	global_store_dwordx4 v[50:51], v[38:41], off offset:32
	global_store_dwordx4 v[50:51], v[34:37], off offset:48
	global_store_dwordx4 v[50:51], v[30:33], off offset:64
	global_store_dwordx4 v[50:51], v[26:29], off offset:80
	global_store_dwordx4 v[50:51], v[22:25], off offset:96
	v_sub_f32_e32 v53, s98, v46
	global_store_dwordx4 v[50:51], v[18:21], off offset:112
	v_readlane_b32 s98, v47, s101
	v_mul_f32_e32 v53, 0x3fb8aa3b, v53
	v_exp_f32_e32 v53, v53
	v_lshlrev_b32_e32 v51, 16, v14
	v_and_b32_e32 v14, 0xffff0000, v14
	v_sub_f32_e32 v50, s98, v47
	v_mul_f32_e32 v51, v53, v51
	v_mul_f32_e32 v50, 0x3fb8aa3b, v50
	v_bfe_u32 v53, v51, 16, 1
	v_exp_f32_e32 v50, v50
	v_add3_u32 v51, v51, v53, s30
	ds_write_b16_d16_hi v66, v51 offset:8192
	v_readlane_b32 s98, v48, s101
	v_mul_f32_e32 v14, v50, v14
	v_bfe_u32 v50, v14, 16, 1
	v_add3_u32 v14, v14, v50, s30
	ds_write_b16_d16_hi v66, v14 offset:8320
	v_sub_f32_e32 v50, s98, v48
	v_readlane_b32 s98, v49, s101
	v_mul_f32_e32 v50, 0x3fb8aa3b, v50
	v_exp_f32_e32 v50, v50
	v_lshlrev_b32_e32 v51, 16, v15
	v_and_b32_e32 v15, 0xffff0000, v15
	v_sub_f32_e32 v14, s98, v49
	v_mul_f32_e32 v50, v50, v51
	v_mul_f32_e32 v14, 0x3fb8aa3b, v14
	v_bfe_u32 v51, v50, 16, 1
	v_exp_f32_e32 v14, v14
	v_add3_u32 v50, v50, v51, s30
	ds_write_b16_d16_hi v66, v50 offset:8448
	v_readlane_b32 s98, v42, s101
	v_mul_f32_e32 v14, v14, v15
	v_bfe_u32 v15, v14, 16, 1
	v_add3_u32 v14, v14, v15, s30
	ds_write_b16_d16_hi v66, v14 offset:8576
	v_sub_f32_e32 v15, s98, v42
	v_readlane_b32 s98, v43, s101
	v_mul_f32_e32 v15, 0x3fb8aa3b, v15
	v_exp_f32_e32 v15, v15
	v_lshlrev_b32_e32 v50, 16, v16
	v_and_b32_e32 v16, 0xffff0000, v16
	v_sub_f32_e32 v14, s98, v43
	v_mul_f32_e32 v15, v15, v50
	v_mul_f32_e32 v14, 0x3fb8aa3b, v14
	v_bfe_u32 v50, v15, 16, 1
	v_exp_f32_e32 v14, v14
	v_add3_u32 v15, v15, v50, s30
	ds_write_b16_d16_hi v66, v15 offset:8704
	v_readlane_b32 s98, v44, s101
	v_mul_f32_e32 v14, v14, v16
	v_bfe_u32 v16, v14, 16, 1
	v_add3_u32 v14, v14, v16, s30
	ds_write_b16_d16_hi v66, v14 offset:8832
	v_sub_f32_e32 v15, s98, v44
	v_readlane_b32 s98, v45, s101
	v_mul_f32_e32 v15, 0x3fb8aa3b, v15
	v_exp_f32_e32 v15, v15
	v_lshlrev_b32_e32 v16, 16, v17
	v_cmp_eq_u32_e32 vcc, 63, v68
	v_sub_f32_e32 v14, s98, v45
	v_mul_f32_e32 v15, v15, v16
	v_mul_f32_e32 v14, 0x3fb8aa3b, v14
	v_bfe_u32 v16, v15, 16, 1
	v_exp_f32_e32 v14, v14
	v_add3_u32 v15, v15, v16, s30
	ds_write_b16_d16_hi v66, v15 offset:8960
	v_readlane_b32 s98, v38, s101
	v_and_b32_e32 v16, 0xffff0000, v17
	v_mul_f32_e32 v14, v14, v16
	v_bfe_u32 v16, v14, 16, 1
	v_add3_u32 v14, v14, v16, s30
	v_sub_f32_e32 v15, s98, v38
	ds_write_b16_d16_hi v66, v14 offset:9088
	v_readlane_b32 s98, v39, s101
	v_mul_f32_e32 v15, 0x3fb8aa3b, v15
	v_exp_f32_e32 v15, v15
	v_lshlrev_b32_e32 v16, 16, v10
	v_and_b32_e32 v10, 0xffff0000, v10
	v_sub_f32_e32 v14, s98, v39
	v_mul_f32_e32 v15, v15, v16
	v_mul_f32_e32 v14, 0x3fb8aa3b, v14
	v_bfe_u32 v16, v15, 16, 1
	v_exp_f32_e32 v14, v14
	v_add3_u32 v15, v15, v16, s30
	ds_write_b16_d16_hi v66, v15 offset:9216
	v_readlane_b32 s98, v40, s101
	v_mul_f32_e32 v10, v14, v10
	v_bfe_u32 v14, v10, 16, 1
	v_add3_u32 v10, v10, v14, s30
	ds_write_b16_d16_hi v66, v10 offset:9344
	v_sub_f32_e32 v14, s98, v40
	v_readlane_b32 s98, v41, s101
	v_mul_f32_e32 v14, 0x3fb8aa3b, v14
	v_exp_f32_e32 v14, v14
	v_lshlrev_b32_e32 v15, 16, v11
	v_and_b32_e32 v11, 0xffff0000, v11
	v_sub_f32_e32 v10, s98, v41
	v_mul_f32_e32 v14, v14, v15
	v_mul_f32_e32 v10, 0x3fb8aa3b, v10
	v_bfe_u32 v15, v14, 16, 1
	v_exp_f32_e32 v10, v10
	v_add3_u32 v14, v14, v15, s30
	ds_write_b16_d16_hi v66, v14 offset:9472
	v_readlane_b32 s98, v34, s101
	v_mul_f32_e32 v10, v10, v11
	v_bfe_u32 v11, v10, 16, 1
	v_add3_u32 v10, v10, v11, s30
	ds_write_b16_d16_hi v66, v10 offset:9600
	v_sub_f32_e32 v11, s98, v34
	v_readlane_b32 s98, v35, s101
	v_mul_f32_e32 v11, 0x3fb8aa3b, v11
	v_exp_f32_e32 v11, v11
	v_lshlrev_b32_e32 v14, 16, v12
	v_and_b32_e32 v12, 0xffff0000, v12
	v_sub_f32_e32 v10, s98, v35
	v_mul_f32_e32 v11, v11, v14
	v_mul_f32_e32 v10, 0x3fb8aa3b, v10
	v_bfe_u32 v14, v11, 16, 1
	v_exp_f32_e32 v10, v10
	v_add3_u32 v11, v11, v14, s30
	ds_write_b16_d16_hi v66, v11 offset:9728
	v_readlane_b32 s98, v36, s101
	v_mul_f32_e32 v10, v10, v12
	v_bfe_u32 v12, v10, 16, 1
	v_add3_u32 v10, v10, v12, s30
	ds_write_b16_d16_hi v66, v10 offset:9856
	v_sub_f32_e32 v11, s98, v36
	v_readlane_b32 s98, v37, s101
	v_mul_f32_e32 v11, 0x3fb8aa3b, v11
	v_exp_f32_e32 v11, v11
	v_lshlrev_b32_e32 v12, 16, v13
	v_sub_f32_e32 v10, s98, v37
	v_mul_f32_e32 v11, v11, v12
	v_mul_f32_e32 v10, 0x3fb8aa3b, v10
	v_bfe_u32 v12, v11, 16, 1
	v_exp_f32_e32 v10, v10
	v_add3_u32 v11, v11, v12, s30
	ds_write_b16_d16_hi v66, v11 offset:9984
	v_readlane_b32 s98, v30, s101
	v_and_b32_e32 v12, 0xffff0000, v13
	v_mul_f32_e32 v10, v10, v12
	v_bfe_u32 v12, v10, 16, 1
	v_add3_u32 v10, v10, v12, s30
	v_sub_f32_e32 v11, s98, v30
	ds_write_b16_d16_hi v66, v10 offset:10112
	v_readlane_b32 s98, v31, s101
	v_mul_f32_e32 v11, 0x3fb8aa3b, v11
	v_exp_f32_e32 v11, v11
	v_lshlrev_b32_e32 v12, 16, v6
	v_and_b32_e32 v6, 0xffff0000, v6
	v_sub_f32_e32 v10, s98, v31
	v_mul_f32_e32 v11, v11, v12
	v_mul_f32_e32 v10, 0x3fb8aa3b, v10
	v_bfe_u32 v12, v11, 16, 1
	v_exp_f32_e32 v10, v10
	v_add3_u32 v11, v11, v12, s30
	ds_write_b16_d16_hi v66, v11 offset:10240
	v_readlane_b32 s98, v32, s101
	v_mul_f32_e32 v6, v10, v6
	v_bfe_u32 v10, v6, 16, 1
	v_add3_u32 v6, v6, v10, s30
	ds_write_b16_d16_hi v66, v6 offset:10368
	v_sub_f32_e32 v10, s98, v32
	v_readlane_b32 s98, v33, s101
	v_mul_f32_e32 v10, 0x3fb8aa3b, v10
	v_exp_f32_e32 v10, v10
	v_lshlrev_b32_e32 v11, 16, v7
	v_and_b32_e32 v7, 0xffff0000, v7
	v_sub_f32_e32 v6, s98, v33
	v_mul_f32_e32 v10, v10, v11
	v_mul_f32_e32 v6, 0x3fb8aa3b, v6
	v_bfe_u32 v11, v10, 16, 1
	v_exp_f32_e32 v6, v6
	v_add3_u32 v10, v10, v11, s30
	ds_write_b16_d16_hi v66, v10 offset:10496
	v_readlane_b32 s98, v26, s101
	v_mul_f32_e32 v6, v6, v7
	v_bfe_u32 v7, v6, 16, 1
	v_add3_u32 v6, v6, v7, s30
	ds_write_b16_d16_hi v66, v6 offset:10624
	v_sub_f32_e32 v7, s98, v26
	v_readlane_b32 s98, v27, s101
	v_mul_f32_e32 v7, 0x3fb8aa3b, v7
	v_exp_f32_e32 v7, v7
	v_lshlrev_b32_e32 v10, 16, v8
	v_and_b32_e32 v8, 0xffff0000, v8
	v_sub_f32_e32 v6, s98, v27
	v_mul_f32_e32 v7, v7, v10
	v_mul_f32_e32 v6, 0x3fb8aa3b, v6
	v_bfe_u32 v10, v7, 16, 1
	v_exp_f32_e32 v6, v6
	v_add3_u32 v7, v7, v10, s30
	ds_write_b16_d16_hi v66, v7 offset:10752
	v_readlane_b32 s98, v28, s101
	v_mul_f32_e32 v6, v6, v8
	v_bfe_u32 v8, v6, 16, 1
	v_add3_u32 v6, v6, v8, s30
	ds_write_b16_d16_hi v66, v6 offset:10880
	v_sub_f32_e32 v7, s98, v28
	v_readlane_b32 s98, v29, s101
	v_mul_f32_e32 v7, 0x3fb8aa3b, v7
	v_exp_f32_e32 v7, v7
	v_lshlrev_b32_e32 v8, 16, v9
	v_sub_f32_e32 v6, s98, v29
	v_mul_f32_e32 v7, v7, v8
	v_mul_f32_e32 v6, 0x3fb8aa3b, v6
	v_bfe_u32 v8, v7, 16, 1
	v_exp_f32_e32 v6, v6
	v_add3_u32 v7, v7, v8, s30
	ds_write_b16_d16_hi v66, v7 offset:11008
	v_readlane_b32 s98, v22, s101
	v_and_b32_e32 v8, 0xffff0000, v9
	v_mul_f32_e32 v6, v6, v8
	v_bfe_u32 v8, v6, 16, 1
	v_add3_u32 v6, v6, v8, s30
	v_sub_f32_e32 v7, s98, v22
	ds_write_b16_d16_hi v66, v6 offset:11136
	v_readlane_b32 s98, v23, s101
	v_mul_f32_e32 v7, 0x3fb8aa3b, v7
	v_exp_f32_e32 v7, v7
	v_lshlrev_b32_e32 v8, 16, v2
	v_and_b32_e32 v2, 0xffff0000, v2
	v_sub_f32_e32 v6, s98, v23
	v_mul_f32_e32 v7, v7, v8
	v_mul_f32_e32 v6, 0x3fb8aa3b, v6
	v_bfe_u32 v8, v7, 16, 1
	v_exp_f32_e32 v6, v6
	v_add3_u32 v7, v7, v8, s30
	ds_write_b16_d16_hi v66, v7 offset:11264
	v_readlane_b32 s98, v24, s101
	v_mul_f32_e32 v2, v6, v2
	v_bfe_u32 v6, v2, 16, 1
	v_add3_u32 v2, v2, v6, s30
	ds_write_b16_d16_hi v66, v2 offset:11392
	v_sub_f32_e32 v6, s98, v24
	v_readlane_b32 s98, v25, s101
	v_mul_f32_e32 v6, 0x3fb8aa3b, v6
	v_exp_f32_e32 v6, v6
	v_lshlrev_b32_e32 v7, 16, v3
	v_and_b32_e32 v3, 0xffff0000, v3
	v_sub_f32_e32 v2, s98, v25
	v_mul_f32_e32 v6, v6, v7
	v_mul_f32_e32 v2, 0x3fb8aa3b, v2
	v_bfe_u32 v7, v6, 16, 1
	v_exp_f32_e32 v2, v2
	v_add3_u32 v6, v6, v7, s30
	ds_write_b16_d16_hi v66, v6 offset:11520
	v_readlane_b32 s98, v18, s101
	v_mul_f32_e32 v2, v2, v3
	v_bfe_u32 v3, v2, 16, 1
	v_add3_u32 v2, v2, v3, s30
	ds_write_b16_d16_hi v66, v2 offset:11648
	v_sub_f32_e32 v3, s98, v18
	v_readlane_b32 s98, v19, s101
	v_mul_f32_e32 v3, 0x3fb8aa3b, v3
	v_exp_f32_e32 v3, v3
	v_lshlrev_b32_e32 v6, 16, v4
	v_and_b32_e32 v4, 0xffff0000, v4
	v_sub_f32_e32 v2, s98, v19
	v_mul_f32_e32 v3, v3, v6
	v_mul_f32_e32 v2, 0x3fb8aa3b, v2
	v_bfe_u32 v6, v3, 16, 1
	v_exp_f32_e32 v2, v2
	v_add3_u32 v3, v3, v6, s30
	ds_write_b16_d16_hi v66, v3 offset:11776
	v_readlane_b32 s98, v20, s101
	v_mul_f32_e32 v2, v2, v4
	v_bfe_u32 v4, v2, 16, 1
	v_add3_u32 v2, v2, v4, s30
	v_readlane_b32 s99, v21, s101
	v_sub_f32_e32 v3, s98, v20
	v_mul_f32_e32 v3, 0x3fb8aa3b, v3
	v_exp_f32_e32 v3, v3
	ds_write_b16_d16_hi v66, v2 offset:11904
	v_sub_f32_e32 v4, s99, v21
	v_lshlrev_b32_e32 v2, 16, v5
	v_mul_f32_e32 v4, 0x3fb8aa3b, v4
	v_mul_f32_e32 v2, v3, v2
	v_exp_f32_e32 v4, v4
	v_bfe_u32 v3, v2, 16, 1
	v_add3_u32 v2, v2, v3, s30
	ds_write_b16_d16_hi v66, v2 offset:12032
	v_and_b32_e32 v2, 0xffff0000, v5
	v_mul_f32_e32 v2, v4, v2
	v_bfe_u32 v3, v2, 16, 1
	v_add3_u32 v2, v2, v3, s30
	ds_write_b16_d16_hi v66, v2 offset:12160
	s_and_saveexec_b64 s[8:9], vcc
	s_cbranch_execz .LBB0_710
	v_mul_f32_e32 v2, 0x3fb8aa3b, v46
	v_mul_f32_e32 v3, 0x3fb8aa3b, v47
	v_mul_f32_e32 v4, 0x3fb8aa3b, v48
	v_mul_f32_e32 v5, 0x3fb8aa3b, v49
	v_exp_f32_e32 v2, v2
	v_exp_f32_e32 v3, v3
	v_exp_f32_e32 v4, v4
	v_exp_f32_e32 v5, v5
	v_mul_f32_e32 v6, 0x3fb8aa3b, v42
	v_mul_f32_e32 v7, 0x3fb8aa3b, v43
	v_mul_f32_e32 v8, 0x3fb8aa3b, v44
	v_mul_f32_e32 v9, 0x3fb8aa3b, v45
	s_lshl_b64 s[10:11], s[6:7], 7
	v_exp_f32_e32 v6, v6
	v_exp_f32_e32 v7, v7
	v_exp_f32_e32 v8, v8
	v_exp_f32_e32 v9, v9
	v_mul_f32_e32 v10, 0x3fb8aa3b, v38
	v_mul_f32_e32 v11, 0x3fb8aa3b, v39
	v_mul_f32_e32 v12, 0x3fb8aa3b, v40
	v_mul_f32_e32 v13, 0x3fb8aa3b, v41
	s_add_u32 s10, s13, s10
	v_exp_f32_e32 v10, v10
	v_exp_f32_e32 v11, v11
	v_exp_f32_e32 v12, v12
	v_exp_f32_e32 v13, v13
	v_mul_f32_e32 v14, 0x3fb8aa3b, v34
	v_mul_f32_e32 v15, 0x3fb8aa3b, v35
	v_mul_f32_e32 v16, 0x3fb8aa3b, v36
	v_mul_f32_e32 v17, 0x3fb8aa3b, v37
	s_addc_u32 s11, s14, s11
	v_exp_f32_e32 v14, v14
	v_exp_f32_e32 v15, v15
	v_exp_f32_e32 v16, v16
	v_exp_f32_e32 v17, v17
	global_store_dwordx4 v67, v[2:5], s[10:11]
	global_store_dwordx4 v67, v[6:9], s[10:11] offset:16
	global_store_dwordx4 v67, v[10:13], s[10:11] offset:32
	global_store_dwordx4 v67, v[14:17], s[10:11] offset:48
	v_mul_f32_e32 v2, 0x3fb8aa3b, v30
	v_mul_f32_e32 v3, 0x3fb8aa3b, v31
	v_mul_f32_e32 v4, 0x3fb8aa3b, v32
	v_mul_f32_e32 v5, 0x3fb8aa3b, v33
	v_exp_f32_e32 v2, v2
	v_exp_f32_e32 v3, v3
	v_exp_f32_e32 v4, v4
	v_exp_f32_e32 v5, v5
	v_mul_f32_e32 v6, 0x3fb8aa3b, v26
	v_mul_f32_e32 v7, 0x3fb8aa3b, v27
	v_mul_f32_e32 v8, 0x3fb8aa3b, v28
	v_mul_f32_e32 v9, 0x3fb8aa3b, v29
	v_exp_f32_e32 v6, v6
	v_exp_f32_e32 v7, v7
	v_exp_f32_e32 v8, v8
	v_exp_f32_e32 v9, v9
	v_mul_f32_e32 v10, 0x3fb8aa3b, v22
	v_mul_f32_e32 v11, 0x3fb8aa3b, v23
	v_mul_f32_e32 v12, 0x3fb8aa3b, v24
	v_mul_f32_e32 v13, 0x3fb8aa3b, v25
	v_exp_f32_e32 v10, v10
	v_exp_f32_e32 v11, v11
	v_exp_f32_e32 v12, v12
	v_exp_f32_e32 v13, v13
	v_mul_f32_e32 v14, 0x3fb8aa3b, v18
	v_mul_f32_e32 v15, 0x3fb8aa3b, v19
	v_mul_f32_e32 v16, 0x3fb8aa3b, v20
	v_mul_f32_e32 v17, 0x3fb8aa3b, v21
	v_exp_f32_e32 v14, v14
	v_exp_f32_e32 v15, v15
	v_exp_f32_e32 v16, v16
	v_exp_f32_e32 v17, v17
	global_store_dwordx4 v67, v[2:5], s[10:11] offset:64
	global_store_dwordx4 v67, v[6:9], s[10:11] offset:80
	global_store_dwordx4 v67, v[10:13], s[10:11] offset:96
	global_store_dwordx4 v67, v[14:17], s[10:11] offset:112
	s_branch .LBB0_710

.LBB0_1946:
	v_mov_b32_e32 v68, v109
	v_mov_b64_e32 v[2:3], s[8:9]
	v_add_u32_e32 v4, s33, v68
	v_mad_i64_i32 v[70:71], s[0:1], v4, s31, v[2:3]
	s_lshl_b32 s0, s14, 1
	s_mov_b32 s1, s15
	v_lshl_add_u64 v[30:31], v[70:71], 0, s[0:1]
	global_load_dwordx4 v[2:5], v[30:31], off offset:512
	global_load_dwordx4 v[6:9], v[30:31], off offset:528
	global_load_dwordx4 v[10:13], v[30:31], off offset:544
	global_load_dwordx4 v[14:17], v[30:31], off offset:560
	global_load_dwordx4 v[18:21], v[30:31], off offset:576
	global_load_dwordx4 v[22:25], v[30:31], off offset:592
	global_load_dwordx4 v[26:29], v[30:31], off offset:608
	s_nop 0
	global_load_dwordx4 v[30:33], v[30:31], off offset:624
	v_readlane_b32 s44, v239, 33
	global_load_dwordx4 v[34:37], v[70:71], off offset:1568
	v_readlane_b32 s48, v239, 37
	v_readlane_b32 s49, v239, 38
	v_readlane_b32 s50, v239, 39
	v_readlane_b32 s51, v239, 40
	v_readlane_b32 s52, v239, 41
	v_readlane_b32 s53, v239, 42
	v_readlane_b32 s54, v239, 43
	v_readlane_b32 s55, v239, 44
	s_lshl_b32 s0, s40, 7
	v_readlane_b32 s56, v239, 45
	v_readlane_b32 s57, v239, 46
	v_readlane_b32 s58, v239, 47
	v_readlane_b32 s59, v239, 48
	s_mov_b64 s[48:49], s[52:53]
	s_add_u32 s16, s10, s0
	v_mov_b32_e32 v123, s0
	s_mov_b64 s[50:51], s[54:55]
	s_mov_b64 s[52:53], s[56:57]
	s_addc_u32 s17, s11, 0
	global_load_dwordx4 v[38:41], v123, s[52:53] offset:512
	global_load_dwordx4 v[42:45], v123, s[10:11]
	global_load_dwordx4 v[46:49], v123, s[10:11] offset:512
	global_load_dwordx4 v[50:53], v123, s[10:11] offset:1024
	global_load_dwordx4 v[54:57], v123, s[10:11] offset:1536
	global_load_dwordx4 v[58:61], v123, s[10:11] offset:2048
	global_load_dwordx4 v[62:65], v123, s[10:11] offset:2560
	global_load_dwordx4 v[74:77], v123, s[10:11] offset:3072
	global_load_dwordx4 v[78:81], v123, s[10:11] offset:3584
	global_load_dwordx4 v[82:85], v110, s[16:17]
	global_load_dwordx4 v[86:89], v110, s[16:17] offset:512
	global_load_dwordx4 v[90:93], v[70:71], off offset:1584
	v_lshl_add_u32 v66, v68, 1, s25
	v_lshl_add_u64 v[70:71], v[70:71], 0, s[14:15]
	v_ashrrev_i32_e32 v69, 31, v68
	v_readlane_b32 s45, v239, 34
	v_readlane_b32 s46, v239, 35
	v_readlane_b32 s47, v239, 36
	s_mov_b64 s[54:55], s[58:59]
	s_waitcnt vmcnt(20)
	ds_write_b16 v66, v2
	ds_write_b16_d16_hi v66, v2 offset:128
	ds_write_b16 v66, v3 offset:256
	ds_write_b16_d16_hi v66, v3 offset:384
	ds_write_b16 v66, v4 offset:512
	ds_write_b16_d16_hi v66, v4 offset:640
	ds_write_b16 v66, v5 offset:768
	ds_write_b16_d16_hi v66, v5 offset:896
	s_waitcnt vmcnt(19)
	ds_write_b16 v66, v6 offset:1024
	ds_write_b16_d16_hi v66, v6 offset:1152
	ds_write_b16 v66, v7 offset:1280
	ds_write_b16_d16_hi v66, v7 offset:1408
	ds_write_b16 v66, v8 offset:1536
	ds_write_b16_d16_hi v66, v8 offset:1664
	ds_write_b16 v66, v9 offset:1792
	ds_write_b16_d16_hi v66, v9 offset:1920
	s_waitcnt vmcnt(18)
	ds_write_b16 v66, v10 offset:2048
	ds_write_b16_d16_hi v66, v10 offset:2176
	ds_write_b16 v66, v11 offset:2304
	ds_write_b16_d16_hi v66, v11 offset:2432
	ds_write_b16 v66, v12 offset:2560
	ds_write_b16_d16_hi v66, v12 offset:2688
	ds_write_b16 v66, v13 offset:2816
	ds_write_b16_d16_hi v66, v13 offset:2944
	s_waitcnt vmcnt(17)
	ds_write_b16 v66, v14 offset:3072
	ds_write_b16_d16_hi v66, v14 offset:3200
	ds_write_b16 v66, v15 offset:3328
	ds_write_b16_d16_hi v66, v15 offset:3456
	ds_write_b16 v66, v16 offset:3584
	ds_write_b16_d16_hi v66, v16 offset:3712
	ds_write_b16 v66, v17 offset:3840
	ds_write_b16_d16_hi v66, v17 offset:3968
	s_waitcnt vmcnt(16)
	ds_write_b16 v66, v18 offset:4096
	ds_write_b16_d16_hi v66, v18 offset:4224
	ds_write_b16 v66, v19 offset:4352
	ds_write_b16_d16_hi v66, v19 offset:4480
	ds_write_b16 v66, v20 offset:4608
	ds_write_b16_d16_hi v66, v20 offset:4736
	ds_write_b16 v66, v21 offset:4864
	ds_write_b16_d16_hi v66, v21 offset:4992
	s_waitcnt vmcnt(15)
	ds_write_b16 v66, v22 offset:5120
	ds_write_b16_d16_hi v66, v22 offset:5248
	ds_write_b16 v66, v23 offset:5376
	ds_write_b16_d16_hi v66, v23 offset:5504
	ds_write_b16 v66, v24 offset:5632
	ds_write_b16_d16_hi v66, v24 offset:5760
	ds_write_b16 v66, v25 offset:5888
	ds_write_b16_d16_hi v66, v25 offset:6016
	s_waitcnt vmcnt(14)
	ds_write_b16 v66, v26 offset:6144
	ds_write_b16_d16_hi v66, v26 offset:6272
	ds_write_b16 v66, v27 offset:6400
	ds_write_b16_d16_hi v66, v27 offset:6528
	ds_write_b16 v66, v28 offset:6656
	ds_write_b16_d16_hi v66, v28 offset:6784
	ds_write_b16 v66, v29 offset:6912
	ds_write_b16_d16_hi v66, v29 offset:7040
	s_waitcnt vmcnt(13)
	ds_write_b16 v66, v30 offset:7168
	ds_write_b16_d16_hi v66, v30 offset:7296
	ds_write_b16 v66, v31 offset:7424
	ds_write_b16_d16_hi v66, v31 offset:7552
	ds_write_b16 v66, v32 offset:7680
	ds_write_b16_d16_hi v66, v32 offset:7808
	ds_write_b16 v66, v33 offset:7936
	ds_write_b16_d16_hi v66, v33 offset:8064
	global_load_dwordx4 v[18:21], v110, s[16:17] offset:1024
	global_load_dwordx4 v[22:25], v110, s[16:17] offset:1536
	global_load_dwordx4 v[14:17], v[70:71], off offset:256
	global_load_dwordx4 v[10:13], v[70:71], off offset:272
	global_load_dwordx4 v[6:9], v[70:71], off offset:288
	global_load_dwordx4 v[2:5], v[70:71], off offset:304
	global_load_dwordx4 v[26:29], v110, s[16:17] offset:2048
	global_load_dwordx4 v[30:33], v110, s[16:17] offset:2560
	global_load_dwordx4 v[94:97], v110, s[16:17] offset:3072
	global_load_dwordx4 v[98:101], v110, s[16:17] offset:3584
	s_waitcnt vmcnt(22)
	v_lshlrev_b32_e32 v118, 16, v34
	v_and_b32_e32 v117, 0xffff0000, v34
	v_lshlrev_b32_e32 v120, 16, v36
	v_and_b32_e32 v119, 0xffff0000, v36
	v_lshlrev_b32_e32 v122, 16, v35
	v_and_b32_e32 v121, 0xffff0000, v35
	v_and_b32_e32 v73, 0xffff0000, v37
	v_lshlrev_b32_e32 v72, 16, v37
	s_waitcnt vmcnt(20)
	v_fma_f32 v36, v42, v118, v38
	s_waitcnt vmcnt(19)
	v_fmac_f32_e32 v36, v46, v117
	s_waitcnt vmcnt(18)
	v_fmac_f32_e32 v36, v50, v122
	v_fma_f32 v38, v43, v118, v39
	s_waitcnt vmcnt(17)
	v_fmac_f32_e32 v36, v54, v121
	v_fmac_f32_e32 v38, v47, v117
	s_waitcnt vmcnt(16)
	v_fmac_f32_e32 v36, v58, v120
	v_fmac_f32_e32 v38, v51, v122
	s_waitcnt vmcnt(14)
	v_mov_b32_e32 v34, v74
	s_waitcnt vmcnt(13)
	v_mov_b32_e32 v35, v78
	v_fmac_f32_e32 v36, v62, v119
	v_fmac_f32_e32 v38, v55, v121
	v_fma_f32 v39, v44, v118, v40
	v_pk_mul_f32 v[34:35], v[34:35], v[72:73]
	v_fmac_f32_e32 v38, v59, v120
	v_fmac_f32_e32 v39, v48, v117
	v_add_f32_e32 v34, v36, v34
	v_mov_b32_e32 v78, v75
	v_fmac_f32_e32 v38, v63, v119
	v_fmac_f32_e32 v39, v52, v122
	v_fmac_f32_e32 v41, v45, v118
	v_add_f32_e32 v36, v34, v35
	v_pk_mul_f32 v[34:35], v[78:79], v[72:73]
	v_fmac_f32_e32 v39, v56, v121
	v_fmac_f32_e32 v41, v49, v117
	v_add_f32_e32 v34, v34, v38
	v_fmac_f32_e32 v39, v60, v120
	v_fmac_f32_e32 v41, v53, v122
	v_add_f32_e32 v37, v35, v34
	v_mov_b32_e32 v34, v76
	v_mov_b32_e32 v35, v80
	v_fmac_f32_e32 v39, v64, v119
	v_fmac_f32_e32 v41, v57, v121
	v_pk_mul_f32 v[34:35], v[34:35], v[72:73]
	v_fmac_f32_e32 v41, v61, v120
	v_add_f32_e32 v34, v34, v39
	v_mov_b32_e32 v80, v77
	v_fmac_f32_e32 v41, v65, v119
	v_add_f32_e32 v38, v35, v34
	v_pk_mul_f32 v[34:35], v[80:81], v[72:73]
	s_waitcnt vmcnt(10)
	v_and_b32_e32 v75, 0xffff0000, v90
	v_add_f32_e32 v34, v34, v41
	v_add_f32_e32 v39, v35, v34
	v_lshlrev_b32_e32 v74, 16, v90
	v_mov_b32_e32 v34, v82
	v_mov_b32_e32 v35, v86
	v_pk_mul_f32 v[34:35], v[34:35], v[74:75]
	v_mov_b32_e32 v86, v83
	v_add_f32_e32 v34, v36, v34
	v_add_f32_e32 v36, v34, v35
	v_pk_mul_f32 v[34:35], v[86:87], v[74:75]
	v_and_b32_e32 v79, 0xffff0000, v91
	v_add_f32_e32 v34, v34, v37
	v_add_f32_e32 v37, v35, v34
	v_mov_b32_e32 v34, v84
	v_mov_b32_e32 v35, v88
	v_pk_mul_f32 v[34:35], v[34:35], v[74:75]
	v_mov_b32_e32 v88, v85
	v_add_f32_e32 v34, v34, v38
	v_add_f32_e32 v38, v35, v34
	v_pk_mul_f32 v[34:35], v[88:89], v[74:75]
	v_lshlrev_b32_e32 v78, 16, v91
	v_add_f32_e32 v34, v34, v39
	v_add_f32_e32 v39, v35, v34
	v_and_b32_e32 v81, 0xffff0000, v92
	v_lshlrev_b32_e32 v80, 16, v92
	v_and_b32_e32 v83, 0xffff0000, v93
	v_lshlrev_b32_e32 v82, 16, v93
	s_waitcnt vmcnt(9)
	v_mov_b32_e32 v34, v18
	s_waitcnt vmcnt(8)
	v_mov_b32_e32 v35, v22
	v_pk_mul_f32 v[34:35], v[34:35], v[78:79]
	v_mov_b32_e32 v22, v19
	v_add_f32_e32 v18, v36, v34
	v_add_f32_e32 v34, v18, v35
	v_pk_mul_f32 v[18:19], v[22:23], v[78:79]
	s_nop 0
	v_add_f32_e32 v18, v18, v37
	v_add_f32_e32 v22, v19, v18
	v_mov_b32_e32 v18, v20
	v_mov_b32_e32 v19, v24
	v_pk_mul_f32 v[18:19], v[18:19], v[78:79]
	v_mov_b32_e32 v24, v21
	v_add_f32_e32 v18, v18, v38
	v_add_f32_e32 v20, v19, v18
	v_pk_mul_f32 v[18:19], v[24:25], v[78:79]
	s_waitcnt vmcnt(0)
	v_mov_b32_e32 v21, v98
	v_add_f32_e32 v18, v18, v39
	v_add_f32_e32 v23, v19, v18
	v_mov_b32_e32 v18, v26
	v_mov_b32_e32 v19, v30
	v_pk_mul_f32 v[18:19], v[18:19], v[80:81]
	v_mov_b32_e32 v30, v27
	v_add_f32_e32 v18, v34, v18
	v_add_f32_e32 v24, v18, v19
	v_pk_mul_f32 v[18:19], v[30:31], v[80:81]
	v_mov_b32_e32 v98, v95
	v_add_f32_e32 v18, v18, v22
	v_add_f32_e32 v22, v19, v18
	v_mov_b32_e32 v18, v28
	v_mov_b32_e32 v19, v32
	v_pk_mul_f32 v[18:19], v[18:19], v[80:81]
	v_mov_b32_e32 v32, v29
	v_add_f32_e32 v18, v18, v20
	v_mov_b32_e32 v20, v94
	v_pk_mul_f32 v[20:21], v[20:21], v[82:83]
	s_nop 0
	v_add_f32_e32 v20, v24, v20
	v_add_f32_e32 v20, v20, v21
	v_mul_f32_e64 v21, |v20|, s34
	v_exp_f32_e32 v21, v21
	v_add_f32_e32 v24, v19, v18
	v_pk_mul_f32 v[18:19], v[32:33], v[80:81]
	v_add_f32_e32 v21, 1.0, v21
	v_cmp_gt_f32_e32 vcc, s35, v21
	v_add_f32_e32 v18, v18, v23
	v_add_f32_e32 v26, v19, v18
	v_cndmask_b32_e64 v25, 0, 32, vcc
	v_ldexp_f32 v21, v21, v25
	v_log_f32_e32 v25, v21
	v_min_f32_e32 v18, 0, v20
	v_pk_mul_f32 v[20:21], v[98:99], v[82:83]
	v_mov_b32_e32 v23, v100
	v_add_f32_e32 v20, v20, v22
	v_add_f32_e32 v21, v21, v20
	v_mul_f32_e64 v20, |v21|, s34
	v_exp_f32_e32 v20, v20
	v_mul_f32_e32 v19, 0x3f317217, v25
	v_fma_f32 v19, v25, s36, -v19
	v_fmac_f32_e32 v19, 0x3377d1cf, v25
	v_fmac_f32_e32 v19, 0x3f317217, v25
	v_cmp_lt_f32_e64 s[0:1], |v25|, s37
	v_add_f32_e32 v20, 1.0, v20
	v_mov_b32_e32 v100, v97
	v_cndmask_b32_e64 v19, v25, v19, s[0:1]
	v_cmp_gt_f32_e64 s[0:1], s35, v20
	s_nop 1
	v_cndmask_b32_e64 v22, 0, 32, s[0:1]
	v_ldexp_f32 v20, v20, v22
	v_mov_b32_e32 v22, v96
	v_pk_mul_f32 v[22:23], v[22:23], v[82:83]
	v_log_f32_e32 v25, v20
	v_add_f32_e32 v22, v22, v24
	v_add_f32_e32 v22, v23, v22
	v_mul_f32_e64 v23, |v22|, s34
	v_cndmask_b32_e32 v20, 0, v111, vcc
	v_exp_f32_e32 v23, v23
	v_sub_f32_e32 v20, v19, v20
	v_min_f32_e32 v19, 0, v21
	v_mul_f32_e32 v21, 0x3f317217, v25
	v_fma_f32 v21, v25, s36, -v21
	v_fmac_f32_e32 v21, 0x3377d1cf, v25
	v_fmac_f32_e32 v21, 0x3f317217, v25
	v_cmp_lt_f32_e64 vcc, |v25|, s37
	v_add_f32_e32 v23, 1.0, v23
	v_cndmask_b32_e64 v24, 0, v111, s[0:1]
	v_cndmask_b32_e32 v21, v25, v21, vcc
	v_cmp_gt_f32_e32 vcc, s35, v23
	v_sub_f32_e32 v21, v21, v24
	v_pk_add_f32 v[18:19], v[18:19], v[20:21] neg_lo:[0,1] neg_hi:[0,1]
	v_cndmask_b32_e64 v24, 0, 32, vcc
	v_ldexp_f32 v23, v23, v24
	v_pk_mul_f32 v[20:21], v[100:101], v[82:83]
	v_log_f32_e32 v23, v23
	v_add_f32_e32 v20, v20, v26
	v_add_f32_e32 v21, v21, v20
	v_mul_f32_e64 v20, |v21|, s34
	v_exp_f32_e32 v20, v20
	v_pk_mul_f32 v[70:71], v[18:19], s[6:7] op_sel_hi:[1,0]
	v_mul_f32_e32 v19, 0x3f317217, v23
	v_fma_f32 v19, v23, s36, -v19
	v_fmac_f32_e32 v19, 0x3377d1cf, v23
	v_fmac_f32_e32 v19, 0x3f317217, v23
	v_cmp_lt_f32_e64 s[0:1], |v23|, s37
	v_add_f32_e32 v20, 1.0, v20
	v_min_f32_e32 v18, 0, v22
	v_cndmask_b32_e64 v19, v23, v19, s[0:1]
	v_cmp_gt_f32_e64 s[0:1], s35, v20
	s_nop 1
	v_cndmask_b32_e64 v22, 0, 32, s[0:1]
	v_ldexp_f32 v20, v20, v22
	v_log_f32_e32 v22, v20
	v_cndmask_b32_e32 v20, 0, v111, vcc
	v_sub_f32_e32 v20, v19, v20
	v_min_f32_e32 v19, 0, v21
	v_mul_f32_e32 v21, 0x3f317217, v22
	v_fma_f32 v21, v22, s36, -v21
	v_fmac_f32_e32 v21, 0x3377d1cf, v22
	v_fmac_f32_e32 v21, 0x3f317217, v22
	v_cmp_lt_f32_e64 vcc, |v22|, s37
	s_nop 1
	v_cndmask_b32_e32 v21, v22, v21, vcc
	v_cndmask_b32_e64 v22, 0, v111, s[0:1]
	v_sub_f32_e32 v21, v21, v22
	v_pk_add_f32 v[18:19], v[18:19], v[20:21] neg_lo:[0,1] neg_hi:[0,1]
	s_nop 0
	v_pk_mul_f32 v[76:77], v[18:19], s[6:7] op_sel_hi:[1,0]
	global_load_dwordx4 v[18:21], v123, s[52:53] offset:528
	global_load_dwordx4 v[22:25], v123, s[10:11] offset:16
	global_load_dwordx4 v[26:29], v123, s[10:11] offset:3088
	global_load_dwordx4 v[30:33], v123, s[10:11] offset:3600
	global_load_dwordx4 v[34:37], v110, s[16:17] offset:16
	global_load_dwordx4 v[38:41], v110, s[16:17] offset:528
	global_load_dwordx4 v[42:45], v110, s[16:17] offset:1040
	global_load_dwordx4 v[46:49], v110, s[16:17] offset:1552
	global_load_dwordx4 v[50:53], v110, s[16:17] offset:2064
	global_load_dwordx4 v[54:57], v110, s[16:17] offset:2576
	global_load_dwordx4 v[58:61], v110, s[16:17] offset:3088
	global_load_dwordx4 v[62:65], v110, s[16:17] offset:3600
	global_load_dwordx4 v[84:87], v123, s[10:11] offset:528
	global_load_dwordx4 v[88:91], v123, s[10:11] offset:1040
	global_load_dwordx4 v[92:95], v123, s[10:11] offset:1552
	global_load_dwordx4 v[96:99], v123, s[10:11] offset:2064
	global_load_dwordx4 v[100:103], v123, s[10:11] offset:2576
	s_waitcnt vmcnt(15)
	v_fma_f32 v130, v22, v118, v18
	v_fma_f32 v20, v24, v118, v20
	s_waitcnt vmcnt(14)
	v_mov_b32_e32 v104, v26
	s_waitcnt vmcnt(13)
	v_mov_b32_e32 v105, v30
	v_fma_f32 v23, v23, v118, v19
	v_mov_b32_e32 v30, v27
	v_mov_b32_e32 v18, v28
	v_mov_b32_e32 v19, v32
	v_pk_mul_f32 v[26:27], v[104:105], v[72:73]
	s_waitcnt vmcnt(12)
	v_mov_b32_e32 v106, v34
	s_waitcnt vmcnt(11)
	v_mov_b32_e32 v107, v38
	s_waitcnt vmcnt(4)
	v_fmac_f32_e32 v130, v84, v117
	v_fmac_f32_e32 v20, v86, v117
	s_waitcnt vmcnt(3)
	v_fmac_f32_e32 v130, v88, v122
	v_fmac_f32_e32 v20, v90, v122
	s_waitcnt vmcnt(2)
	v_fmac_f32_e32 v130, v92, v121
	v_fmac_f32_e32 v20, v94, v121
	s_waitcnt vmcnt(1)
	v_fmac_f32_e32 v130, v96, v120
	v_fmac_f32_e32 v20, v98, v120
	s_waitcnt vmcnt(0)
	v_fmac_f32_e32 v130, v100, v119
	v_fmac_f32_e32 v23, v85, v117
	v_pk_mul_f32 v[18:19], v[18:19], v[72:73]
	v_fmac_f32_e32 v20, v102, v119
	v_add_f32_e32 v24, v130, v26
	v_mov_b32_e32 v38, v35
	v_pk_mul_f32 v[34:35], v[106:107], v[74:75]
	v_fmac_f32_e32 v23, v89, v122
	v_add_f32_e32 v18, v18, v20
	v_add_f32_e32 v20, v24, v27
	v_mov_b32_e32 v124, v42
	v_mov_b32_e32 v125, v46
	v_fmac_f32_e32 v23, v93, v121
	v_add_f32_e32 v20, v20, v34
	v_mov_b32_e32 v46, v43
	v_pk_mul_f32 v[42:43], v[124:125], v[78:79]
	v_fmac_f32_e32 v23, v97, v120
	v_add_f32_e32 v20, v20, v35
	v_mov_b32_e32 v126, v50
	v_mov_b32_e32 v127, v54
	v_pk_mul_f32 v[30:31], v[30:31], v[72:73]
	v_fmac_f32_e32 v23, v101, v119
	v_add_f32_e32 v20, v20, v42
	v_mov_b32_e32 v54, v51
	v_pk_mul_f32 v[50:51], v[126:127], v[80:81]
	v_add_f32_e32 v23, v30, v23
	v_add_f32_e32 v20, v20, v43
	v_mov_b32_e32 v128, v58
	v_mov_b32_e32 v129, v62
	v_pk_mul_f32 v[38:39], v[38:39], v[74:75]
	v_add_f32_e32 v23, v31, v23
	v_add_f32_e32 v20, v20, v50
	v_mov_b32_e32 v62, v59
	v_pk_mul_f32 v[58:59], v[128:129], v[82:83]
	v_add_f32_e32 v23, v38, v23
	v_add_f32_e32 v20, v20, v51
	v_pk_mul_f32 v[46:47], v[46:47], v[78:79]
	v_add_f32_e32 v23, v39, v23
	v_add_f32_e32 v20, v20, v58
	v_add_f32_e32 v23, v46, v23
	v_add_f32_e32 v20, v20, v59
	v_pk_mul_f32 v[54:55], v[54:55], v[80:81]
	v_add_f32_e32 v23, v47, v23
	v_mul_f32_e64 v24, |v20|, s34
	v_add_f32_e32 v23, v54, v23
	v_exp_f32_e32 v24, v24
	v_pk_mul_f32 v[62:63], v[62:63], v[82:83]
	v_add_f32_e32 v23, v55, v23
	v_add_f32_e32 v23, v62, v23
	v_add_f32_e32 v23, v63, v23
	v_mul_f32_e64 v26, |v23|, s34
	v_add_f32_e32 v27, v19, v18
	v_add_f32_e32 v19, 1.0, v24
	v_exp_f32_e32 v26, v26
	v_cmp_gt_f32_e32 vcc, s35, v19
	v_min_f32_e32 v18, 0, v20
	v_mov_b32_e32 v22, v36
	v_cndmask_b32_e64 v24, 0, 32, vcc
	v_ldexp_f32 v19, v19, v24
	v_log_f32_e32 v24, v19
	v_add_f32_e32 v20, 1.0, v26
	v_cmp_gt_f32_e64 s[0:1], s35, v20
	v_min_f32_e32 v19, 0, v23
	v_cndmask_b32_e32 v23, 0, v111, vcc
	v_cndmask_b32_e64 v26, 0, 32, s[0:1]
	v_ldexp_f32 v20, v20, v26
	v_mul_f32_e32 v26, 0x3f317217, v24
	v_fma_f32 v26, v24, s36, -v26
	v_fmac_f32_e32 v26, 0x3377d1cf, v24
	v_fmac_f32_e32 v26, 0x3f317217, v24
	v_cmp_lt_f32_e64 vcc, |v24|, s37
	v_log_f32_e32 v20, v20
	v_fmac_f32_e32 v21, v25, v118
	v_cndmask_b32_e32 v24, v24, v26, vcc
	v_sub_f32_e32 v26, v24, v23
	v_mov_b32_e32 v23, v40
	v_pk_mul_f32 v[22:23], v[22:23], v[74:75]
	v_mul_f32_e32 v28, 0x3f317217, v20
	v_add_f32_e32 v22, v22, v27
	v_add_f32_e32 v24, v23, v22
	v_mov_b32_e32 v22, v44
	v_mov_b32_e32 v23, v48
	v_pk_mul_f32 v[22:23], v[22:23], v[78:79]
	v_fma_f32 v28, v20, s36, -v28
	v_add_f32_e32 v22, v22, v24
	v_add_f32_e32 v24, v23, v22
	v_mov_b32_e32 v22, v52
	v_mov_b32_e32 v23, v56
	v_pk_mul_f32 v[22:23], v[22:23], v[80:81]
	v_fmac_f32_e32 v28, 0x3377d1cf, v20
	v_add_f32_e32 v22, v22, v24
	v_add_f32_e32 v24, v23, v22
	v_mov_b32_e32 v22, v60
	v_mov_b32_e32 v23, v64
	v_pk_mul_f32 v[22:23], v[22:23], v[82:83]
	v_fmac_f32_e32 v28, 0x3f317217, v20
	v_add_f32_e32 v22, v22, v24
	v_add_f32_e32 v22, v23, v22
	v_mul_f32_e64 v23, |v22|, s34
	v_exp_f32_e32 v23, v23
	v_cmp_lt_f32_e64 vcc, |v20|, s37
	v_cndmask_b32_e64 v24, 0, v111, s[0:1]
	v_fmac_f32_e32 v21, v87, v117
	v_cndmask_b32_e32 v20, v20, v28, vcc
	v_sub_f32_e32 v27, v20, v24
	v_add_f32_e32 v20, 1.0, v23
	v_fmac_f32_e32 v21, v91, v122
	v_cmp_gt_f32_e32 vcc, s35, v20
	v_fmac_f32_e32 v21, v95, v121
	v_pk_add_f32 v[18:19], v[18:19], v[26:27] neg_lo:[0,1] neg_hi:[0,1]
	v_cndmask_b32_e64 v23, 0, 32, vcc
	v_fmac_f32_e32 v21, v99, v120
	v_mov_b32_e32 v32, v29
	v_ldexp_f32 v20, v20, v23
	v_pk_mul_f32 v[84:85], v[18:19], s[6:7] op_sel_hi:[1,0]
	v_min_f32_e32 v18, 0, v22
	v_fmac_f32_e32 v21, v103, v119
	v_pk_mul_f32 v[22:23], v[32:33], v[72:73]
	v_log_f32_e32 v24, v20
	v_add_f32_e32 v20, v22, v21
	v_mov_b32_e32 v40, v37
	v_add_f32_e32 v22, v23, v20
	v_pk_mul_f32 v[20:21], v[40:41], v[74:75]
	v_mov_b32_e32 v48, v45
	v_add_f32_e32 v20, v20, v22
	v_add_f32_e32 v22, v21, v20
	v_pk_mul_f32 v[20:21], v[48:49], v[78:79]
	v_mov_b32_e32 v56, v53
	v_add_f32_e32 v20, v20, v22
	v_add_f32_e32 v22, v21, v20
	v_pk_mul_f32 v[20:21], v[56:57], v[80:81]
	v_mov_b32_e32 v64, v61
	v_add_f32_e32 v20, v20, v22
	v_add_f32_e32 v22, v21, v20
	v_pk_mul_f32 v[20:21], v[64:65], v[82:83]
	v_mul_f32_e32 v19, 0x3f317217, v24
	v_add_f32_e32 v20, v20, v22
	v_add_f32_e32 v21, v21, v20
	v_mul_f32_e64 v20, |v21|, s34
	v_exp_f32_e32 v20, v20
	v_fma_f32 v19, v24, s36, -v19
	v_fmac_f32_e32 v19, 0x3377d1cf, v24
	v_fmac_f32_e32 v19, 0x3f317217, v24
	v_cmp_lt_f32_e64 s[0:1], |v24|, s37
	v_add_f32_e32 v20, 1.0, v20
	s_nop 0
	v_cndmask_b32_e64 v19, v24, v19, s[0:1]
	v_cmp_gt_f32_e64 s[0:1], s35, v20
	s_nop 1
	v_cndmask_b32_e64 v22, 0, 32, s[0:1]
	v_ldexp_f32 v20, v20, v22
	v_log_f32_e32 v22, v20
	v_cndmask_b32_e32 v20, 0, v111, vcc
	v_sub_f32_e32 v20, v19, v20
	v_min_f32_e32 v19, 0, v21
	v_mul_f32_e32 v21, 0x3f317217, v22
	v_fma_f32 v21, v22, s36, -v21
	v_fmac_f32_e32 v21, 0x3377d1cf, v22
	v_fmac_f32_e32 v21, 0x3f317217, v22
	v_cmp_lt_f32_e64 vcc, |v22|, s37
	s_nop 1
	v_cndmask_b32_e32 v21, v22, v21, vcc
	v_cndmask_b32_e64 v22, 0, v111, s[0:1]
	v_sub_f32_e32 v21, v21, v22
	v_pk_add_f32 v[18:19], v[18:19], v[20:21] neg_lo:[0,1] neg_hi:[0,1]
	s_nop 0
	v_pk_mul_f32 v[86:87], v[18:19], s[6:7] op_sel_hi:[1,0]
	global_load_dwordx4 v[18:21], v123, s[52:53] offset:544
	global_load_dwordx4 v[22:25], v123, s[10:11] offset:32
	global_load_dwordx4 v[26:29], v123, s[10:11] offset:3104
	global_load_dwordx4 v[30:33], v123, s[10:11] offset:3616
	global_load_dwordx4 v[34:37], v110, s[16:17] offset:32
	global_load_dwordx4 v[38:41], v110, s[16:17] offset:544
	global_load_dwordx4 v[42:45], v110, s[16:17] offset:1056
	global_load_dwordx4 v[46:49], v110, s[16:17] offset:1568
	global_load_dwordx4 v[50:53], v110, s[16:17] offset:2080
	global_load_dwordx4 v[54:57], v110, s[16:17] offset:2592
	global_load_dwordx4 v[58:61], v110, s[16:17] offset:3104
	global_load_dwordx4 v[62:65], v110, s[16:17] offset:3616
	global_load_dwordx4 v[88:91], v123, s[10:11] offset:544
	global_load_dwordx4 v[92:95], v123, s[10:11] offset:1056
	global_load_dwordx4 v[96:99], v123, s[10:11] offset:1568
	global_load_dwordx4 v[100:103], v123, s[10:11] offset:2080
	global_load_dwordx4 v[104:107], v123, s[10:11] offset:2592
	s_waitcnt vmcnt(15)
	v_fma_f32 v134, v22, v118, v18
	v_fma_f32 v20, v24, v118, v20
	s_waitcnt vmcnt(14)
	v_mov_b32_e32 v124, v26
	s_waitcnt vmcnt(13)
	v_mov_b32_e32 v125, v30
	v_fma_f32 v23, v23, v118, v19
	v_mov_b32_e32 v30, v27
	v_mov_b32_e32 v18, v28
	v_mov_b32_e32 v19, v32
	v_pk_mul_f32 v[26:27], v[124:125], v[72:73]
	s_waitcnt vmcnt(12)
	v_mov_b32_e32 v126, v34
	s_waitcnt vmcnt(11)
	v_mov_b32_e32 v127, v38
	s_waitcnt vmcnt(4)
	v_fmac_f32_e32 v134, v88, v117
	v_fmac_f32_e32 v20, v90, v117
	s_waitcnt vmcnt(3)
	v_fmac_f32_e32 v134, v92, v122
	v_fmac_f32_e32 v20, v94, v122
	s_waitcnt vmcnt(2)
	v_fmac_f32_e32 v134, v96, v121
	v_fmac_f32_e32 v20, v98, v121
	s_waitcnt vmcnt(1)
	v_fmac_f32_e32 v134, v100, v120
	v_fmac_f32_e32 v20, v102, v120
	s_waitcnt vmcnt(0)
	v_fmac_f32_e32 v134, v104, v119
	v_fmac_f32_e32 v23, v89, v117
	v_pk_mul_f32 v[18:19], v[18:19], v[72:73]
	v_fmac_f32_e32 v20, v106, v119
	v_add_f32_e32 v24, v134, v26
	v_mov_b32_e32 v38, v35
	v_pk_mul_f32 v[34:35], v[126:127], v[74:75]
	v_fmac_f32_e32 v23, v93, v122
	v_add_f32_e32 v18, v18, v20
	v_add_f32_e32 v20, v24, v27
	v_mov_b32_e32 v128, v42
	v_mov_b32_e32 v129, v46
	v_fmac_f32_e32 v23, v97, v121
	v_add_f32_e32 v20, v20, v34
	v_mov_b32_e32 v46, v43
	v_pk_mul_f32 v[42:43], v[128:129], v[78:79]
	v_fmac_f32_e32 v23, v101, v120
	v_add_f32_e32 v20, v20, v35
	v_mov_b32_e32 v130, v50
	v_mov_b32_e32 v131, v54
	v_pk_mul_f32 v[30:31], v[30:31], v[72:73]
	v_fmac_f32_e32 v23, v105, v119
	v_add_f32_e32 v20, v20, v42
	v_mov_b32_e32 v54, v51
	v_pk_mul_f32 v[50:51], v[130:131], v[80:81]
	v_add_f32_e32 v23, v30, v23
	v_add_f32_e32 v20, v20, v43
	v_mov_b32_e32 v132, v58
	v_mov_b32_e32 v133, v62
	v_pk_mul_f32 v[38:39], v[38:39], v[74:75]
	v_add_f32_e32 v23, v31, v23
	v_add_f32_e32 v20, v20, v50
	v_mov_b32_e32 v62, v59
	v_pk_mul_f32 v[58:59], v[132:133], v[82:83]
	v_add_f32_e32 v23, v38, v23
	v_add_f32_e32 v20, v20, v51
	v_pk_mul_f32 v[46:47], v[46:47], v[78:79]
	v_add_f32_e32 v23, v39, v23
	v_add_f32_e32 v20, v20, v58
	v_add_f32_e32 v23, v46, v23
	v_add_f32_e32 v20, v20, v59
	v_pk_mul_f32 v[54:55], v[54:55], v[80:81]
	v_add_f32_e32 v23, v47, v23
	v_mul_f32_e64 v24, |v20|, s34
	v_add_f32_e32 v23, v54, v23
	v_exp_f32_e32 v24, v24
	v_pk_mul_f32 v[62:63], v[62:63], v[82:83]
	v_add_f32_e32 v23, v55, v23
	v_add_f32_e32 v23, v62, v23
	v_add_f32_e32 v23, v63, v23
	v_mul_f32_e64 v26, |v23|, s34
	v_add_f32_e32 v27, v19, v18
	v_add_f32_e32 v19, 1.0, v24
	v_exp_f32_e32 v26, v26
	v_cmp_gt_f32_e32 vcc, s35, v19
	v_min_f32_e32 v18, 0, v20
	v_mov_b32_e32 v22, v36
	v_cndmask_b32_e64 v24, 0, 32, vcc
	v_ldexp_f32 v19, v19, v24
	v_log_f32_e32 v24, v19
	v_add_f32_e32 v20, 1.0, v26
	v_cmp_gt_f32_e64 s[0:1], s35, v20
	v_min_f32_e32 v19, 0, v23
	v_cndmask_b32_e32 v23, 0, v111, vcc
	v_cndmask_b32_e64 v26, 0, 32, s[0:1]
	v_ldexp_f32 v20, v20, v26
	v_mul_f32_e32 v26, 0x3f317217, v24
	v_fma_f32 v26, v24, s36, -v26
	v_fmac_f32_e32 v26, 0x3377d1cf, v24
	v_fmac_f32_e32 v26, 0x3f317217, v24
	v_cmp_lt_f32_e64 vcc, |v24|, s37
	v_log_f32_e32 v20, v20
	v_fmac_f32_e32 v21, v25, v118
	v_cndmask_b32_e32 v24, v24, v26, vcc
	v_sub_f32_e32 v26, v24, v23
	v_mov_b32_e32 v23, v40
	v_pk_mul_f32 v[22:23], v[22:23], v[74:75]
	v_mul_f32_e32 v28, 0x3f317217, v20
	v_add_f32_e32 v22, v22, v27
	v_add_f32_e32 v24, v23, v22
	v_mov_b32_e32 v22, v44
	v_mov_b32_e32 v23, v48
	v_pk_mul_f32 v[22:23], v[22:23], v[78:79]
	v_fma_f32 v28, v20, s36, -v28
	v_add_f32_e32 v22, v22, v24
	v_add_f32_e32 v24, v23, v22
	v_mov_b32_e32 v22, v52
	v_mov_b32_e32 v23, v56
	v_pk_mul_f32 v[22:23], v[22:23], v[80:81]
	v_fmac_f32_e32 v28, 0x3377d1cf, v20
	v_add_f32_e32 v22, v22, v24
	v_add_f32_e32 v24, v23, v22
	v_mov_b32_e32 v22, v60
	v_mov_b32_e32 v23, v64
	v_pk_mul_f32 v[22:23], v[22:23], v[82:83]
	v_fmac_f32_e32 v28, 0x3f317217, v20
	v_add_f32_e32 v22, v22, v24
	v_add_f32_e32 v22, v23, v22
	v_mul_f32_e64 v23, |v22|, s34
	v_exp_f32_e32 v23, v23
	v_cmp_lt_f32_e64 vcc, |v20|, s37
	v_cndmask_b32_e64 v24, 0, v111, s[0:1]
	v_fmac_f32_e32 v21, v91, v117
	v_cndmask_b32_e32 v20, v20, v28, vcc
	v_sub_f32_e32 v27, v20, v24
	v_add_f32_e32 v20, 1.0, v23
	v_fmac_f32_e32 v21, v95, v122
	v_cmp_gt_f32_e32 vcc, s35, v20
	v_fmac_f32_e32 v21, v99, v121
	v_pk_add_f32 v[18:19], v[18:19], v[26:27] neg_lo:[0,1] neg_hi:[0,1]
	v_cndmask_b32_e64 v23, 0, 32, vcc
	v_fmac_f32_e32 v21, v103, v120
	v_mov_b32_e32 v32, v29
	v_ldexp_f32 v20, v20, v23
	v_pk_mul_f32 v[88:89], v[18:19], s[6:7] op_sel_hi:[1,0]
	v_min_f32_e32 v18, 0, v22
	v_fmac_f32_e32 v21, v107, v119
	v_pk_mul_f32 v[22:23], v[32:33], v[72:73]
	v_log_f32_e32 v24, v20
	v_add_f32_e32 v20, v22, v21
	v_mov_b32_e32 v40, v37
	v_add_f32_e32 v22, v23, v20
	v_pk_mul_f32 v[20:21], v[40:41], v[74:75]
	v_mov_b32_e32 v48, v45
	v_add_f32_e32 v20, v20, v22
	v_add_f32_e32 v22, v21, v20
	v_pk_mul_f32 v[20:21], v[48:49], v[78:79]
	v_mov_b32_e32 v56, v53
	v_add_f32_e32 v20, v20, v22
	v_add_f32_e32 v22, v21, v20
	v_pk_mul_f32 v[20:21], v[56:57], v[80:81]
	v_mov_b32_e32 v64, v61
	v_add_f32_e32 v20, v20, v22
	v_add_f32_e32 v22, v21, v20
	v_pk_mul_f32 v[20:21], v[64:65], v[82:83]
	v_mul_f32_e32 v19, 0x3f317217, v24
	v_add_f32_e32 v20, v20, v22
	v_add_f32_e32 v21, v21, v20
	v_mul_f32_e64 v20, |v21|, s34
	v_exp_f32_e32 v20, v20
	v_fma_f32 v19, v24, s36, -v19
	v_fmac_f32_e32 v19, 0x3377d1cf, v24
	v_fmac_f32_e32 v19, 0x3f317217, v24
	v_cmp_lt_f32_e64 s[0:1], |v24|, s37
	v_add_f32_e32 v20, 1.0, v20
	s_nop 0
	v_cndmask_b32_e64 v19, v24, v19, s[0:1]
	v_cmp_gt_f32_e64 s[0:1], s35, v20
	s_nop 1
	v_cndmask_b32_e64 v22, 0, 32, s[0:1]
	v_ldexp_f32 v20, v20, v22
	v_log_f32_e32 v22, v20
	v_cndmask_b32_e32 v20, 0, v111, vcc
	v_sub_f32_e32 v20, v19, v20
	v_min_f32_e32 v19, 0, v21
	v_mul_f32_e32 v21, 0x3f317217, v22
	v_fma_f32 v21, v22, s36, -v21
	v_fmac_f32_e32 v21, 0x3377d1cf, v22
	v_fmac_f32_e32 v21, 0x3f317217, v22
	v_cmp_lt_f32_e64 vcc, |v22|, s37
	s_nop 1
	v_cndmask_b32_e32 v21, v22, v21, vcc
	v_cndmask_b32_e64 v22, 0, v111, s[0:1]
	v_sub_f32_e32 v21, v21, v22
	v_pk_add_f32 v[18:19], v[18:19], v[20:21] neg_lo:[0,1] neg_hi:[0,1]
	s_nop 0
	v_pk_mul_f32 v[90:91], v[18:19], s[6:7] op_sel_hi:[1,0]
	global_load_dwordx4 v[18:21], v123, s[52:53] offset:560
	global_load_dwordx4 v[22:25], v123, s[10:11] offset:48
	global_load_dwordx4 v[26:29], v123, s[10:11] offset:3120
	global_load_dwordx4 v[30:33], v123, s[10:11] offset:3632
	global_load_dwordx4 v[34:37], v110, s[16:17] offset:48
	global_load_dwordx4 v[38:41], v110, s[16:17] offset:560
	global_load_dwordx4 v[42:45], v110, s[16:17] offset:1072
	global_load_dwordx4 v[46:49], v110, s[16:17] offset:1584
	global_load_dwordx4 v[50:53], v110, s[16:17] offset:2096
	global_load_dwordx4 v[54:57], v110, s[16:17] offset:2608
	global_load_dwordx4 v[58:61], v110, s[16:17] offset:3120
	global_load_dwordx4 v[62:65], v110, s[16:17] offset:3632
	global_load_dwordx4 v[92:95], v123, s[10:11] offset:560
	global_load_dwordx4 v[96:99], v123, s[10:11] offset:1072
	global_load_dwordx4 v[100:103], v123, s[10:11] offset:1584
	global_load_dwordx4 v[104:107], v123, s[10:11] offset:2096
	global_load_dwordx4 v[124:127], v123, s[10:11] offset:2608
	s_waitcnt vmcnt(15)
	v_fma_f32 v138, v22, v118, v18
	v_fma_f32 v20, v24, v118, v20
	s_waitcnt vmcnt(14)
	v_mov_b32_e32 v128, v26
	s_waitcnt vmcnt(13)
	v_mov_b32_e32 v129, v30
	v_fma_f32 v23, v23, v118, v19
	v_mov_b32_e32 v30, v27
	v_mov_b32_e32 v18, v28
	v_mov_b32_e32 v19, v32
	v_pk_mul_f32 v[26:27], v[128:129], v[72:73]
	s_waitcnt vmcnt(12)
	v_mov_b32_e32 v130, v34
	s_waitcnt vmcnt(11)
	v_mov_b32_e32 v131, v38
	s_waitcnt vmcnt(4)
	v_fmac_f32_e32 v138, v92, v117
	v_fmac_f32_e32 v20, v94, v117
	s_waitcnt vmcnt(3)
	v_fmac_f32_e32 v138, v96, v122
	v_fmac_f32_e32 v20, v98, v122
	s_waitcnt vmcnt(2)
	v_fmac_f32_e32 v138, v100, v121
	v_fmac_f32_e32 v20, v102, v121
	s_waitcnt vmcnt(1)
	v_fmac_f32_e32 v138, v104, v120
	v_fmac_f32_e32 v20, v106, v120
	s_waitcnt vmcnt(0)
	v_fmac_f32_e32 v138, v124, v119
	v_fmac_f32_e32 v23, v93, v117
	v_pk_mul_f32 v[18:19], v[18:19], v[72:73]
	v_fmac_f32_e32 v20, v126, v119
	v_add_f32_e32 v24, v138, v26
	v_mov_b32_e32 v38, v35
	v_pk_mul_f32 v[34:35], v[130:131], v[74:75]
	v_fmac_f32_e32 v23, v97, v122
	v_add_f32_e32 v18, v18, v20
	v_add_f32_e32 v20, v24, v27
	v_mov_b32_e32 v132, v42
	v_mov_b32_e32 v133, v46
	v_fmac_f32_e32 v23, v101, v121
	v_add_f32_e32 v20, v20, v34
	v_mov_b32_e32 v46, v43
	v_pk_mul_f32 v[42:43], v[132:133], v[78:79]
	v_fmac_f32_e32 v23, v105, v120
	v_add_f32_e32 v20, v20, v35
	v_mov_b32_e32 v134, v50
	v_mov_b32_e32 v135, v54
	v_pk_mul_f32 v[30:31], v[30:31], v[72:73]
	v_fmac_f32_e32 v23, v125, v119
	v_add_f32_e32 v20, v20, v42
	v_mov_b32_e32 v54, v51
	v_pk_mul_f32 v[50:51], v[134:135], v[80:81]
	v_add_f32_e32 v23, v30, v23
	v_add_f32_e32 v20, v20, v43
	v_mov_b32_e32 v136, v58
	v_mov_b32_e32 v137, v62
	v_pk_mul_f32 v[38:39], v[38:39], v[74:75]
	v_add_f32_e32 v23, v31, v23
	v_add_f32_e32 v20, v20, v50
	v_mov_b32_e32 v62, v59
	v_pk_mul_f32 v[58:59], v[136:137], v[82:83]
	v_add_f32_e32 v23, v38, v23
	v_add_f32_e32 v20, v20, v51
	v_pk_mul_f32 v[46:47], v[46:47], v[78:79]
	v_add_f32_e32 v23, v39, v23
	v_add_f32_e32 v20, v20, v58
	v_add_f32_e32 v23, v46, v23
	v_add_f32_e32 v20, v20, v59
	v_pk_mul_f32 v[54:55], v[54:55], v[80:81]
	v_add_f32_e32 v23, v47, v23
	v_mul_f32_e64 v24, |v20|, s34
	v_add_f32_e32 v23, v54, v23
	v_exp_f32_e32 v24, v24
	v_pk_mul_f32 v[62:63], v[62:63], v[82:83]
	v_add_f32_e32 v23, v55, v23
	v_add_f32_e32 v23, v62, v23
	v_add_f32_e32 v23, v63, v23
	v_mul_f32_e64 v26, |v23|, s34
	v_add_f32_e32 v27, v19, v18
	v_add_f32_e32 v19, 1.0, v24
	v_exp_f32_e32 v26, v26
	v_cmp_gt_f32_e32 vcc, s35, v19
	v_min_f32_e32 v18, 0, v20
	v_mov_b32_e32 v22, v36
	v_cndmask_b32_e64 v24, 0, 32, vcc
	v_ldexp_f32 v19, v19, v24
	v_log_f32_e32 v24, v19
	v_add_f32_e32 v20, 1.0, v26
	v_cmp_gt_f32_e64 s[0:1], s35, v20
	v_min_f32_e32 v19, 0, v23
	v_cndmask_b32_e32 v23, 0, v111, vcc
	v_cndmask_b32_e64 v26, 0, 32, s[0:1]
	v_ldexp_f32 v20, v20, v26
	v_mul_f32_e32 v26, 0x3f317217, v24
	v_fma_f32 v26, v24, s36, -v26
	v_fmac_f32_e32 v26, 0x3377d1cf, v24
	v_fmac_f32_e32 v26, 0x3f317217, v24
	v_cmp_lt_f32_e64 vcc, |v24|, s37
	v_log_f32_e32 v20, v20
	v_fmac_f32_e32 v21, v25, v118
	v_cndmask_b32_e32 v24, v24, v26, vcc
	v_sub_f32_e32 v26, v24, v23
	v_mov_b32_e32 v23, v40
	v_pk_mul_f32 v[22:23], v[22:23], v[74:75]
	v_mul_f32_e32 v28, 0x3f317217, v20
	v_add_f32_e32 v22, v22, v27
	v_add_f32_e32 v24, v23, v22
	v_mov_b32_e32 v22, v44
	v_mov_b32_e32 v23, v48
	v_pk_mul_f32 v[22:23], v[22:23], v[78:79]
	v_fma_f32 v28, v20, s36, -v28
	v_add_f32_e32 v22, v22, v24
	v_add_f32_e32 v24, v23, v22
	v_mov_b32_e32 v22, v52
	v_mov_b32_e32 v23, v56
	v_pk_mul_f32 v[22:23], v[22:23], v[80:81]
	v_fmac_f32_e32 v28, 0x3377d1cf, v20
	v_add_f32_e32 v22, v22, v24
	v_add_f32_e32 v24, v23, v22
	v_mov_b32_e32 v22, v60
	v_mov_b32_e32 v23, v64
	v_pk_mul_f32 v[22:23], v[22:23], v[82:83]
	v_fmac_f32_e32 v28, 0x3f317217, v20
	v_add_f32_e32 v22, v22, v24
	v_add_f32_e32 v22, v23, v22
	v_mul_f32_e64 v23, |v22|, s34
	v_exp_f32_e32 v23, v23
	v_cmp_lt_f32_e64 vcc, |v20|, s37
	v_cndmask_b32_e64 v24, 0, v111, s[0:1]
	v_fmac_f32_e32 v21, v95, v117
	v_cndmask_b32_e32 v20, v20, v28, vcc
	v_sub_f32_e32 v27, v20, v24
	v_add_f32_e32 v20, 1.0, v23
	v_fmac_f32_e32 v21, v99, v122
	v_cmp_gt_f32_e32 vcc, s35, v20
	v_fmac_f32_e32 v21, v103, v121
	v_pk_add_f32 v[18:19], v[18:19], v[26:27] neg_lo:[0,1] neg_hi:[0,1]
	v_cndmask_b32_e64 v23, 0, 32, vcc
	v_fmac_f32_e32 v21, v107, v120
	v_mov_b32_e32 v32, v29
	v_ldexp_f32 v20, v20, v23
	v_pk_mul_f32 v[92:93], v[18:19], s[6:7] op_sel_hi:[1,0]
	v_min_f32_e32 v18, 0, v22
	v_fmac_f32_e32 v21, v127, v119
	v_pk_mul_f32 v[22:23], v[32:33], v[72:73]
	v_log_f32_e32 v24, v20
	v_add_f32_e32 v20, v22, v21
	v_mov_b32_e32 v40, v37
	v_add_f32_e32 v22, v23, v20
	v_pk_mul_f32 v[20:21], v[40:41], v[74:75]
	v_mov_b32_e32 v48, v45
	v_add_f32_e32 v20, v20, v22
	v_add_f32_e32 v22, v21, v20
	v_pk_mul_f32 v[20:21], v[48:49], v[78:79]
	v_mov_b32_e32 v56, v53
	v_add_f32_e32 v20, v20, v22
	v_add_f32_e32 v22, v21, v20
	v_pk_mul_f32 v[20:21], v[56:57], v[80:81]
	v_mov_b32_e32 v64, v61
	v_add_f32_e32 v20, v20, v22
	v_add_f32_e32 v22, v21, v20
	v_pk_mul_f32 v[20:21], v[64:65], v[82:83]
	v_mul_f32_e32 v19, 0x3f317217, v24
	v_add_f32_e32 v20, v20, v22
	v_add_f32_e32 v21, v21, v20
	v_mul_f32_e64 v20, |v21|, s34
	v_exp_f32_e32 v20, v20
	v_fma_f32 v19, v24, s36, -v19
	v_fmac_f32_e32 v19, 0x3377d1cf, v24
	v_fmac_f32_e32 v19, 0x3f317217, v24
	v_cmp_lt_f32_e64 s[0:1], |v24|, s37
	v_add_f32_e32 v20, 1.0, v20
	s_nop 0
	v_cndmask_b32_e64 v19, v24, v19, s[0:1]
	v_cmp_gt_f32_e64 s[0:1], s35, v20
	s_nop 1
	v_cndmask_b32_e64 v22, 0, 32, s[0:1]
	v_ldexp_f32 v20, v20, v22
	v_log_f32_e32 v22, v20
	v_cndmask_b32_e32 v20, 0, v111, vcc
	v_sub_f32_e32 v20, v19, v20
	v_min_f32_e32 v19, 0, v21
	v_mul_f32_e32 v21, 0x3f317217, v22
	v_fma_f32 v21, v22, s36, -v21
	v_fmac_f32_e32 v21, 0x3377d1cf, v22
	v_fmac_f32_e32 v21, 0x3f317217, v22
	v_cmp_lt_f32_e64 vcc, |v22|, s37
	s_nop 1
	v_cndmask_b32_e32 v21, v22, v21, vcc
	v_cndmask_b32_e64 v22, 0, v111, s[0:1]
	v_sub_f32_e32 v21, v21, v22
	v_pk_add_f32 v[18:19], v[18:19], v[20:21] neg_lo:[0,1] neg_hi:[0,1]
	s_nop 0
	v_pk_mul_f32 v[94:95], v[18:19], s[6:7] op_sel_hi:[1,0]
	global_load_dwordx4 v[18:21], v123, s[52:53] offset:576
	global_load_dwordx4 v[22:25], v123, s[10:11] offset:64
	global_load_dwordx4 v[26:29], v123, s[10:11] offset:3136
	global_load_dwordx4 v[30:33], v123, s[10:11] offset:3648
	global_load_dwordx4 v[34:37], v110, s[16:17] offset:64
	global_load_dwordx4 v[38:41], v110, s[16:17] offset:576
	global_load_dwordx4 v[42:45], v110, s[16:17] offset:1088
	global_load_dwordx4 v[46:49], v110, s[16:17] offset:1600
	global_load_dwordx4 v[50:53], v110, s[16:17] offset:2112
	global_load_dwordx4 v[54:57], v110, s[16:17] offset:2624
	global_load_dwordx4 v[58:61], v110, s[16:17] offset:3136
	global_load_dwordx4 v[62:65], v110, s[16:17] offset:3648
	global_load_dwordx4 v[96:99], v123, s[10:11] offset:576
	global_load_dwordx4 v[100:103], v123, s[10:11] offset:1088
	global_load_dwordx4 v[104:107], v123, s[10:11] offset:1600
	global_load_dwordx4 v[124:127], v123, s[10:11] offset:2112
	global_load_dwordx4 v[128:131], v123, s[10:11] offset:2624
	s_waitcnt vmcnt(15)
	v_fma_f32 v142, v22, v118, v18
	v_fma_f32 v20, v24, v118, v20
	s_waitcnt vmcnt(14)
	v_mov_b32_e32 v132, v26
	s_waitcnt vmcnt(13)
	v_mov_b32_e32 v133, v30
	v_fma_f32 v23, v23, v118, v19
	v_mov_b32_e32 v30, v27
	v_mov_b32_e32 v18, v28
	v_mov_b32_e32 v19, v32
	v_pk_mul_f32 v[26:27], v[132:133], v[72:73]
	s_waitcnt vmcnt(12)
	v_mov_b32_e32 v134, v34
	s_waitcnt vmcnt(11)
	v_mov_b32_e32 v135, v38
	s_waitcnt vmcnt(4)
	v_fmac_f32_e32 v142, v96, v117
	v_fmac_f32_e32 v20, v98, v117
	s_waitcnt vmcnt(3)
	v_fmac_f32_e32 v142, v100, v122
	v_fmac_f32_e32 v20, v102, v122
	s_waitcnt vmcnt(2)
	v_fmac_f32_e32 v142, v104, v121
	v_fmac_f32_e32 v20, v106, v121
	s_waitcnt vmcnt(1)
	v_fmac_f32_e32 v142, v124, v120
	v_fmac_f32_e32 v20, v126, v120
	s_waitcnt vmcnt(0)
	v_fmac_f32_e32 v142, v128, v119
	v_fmac_f32_e32 v23, v97, v117
	v_pk_mul_f32 v[18:19], v[18:19], v[72:73]
	v_fmac_f32_e32 v20, v130, v119
	v_add_f32_e32 v24, v142, v26
	v_mov_b32_e32 v38, v35
	v_pk_mul_f32 v[34:35], v[134:135], v[74:75]
	v_fmac_f32_e32 v23, v101, v122
	v_add_f32_e32 v18, v18, v20
	v_add_f32_e32 v20, v24, v27
	v_mov_b32_e32 v136, v42
	v_mov_b32_e32 v137, v46
	v_fmac_f32_e32 v23, v105, v121
	v_add_f32_e32 v20, v20, v34
	v_mov_b32_e32 v46, v43
	v_pk_mul_f32 v[42:43], v[136:137], v[78:79]
	v_fmac_f32_e32 v23, v125, v120
	v_add_f32_e32 v20, v20, v35
	v_mov_b32_e32 v138, v50
	v_mov_b32_e32 v139, v54
	v_pk_mul_f32 v[30:31], v[30:31], v[72:73]
	v_fmac_f32_e32 v23, v129, v119
	v_add_f32_e32 v20, v20, v42
	v_mov_b32_e32 v54, v51
	v_pk_mul_f32 v[50:51], v[138:139], v[80:81]
	v_add_f32_e32 v23, v30, v23
	v_add_f32_e32 v20, v20, v43
	v_mov_b32_e32 v140, v58
	v_mov_b32_e32 v141, v62
	v_pk_mul_f32 v[38:39], v[38:39], v[74:75]
	v_add_f32_e32 v23, v31, v23
	v_add_f32_e32 v20, v20, v50
	v_mov_b32_e32 v62, v59
	v_pk_mul_f32 v[58:59], v[140:141], v[82:83]
	v_add_f32_e32 v23, v38, v23
	v_add_f32_e32 v20, v20, v51
	v_pk_mul_f32 v[46:47], v[46:47], v[78:79]
	v_add_f32_e32 v23, v39, v23
	v_add_f32_e32 v20, v20, v58
	v_add_f32_e32 v23, v46, v23
	v_add_f32_e32 v20, v20, v59
	v_pk_mul_f32 v[54:55], v[54:55], v[80:81]
	v_add_f32_e32 v23, v47, v23
	v_mul_f32_e64 v24, |v20|, s34
	v_add_f32_e32 v23, v54, v23
	v_exp_f32_e32 v24, v24
	v_pk_mul_f32 v[62:63], v[62:63], v[82:83]
	v_add_f32_e32 v23, v55, v23
	v_add_f32_e32 v23, v62, v23
	v_add_f32_e32 v23, v63, v23
	v_mul_f32_e64 v26, |v23|, s34
	v_add_f32_e32 v27, v19, v18
	v_add_f32_e32 v19, 1.0, v24
	v_exp_f32_e32 v26, v26
	v_cmp_gt_f32_e32 vcc, s35, v19
	v_min_f32_e32 v18, 0, v20
	v_mov_b32_e32 v22, v36
	v_cndmask_b32_e64 v24, 0, 32, vcc
	v_ldexp_f32 v19, v19, v24
	v_log_f32_e32 v24, v19
	v_add_f32_e32 v20, 1.0, v26
	v_cmp_gt_f32_e64 s[0:1], s35, v20
	v_min_f32_e32 v19, 0, v23
	v_cndmask_b32_e32 v23, 0, v111, vcc
	v_cndmask_b32_e64 v26, 0, 32, s[0:1]
	v_ldexp_f32 v20, v20, v26
	v_mul_f32_e32 v26, 0x3f317217, v24
	v_fma_f32 v26, v24, s36, -v26
	v_fmac_f32_e32 v26, 0x3377d1cf, v24
	v_fmac_f32_e32 v26, 0x3f317217, v24
	v_cmp_lt_f32_e64 vcc, |v24|, s37
	v_log_f32_e32 v20, v20
	v_fmac_f32_e32 v21, v25, v118
	v_cndmask_b32_e32 v24, v24, v26, vcc
	v_sub_f32_e32 v26, v24, v23
	v_mov_b32_e32 v23, v40
	v_pk_mul_f32 v[22:23], v[22:23], v[74:75]
	v_mul_f32_e32 v28, 0x3f317217, v20
	v_add_f32_e32 v22, v22, v27
	v_add_f32_e32 v24, v23, v22
	v_mov_b32_e32 v22, v44
	v_mov_b32_e32 v23, v48
	v_pk_mul_f32 v[22:23], v[22:23], v[78:79]
	v_fma_f32 v28, v20, s36, -v28
	v_add_f32_e32 v22, v22, v24
	v_add_f32_e32 v24, v23, v22
	v_mov_b32_e32 v22, v52
	v_mov_b32_e32 v23, v56
	v_pk_mul_f32 v[22:23], v[22:23], v[80:81]
	v_fmac_f32_e32 v28, 0x3377d1cf, v20
	v_add_f32_e32 v22, v22, v24
	v_add_f32_e32 v24, v23, v22
	v_mov_b32_e32 v22, v60
	v_mov_b32_e32 v23, v64
	v_pk_mul_f32 v[22:23], v[22:23], v[82:83]
	v_fmac_f32_e32 v28, 0x3f317217, v20
	v_add_f32_e32 v22, v22, v24
	v_add_f32_e32 v22, v23, v22
	v_mul_f32_e64 v23, |v22|, s34
	v_exp_f32_e32 v23, v23
	v_cmp_lt_f32_e64 vcc, |v20|, s37
	v_cndmask_b32_e64 v24, 0, v111, s[0:1]
	v_fmac_f32_e32 v21, v99, v117
	v_cndmask_b32_e32 v20, v20, v28, vcc
	v_sub_f32_e32 v27, v20, v24
	v_add_f32_e32 v20, 1.0, v23
	v_fmac_f32_e32 v21, v103, v122
	v_cmp_gt_f32_e32 vcc, s35, v20
	v_fmac_f32_e32 v21, v107, v121
	v_pk_add_f32 v[18:19], v[18:19], v[26:27] neg_lo:[0,1] neg_hi:[0,1]
	v_cndmask_b32_e64 v23, 0, 32, vcc
	v_fmac_f32_e32 v21, v127, v120
	v_mov_b32_e32 v32, v29
	v_ldexp_f32 v20, v20, v23
	v_pk_mul_f32 v[96:97], v[18:19], s[6:7] op_sel_hi:[1,0]
	v_min_f32_e32 v18, 0, v22
	v_fmac_f32_e32 v21, v131, v119
	v_pk_mul_f32 v[22:23], v[32:33], v[72:73]
	v_log_f32_e32 v24, v20
	v_add_f32_e32 v20, v22, v21
	v_mov_b32_e32 v40, v37
	v_add_f32_e32 v22, v23, v20
	v_pk_mul_f32 v[20:21], v[40:41], v[74:75]
	v_mov_b32_e32 v48, v45
	v_add_f32_e32 v20, v20, v22
	v_add_f32_e32 v22, v21, v20
	v_pk_mul_f32 v[20:21], v[48:49], v[78:79]
	v_mov_b32_e32 v56, v53
	v_add_f32_e32 v20, v20, v22
	v_add_f32_e32 v22, v21, v20
	v_pk_mul_f32 v[20:21], v[56:57], v[80:81]
	v_mov_b32_e32 v64, v61
	v_add_f32_e32 v20, v20, v22
	v_add_f32_e32 v22, v21, v20
	v_pk_mul_f32 v[20:21], v[64:65], v[82:83]
	v_mul_f32_e32 v19, 0x3f317217, v24
	v_add_f32_e32 v20, v20, v22
	v_add_f32_e32 v21, v21, v20
	v_mul_f32_e64 v20, |v21|, s34
	v_exp_f32_e32 v20, v20
	v_fma_f32 v19, v24, s36, -v19
	v_fmac_f32_e32 v19, 0x3377d1cf, v24
	v_fmac_f32_e32 v19, 0x3f317217, v24
	v_cmp_lt_f32_e64 s[0:1], |v24|, s37
	v_add_f32_e32 v20, 1.0, v20
	s_nop 0
	v_cndmask_b32_e64 v19, v24, v19, s[0:1]
	v_cmp_gt_f32_e64 s[0:1], s35, v20
	s_nop 1
	v_cndmask_b32_e64 v22, 0, 32, s[0:1]
	v_ldexp_f32 v20, v20, v22
	v_log_f32_e32 v22, v20
	v_cndmask_b32_e32 v20, 0, v111, vcc
	v_sub_f32_e32 v20, v19, v20
	v_min_f32_e32 v19, 0, v21
	v_mul_f32_e32 v21, 0x3f317217, v22
	v_fma_f32 v21, v22, s36, -v21
	v_fmac_f32_e32 v21, 0x3377d1cf, v22
	v_fmac_f32_e32 v21, 0x3f317217, v22
	v_cmp_lt_f32_e64 vcc, |v22|, s37
	s_nop 1
	v_cndmask_b32_e32 v21, v22, v21, vcc
	v_cndmask_b32_e64 v22, 0, v111, s[0:1]
	v_sub_f32_e32 v21, v21, v22
	v_pk_add_f32 v[18:19], v[18:19], v[20:21] neg_lo:[0,1] neg_hi:[0,1]
	s_nop 0
	v_pk_mul_f32 v[98:99], v[18:19], s[6:7] op_sel_hi:[1,0]
	global_load_dwordx4 v[18:21], v123, s[52:53] offset:592
	global_load_dwordx4 v[22:25], v123, s[10:11] offset:80
	global_load_dwordx4 v[26:29], v123, s[10:11] offset:3152
	global_load_dwordx4 v[30:33], v123, s[10:11] offset:3664
	global_load_dwordx4 v[34:37], v110, s[16:17] offset:80
	global_load_dwordx4 v[38:41], v110, s[16:17] offset:592
	global_load_dwordx4 v[42:45], v110, s[16:17] offset:1104
	global_load_dwordx4 v[46:49], v110, s[16:17] offset:1616
	global_load_dwordx4 v[50:53], v110, s[16:17] offset:2128
	global_load_dwordx4 v[54:57], v110, s[16:17] offset:2640
	global_load_dwordx4 v[58:61], v110, s[16:17] offset:3152
	global_load_dwordx4 v[62:65], v110, s[16:17] offset:3664
	global_load_dwordx4 v[100:103], v123, s[10:11] offset:592
	global_load_dwordx4 v[104:107], v123, s[10:11] offset:1104
	global_load_dwordx4 v[124:127], v123, s[10:11] offset:1616
	global_load_dwordx4 v[128:131], v123, s[10:11] offset:2128
	global_load_dwordx4 v[132:135], v123, s[10:11] offset:2640
	s_waitcnt vmcnt(15)
	v_fma_f32 v146, v22, v118, v18
	v_fma_f32 v20, v24, v118, v20
	s_waitcnt vmcnt(14)
	v_mov_b32_e32 v136, v26
	s_waitcnt vmcnt(13)
	v_mov_b32_e32 v137, v30
	v_fma_f32 v23, v23, v118, v19
	v_mov_b32_e32 v30, v27
	v_mov_b32_e32 v18, v28
	v_mov_b32_e32 v19, v32
	v_pk_mul_f32 v[26:27], v[136:137], v[72:73]
	s_waitcnt vmcnt(12)
	v_mov_b32_e32 v138, v34
	s_waitcnt vmcnt(11)
	v_mov_b32_e32 v139, v38
	s_waitcnt vmcnt(4)
	v_fmac_f32_e32 v146, v100, v117
	v_fmac_f32_e32 v20, v102, v117
	s_waitcnt vmcnt(3)
	v_fmac_f32_e32 v146, v104, v122
	v_fmac_f32_e32 v20, v106, v122
	s_waitcnt vmcnt(2)
	v_fmac_f32_e32 v146, v124, v121
	v_fmac_f32_e32 v20, v126, v121
	s_waitcnt vmcnt(1)
	v_fmac_f32_e32 v146, v128, v120
	v_fmac_f32_e32 v20, v130, v120
	s_waitcnt vmcnt(0)
	v_fmac_f32_e32 v146, v132, v119
	v_fmac_f32_e32 v23, v101, v117
	v_pk_mul_f32 v[18:19], v[18:19], v[72:73]
	v_fmac_f32_e32 v20, v134, v119
	v_add_f32_e32 v24, v146, v26
	v_mov_b32_e32 v38, v35
	v_pk_mul_f32 v[34:35], v[138:139], v[74:75]
	v_fmac_f32_e32 v23, v105, v122
	v_add_f32_e32 v18, v18, v20
	v_add_f32_e32 v20, v24, v27
	v_mov_b32_e32 v140, v42
	v_mov_b32_e32 v141, v46
	v_fmac_f32_e32 v23, v125, v121
	v_add_f32_e32 v20, v20, v34
	v_mov_b32_e32 v46, v43
	v_pk_mul_f32 v[42:43], v[140:141], v[78:79]
	v_fmac_f32_e32 v23, v129, v120
	v_add_f32_e32 v20, v20, v35
	v_mov_b32_e32 v142, v50
	v_mov_b32_e32 v143, v54
	v_pk_mul_f32 v[30:31], v[30:31], v[72:73]
	v_fmac_f32_e32 v23, v133, v119
	v_add_f32_e32 v20, v20, v42
	v_mov_b32_e32 v54, v51
	v_pk_mul_f32 v[50:51], v[142:143], v[80:81]
	v_add_f32_e32 v23, v30, v23
	v_add_f32_e32 v20, v20, v43
	v_mov_b32_e32 v144, v58
	v_mov_b32_e32 v145, v62
	v_pk_mul_f32 v[38:39], v[38:39], v[74:75]
	v_add_f32_e32 v23, v31, v23
	v_add_f32_e32 v20, v20, v50
	v_mov_b32_e32 v62, v59
	v_pk_mul_f32 v[58:59], v[144:145], v[82:83]
	v_add_f32_e32 v23, v38, v23
	v_add_f32_e32 v20, v20, v51
	v_pk_mul_f32 v[46:47], v[46:47], v[78:79]
	v_add_f32_e32 v23, v39, v23
	v_add_f32_e32 v20, v20, v58
	v_add_f32_e32 v23, v46, v23
	v_add_f32_e32 v20, v20, v59
	v_pk_mul_f32 v[54:55], v[54:55], v[80:81]
	v_add_f32_e32 v23, v47, v23
	v_mul_f32_e64 v24, |v20|, s34
	v_add_f32_e32 v23, v54, v23
	v_exp_f32_e32 v24, v24
	v_pk_mul_f32 v[62:63], v[62:63], v[82:83]
	v_add_f32_e32 v23, v55, v23
	v_add_f32_e32 v23, v62, v23
	v_add_f32_e32 v23, v63, v23
	v_mul_f32_e64 v26, |v23|, s34
	v_add_f32_e32 v27, v19, v18
	v_add_f32_e32 v19, 1.0, v24
	v_exp_f32_e32 v26, v26
	v_cmp_gt_f32_e32 vcc, s35, v19
	v_min_f32_e32 v18, 0, v20
	v_mov_b32_e32 v22, v36
	v_cndmask_b32_e64 v24, 0, 32, vcc
	v_ldexp_f32 v19, v19, v24
	v_log_f32_e32 v24, v19
	v_add_f32_e32 v20, 1.0, v26
	v_cmp_gt_f32_e64 s[0:1], s35, v20
	v_min_f32_e32 v19, 0, v23
	v_cndmask_b32_e32 v23, 0, v111, vcc
	v_cndmask_b32_e64 v26, 0, 32, s[0:1]
	v_ldexp_f32 v20, v20, v26
	v_mul_f32_e32 v26, 0x3f317217, v24
	v_fma_f32 v26, v24, s36, -v26
	v_fmac_f32_e32 v26, 0x3377d1cf, v24
	v_fmac_f32_e32 v26, 0x3f317217, v24
	v_cmp_lt_f32_e64 vcc, |v24|, s37
	v_log_f32_e32 v20, v20
	v_fmac_f32_e32 v21, v25, v118
	v_cndmask_b32_e32 v24, v24, v26, vcc
	v_sub_f32_e32 v26, v24, v23
	v_mov_b32_e32 v23, v40
	v_pk_mul_f32 v[22:23], v[22:23], v[74:75]
	v_mul_f32_e32 v28, 0x3f317217, v20
	v_add_f32_e32 v22, v22, v27
	v_add_f32_e32 v24, v23, v22
	v_mov_b32_e32 v22, v44
	v_mov_b32_e32 v23, v48
	v_pk_mul_f32 v[22:23], v[22:23], v[78:79]
	v_fma_f32 v28, v20, s36, -v28
	v_add_f32_e32 v22, v22, v24
	v_add_f32_e32 v24, v23, v22
	v_mov_b32_e32 v22, v52
	v_mov_b32_e32 v23, v56
	v_pk_mul_f32 v[22:23], v[22:23], v[80:81]
	v_fmac_f32_e32 v28, 0x3377d1cf, v20
	v_add_f32_e32 v22, v22, v24
	v_add_f32_e32 v24, v23, v22
	v_mov_b32_e32 v22, v60
	v_mov_b32_e32 v23, v64
	v_pk_mul_f32 v[22:23], v[22:23], v[82:83]
	v_fmac_f32_e32 v28, 0x3f317217, v20
	v_add_f32_e32 v22, v22, v24
	v_add_f32_e32 v22, v23, v22
	v_mul_f32_e64 v23, |v22|, s34
	v_exp_f32_e32 v23, v23
	v_cmp_lt_f32_e64 vcc, |v20|, s37
	v_cndmask_b32_e64 v24, 0, v111, s[0:1]
	v_fmac_f32_e32 v21, v103, v117
	v_cndmask_b32_e32 v20, v20, v28, vcc
	v_sub_f32_e32 v27, v20, v24
	v_add_f32_e32 v20, 1.0, v23
	v_fmac_f32_e32 v21, v107, v122
	v_cmp_gt_f32_e32 vcc, s35, v20
	v_fmac_f32_e32 v21, v127, v121
	v_pk_add_f32 v[18:19], v[18:19], v[26:27] neg_lo:[0,1] neg_hi:[0,1]
	v_cndmask_b32_e64 v23, 0, 32, vcc
	v_fmac_f32_e32 v21, v131, v120
	v_mov_b32_e32 v32, v29
	v_ldexp_f32 v20, v20, v23
	v_pk_mul_f32 v[100:101], v[18:19], s[6:7] op_sel_hi:[1,0]
	v_min_f32_e32 v18, 0, v22
	v_fmac_f32_e32 v21, v135, v119
	v_pk_mul_f32 v[22:23], v[32:33], v[72:73]
	v_log_f32_e32 v24, v20
	v_add_f32_e32 v20, v22, v21
	v_mov_b32_e32 v40, v37
	v_add_f32_e32 v22, v23, v20
	v_pk_mul_f32 v[20:21], v[40:41], v[74:75]
	v_mov_b32_e32 v48, v45
	v_add_f32_e32 v20, v20, v22
	v_add_f32_e32 v22, v21, v20
	v_pk_mul_f32 v[20:21], v[48:49], v[78:79]
	v_mov_b32_e32 v56, v53
	v_add_f32_e32 v20, v20, v22
	v_add_f32_e32 v22, v21, v20
	v_pk_mul_f32 v[20:21], v[56:57], v[80:81]
	v_mov_b32_e32 v64, v61
	v_add_f32_e32 v20, v20, v22
	v_add_f32_e32 v22, v21, v20
	v_pk_mul_f32 v[20:21], v[64:65], v[82:83]
	v_mul_f32_e32 v19, 0x3f317217, v24
	v_add_f32_e32 v20, v20, v22
	v_add_f32_e32 v21, v21, v20
	v_mul_f32_e64 v20, |v21|, s34
	v_exp_f32_e32 v20, v20
	v_fma_f32 v19, v24, s36, -v19
	v_fmac_f32_e32 v19, 0x3377d1cf, v24
	v_fmac_f32_e32 v19, 0x3f317217, v24
	v_cmp_lt_f32_e64 s[0:1], |v24|, s37
	v_add_f32_e32 v20, 1.0, v20
	s_nop 0
	v_cndmask_b32_e64 v19, v24, v19, s[0:1]
	v_cmp_gt_f32_e64 s[0:1], s35, v20
	s_nop 1
	v_cndmask_b32_e64 v22, 0, 32, s[0:1]
	v_ldexp_f32 v20, v20, v22
	v_log_f32_e32 v22, v20
	v_cndmask_b32_e32 v20, 0, v111, vcc
	v_sub_f32_e32 v20, v19, v20
	v_min_f32_e32 v19, 0, v21
	v_mul_f32_e32 v21, 0x3f317217, v22
	v_fma_f32 v21, v22, s36, -v21
	v_fmac_f32_e32 v21, 0x3377d1cf, v22
	v_fmac_f32_e32 v21, 0x3f317217, v22
	v_cmp_lt_f32_e64 vcc, |v22|, s37
	s_nop 1
	v_cndmask_b32_e32 v21, v22, v21, vcc
	v_cndmask_b32_e64 v22, 0, v111, s[0:1]
	v_sub_f32_e32 v21, v21, v22
	v_pk_add_f32 v[18:19], v[18:19], v[20:21] neg_lo:[0,1] neg_hi:[0,1]
	s_nop 0
	v_pk_mul_f32 v[102:103], v[18:19], s[6:7] op_sel_hi:[1,0]
	global_load_dwordx4 v[18:21], v123, s[52:53] offset:608
	global_load_dwordx4 v[22:25], v123, s[10:11] offset:96
	global_load_dwordx4 v[26:29], v123, s[10:11] offset:3168
	global_load_dwordx4 v[30:33], v123, s[10:11] offset:3680
	global_load_dwordx4 v[34:37], v110, s[16:17] offset:96
	global_load_dwordx4 v[38:41], v110, s[16:17] offset:608
	global_load_dwordx4 v[42:45], v110, s[16:17] offset:1120
	global_load_dwordx4 v[46:49], v110, s[16:17] offset:1632
	global_load_dwordx4 v[50:53], v110, s[16:17] offset:2144
	global_load_dwordx4 v[54:57], v110, s[16:17] offset:2656
	global_load_dwordx4 v[58:61], v110, s[16:17] offset:3168
	global_load_dwordx4 v[62:65], v110, s[16:17] offset:3680
	global_load_dwordx4 v[104:107], v123, s[10:11] offset:608
	global_load_dwordx4 v[124:127], v123, s[10:11] offset:1120
	global_load_dwordx4 v[128:131], v123, s[10:11] offset:1632
	global_load_dwordx4 v[132:135], v123, s[10:11] offset:2144
	global_load_dwordx4 v[136:139], v123, s[10:11] offset:2656
	s_waitcnt vmcnt(15)
	v_fma_f32 v150, v22, v118, v18
	v_fma_f32 v20, v24, v118, v20
	s_waitcnt vmcnt(14)
	v_mov_b32_e32 v140, v26
	s_waitcnt vmcnt(13)
	v_mov_b32_e32 v141, v30
	v_fma_f32 v23, v23, v118, v19
	v_mov_b32_e32 v30, v27
	v_mov_b32_e32 v18, v28
	v_mov_b32_e32 v19, v32
	v_pk_mul_f32 v[26:27], v[140:141], v[72:73]
	s_waitcnt vmcnt(12)
	v_mov_b32_e32 v142, v34
	s_waitcnt vmcnt(11)
	v_mov_b32_e32 v143, v38
	s_waitcnt vmcnt(4)
	v_fmac_f32_e32 v150, v104, v117
	v_fmac_f32_e32 v20, v106, v117
	s_waitcnt vmcnt(3)
	v_fmac_f32_e32 v150, v124, v122
	v_fmac_f32_e32 v20, v126, v122
	s_waitcnt vmcnt(2)
	v_fmac_f32_e32 v150, v128, v121
	v_fmac_f32_e32 v20, v130, v121
	s_waitcnt vmcnt(1)
	v_fmac_f32_e32 v150, v132, v120
	v_fmac_f32_e32 v20, v134, v120
	s_waitcnt vmcnt(0)
	v_fmac_f32_e32 v150, v136, v119
	v_fmac_f32_e32 v23, v105, v117
	v_pk_mul_f32 v[18:19], v[18:19], v[72:73]
	v_fmac_f32_e32 v20, v138, v119
	v_add_f32_e32 v24, v150, v26
	v_mov_b32_e32 v38, v35
	v_pk_mul_f32 v[34:35], v[142:143], v[74:75]
	v_fmac_f32_e32 v23, v125, v122
	v_add_f32_e32 v18, v18, v20
	v_add_f32_e32 v20, v24, v27
	v_mov_b32_e32 v144, v42
	v_mov_b32_e32 v145, v46
	v_fmac_f32_e32 v23, v129, v121
	v_add_f32_e32 v20, v20, v34
	v_mov_b32_e32 v46, v43
	v_pk_mul_f32 v[42:43], v[144:145], v[78:79]
	v_fmac_f32_e32 v23, v133, v120
	v_add_f32_e32 v20, v20, v35
	v_mov_b32_e32 v146, v50
	v_mov_b32_e32 v147, v54
	v_pk_mul_f32 v[30:31], v[30:31], v[72:73]
	v_fmac_f32_e32 v23, v137, v119
	v_add_f32_e32 v20, v20, v42
	v_mov_b32_e32 v54, v51
	v_pk_mul_f32 v[50:51], v[146:147], v[80:81]
	v_add_f32_e32 v23, v30, v23
	v_add_f32_e32 v20, v20, v43
	v_mov_b32_e32 v148, v58
	v_mov_b32_e32 v149, v62
	v_pk_mul_f32 v[38:39], v[38:39], v[74:75]
	v_add_f32_e32 v23, v31, v23
	v_add_f32_e32 v20, v20, v50
	v_mov_b32_e32 v62, v59
	v_pk_mul_f32 v[58:59], v[148:149], v[82:83]
	v_add_f32_e32 v23, v38, v23
	v_add_f32_e32 v20, v20, v51
	v_pk_mul_f32 v[46:47], v[46:47], v[78:79]
	v_add_f32_e32 v23, v39, v23
	v_add_f32_e32 v20, v20, v58
	v_add_f32_e32 v23, v46, v23
	v_add_f32_e32 v20, v20, v59
	v_pk_mul_f32 v[54:55], v[54:55], v[80:81]
	v_add_f32_e32 v23, v47, v23
	v_mul_f32_e64 v24, |v20|, s34
	v_add_f32_e32 v23, v54, v23
	v_exp_f32_e32 v24, v24
	v_pk_mul_f32 v[62:63], v[62:63], v[82:83]
	v_add_f32_e32 v23, v55, v23
	v_add_f32_e32 v23, v62, v23
	v_add_f32_e32 v23, v63, v23
	v_mul_f32_e64 v26, |v23|, s34
	v_add_f32_e32 v27, v19, v18
	v_add_f32_e32 v19, 1.0, v24
	v_exp_f32_e32 v26, v26
	v_cmp_gt_f32_e32 vcc, s35, v19
	v_min_f32_e32 v18, 0, v20
	v_mov_b32_e32 v22, v36
	v_cndmask_b32_e64 v24, 0, 32, vcc
	v_ldexp_f32 v19, v19, v24
	v_log_f32_e32 v24, v19
	v_add_f32_e32 v20, 1.0, v26
	v_cmp_gt_f32_e64 s[0:1], s35, v20
	v_min_f32_e32 v19, 0, v23
	v_cndmask_b32_e32 v23, 0, v111, vcc
	v_cndmask_b32_e64 v26, 0, 32, s[0:1]
	v_ldexp_f32 v20, v20, v26
	v_mul_f32_e32 v26, 0x3f317217, v24
	v_fma_f32 v26, v24, s36, -v26
	v_fmac_f32_e32 v26, 0x3377d1cf, v24
	v_fmac_f32_e32 v26, 0x3f317217, v24
	v_cmp_lt_f32_e64 vcc, |v24|, s37
	v_log_f32_e32 v20, v20
	v_fmac_f32_e32 v21, v25, v118
	v_cndmask_b32_e32 v24, v24, v26, vcc
	v_sub_f32_e32 v26, v24, v23
	v_mov_b32_e32 v23, v40
	v_pk_mul_f32 v[22:23], v[22:23], v[74:75]
	v_mul_f32_e32 v28, 0x3f317217, v20
	v_add_f32_e32 v22, v22, v27
	v_add_f32_e32 v24, v23, v22
	v_mov_b32_e32 v22, v44
	v_mov_b32_e32 v23, v48
	v_pk_mul_f32 v[22:23], v[22:23], v[78:79]
	v_fma_f32 v28, v20, s36, -v28
	v_add_f32_e32 v22, v22, v24
	v_add_f32_e32 v24, v23, v22
	v_mov_b32_e32 v22, v52
	v_mov_b32_e32 v23, v56
	v_pk_mul_f32 v[22:23], v[22:23], v[80:81]
	v_fmac_f32_e32 v28, 0x3377d1cf, v20
	v_add_f32_e32 v22, v22, v24
	v_add_f32_e32 v24, v23, v22
	v_mov_b32_e32 v22, v60
	v_mov_b32_e32 v23, v64
	v_pk_mul_f32 v[22:23], v[22:23], v[82:83]
	v_fmac_f32_e32 v28, 0x3f317217, v20
	v_add_f32_e32 v22, v22, v24
	v_add_f32_e32 v22, v23, v22
	v_mul_f32_e64 v23, |v22|, s34
	v_exp_f32_e32 v23, v23
	v_cmp_lt_f32_e64 vcc, |v20|, s37
	v_cndmask_b32_e64 v24, 0, v111, s[0:1]
	v_fmac_f32_e32 v21, v107, v117
	v_cndmask_b32_e32 v20, v20, v28, vcc
	v_sub_f32_e32 v27, v20, v24
	v_add_f32_e32 v20, 1.0, v23
	v_fmac_f32_e32 v21, v127, v122
	v_cmp_gt_f32_e32 vcc, s35, v20
	v_fmac_f32_e32 v21, v131, v121
	v_pk_add_f32 v[18:19], v[18:19], v[26:27] neg_lo:[0,1] neg_hi:[0,1]
	v_cndmask_b32_e64 v23, 0, 32, vcc
	v_fmac_f32_e32 v21, v135, v120
	v_mov_b32_e32 v32, v29
	v_ldexp_f32 v20, v20, v23
	v_pk_mul_f32 v[104:105], v[18:19], s[6:7] op_sel_hi:[1,0]
	v_min_f32_e32 v18, 0, v22
	v_fmac_f32_e32 v21, v139, v119
	v_pk_mul_f32 v[22:23], v[32:33], v[72:73]
	v_log_f32_e32 v24, v20
	v_add_f32_e32 v20, v22, v21
	v_mov_b32_e32 v40, v37
	v_add_f32_e32 v22, v23, v20
	v_pk_mul_f32 v[20:21], v[40:41], v[74:75]
	v_mov_b32_e32 v48, v45
	v_add_f32_e32 v20, v20, v22
	v_add_f32_e32 v22, v21, v20
	v_pk_mul_f32 v[20:21], v[48:49], v[78:79]
	v_mov_b32_e32 v56, v53
	v_add_f32_e32 v20, v20, v22
	v_add_f32_e32 v22, v21, v20
	v_pk_mul_f32 v[20:21], v[56:57], v[80:81]
	v_mov_b32_e32 v64, v61
	v_add_f32_e32 v20, v20, v22
	v_add_f32_e32 v22, v21, v20
	v_pk_mul_f32 v[20:21], v[64:65], v[82:83]
	v_mul_f32_e32 v19, 0x3f317217, v24
	v_add_f32_e32 v20, v20, v22
	v_add_f32_e32 v21, v21, v20
	v_mul_f32_e64 v20, |v21|, s34
	v_exp_f32_e32 v20, v20
	v_fma_f32 v19, v24, s36, -v19
	v_fmac_f32_e32 v19, 0x3377d1cf, v24
	v_fmac_f32_e32 v19, 0x3f317217, v24
	v_cmp_lt_f32_e64 s[0:1], |v24|, s37
	v_add_f32_e32 v20, 1.0, v20
	s_nop 0
	v_cndmask_b32_e64 v19, v24, v19, s[0:1]
	v_cmp_gt_f32_e64 s[0:1], s35, v20
	s_nop 1
	v_cndmask_b32_e64 v22, 0, 32, s[0:1]
	v_ldexp_f32 v20, v20, v22
	v_log_f32_e32 v22, v20
	v_cndmask_b32_e32 v20, 0, v111, vcc
	v_sub_f32_e32 v20, v19, v20
	v_min_f32_e32 v19, 0, v21
	v_mul_f32_e32 v21, 0x3f317217, v22
	v_fma_f32 v21, v22, s36, -v21
	v_fmac_f32_e32 v21, 0x3377d1cf, v22
	v_fmac_f32_e32 v21, 0x3f317217, v22
	v_cmp_lt_f32_e64 vcc, |v22|, s37
	s_nop 1
	v_cndmask_b32_e32 v21, v22, v21, vcc
	v_cndmask_b32_e64 v22, 0, v111, s[0:1]
	v_sub_f32_e32 v21, v21, v22
	v_pk_add_f32 v[18:19], v[18:19], v[20:21] neg_lo:[0,1] neg_hi:[0,1]
	s_nop 0
	v_pk_mul_f32 v[106:107], v[18:19], s[6:7] op_sel_hi:[1,0]
	global_load_dwordx4 v[18:21], v123, s[52:53] offset:624
	global_load_dwordx4 v[22:25], v123, s[10:11] offset:112
	global_load_dwordx4 v[26:29], v123, s[10:11] offset:3184
	global_load_dwordx4 v[30:33], v123, s[10:11] offset:3696
	global_load_dwordx4 v[34:37], v110, s[16:17] offset:112
	global_load_dwordx4 v[38:41], v110, s[16:17] offset:624
	global_load_dwordx4 v[42:45], v110, s[16:17] offset:1136
	global_load_dwordx4 v[46:49], v110, s[16:17] offset:1648
	global_load_dwordx4 v[50:53], v110, s[16:17] offset:2160
	global_load_dwordx4 v[54:57], v110, s[16:17] offset:2672
	global_load_dwordx4 v[58:61], v110, s[16:17] offset:3184
	global_load_dwordx4 v[62:65], v110, s[16:17] offset:3696
	global_load_dwordx4 v[124:127], v123, s[10:11] offset:624
	global_load_dwordx4 v[128:131], v123, s[10:11] offset:1136
	global_load_dwordx4 v[132:135], v123, s[10:11] offset:1648
	global_load_dwordx4 v[136:139], v123, s[10:11] offset:2160
	global_load_dwordx4 v[140:143], v123, s[10:11] offset:2672
	s_waitcnt vmcnt(15)
	v_fma_f32 v123, v22, v118, v18
	v_fma_f32 v20, v24, v118, v20
	s_waitcnt vmcnt(14)
	v_mov_b32_e32 v144, v26
	s_waitcnt vmcnt(13)
	v_mov_b32_e32 v145, v30
	v_fma_f32 v23, v23, v118, v19
	v_mov_b32_e32 v30, v27
	v_mov_b32_e32 v18, v28
	v_mov_b32_e32 v19, v32
	v_pk_mul_f32 v[26:27], v[144:145], v[72:73]
	s_waitcnt vmcnt(12)
	v_mov_b32_e32 v146, v34
	s_waitcnt vmcnt(11)
	v_mov_b32_e32 v147, v38
	s_waitcnt vmcnt(4)
	v_fmac_f32_e32 v123, v124, v117
	v_fmac_f32_e32 v20, v126, v117
	s_waitcnt vmcnt(3)
	v_fmac_f32_e32 v123, v128, v122
	v_fmac_f32_e32 v20, v130, v122
	s_waitcnt vmcnt(2)
	v_fmac_f32_e32 v123, v132, v121
	v_fmac_f32_e32 v20, v134, v121
	s_waitcnt vmcnt(1)
	v_fmac_f32_e32 v123, v136, v120
	v_fmac_f32_e32 v20, v138, v120
	s_waitcnt vmcnt(0)
	v_fmac_f32_e32 v123, v140, v119
	v_fmac_f32_e32 v23, v125, v117
	v_pk_mul_f32 v[18:19], v[18:19], v[72:73]
	v_fmac_f32_e32 v20, v142, v119
	v_add_f32_e32 v24, v123, v26
	v_mov_b32_e32 v38, v35
	v_pk_mul_f32 v[34:35], v[146:147], v[74:75]
	v_fmac_f32_e32 v23, v129, v122
	v_add_f32_e32 v18, v18, v20
	v_add_f32_e32 v20, v24, v27
	v_mov_b32_e32 v148, v42
	v_mov_b32_e32 v149, v46
	v_fmac_f32_e32 v23, v133, v121
	v_add_f32_e32 v20, v20, v34
	v_mov_b32_e32 v46, v43
	v_pk_mul_f32 v[42:43], v[148:149], v[78:79]
	v_fmac_f32_e32 v23, v137, v120
	v_add_f32_e32 v20, v20, v35
	v_mov_b32_e32 v150, v50
	v_mov_b32_e32 v151, v54
	v_pk_mul_f32 v[30:31], v[30:31], v[72:73]
	v_fmac_f32_e32 v23, v141, v119
	v_add_f32_e32 v20, v20, v42
	v_mov_b32_e32 v54, v51
	v_pk_mul_f32 v[50:51], v[150:151], v[80:81]
	v_add_f32_e32 v23, v30, v23
	v_add_f32_e32 v20, v20, v43
	v_mov_b32_e32 v152, v58
	v_mov_b32_e32 v153, v62
	v_pk_mul_f32 v[38:39], v[38:39], v[74:75]
	v_add_f32_e32 v23, v31, v23
	v_add_f32_e32 v20, v20, v50
	v_mov_b32_e32 v62, v59
	v_pk_mul_f32 v[58:59], v[152:153], v[82:83]
	v_add_f32_e32 v23, v38, v23
	v_add_f32_e32 v20, v20, v51
	v_pk_mul_f32 v[46:47], v[46:47], v[78:79]
	v_add_f32_e32 v23, v39, v23
	v_add_f32_e32 v20, v20, v58
	v_add_f32_e32 v23, v46, v23
	v_add_f32_e32 v20, v20, v59
	v_pk_mul_f32 v[54:55], v[54:55], v[80:81]
	v_add_f32_e32 v23, v47, v23
	v_mul_f32_e64 v24, |v20|, s34
	v_add_f32_e32 v23, v54, v23
	v_exp_f32_e32 v24, v24
	v_pk_mul_f32 v[62:63], v[62:63], v[82:83]
	v_add_f32_e32 v23, v55, v23
	v_add_f32_e32 v23, v62, v23
	v_add_f32_e32 v23, v63, v23
	v_mul_f32_e64 v26, |v23|, s34
	v_add_f32_e32 v27, v19, v18
	v_add_f32_e32 v19, 1.0, v24
	v_exp_f32_e32 v26, v26
	v_cmp_gt_f32_e32 vcc, s35, v19
	v_min_f32_e32 v18, 0, v20
	v_mov_b32_e32 v22, v36
	v_cndmask_b32_e64 v24, 0, 32, vcc
	v_ldexp_f32 v19, v19, v24
	v_log_f32_e32 v24, v19
	v_add_f32_e32 v20, 1.0, v26
	v_cmp_gt_f32_e64 s[0:1], s35, v20
	v_min_f32_e32 v19, 0, v23
	v_cndmask_b32_e32 v23, 0, v111, vcc
	v_cndmask_b32_e64 v26, 0, 32, s[0:1]
	v_ldexp_f32 v20, v20, v26
	v_mul_f32_e32 v26, 0x3f317217, v24
	v_fma_f32 v26, v24, s36, -v26
	v_fmac_f32_e32 v26, 0x3377d1cf, v24
	v_fmac_f32_e32 v26, 0x3f317217, v24
	v_cmp_lt_f32_e64 vcc, |v24|, s37
	v_log_f32_e32 v20, v20
	v_fmac_f32_e32 v21, v25, v118
	v_cndmask_b32_e32 v24, v24, v26, vcc
	v_sub_f32_e32 v26, v24, v23
	v_mov_b32_e32 v23, v40
	v_pk_mul_f32 v[22:23], v[22:23], v[74:75]
	v_mul_f32_e32 v28, 0x3f317217, v20
	v_add_f32_e32 v22, v22, v27
	v_add_f32_e32 v24, v23, v22
	v_mov_b32_e32 v22, v44
	v_mov_b32_e32 v23, v48
	v_pk_mul_f32 v[22:23], v[22:23], v[78:79]
	v_fma_f32 v28, v20, s36, -v28
	v_add_f32_e32 v22, v22, v24
	v_add_f32_e32 v24, v23, v22
	v_mov_b32_e32 v22, v52
	v_mov_b32_e32 v23, v56
	v_pk_mul_f32 v[22:23], v[22:23], v[80:81]
	v_fmac_f32_e32 v28, 0x3377d1cf, v20
	v_add_f32_e32 v22, v22, v24
	v_add_f32_e32 v24, v23, v22
	v_mov_b32_e32 v22, v60
	v_mov_b32_e32 v23, v64
	v_pk_mul_f32 v[22:23], v[22:23], v[82:83]
	v_fmac_f32_e32 v28, 0x3f317217, v20
	v_add_f32_e32 v22, v22, v24
	v_add_f32_e32 v22, v23, v22
	v_mul_f32_e64 v23, |v22|, s34
	v_exp_f32_e32 v23, v23
	v_cmp_lt_f32_e64 vcc, |v20|, s37
	v_cndmask_b32_e64 v24, 0, v111, s[0:1]
	v_fmac_f32_e32 v21, v127, v117
	v_cndmask_b32_e32 v20, v20, v28, vcc
	v_sub_f32_e32 v27, v20, v24
	v_add_f32_e32 v20, 1.0, v23
	v_cmp_gt_f32_e32 vcc, s35, v20
	v_fmac_f32_e32 v21, v131, v122
	v_fmac_f32_e32 v21, v135, v121
	v_cndmask_b32_e64 v23, 0, 32, vcc
	v_ldexp_f32 v20, v20, v23
	v_log_f32_e32 v24, v20
	v_min_f32_e32 v20, 0, v22
	v_fmac_f32_e32 v21, v139, v120
	v_mov_b32_e32 v32, v29
	v_mul_f32_e32 v22, 0x3f317217, v24
	v_pk_add_f32 v[18:19], v[18:19], v[26:27] neg_lo:[0,1] neg_hi:[0,1]
	v_fma_f32 v26, v24, s36, -v22
	v_fmac_f32_e32 v21, v143, v119
	v_pk_mul_f32 v[22:23], v[32:33], v[72:73]
	v_mov_b32_e32 v40, v37
	v_add_f32_e32 v21, v22, v21
	v_add_f32_e32 v21, v23, v21
	v_pk_mul_f32 v[22:23], v[40:41], v[74:75]
	v_mov_b32_e32 v48, v45
	v_add_f32_e32 v21, v22, v21
	v_add_f32_e32 v21, v23, v21
	v_pk_mul_f32 v[22:23], v[48:49], v[78:79]
	v_mov_b32_e32 v56, v53
	v_add_f32_e32 v21, v22, v21
	v_add_f32_e32 v21, v23, v21
	v_pk_mul_f32 v[22:23], v[56:57], v[80:81]
	v_mov_b32_e32 v64, v61
	v_add_f32_e32 v21, v22, v21
	v_add_f32_e32 v21, v23, v21
	v_pk_mul_f32 v[22:23], v[64:65], v[82:83]
	v_fmac_f32_e32 v26, 0x3377d1cf, v24
	v_add_f32_e32 v21, v22, v21
	v_add_f32_e32 v21, v23, v21
	v_mul_f32_e64 v22, |v21|, s34
	v_exp_f32_e32 v22, v22
	v_fmac_f32_e32 v26, 0x3f317217, v24
	v_cmp_lt_f32_e64 s[0:1], |v24|, s37
	v_min_f32_e32 v21, 0, v21
	v_add_f32_e32 v22, 1.0, v22
	v_cndmask_b32_e64 v23, v24, v26, s[0:1]
	v_cmp_gt_f32_e64 s[0:1], s35, v22
	v_pk_mul_f32 v[18:19], v[18:19], s[6:7] op_sel_hi:[1,0]
	s_nop 0
	v_cndmask_b32_e64 v24, 0, 32, s[0:1]
	v_ldexp_f32 v22, v22, v24
	v_log_f32_e32 v24, v22
	v_cndmask_b32_e32 v22, 0, v111, vcc
	v_sub_f32_e32 v22, v23, v22
	v_mul_f32_e32 v23, 0x3f317217, v24
	v_fma_f32 v23, v24, s36, -v23
	v_fmac_f32_e32 v23, 0x3377d1cf, v24
	v_fmac_f32_e32 v23, 0x3f317217, v24
	v_cmp_lt_f32_e64 vcc, |v24|, s37
	s_nop 1
	v_cndmask_b32_e32 v23, v24, v23, vcc
	v_cndmask_b32_e64 v24, 0, v111, s[0:1]
	v_sub_f32_e32 v23, v23, v24
	v_pk_add_f32 v[20:21], v[20:21], v[22:23] neg_lo:[0,1] neg_hi:[0,1]
	s_nop 0
	v_pk_mul_f32 v[20:21], v[20:21], s[6:7] op_sel_hi:[1,0]
	v_cmp_ne_u32_e32 vcc, 63, v113
	v_cmp_gt_u32_e64 s[0:1], 62, v113
	s_nop 0
	v_addc_co_u32_e32 v22, vcc, 0, v112, vcc
	v_lshlrev_b32_e32 v22, 2, v22
	ds_bpermute_b32 v23, v22, v70
	ds_bpermute_b32 v24, v22, v71
	ds_bpermute_b32 v25, v22, v76
	ds_bpermute_b32 v26, v22, v77
	ds_bpermute_b32 v27, v22, v84
	ds_bpermute_b32 v28, v22, v85
	ds_bpermute_b32 v29, v22, v86
	ds_bpermute_b32 v30, v22, v87
	ds_bpermute_b32 v31, v22, v88
	ds_bpermute_b32 v32, v22, v89
	ds_bpermute_b32 v33, v22, v90
	ds_bpermute_b32 v34, v22, v91
	ds_bpermute_b32 v35, v22, v92
	ds_bpermute_b32 v36, v22, v93
	ds_bpermute_b32 v37, v22, v94
	ds_bpermute_b32 v38, v22, v95
	ds_bpermute_b32 v39, v22, v96
	ds_bpermute_b32 v40, v22, v97
	ds_bpermute_b32 v41, v22, v98
	ds_bpermute_b32 v42, v22, v99
	ds_bpermute_b32 v43, v22, v100
	ds_bpermute_b32 v44, v22, v101
	ds_bpermute_b32 v45, v22, v102
	ds_bpermute_b32 v46, v22, v103
	ds_bpermute_b32 v47, v22, v104
	ds_bpermute_b32 v48, v22, v105
	ds_bpermute_b32 v49, v22, v106
	ds_bpermute_b32 v50, v22, v107
	ds_bpermute_b32 v51, v22, v18
	ds_bpermute_b32 v52, v22, v19
	ds_bpermute_b32 v53, v22, v20
	ds_bpermute_b32 v22, v22, v21
	v_cmp_gt_i32_e32 vcc, 63, v68
	s_waitcnt lgkmcnt(6)
	v_add_f32_e32 v48, v105, v48
	v_add_f32_e32 v23, v70, v23
	v_add_f32_e32 v24, v71, v24
	s_waitcnt lgkmcnt(0)
	v_add_f32_e32 v22, v21, v22
	v_add_f32_e32 v25, v76, v25
	v_add_f32_e32 v26, v77, v26
	v_add_f32_e32 v27, v84, v27
	v_add_f32_e32 v28, v85, v28
	v_add_f32_e32 v29, v86, v29
	v_add_f32_e32 v30, v87, v30
	v_add_f32_e32 v31, v88, v31
	v_add_f32_e32 v32, v89, v32
	v_add_f32_e32 v33, v90, v33
	v_add_f32_e32 v34, v91, v34
	v_add_f32_e32 v35, v92, v35
	v_add_f32_e32 v36, v93, v36
	v_add_f32_e32 v37, v94, v37
	v_add_f32_e32 v38, v95, v38
	v_add_f32_e32 v39, v96, v39
	v_add_f32_e32 v40, v97, v40
	v_add_f32_e32 v41, v98, v41
	v_add_f32_e32 v42, v99, v42
	v_add_f32_e32 v43, v100, v43
	v_add_f32_e32 v44, v101, v44
	v_add_f32_e32 v45, v102, v45
	v_add_f32_e32 v46, v103, v46
	v_add_f32_e32 v47, v104, v47
	v_add_f32_e32 v49, v106, v49
	v_add_f32_e32 v50, v107, v50
	v_add_f32_e32 v51, v18, v51
	v_add_f32_e32 v52, v19, v52
	v_add_f32_e32 v53, v20, v53
	v_cndmask_b32_e32 v21, v21, v22, vcc
	v_cndmask_b32_e32 v22, v105, v48, vcc
	v_cndmask_b32_e64 v48, 0, 2, s[0:1]
	v_cndmask_b32_e32 v23, v70, v23, vcc
	v_cndmask_b32_e32 v25, v76, v25, vcc
	v_cndmask_b32_e32 v26, v77, v26, vcc
	v_cndmask_b32_e32 v28, v85, v28, vcc
	v_cndmask_b32_e32 v29, v86, v29, vcc
	v_cndmask_b32_e32 v31, v88, v31, vcc
	v_cndmask_b32_e32 v32, v89, v32, vcc
	v_cndmask_b32_e32 v34, v91, v34, vcc
	v_cndmask_b32_e32 v35, v92, v35, vcc
	v_cndmask_b32_e32 v37, v94, v37, vcc
	v_cndmask_b32_e32 v38, v95, v38, vcc
	v_cndmask_b32_e32 v40, v97, v40, vcc
	v_cndmask_b32_e32 v41, v98, v41, vcc
	v_cndmask_b32_e32 v43, v100, v43, vcc
	v_cndmask_b32_e32 v44, v101, v44, vcc
	v_cndmask_b32_e32 v46, v103, v46, vcc
	v_cndmask_b32_e32 v47, v104, v47, vcc
	v_cndmask_b32_e32 v49, v106, v49, vcc
	v_cndmask_b32_e32 v50, v107, v50, vcc
	v_cndmask_b32_e32 v52, v19, v52, vcc
	v_cndmask_b32_e32 v53, v20, v53, vcc
	v_cndmask_b32_e32 v18, v18, v51, vcc
	v_cndmask_b32_e32 v45, v102, v45, vcc
	v_cndmask_b32_e32 v42, v99, v42, vcc
	v_cndmask_b32_e32 v39, v96, v39, vcc
	v_cndmask_b32_e32 v36, v93, v36, vcc
	v_cndmask_b32_e32 v33, v90, v33, vcc
	v_add_lshl_u32 v48, v48, v112, 2
	v_cndmask_b32_e32 v30, v87, v30, vcc
	v_cndmask_b32_e32 v27, v84, v27, vcc
	v_cndmask_b32_e32 v24, v71, v24, vcc
	v_cndmask_b32_e32 v54, v70, v23, vcc
	v_cndmask_b32_e32 v55, v76, v25, vcc
	v_cndmask_b32_e32 v57, v85, v28, vcc
	v_cndmask_b32_e32 v58, v86, v29, vcc
	v_cndmask_b32_e32 v59, v88, v31, vcc
	v_cndmask_b32_e32 v60, v89, v32, vcc
	v_cndmask_b32_e32 v61, v91, v34, vcc
	v_cndmask_b32_e32 v62, v92, v35, vcc
	v_cndmask_b32_e32 v63, v94, v37, vcc
	v_cndmask_b32_e32 v64, v95, v38, vcc
	v_cndmask_b32_e32 v65, v97, v40, vcc
	v_cndmask_b32_e32 v70, v98, v41, vcc
	v_cndmask_b32_e32 v72, v100, v43, vcc
	v_cndmask_b32_e32 v73, v101, v44, vcc
	v_cndmask_b32_e32 v74, v103, v46, vcc
	v_cndmask_b32_e32 v75, v104, v47, vcc
	v_cndmask_b32_e32 v76, v106, v49, vcc
	ds_bpermute_b32 v51, v48, v23
	ds_bpermute_b32 v71, v48, v24
	ds_bpermute_b32 v78, v48, v25
	ds_bpermute_b32 v79, v48, v26
	ds_bpermute_b32 v80, v48, v27
	ds_bpermute_b32 v81, v48, v28
	ds_bpermute_b32 v82, v48, v29
	ds_bpermute_b32 v83, v48, v30
	ds_bpermute_b32 v84, v48, v31
	ds_bpermute_b32 v85, v48, v32
	ds_bpermute_b32 v86, v48, v33
	ds_bpermute_b32 v87, v48, v34
	ds_bpermute_b32 v88, v48, v35
	ds_bpermute_b32 v89, v48, v36
	ds_bpermute_b32 v90, v48, v37
	ds_bpermute_b32 v91, v48, v38
	ds_bpermute_b32 v92, v48, v39
	ds_bpermute_b32 v93, v48, v40
	ds_bpermute_b32 v94, v48, v41
	ds_bpermute_b32 v95, v48, v42
	ds_bpermute_b32 v96, v48, v43
	ds_bpermute_b32 v97, v48, v44
	ds_bpermute_b32 v98, v48, v45
	ds_bpermute_b32 v99, v48, v46
	ds_bpermute_b32 v100, v48, v47
	ds_bpermute_b32 v101, v48, v22
	ds_bpermute_b32 v102, v48, v49
	ds_bpermute_b32 v103, v48, v50
	ds_bpermute_b32 v104, v48, v18
	ds_bpermute_b32 v105, v48, v52
	ds_bpermute_b32 v106, v48, v53
	ds_bpermute_b32 v48, v48, v21
	v_cndmask_b32_e32 v56, v77, v26, vcc
	v_cndmask_b32_e32 v77, v107, v50, vcc
	v_cndmask_b32_e32 v19, v19, v52, vcc
	v_cndmask_b32_e32 v20, v20, v53, vcc
	v_cmp_gt_i32_e32 vcc, 62, v68
	s_waitcnt lgkmcnt(0)
	v_add_f32_e32 v48, v21, v48
	v_cmp_gt_u32_e64 s[0:1], 60, v113
	v_add_f32_e32 v51, v23, v51
	v_add_f32_e32 v71, v24, v71
	v_add_f32_e32 v78, v25, v78
	v_add_f32_e32 v79, v26, v79
	v_add_f32_e32 v80, v27, v80
	v_add_f32_e32 v81, v28, v81
	v_add_f32_e32 v82, v29, v82
	v_add_f32_e32 v83, v30, v83
	v_add_f32_e32 v84, v31, v84
	v_add_f32_e32 v85, v32, v85
	v_add_f32_e32 v86, v33, v86
	v_add_f32_e32 v87, v34, v87
	v_add_f32_e32 v88, v35, v88
	v_add_f32_e32 v89, v36, v89
	v_add_f32_e32 v90, v37, v90
	v_add_f32_e32 v91, v38, v91
	v_add_f32_e32 v92, v39, v92
	v_add_f32_e32 v93, v40, v93
	v_add_f32_e32 v94, v41, v94
	v_add_f32_e32 v95, v42, v95
	v_add_f32_e32 v96, v43, v96
	v_add_f32_e32 v97, v44, v97
	v_add_f32_e32 v98, v45, v98
	v_add_f32_e32 v99, v46, v99
	v_add_f32_e32 v100, v47, v100
	v_add_f32_e32 v101, v22, v101
	v_add_f32_e32 v102, v49, v102
	v_add_f32_e32 v103, v50, v103
	v_add_f32_e32 v104, v18, v104
	v_add_f32_e32 v105, v52, v105
	v_add_f32_e32 v106, v53, v106
	v_cndmask_b32_e32 v21, v21, v48, vcc
	v_cndmask_b32_e64 v48, 0, 4, s[0:1]
	v_cndmask_b32_e32 v23, v23, v51, vcc
	v_cndmask_b32_e32 v25, v25, v78, vcc
	v_cndmask_b32_e32 v26, v26, v79, vcc
	v_cndmask_b32_e32 v28, v28, v81, vcc
	v_cndmask_b32_e32 v29, v29, v82, vcc
	v_cndmask_b32_e32 v31, v31, v84, vcc
	v_cndmask_b32_e32 v32, v32, v85, vcc
	v_cndmask_b32_e32 v34, v34, v87, vcc
	v_cndmask_b32_e32 v35, v35, v88, vcc
	v_cndmask_b32_e32 v37, v37, v90, vcc
	v_cndmask_b32_e32 v38, v38, v91, vcc
	v_cndmask_b32_e32 v40, v40, v93, vcc
	v_cndmask_b32_e32 v41, v41, v94, vcc
	v_cndmask_b32_e32 v43, v43, v96, vcc
	v_cndmask_b32_e32 v44, v44, v97, vcc
	v_cndmask_b32_e32 v46, v46, v99, vcc
	v_cndmask_b32_e32 v47, v47, v100, vcc
	v_cndmask_b32_e32 v49, v49, v102, vcc
	v_cndmask_b32_e32 v50, v50, v103, vcc
	v_cndmask_b32_e32 v52, v52, v105, vcc
	v_cndmask_b32_e32 v53, v53, v106, vcc
	v_cndmask_b32_e32 v18, v18, v104, vcc
	v_cndmask_b32_e32 v22, v22, v101, vcc
	v_cndmask_b32_e32 v45, v45, v98, vcc
	v_cndmask_b32_e32 v42, v42, v95, vcc
	v_cndmask_b32_e32 v39, v39, v92, vcc
	v_cndmask_b32_e32 v36, v36, v89, vcc
	v_cndmask_b32_e32 v33, v33, v86, vcc
	v_add_lshl_u32 v48, v48, v112, 2
	v_cndmask_b32_e32 v30, v30, v83, vcc
	v_cndmask_b32_e32 v27, v27, v80, vcc
	v_cndmask_b32_e32 v24, v24, v71, vcc
	v_cndmask_b32_e32 v20, v20, v106, vcc
	v_cndmask_b32_e32 v19, v19, v105, vcc
	v_cndmask_b32_e32 v77, v77, v103, vcc
	v_cndmask_b32_e32 v76, v76, v102, vcc
	v_cndmask_b32_e32 v75, v75, v100, vcc
	v_cndmask_b32_e32 v74, v74, v99, vcc
	v_cndmask_b32_e32 v73, v73, v97, vcc
	v_cndmask_b32_e32 v72, v72, v96, vcc
	v_cndmask_b32_e32 v70, v70, v94, vcc
	v_cndmask_b32_e32 v65, v65, v93, vcc
	v_cndmask_b32_e32 v64, v64, v91, vcc
	v_cndmask_b32_e32 v63, v63, v90, vcc
	v_cndmask_b32_e32 v62, v62, v88, vcc
	v_cndmask_b32_e32 v61, v61, v87, vcc
	v_cndmask_b32_e32 v60, v60, v85, vcc
	v_cndmask_b32_e32 v59, v59, v84, vcc
	v_cndmask_b32_e32 v58, v58, v82, vcc
	v_cndmask_b32_e32 v57, v57, v81, vcc
	v_cndmask_b32_e32 v56, v56, v79, vcc
	v_cndmask_b32_e32 v55, v55, v78, vcc
	v_cndmask_b32_e32 v51, v54, v51, vcc
	ds_bpermute_b32 v54, v48, v23
	ds_bpermute_b32 v71, v48, v24
	ds_bpermute_b32 v78, v48, v25
	ds_bpermute_b32 v79, v48, v26
	ds_bpermute_b32 v80, v48, v27
	ds_bpermute_b32 v81, v48, v28
	ds_bpermute_b32 v82, v48, v29
	ds_bpermute_b32 v83, v48, v30
	ds_bpermute_b32 v84, v48, v31
	ds_bpermute_b32 v85, v48, v32
	ds_bpermute_b32 v86, v48, v33
	ds_bpermute_b32 v87, v48, v34
	ds_bpermute_b32 v88, v48, v35
	ds_bpermute_b32 v89, v48, v36
	ds_bpermute_b32 v90, v48, v37
	ds_bpermute_b32 v91, v48, v38
	ds_bpermute_b32 v92, v48, v39
	ds_bpermute_b32 v93, v48, v40
	ds_bpermute_b32 v94, v48, v41
	ds_bpermute_b32 v95, v48, v42
	ds_bpermute_b32 v96, v48, v43
	ds_bpermute_b32 v97, v48, v44
	ds_bpermute_b32 v98, v48, v45
	ds_bpermute_b32 v99, v48, v46
	ds_bpermute_b32 v100, v48, v47
	ds_bpermute_b32 v101, v48, v22
	ds_bpermute_b32 v102, v48, v49
	ds_bpermute_b32 v103, v48, v50
	ds_bpermute_b32 v104, v48, v18
	ds_bpermute_b32 v105, v48, v52
	ds_bpermute_b32 v106, v48, v53
	ds_bpermute_b32 v48, v48, v21
	v_cmp_gt_i32_e32 vcc, 60, v68
	v_cmp_gt_u32_e64 s[0:1], 56, v113
	s_waitcnt lgkmcnt(14)
	v_add_f32_e32 v54, v23, v54
	v_add_f32_e32 v71, v24, v71
	s_waitcnt lgkmcnt(0)
	v_add_f32_e32 v48, v21, v48
	v_cndmask_b32_e32 v21, v21, v48, vcc
	v_cndmask_b32_e64 v48, 0, 8, s[0:1]
	v_cndmask_b32_e32 v23, v23, v54, vcc
	v_add_f32_e32 v78, v25, v78
	v_add_f32_e32 v79, v26, v79
	v_add_f32_e32 v81, v28, v81
	v_add_f32_e32 v82, v29, v82
	v_add_f32_e32 v84, v31, v84
	v_add_f32_e32 v85, v32, v85
	v_add_f32_e32 v87, v34, v87
	v_add_f32_e32 v88, v35, v88
	v_add_f32_e32 v90, v37, v90
	v_add_f32_e32 v91, v38, v91
	v_add_f32_e32 v93, v40, v93
	v_add_f32_e32 v94, v41, v94
	v_add_f32_e32 v96, v43, v96
	v_add_f32_e32 v97, v44, v97
	v_add_f32_e32 v99, v46, v99
	v_add_f32_e32 v100, v47, v100
	v_add_f32_e32 v102, v49, v102
	v_add_f32_e32 v103, v50, v103
	v_cndmask_b32_e32 v24, v24, v71, vcc
	v_add_lshl_u32 v48, v48, v112, 2
	v_cndmask_b32_e32 v51, v51, v54, vcc
	v_cndmask_b32_e32 v54, v55, v78, vcc
	v_cndmask_b32_e32 v55, v56, v79, vcc
	v_cndmask_b32_e32 v56, v57, v81, vcc
	v_cndmask_b32_e32 v57, v58, v82, vcc
	v_cndmask_b32_e32 v58, v59, v84, vcc
	v_cndmask_b32_e32 v59, v60, v85, vcc
	v_cndmask_b32_e32 v60, v61, v87, vcc
	v_cndmask_b32_e32 v61, v62, v88, vcc
	v_cndmask_b32_e32 v62, v63, v90, vcc
	v_cndmask_b32_e32 v63, v64, v91, vcc
	v_cndmask_b32_e32 v64, v65, v93, vcc
	v_cndmask_b32_e32 v65, v70, v94, vcc
	v_cndmask_b32_e32 v70, v72, v96, vcc
	v_cndmask_b32_e32 v72, v73, v97, vcc
	v_cndmask_b32_e32 v73, v74, v99, vcc
	v_cndmask_b32_e32 v74, v75, v100, vcc
	v_cndmask_b32_e32 v75, v76, v102, vcc
	v_cndmask_b32_e32 v76, v77, v103, vcc
	ds_bpermute_b32 v71, v48, v23
	ds_bpermute_b32 v77, v48, v24
	v_add_f32_e32 v80, v27, v80
	v_cndmask_b32_e32 v25, v25, v78, vcc
	v_cndmask_b32_e32 v28, v28, v81, vcc
	v_cndmask_b32_e32 v29, v29, v82, vcc
	v_cndmask_b32_e32 v27, v27, v80, vcc
	v_cndmask_b32_e32 v26, v26, v79, vcc
	s_waitcnt lgkmcnt(1)
	v_add_f32_e32 v23, v23, v71
	s_waitcnt lgkmcnt(0)
	v_add_f32_e32 v71, v24, v77
	ds_bpermute_b32 v77, v48, v25
	ds_bpermute_b32 v79, v48, v27
	ds_bpermute_b32 v80, v48, v28
	ds_bpermute_b32 v81, v48, v29
	v_add_f32_e32 v86, v33, v86
	v_cndmask_b32_e32 v31, v31, v84, vcc
	v_cndmask_b32_e32 v32, v32, v85, vcc
	v_cndmask_b32_e32 v34, v34, v87, vcc
	v_cndmask_b32_e32 v33, v33, v86, vcc
	s_waitcnt lgkmcnt(3)
	v_add_f32_e32 v25, v25, v77
	s_waitcnt lgkmcnt(2)
	v_add_f32_e32 v77, v27, v79
	s_waitcnt lgkmcnt(1)
	v_add_f32_e32 v28, v28, v80
	s_waitcnt lgkmcnt(0)
	v_add_f32_e32 v29, v29, v81
	ds_bpermute_b32 v79, v48, v31
	ds_bpermute_b32 v80, v48, v32
	ds_bpermute_b32 v81, v48, v33
	ds_bpermute_b32 v82, v48, v34
	v_add_f32_e32 v89, v36, v89
	v_add_f32_e32 v92, v39, v92
	v_cndmask_b32_e32 v35, v35, v88, vcc
	v_cndmask_b32_e32 v37, v37, v90, vcc
	v_cndmask_b32_e32 v39, v39, v92, vcc
	v_cndmask_b32_e32 v36, v36, v89, vcc
	s_waitcnt lgkmcnt(3)
	v_add_f32_e32 v31, v31, v79
	s_waitcnt lgkmcnt(2)
	v_add_f32_e32 v32, v32, v80
	s_waitcnt lgkmcnt(1)
	v_add_f32_e32 v79, v33, v81
	s_waitcnt lgkmcnt(0)
	v_add_f32_e32 v34, v34, v82
	ds_bpermute_b32 v80, v48, v35
	ds_bpermute_b32 v81, v48, v36
	ds_bpermute_b32 v82, v48, v37
	ds_bpermute_b32 v84, v48, v39
	v_add_f32_e32 v95, v42, v95
	v_add_f32_e32 v83, v30, v83
	v_cndmask_b32_e32 v38, v38, v91, vcc
	v_cndmask_b32_e32 v40, v40, v93, vcc
	v_cndmask_b32_e32 v43, v43, v96, vcc
	v_cndmask_b32_e32 v44, v44, v97, vcc
	v_cndmask_b32_e32 v42, v42, v95, vcc
	v_cndmask_b32_e32 v30, v30, v83, vcc
	ds_bpermute_b32 v83, v48, v38
	s_waitcnt lgkmcnt(4)
	v_add_f32_e32 v35, v35, v80
	s_waitcnt lgkmcnt(3)
	v_add_f32_e32 v80, v36, v81
	s_waitcnt lgkmcnt(2)
	v_add_f32_e32 v37, v37, v82
	s_waitcnt lgkmcnt(1)
	v_add_f32_e32 v81, v39, v84
	ds_bpermute_b32 v82, v48, v40
	ds_bpermute_b32 v84, v48, v42
	ds_bpermute_b32 v85, v48, v43
	ds_bpermute_b32 v86, v48, v44
	v_add_f32_e32 v101, v22, v101
	v_cndmask_b32_e32 v41, v41, v94, vcc
	v_cndmask_b32_e32 v46, v46, v99, vcc
	v_cndmask_b32_e32 v47, v47, v100, vcc
	v_cndmask_b32_e32 v49, v49, v102, vcc
	v_cndmask_b32_e32 v22, v22, v101, vcc
	ds_bpermute_b32 v78, v48, v26
	s_waitcnt lgkmcnt(5)
	v_add_f32_e32 v38, v38, v83
	ds_bpermute_b32 v83, v48, v41
	s_waitcnt lgkmcnt(5)
	v_add_f32_e32 v40, v40, v82
	s_waitcnt lgkmcnt(4)
	v_add_f32_e32 v82, v42, v84
	s_waitcnt lgkmcnt(3)
	v_add_f32_e32 v43, v43, v85
	s_waitcnt lgkmcnt(2)
	v_add_f32_e32 v44, v44, v86
	ds_bpermute_b32 v84, v48, v46
	ds_bpermute_b32 v85, v48, v47
	ds_bpermute_b32 v86, v48, v22
	ds_bpermute_b32 v87, v48, v49
	v_add_f32_e32 v98, v45, v98
	v_add_f32_e32 v104, v18, v104
	v_add_f32_e32 v105, v52, v105
	v_add_f32_e32 v106, v53, v106
	v_cndmask_b32_e32 v50, v50, v103, vcc
	v_cndmask_b32_e32 v52, v52, v105, vcc
	v_cndmask_b32_e32 v53, v53, v106, vcc
	v_cndmask_b32_e32 v18, v18, v104, vcc
	v_cndmask_b32_e32 v45, v45, v98, vcc
	s_waitcnt lgkmcnt(5)
	v_add_f32_e32 v26, v26, v78
	ds_bpermute_b32 v78, v48, v30
	s_waitcnt lgkmcnt(5)
	v_add_f32_e32 v41, v41, v83
	ds_bpermute_b32 v83, v48, v45
	s_waitcnt lgkmcnt(5)
	v_add_f32_e32 v46, v46, v84
	s_waitcnt lgkmcnt(4)
	v_add_f32_e32 v47, v47, v85
	s_waitcnt lgkmcnt(3)
	v_add_f32_e32 v84, v22, v86
	s_waitcnt lgkmcnt(2)
	v_add_f32_e32 v49, v49, v87
	ds_bpermute_b32 v85, v48, v50
	ds_bpermute_b32 v86, v48, v18
	ds_bpermute_b32 v87, v48, v52
	ds_bpermute_b32 v88, v48, v53
	ds_bpermute_b32 v48, v48, v21
	v_cndmask_b32_e32 v19, v19, v105, vcc
	v_cndmask_b32_e32 v20, v20, v106, vcc
	s_waitcnt lgkmcnt(4)
	v_add_f32_e32 v50, v50, v85
	v_cmp_gt_i32_e32 vcc, 56, v68
	v_lshrrev_b32_e32 v255, 2, v115
	s_nop 0
	v_readfirstlane_b32 s101, v255
	s_nop 3
	s_waitcnt lgkmcnt(0)
	v_add_f32_e32 v48, v21, v48
	v_cmp_gt_u32_e64 s[0:1], 48, v113
	v_cndmask_b32_e32 v21, v21, v48, vcc
	v_cndmask_b32_e32 v48, v76, v50, vcc
	v_cndmask_b32_e64 v50, 0, 16, s[0:1]
	v_cndmask_b32_e32 v47, v74, v47, vcc
	v_cndmask_b32_e32 v40, v64, v40, vcc
	v_cndmask_b32_e32 v31, v58, v31, vcc
	v_cndmask_b32_e32 v23, v51, v23, vcc
	v_add_lshl_u32 v50, v50, v112, 2
	v_add_f32_e32 v52, v52, v87
	v_cndmask_b32_e32 v22, v22, v84, vcc
	v_cndmask_b32_e32 v44, v72, v44, vcc
	v_cndmask_b32_e32 v33, v33, v79, vcc
	v_cndmask_b32_e32 v32, v59, v32, vcc
	ds_bpermute_b32 v51, v50, v23
	v_cndmask_b32_e32 v24, v24, v71, vcc
	ds_bpermute_b32 v59, v50, v31
	ds_bpermute_b32 v72, v50, v40
	ds_bpermute_b32 v79, v50, v47
	v_cndmask_b32_e32 v19, v19, v52, vcc
	v_cndmask_b32_e32 v36, v36, v80, vcc
	ds_bpermute_b32 v52, v50, v24
	ds_bpermute_b32 v80, v50, v22
	v_cndmask_b32_e32 v28, v56, v28, vcc
	v_add_f32_e32 v78, v30, v78
	v_add_f32_e32 v83, v45, v83
	v_add_f32_e32 v85, v18, v86
	v_add_f32_e32 v53, v53, v88
	v_cndmask_b32_e32 v46, v73, v46, vcc
	v_cndmask_b32_e32 v43, v70, v43, vcc
	v_cndmask_b32_e32 v41, v65, v41, vcc
	v_cndmask_b32_e32 v29, v57, v29, vcc
	v_cndmask_b32_e32 v27, v27, v77, vcc
	v_cndmask_b32_e32 v26, v55, v26, vcc
	v_cndmask_b32_e32 v25, v54, v25, vcc
	ds_bpermute_b32 v56, v50, v28
	ds_bpermute_b32 v76, v50, v44
	v_cndmask_b32_e32 v20, v20, v53, vcc
	v_cndmask_b32_e32 v18, v18, v85, vcc
	v_cndmask_b32_e32 v49, v75, v49, vcc
	v_cndmask_b32_e32 v45, v45, v83, vcc
	v_cndmask_b32_e32 v42, v42, v82, vcc
	v_cndmask_b32_e32 v39, v39, v81, vcc
	v_cndmask_b32_e32 v38, v63, v38, vcc
	v_cndmask_b32_e32 v37, v62, v37, vcc
	v_cndmask_b32_e32 v35, v61, v35, vcc
	v_cndmask_b32_e32 v34, v60, v34, vcc
	v_cndmask_b32_e32 v30, v30, v78, vcc
	s_waitcnt lgkmcnt(7)
	v_add_f32_e32 v51, v23, v51
	ds_bpermute_b32 v53, v50, v25
	v_cmp_gt_i32_e32 vcc, 48, v68
	ds_bpermute_b32 v54, v50, v26
	ds_bpermute_b32 v55, v50, v27
	ds_bpermute_b32 v57, v50, v29
	ds_bpermute_b32 v60, v50, v32
	s_waitcnt lgkmcnt(11)
	v_add_f32_e32 v59, v31, v59
	ds_bpermute_b32 v73, v50, v41
	s_waitcnt lgkmcnt(11)
	v_add_f32_e32 v72, v40, v72
	ds_bpermute_b32 v75, v50, v43
	ds_bpermute_b32 v78, v50, v46
	s_waitcnt lgkmcnt(12)
	v_add_f32_e32 v79, v47, v79
	v_cndmask_b32_e32 v51, v23, v51, vcc
	s_waitcnt lgkmcnt(11)
	v_add_f32_e32 v52, v24, v52
	ds_bpermute_b32 v58, v50, v30
	ds_bpermute_b32 v61, v50, v33
	v_cndmask_b32_e32 v59, v31, v59, vcc
	v_cndmask_b32_e32 v72, v40, v72, vcc
	ds_bpermute_b32 v77, v50, v45
	v_cndmask_b32_e32 v79, v47, v79, vcc
	ds_bpermute_b32 v82, v50, v48
	s_waitcnt lgkmcnt(14)
	v_add_f32_e32 v80, v22, v80
	v_cndmask_b32_e32 v88, v23, v51, vcc
	v_cndmask_b32_e32 v93, v31, v59, vcc
	v_cndmask_b32_e32 v31, v40, v72, vcc
	v_cndmask_b32_e32 v23, v47, v79, vcc
	v_cndmask_b32_e32 v40, v22, v80, vcc
	v_cndmask_b32_e32 v47, v24, v52, vcc
	ds_bpermute_b32 v22, v114, v51
	ds_bpermute_b32 v24, v114, v47
	s_waitcnt lgkmcnt(15)
	v_add_f32_e32 v56, v28, v56
	s_waitcnt lgkmcnt(14)
	v_add_f32_e32 v76, v44, v76
	s_waitcnt lgkmcnt(13)
	v_add_f32_e32 v53, v25, v53
	s_waitcnt lgkmcnt(12)
	v_add_f32_e32 v54, v26, v54
	s_waitcnt lgkmcnt(11)
	v_add_f32_e32 v55, v27, v55
	v_cndmask_b32_e32 v56, v28, v56, vcc
	s_waitcnt lgkmcnt(10)
	v_add_f32_e32 v57, v29, v57
	ds_bpermute_b32 v62, v50, v34
	s_waitcnt lgkmcnt(10)
	v_add_f32_e32 v60, v32, v60
	ds_bpermute_b32 v63, v50, v35
	s_waitcnt lgkmcnt(10)
	v_add_f32_e32 v73, v41, v73
	s_waitcnt lgkmcnt(9)
	v_add_f32_e32 v75, v43, v75
	v_cndmask_b32_e32 v76, v44, v76, vcc
	s_waitcnt lgkmcnt(8)
	v_add_f32_e32 v78, v46, v78
	ds_bpermute_b32 v81, v50, v49
	v_cndmask_b32_e32 v53, v25, v53, vcc
	v_cndmask_b32_e32 v54, v26, v54, vcc
	v_cndmask_b32_e32 v57, v29, v57, vcc
	s_waitcnt lgkmcnt(8)
	v_add_f32_e32 v58, v30, v58
	v_cndmask_b32_e32 v60, v32, v60, vcc
	s_waitcnt lgkmcnt(7)
	v_add_f32_e32 v61, v33, v61
	v_cndmask_b32_e32 v73, v41, v73, vcc
	v_cndmask_b32_e32 v75, v43, v75, vcc
	s_waitcnt lgkmcnt(6)
	v_add_f32_e32 v77, v45, v77
	v_cndmask_b32_e32 v78, v46, v78, vcc
	s_waitcnt lgkmcnt(5)
	v_add_f32_e32 v82, v48, v82
	v_cndmask_b32_e32 v90, v28, v56, vcc
	v_cndmask_b32_e32 v28, v44, v76, vcc
	v_cndmask_b32_e32 v44, v27, v55, vcc
	ds_bpermute_b32 v64, v50, v36
	ds_bpermute_b32 v65, v50, v37
	ds_bpermute_b32 v70, v50, v38
	ds_bpermute_b32 v71, v50, v39
	ds_bpermute_b32 v74, v50, v42
	ds_bpermute_b32 v83, v50, v18
	ds_bpermute_b32 v84, v50, v19
	v_cndmask_b32_e32 v82, v48, v82, vcc
	ds_bpermute_b32 v85, v50, v20
	ds_bpermute_b32 v50, v50, v21
	v_cndmask_b32_e32 v86, v26, v54, vcc
	v_cndmask_b32_e32 v89, v29, v57, vcc
	v_cndmask_b32_e32 v92, v32, v60, vcc
	v_cndmask_b32_e32 v32, v41, v73, vcc
	v_cndmask_b32_e32 v29, v46, v78, vcc
	v_cndmask_b32_e32 v26, v43, v75, vcc
	v_cndmask_b32_e32 v41, v45, v77, vcc
	v_cndmask_b32_e32 v43, v33, v61, vcc
	v_cndmask_b32_e32 v45, v30, v58, vcc
	s_waitcnt lgkmcnt(13)
	v_add_f32_e32 v46, v51, v22
	ds_bpermute_b32 v22, v114, v53
	ds_bpermute_b32 v27, v114, v44
	ds_bpermute_b32 v30, v114, v56
	ds_bpermute_b32 v33, v114, v57
	v_cndmask_b32_e32 v87, v25, v53, vcc
	v_cndmask_b32_e32 v25, v48, v82, vcc
	s_waitcnt lgkmcnt(15)
	v_add_f32_e32 v48, v47, v24
	ds_bpermute_b32 v24, v114, v54
	s_waitcnt lgkmcnt(15)
	v_add_f32_e32 v62, v34, v62
	s_waitcnt lgkmcnt(15)
	v_add_f32_e32 v63, v35, v63
	s_waitcnt lgkmcnt(14)
	v_add_f32_e32 v81, v49, v81
	v_cndmask_b32_e32 v62, v34, v62, vcc
	v_cndmask_b32_e32 v63, v35, v63, vcc
	v_cndmask_b32_e32 v81, v49, v81, vcc
	s_waitcnt lgkmcnt(5)
	v_add_f32_e32 v50, v21, v50
	v_cndmask_b32_e32 v91, v34, v62, vcc
	v_cndmask_b32_e32 v34, v35, v63, vcc
	v_cndmask_b32_e32 v35, v49, v81, vcc
	s_waitcnt lgkmcnt(4)
	v_add_f32_e32 v49, v53, v22
	s_waitcnt lgkmcnt(3)
	v_add_f32_e32 v51, v44, v27
	s_waitcnt lgkmcnt(2)
	v_add_f32_e32 v52, v56, v30
	s_waitcnt lgkmcnt(1)
	v_add_f32_e32 v53, v57, v33
	ds_bpermute_b32 v22, v114, v45
	ds_bpermute_b32 v27, v114, v60
	ds_bpermute_b32 v30, v114, v43
	ds_bpermute_b32 v33, v114, v62
	v_cndmask_b32_e32 v21, v21, v50, vcc
	s_waitcnt lgkmcnt(4)
	v_add_f32_e32 v50, v54, v24
	ds_bpermute_b32 v24, v114, v59
	v_add_f32_e32 v65, v37, v65
	v_add_f32_e32 v70, v38, v70
	v_add_f32_e32 v71, v39, v71
	v_add_f32_e32 v64, v36, v64
	v_cndmask_b32_e32 v65, v37, v65, vcc
	v_cndmask_b32_e32 v70, v38, v70, vcc
	v_cndmask_b32_e32 v39, v39, v71, vcc
	v_cndmask_b32_e32 v36, v36, v64, vcc
	s_waitcnt lgkmcnt(4)
	v_add_f32_e32 v54, v45, v22
	s_waitcnt lgkmcnt(3)
	v_add_f32_e32 v56, v60, v27
	s_waitcnt lgkmcnt(2)
	v_add_f32_e32 v57, v43, v30
	s_waitcnt lgkmcnt(1)
	v_add_f32_e32 v58, v62, v33
	ds_bpermute_b32 v22, v114, v63
	ds_bpermute_b32 v27, v114, v65
	ds_bpermute_b32 v30, v114, v70
	ds_bpermute_b32 v33, v114, v39
	s_waitcnt lgkmcnt(4)
	v_add_f32_e32 v55, v59, v24
	ds_bpermute_b32 v24, v114, v36
	v_add_f32_e32 v74, v42, v74
	v_cndmask_b32_e32 v42, v42, v74, vcc
	s_waitcnt lgkmcnt(4)
	v_add_f32_e32 v59, v63, v22
	s_waitcnt lgkmcnt(3)
	v_add_f32_e32 v61, v65, v27
	s_waitcnt lgkmcnt(2)
	v_add_f32_e32 v62, v70, v30
	s_waitcnt lgkmcnt(1)
	v_add_f32_e32 v30, v39, v33
	ds_bpermute_b32 v22, v114, v72
	ds_bpermute_b32 v27, v114, v42
	ds_bpermute_b32 v33, v114, v75
	ds_bpermute_b32 v63, v114, v76
	s_waitcnt lgkmcnt(4)
	v_add_f32_e32 v60, v36, v24
	ds_bpermute_b32 v24, v114, v73
	v_cndmask_b32_e32 v38, v38, v70, vcc
	s_waitcnt lgkmcnt(4)
	v_add_f32_e32 v64, v72, v22
	s_waitcnt lgkmcnt(3)
	v_add_f32_e32 v70, v42, v27
	s_waitcnt lgkmcnt(2)
	v_add_f32_e32 v27, v75, v33
	s_waitcnt lgkmcnt(1)
	v_add_f32_e32 v33, v76, v63
	ds_bpermute_b32 v22, v114, v41
	ds_bpermute_b32 v63, v114, v79
	ds_bpermute_b32 v72, v114, v81
	v_cndmask_b32_e32 v37, v37, v65, vcc
	s_waitcnt lgkmcnt(3)
	v_add_f32_e32 v65, v73, v24
	ds_bpermute_b32 v24, v114, v78
	ds_bpermute_b32 v71, v114, v40
	s_lshl_b32 s1, s42, 3
	v_add_f32_e32 v83, v18, v83
	v_add_f32_e32 v84, v19, v84
	v_add_f32_e32 v85, v20, v85
	s_or_b32 s1, s40, s1
	v_cndmask_b32_e32 v84, v19, v84, vcc
	v_cndmask_b32_e32 v85, v20, v85, vcc
	v_cndmask_b32_e32 v18, v18, v83, vcc
	s_or_b32 s2, s1, 4
	v_cndmask_b32_e32 v20, v20, v85, vcc
	v_cndmask_b32_e32 v19, v19, v84, vcc
	s_waitcnt lgkmcnt(4)
	v_add_f32_e32 v73, v41, v22
	s_waitcnt lgkmcnt(3)
	v_add_f32_e32 v22, v79, v63
	s_waitcnt lgkmcnt(2)
	v_add_f32_e32 v63, v81, v72
	ds_bpermute_b32 v72, v114, v18
	ds_bpermute_b32 v75, v114, v84
	ds_bpermute_b32 v76, v114, v85
	ds_bpermute_b32 v77, v114, v21
	v_cmp_gt_i32_e32 vcc, 32, v68
	s_sub_i32 s0, 0x103, s18
	s_mul_hi_i32 s1, s2, 0x104
	s_mulk_i32 s2, 0x104
	s_waitcnt lgkmcnt(5)
	v_add_f32_e32 v74, v78, v24
	s_waitcnt lgkmcnt(4)
	v_add_f32_e32 v24, v40, v71
	ds_bpermute_b32 v71, v114, v82
	v_cndmask_b32_e32 v46, v88, v46, vcc
	s_add_u32 s16, s2, s41
	v_cndmask_b32_e32 v22, v23, v22, vcc
	v_cndmask_b32_e32 v23, v40, v24, vcc
	v_cndmask_b32_e32 v40, v43, v57, vcc
	v_cndmask_b32_e32 v43, v90, v52, vcc
	s_addc_u32 s17, s1, 0
	v_readlane_b32 s98, v46, s101
	s_lshl_b64 s[16:17], s[16:17], 13
	s_add_u32 s16, s22, s16
	s_waitcnt lgkmcnt(4)
	v_add_f32_e32 v72, v18, v72
	s_waitcnt lgkmcnt(3)
	v_add_f32_e32 v75, v84, v75
	s_waitcnt lgkmcnt(2)
	v_add_f32_e32 v76, v85, v76
	s_waitcnt lgkmcnt(1)
	v_add_f32_e32 v77, v21, v77
	v_cndmask_b32_e32 v26, v26, v27, vcc
	v_cndmask_b32_e32 v27, v28, v33, vcc
	v_cndmask_b32_e32 v33, v42, v70, vcc
	v_cndmask_b32_e32 v42, v44, v51, vcc
	v_cndmask_b32_e32 v47, v47, v48, vcc
	v_cndmask_b32_e32 v48, v87, v49, vcc
	v_cndmask_b32_e32 v49, v86, v50, vcc
	s_addc_u32 s17, s23, s17
	v_lshlrev_b64 v[50:51], 7, v[68:69]
	s_waitcnt lgkmcnt(0)
	v_add_f32_e32 v71, v82, v71
	v_cndmask_b32_e32 v18, v18, v72, vcc
	v_cndmask_b32_e32 v19, v19, v75, vcc
	v_cndmask_b32_e32 v20, v20, v76, vcc
	v_cndmask_b32_e32 v21, v21, v77, vcc
	v_cndmask_b32_e32 v24, v35, v63, vcc
	v_cndmask_b32_e32 v34, v34, v59, vcc
	v_cndmask_b32_e32 v35, v36, v60, vcc
	v_cndmask_b32_e32 v36, v37, v61, vcc
	v_cndmask_b32_e32 v37, v38, v62, vcc
	v_lshl_add_u64 v[50:51], s[16:17], 0, v[50:51]
	v_cndmask_b32_e32 v25, v25, v71, vcc
	v_cndmask_b32_e32 v28, v41, v73, vcc
	v_cndmask_b32_e32 v29, v29, v74, vcc
	v_cndmask_b32_e32 v30, v39, v30, vcc
	v_cndmask_b32_e32 v31, v31, v64, vcc
	v_cndmask_b32_e32 v32, v32, v65, vcc
	v_cndmask_b32_e32 v38, v93, v55, vcc
	v_cndmask_b32_e32 v39, v92, v56, vcc
	v_cndmask_b32_e32 v41, v91, v58, vcc
	v_cndmask_b32_e32 v44, v89, v53, vcc
	v_cndmask_b32_e32 v45, v45, v54, vcc
	global_store_dwordx4 v[50:51], v[46:49], off
	global_store_dwordx4 v[50:51], v[42:45], off offset:16
	global_store_dwordx4 v[50:51], v[38:41], off offset:32
	global_store_dwordx4 v[50:51], v[34:37], off offset:48
	global_store_dwordx4 v[50:51], v[30:33], off offset:64
	global_store_dwordx4 v[50:51], v[26:29], off offset:80
	global_store_dwordx4 v[50:51], v[22:25], off offset:96
	v_sub_f32_e32 v52, s98, v46
	global_store_dwordx4 v[50:51], v[18:21], off offset:112
	v_readlane_b32 s98, v47, s101
	v_mul_f32_e32 v52, 0x3fb8aa3b, v52
	v_exp_f32_e32 v52, v52
	v_lshlrev_b32_e32 v51, 16, v14
	v_and_b32_e32 v14, 0xffff0000, v14
	v_sub_f32_e32 v50, s98, v47
	v_mul_f32_e32 v51, v52, v51
	v_mul_f32_e32 v50, 0x3fb8aa3b, v50
	v_bfe_u32 v52, v51, 16, 1
	v_exp_f32_e32 v50, v50
	v_add3_u32 v51, v51, v52, s38
	ds_write_b16_d16_hi v66, v51 offset:8192
	v_readlane_b32 s98, v48, s101
	v_mul_f32_e32 v14, v50, v14
	v_bfe_u32 v50, v14, 16, 1
	v_add3_u32 v14, v14, v50, s38
	ds_write_b16_d16_hi v66, v14 offset:8320
	v_sub_f32_e32 v50, s98, v48
	v_readlane_b32 s98, v49, s101
	v_mul_f32_e32 v50, 0x3fb8aa3b, v50
	v_exp_f32_e32 v50, v50
	v_lshlrev_b32_e32 v51, 16, v15
	v_and_b32_e32 v15, 0xffff0000, v15
	v_sub_f32_e32 v14, s98, v49
	v_mul_f32_e32 v50, v50, v51
	v_mul_f32_e32 v14, 0x3fb8aa3b, v14
	v_bfe_u32 v51, v50, 16, 1
	v_exp_f32_e32 v14, v14
	v_add3_u32 v50, v50, v51, s38
	ds_write_b16_d16_hi v66, v50 offset:8448
	v_readlane_b32 s98, v42, s101
	v_mul_f32_e32 v14, v14, v15
	v_bfe_u32 v15, v14, 16, 1
	v_add3_u32 v14, v14, v15, s38
	ds_write_b16_d16_hi v66, v14 offset:8576
	v_sub_f32_e32 v15, s98, v42
	v_readlane_b32 s98, v43, s101
	v_mul_f32_e32 v15, 0x3fb8aa3b, v15
	v_exp_f32_e32 v15, v15
	v_lshlrev_b32_e32 v50, 16, v16
	v_and_b32_e32 v16, 0xffff0000, v16
	v_sub_f32_e32 v14, s98, v43
	v_mul_f32_e32 v15, v15, v50
	v_mul_f32_e32 v14, 0x3fb8aa3b, v14
	v_bfe_u32 v50, v15, 16, 1
	v_exp_f32_e32 v14, v14
	v_add3_u32 v15, v15, v50, s38
	ds_write_b16_d16_hi v66, v15 offset:8704
	v_readlane_b32 s98, v44, s101
	v_mul_f32_e32 v14, v14, v16
	v_bfe_u32 v16, v14, 16, 1
	v_add3_u32 v14, v14, v16, s38
	ds_write_b16_d16_hi v66, v14 offset:8832
	v_sub_f32_e32 v15, s98, v44
	v_readlane_b32 s98, v45, s101
	v_mul_f32_e32 v15, 0x3fb8aa3b, v15
	v_exp_f32_e32 v15, v15
	v_lshlrev_b32_e32 v16, 16, v17
	s_add_u32 s0, s2, s0
	v_sub_f32_e32 v14, s98, v45
	v_mul_f32_e32 v15, v15, v16
	v_mul_f32_e32 v14, 0x3fb8aa3b, v14
	v_bfe_u32 v16, v15, 16, 1
	v_exp_f32_e32 v14, v14
	v_add3_u32 v15, v15, v16, s38
	ds_write_b16_d16_hi v66, v15 offset:8960
	v_readlane_b32 s98, v38, s101
	v_and_b32_e32 v16, 0xffff0000, v17
	v_mul_f32_e32 v14, v14, v16
	v_bfe_u32 v16, v14, 16, 1
	v_add3_u32 v14, v14, v16, s38
	v_sub_f32_e32 v15, s98, v38
	ds_write_b16_d16_hi v66, v14 offset:9088
	v_readlane_b32 s98, v39, s101
	v_mul_f32_e32 v15, 0x3fb8aa3b, v15
	v_exp_f32_e32 v15, v15
	v_lshlrev_b32_e32 v16, 16, v10
	v_and_b32_e32 v10, 0xffff0000, v10
	v_sub_f32_e32 v14, s98, v39
	v_mul_f32_e32 v15, v15, v16
	v_mul_f32_e32 v14, 0x3fb8aa3b, v14
	v_bfe_u32 v16, v15, 16, 1
	v_exp_f32_e32 v14, v14
	v_add3_u32 v15, v15, v16, s38
	ds_write_b16_d16_hi v66, v15 offset:9216
	v_readlane_b32 s98, v40, s101
	v_mul_f32_e32 v10, v14, v10
	v_bfe_u32 v14, v10, 16, 1
	v_add3_u32 v10, v10, v14, s38
	ds_write_b16_d16_hi v66, v10 offset:9344
	v_sub_f32_e32 v14, s98, v40
	v_readlane_b32 s98, v41, s101
	v_mul_f32_e32 v14, 0x3fb8aa3b, v14
	v_exp_f32_e32 v14, v14
	v_lshlrev_b32_e32 v15, 16, v11
	v_and_b32_e32 v11, 0xffff0000, v11
	v_sub_f32_e32 v10, s98, v41
	v_mul_f32_e32 v14, v14, v15
	v_mul_f32_e32 v10, 0x3fb8aa3b, v10
	v_bfe_u32 v15, v14, 16, 1
	v_exp_f32_e32 v10, v10
	v_add3_u32 v14, v14, v15, s38
	ds_write_b16_d16_hi v66, v14 offset:9472
	v_readlane_b32 s98, v34, s101
	v_mul_f32_e32 v10, v10, v11
	v_bfe_u32 v11, v10, 16, 1
	v_add3_u32 v10, v10, v11, s38
	ds_write_b16_d16_hi v66, v10 offset:9600
	v_sub_f32_e32 v11, s98, v34
	v_readlane_b32 s98, v35, s101
	v_mul_f32_e32 v11, 0x3fb8aa3b, v11
	v_exp_f32_e32 v11, v11
	v_lshlrev_b32_e32 v14, 16, v12
	v_and_b32_e32 v12, 0xffff0000, v12
	v_sub_f32_e32 v10, s98, v35
	v_mul_f32_e32 v11, v11, v14
	v_mul_f32_e32 v10, 0x3fb8aa3b, v10
	v_bfe_u32 v14, v11, 16, 1
	v_exp_f32_e32 v10, v10
	v_add3_u32 v11, v11, v14, s38
	ds_write_b16_d16_hi v66, v11 offset:9728
	v_readlane_b32 s98, v36, s101
	v_mul_f32_e32 v10, v10, v12
	v_bfe_u32 v12, v10, 16, 1
	v_add3_u32 v10, v10, v12, s38
	ds_write_b16_d16_hi v66, v10 offset:9856
	v_sub_f32_e32 v11, s98, v36
	v_readlane_b32 s98, v37, s101
	v_mul_f32_e32 v11, 0x3fb8aa3b, v11
	v_exp_f32_e32 v11, v11
	v_lshlrev_b32_e32 v12, 16, v13
	s_addc_u32 s1, s1, 0
	v_sub_f32_e32 v10, s98, v37
	v_mul_f32_e32 v11, v11, v12
	v_mul_f32_e32 v10, 0x3fb8aa3b, v10
	v_bfe_u32 v12, v11, 16, 1
	v_exp_f32_e32 v10, v10
	v_add3_u32 v11, v11, v12, s38
	ds_write_b16_d16_hi v66, v11 offset:9984
	v_readlane_b32 s98, v30, s101
	v_and_b32_e32 v12, 0xffff0000, v13
	v_mul_f32_e32 v10, v10, v12
	v_bfe_u32 v12, v10, 16, 1
	v_add3_u32 v10, v10, v12, s38
	v_sub_f32_e32 v11, s98, v30
	ds_write_b16_d16_hi v66, v10 offset:10112
	v_readlane_b32 s98, v31, s101
	v_mul_f32_e32 v11, 0x3fb8aa3b, v11
	v_exp_f32_e32 v11, v11
	v_lshlrev_b32_e32 v12, 16, v6
	v_and_b32_e32 v6, 0xffff0000, v6
	v_sub_f32_e32 v10, s98, v31
	v_mul_f32_e32 v11, v11, v12
	v_mul_f32_e32 v10, 0x3fb8aa3b, v10
	v_bfe_u32 v12, v11, 16, 1
	v_exp_f32_e32 v10, v10
	v_add3_u32 v11, v11, v12, s38
	ds_write_b16_d16_hi v66, v11 offset:10240
	v_readlane_b32 s98, v32, s101
	v_mul_f32_e32 v6, v10, v6
	v_bfe_u32 v10, v6, 16, 1
	v_add3_u32 v6, v6, v10, s38
	ds_write_b16_d16_hi v66, v6 offset:10368
	v_sub_f32_e32 v10, s98, v32
	v_readlane_b32 s98, v33, s101
	v_mul_f32_e32 v10, 0x3fb8aa3b, v10
	v_exp_f32_e32 v10, v10
	v_lshlrev_b32_e32 v11, 16, v7
	v_and_b32_e32 v7, 0xffff0000, v7
	v_sub_f32_e32 v6, s98, v33
	v_mul_f32_e32 v10, v10, v11
	v_mul_f32_e32 v6, 0x3fb8aa3b, v6
	v_bfe_u32 v11, v10, 16, 1
	v_exp_f32_e32 v6, v6
	v_add3_u32 v10, v10, v11, s38
	ds_write_b16_d16_hi v66, v10 offset:10496
	v_readlane_b32 s98, v26, s101
	v_mul_f32_e32 v6, v6, v7
	v_bfe_u32 v7, v6, 16, 1
	v_add3_u32 v6, v6, v7, s38
	ds_write_b16_d16_hi v66, v6 offset:10624
	v_sub_f32_e32 v7, s98, v26
	v_readlane_b32 s98, v27, s101
	v_mul_f32_e32 v7, 0x3fb8aa3b, v7
	v_exp_f32_e32 v7, v7
	v_lshlrev_b32_e32 v10, 16, v8
	v_and_b32_e32 v8, 0xffff0000, v8
	v_sub_f32_e32 v6, s98, v27
	v_mul_f32_e32 v7, v7, v10
	v_mul_f32_e32 v6, 0x3fb8aa3b, v6
	v_bfe_u32 v10, v7, 16, 1
	v_exp_f32_e32 v6, v6
	v_add3_u32 v7, v7, v10, s38
	ds_write_b16_d16_hi v66, v7 offset:10752
	v_readlane_b32 s98, v28, s101
	v_mul_f32_e32 v6, v6, v8
	v_bfe_u32 v8, v6, 16, 1
	v_add3_u32 v6, v6, v8, s38
	ds_write_b16_d16_hi v66, v6 offset:10880
	v_sub_f32_e32 v7, s98, v28
	v_readlane_b32 s98, v29, s101
	v_mul_f32_e32 v7, 0x3fb8aa3b, v7
	v_exp_f32_e32 v7, v7
	v_lshlrev_b32_e32 v8, 16, v9
	v_cmp_eq_u32_e32 vcc, 0, v68
	v_sub_f32_e32 v6, s98, v29
	v_mul_f32_e32 v7, v7, v8
	v_mul_f32_e32 v6, 0x3fb8aa3b, v6
	v_bfe_u32 v8, v7, 16, 1
	v_exp_f32_e32 v6, v6
	v_add3_u32 v7, v7, v8, s38
	ds_write_b16_d16_hi v66, v7 offset:11008
	v_readlane_b32 s98, v22, s101
	v_and_b32_e32 v8, 0xffff0000, v9
	v_mul_f32_e32 v6, v6, v8
	v_bfe_u32 v8, v6, 16, 1
	v_add3_u32 v6, v6, v8, s38
	v_sub_f32_e32 v7, s98, v22
	ds_write_b16_d16_hi v66, v6 offset:11136
	v_readlane_b32 s98, v23, s101
	v_mul_f32_e32 v7, 0x3fb8aa3b, v7
	v_exp_f32_e32 v7, v7
	v_lshlrev_b32_e32 v8, 16, v2
	v_and_b32_e32 v2, 0xffff0000, v2
	v_sub_f32_e32 v6, s98, v23
	v_mul_f32_e32 v7, v7, v8
	v_mul_f32_e32 v6, 0x3fb8aa3b, v6
	v_bfe_u32 v8, v7, 16, 1
	v_exp_f32_e32 v6, v6
	v_add3_u32 v7, v7, v8, s38
	ds_write_b16_d16_hi v66, v7 offset:11264
	v_readlane_b32 s98, v24, s101
	v_mul_f32_e32 v2, v6, v2
	v_bfe_u32 v6, v2, 16, 1
	v_add3_u32 v2, v2, v6, s38
	ds_write_b16_d16_hi v66, v2 offset:11392
	v_sub_f32_e32 v6, s98, v24
	v_readlane_b32 s98, v25, s101
	v_mul_f32_e32 v6, 0x3fb8aa3b, v6
	v_exp_f32_e32 v6, v6
	v_lshlrev_b32_e32 v7, 16, v3
	v_and_b32_e32 v3, 0xffff0000, v3
	v_sub_f32_e32 v2, s98, v25
	v_mul_f32_e32 v6, v6, v7
	v_mul_f32_e32 v2, 0x3fb8aa3b, v2
	v_bfe_u32 v7, v6, 16, 1
	v_exp_f32_e32 v2, v2
	v_add3_u32 v6, v6, v7, s38
	ds_write_b16_d16_hi v66, v6 offset:11520
	v_readlane_b32 s98, v18, s101
	v_mul_f32_e32 v2, v2, v3
	v_bfe_u32 v3, v2, 16, 1
	v_add3_u32 v2, v2, v3, s38
	ds_write_b16_d16_hi v66, v2 offset:11648
	v_sub_f32_e32 v3, s98, v18
	v_readlane_b32 s98, v19, s101
	v_mul_f32_e32 v3, 0x3fb8aa3b, v3
	v_exp_f32_e32 v3, v3
	v_lshlrev_b32_e32 v6, 16, v4
	v_and_b32_e32 v4, 0xffff0000, v4
	v_sub_f32_e32 v2, s98, v19
	v_mul_f32_e32 v3, v3, v6
	v_mul_f32_e32 v2, 0x3fb8aa3b, v2
	v_bfe_u32 v6, v3, 16, 1
	v_exp_f32_e32 v2, v2
	v_add3_u32 v3, v3, v6, s38
	ds_write_b16_d16_hi v66, v3 offset:11776
	v_readlane_b32 s98, v20, s101
	v_mul_f32_e32 v2, v2, v4
	v_bfe_u32 v4, v2, 16, 1
	v_add3_u32 v2, v2, v4, s38
	v_readlane_b32 s99, v21, s101
	v_sub_f32_e32 v3, s98, v20
	v_mul_f32_e32 v3, 0x3fb8aa3b, v3
	v_exp_f32_e32 v3, v3
	ds_write_b16_d16_hi v66, v2 offset:11904
	v_sub_f32_e32 v4, s99, v21
	v_lshlrev_b32_e32 v2, 16, v5
	v_mul_f32_e32 v4, 0x3fb8aa3b, v4
	v_mul_f32_e32 v2, v3, v2
	v_exp_f32_e32 v4, v4
	v_bfe_u32 v3, v2, 16, 1
	v_add3_u32 v2, v2, v3, s38
	ds_write_b16_d16_hi v66, v2 offset:12032
	v_and_b32_e32 v2, 0xffff0000, v5
	v_mul_f32_e32 v2, v4, v2
	v_bfe_u32 v3, v2, 16, 1
	v_add3_u32 v2, v2, v3, s38
	ds_write_b16_d16_hi v66, v2 offset:12160
	s_and_saveexec_b64 s[16:17], vcc
	s_cbranch_execz .LBB0_1948
	v_mul_f32_e32 v2, 0x3fb8aa3b, v46
	v_mul_f32_e32 v3, 0x3fb8aa3b, v47
	v_mul_f32_e32 v4, 0x3fb8aa3b, v48
	v_mul_f32_e32 v5, 0x3fb8aa3b, v49
	v_exp_f32_e32 v2, v2
	v_exp_f32_e32 v3, v3
	v_exp_f32_e32 v4, v4
	v_exp_f32_e32 v5, v5
	v_mul_f32_e32 v6, 0x3fb8aa3b, v42
	v_mul_f32_e32 v7, 0x3fb8aa3b, v43
	v_mul_f32_e32 v8, 0x3fb8aa3b, v44
	v_mul_f32_e32 v9, 0x3fb8aa3b, v45
	s_lshl_b64 s[18:19], s[0:1], 7
	v_exp_f32_e32 v6, v6
	v_exp_f32_e32 v7, v7
	v_exp_f32_e32 v8, v8
	v_exp_f32_e32 v9, v9
	v_mul_f32_e32 v10, 0x3fb8aa3b, v38
	v_mul_f32_e32 v11, 0x3fb8aa3b, v39
	v_mul_f32_e32 v12, 0x3fb8aa3b, v40
	v_mul_f32_e32 v13, 0x3fb8aa3b, v41
	s_add_u32 s18, s27, s18
	v_exp_f32_e32 v10, v10
	v_exp_f32_e32 v11, v11
	v_exp_f32_e32 v12, v12
	v_exp_f32_e32 v13, v13
	v_mul_f32_e32 v14, 0x3fb8aa3b, v34
	v_mul_f32_e32 v15, 0x3fb8aa3b, v35
	v_mul_f32_e32 v16, 0x3fb8aa3b, v36
	v_mul_f32_e32 v17, 0x3fb8aa3b, v37
	s_addc_u32 s19, s28, s19
	v_exp_f32_e32 v14, v14
	v_exp_f32_e32 v15, v15
	v_exp_f32_e32 v16, v16
	v_exp_f32_e32 v17, v17
	global_store_dwordx4 v67, v[2:5], s[18:19]
	global_store_dwordx4 v67, v[6:9], s[18:19] offset:16
	global_store_dwordx4 v67, v[10:13], s[18:19] offset:32
	global_store_dwordx4 v67, v[14:17], s[18:19] offset:48
	v_mul_f32_e32 v2, 0x3fb8aa3b, v30
	v_mul_f32_e32 v3, 0x3fb8aa3b, v31
	v_mul_f32_e32 v4, 0x3fb8aa3b, v32
	v_mul_f32_e32 v5, 0x3fb8aa3b, v33
	v_exp_f32_e32 v2, v2
	v_exp_f32_e32 v3, v3
	v_exp_f32_e32 v4, v4
	v_exp_f32_e32 v5, v5
	v_mul_f32_e32 v6, 0x3fb8aa3b, v26
	v_mul_f32_e32 v7, 0x3fb8aa3b, v27
	v_mul_f32_e32 v8, 0x3fb8aa3b, v28
	v_mul_f32_e32 v9, 0x3fb8aa3b, v29
	v_exp_f32_e32 v6, v6
	v_exp_f32_e32 v7, v7
	v_exp_f32_e32 v8, v8
	v_exp_f32_e32 v9, v9
	v_mul_f32_e32 v10, 0x3fb8aa3b, v22
	v_mul_f32_e32 v11, 0x3fb8aa3b, v23
	v_mul_f32_e32 v12, 0x3fb8aa3b, v24
	v_mul_f32_e32 v13, 0x3fb8aa3b, v25
	v_exp_f32_e32 v10, v10
	v_exp_f32_e32 v11, v11
	v_exp_f32_e32 v12, v12
	v_exp_f32_e32 v13, v13
	v_mul_f32_e32 v14, 0x3fb8aa3b, v18
	v_mul_f32_e32 v15, 0x3fb8aa3b, v19
	v_mul_f32_e32 v16, 0x3fb8aa3b, v20
	v_mul_f32_e32 v17, 0x3fb8aa3b, v21
	v_exp_f32_e32 v14, v14
	v_exp_f32_e32 v15, v15
	v_exp_f32_e32 v16, v16
	v_exp_f32_e32 v17, v17
	global_store_dwordx4 v67, v[2:5], s[18:19] offset:64
	global_store_dwordx4 v67, v[6:9], s[18:19] offset:80
	global_store_dwordx4 v67, v[10:13], s[18:19] offset:96
	global_store_dwordx4 v67, v[14:17], s[18:19] offset:112

.LBB0_1949:
	v_mov_b32_e32 v68, v109
	v_mov_b64_e32 v[2:3], s[8:9]
	v_add_u32_e32 v4, s33, v68
	v_mad_i64_i32 v[70:71], s[0:1], v4, s31, v[2:3]
	s_lshl_b32 s0, s14, 1
	s_mov_b32 s1, s15
	v_lshl_add_u64 v[30:31], v[70:71], 0, s[0:1]
	global_load_dwordx4 v[2:5], v[30:31], off offset:512
	global_load_dwordx4 v[6:9], v[30:31], off offset:528
	global_load_dwordx4 v[10:13], v[30:31], off offset:544
	global_load_dwordx4 v[14:17], v[30:31], off offset:560
	global_load_dwordx4 v[18:21], v[30:31], off offset:576
	global_load_dwordx4 v[22:25], v[30:31], off offset:592
	global_load_dwordx4 v[26:29], v[30:31], off offset:608
	s_nop 0
	global_load_dwordx4 v[30:33], v[30:31], off offset:624
	v_readlane_b32 s44, v239, 33
	global_load_dwordx4 v[34:37], v[70:71], off offset:1536
	s_lshl_b32 s0, s40, 7
	v_readlane_b32 s48, v239, 37
	v_readlane_b32 s49, v239, 38
	v_readlane_b32 s50, v239, 39
	v_readlane_b32 s51, v239, 40
	v_readlane_b32 s52, v239, 41
	v_readlane_b32 s53, v239, 42
	v_readlane_b32 s54, v239, 43
	v_readlane_b32 s55, v239, 44
	s_add_u32 s16, s12, s0
	v_mov_b32_e32 v123, s0
	v_readlane_b32 s56, v239, 45
	v_readlane_b32 s57, v239, 46
	v_readlane_b32 s58, v239, 47
	v_readlane_b32 s59, v239, 48
	s_mov_b64 s[48:49], s[52:53]
	s_addc_u32 s17, s13, 0
	global_load_dwordx4 v[38:41], v123, s[48:49] offset:512
	global_load_dwordx4 v[42:45], v123, s[12:13]
	global_load_dwordx4 v[46:49], v123, s[12:13] offset:512
	global_load_dwordx4 v[50:53], v123, s[12:13] offset:1024
	global_load_dwordx4 v[54:57], v123, s[12:13] offset:1536
	global_load_dwordx4 v[58:61], v123, s[12:13] offset:2048
	global_load_dwordx4 v[62:65], v123, s[12:13] offset:2560
	global_load_dwordx4 v[74:77], v123, s[12:13] offset:3072
	global_load_dwordx4 v[78:81], v123, s[12:13] offset:3584
	global_load_dwordx4 v[82:85], v110, s[16:17]
	global_load_dwordx4 v[86:89], v110, s[16:17] offset:512
	global_load_dwordx4 v[90:93], v[70:71], off offset:1552
	v_lshl_add_u32 v66, v68, 1, s25
	v_lshl_add_u64 v[70:71], v[70:71], 0, s[14:15]
	v_ashrrev_i32_e32 v69, 31, v68
	v_readlane_b32 s45, v239, 34
	v_readlane_b32 s46, v239, 35
	v_readlane_b32 s47, v239, 36
	s_mov_b64 s[50:51], s[54:55]
	s_mov_b64 s[52:53], s[56:57]
	s_mov_b64 s[54:55], s[58:59]
	s_waitcnt vmcnt(20)
	ds_write_b16 v66, v2
	ds_write_b16_d16_hi v66, v2 offset:128
	ds_write_b16 v66, v3 offset:256
	ds_write_b16_d16_hi v66, v3 offset:384
	ds_write_b16 v66, v4 offset:512
	ds_write_b16_d16_hi v66, v4 offset:640
	ds_write_b16 v66, v5 offset:768
	ds_write_b16_d16_hi v66, v5 offset:896
	s_waitcnt vmcnt(19)
	ds_write_b16 v66, v6 offset:1024
	ds_write_b16_d16_hi v66, v6 offset:1152
	ds_write_b16 v66, v7 offset:1280
	ds_write_b16_d16_hi v66, v7 offset:1408
	ds_write_b16 v66, v8 offset:1536
	ds_write_b16_d16_hi v66, v8 offset:1664
	ds_write_b16 v66, v9 offset:1792
	ds_write_b16_d16_hi v66, v9 offset:1920
	s_waitcnt vmcnt(18)
	ds_write_b16 v66, v10 offset:2048
	ds_write_b16_d16_hi v66, v10 offset:2176
	ds_write_b16 v66, v11 offset:2304
	ds_write_b16_d16_hi v66, v11 offset:2432
	ds_write_b16 v66, v12 offset:2560
	ds_write_b16_d16_hi v66, v12 offset:2688
	ds_write_b16 v66, v13 offset:2816
	ds_write_b16_d16_hi v66, v13 offset:2944
	s_waitcnt vmcnt(17)
	ds_write_b16 v66, v14 offset:3072
	ds_write_b16_d16_hi v66, v14 offset:3200
	ds_write_b16 v66, v15 offset:3328
	ds_write_b16_d16_hi v66, v15 offset:3456
	ds_write_b16 v66, v16 offset:3584
	ds_write_b16_d16_hi v66, v16 offset:3712
	ds_write_b16 v66, v17 offset:3840
	ds_write_b16_d16_hi v66, v17 offset:3968
	s_waitcnt vmcnt(16)
	ds_write_b16 v66, v18 offset:4096
	ds_write_b16_d16_hi v66, v18 offset:4224
	ds_write_b16 v66, v19 offset:4352
	ds_write_b16_d16_hi v66, v19 offset:4480
	ds_write_b16 v66, v20 offset:4608
	ds_write_b16_d16_hi v66, v20 offset:4736
	ds_write_b16 v66, v21 offset:4864
	ds_write_b16_d16_hi v66, v21 offset:4992
	s_waitcnt vmcnt(15)
	ds_write_b16 v66, v22 offset:5120
	ds_write_b16_d16_hi v66, v22 offset:5248
	ds_write_b16 v66, v23 offset:5376
	ds_write_b16_d16_hi v66, v23 offset:5504
	ds_write_b16 v66, v24 offset:5632
	ds_write_b16_d16_hi v66, v24 offset:5760
	ds_write_b16 v66, v25 offset:5888
	ds_write_b16_d16_hi v66, v25 offset:6016
	s_waitcnt vmcnt(14)
	ds_write_b16 v66, v26 offset:6144
	ds_write_b16_d16_hi v66, v26 offset:6272
	ds_write_b16 v66, v27 offset:6400
	ds_write_b16_d16_hi v66, v27 offset:6528
	ds_write_b16 v66, v28 offset:6656
	ds_write_b16_d16_hi v66, v28 offset:6784
	ds_write_b16 v66, v29 offset:6912
	ds_write_b16_d16_hi v66, v29 offset:7040
	s_waitcnt vmcnt(13)
	ds_write_b16 v66, v30 offset:7168
	ds_write_b16_d16_hi v66, v30 offset:7296
	ds_write_b16 v66, v31 offset:7424
	ds_write_b16_d16_hi v66, v31 offset:7552
	ds_write_b16 v66, v32 offset:7680
	ds_write_b16_d16_hi v66, v32 offset:7808
	ds_write_b16 v66, v33 offset:7936
	ds_write_b16_d16_hi v66, v33 offset:8064
	global_load_dwordx4 v[18:21], v110, s[16:17] offset:1024
	global_load_dwordx4 v[22:25], v110, s[16:17] offset:1536
	global_load_dwordx4 v[14:17], v[70:71], off offset:256
	global_load_dwordx4 v[10:13], v[70:71], off offset:272
	global_load_dwordx4 v[6:9], v[70:71], off offset:288
	global_load_dwordx4 v[2:5], v[70:71], off offset:304
	global_load_dwordx4 v[26:29], v110, s[16:17] offset:2048
	global_load_dwordx4 v[30:33], v110, s[16:17] offset:2560
	global_load_dwordx4 v[94:97], v110, s[16:17] offset:3072
	global_load_dwordx4 v[98:101], v110, s[16:17] offset:3584
	s_waitcnt vmcnt(22)
	v_lshlrev_b32_e32 v118, 16, v34
	v_and_b32_e32 v117, 0xffff0000, v34
	v_lshlrev_b32_e32 v120, 16, v36
	v_and_b32_e32 v119, 0xffff0000, v36
	v_lshlrev_b32_e32 v122, 16, v35
	v_and_b32_e32 v121, 0xffff0000, v35
	s_waitcnt vmcnt(20)
	v_fma_f32 v36, v42, v118, v38
	s_waitcnt vmcnt(19)
	v_fmac_f32_e32 v36, v46, v117
	s_waitcnt vmcnt(18)
	v_fmac_f32_e32 v36, v50, v122
	v_fma_f32 v38, v43, v118, v39
	s_waitcnt vmcnt(17)
	v_fmac_f32_e32 v36, v54, v121
	v_fmac_f32_e32 v38, v47, v117
	s_waitcnt vmcnt(16)
	v_fmac_f32_e32 v36, v58, v120
	v_fmac_f32_e32 v38, v51, v122
	v_and_b32_e32 v73, 0xffff0000, v37
	v_lshlrev_b32_e32 v72, 16, v37
	s_waitcnt vmcnt(14)
	v_mov_b32_e32 v34, v74
	s_waitcnt vmcnt(13)
	v_mov_b32_e32 v35, v78
	v_fmac_f32_e32 v36, v62, v119
	v_fmac_f32_e32 v38, v55, v121
	v_fma_f32 v39, v44, v118, v40
	v_pk_mul_f32 v[34:35], v[34:35], v[72:73]
	v_fmac_f32_e32 v38, v59, v120
	v_fmac_f32_e32 v39, v48, v117
	v_add_f32_e32 v34, v36, v34
	v_mov_b32_e32 v78, v75
	v_fmac_f32_e32 v38, v63, v119
	v_fmac_f32_e32 v39, v52, v122
	v_fmac_f32_e32 v41, v45, v118
	v_add_f32_e32 v36, v34, v35
	v_pk_mul_f32 v[34:35], v[78:79], v[72:73]
	v_fmac_f32_e32 v39, v56, v121
	v_fmac_f32_e32 v41, v49, v117
	v_add_f32_e32 v34, v34, v38
	v_fmac_f32_e32 v39, v60, v120
	v_fmac_f32_e32 v41, v53, v122
	v_add_f32_e32 v37, v35, v34
	v_mov_b32_e32 v34, v76
	v_mov_b32_e32 v35, v80
	v_fmac_f32_e32 v39, v64, v119
	v_fmac_f32_e32 v41, v57, v121
	v_pk_mul_f32 v[34:35], v[34:35], v[72:73]
	v_fmac_f32_e32 v41, v61, v120
	v_add_f32_e32 v34, v34, v39
	v_mov_b32_e32 v80, v77
	v_fmac_f32_e32 v41, v65, v119
	v_add_f32_e32 v38, v35, v34
	v_pk_mul_f32 v[34:35], v[80:81], v[72:73]
	s_waitcnt vmcnt(10)
	v_and_b32_e32 v75, 0xffff0000, v90
	v_add_f32_e32 v34, v34, v41
	v_add_f32_e32 v39, v35, v34
	v_lshlrev_b32_e32 v74, 16, v90
	v_mov_b32_e32 v34, v82
	v_mov_b32_e32 v35, v86
	v_pk_mul_f32 v[34:35], v[34:35], v[74:75]
	v_mov_b32_e32 v86, v83
	v_add_f32_e32 v34, v36, v34
	v_add_f32_e32 v36, v34, v35
	v_pk_mul_f32 v[34:35], v[86:87], v[74:75]
	v_and_b32_e32 v79, 0xffff0000, v91
	v_add_f32_e32 v34, v34, v37
	v_add_f32_e32 v37, v35, v34
	v_mov_b32_e32 v34, v84
	v_mov_b32_e32 v35, v88
	v_pk_mul_f32 v[34:35], v[34:35], v[74:75]
	v_mov_b32_e32 v88, v85
	v_add_f32_e32 v34, v34, v38
	v_add_f32_e32 v38, v35, v34
	v_pk_mul_f32 v[34:35], v[88:89], v[74:75]
	v_lshlrev_b32_e32 v78, 16, v91
	v_add_f32_e32 v34, v34, v39
	v_add_f32_e32 v39, v35, v34
	v_and_b32_e32 v81, 0xffff0000, v92
	v_lshlrev_b32_e32 v80, 16, v92
	v_and_b32_e32 v83, 0xffff0000, v93
	v_lshlrev_b32_e32 v82, 16, v93
	s_waitcnt vmcnt(9)
	v_mov_b32_e32 v34, v18
	s_waitcnt vmcnt(8)
	v_mov_b32_e32 v35, v22
	v_pk_mul_f32 v[34:35], v[34:35], v[78:79]
	v_mov_b32_e32 v22, v19
	v_add_f32_e32 v18, v36, v34
	v_add_f32_e32 v34, v18, v35
	v_pk_mul_f32 v[18:19], v[22:23], v[78:79]
	s_nop 0
	v_add_f32_e32 v18, v18, v37
	v_add_f32_e32 v22, v19, v18
	v_mov_b32_e32 v18, v20
	v_mov_b32_e32 v19, v24
	v_pk_mul_f32 v[18:19], v[18:19], v[78:79]
	v_mov_b32_e32 v24, v21
	v_add_f32_e32 v18, v18, v38
	v_add_f32_e32 v20, v19, v18
	v_pk_mul_f32 v[18:19], v[24:25], v[78:79]
	s_waitcnt vmcnt(0)
	v_mov_b32_e32 v21, v98
	v_add_f32_e32 v18, v18, v39
	v_add_f32_e32 v23, v19, v18
	v_mov_b32_e32 v18, v26
	v_mov_b32_e32 v19, v30
	v_pk_mul_f32 v[18:19], v[18:19], v[80:81]
	v_mov_b32_e32 v30, v27
	v_add_f32_e32 v18, v34, v18
	v_add_f32_e32 v24, v18, v19
	v_pk_mul_f32 v[18:19], v[30:31], v[80:81]
	v_mov_b32_e32 v98, v95
	v_add_f32_e32 v18, v18, v22
	v_add_f32_e32 v22, v19, v18
	v_mov_b32_e32 v18, v28
	v_mov_b32_e32 v19, v32
	v_pk_mul_f32 v[18:19], v[18:19], v[80:81]
	v_mov_b32_e32 v32, v29
	v_add_f32_e32 v18, v18, v20
	v_mov_b32_e32 v20, v94
	v_pk_mul_f32 v[20:21], v[20:21], v[82:83]
	s_nop 0
	v_add_f32_e32 v20, v24, v20
	v_add_f32_e32 v20, v20, v21
	v_mul_f32_e64 v21, |v20|, s34
	v_exp_f32_e32 v21, v21
	v_add_f32_e32 v24, v19, v18
	v_pk_mul_f32 v[18:19], v[32:33], v[80:81]
	v_add_f32_e32 v21, 1.0, v21
	v_cmp_gt_f32_e32 vcc, s35, v21
	v_add_f32_e32 v18, v18, v23
	v_add_f32_e32 v26, v19, v18
	v_cndmask_b32_e64 v25, 0, 32, vcc
	v_ldexp_f32 v21, v21, v25
	v_log_f32_e32 v25, v21
	v_min_f32_e32 v18, 0, v20
	v_pk_mul_f32 v[20:21], v[98:99], v[82:83]
	v_mov_b32_e32 v23, v100
	v_add_f32_e32 v20, v20, v22
	v_add_f32_e32 v21, v21, v20
	v_mul_f32_e64 v20, |v21|, s34
	v_exp_f32_e32 v20, v20
	v_mul_f32_e32 v19, 0x3f317217, v25
	v_fma_f32 v19, v25, s36, -v19
	v_fmac_f32_e32 v19, 0x3377d1cf, v25
	v_fmac_f32_e32 v19, 0x3f317217, v25
	v_cmp_lt_f32_e64 s[0:1], |v25|, s37
	v_add_f32_e32 v20, 1.0, v20
	v_mov_b32_e32 v100, v97
	v_cndmask_b32_e64 v19, v25, v19, s[0:1]
	v_cmp_gt_f32_e64 s[0:1], s35, v20
	s_nop 1
	v_cndmask_b32_e64 v22, 0, 32, s[0:1]
	v_ldexp_f32 v20, v20, v22
	v_mov_b32_e32 v22, v96
	v_pk_mul_f32 v[22:23], v[22:23], v[82:83]
	v_log_f32_e32 v25, v20
	v_add_f32_e32 v22, v22, v24
	v_add_f32_e32 v22, v23, v22
	v_mul_f32_e64 v23, |v22|, s34
	v_cndmask_b32_e32 v20, 0, v111, vcc
	v_exp_f32_e32 v23, v23
	v_sub_f32_e32 v20, v19, v20
	v_min_f32_e32 v19, 0, v21
	v_mul_f32_e32 v21, 0x3f317217, v25
	v_fma_f32 v21, v25, s36, -v21
	v_fmac_f32_e32 v21, 0x3377d1cf, v25
	v_fmac_f32_e32 v21, 0x3f317217, v25
	v_cmp_lt_f32_e64 vcc, |v25|, s37
	v_add_f32_e32 v23, 1.0, v23
	v_cndmask_b32_e64 v24, 0, v111, s[0:1]
	v_cndmask_b32_e32 v21, v25, v21, vcc
	v_cmp_gt_f32_e32 vcc, s35, v23
	v_sub_f32_e32 v21, v21, v24
	v_pk_add_f32 v[18:19], v[18:19], v[20:21] neg_lo:[0,1] neg_hi:[0,1]
	v_cndmask_b32_e64 v24, 0, 32, vcc
	v_ldexp_f32 v23, v23, v24
	v_pk_mul_f32 v[20:21], v[100:101], v[82:83]
	v_log_f32_e32 v23, v23
	v_add_f32_e32 v20, v20, v26
	v_add_f32_e32 v21, v21, v20
	v_mul_f32_e64 v20, |v21|, s34
	v_exp_f32_e32 v20, v20
	v_pk_mul_f32 v[70:71], v[18:19], s[6:7] op_sel_hi:[1,0]
	v_mul_f32_e32 v19, 0x3f317217, v23
	v_fma_f32 v19, v23, s36, -v19
	v_fmac_f32_e32 v19, 0x3377d1cf, v23
	v_fmac_f32_e32 v19, 0x3f317217, v23
	v_cmp_lt_f32_e64 s[0:1], |v23|, s37
	v_add_f32_e32 v20, 1.0, v20
	v_min_f32_e32 v18, 0, v22
	v_cndmask_b32_e64 v19, v23, v19, s[0:1]
	v_cmp_gt_f32_e64 s[0:1], s35, v20
	s_nop 1
	v_cndmask_b32_e64 v22, 0, 32, s[0:1]
	v_ldexp_f32 v20, v20, v22
	v_log_f32_e32 v22, v20
	v_cndmask_b32_e32 v20, 0, v111, vcc
	v_sub_f32_e32 v20, v19, v20
	v_min_f32_e32 v19, 0, v21
	v_mul_f32_e32 v21, 0x3f317217, v22
	v_fma_f32 v21, v22, s36, -v21
	v_fmac_f32_e32 v21, 0x3377d1cf, v22
	v_fmac_f32_e32 v21, 0x3f317217, v22
	v_cmp_lt_f32_e64 vcc, |v22|, s37
	s_nop 1
	v_cndmask_b32_e32 v21, v22, v21, vcc
	v_cndmask_b32_e64 v22, 0, v111, s[0:1]
	v_sub_f32_e32 v21, v21, v22
	v_pk_add_f32 v[18:19], v[18:19], v[20:21] neg_lo:[0,1] neg_hi:[0,1]
	s_nop 0
	v_pk_mul_f32 v[76:77], v[18:19], s[6:7] op_sel_hi:[1,0]
	global_load_dwordx4 v[18:21], v123, s[48:49] offset:528
	global_load_dwordx4 v[22:25], v123, s[12:13] offset:16
	global_load_dwordx4 v[26:29], v123, s[12:13] offset:3088
	global_load_dwordx4 v[30:33], v123, s[12:13] offset:3600
	global_load_dwordx4 v[34:37], v110, s[16:17] offset:16
	global_load_dwordx4 v[38:41], v110, s[16:17] offset:528
	global_load_dwordx4 v[42:45], v110, s[16:17] offset:1040
	global_load_dwordx4 v[46:49], v110, s[16:17] offset:1552
	global_load_dwordx4 v[50:53], v110, s[16:17] offset:2064
	global_load_dwordx4 v[54:57], v110, s[16:17] offset:2576
	global_load_dwordx4 v[58:61], v110, s[16:17] offset:3088
	global_load_dwordx4 v[62:65], v110, s[16:17] offset:3600
	global_load_dwordx4 v[84:87], v123, s[12:13] offset:528
	global_load_dwordx4 v[88:91], v123, s[12:13] offset:1040
	global_load_dwordx4 v[92:95], v123, s[12:13] offset:1552
	global_load_dwordx4 v[96:99], v123, s[12:13] offset:2064
	global_load_dwordx4 v[100:103], v123, s[12:13] offset:2576
	s_waitcnt vmcnt(15)
	v_fma_f32 v130, v22, v118, v18
	v_fma_f32 v20, v24, v118, v20
	s_waitcnt vmcnt(14)
	v_mov_b32_e32 v104, v26
	s_waitcnt vmcnt(13)
	v_mov_b32_e32 v105, v30
	v_fma_f32 v23, v23, v118, v19
	v_mov_b32_e32 v30, v27
	v_mov_b32_e32 v18, v28
	v_mov_b32_e32 v19, v32
	v_pk_mul_f32 v[26:27], v[104:105], v[72:73]
	s_waitcnt vmcnt(12)
	v_mov_b32_e32 v106, v34
	s_waitcnt vmcnt(11)
	v_mov_b32_e32 v107, v38
	s_waitcnt vmcnt(4)
	v_fmac_f32_e32 v130, v84, v117
	v_fmac_f32_e32 v20, v86, v117
	s_waitcnt vmcnt(3)
	v_fmac_f32_e32 v130, v88, v122
	v_fmac_f32_e32 v20, v90, v122
	s_waitcnt vmcnt(2)
	v_fmac_f32_e32 v130, v92, v121
	v_fmac_f32_e32 v20, v94, v121
	s_waitcnt vmcnt(1)
	v_fmac_f32_e32 v130, v96, v120
	v_fmac_f32_e32 v20, v98, v120
	s_waitcnt vmcnt(0)
	v_fmac_f32_e32 v130, v100, v119
	v_fmac_f32_e32 v23, v85, v117
	v_pk_mul_f32 v[18:19], v[18:19], v[72:73]
	v_fmac_f32_e32 v20, v102, v119
	v_add_f32_e32 v24, v130, v26
	v_mov_b32_e32 v38, v35
	v_pk_mul_f32 v[34:35], v[106:107], v[74:75]
	v_fmac_f32_e32 v23, v89, v122
	v_add_f32_e32 v18, v18, v20
	v_add_f32_e32 v20, v24, v27
	v_mov_b32_e32 v124, v42
	v_mov_b32_e32 v125, v46
	v_fmac_f32_e32 v23, v93, v121
	v_add_f32_e32 v20, v20, v34
	v_mov_b32_e32 v46, v43
	v_pk_mul_f32 v[42:43], v[124:125], v[78:79]
	v_fmac_f32_e32 v23, v97, v120
	v_add_f32_e32 v20, v20, v35
	v_mov_b32_e32 v126, v50
	v_mov_b32_e32 v127, v54
	v_pk_mul_f32 v[30:31], v[30:31], v[72:73]
	v_fmac_f32_e32 v23, v101, v119
	v_add_f32_e32 v20, v20, v42
	v_mov_b32_e32 v54, v51
	v_pk_mul_f32 v[50:51], v[126:127], v[80:81]
	v_add_f32_e32 v23, v30, v23
	v_add_f32_e32 v20, v20, v43
	v_mov_b32_e32 v128, v58
	v_mov_b32_e32 v129, v62
	v_pk_mul_f32 v[38:39], v[38:39], v[74:75]
	v_add_f32_e32 v23, v31, v23
	v_add_f32_e32 v20, v20, v50
	v_mov_b32_e32 v62, v59
	v_pk_mul_f32 v[58:59], v[128:129], v[82:83]
	v_add_f32_e32 v23, v38, v23
	v_add_f32_e32 v20, v20, v51
	v_pk_mul_f32 v[46:47], v[46:47], v[78:79]
	v_add_f32_e32 v23, v39, v23
	v_add_f32_e32 v20, v20, v58
	v_add_f32_e32 v23, v46, v23
	v_add_f32_e32 v20, v20, v59
	v_pk_mul_f32 v[54:55], v[54:55], v[80:81]
	v_add_f32_e32 v23, v47, v23
	v_mul_f32_e64 v24, |v20|, s34
	v_add_f32_e32 v23, v54, v23
	v_exp_f32_e32 v24, v24
	v_pk_mul_f32 v[62:63], v[62:63], v[82:83]
	v_add_f32_e32 v23, v55, v23
	v_add_f32_e32 v23, v62, v23
	v_add_f32_e32 v23, v63, v23
	v_mul_f32_e64 v26, |v23|, s34
	v_add_f32_e32 v27, v19, v18
	v_add_f32_e32 v19, 1.0, v24
	v_exp_f32_e32 v26, v26
	v_cmp_gt_f32_e32 vcc, s35, v19
	v_min_f32_e32 v18, 0, v20
	v_mov_b32_e32 v22, v36
	v_cndmask_b32_e64 v24, 0, 32, vcc
	v_ldexp_f32 v19, v19, v24
	v_log_f32_e32 v24, v19
	v_add_f32_e32 v20, 1.0, v26
	v_cmp_gt_f32_e64 s[0:1], s35, v20
	v_min_f32_e32 v19, 0, v23
	v_cndmask_b32_e32 v23, 0, v111, vcc
	v_cndmask_b32_e64 v26, 0, 32, s[0:1]
	v_ldexp_f32 v20, v20, v26
	v_mul_f32_e32 v26, 0x3f317217, v24
	v_fma_f32 v26, v24, s36, -v26
	v_fmac_f32_e32 v26, 0x3377d1cf, v24
	v_fmac_f32_e32 v26, 0x3f317217, v24
	v_cmp_lt_f32_e64 vcc, |v24|, s37
	v_log_f32_e32 v20, v20
	v_fmac_f32_e32 v21, v25, v118
	v_cndmask_b32_e32 v24, v24, v26, vcc
	v_sub_f32_e32 v26, v24, v23
	v_mov_b32_e32 v23, v40
	v_pk_mul_f32 v[22:23], v[22:23], v[74:75]
	v_mul_f32_e32 v28, 0x3f317217, v20
	v_add_f32_e32 v22, v22, v27
	v_add_f32_e32 v24, v23, v22
	v_mov_b32_e32 v22, v44
	v_mov_b32_e32 v23, v48
	v_pk_mul_f32 v[22:23], v[22:23], v[78:79]
	v_fma_f32 v28, v20, s36, -v28
	v_add_f32_e32 v22, v22, v24
	v_add_f32_e32 v24, v23, v22
	v_mov_b32_e32 v22, v52
	v_mov_b32_e32 v23, v56
	v_pk_mul_f32 v[22:23], v[22:23], v[80:81]
	v_fmac_f32_e32 v28, 0x3377d1cf, v20
	v_add_f32_e32 v22, v22, v24
	v_add_f32_e32 v24, v23, v22
	v_mov_b32_e32 v22, v60
	v_mov_b32_e32 v23, v64
	v_pk_mul_f32 v[22:23], v[22:23], v[82:83]
	v_fmac_f32_e32 v28, 0x3f317217, v20
	v_add_f32_e32 v22, v22, v24
	v_add_f32_e32 v22, v23, v22
	v_mul_f32_e64 v23, |v22|, s34
	v_exp_f32_e32 v23, v23
	v_cmp_lt_f32_e64 vcc, |v20|, s37
	v_cndmask_b32_e64 v24, 0, v111, s[0:1]
	v_fmac_f32_e32 v21, v87, v117
	v_cndmask_b32_e32 v20, v20, v28, vcc
	v_sub_f32_e32 v27, v20, v24
	v_add_f32_e32 v20, 1.0, v23
	v_fmac_f32_e32 v21, v91, v122
	v_cmp_gt_f32_e32 vcc, s35, v20
	v_fmac_f32_e32 v21, v95, v121
	v_pk_add_f32 v[18:19], v[18:19], v[26:27] neg_lo:[0,1] neg_hi:[0,1]
	v_cndmask_b32_e64 v23, 0, 32, vcc
	v_fmac_f32_e32 v21, v99, v120
	v_mov_b32_e32 v32, v29
	v_ldexp_f32 v20, v20, v23
	v_pk_mul_f32 v[84:85], v[18:19], s[6:7] op_sel_hi:[1,0]
	v_min_f32_e32 v18, 0, v22
	v_fmac_f32_e32 v21, v103, v119
	v_pk_mul_f32 v[22:23], v[32:33], v[72:73]
	v_log_f32_e32 v24, v20
	v_add_f32_e32 v20, v22, v21
	v_mov_b32_e32 v40, v37
	v_add_f32_e32 v22, v23, v20
	v_pk_mul_f32 v[20:21], v[40:41], v[74:75]
	v_mov_b32_e32 v48, v45
	v_add_f32_e32 v20, v20, v22
	v_add_f32_e32 v22, v21, v20
	v_pk_mul_f32 v[20:21], v[48:49], v[78:79]
	v_mov_b32_e32 v56, v53
	v_add_f32_e32 v20, v20, v22
	v_add_f32_e32 v22, v21, v20
	v_pk_mul_f32 v[20:21], v[56:57], v[80:81]
	v_mov_b32_e32 v64, v61
	v_add_f32_e32 v20, v20, v22
	v_add_f32_e32 v22, v21, v20
	v_pk_mul_f32 v[20:21], v[64:65], v[82:83]
	v_mul_f32_e32 v19, 0x3f317217, v24
	v_add_f32_e32 v20, v20, v22
	v_add_f32_e32 v21, v21, v20
	v_mul_f32_e64 v20, |v21|, s34
	v_exp_f32_e32 v20, v20
	v_fma_f32 v19, v24, s36, -v19
	v_fmac_f32_e32 v19, 0x3377d1cf, v24
	v_fmac_f32_e32 v19, 0x3f317217, v24
	v_cmp_lt_f32_e64 s[0:1], |v24|, s37
	v_add_f32_e32 v20, 1.0, v20
	s_nop 0
	v_cndmask_b32_e64 v19, v24, v19, s[0:1]
	v_cmp_gt_f32_e64 s[0:1], s35, v20
	s_nop 1
	v_cndmask_b32_e64 v22, 0, 32, s[0:1]
	v_ldexp_f32 v20, v20, v22
	v_log_f32_e32 v22, v20
	v_cndmask_b32_e32 v20, 0, v111, vcc
	v_sub_f32_e32 v20, v19, v20
	v_min_f32_e32 v19, 0, v21
	v_mul_f32_e32 v21, 0x3f317217, v22
	v_fma_f32 v21, v22, s36, -v21
	v_fmac_f32_e32 v21, 0x3377d1cf, v22
	v_fmac_f32_e32 v21, 0x3f317217, v22
	v_cmp_lt_f32_e64 vcc, |v22|, s37
	s_nop 1
	v_cndmask_b32_e32 v21, v22, v21, vcc
	v_cndmask_b32_e64 v22, 0, v111, s[0:1]
	v_sub_f32_e32 v21, v21, v22
	v_pk_add_f32 v[18:19], v[18:19], v[20:21] neg_lo:[0,1] neg_hi:[0,1]
	s_nop 0
	v_pk_mul_f32 v[86:87], v[18:19], s[6:7] op_sel_hi:[1,0]
	global_load_dwordx4 v[18:21], v123, s[48:49] offset:544
	global_load_dwordx4 v[22:25], v123, s[12:13] offset:32
	global_load_dwordx4 v[26:29], v123, s[12:13] offset:3104
	global_load_dwordx4 v[30:33], v123, s[12:13] offset:3616
	global_load_dwordx4 v[34:37], v110, s[16:17] offset:32
	global_load_dwordx4 v[38:41], v110, s[16:17] offset:544
	global_load_dwordx4 v[42:45], v110, s[16:17] offset:1056
	global_load_dwordx4 v[46:49], v110, s[16:17] offset:1568
	global_load_dwordx4 v[50:53], v110, s[16:17] offset:2080
	global_load_dwordx4 v[54:57], v110, s[16:17] offset:2592
	global_load_dwordx4 v[58:61], v110, s[16:17] offset:3104
	global_load_dwordx4 v[62:65], v110, s[16:17] offset:3616
	global_load_dwordx4 v[88:91], v123, s[12:13] offset:544
	global_load_dwordx4 v[92:95], v123, s[12:13] offset:1056
	global_load_dwordx4 v[96:99], v123, s[12:13] offset:1568
	global_load_dwordx4 v[100:103], v123, s[12:13] offset:2080
	global_load_dwordx4 v[104:107], v123, s[12:13] offset:2592
	s_waitcnt vmcnt(15)
	v_fma_f32 v134, v22, v118, v18
	v_fma_f32 v20, v24, v118, v20
	s_waitcnt vmcnt(14)
	v_mov_b32_e32 v124, v26
	s_waitcnt vmcnt(13)
	v_mov_b32_e32 v125, v30
	v_fma_f32 v23, v23, v118, v19
	v_mov_b32_e32 v30, v27
	v_mov_b32_e32 v18, v28
	v_mov_b32_e32 v19, v32
	v_pk_mul_f32 v[26:27], v[124:125], v[72:73]
	s_waitcnt vmcnt(12)
	v_mov_b32_e32 v126, v34
	s_waitcnt vmcnt(11)
	v_mov_b32_e32 v127, v38
	s_waitcnt vmcnt(4)
	v_fmac_f32_e32 v134, v88, v117
	v_fmac_f32_e32 v20, v90, v117
	s_waitcnt vmcnt(3)
	v_fmac_f32_e32 v134, v92, v122
	v_fmac_f32_e32 v20, v94, v122
	s_waitcnt vmcnt(2)
	v_fmac_f32_e32 v134, v96, v121
	v_fmac_f32_e32 v20, v98, v121
	s_waitcnt vmcnt(1)
	v_fmac_f32_e32 v134, v100, v120
	v_fmac_f32_e32 v20, v102, v120
	s_waitcnt vmcnt(0)
	v_fmac_f32_e32 v134, v104, v119
	v_fmac_f32_e32 v23, v89, v117
	v_pk_mul_f32 v[18:19], v[18:19], v[72:73]
	v_fmac_f32_e32 v20, v106, v119
	v_add_f32_e32 v24, v134, v26
	v_mov_b32_e32 v38, v35
	v_pk_mul_f32 v[34:35], v[126:127], v[74:75]
	v_fmac_f32_e32 v23, v93, v122
	v_add_f32_e32 v18, v18, v20
	v_add_f32_e32 v20, v24, v27
	v_mov_b32_e32 v128, v42
	v_mov_b32_e32 v129, v46
	v_fmac_f32_e32 v23, v97, v121
	v_add_f32_e32 v20, v20, v34
	v_mov_b32_e32 v46, v43
	v_pk_mul_f32 v[42:43], v[128:129], v[78:79]
	v_fmac_f32_e32 v23, v101, v120
	v_add_f32_e32 v20, v20, v35
	v_mov_b32_e32 v130, v50
	v_mov_b32_e32 v131, v54
	v_pk_mul_f32 v[30:31], v[30:31], v[72:73]
	v_fmac_f32_e32 v23, v105, v119
	v_add_f32_e32 v20, v20, v42
	v_mov_b32_e32 v54, v51
	v_pk_mul_f32 v[50:51], v[130:131], v[80:81]
	v_add_f32_e32 v23, v30, v23
	v_add_f32_e32 v20, v20, v43
	v_mov_b32_e32 v132, v58
	v_mov_b32_e32 v133, v62
	v_pk_mul_f32 v[38:39], v[38:39], v[74:75]
	v_add_f32_e32 v23, v31, v23
	v_add_f32_e32 v20, v20, v50
	v_mov_b32_e32 v62, v59
	v_pk_mul_f32 v[58:59], v[132:133], v[82:83]
	v_add_f32_e32 v23, v38, v23
	v_add_f32_e32 v20, v20, v51
	v_pk_mul_f32 v[46:47], v[46:47], v[78:79]
	v_add_f32_e32 v23, v39, v23
	v_add_f32_e32 v20, v20, v58
	v_add_f32_e32 v23, v46, v23
	v_add_f32_e32 v20, v20, v59
	v_pk_mul_f32 v[54:55], v[54:55], v[80:81]
	v_add_f32_e32 v23, v47, v23
	v_mul_f32_e64 v24, |v20|, s34
	v_add_f32_e32 v23, v54, v23
	v_exp_f32_e32 v24, v24
	v_pk_mul_f32 v[62:63], v[62:63], v[82:83]
	v_add_f32_e32 v23, v55, v23
	v_add_f32_e32 v23, v62, v23
	v_add_f32_e32 v23, v63, v23
	v_mul_f32_e64 v26, |v23|, s34
	v_add_f32_e32 v27, v19, v18
	v_add_f32_e32 v19, 1.0, v24
	v_exp_f32_e32 v26, v26
	v_cmp_gt_f32_e32 vcc, s35, v19
	v_min_f32_e32 v18, 0, v20
	v_mov_b32_e32 v22, v36
	v_cndmask_b32_e64 v24, 0, 32, vcc
	v_ldexp_f32 v19, v19, v24
	v_log_f32_e32 v24, v19
	v_add_f32_e32 v20, 1.0, v26
	v_cmp_gt_f32_e64 s[0:1], s35, v20
	v_min_f32_e32 v19, 0, v23
	v_cndmask_b32_e32 v23, 0, v111, vcc
	v_cndmask_b32_e64 v26, 0, 32, s[0:1]
	v_ldexp_f32 v20, v20, v26
	v_mul_f32_e32 v26, 0x3f317217, v24
	v_fma_f32 v26, v24, s36, -v26
	v_fmac_f32_e32 v26, 0x3377d1cf, v24
	v_fmac_f32_e32 v26, 0x3f317217, v24
	v_cmp_lt_f32_e64 vcc, |v24|, s37
	v_log_f32_e32 v20, v20
	v_fmac_f32_e32 v21, v25, v118
	v_cndmask_b32_e32 v24, v24, v26, vcc
	v_sub_f32_e32 v26, v24, v23
	v_mov_b32_e32 v23, v40
	v_pk_mul_f32 v[22:23], v[22:23], v[74:75]
	v_mul_f32_e32 v28, 0x3f317217, v20
	v_add_f32_e32 v22, v22, v27
	v_add_f32_e32 v24, v23, v22
	v_mov_b32_e32 v22, v44
	v_mov_b32_e32 v23, v48
	v_pk_mul_f32 v[22:23], v[22:23], v[78:79]
	v_fma_f32 v28, v20, s36, -v28
	v_add_f32_e32 v22, v22, v24
	v_add_f32_e32 v24, v23, v22
	v_mov_b32_e32 v22, v52
	v_mov_b32_e32 v23, v56
	v_pk_mul_f32 v[22:23], v[22:23], v[80:81]
	v_fmac_f32_e32 v28, 0x3377d1cf, v20
	v_add_f32_e32 v22, v22, v24
	v_add_f32_e32 v24, v23, v22
	v_mov_b32_e32 v22, v60
	v_mov_b32_e32 v23, v64
	v_pk_mul_f32 v[22:23], v[22:23], v[82:83]
	v_fmac_f32_e32 v28, 0x3f317217, v20
	v_add_f32_e32 v22, v22, v24
	v_add_f32_e32 v22, v23, v22
	v_mul_f32_e64 v23, |v22|, s34
	v_exp_f32_e32 v23, v23
	v_cmp_lt_f32_e64 vcc, |v20|, s37
	v_cndmask_b32_e64 v24, 0, v111, s[0:1]
	v_fmac_f32_e32 v21, v91, v117
	v_cndmask_b32_e32 v20, v20, v28, vcc
	v_sub_f32_e32 v27, v20, v24
	v_add_f32_e32 v20, 1.0, v23
	v_fmac_f32_e32 v21, v95, v122
	v_cmp_gt_f32_e32 vcc, s35, v20
	v_fmac_f32_e32 v21, v99, v121
	v_pk_add_f32 v[18:19], v[18:19], v[26:27] neg_lo:[0,1] neg_hi:[0,1]
	v_cndmask_b32_e64 v23, 0, 32, vcc
	v_fmac_f32_e32 v21, v103, v120
	v_mov_b32_e32 v32, v29
	v_ldexp_f32 v20, v20, v23
	v_pk_mul_f32 v[88:89], v[18:19], s[6:7] op_sel_hi:[1,0]
	v_min_f32_e32 v18, 0, v22
	v_fmac_f32_e32 v21, v107, v119
	v_pk_mul_f32 v[22:23], v[32:33], v[72:73]
	v_log_f32_e32 v24, v20
	v_add_f32_e32 v20, v22, v21
	v_mov_b32_e32 v40, v37
	v_add_f32_e32 v22, v23, v20
	v_pk_mul_f32 v[20:21], v[40:41], v[74:75]
	v_mov_b32_e32 v48, v45
	v_add_f32_e32 v20, v20, v22
	v_add_f32_e32 v22, v21, v20
	v_pk_mul_f32 v[20:21], v[48:49], v[78:79]
	v_mov_b32_e32 v56, v53
	v_add_f32_e32 v20, v20, v22
	v_add_f32_e32 v22, v21, v20
	v_pk_mul_f32 v[20:21], v[56:57], v[80:81]
	v_mov_b32_e32 v64, v61
	v_add_f32_e32 v20, v20, v22
	v_add_f32_e32 v22, v21, v20
	v_pk_mul_f32 v[20:21], v[64:65], v[82:83]
	v_mul_f32_e32 v19, 0x3f317217, v24
	v_add_f32_e32 v20, v20, v22
	v_add_f32_e32 v21, v21, v20
	v_mul_f32_e64 v20, |v21|, s34
	v_exp_f32_e32 v20, v20
	v_fma_f32 v19, v24, s36, -v19
	v_fmac_f32_e32 v19, 0x3377d1cf, v24
	v_fmac_f32_e32 v19, 0x3f317217, v24
	v_cmp_lt_f32_e64 s[0:1], |v24|, s37
	v_add_f32_e32 v20, 1.0, v20
	s_nop 0
	v_cndmask_b32_e64 v19, v24, v19, s[0:1]
	v_cmp_gt_f32_e64 s[0:1], s35, v20
	s_nop 1
	v_cndmask_b32_e64 v22, 0, 32, s[0:1]
	v_ldexp_f32 v20, v20, v22
	v_log_f32_e32 v22, v20
	v_cndmask_b32_e32 v20, 0, v111, vcc
	v_sub_f32_e32 v20, v19, v20
	v_min_f32_e32 v19, 0, v21
	v_mul_f32_e32 v21, 0x3f317217, v22
	v_fma_f32 v21, v22, s36, -v21
	v_fmac_f32_e32 v21, 0x3377d1cf, v22
	v_fmac_f32_e32 v21, 0x3f317217, v22
	v_cmp_lt_f32_e64 vcc, |v22|, s37
	s_nop 1
	v_cndmask_b32_e32 v21, v22, v21, vcc
	v_cndmask_b32_e64 v22, 0, v111, s[0:1]
	v_sub_f32_e32 v21, v21, v22
	v_pk_add_f32 v[18:19], v[18:19], v[20:21] neg_lo:[0,1] neg_hi:[0,1]
	s_nop 0
	v_pk_mul_f32 v[90:91], v[18:19], s[6:7] op_sel_hi:[1,0]
	global_load_dwordx4 v[18:21], v123, s[48:49] offset:560
	global_load_dwordx4 v[22:25], v123, s[12:13] offset:48
	global_load_dwordx4 v[26:29], v123, s[12:13] offset:3120
	global_load_dwordx4 v[30:33], v123, s[12:13] offset:3632
	global_load_dwordx4 v[34:37], v110, s[16:17] offset:48
	global_load_dwordx4 v[38:41], v110, s[16:17] offset:560
	global_load_dwordx4 v[42:45], v110, s[16:17] offset:1072
	global_load_dwordx4 v[46:49], v110, s[16:17] offset:1584
	global_load_dwordx4 v[50:53], v110, s[16:17] offset:2096
	global_load_dwordx4 v[54:57], v110, s[16:17] offset:2608
	global_load_dwordx4 v[58:61], v110, s[16:17] offset:3120
	global_load_dwordx4 v[62:65], v110, s[16:17] offset:3632
	global_load_dwordx4 v[92:95], v123, s[12:13] offset:560
	global_load_dwordx4 v[96:99], v123, s[12:13] offset:1072
	global_load_dwordx4 v[100:103], v123, s[12:13] offset:1584
	global_load_dwordx4 v[104:107], v123, s[12:13] offset:2096
	global_load_dwordx4 v[124:127], v123, s[12:13] offset:2608
	s_waitcnt vmcnt(15)
	v_fma_f32 v138, v22, v118, v18
	v_fma_f32 v20, v24, v118, v20
	s_waitcnt vmcnt(14)
	v_mov_b32_e32 v128, v26
	s_waitcnt vmcnt(13)
	v_mov_b32_e32 v129, v30
	v_fma_f32 v23, v23, v118, v19
	v_mov_b32_e32 v30, v27
	v_mov_b32_e32 v18, v28
	v_mov_b32_e32 v19, v32
	v_pk_mul_f32 v[26:27], v[128:129], v[72:73]
	s_waitcnt vmcnt(12)
	v_mov_b32_e32 v130, v34
	s_waitcnt vmcnt(11)
	v_mov_b32_e32 v131, v38
	s_waitcnt vmcnt(4)
	v_fmac_f32_e32 v138, v92, v117
	v_fmac_f32_e32 v20, v94, v117
	s_waitcnt vmcnt(3)
	v_fmac_f32_e32 v138, v96, v122
	v_fmac_f32_e32 v20, v98, v122
	s_waitcnt vmcnt(2)
	v_fmac_f32_e32 v138, v100, v121
	v_fmac_f32_e32 v20, v102, v121
	s_waitcnt vmcnt(1)
	v_fmac_f32_e32 v138, v104, v120
	v_fmac_f32_e32 v20, v106, v120
	s_waitcnt vmcnt(0)
	v_fmac_f32_e32 v138, v124, v119
	v_fmac_f32_e32 v23, v93, v117
	v_pk_mul_f32 v[18:19], v[18:19], v[72:73]
	v_fmac_f32_e32 v20, v126, v119
	v_add_f32_e32 v24, v138, v26
	v_mov_b32_e32 v38, v35
	v_pk_mul_f32 v[34:35], v[130:131], v[74:75]
	v_fmac_f32_e32 v23, v97, v122
	v_add_f32_e32 v18, v18, v20
	v_add_f32_e32 v20, v24, v27
	v_mov_b32_e32 v132, v42
	v_mov_b32_e32 v133, v46
	v_fmac_f32_e32 v23, v101, v121
	v_add_f32_e32 v20, v20, v34
	v_mov_b32_e32 v46, v43
	v_pk_mul_f32 v[42:43], v[132:133], v[78:79]
	v_fmac_f32_e32 v23, v105, v120
	v_add_f32_e32 v20, v20, v35
	v_mov_b32_e32 v134, v50
	v_mov_b32_e32 v135, v54
	v_pk_mul_f32 v[30:31], v[30:31], v[72:73]
	v_fmac_f32_e32 v23, v125, v119
	v_add_f32_e32 v20, v20, v42
	v_mov_b32_e32 v54, v51
	v_pk_mul_f32 v[50:51], v[134:135], v[80:81]
	v_add_f32_e32 v23, v30, v23
	v_add_f32_e32 v20, v20, v43
	v_mov_b32_e32 v136, v58
	v_mov_b32_e32 v137, v62
	v_pk_mul_f32 v[38:39], v[38:39], v[74:75]
	v_add_f32_e32 v23, v31, v23
	v_add_f32_e32 v20, v20, v50
	v_mov_b32_e32 v62, v59
	v_pk_mul_f32 v[58:59], v[136:137], v[82:83]
	v_add_f32_e32 v23, v38, v23
	v_add_f32_e32 v20, v20, v51
	v_pk_mul_f32 v[46:47], v[46:47], v[78:79]
	v_add_f32_e32 v23, v39, v23
	v_add_f32_e32 v20, v20, v58
	v_add_f32_e32 v23, v46, v23
	v_add_f32_e32 v20, v20, v59
	v_pk_mul_f32 v[54:55], v[54:55], v[80:81]
	v_add_f32_e32 v23, v47, v23
	v_mul_f32_e64 v24, |v20|, s34
	v_add_f32_e32 v23, v54, v23
	v_exp_f32_e32 v24, v24
	v_pk_mul_f32 v[62:63], v[62:63], v[82:83]
	v_add_f32_e32 v23, v55, v23
	v_add_f32_e32 v23, v62, v23
	v_add_f32_e32 v23, v63, v23
	v_mul_f32_e64 v26, |v23|, s34
	v_add_f32_e32 v27, v19, v18
	v_add_f32_e32 v19, 1.0, v24
	v_exp_f32_e32 v26, v26
	v_cmp_gt_f32_e32 vcc, s35, v19
	v_min_f32_e32 v18, 0, v20
	v_mov_b32_e32 v22, v36
	v_cndmask_b32_e64 v24, 0, 32, vcc
	v_ldexp_f32 v19, v19, v24
	v_log_f32_e32 v24, v19
	v_add_f32_e32 v20, 1.0, v26
	v_cmp_gt_f32_e64 s[0:1], s35, v20
	v_min_f32_e32 v19, 0, v23
	v_cndmask_b32_e32 v23, 0, v111, vcc
	v_cndmask_b32_e64 v26, 0, 32, s[0:1]
	v_ldexp_f32 v20, v20, v26
	v_mul_f32_e32 v26, 0x3f317217, v24
	v_fma_f32 v26, v24, s36, -v26
	v_fmac_f32_e32 v26, 0x3377d1cf, v24
	v_fmac_f32_e32 v26, 0x3f317217, v24
	v_cmp_lt_f32_e64 vcc, |v24|, s37
	v_log_f32_e32 v20, v20
	v_fmac_f32_e32 v21, v25, v118
	v_cndmask_b32_e32 v24, v24, v26, vcc
	v_sub_f32_e32 v26, v24, v23
	v_mov_b32_e32 v23, v40
	v_pk_mul_f32 v[22:23], v[22:23], v[74:75]
	v_mul_f32_e32 v28, 0x3f317217, v20
	v_add_f32_e32 v22, v22, v27
	v_add_f32_e32 v24, v23, v22
	v_mov_b32_e32 v22, v44
	v_mov_b32_e32 v23, v48
	v_pk_mul_f32 v[22:23], v[22:23], v[78:79]
	v_fma_f32 v28, v20, s36, -v28
	v_add_f32_e32 v22, v22, v24
	v_add_f32_e32 v24, v23, v22
	v_mov_b32_e32 v22, v52
	v_mov_b32_e32 v23, v56
	v_pk_mul_f32 v[22:23], v[22:23], v[80:81]
	v_fmac_f32_e32 v28, 0x3377d1cf, v20
	v_add_f32_e32 v22, v22, v24
	v_add_f32_e32 v24, v23, v22
	v_mov_b32_e32 v22, v60
	v_mov_b32_e32 v23, v64
	v_pk_mul_f32 v[22:23], v[22:23], v[82:83]
	v_fmac_f32_e32 v28, 0x3f317217, v20
	v_add_f32_e32 v22, v22, v24
	v_add_f32_e32 v22, v23, v22
	v_mul_f32_e64 v23, |v22|, s34
	v_exp_f32_e32 v23, v23
	v_cmp_lt_f32_e64 vcc, |v20|, s37
	v_cndmask_b32_e64 v24, 0, v111, s[0:1]
	v_fmac_f32_e32 v21, v95, v117
	v_cndmask_b32_e32 v20, v20, v28, vcc
	v_sub_f32_e32 v27, v20, v24
	v_add_f32_e32 v20, 1.0, v23
	v_fmac_f32_e32 v21, v99, v122
	v_cmp_gt_f32_e32 vcc, s35, v20
	v_fmac_f32_e32 v21, v103, v121
	v_pk_add_f32 v[18:19], v[18:19], v[26:27] neg_lo:[0,1] neg_hi:[0,1]
	v_cndmask_b32_e64 v23, 0, 32, vcc
	v_fmac_f32_e32 v21, v107, v120
	v_mov_b32_e32 v32, v29
	v_ldexp_f32 v20, v20, v23
	v_pk_mul_f32 v[92:93], v[18:19], s[6:7] op_sel_hi:[1,0]
	v_min_f32_e32 v18, 0, v22
	v_fmac_f32_e32 v21, v127, v119
	v_pk_mul_f32 v[22:23], v[32:33], v[72:73]
	v_log_f32_e32 v24, v20
	v_add_f32_e32 v20, v22, v21
	v_mov_b32_e32 v40, v37
	v_add_f32_e32 v22, v23, v20
	v_pk_mul_f32 v[20:21], v[40:41], v[74:75]
	v_mov_b32_e32 v48, v45
	v_add_f32_e32 v20, v20, v22
	v_add_f32_e32 v22, v21, v20
	v_pk_mul_f32 v[20:21], v[48:49], v[78:79]
	v_mov_b32_e32 v56, v53
	v_add_f32_e32 v20, v20, v22
	v_add_f32_e32 v22, v21, v20
	v_pk_mul_f32 v[20:21], v[56:57], v[80:81]
	v_mov_b32_e32 v64, v61
	v_add_f32_e32 v20, v20, v22
	v_add_f32_e32 v22, v21, v20
	v_pk_mul_f32 v[20:21], v[64:65], v[82:83]
	v_mul_f32_e32 v19, 0x3f317217, v24
	v_add_f32_e32 v20, v20, v22
	v_add_f32_e32 v21, v21, v20
	v_mul_f32_e64 v20, |v21|, s34
	v_exp_f32_e32 v20, v20
	v_fma_f32 v19, v24, s36, -v19
	v_fmac_f32_e32 v19, 0x3377d1cf, v24
	v_fmac_f32_e32 v19, 0x3f317217, v24
	v_cmp_lt_f32_e64 s[0:1], |v24|, s37
	v_add_f32_e32 v20, 1.0, v20
	s_nop 0
	v_cndmask_b32_e64 v19, v24, v19, s[0:1]
	v_cmp_gt_f32_e64 s[0:1], s35, v20
	s_nop 1
	v_cndmask_b32_e64 v22, 0, 32, s[0:1]
	v_ldexp_f32 v20, v20, v22
	v_log_f32_e32 v22, v20
	v_cndmask_b32_e32 v20, 0, v111, vcc
	v_sub_f32_e32 v20, v19, v20
	v_min_f32_e32 v19, 0, v21
	v_mul_f32_e32 v21, 0x3f317217, v22
	v_fma_f32 v21, v22, s36, -v21
	v_fmac_f32_e32 v21, 0x3377d1cf, v22
	v_fmac_f32_e32 v21, 0x3f317217, v22
	v_cmp_lt_f32_e64 vcc, |v22|, s37
	s_nop 1
	v_cndmask_b32_e32 v21, v22, v21, vcc
	v_cndmask_b32_e64 v22, 0, v111, s[0:1]
	v_sub_f32_e32 v21, v21, v22
	v_pk_add_f32 v[18:19], v[18:19], v[20:21] neg_lo:[0,1] neg_hi:[0,1]
	s_nop 0
	v_pk_mul_f32 v[94:95], v[18:19], s[6:7] op_sel_hi:[1,0]
	global_load_dwordx4 v[18:21], v123, s[48:49] offset:576
	global_load_dwordx4 v[22:25], v123, s[12:13] offset:64
	global_load_dwordx4 v[26:29], v123, s[12:13] offset:3136
	global_load_dwordx4 v[30:33], v123, s[12:13] offset:3648
	global_load_dwordx4 v[34:37], v110, s[16:17] offset:64
	global_load_dwordx4 v[38:41], v110, s[16:17] offset:576
	global_load_dwordx4 v[42:45], v110, s[16:17] offset:1088
	global_load_dwordx4 v[46:49], v110, s[16:17] offset:1600
	global_load_dwordx4 v[50:53], v110, s[16:17] offset:2112
	global_load_dwordx4 v[54:57], v110, s[16:17] offset:2624
	global_load_dwordx4 v[58:61], v110, s[16:17] offset:3136
	global_load_dwordx4 v[62:65], v110, s[16:17] offset:3648
	global_load_dwordx4 v[96:99], v123, s[12:13] offset:576
	global_load_dwordx4 v[100:103], v123, s[12:13] offset:1088
	global_load_dwordx4 v[104:107], v123, s[12:13] offset:1600
	global_load_dwordx4 v[124:127], v123, s[12:13] offset:2112
	global_load_dwordx4 v[128:131], v123, s[12:13] offset:2624
	s_waitcnt vmcnt(15)
	v_fma_f32 v142, v22, v118, v18
	v_fma_f32 v20, v24, v118, v20
	s_waitcnt vmcnt(14)
	v_mov_b32_e32 v132, v26
	s_waitcnt vmcnt(13)
	v_mov_b32_e32 v133, v30
	v_fma_f32 v23, v23, v118, v19
	v_mov_b32_e32 v30, v27
	v_mov_b32_e32 v18, v28
	v_mov_b32_e32 v19, v32
	v_pk_mul_f32 v[26:27], v[132:133], v[72:73]
	s_waitcnt vmcnt(12)
	v_mov_b32_e32 v134, v34
	s_waitcnt vmcnt(11)
	v_mov_b32_e32 v135, v38
	s_waitcnt vmcnt(4)
	v_fmac_f32_e32 v142, v96, v117
	v_fmac_f32_e32 v20, v98, v117
	s_waitcnt vmcnt(3)
	v_fmac_f32_e32 v142, v100, v122
	v_fmac_f32_e32 v20, v102, v122
	s_waitcnt vmcnt(2)
	v_fmac_f32_e32 v142, v104, v121
	v_fmac_f32_e32 v20, v106, v121
	s_waitcnt vmcnt(1)
	v_fmac_f32_e32 v142, v124, v120
	v_fmac_f32_e32 v20, v126, v120
	s_waitcnt vmcnt(0)
	v_fmac_f32_e32 v142, v128, v119
	v_fmac_f32_e32 v23, v97, v117
	v_pk_mul_f32 v[18:19], v[18:19], v[72:73]
	v_fmac_f32_e32 v20, v130, v119
	v_add_f32_e32 v24, v142, v26
	v_mov_b32_e32 v38, v35
	v_pk_mul_f32 v[34:35], v[134:135], v[74:75]
	v_fmac_f32_e32 v23, v101, v122
	v_add_f32_e32 v18, v18, v20
	v_add_f32_e32 v20, v24, v27
	v_mov_b32_e32 v136, v42
	v_mov_b32_e32 v137, v46
	v_fmac_f32_e32 v23, v105, v121
	v_add_f32_e32 v20, v20, v34
	v_mov_b32_e32 v46, v43
	v_pk_mul_f32 v[42:43], v[136:137], v[78:79]
	v_fmac_f32_e32 v23, v125, v120
	v_add_f32_e32 v20, v20, v35
	v_mov_b32_e32 v138, v50
	v_mov_b32_e32 v139, v54
	v_pk_mul_f32 v[30:31], v[30:31], v[72:73]
	v_fmac_f32_e32 v23, v129, v119
	v_add_f32_e32 v20, v20, v42
	v_mov_b32_e32 v54, v51
	v_pk_mul_f32 v[50:51], v[138:139], v[80:81]
	v_add_f32_e32 v23, v30, v23
	v_add_f32_e32 v20, v20, v43
	v_mov_b32_e32 v140, v58
	v_mov_b32_e32 v141, v62
	v_pk_mul_f32 v[38:39], v[38:39], v[74:75]
	v_add_f32_e32 v23, v31, v23
	v_add_f32_e32 v20, v20, v50
	v_mov_b32_e32 v62, v59
	v_pk_mul_f32 v[58:59], v[140:141], v[82:83]
	v_add_f32_e32 v23, v38, v23
	v_add_f32_e32 v20, v20, v51
	v_pk_mul_f32 v[46:47], v[46:47], v[78:79]
	v_add_f32_e32 v23, v39, v23
	v_add_f32_e32 v20, v20, v58
	v_add_f32_e32 v23, v46, v23
	v_add_f32_e32 v20, v20, v59
	v_pk_mul_f32 v[54:55], v[54:55], v[80:81]
	v_add_f32_e32 v23, v47, v23
	v_mul_f32_e64 v24, |v20|, s34
	v_add_f32_e32 v23, v54, v23
	v_exp_f32_e32 v24, v24
	v_pk_mul_f32 v[62:63], v[62:63], v[82:83]
	v_add_f32_e32 v23, v55, v23
	v_add_f32_e32 v23, v62, v23
	v_add_f32_e32 v23, v63, v23
	v_mul_f32_e64 v26, |v23|, s34
	v_add_f32_e32 v27, v19, v18
	v_add_f32_e32 v19, 1.0, v24
	v_exp_f32_e32 v26, v26
	v_cmp_gt_f32_e32 vcc, s35, v19
	v_min_f32_e32 v18, 0, v20
	v_mov_b32_e32 v22, v36
	v_cndmask_b32_e64 v24, 0, 32, vcc
	v_ldexp_f32 v19, v19, v24
	v_log_f32_e32 v24, v19
	v_add_f32_e32 v20, 1.0, v26
	v_cmp_gt_f32_e64 s[0:1], s35, v20
	v_min_f32_e32 v19, 0, v23
	v_cndmask_b32_e32 v23, 0, v111, vcc
	v_cndmask_b32_e64 v26, 0, 32, s[0:1]
	v_ldexp_f32 v20, v20, v26
	v_mul_f32_e32 v26, 0x3f317217, v24
	v_fma_f32 v26, v24, s36, -v26
	v_fmac_f32_e32 v26, 0x3377d1cf, v24
	v_fmac_f32_e32 v26, 0x3f317217, v24
	v_cmp_lt_f32_e64 vcc, |v24|, s37
	v_log_f32_e32 v20, v20
	v_fmac_f32_e32 v21, v25, v118
	v_cndmask_b32_e32 v24, v24, v26, vcc
	v_sub_f32_e32 v26, v24, v23
	v_mov_b32_e32 v23, v40
	v_pk_mul_f32 v[22:23], v[22:23], v[74:75]
	v_mul_f32_e32 v28, 0x3f317217, v20
	v_add_f32_e32 v22, v22, v27
	v_add_f32_e32 v24, v23, v22
	v_mov_b32_e32 v22, v44
	v_mov_b32_e32 v23, v48
	v_pk_mul_f32 v[22:23], v[22:23], v[78:79]
	v_fma_f32 v28, v20, s36, -v28
	v_add_f32_e32 v22, v22, v24
	v_add_f32_e32 v24, v23, v22
	v_mov_b32_e32 v22, v52
	v_mov_b32_e32 v23, v56
	v_pk_mul_f32 v[22:23], v[22:23], v[80:81]
	v_fmac_f32_e32 v28, 0x3377d1cf, v20
	v_add_f32_e32 v22, v22, v24
	v_add_f32_e32 v24, v23, v22
	v_mov_b32_e32 v22, v60
	v_mov_b32_e32 v23, v64
	v_pk_mul_f32 v[22:23], v[22:23], v[82:83]
	v_fmac_f32_e32 v28, 0x3f317217, v20
	v_add_f32_e32 v22, v22, v24
	v_add_f32_e32 v22, v23, v22
	v_mul_f32_e64 v23, |v22|, s34
	v_exp_f32_e32 v23, v23
	v_cmp_lt_f32_e64 vcc, |v20|, s37
	v_cndmask_b32_e64 v24, 0, v111, s[0:1]
	v_fmac_f32_e32 v21, v99, v117
	v_cndmask_b32_e32 v20, v20, v28, vcc
	v_sub_f32_e32 v27, v20, v24
	v_add_f32_e32 v20, 1.0, v23
	v_fmac_f32_e32 v21, v103, v122
	v_cmp_gt_f32_e32 vcc, s35, v20
	v_fmac_f32_e32 v21, v107, v121
	v_pk_add_f32 v[18:19], v[18:19], v[26:27] neg_lo:[0,1] neg_hi:[0,1]
	v_cndmask_b32_e64 v23, 0, 32, vcc
	v_fmac_f32_e32 v21, v127, v120
	v_mov_b32_e32 v32, v29
	v_ldexp_f32 v20, v20, v23
	v_pk_mul_f32 v[96:97], v[18:19], s[6:7] op_sel_hi:[1,0]
	v_min_f32_e32 v18, 0, v22
	v_fmac_f32_e32 v21, v131, v119
	v_pk_mul_f32 v[22:23], v[32:33], v[72:73]
	v_log_f32_e32 v24, v20
	v_add_f32_e32 v20, v22, v21
	v_mov_b32_e32 v40, v37
	v_add_f32_e32 v22, v23, v20
	v_pk_mul_f32 v[20:21], v[40:41], v[74:75]
	v_mov_b32_e32 v48, v45
	v_add_f32_e32 v20, v20, v22
	v_add_f32_e32 v22, v21, v20
	v_pk_mul_f32 v[20:21], v[48:49], v[78:79]
	v_mov_b32_e32 v56, v53
	v_add_f32_e32 v20, v20, v22
	v_add_f32_e32 v22, v21, v20
	v_pk_mul_f32 v[20:21], v[56:57], v[80:81]
	v_mov_b32_e32 v64, v61
	v_add_f32_e32 v20, v20, v22
	v_add_f32_e32 v22, v21, v20
	v_pk_mul_f32 v[20:21], v[64:65], v[82:83]
	v_mul_f32_e32 v19, 0x3f317217, v24
	v_add_f32_e32 v20, v20, v22
	v_add_f32_e32 v21, v21, v20
	v_mul_f32_e64 v20, |v21|, s34
	v_exp_f32_e32 v20, v20
	v_fma_f32 v19, v24, s36, -v19
	v_fmac_f32_e32 v19, 0x3377d1cf, v24
	v_fmac_f32_e32 v19, 0x3f317217, v24
	v_cmp_lt_f32_e64 s[0:1], |v24|, s37
	v_add_f32_e32 v20, 1.0, v20
	s_nop 0
	v_cndmask_b32_e64 v19, v24, v19, s[0:1]
	v_cmp_gt_f32_e64 s[0:1], s35, v20
	s_nop 1
	v_cndmask_b32_e64 v22, 0, 32, s[0:1]
	v_ldexp_f32 v20, v20, v22
	v_log_f32_e32 v22, v20
	v_cndmask_b32_e32 v20, 0, v111, vcc
	v_sub_f32_e32 v20, v19, v20
	v_min_f32_e32 v19, 0, v21
	v_mul_f32_e32 v21, 0x3f317217, v22
	v_fma_f32 v21, v22, s36, -v21
	v_fmac_f32_e32 v21, 0x3377d1cf, v22
	v_fmac_f32_e32 v21, 0x3f317217, v22
	v_cmp_lt_f32_e64 vcc, |v22|, s37
	s_nop 1
	v_cndmask_b32_e32 v21, v22, v21, vcc
	v_cndmask_b32_e64 v22, 0, v111, s[0:1]
	v_sub_f32_e32 v21, v21, v22
	v_pk_add_f32 v[18:19], v[18:19], v[20:21] neg_lo:[0,1] neg_hi:[0,1]
	s_nop 0
	v_pk_mul_f32 v[98:99], v[18:19], s[6:7] op_sel_hi:[1,0]
	global_load_dwordx4 v[18:21], v123, s[48:49] offset:592
	global_load_dwordx4 v[22:25], v123, s[12:13] offset:80
	global_load_dwordx4 v[26:29], v123, s[12:13] offset:3152
	global_load_dwordx4 v[30:33], v123, s[12:13] offset:3664
	global_load_dwordx4 v[34:37], v110, s[16:17] offset:80
	global_load_dwordx4 v[38:41], v110, s[16:17] offset:592
	global_load_dwordx4 v[42:45], v110, s[16:17] offset:1104
	global_load_dwordx4 v[46:49], v110, s[16:17] offset:1616
	global_load_dwordx4 v[50:53], v110, s[16:17] offset:2128
	global_load_dwordx4 v[54:57], v110, s[16:17] offset:2640
	global_load_dwordx4 v[58:61], v110, s[16:17] offset:3152
	global_load_dwordx4 v[62:65], v110, s[16:17] offset:3664
	global_load_dwordx4 v[100:103], v123, s[12:13] offset:592
	global_load_dwordx4 v[104:107], v123, s[12:13] offset:1104
	global_load_dwordx4 v[124:127], v123, s[12:13] offset:1616
	global_load_dwordx4 v[128:131], v123, s[12:13] offset:2128
	global_load_dwordx4 v[132:135], v123, s[12:13] offset:2640
	s_waitcnt vmcnt(15)
	v_fma_f32 v146, v22, v118, v18
	v_fma_f32 v20, v24, v118, v20
	s_waitcnt vmcnt(14)
	v_mov_b32_e32 v136, v26
	s_waitcnt vmcnt(13)
	v_mov_b32_e32 v137, v30
	v_fma_f32 v23, v23, v118, v19
	v_mov_b32_e32 v30, v27
	v_mov_b32_e32 v18, v28
	v_mov_b32_e32 v19, v32
	v_pk_mul_f32 v[26:27], v[136:137], v[72:73]
	s_waitcnt vmcnt(12)
	v_mov_b32_e32 v138, v34
	s_waitcnt vmcnt(11)
	v_mov_b32_e32 v139, v38
	s_waitcnt vmcnt(4)
	v_fmac_f32_e32 v146, v100, v117
	v_fmac_f32_e32 v20, v102, v117
	s_waitcnt vmcnt(3)
	v_fmac_f32_e32 v146, v104, v122
	v_fmac_f32_e32 v20, v106, v122
	s_waitcnt vmcnt(2)
	v_fmac_f32_e32 v146, v124, v121
	v_fmac_f32_e32 v20, v126, v121
	s_waitcnt vmcnt(1)
	v_fmac_f32_e32 v146, v128, v120
	v_fmac_f32_e32 v20, v130, v120
	s_waitcnt vmcnt(0)
	v_fmac_f32_e32 v146, v132, v119
	v_fmac_f32_e32 v23, v101, v117
	v_pk_mul_f32 v[18:19], v[18:19], v[72:73]
	v_fmac_f32_e32 v20, v134, v119
	v_add_f32_e32 v24, v146, v26
	v_mov_b32_e32 v38, v35
	v_pk_mul_f32 v[34:35], v[138:139], v[74:75]
	v_fmac_f32_e32 v23, v105, v122
	v_add_f32_e32 v18, v18, v20
	v_add_f32_e32 v20, v24, v27
	v_mov_b32_e32 v140, v42
	v_mov_b32_e32 v141, v46
	v_fmac_f32_e32 v23, v125, v121
	v_add_f32_e32 v20, v20, v34
	v_mov_b32_e32 v46, v43
	v_pk_mul_f32 v[42:43], v[140:141], v[78:79]
	v_fmac_f32_e32 v23, v129, v120
	v_add_f32_e32 v20, v20, v35
	v_mov_b32_e32 v142, v50
	v_mov_b32_e32 v143, v54
	v_pk_mul_f32 v[30:31], v[30:31], v[72:73]
	v_fmac_f32_e32 v23, v133, v119
	v_add_f32_e32 v20, v20, v42
	v_mov_b32_e32 v54, v51
	v_pk_mul_f32 v[50:51], v[142:143], v[80:81]
	v_add_f32_e32 v23, v30, v23
	v_add_f32_e32 v20, v20, v43
	v_mov_b32_e32 v144, v58
	v_mov_b32_e32 v145, v62
	v_pk_mul_f32 v[38:39], v[38:39], v[74:75]
	v_add_f32_e32 v23, v31, v23
	v_add_f32_e32 v20, v20, v50
	v_mov_b32_e32 v62, v59
	v_pk_mul_f32 v[58:59], v[144:145], v[82:83]
	v_add_f32_e32 v23, v38, v23
	v_add_f32_e32 v20, v20, v51
	v_pk_mul_f32 v[46:47], v[46:47], v[78:79]
	v_add_f32_e32 v23, v39, v23
	v_add_f32_e32 v20, v20, v58
	v_add_f32_e32 v23, v46, v23
	v_add_f32_e32 v20, v20, v59
	v_pk_mul_f32 v[54:55], v[54:55], v[80:81]
	v_add_f32_e32 v23, v47, v23
	v_mul_f32_e64 v24, |v20|, s34
	v_add_f32_e32 v23, v54, v23
	v_exp_f32_e32 v24, v24
	v_pk_mul_f32 v[62:63], v[62:63], v[82:83]
	v_add_f32_e32 v23, v55, v23
	v_add_f32_e32 v23, v62, v23
	v_add_f32_e32 v23, v63, v23
	v_mul_f32_e64 v26, |v23|, s34
	v_add_f32_e32 v27, v19, v18
	v_add_f32_e32 v19, 1.0, v24
	v_exp_f32_e32 v26, v26
	v_cmp_gt_f32_e32 vcc, s35, v19
	v_min_f32_e32 v18, 0, v20
	v_mov_b32_e32 v22, v36
	v_cndmask_b32_e64 v24, 0, 32, vcc
	v_ldexp_f32 v19, v19, v24
	v_log_f32_e32 v24, v19
	v_add_f32_e32 v20, 1.0, v26
	v_cmp_gt_f32_e64 s[0:1], s35, v20
	v_min_f32_e32 v19, 0, v23
	v_cndmask_b32_e32 v23, 0, v111, vcc
	v_cndmask_b32_e64 v26, 0, 32, s[0:1]
	v_ldexp_f32 v20, v20, v26
	v_mul_f32_e32 v26, 0x3f317217, v24
	v_fma_f32 v26, v24, s36, -v26
	v_fmac_f32_e32 v26, 0x3377d1cf, v24
	v_fmac_f32_e32 v26, 0x3f317217, v24
	v_cmp_lt_f32_e64 vcc, |v24|, s37
	v_log_f32_e32 v20, v20
	v_fmac_f32_e32 v21, v25, v118
	v_cndmask_b32_e32 v24, v24, v26, vcc
	v_sub_f32_e32 v26, v24, v23
	v_mov_b32_e32 v23, v40
	v_pk_mul_f32 v[22:23], v[22:23], v[74:75]
	v_mul_f32_e32 v28, 0x3f317217, v20
	v_add_f32_e32 v22, v22, v27
	v_add_f32_e32 v24, v23, v22
	v_mov_b32_e32 v22, v44
	v_mov_b32_e32 v23, v48
	v_pk_mul_f32 v[22:23], v[22:23], v[78:79]
	v_fma_f32 v28, v20, s36, -v28
	v_add_f32_e32 v22, v22, v24
	v_add_f32_e32 v24, v23, v22
	v_mov_b32_e32 v22, v52
	v_mov_b32_e32 v23, v56
	v_pk_mul_f32 v[22:23], v[22:23], v[80:81]
	v_fmac_f32_e32 v28, 0x3377d1cf, v20
	v_add_f32_e32 v22, v22, v24
	v_add_f32_e32 v24, v23, v22
	v_mov_b32_e32 v22, v60
	v_mov_b32_e32 v23, v64
	v_pk_mul_f32 v[22:23], v[22:23], v[82:83]
	v_fmac_f32_e32 v28, 0x3f317217, v20
	v_add_f32_e32 v22, v22, v24
	v_add_f32_e32 v22, v23, v22
	v_mul_f32_e64 v23, |v22|, s34
	v_exp_f32_e32 v23, v23
	v_cmp_lt_f32_e64 vcc, |v20|, s37
	v_cndmask_b32_e64 v24, 0, v111, s[0:1]
	v_fmac_f32_e32 v21, v103, v117
	v_cndmask_b32_e32 v20, v20, v28, vcc
	v_sub_f32_e32 v27, v20, v24
	v_add_f32_e32 v20, 1.0, v23
	v_fmac_f32_e32 v21, v107, v122
	v_cmp_gt_f32_e32 vcc, s35, v20
	v_fmac_f32_e32 v21, v127, v121
	v_pk_add_f32 v[18:19], v[18:19], v[26:27] neg_lo:[0,1] neg_hi:[0,1]
	v_cndmask_b32_e64 v23, 0, 32, vcc
	v_fmac_f32_e32 v21, v131, v120
	v_mov_b32_e32 v32, v29
	v_ldexp_f32 v20, v20, v23
	v_pk_mul_f32 v[100:101], v[18:19], s[6:7] op_sel_hi:[1,0]
	v_min_f32_e32 v18, 0, v22
	v_fmac_f32_e32 v21, v135, v119
	v_pk_mul_f32 v[22:23], v[32:33], v[72:73]
	v_log_f32_e32 v24, v20
	v_add_f32_e32 v20, v22, v21
	v_mov_b32_e32 v40, v37
	v_add_f32_e32 v22, v23, v20
	v_pk_mul_f32 v[20:21], v[40:41], v[74:75]
	v_mov_b32_e32 v48, v45
	v_add_f32_e32 v20, v20, v22
	v_add_f32_e32 v22, v21, v20
	v_pk_mul_f32 v[20:21], v[48:49], v[78:79]
	v_mov_b32_e32 v56, v53
	v_add_f32_e32 v20, v20, v22
	v_add_f32_e32 v22, v21, v20
	v_pk_mul_f32 v[20:21], v[56:57], v[80:81]
	v_mov_b32_e32 v64, v61
	v_add_f32_e32 v20, v20, v22
	v_add_f32_e32 v22, v21, v20
	v_pk_mul_f32 v[20:21], v[64:65], v[82:83]
	v_mul_f32_e32 v19, 0x3f317217, v24
	v_add_f32_e32 v20, v20, v22
	v_add_f32_e32 v21, v21, v20
	v_mul_f32_e64 v20, |v21|, s34
	v_exp_f32_e32 v20, v20
	v_fma_f32 v19, v24, s36, -v19
	v_fmac_f32_e32 v19, 0x3377d1cf, v24
	v_fmac_f32_e32 v19, 0x3f317217, v24
	v_cmp_lt_f32_e64 s[0:1], |v24|, s37
	v_add_f32_e32 v20, 1.0, v20
	s_nop 0
	v_cndmask_b32_e64 v19, v24, v19, s[0:1]
	v_cmp_gt_f32_e64 s[0:1], s35, v20
	s_nop 1
	v_cndmask_b32_e64 v22, 0, 32, s[0:1]
	v_ldexp_f32 v20, v20, v22
	v_log_f32_e32 v22, v20
	v_cndmask_b32_e32 v20, 0, v111, vcc
	v_sub_f32_e32 v20, v19, v20
	v_min_f32_e32 v19, 0, v21
	v_mul_f32_e32 v21, 0x3f317217, v22
	v_fma_f32 v21, v22, s36, -v21
	v_fmac_f32_e32 v21, 0x3377d1cf, v22
	v_fmac_f32_e32 v21, 0x3f317217, v22
	v_cmp_lt_f32_e64 vcc, |v22|, s37
	s_nop 1
	v_cndmask_b32_e32 v21, v22, v21, vcc
	v_cndmask_b32_e64 v22, 0, v111, s[0:1]
	v_sub_f32_e32 v21, v21, v22
	v_pk_add_f32 v[18:19], v[18:19], v[20:21] neg_lo:[0,1] neg_hi:[0,1]
	s_nop 0
	v_pk_mul_f32 v[102:103], v[18:19], s[6:7] op_sel_hi:[1,0]
	global_load_dwordx4 v[18:21], v123, s[48:49] offset:608
	global_load_dwordx4 v[22:25], v123, s[12:13] offset:96
	global_load_dwordx4 v[26:29], v123, s[12:13] offset:3168
	global_load_dwordx4 v[30:33], v123, s[12:13] offset:3680
	global_load_dwordx4 v[34:37], v110, s[16:17] offset:96
	global_load_dwordx4 v[38:41], v110, s[16:17] offset:608
	global_load_dwordx4 v[42:45], v110, s[16:17] offset:1120
	global_load_dwordx4 v[46:49], v110, s[16:17] offset:1632
	global_load_dwordx4 v[50:53], v110, s[16:17] offset:2144
	global_load_dwordx4 v[54:57], v110, s[16:17] offset:2656
	global_load_dwordx4 v[58:61], v110, s[16:17] offset:3168
	global_load_dwordx4 v[62:65], v110, s[16:17] offset:3680
	global_load_dwordx4 v[104:107], v123, s[12:13] offset:608
	global_load_dwordx4 v[124:127], v123, s[12:13] offset:1120
	global_load_dwordx4 v[128:131], v123, s[12:13] offset:1632
	global_load_dwordx4 v[132:135], v123, s[12:13] offset:2144
	global_load_dwordx4 v[136:139], v123, s[12:13] offset:2656
	s_waitcnt vmcnt(15)
	v_fma_f32 v150, v22, v118, v18
	v_fma_f32 v20, v24, v118, v20
	s_waitcnt vmcnt(14)
	v_mov_b32_e32 v140, v26
	s_waitcnt vmcnt(13)
	v_mov_b32_e32 v141, v30
	v_fma_f32 v23, v23, v118, v19
	v_mov_b32_e32 v30, v27
	v_mov_b32_e32 v18, v28
	v_mov_b32_e32 v19, v32
	v_pk_mul_f32 v[26:27], v[140:141], v[72:73]
	s_waitcnt vmcnt(12)
	v_mov_b32_e32 v142, v34
	s_waitcnt vmcnt(11)
	v_mov_b32_e32 v143, v38
	s_waitcnt vmcnt(4)
	v_fmac_f32_e32 v150, v104, v117
	v_fmac_f32_e32 v20, v106, v117
	s_waitcnt vmcnt(3)
	v_fmac_f32_e32 v150, v124, v122
	v_fmac_f32_e32 v20, v126, v122
	s_waitcnt vmcnt(2)
	v_fmac_f32_e32 v150, v128, v121
	v_fmac_f32_e32 v20, v130, v121
	s_waitcnt vmcnt(1)
	v_fmac_f32_e32 v150, v132, v120
	v_fmac_f32_e32 v20, v134, v120
	s_waitcnt vmcnt(0)
	v_fmac_f32_e32 v150, v136, v119
	v_fmac_f32_e32 v23, v105, v117
	v_pk_mul_f32 v[18:19], v[18:19], v[72:73]
	v_fmac_f32_e32 v20, v138, v119
	v_add_f32_e32 v24, v150, v26
	v_mov_b32_e32 v38, v35
	v_pk_mul_f32 v[34:35], v[142:143], v[74:75]
	v_fmac_f32_e32 v23, v125, v122
	v_add_f32_e32 v18, v18, v20
	v_add_f32_e32 v20, v24, v27
	v_mov_b32_e32 v144, v42
	v_mov_b32_e32 v145, v46
	v_fmac_f32_e32 v23, v129, v121
	v_add_f32_e32 v20, v20, v34
	v_mov_b32_e32 v46, v43
	v_pk_mul_f32 v[42:43], v[144:145], v[78:79]
	v_fmac_f32_e32 v23, v133, v120
	v_add_f32_e32 v20, v20, v35
	v_mov_b32_e32 v146, v50
	v_mov_b32_e32 v147, v54
	v_pk_mul_f32 v[30:31], v[30:31], v[72:73]
	v_fmac_f32_e32 v23, v137, v119
	v_add_f32_e32 v20, v20, v42
	v_mov_b32_e32 v54, v51
	v_pk_mul_f32 v[50:51], v[146:147], v[80:81]
	v_add_f32_e32 v23, v30, v23
	v_add_f32_e32 v20, v20, v43
	v_mov_b32_e32 v148, v58
	v_mov_b32_e32 v149, v62
	v_pk_mul_f32 v[38:39], v[38:39], v[74:75]
	v_add_f32_e32 v23, v31, v23
	v_add_f32_e32 v20, v20, v50
	v_mov_b32_e32 v62, v59
	v_pk_mul_f32 v[58:59], v[148:149], v[82:83]
	v_add_f32_e32 v23, v38, v23
	v_add_f32_e32 v20, v20, v51
	v_pk_mul_f32 v[46:47], v[46:47], v[78:79]
	v_add_f32_e32 v23, v39, v23
	v_add_f32_e32 v20, v20, v58
	v_add_f32_e32 v23, v46, v23
	v_add_f32_e32 v20, v20, v59
	v_pk_mul_f32 v[54:55], v[54:55], v[80:81]
	v_add_f32_e32 v23, v47, v23
	v_mul_f32_e64 v24, |v20|, s34
	v_add_f32_e32 v23, v54, v23
	v_exp_f32_e32 v24, v24
	v_pk_mul_f32 v[62:63], v[62:63], v[82:83]
	v_add_f32_e32 v23, v55, v23
	v_add_f32_e32 v23, v62, v23
	v_add_f32_e32 v23, v63, v23
	v_mul_f32_e64 v26, |v23|, s34
	v_add_f32_e32 v27, v19, v18
	v_add_f32_e32 v19, 1.0, v24
	v_exp_f32_e32 v26, v26
	v_cmp_gt_f32_e32 vcc, s35, v19
	v_min_f32_e32 v18, 0, v20
	v_mov_b32_e32 v22, v36
	v_cndmask_b32_e64 v24, 0, 32, vcc
	v_ldexp_f32 v19, v19, v24
	v_log_f32_e32 v24, v19
	v_add_f32_e32 v20, 1.0, v26
	v_cmp_gt_f32_e64 s[0:1], s35, v20
	v_min_f32_e32 v19, 0, v23
	v_cndmask_b32_e32 v23, 0, v111, vcc
	v_cndmask_b32_e64 v26, 0, 32, s[0:1]
	v_ldexp_f32 v20, v20, v26
	v_mul_f32_e32 v26, 0x3f317217, v24
	v_fma_f32 v26, v24, s36, -v26
	v_fmac_f32_e32 v26, 0x3377d1cf, v24
	v_fmac_f32_e32 v26, 0x3f317217, v24
	v_cmp_lt_f32_e64 vcc, |v24|, s37
	v_log_f32_e32 v20, v20
	v_fmac_f32_e32 v21, v25, v118
	v_cndmask_b32_e32 v24, v24, v26, vcc
	v_sub_f32_e32 v26, v24, v23
	v_mov_b32_e32 v23, v40
	v_pk_mul_f32 v[22:23], v[22:23], v[74:75]
	v_mul_f32_e32 v28, 0x3f317217, v20
	v_add_f32_e32 v22, v22, v27
	v_add_f32_e32 v24, v23, v22
	v_mov_b32_e32 v22, v44
	v_mov_b32_e32 v23, v48
	v_pk_mul_f32 v[22:23], v[22:23], v[78:79]
	v_fma_f32 v28, v20, s36, -v28
	v_add_f32_e32 v22, v22, v24
	v_add_f32_e32 v24, v23, v22
	v_mov_b32_e32 v22, v52
	v_mov_b32_e32 v23, v56
	v_pk_mul_f32 v[22:23], v[22:23], v[80:81]
	v_fmac_f32_e32 v28, 0x3377d1cf, v20
	v_add_f32_e32 v22, v22, v24
	v_add_f32_e32 v24, v23, v22
	v_mov_b32_e32 v22, v60
	v_mov_b32_e32 v23, v64
	v_pk_mul_f32 v[22:23], v[22:23], v[82:83]
	v_fmac_f32_e32 v28, 0x3f317217, v20
	v_add_f32_e32 v22, v22, v24
	v_add_f32_e32 v22, v23, v22
	v_mul_f32_e64 v23, |v22|, s34
	v_exp_f32_e32 v23, v23
	v_cmp_lt_f32_e64 vcc, |v20|, s37
	v_cndmask_b32_e64 v24, 0, v111, s[0:1]
	v_fmac_f32_e32 v21, v107, v117
	v_cndmask_b32_e32 v20, v20, v28, vcc
	v_sub_f32_e32 v27, v20, v24
	v_add_f32_e32 v20, 1.0, v23
	v_fmac_f32_e32 v21, v127, v122
	v_cmp_gt_f32_e32 vcc, s35, v20
	v_fmac_f32_e32 v21, v131, v121
	v_pk_add_f32 v[18:19], v[18:19], v[26:27] neg_lo:[0,1] neg_hi:[0,1]
	v_cndmask_b32_e64 v23, 0, 32, vcc
	v_fmac_f32_e32 v21, v135, v120
	v_mov_b32_e32 v32, v29
	v_ldexp_f32 v20, v20, v23
	v_pk_mul_f32 v[104:105], v[18:19], s[6:7] op_sel_hi:[1,0]
	v_min_f32_e32 v18, 0, v22
	v_fmac_f32_e32 v21, v139, v119
	v_pk_mul_f32 v[22:23], v[32:33], v[72:73]
	v_log_f32_e32 v24, v20
	v_add_f32_e32 v20, v22, v21
	v_mov_b32_e32 v40, v37
	v_add_f32_e32 v22, v23, v20
	v_pk_mul_f32 v[20:21], v[40:41], v[74:75]
	v_mov_b32_e32 v48, v45
	v_add_f32_e32 v20, v20, v22
	v_add_f32_e32 v22, v21, v20
	v_pk_mul_f32 v[20:21], v[48:49], v[78:79]
	v_mov_b32_e32 v56, v53
	v_add_f32_e32 v20, v20, v22
	v_add_f32_e32 v22, v21, v20
	v_pk_mul_f32 v[20:21], v[56:57], v[80:81]
	v_mov_b32_e32 v64, v61
	v_add_f32_e32 v20, v20, v22
	v_add_f32_e32 v22, v21, v20
	v_pk_mul_f32 v[20:21], v[64:65], v[82:83]
	v_mul_f32_e32 v19, 0x3f317217, v24
	v_add_f32_e32 v20, v20, v22
	v_add_f32_e32 v21, v21, v20
	v_mul_f32_e64 v20, |v21|, s34
	v_exp_f32_e32 v20, v20
	v_fma_f32 v19, v24, s36, -v19
	v_fmac_f32_e32 v19, 0x3377d1cf, v24
	v_fmac_f32_e32 v19, 0x3f317217, v24
	v_cmp_lt_f32_e64 s[0:1], |v24|, s37
	v_add_f32_e32 v20, 1.0, v20
	s_nop 0
	v_cndmask_b32_e64 v19, v24, v19, s[0:1]
	v_cmp_gt_f32_e64 s[0:1], s35, v20
	s_nop 1
	v_cndmask_b32_e64 v22, 0, 32, s[0:1]
	v_ldexp_f32 v20, v20, v22
	v_log_f32_e32 v22, v20
	v_cndmask_b32_e32 v20, 0, v111, vcc
	v_sub_f32_e32 v20, v19, v20
	v_min_f32_e32 v19, 0, v21
	v_mul_f32_e32 v21, 0x3f317217, v22
	v_fma_f32 v21, v22, s36, -v21
	v_fmac_f32_e32 v21, 0x3377d1cf, v22
	v_fmac_f32_e32 v21, 0x3f317217, v22
	v_cmp_lt_f32_e64 vcc, |v22|, s37
	s_nop 1
	v_cndmask_b32_e32 v21, v22, v21, vcc
	v_cndmask_b32_e64 v22, 0, v111, s[0:1]
	v_sub_f32_e32 v21, v21, v22
	v_pk_add_f32 v[18:19], v[18:19], v[20:21] neg_lo:[0,1] neg_hi:[0,1]
	s_nop 0
	v_pk_mul_f32 v[106:107], v[18:19], s[6:7] op_sel_hi:[1,0]
	global_load_dwordx4 v[18:21], v123, s[48:49] offset:624
	global_load_dwordx4 v[22:25], v123, s[12:13] offset:112
	global_load_dwordx4 v[26:29], v123, s[12:13] offset:3184
	global_load_dwordx4 v[30:33], v123, s[12:13] offset:3696
	global_load_dwordx4 v[34:37], v110, s[16:17] offset:112
	global_load_dwordx4 v[38:41], v110, s[16:17] offset:624
	global_load_dwordx4 v[42:45], v110, s[16:17] offset:1136
	global_load_dwordx4 v[46:49], v110, s[16:17] offset:1648
	global_load_dwordx4 v[50:53], v110, s[16:17] offset:2160
	global_load_dwordx4 v[54:57], v110, s[16:17] offset:2672
	global_load_dwordx4 v[58:61], v110, s[16:17] offset:3184
	global_load_dwordx4 v[62:65], v110, s[16:17] offset:3696
	global_load_dwordx4 v[124:127], v123, s[12:13] offset:624
	global_load_dwordx4 v[128:131], v123, s[12:13] offset:1136
	global_load_dwordx4 v[132:135], v123, s[12:13] offset:1648
	global_load_dwordx4 v[136:139], v123, s[12:13] offset:2160
	global_load_dwordx4 v[140:143], v123, s[12:13] offset:2672
	s_waitcnt vmcnt(15)
	v_fma_f32 v123, v22, v118, v18
	v_fma_f32 v20, v24, v118, v20
	s_waitcnt vmcnt(14)
	v_mov_b32_e32 v144, v26
	s_waitcnt vmcnt(13)
	v_mov_b32_e32 v145, v30
	v_fma_f32 v23, v23, v118, v19
	v_mov_b32_e32 v30, v27
	v_mov_b32_e32 v18, v28
	v_mov_b32_e32 v19, v32
	v_pk_mul_f32 v[26:27], v[144:145], v[72:73]
	s_waitcnt vmcnt(12)
	v_mov_b32_e32 v146, v34
	s_waitcnt vmcnt(11)
	v_mov_b32_e32 v147, v38
	s_waitcnt vmcnt(4)
	v_fmac_f32_e32 v123, v124, v117
	v_fmac_f32_e32 v20, v126, v117
	s_waitcnt vmcnt(3)
	v_fmac_f32_e32 v123, v128, v122
	v_fmac_f32_e32 v20, v130, v122
	s_waitcnt vmcnt(2)
	v_fmac_f32_e32 v123, v132, v121
	v_fmac_f32_e32 v20, v134, v121
	s_waitcnt vmcnt(1)
	v_fmac_f32_e32 v123, v136, v120
	v_fmac_f32_e32 v20, v138, v120
	s_waitcnt vmcnt(0)
	v_fmac_f32_e32 v123, v140, v119
	v_fmac_f32_e32 v23, v125, v117
	v_pk_mul_f32 v[18:19], v[18:19], v[72:73]
	v_fmac_f32_e32 v20, v142, v119
	v_add_f32_e32 v24, v123, v26
	v_mov_b32_e32 v38, v35
	v_pk_mul_f32 v[34:35], v[146:147], v[74:75]
	v_fmac_f32_e32 v23, v129, v122
	v_add_f32_e32 v18, v18, v20
	v_add_f32_e32 v20, v24, v27
	v_mov_b32_e32 v148, v42
	v_mov_b32_e32 v149, v46
	v_fmac_f32_e32 v23, v133, v121
	v_add_f32_e32 v20, v20, v34
	v_mov_b32_e32 v46, v43
	v_pk_mul_f32 v[42:43], v[148:149], v[78:79]
	v_fmac_f32_e32 v23, v137, v120
	v_add_f32_e32 v20, v20, v35
	v_mov_b32_e32 v150, v50
	v_mov_b32_e32 v151, v54
	v_pk_mul_f32 v[30:31], v[30:31], v[72:73]
	v_fmac_f32_e32 v23, v141, v119
	v_add_f32_e32 v20, v20, v42
	v_mov_b32_e32 v54, v51
	v_pk_mul_f32 v[50:51], v[150:151], v[80:81]
	v_add_f32_e32 v23, v30, v23
	v_add_f32_e32 v20, v20, v43
	v_mov_b32_e32 v152, v58
	v_mov_b32_e32 v153, v62
	v_pk_mul_f32 v[38:39], v[38:39], v[74:75]
	v_add_f32_e32 v23, v31, v23
	v_add_f32_e32 v20, v20, v50
	v_mov_b32_e32 v62, v59
	v_pk_mul_f32 v[58:59], v[152:153], v[82:83]
	v_add_f32_e32 v23, v38, v23
	v_add_f32_e32 v20, v20, v51
	v_pk_mul_f32 v[46:47], v[46:47], v[78:79]
	v_add_f32_e32 v23, v39, v23
	v_add_f32_e32 v20, v20, v58
	v_add_f32_e32 v23, v46, v23
	v_add_f32_e32 v20, v20, v59
	v_pk_mul_f32 v[54:55], v[54:55], v[80:81]
	v_add_f32_e32 v23, v47, v23
	v_mul_f32_e64 v24, |v20|, s34
	v_add_f32_e32 v23, v54, v23
	v_exp_f32_e32 v24, v24
	v_pk_mul_f32 v[62:63], v[62:63], v[82:83]
	v_add_f32_e32 v23, v55, v23
	v_add_f32_e32 v23, v62, v23
	v_add_f32_e32 v23, v63, v23
	v_mul_f32_e64 v26, |v23|, s34
	v_add_f32_e32 v27, v19, v18
	v_add_f32_e32 v19, 1.0, v24
	v_exp_f32_e32 v26, v26
	v_cmp_gt_f32_e32 vcc, s35, v19
	v_min_f32_e32 v18, 0, v20
	v_mov_b32_e32 v22, v36
	v_cndmask_b32_e64 v24, 0, 32, vcc
	v_ldexp_f32 v19, v19, v24
	v_log_f32_e32 v24, v19
	v_add_f32_e32 v20, 1.0, v26
	v_cmp_gt_f32_e64 s[0:1], s35, v20
	v_min_f32_e32 v19, 0, v23
	v_cndmask_b32_e32 v23, 0, v111, vcc
	v_cndmask_b32_e64 v26, 0, 32, s[0:1]
	v_ldexp_f32 v20, v20, v26
	v_mul_f32_e32 v26, 0x3f317217, v24
	v_fma_f32 v26, v24, s36, -v26
	v_fmac_f32_e32 v26, 0x3377d1cf, v24
	v_fmac_f32_e32 v26, 0x3f317217, v24
	v_cmp_lt_f32_e64 vcc, |v24|, s37
	v_log_f32_e32 v20, v20
	v_fmac_f32_e32 v21, v25, v118
	v_cndmask_b32_e32 v24, v24, v26, vcc
	v_sub_f32_e32 v26, v24, v23
	v_mov_b32_e32 v23, v40
	v_pk_mul_f32 v[22:23], v[22:23], v[74:75]
	v_mul_f32_e32 v28, 0x3f317217, v20
	v_add_f32_e32 v22, v22, v27
	v_add_f32_e32 v24, v23, v22
	v_mov_b32_e32 v22, v44
	v_mov_b32_e32 v23, v48
	v_pk_mul_f32 v[22:23], v[22:23], v[78:79]
	v_fma_f32 v28, v20, s36, -v28
	v_add_f32_e32 v22, v22, v24
	v_add_f32_e32 v24, v23, v22
	v_mov_b32_e32 v22, v52
	v_mov_b32_e32 v23, v56
	v_pk_mul_f32 v[22:23], v[22:23], v[80:81]
	v_fmac_f32_e32 v28, 0x3377d1cf, v20
	v_add_f32_e32 v22, v22, v24
	v_add_f32_e32 v24, v23, v22
	v_mov_b32_e32 v22, v60
	v_mov_b32_e32 v23, v64
	v_pk_mul_f32 v[22:23], v[22:23], v[82:83]
	v_fmac_f32_e32 v28, 0x3f317217, v20
	v_add_f32_e32 v22, v22, v24
	v_add_f32_e32 v24, v23, v22
	v_mul_f32_e64 v22, |v24|, s34
	v_exp_f32_e32 v22, v22
	v_cmp_lt_f32_e64 vcc, |v20|, s37
	v_cndmask_b32_e64 v23, 0, v111, s[0:1]
	v_fmac_f32_e32 v21, v127, v117
	v_cndmask_b32_e32 v20, v20, v28, vcc
	v_sub_f32_e32 v27, v20, v23
	v_add_f32_e32 v20, 1.0, v22
	v_fmac_f32_e32 v21, v131, v122
	v_cmp_gt_f32_e32 vcc, s35, v20
	v_fmac_f32_e32 v21, v135, v121
	v_pk_add_f32 v[18:19], v[18:19], v[26:27] neg_lo:[0,1] neg_hi:[0,1]
	v_cndmask_b32_e64 v22, 0, 32, vcc
	v_fmac_f32_e32 v21, v139, v120
	v_mov_b32_e32 v32, v29
	v_ldexp_f32 v20, v20, v22
	v_pk_mul_f32 v[22:23], v[18:19], s[6:7] op_sel_hi:[1,0]
	v_min_f32_e32 v18, 0, v24
	v_fmac_f32_e32 v21, v143, v119
	v_pk_mul_f32 v[24:25], v[32:33], v[72:73]
	v_log_f32_e32 v28, v20
	v_add_f32_e32 v20, v24, v21
	v_mov_b32_e32 v40, v37
	v_add_f32_e32 v24, v25, v20
	v_pk_mul_f32 v[20:21], v[40:41], v[74:75]
	v_mov_b32_e32 v48, v45
	v_add_f32_e32 v20, v20, v24
	v_add_f32_e32 v24, v21, v20
	v_pk_mul_f32 v[20:21], v[48:49], v[78:79]
	v_mov_b32_e32 v56, v53
	v_add_f32_e32 v20, v20, v24
	v_add_f32_e32 v24, v21, v20
	v_pk_mul_f32 v[20:21], v[56:57], v[80:81]
	v_mov_b32_e32 v64, v61
	v_add_f32_e32 v20, v20, v24
	v_add_f32_e32 v24, v21, v20
	v_pk_mul_f32 v[20:21], v[64:65], v[82:83]
	v_mul_f32_e32 v19, 0x3f317217, v28
	v_add_f32_e32 v20, v20, v24
	v_add_f32_e32 v21, v21, v20
	v_mul_f32_e64 v20, |v21|, s34
	v_exp_f32_e32 v20, v20
	v_fma_f32 v19, v28, s36, -v19
	v_fmac_f32_e32 v19, 0x3377d1cf, v28
	v_fmac_f32_e32 v19, 0x3f317217, v28
	v_cmp_lt_f32_e64 s[0:1], |v28|, s37
	v_add_f32_e32 v20, 1.0, v20
	s_nop 0
	v_cndmask_b32_e64 v19, v28, v19, s[0:1]
	v_cmp_gt_f32_e64 s[0:1], s35, v20
	s_nop 1
	v_cndmask_b32_e64 v24, 0, 32, s[0:1]
	v_ldexp_f32 v20, v20, v24
	v_log_f32_e32 v24, v20
	v_cndmask_b32_e32 v20, 0, v111, vcc
	v_sub_f32_e32 v20, v19, v20
	v_min_f32_e32 v19, 0, v21
	v_mul_f32_e32 v21, 0x3f317217, v24
	v_fma_f32 v21, v24, s36, -v21
	v_fmac_f32_e32 v21, 0x3377d1cf, v24
	v_fmac_f32_e32 v21, 0x3f317217, v24
	v_cmp_lt_f32_e64 vcc, |v24|, s37
	s_nop 1
	v_cndmask_b32_e32 v21, v24, v21, vcc
	v_cndmask_b32_e64 v24, 0, v111, s[0:1]
	v_sub_f32_e32 v21, v21, v24
	v_pk_add_f32 v[18:19], v[18:19], v[20:21] neg_lo:[0,1] neg_hi:[0,1]
	s_nop 0
	v_pk_mul_f32 v[20:21], v[18:19], s[6:7] op_sel_hi:[1,0]
	v_and_b32_e32 v18, 64, v112
	v_add_u32_e32 v19, -1, v112
	v_cmp_lt_i32_e32 vcc, v19, v18
	s_nop 1
	v_cndmask_b32_e32 v19, v19, v112, vcc
	v_lshlrev_b32_e32 v19, 2, v19
	ds_bpermute_b32 v24, v19, v70
	ds_bpermute_b32 v25, v19, v71
	ds_bpermute_b32 v26, v19, v76
	ds_bpermute_b32 v27, v19, v77
	ds_bpermute_b32 v28, v19, v84
	ds_bpermute_b32 v29, v19, v85
	ds_bpermute_b32 v30, v19, v86
	ds_bpermute_b32 v31, v19, v87
	ds_bpermute_b32 v32, v19, v88
	ds_bpermute_b32 v33, v19, v89
	ds_bpermute_b32 v34, v19, v90
	ds_bpermute_b32 v35, v19, v91
	ds_bpermute_b32 v36, v19, v92
	ds_bpermute_b32 v37, v19, v93
	ds_bpermute_b32 v38, v19, v94
	ds_bpermute_b32 v39, v19, v95
	ds_bpermute_b32 v40, v19, v96
	ds_bpermute_b32 v41, v19, v97
	ds_bpermute_b32 v42, v19, v98
	ds_bpermute_b32 v43, v19, v99
	ds_bpermute_b32 v44, v19, v100
	ds_bpermute_b32 v45, v19, v101
	ds_bpermute_b32 v46, v19, v102
	ds_bpermute_b32 v47, v19, v103
	ds_bpermute_b32 v48, v19, v104
	ds_bpermute_b32 v49, v19, v105
	ds_bpermute_b32 v50, v19, v106
	ds_bpermute_b32 v51, v19, v107
	ds_bpermute_b32 v52, v19, v22
	ds_bpermute_b32 v53, v19, v23
	ds_bpermute_b32 v54, v19, v20
	ds_bpermute_b32 v19, v19, v21
	v_cmp_gt_i32_e32 vcc, 1, v68
	s_waitcnt lgkmcnt(6)
	v_add_f32_e32 v49, v105, v49
	s_waitcnt lgkmcnt(3)
	v_add_f32_e32 v52, v22, v52
	v_add_f32_e32 v24, v70, v24
	s_waitcnt lgkmcnt(0)
	v_add_f32_e32 v19, v21, v19
	v_cndmask_b32_e32 v19, v19, v21, vcc
	v_cndmask_b32_e32 v21, v52, v22, vcc
	v_cndmask_b32_e32 v22, v49, v105, vcc
	v_add_u32_e32 v49, -2, v112
	v_cmp_lt_i32_e64 s[0:1], v49, v18
	v_add_f32_e32 v25, v71, v25
	v_add_f32_e32 v26, v76, v26
	v_add_f32_e32 v27, v77, v27
	v_add_f32_e32 v28, v84, v28
	v_add_f32_e32 v29, v85, v29
	v_add_f32_e32 v30, v86, v30
	v_add_f32_e32 v31, v87, v31
	v_add_f32_e32 v32, v88, v32
	v_add_f32_e32 v33, v89, v33
	v_add_f32_e32 v34, v90, v34
	v_add_f32_e32 v35, v91, v35
	v_add_f32_e32 v36, v92, v36
	v_add_f32_e32 v37, v93, v37
	v_add_f32_e32 v38, v94, v38
	v_add_f32_e32 v39, v95, v39
	v_add_f32_e32 v40, v96, v40
	v_add_f32_e32 v41, v97, v41
	v_add_f32_e32 v42, v98, v42
	v_add_f32_e32 v43, v99, v43
	v_add_f32_e32 v44, v100, v44
	v_add_f32_e32 v45, v101, v45
	v_add_f32_e32 v46, v102, v46
	v_add_f32_e32 v47, v103, v47
	v_add_f32_e32 v48, v104, v48
	v_add_f32_e32 v50, v106, v50
	v_add_f32_e32 v51, v107, v51
	v_add_f32_e32 v53, v23, v53
	v_add_f32_e32 v54, v20, v54
	v_cndmask_b32_e64 v49, v49, v112, s[0:1]
	v_cndmask_b32_e32 v24, v24, v70, vcc
	v_cndmask_b32_e32 v26, v26, v76, vcc
	v_cndmask_b32_e32 v27, v27, v77, vcc
	v_cndmask_b32_e32 v29, v29, v85, vcc
	v_cndmask_b32_e32 v30, v30, v86, vcc
	v_cndmask_b32_e32 v32, v32, v88, vcc
	v_cndmask_b32_e32 v33, v33, v89, vcc
	v_cndmask_b32_e32 v35, v35, v91, vcc
	v_cndmask_b32_e32 v36, v36, v92, vcc
	v_cndmask_b32_e32 v38, v38, v94, vcc
	v_cndmask_b32_e32 v39, v39, v95, vcc
	v_cndmask_b32_e32 v41, v41, v97, vcc
	v_cndmask_b32_e32 v42, v42, v98, vcc
	v_cndmask_b32_e32 v44, v44, v100, vcc
	v_cndmask_b32_e32 v45, v45, v101, vcc
	v_cndmask_b32_e32 v47, v47, v103, vcc
	v_cndmask_b32_e32 v48, v48, v104, vcc
	v_cndmask_b32_e32 v50, v50, v106, vcc
	v_cndmask_b32_e32 v51, v51, v107, vcc
	v_cndmask_b32_e32 v53, v53, v23, vcc
	v_cndmask_b32_e32 v54, v54, v20, vcc
	v_cndmask_b32_e32 v46, v46, v102, vcc
	v_cndmask_b32_e32 v43, v43, v99, vcc
	v_cndmask_b32_e32 v40, v40, v96, vcc
	v_cndmask_b32_e32 v37, v37, v93, vcc
	v_cndmask_b32_e32 v34, v34, v90, vcc
	v_lshlrev_b32_e32 v49, 2, v49
	v_cndmask_b32_e32 v31, v31, v87, vcc
	v_cndmask_b32_e32 v28, v28, v84, vcc
	v_cndmask_b32_e32 v25, v25, v71, vcc
	v_cndmask_b32_e32 v55, v24, v70, vcc
	v_cndmask_b32_e32 v56, v26, v76, vcc
	v_cndmask_b32_e32 v57, v27, v77, vcc
	v_cndmask_b32_e32 v58, v29, v85, vcc
	v_cndmask_b32_e32 v59, v30, v86, vcc
	v_cndmask_b32_e32 v60, v32, v88, vcc
	v_cndmask_b32_e32 v61, v33, v89, vcc
	v_cndmask_b32_e32 v62, v35, v91, vcc
	v_cndmask_b32_e32 v63, v36, v92, vcc
	v_cndmask_b32_e32 v64, v38, v94, vcc
	v_cndmask_b32_e32 v65, v39, v95, vcc
	v_cndmask_b32_e32 v70, v41, v97, vcc
	v_cndmask_b32_e32 v72, v42, v98, vcc
	v_cndmask_b32_e32 v73, v44, v100, vcc
	v_cndmask_b32_e32 v74, v45, v101, vcc
	v_cndmask_b32_e32 v75, v47, v103, vcc
	v_cndmask_b32_e32 v76, v48, v104, vcc
	v_cndmask_b32_e32 v77, v50, v106, vcc
	v_cndmask_b32_e32 v78, v51, v107, vcc
	ds_bpermute_b32 v52, v49, v24
	ds_bpermute_b32 v71, v49, v25
	ds_bpermute_b32 v79, v49, v26
	ds_bpermute_b32 v80, v49, v27
	ds_bpermute_b32 v81, v49, v28
	ds_bpermute_b32 v82, v49, v29
	ds_bpermute_b32 v83, v49, v30
	ds_bpermute_b32 v84, v49, v31
	ds_bpermute_b32 v85, v49, v32
	ds_bpermute_b32 v86, v49, v33
	ds_bpermute_b32 v87, v49, v34
	ds_bpermute_b32 v88, v49, v35
	ds_bpermute_b32 v89, v49, v36
	ds_bpermute_b32 v90, v49, v37
	ds_bpermute_b32 v91, v49, v38
	ds_bpermute_b32 v92, v49, v39
	ds_bpermute_b32 v93, v49, v40
	ds_bpermute_b32 v94, v49, v41
	ds_bpermute_b32 v95, v49, v42
	ds_bpermute_b32 v96, v49, v43
	ds_bpermute_b32 v97, v49, v44
	ds_bpermute_b32 v98, v49, v45
	ds_bpermute_b32 v99, v49, v46
	ds_bpermute_b32 v100, v49, v47
	ds_bpermute_b32 v101, v49, v48
	ds_bpermute_b32 v102, v49, v22
	ds_bpermute_b32 v103, v49, v50
	ds_bpermute_b32 v104, v49, v51
	ds_bpermute_b32 v105, v49, v21
	ds_bpermute_b32 v106, v49, v53
	ds_bpermute_b32 v107, v49, v54
	ds_bpermute_b32 v49, v49, v19
	v_cndmask_b32_e32 v23, v53, v23, vcc
	v_cndmask_b32_e32 v20, v54, v20, vcc
	v_cmp_gt_i32_e32 vcc, 2, v68
	s_waitcnt lgkmcnt(14)
	v_add_f32_e32 v52, v24, v52
	s_waitcnt lgkmcnt(0)
	v_add_f32_e32 v49, v19, v49
	v_cndmask_b32_e32 v19, v49, v19, vcc
	v_add_u32_e32 v49, -4, v112
	v_cmp_lt_i32_e64 s[0:1], v49, v18
	v_add_f32_e32 v71, v25, v71
	v_add_f32_e32 v79, v26, v79
	v_add_f32_e32 v80, v27, v80
	v_add_f32_e32 v81, v28, v81
	v_add_f32_e32 v82, v29, v82
	v_add_f32_e32 v83, v30, v83
	v_add_f32_e32 v84, v31, v84
	v_add_f32_e32 v85, v32, v85
	v_add_f32_e32 v86, v33, v86
	v_add_f32_e32 v87, v34, v87
	v_add_f32_e32 v88, v35, v88
	v_add_f32_e32 v89, v36, v89
	v_add_f32_e32 v90, v37, v90
	v_add_f32_e32 v91, v38, v91
	v_add_f32_e32 v92, v39, v92
	v_add_f32_e32 v93, v40, v93
	v_add_f32_e32 v94, v41, v94
	v_add_f32_e32 v95, v42, v95
	v_add_f32_e32 v96, v43, v96
	v_add_f32_e32 v97, v44, v97
	v_add_f32_e32 v98, v45, v98
	v_add_f32_e32 v99, v46, v99
	v_add_f32_e32 v100, v47, v100
	v_add_f32_e32 v101, v48, v101
	v_add_f32_e32 v102, v22, v102
	v_add_f32_e32 v103, v50, v103
	v_add_f32_e32 v104, v51, v104
	v_add_f32_e32 v105, v21, v105
	v_add_f32_e32 v106, v53, v106
	v_add_f32_e32 v107, v54, v107
	v_cndmask_b32_e64 v49, v49, v112, s[0:1]
	v_cndmask_b32_e32 v24, v52, v24, vcc
	v_cndmask_b32_e32 v26, v79, v26, vcc
	v_cndmask_b32_e32 v27, v80, v27, vcc
	v_cndmask_b32_e32 v29, v82, v29, vcc
	v_cndmask_b32_e32 v30, v83, v30, vcc
	v_cndmask_b32_e32 v32, v85, v32, vcc
	v_cndmask_b32_e32 v33, v86, v33, vcc
	v_cndmask_b32_e32 v35, v88, v35, vcc
	v_cndmask_b32_e32 v36, v89, v36, vcc
	v_cndmask_b32_e32 v38, v91, v38, vcc
	v_cndmask_b32_e32 v39, v92, v39, vcc
	v_cndmask_b32_e32 v41, v94, v41, vcc
	v_cndmask_b32_e32 v42, v95, v42, vcc
	v_cndmask_b32_e32 v44, v97, v44, vcc
	v_cndmask_b32_e32 v45, v98, v45, vcc
	v_cndmask_b32_e32 v47, v100, v47, vcc
	v_cndmask_b32_e32 v48, v101, v48, vcc
	v_cndmask_b32_e32 v50, v103, v50, vcc
	v_cndmask_b32_e32 v51, v104, v51, vcc
	v_cndmask_b32_e32 v53, v106, v53, vcc
	v_cndmask_b32_e32 v54, v107, v54, vcc
	v_cndmask_b32_e32 v21, v105, v21, vcc
	v_cndmask_b32_e32 v22, v102, v22, vcc
	v_cndmask_b32_e32 v46, v99, v46, vcc
	v_cndmask_b32_e32 v43, v96, v43, vcc
	v_cndmask_b32_e32 v40, v93, v40, vcc
	v_cndmask_b32_e32 v37, v90, v37, vcc
	v_cndmask_b32_e32 v34, v87, v34, vcc
	v_lshlrev_b32_e32 v49, 2, v49
	v_cndmask_b32_e32 v31, v84, v31, vcc
	v_cndmask_b32_e32 v28, v81, v28, vcc
	v_cndmask_b32_e32 v25, v71, v25, vcc
	v_cndmask_b32_e32 v20, v107, v20, vcc
	v_cndmask_b32_e32 v23, v106, v23, vcc
	v_cndmask_b32_e32 v78, v104, v78, vcc
	v_cndmask_b32_e32 v77, v103, v77, vcc
	v_cndmask_b32_e32 v76, v101, v76, vcc
	v_cndmask_b32_e32 v75, v100, v75, vcc
	v_cndmask_b32_e32 v74, v98, v74, vcc
	v_cndmask_b32_e32 v73, v97, v73, vcc
	v_cndmask_b32_e32 v72, v95, v72, vcc
	v_cndmask_b32_e32 v70, v94, v70, vcc
	v_cndmask_b32_e32 v65, v92, v65, vcc
	v_cndmask_b32_e32 v64, v91, v64, vcc
	v_cndmask_b32_e32 v63, v89, v63, vcc
	v_cndmask_b32_e32 v62, v88, v62, vcc
	v_cndmask_b32_e32 v61, v86, v61, vcc
	v_cndmask_b32_e32 v60, v85, v60, vcc
	v_cndmask_b32_e32 v59, v83, v59, vcc
	v_cndmask_b32_e32 v58, v82, v58, vcc
	v_cndmask_b32_e32 v57, v80, v57, vcc
	v_cndmask_b32_e32 v56, v79, v56, vcc
	v_cndmask_b32_e32 v52, v52, v55, vcc
	ds_bpermute_b32 v55, v49, v24
	ds_bpermute_b32 v71, v49, v25
	ds_bpermute_b32 v79, v49, v26
	ds_bpermute_b32 v80, v49, v27
	ds_bpermute_b32 v81, v49, v28
	ds_bpermute_b32 v82, v49, v29
	ds_bpermute_b32 v83, v49, v30
	ds_bpermute_b32 v84, v49, v31
	ds_bpermute_b32 v85, v49, v32
	ds_bpermute_b32 v86, v49, v33
	ds_bpermute_b32 v87, v49, v34
	ds_bpermute_b32 v88, v49, v35
	ds_bpermute_b32 v89, v49, v36
	ds_bpermute_b32 v90, v49, v37
	ds_bpermute_b32 v91, v49, v38
	ds_bpermute_b32 v92, v49, v39
	ds_bpermute_b32 v93, v49, v40
	ds_bpermute_b32 v94, v49, v41
	ds_bpermute_b32 v95, v49, v42
	ds_bpermute_b32 v96, v49, v43
	ds_bpermute_b32 v97, v49, v44
	ds_bpermute_b32 v98, v49, v45
	ds_bpermute_b32 v99, v49, v46
	ds_bpermute_b32 v100, v49, v47
	ds_bpermute_b32 v101, v49, v48
	ds_bpermute_b32 v102, v49, v22
	ds_bpermute_b32 v103, v49, v50
	ds_bpermute_b32 v104, v49, v51
	ds_bpermute_b32 v105, v49, v21
	ds_bpermute_b32 v106, v49, v53
	ds_bpermute_b32 v107, v49, v54
	ds_bpermute_b32 v49, v49, v19
	v_cmp_gt_i32_e32 vcc, 4, v68
	s_waitcnt lgkmcnt(14)
	v_add_f32_e32 v55, v24, v55
	v_add_f32_e32 v71, v25, v71
	v_cndmask_b32_e32 v24, v55, v24, vcc
	s_waitcnt lgkmcnt(0)
	v_add_f32_e32 v49, v19, v49
	v_cndmask_b32_e32 v19, v49, v19, vcc
	v_add_u32_e32 v49, -8, v112
	v_cmp_lt_i32_e64 s[0:1], v49, v18
	v_add_f32_e32 v79, v26, v79
	v_add_f32_e32 v80, v27, v80
	v_cndmask_b32_e64 v49, v49, v112, s[0:1]
	v_add_f32_e32 v82, v29, v82
	v_add_f32_e32 v83, v30, v83
	v_add_f32_e32 v85, v32, v85
	v_add_f32_e32 v86, v33, v86
	v_add_f32_e32 v88, v35, v88
	v_add_f32_e32 v89, v36, v89
	v_add_f32_e32 v91, v38, v91
	v_add_f32_e32 v92, v39, v92
	v_add_f32_e32 v94, v41, v94
	v_add_f32_e32 v95, v42, v95
	v_add_f32_e32 v97, v44, v97
	v_add_f32_e32 v98, v45, v98
	v_add_f32_e32 v100, v47, v100
	v_add_f32_e32 v101, v48, v101
	v_add_f32_e32 v103, v50, v103
	v_add_f32_e32 v104, v51, v104
	v_cndmask_b32_e32 v25, v71, v25, vcc
	v_lshlrev_b32_e32 v49, 2, v49
	v_cndmask_b32_e32 v52, v55, v52, vcc
	v_cndmask_b32_e32 v55, v79, v56, vcc
	v_cndmask_b32_e32 v56, v80, v57, vcc
	v_cndmask_b32_e32 v57, v82, v58, vcc
	v_cndmask_b32_e32 v58, v83, v59, vcc
	v_cndmask_b32_e32 v59, v85, v60, vcc
	v_cndmask_b32_e32 v60, v86, v61, vcc
	v_cndmask_b32_e32 v61, v88, v62, vcc
	v_cndmask_b32_e32 v62, v89, v63, vcc
	v_cndmask_b32_e32 v63, v91, v64, vcc
	v_cndmask_b32_e32 v64, v92, v65, vcc
	v_cndmask_b32_e32 v65, v94, v70, vcc
	v_cndmask_b32_e32 v70, v95, v72, vcc
	v_cndmask_b32_e32 v72, v97, v73, vcc
	v_cndmask_b32_e32 v73, v98, v74, vcc
	v_cndmask_b32_e32 v74, v100, v75, vcc
	v_cndmask_b32_e32 v75, v101, v76, vcc
	v_cndmask_b32_e32 v76, v103, v77, vcc
	v_cndmask_b32_e32 v77, v104, v78, vcc
	ds_bpermute_b32 v71, v49, v24
	ds_bpermute_b32 v78, v49, v25
	v_add_f32_e32 v81, v28, v81
	v_cndmask_b32_e32 v26, v79, v26, vcc
	v_cndmask_b32_e32 v29, v82, v29, vcc
	v_cndmask_b32_e32 v30, v83, v30, vcc
	v_cndmask_b32_e32 v28, v81, v28, vcc
	v_cndmask_b32_e32 v27, v80, v27, vcc
	s_waitcnt lgkmcnt(1)
	v_add_f32_e32 v24, v24, v71
	s_waitcnt lgkmcnt(0)
	v_add_f32_e32 v71, v25, v78
	ds_bpermute_b32 v78, v49, v26
	ds_bpermute_b32 v80, v49, v28
	ds_bpermute_b32 v81, v49, v29
	ds_bpermute_b32 v82, v49, v30
	v_add_f32_e32 v87, v34, v87
	v_cndmask_b32_e32 v32, v85, v32, vcc
	v_cndmask_b32_e32 v33, v86, v33, vcc
	v_cndmask_b32_e32 v35, v88, v35, vcc
	v_cndmask_b32_e32 v34, v87, v34, vcc
	s_waitcnt lgkmcnt(3)
	v_add_f32_e32 v26, v26, v78
	s_waitcnt lgkmcnt(2)
	v_add_f32_e32 v78, v28, v80
	s_waitcnt lgkmcnt(1)
	v_add_f32_e32 v29, v29, v81
	s_waitcnt lgkmcnt(0)
	v_add_f32_e32 v30, v30, v82
	ds_bpermute_b32 v80, v49, v32
	ds_bpermute_b32 v81, v49, v33
	ds_bpermute_b32 v82, v49, v34
	ds_bpermute_b32 v83, v49, v35
	v_add_f32_e32 v90, v37, v90
	v_add_f32_e32 v93, v40, v93
	v_cndmask_b32_e32 v36, v89, v36, vcc
	v_cndmask_b32_e32 v38, v91, v38, vcc
	v_cndmask_b32_e32 v40, v93, v40, vcc
	v_cndmask_b32_e32 v37, v90, v37, vcc
	s_waitcnt lgkmcnt(3)
	v_add_f32_e32 v32, v32, v80
	s_waitcnt lgkmcnt(2)
	v_add_f32_e32 v33, v33, v81
	s_waitcnt lgkmcnt(1)
	v_add_f32_e32 v80, v34, v82
	s_waitcnt lgkmcnt(0)
	v_add_f32_e32 v35, v35, v83
	ds_bpermute_b32 v81, v49, v36
	ds_bpermute_b32 v82, v49, v37
	ds_bpermute_b32 v83, v49, v38
	ds_bpermute_b32 v85, v49, v40
	v_add_f32_e32 v96, v43, v96
	v_add_f32_e32 v84, v31, v84
	v_cndmask_b32_e32 v39, v92, v39, vcc
	v_cndmask_b32_e32 v41, v94, v41, vcc
	v_cndmask_b32_e32 v44, v97, v44, vcc
	v_cndmask_b32_e32 v45, v98, v45, vcc
	v_cndmask_b32_e32 v43, v96, v43, vcc
	v_cndmask_b32_e32 v31, v84, v31, vcc
	ds_bpermute_b32 v84, v49, v39
	s_waitcnt lgkmcnt(4)
	v_add_f32_e32 v36, v36, v81
	s_waitcnt lgkmcnt(3)
	v_add_f32_e32 v81, v37, v82
	s_waitcnt lgkmcnt(2)
	v_add_f32_e32 v38, v38, v83
	s_waitcnt lgkmcnt(1)
	v_add_f32_e32 v82, v40, v85
	ds_bpermute_b32 v83, v49, v41
	ds_bpermute_b32 v85, v49, v43
	ds_bpermute_b32 v86, v49, v44
	ds_bpermute_b32 v87, v49, v45
	v_add_f32_e32 v102, v22, v102
	v_cndmask_b32_e32 v42, v95, v42, vcc
	v_cndmask_b32_e32 v47, v100, v47, vcc
	v_cndmask_b32_e32 v48, v101, v48, vcc
	v_cndmask_b32_e32 v50, v103, v50, vcc
	v_cndmask_b32_e32 v22, v102, v22, vcc
	ds_bpermute_b32 v79, v49, v27
	s_waitcnt lgkmcnt(5)
	v_add_f32_e32 v39, v39, v84
	ds_bpermute_b32 v84, v49, v42
	s_waitcnt lgkmcnt(5)
	v_add_f32_e32 v41, v41, v83
	s_waitcnt lgkmcnt(4)
	v_add_f32_e32 v83, v43, v85
	s_waitcnt lgkmcnt(3)
	v_add_f32_e32 v44, v44, v86
	s_waitcnt lgkmcnt(2)
	v_add_f32_e32 v45, v45, v87
	ds_bpermute_b32 v85, v49, v47
	ds_bpermute_b32 v86, v49, v48
	ds_bpermute_b32 v87, v49, v22
	ds_bpermute_b32 v88, v49, v50
	v_add_f32_e32 v99, v46, v99
	v_add_f32_e32 v105, v21, v105
	v_add_f32_e32 v106, v53, v106
	v_add_f32_e32 v107, v54, v107
	v_cndmask_b32_e32 v51, v104, v51, vcc
	v_cndmask_b32_e32 v53, v106, v53, vcc
	v_cndmask_b32_e32 v54, v107, v54, vcc
	v_cndmask_b32_e32 v21, v105, v21, vcc
	v_cndmask_b32_e32 v46, v99, v46, vcc
	s_waitcnt lgkmcnt(5)
	v_add_f32_e32 v27, v27, v79
	ds_bpermute_b32 v79, v49, v31
	s_waitcnt lgkmcnt(5)
	v_add_f32_e32 v42, v42, v84
	ds_bpermute_b32 v84, v49, v46
	s_waitcnt lgkmcnt(5)
	v_add_f32_e32 v47, v47, v85
	s_waitcnt lgkmcnt(4)
	v_add_f32_e32 v48, v48, v86
	s_waitcnt lgkmcnt(3)
	v_add_f32_e32 v85, v22, v87
	s_waitcnt lgkmcnt(2)
	v_add_f32_e32 v50, v50, v88
	ds_bpermute_b32 v86, v49, v51
	ds_bpermute_b32 v87, v49, v21
	ds_bpermute_b32 v88, v49, v53
	ds_bpermute_b32 v89, v49, v54
	ds_bpermute_b32 v49, v49, v19
	v_cndmask_b32_e32 v23, v106, v23, vcc
	v_cndmask_b32_e32 v20, v107, v20, vcc
	s_waitcnt lgkmcnt(4)
	v_add_f32_e32 v51, v51, v86
	v_cmp_gt_i32_e32 vcc, 8, v68
	s_waitcnt lgkmcnt(0)
	v_add_f32_e32 v49, v19, v49
	v_add_f32_e32 v79, v31, v79
	v_cndmask_b32_e32 v19, v49, v19, vcc
	v_cndmask_b32_e32 v49, v51, v77, vcc
	v_add_u32_e32 v51, -16, v112
	v_cmp_lt_i32_e64 s[0:1], v51, v18
	v_add_f32_e32 v84, v46, v84
	v_add_f32_e32 v86, v21, v87
	v_cndmask_b32_e64 v51, v51, v112, s[0:1]
	v_add_f32_e32 v53, v53, v88
	v_add_f32_e32 v54, v54, v89
	v_cndmask_b32_e32 v41, v41, v65, vcc
	v_cndmask_b32_e32 v33, v33, v60, vcc
	v_lshlrev_b32_e32 v51, 2, v51
	v_cndmask_b32_e32 v20, v54, v20, vcc
	v_cndmask_b32_e32 v23, v53, v23, vcc
	v_cndmask_b32_e32 v21, v86, v21, vcc
	v_cndmask_b32_e32 v50, v50, v76, vcc
	v_cndmask_b32_e32 v22, v85, v22, vcc
	v_cndmask_b32_e32 v48, v48, v75, vcc
	v_cndmask_b32_e32 v47, v47, v74, vcc
	v_cndmask_b32_e32 v46, v84, v46, vcc
	v_cndmask_b32_e32 v45, v45, v73, vcc
	v_cndmask_b32_e32 v44, v44, v72, vcc
	v_cndmask_b32_e32 v43, v83, v43, vcc
	v_cndmask_b32_e32 v42, v42, v70, vcc
	v_cndmask_b32_e32 v40, v82, v40, vcc
	v_cndmask_b32_e32 v39, v39, v64, vcc
	v_cndmask_b32_e32 v38, v38, v63, vcc
	v_cndmask_b32_e32 v37, v81, v37, vcc
	v_cndmask_b32_e32 v36, v36, v62, vcc
	v_cndmask_b32_e32 v35, v35, v61, vcc
	v_cndmask_b32_e32 v34, v80, v34, vcc
	v_cndmask_b32_e32 v32, v32, v59, vcc
	v_cndmask_b32_e32 v31, v79, v31, vcc
	v_cndmask_b32_e32 v30, v30, v58, vcc
	v_cndmask_b32_e32 v29, v29, v57, vcc
	v_cndmask_b32_e32 v28, v78, v28, vcc
	v_cndmask_b32_e32 v24, v24, v52, vcc
	v_cndmask_b32_e32 v27, v27, v56, vcc
	v_cndmask_b32_e32 v26, v26, v55, vcc
	v_cndmask_b32_e32 v25, v71, v25, vcc
	ds_bpermute_b32 v61, v51, v33
	ds_bpermute_b32 v73, v51, v41
	ds_bpermute_b32 v52, v51, v24
	ds_bpermute_b32 v53, v51, v25
	ds_bpermute_b32 v54, v51, v26
	ds_bpermute_b32 v55, v51, v27
	ds_bpermute_b32 v56, v51, v28
	ds_bpermute_b32 v57, v51, v29
	ds_bpermute_b32 v58, v51, v30
	ds_bpermute_b32 v59, v51, v31
	ds_bpermute_b32 v60, v51, v32
	ds_bpermute_b32 v62, v51, v34
	ds_bpermute_b32 v63, v51, v35
	ds_bpermute_b32 v64, v51, v36
	ds_bpermute_b32 v65, v51, v37
	ds_bpermute_b32 v70, v51, v38
	ds_bpermute_b32 v71, v51, v39
	ds_bpermute_b32 v72, v51, v40
	ds_bpermute_b32 v74, v51, v42
	ds_bpermute_b32 v75, v51, v43
	ds_bpermute_b32 v76, v51, v44
	ds_bpermute_b32 v77, v51, v45
	ds_bpermute_b32 v78, v51, v46
	ds_bpermute_b32 v79, v51, v47
	ds_bpermute_b32 v80, v51, v48
	ds_bpermute_b32 v81, v51, v22
	ds_bpermute_b32 v82, v51, v50
	ds_bpermute_b32 v83, v51, v49
	ds_bpermute_b32 v84, v51, v21
	ds_bpermute_b32 v85, v51, v23
	ds_bpermute_b32 v86, v51, v20
	ds_bpermute_b32 v51, v51, v19
	v_cmp_gt_i32_e32 vcc, 16, v68
	s_waitcnt lgkmcnt(14)
	v_add_f32_e32 v61, v33, v61
	v_add_f32_e32 v73, v41, v73
	v_cndmask_b32_e32 v61, v61, v33, vcc
	v_cndmask_b32_e32 v73, v73, v41, vcc
	s_waitcnt lgkmcnt(3)
	v_add_f32_e32 v84, v21, v84
	s_waitcnt lgkmcnt(0)
	v_add_f32_e32 v51, v19, v51
	v_cndmask_b32_e32 v93, v61, v33, vcc
	v_cndmask_b32_e32 v33, v73, v41, vcc
	v_cndmask_b32_e32 v41, v51, v19, vcc
	v_cndmask_b32_e32 v19, v84, v21, vcc
	v_subrev_u32_e32 v21, 32, v112
	v_add_f32_e32 v57, v29, v57
	v_add_f32_e32 v79, v47, v79
	v_cmp_lt_i32_e64 s[0:1], v21, v18
	v_add_f32_e32 v52, v24, v52
	v_add_f32_e32 v53, v25, v53
	v_cndmask_b32_e32 v57, v57, v29, vcc
	v_add_f32_e32 v60, v32, v60
	v_add_f32_e32 v74, v42, v74
	v_cndmask_b32_e32 v79, v79, v47, vcc
	v_cndmask_b32_e64 v18, v21, v112, s[0:1]
	v_cndmask_b32_e32 v52, v52, v24, vcc
	v_cndmask_b32_e32 v60, v60, v32, vcc
	v_cndmask_b32_e32 v74, v74, v42, vcc
	v_add_f32_e32 v81, v22, v81
	v_cndmask_b32_e32 v91, v57, v29, vcc
	v_cndmask_b32_e32 v29, v79, v47, vcc
	v_cndmask_b32_e32 v47, v53, v25, vcc
	v_lshlrev_b32_e32 v18, 2, v18
	v_cndmask_b32_e32 v94, v60, v32, vcc
	v_cndmask_b32_e32 v32, v74, v42, vcc
	v_cndmask_b32_e32 v42, v81, v22, vcc
	ds_bpermute_b32 v21, v18, v52
	ds_bpermute_b32 v22, v18, v47
	v_add_f32_e32 v63, v35, v63
	v_add_f32_e32 v64, v36, v64
	v_add_f32_e32 v80, v48, v80
	v_add_f32_e32 v54, v26, v54
	v_add_f32_e32 v55, v27, v55
	v_add_f32_e32 v56, v28, v56
	v_add_f32_e32 v58, v30, v58
	v_cndmask_b32_e32 v63, v63, v35, vcc
	v_cndmask_b32_e32 v64, v64, v36, vcc
	v_cndmask_b32_e32 v80, v80, v48, vcc
	v_add_f32_e32 v82, v50, v82
	v_add_f32_e32 v83, v49, v83
	v_cndmask_b32_e32 v54, v54, v26, vcc
	v_cndmask_b32_e32 v55, v55, v27, vcc
	v_cndmask_b32_e32 v58, v58, v30, vcc
	v_cndmask_b32_e32 v82, v82, v50, vcc
	v_cndmask_b32_e32 v83, v83, v49, vcc
	v_cndmask_b32_e32 v92, v63, v35, vcc
	v_cndmask_b32_e32 v35, v64, v36, vcc
	v_cndmask_b32_e32 v36, v80, v48, vcc
	v_cndmask_b32_e32 v48, v56, v28, vcc
	v_cndmask_b32_e32 v89, v52, v24, vcc
	v_cndmask_b32_e32 v90, v58, v30, vcc
	v_cndmask_b32_e32 v30, v83, v49, vcc
	v_cndmask_b32_e32 v24, v82, v50, vcc
	s_waitcnt lgkmcnt(1)
	v_add_f32_e32 v49, v52, v21
	s_waitcnt lgkmcnt(0)
	v_add_f32_e32 v50, v47, v22
	ds_bpermute_b32 v21, v18, v54
	ds_bpermute_b32 v22, v18, v55
	ds_bpermute_b32 v25, v18, v48
	v_add_f32_e32 v76, v44, v76
	v_add_f32_e32 v59, v31, v59
	v_cndmask_b32_e32 v76, v76, v44, vcc
	v_add_f32_e32 v78, v46, v78
	v_cndmask_b32_e32 v88, v54, v26, vcc
	v_cndmask_b32_e32 v26, v76, v44, vcc
	v_cndmask_b32_e32 v44, v78, v46, vcc
	v_cndmask_b32_e32 v46, v59, v31, vcc
	ds_bpermute_b32 v28, v18, v57
	ds_bpermute_b32 v31, v18, v58
	s_waitcnt lgkmcnt(4)
	v_add_f32_e32 v51, v54, v21
	s_waitcnt lgkmcnt(3)
	v_add_f32_e32 v52, v55, v22
	s_waitcnt lgkmcnt(2)
	v_add_f32_e32 v53, v48, v25
	ds_bpermute_b32 v21, v18, v46
	ds_bpermute_b32 v22, v18, v60
	ds_bpermute_b32 v25, v18, v61
	v_add_f32_e32 v77, v45, v77
	v_add_f32_e32 v62, v34, v62
	v_add_f32_e32 v65, v37, v65
	v_add_f32_e32 v70, v38, v70
	v_cndmask_b32_e32 v77, v77, v45, vcc
	v_cndmask_b32_e32 v70, v70, v38, vcc
	v_cndmask_b32_e32 v87, v55, v27, vcc
	v_cndmask_b32_e32 v27, v77, v45, vcc
	v_cndmask_b32_e32 v37, v65, v37, vcc
	v_cndmask_b32_e32 v45, v62, v34, vcc
	s_waitcnt lgkmcnt(4)
	v_add_f32_e32 v54, v57, v28
	s_waitcnt lgkmcnt(3)
	v_add_f32_e32 v55, v58, v31
	ds_bpermute_b32 v28, v18, v45
	s_waitcnt lgkmcnt(3)
	v_add_f32_e32 v56, v46, v21
	s_waitcnt lgkmcnt(2)
	v_add_f32_e32 v57, v60, v22
	s_waitcnt lgkmcnt(1)
	v_add_f32_e32 v58, v61, v25
	ds_bpermute_b32 v21, v18, v64
	ds_bpermute_b32 v22, v18, v37
	ds_bpermute_b32 v25, v18, v70
	v_add_f32_e32 v71, v39, v71
	v_add_f32_e32 v75, v43, v75
	v_cndmask_b32_e32 v71, v71, v39, vcc
	v_cndmask_b32_e32 v43, v75, v43, vcc
	ds_bpermute_b32 v31, v18, v63
	s_waitcnt lgkmcnt(4)
	v_add_f32_e32 v59, v45, v28
	ds_bpermute_b32 v28, v18, v71
	s_waitcnt lgkmcnt(4)
	v_add_f32_e32 v34, v64, v21
	s_waitcnt lgkmcnt(3)
	v_add_f32_e32 v61, v37, v22
	s_waitcnt lgkmcnt(2)
	v_add_f32_e32 v62, v70, v25
	ds_bpermute_b32 v21, v18, v73
	ds_bpermute_b32 v22, v18, v74
	ds_bpermute_b32 v25, v18, v43
	v_add_f32_e32 v72, v40, v72
	v_cndmask_b32_e32 v39, v71, v39, vcc
	v_cndmask_b32_e32 v38, v70, v38, vcc
	v_cndmask_b32_e32 v40, v72, v40, vcc
	s_waitcnt lgkmcnt(4)
	v_add_f32_e32 v60, v63, v31
	s_waitcnt lgkmcnt(3)
	v_add_f32_e32 v63, v71, v28
	ds_bpermute_b32 v28, v18, v76
	s_waitcnt lgkmcnt(3)
	v_add_f32_e32 v65, v73, v21
	s_waitcnt lgkmcnt(2)
	v_add_f32_e32 v70, v74, v22
	s_waitcnt lgkmcnt(1)
	v_add_f32_e32 v71, v43, v25
	ds_bpermute_b32 v21, v18, v44
	ds_bpermute_b32 v22, v18, v79
	ds_bpermute_b32 v25, v18, v80
	ds_bpermute_b32 v72, v18, v42
	ds_bpermute_b32 v73, v18, v82
	ds_bpermute_b32 v64, v18, v77
	v_add_f32_e32 v85, v23, v85
	v_cndmask_b32_e32 v85, v85, v23, vcc
	v_add_f32_e32 v86, v20, v86
	v_cndmask_b32_e32 v86, v86, v20, vcc
	ds_bpermute_b32 v31, v18, v40
	s_waitcnt lgkmcnt(7)
	v_add_f32_e32 v28, v76, v28
	s_waitcnt lgkmcnt(6)
	v_add_f32_e32 v74, v44, v21
	s_waitcnt lgkmcnt(5)
	v_add_f32_e32 v75, v79, v22
	s_waitcnt lgkmcnt(4)
	v_add_f32_e32 v22, v80, v25
	s_waitcnt lgkmcnt(3)
	v_add_f32_e32 v25, v42, v72
	s_waitcnt lgkmcnt(2)
	v_add_f32_e32 v72, v82, v73
	ds_bpermute_b32 v21, v18, v83
	ds_bpermute_b32 v73, v18, v19
	ds_bpermute_b32 v76, v18, v85
	s_waitcnt lgkmcnt(4)
	v_add_f32_e32 v64, v77, v64
	ds_bpermute_b32 v77, v18, v86
	ds_bpermute_b32 v18, v18, v41
	s_lshl_b32 s0, s42, 3
	s_or_b32 s0, s40, s0
	v_cndmask_b32_e32 v20, v86, v20, vcc
	v_cndmask_b32_e32 v23, v85, v23, vcc
	s_waitcnt lgkmcnt(5)
	v_add_f32_e32 v31, v40, v31
	s_waitcnt lgkmcnt(4)
	v_add_f32_e32 v78, v83, v21
	s_waitcnt lgkmcnt(3)
	v_add_f32_e32 v21, v19, v73
	s_waitcnt lgkmcnt(2)
	v_add_f32_e32 v73, v85, v76
	v_cmp_gt_i32_e32 vcc, 32, v68
	s_mul_hi_i32 s1, s0, 0x104
	s_mulk_i32 s0, 0x104
	s_waitcnt lgkmcnt(1)
	v_add_f32_e32 v76, v86, v77
	s_waitcnt lgkmcnt(0)
	v_add_f32_e32 v77, v41, v18
	v_cndmask_b32_e32 v18, v21, v19, vcc
	v_cndmask_b32_e32 v19, v73, v23, vcc
	v_cndmask_b32_e32 v23, v25, v42, vcc
	v_cndmask_b32_e32 v25, v78, v30, vcc
	v_cndmask_b32_e32 v30, v31, v40, vcc
	v_cndmask_b32_e32 v40, v59, v45, vcc
	v_cndmask_b32_e32 v45, v56, v46, vcc
	v_cndmask_b32_e32 v46, v49, v89, vcc
	v_cndmask_b32_e32 v49, v52, v87, vcc
	s_add_u32 s16, s0, s41
	v_lshl_or_b32 v52, v112, 2, v116
	v_lshrrev_b32_e32 v255, 2, v52
	s_nop 0
	v_readfirstlane_b32 s101, v255
	s_nop 3
	v_cndmask_b32_e32 v42, v53, v48, vcc
	s_addc_u32 s17, s1, 0
	v_readlane_b32 s98, v46, s101
	s_lshl_b64 s[0:1], s[16:17], 13
	s_add_u32 s18, s22, s0
	v_cndmask_b32_e32 v47, v50, v47, vcc
	v_cndmask_b32_e32 v48, v51, v88, vcc
	s_addc_u32 s19, s23, s1
	v_lshlrev_b64 v[50:51], 7, v[68:69]
	v_cndmask_b32_e32 v20, v76, v20, vcc
	v_cndmask_b32_e32 v21, v77, v41, vcc
	v_cndmask_b32_e32 v22, v22, v36, vcc
	v_cndmask_b32_e32 v34, v34, v35, vcc
	v_cndmask_b32_e32 v35, v61, v37, vcc
	v_cndmask_b32_e32 v36, v62, v38, vcc
	v_cndmask_b32_e32 v37, v63, v39, vcc
	v_lshl_add_u64 v[50:51], s[18:19], 0, v[50:51]
	v_cndmask_b32_e32 v24, v72, v24, vcc
	v_cndmask_b32_e32 v26, v28, v26, vcc
	v_cndmask_b32_e32 v27, v64, v27, vcc
	v_cndmask_b32_e32 v28, v74, v44, vcc
	v_cndmask_b32_e32 v29, v75, v29, vcc
	v_cndmask_b32_e32 v31, v65, v33, vcc
	v_cndmask_b32_e32 v32, v70, v32, vcc
	v_cndmask_b32_e32 v33, v71, v43, vcc
	v_cndmask_b32_e32 v38, v57, v94, vcc
	v_cndmask_b32_e32 v39, v58, v93, vcc
	v_cndmask_b32_e32 v41, v60, v92, vcc
	v_cndmask_b32_e32 v43, v54, v91, vcc
	v_cndmask_b32_e32 v44, v55, v90, vcc
	global_store_dwordx4 v[50:51], v[46:49], off
	global_store_dwordx4 v[50:51], v[42:45], off offset:16
	global_store_dwordx4 v[50:51], v[38:41], off offset:32
	global_store_dwordx4 v[50:51], v[34:37], off offset:48
	global_store_dwordx4 v[50:51], v[30:33], off offset:64
	global_store_dwordx4 v[50:51], v[26:29], off offset:80
	global_store_dwordx4 v[50:51], v[22:25], off offset:96
	v_sub_f32_e32 v53, s98, v46
	global_store_dwordx4 v[50:51], v[18:21], off offset:112
	v_readlane_b32 s98, v47, s101
	v_mul_f32_e32 v53, 0x3fb8aa3b, v53
	v_exp_f32_e32 v53, v53
	v_lshlrev_b32_e32 v51, 16, v14
	v_and_b32_e32 v14, 0xffff0000, v14
	v_sub_f32_e32 v50, s98, v47
	v_mul_f32_e32 v51, v53, v51
	v_mul_f32_e32 v50, 0x3fb8aa3b, v50
	v_bfe_u32 v53, v51, 16, 1
	v_exp_f32_e32 v50, v50
	v_add3_u32 v51, v51, v53, s38
	ds_write_b16_d16_hi v66, v51 offset:8192
	v_readlane_b32 s98, v48, s101
	v_mul_f32_e32 v14, v50, v14
	v_bfe_u32 v50, v14, 16, 1
	v_add3_u32 v14, v14, v50, s38
	ds_write_b16_d16_hi v66, v14 offset:8320
	v_sub_f32_e32 v50, s98, v48
	v_readlane_b32 s98, v49, s101
	v_mul_f32_e32 v50, 0x3fb8aa3b, v50
	v_exp_f32_e32 v50, v50
	v_lshlrev_b32_e32 v51, 16, v15
	v_and_b32_e32 v15, 0xffff0000, v15
	v_sub_f32_e32 v14, s98, v49
	v_mul_f32_e32 v50, v50, v51
	v_mul_f32_e32 v14, 0x3fb8aa3b, v14
	v_bfe_u32 v51, v50, 16, 1
	v_exp_f32_e32 v14, v14
	v_add3_u32 v50, v50, v51, s38
	ds_write_b16_d16_hi v66, v50 offset:8448
	v_readlane_b32 s98, v42, s101
	v_mul_f32_e32 v14, v14, v15
	v_bfe_u32 v15, v14, 16, 1
	v_add3_u32 v14, v14, v15, s38
	ds_write_b16_d16_hi v66, v14 offset:8576
	v_sub_f32_e32 v15, s98, v42
	v_readlane_b32 s98, v43, s101
	v_mul_f32_e32 v15, 0x3fb8aa3b, v15
	v_exp_f32_e32 v15, v15
	v_lshlrev_b32_e32 v50, 16, v16
	v_and_b32_e32 v16, 0xffff0000, v16
	v_sub_f32_e32 v14, s98, v43
	v_mul_f32_e32 v15, v15, v50
	v_mul_f32_e32 v14, 0x3fb8aa3b, v14
	v_bfe_u32 v50, v15, 16, 1
	v_exp_f32_e32 v14, v14
	v_add3_u32 v15, v15, v50, s38
	ds_write_b16_d16_hi v66, v15 offset:8704
	v_readlane_b32 s98, v44, s101
	v_mul_f32_e32 v14, v14, v16
	v_bfe_u32 v16, v14, 16, 1
	v_add3_u32 v14, v14, v16, s38
	ds_write_b16_d16_hi v66, v14 offset:8832
	v_sub_f32_e32 v15, s98, v44
	v_readlane_b32 s98, v45, s101
	v_mul_f32_e32 v15, 0x3fb8aa3b, v15
	v_exp_f32_e32 v15, v15
	v_lshlrev_b32_e32 v16, 16, v17
	v_cmp_eq_u32_e32 vcc, 63, v68
	v_sub_f32_e32 v14, s98, v45
	v_mul_f32_e32 v15, v15, v16
	v_mul_f32_e32 v14, 0x3fb8aa3b, v14
	v_bfe_u32 v16, v15, 16, 1
	v_exp_f32_e32 v14, v14
	v_add3_u32 v15, v15, v16, s38
	ds_write_b16_d16_hi v66, v15 offset:8960
	v_readlane_b32 s98, v38, s101
	v_and_b32_e32 v16, 0xffff0000, v17
	v_mul_f32_e32 v14, v14, v16
	v_bfe_u32 v16, v14, 16, 1
	v_add3_u32 v14, v14, v16, s38
	v_sub_f32_e32 v15, s98, v38
	ds_write_b16_d16_hi v66, v14 offset:9088
	v_readlane_b32 s98, v39, s101
	v_mul_f32_e32 v15, 0x3fb8aa3b, v15
	v_exp_f32_e32 v15, v15
	v_lshlrev_b32_e32 v16, 16, v10
	v_and_b32_e32 v10, 0xffff0000, v10
	v_sub_f32_e32 v14, s98, v39
	v_mul_f32_e32 v15, v15, v16
	v_mul_f32_e32 v14, 0x3fb8aa3b, v14
	v_bfe_u32 v16, v15, 16, 1
	v_exp_f32_e32 v14, v14
	v_add3_u32 v15, v15, v16, s38
	ds_write_b16_d16_hi v66, v15 offset:9216
	v_readlane_b32 s98, v40, s101
	v_mul_f32_e32 v10, v14, v10
	v_bfe_u32 v14, v10, 16, 1
	v_add3_u32 v10, v10, v14, s38
	ds_write_b16_d16_hi v66, v10 offset:9344
	v_sub_f32_e32 v14, s98, v40
	v_readlane_b32 s98, v41, s101
	v_mul_f32_e32 v14, 0x3fb8aa3b, v14
	v_exp_f32_e32 v14, v14
	v_lshlrev_b32_e32 v15, 16, v11
	v_and_b32_e32 v11, 0xffff0000, v11
	v_sub_f32_e32 v10, s98, v41
	v_mul_f32_e32 v14, v14, v15
	v_mul_f32_e32 v10, 0x3fb8aa3b, v10
	v_bfe_u32 v15, v14, 16, 1
	v_exp_f32_e32 v10, v10
	v_add3_u32 v14, v14, v15, s38
	ds_write_b16_d16_hi v66, v14 offset:9472
	v_readlane_b32 s98, v34, s101
	v_mul_f32_e32 v10, v10, v11
	v_bfe_u32 v11, v10, 16, 1
	v_add3_u32 v10, v10, v11, s38
	ds_write_b16_d16_hi v66, v10 offset:9600
	v_sub_f32_e32 v11, s98, v34
	v_readlane_b32 s98, v35, s101
	v_mul_f32_e32 v11, 0x3fb8aa3b, v11
	v_exp_f32_e32 v11, v11
	v_lshlrev_b32_e32 v14, 16, v12
	v_and_b32_e32 v12, 0xffff0000, v12
	v_sub_f32_e32 v10, s98, v35
	v_mul_f32_e32 v11, v11, v14
	v_mul_f32_e32 v10, 0x3fb8aa3b, v10
	v_bfe_u32 v14, v11, 16, 1
	v_exp_f32_e32 v10, v10
	v_add3_u32 v11, v11, v14, s38
	ds_write_b16_d16_hi v66, v11 offset:9728
	v_readlane_b32 s98, v36, s101
	v_mul_f32_e32 v10, v10, v12
	v_bfe_u32 v12, v10, 16, 1
	v_add3_u32 v10, v10, v12, s38
	ds_write_b16_d16_hi v66, v10 offset:9856
	v_sub_f32_e32 v11, s98, v36
	v_readlane_b32 s98, v37, s101
	v_mul_f32_e32 v11, 0x3fb8aa3b, v11
	v_exp_f32_e32 v11, v11
	v_lshlrev_b32_e32 v12, 16, v13
	v_sub_f32_e32 v10, s98, v37
	v_mul_f32_e32 v11, v11, v12
	v_mul_f32_e32 v10, 0x3fb8aa3b, v10
	v_bfe_u32 v12, v11, 16, 1
	v_exp_f32_e32 v10, v10
	v_add3_u32 v11, v11, v12, s38
	ds_write_b16_d16_hi v66, v11 offset:9984
	v_readlane_b32 s98, v30, s101
	v_and_b32_e32 v12, 0xffff0000, v13
	v_mul_f32_e32 v10, v10, v12
	v_bfe_u32 v12, v10, 16, 1
	v_add3_u32 v10, v10, v12, s38
	v_sub_f32_e32 v11, s98, v30
	ds_write_b16_d16_hi v66, v10 offset:10112
	v_readlane_b32 s98, v31, s101
	v_mul_f32_e32 v11, 0x3fb8aa3b, v11
	v_exp_f32_e32 v11, v11
	v_lshlrev_b32_e32 v12, 16, v6
	v_and_b32_e32 v6, 0xffff0000, v6
	v_sub_f32_e32 v10, s98, v31
	v_mul_f32_e32 v11, v11, v12
	v_mul_f32_e32 v10, 0x3fb8aa3b, v10
	v_bfe_u32 v12, v11, 16, 1
	v_exp_f32_e32 v10, v10
	v_add3_u32 v11, v11, v12, s38
	ds_write_b16_d16_hi v66, v11 offset:10240
	v_readlane_b32 s98, v32, s101
	v_mul_f32_e32 v6, v10, v6
	v_bfe_u32 v10, v6, 16, 1
	v_add3_u32 v6, v6, v10, s38
	ds_write_b16_d16_hi v66, v6 offset:10368
	v_sub_f32_e32 v10, s98, v32
	v_readlane_b32 s98, v33, s101
	v_mul_f32_e32 v10, 0x3fb8aa3b, v10
	v_exp_f32_e32 v10, v10
	v_lshlrev_b32_e32 v11, 16, v7
	v_and_b32_e32 v7, 0xffff0000, v7
	v_sub_f32_e32 v6, s98, v33
	v_mul_f32_e32 v10, v10, v11
	v_mul_f32_e32 v6, 0x3fb8aa3b, v6
	v_bfe_u32 v11, v10, 16, 1
	v_exp_f32_e32 v6, v6
	v_add3_u32 v10, v10, v11, s38
	ds_write_b16_d16_hi v66, v10 offset:10496
	v_readlane_b32 s98, v26, s101
	v_mul_f32_e32 v6, v6, v7
	v_bfe_u32 v7, v6, 16, 1
	v_add3_u32 v6, v6, v7, s38
	ds_write_b16_d16_hi v66, v6 offset:10624
	v_sub_f32_e32 v7, s98, v26
	v_readlane_b32 s98, v27, s101
	v_mul_f32_e32 v7, 0x3fb8aa3b, v7
	v_exp_f32_e32 v7, v7
	v_lshlrev_b32_e32 v10, 16, v8
	v_and_b32_e32 v8, 0xffff0000, v8
	v_sub_f32_e32 v6, s98, v27
	v_mul_f32_e32 v7, v7, v10
	v_mul_f32_e32 v6, 0x3fb8aa3b, v6
	v_bfe_u32 v10, v7, 16, 1
	v_exp_f32_e32 v6, v6
	v_add3_u32 v7, v7, v10, s38
	ds_write_b16_d16_hi v66, v7 offset:10752
	v_readlane_b32 s98, v28, s101
	v_mul_f32_e32 v6, v6, v8
	v_bfe_u32 v8, v6, 16, 1
	v_add3_u32 v6, v6, v8, s38
	ds_write_b16_d16_hi v66, v6 offset:10880
	v_sub_f32_e32 v7, s98, v28
	v_readlane_b32 s98, v29, s101
	v_mul_f32_e32 v7, 0x3fb8aa3b, v7
	v_exp_f32_e32 v7, v7
	v_lshlrev_b32_e32 v8, 16, v9
	v_sub_f32_e32 v6, s98, v29
	v_mul_f32_e32 v7, v7, v8
	v_mul_f32_e32 v6, 0x3fb8aa3b, v6
	v_bfe_u32 v8, v7, 16, 1
	v_exp_f32_e32 v6, v6
	v_add3_u32 v7, v7, v8, s38
	ds_write_b16_d16_hi v66, v7 offset:11008
	v_readlane_b32 s98, v22, s101
	v_and_b32_e32 v8, 0xffff0000, v9
	v_mul_f32_e32 v6, v6, v8
	v_bfe_u32 v8, v6, 16, 1
	v_add3_u32 v6, v6, v8, s38
	v_sub_f32_e32 v7, s98, v22
	ds_write_b16_d16_hi v66, v6 offset:11136
	v_readlane_b32 s98, v23, s101
	v_mul_f32_e32 v7, 0x3fb8aa3b, v7
	v_exp_f32_e32 v7, v7
	v_lshlrev_b32_e32 v8, 16, v2
	v_and_b32_e32 v2, 0xffff0000, v2
	v_sub_f32_e32 v6, s98, v23
	v_mul_f32_e32 v7, v7, v8
	v_mul_f32_e32 v6, 0x3fb8aa3b, v6
	v_bfe_u32 v8, v7, 16, 1
	v_exp_f32_e32 v6, v6
	v_add3_u32 v7, v7, v8, s38
	ds_write_b16_d16_hi v66, v7 offset:11264
	v_readlane_b32 s98, v24, s101
	v_mul_f32_e32 v2, v6, v2
	v_bfe_u32 v6, v2, 16, 1
	v_add3_u32 v2, v2, v6, s38
	ds_write_b16_d16_hi v66, v2 offset:11392
	v_sub_f32_e32 v6, s98, v24
	v_readlane_b32 s98, v25, s101
	v_mul_f32_e32 v6, 0x3fb8aa3b, v6
	v_exp_f32_e32 v6, v6
	v_lshlrev_b32_e32 v7, 16, v3
	v_and_b32_e32 v3, 0xffff0000, v3
	v_sub_f32_e32 v2, s98, v25
	v_mul_f32_e32 v6, v6, v7
	v_mul_f32_e32 v2, 0x3fb8aa3b, v2
	v_bfe_u32 v7, v6, 16, 1
	v_exp_f32_e32 v2, v2
	v_add3_u32 v6, v6, v7, s38
	ds_write_b16_d16_hi v66, v6 offset:11520
	v_readlane_b32 s98, v18, s101
	v_mul_f32_e32 v2, v2, v3
	v_bfe_u32 v3, v2, 16, 1
	v_add3_u32 v2, v2, v3, s38
	ds_write_b16_d16_hi v66, v2 offset:11648
	v_sub_f32_e32 v3, s98, v18
	v_readlane_b32 s98, v19, s101
	v_mul_f32_e32 v3, 0x3fb8aa3b, v3
	v_exp_f32_e32 v3, v3
	v_lshlrev_b32_e32 v6, 16, v4
	v_and_b32_e32 v4, 0xffff0000, v4
	v_sub_f32_e32 v2, s98, v19
	v_mul_f32_e32 v3, v3, v6
	v_mul_f32_e32 v2, 0x3fb8aa3b, v2
	v_bfe_u32 v6, v3, 16, 1
	v_exp_f32_e32 v2, v2
	v_add3_u32 v3, v3, v6, s38
	ds_write_b16_d16_hi v66, v3 offset:11776
	v_readlane_b32 s98, v20, s101
	v_mul_f32_e32 v2, v2, v4
	v_bfe_u32 v4, v2, 16, 1
	v_add3_u32 v2, v2, v4, s38
	v_readlane_b32 s99, v21, s101
	v_sub_f32_e32 v3, s98, v20
	v_mul_f32_e32 v3, 0x3fb8aa3b, v3
	v_exp_f32_e32 v3, v3
	ds_write_b16_d16_hi v66, v2 offset:11904
	v_sub_f32_e32 v4, s99, v21
	v_lshlrev_b32_e32 v2, 16, v5
	v_mul_f32_e32 v4, 0x3fb8aa3b, v4
	v_mul_f32_e32 v2, v3, v2
	v_exp_f32_e32 v4, v4
	v_bfe_u32 v3, v2, 16, 1
	v_add3_u32 v2, v2, v3, s38
	ds_write_b16_d16_hi v66, v2 offset:12032
	v_and_b32_e32 v2, 0xffff0000, v5
	v_mul_f32_e32 v2, v4, v2
	v_bfe_u32 v3, v2, 16, 1
	v_add3_u32 v2, v2, v3, s38
	ds_write_b16_d16_hi v66, v2 offset:12160
	s_and_saveexec_b64 s[18:19], vcc
	s_cbranch_execz .LBB0_1942
	v_mul_f32_e32 v2, 0x3fb8aa3b, v46
	v_mul_f32_e32 v3, 0x3fb8aa3b, v47
	v_mul_f32_e32 v4, 0x3fb8aa3b, v48
	v_mul_f32_e32 v5, 0x3fb8aa3b, v49
	v_exp_f32_e32 v2, v2
	v_exp_f32_e32 v3, v3
	v_exp_f32_e32 v4, v4
	v_exp_f32_e32 v5, v5
	v_mul_f32_e32 v6, 0x3fb8aa3b, v42
	v_mul_f32_e32 v7, 0x3fb8aa3b, v43
	v_mul_f32_e32 v8, 0x3fb8aa3b, v44
	v_mul_f32_e32 v9, 0x3fb8aa3b, v45
	s_lshl_b64 s[16:17], s[16:17], 7
	v_exp_f32_e32 v6, v6
	v_exp_f32_e32 v7, v7
	v_exp_f32_e32 v8, v8
	v_exp_f32_e32 v9, v9
	v_mul_f32_e32 v10, 0x3fb8aa3b, v38
	v_mul_f32_e32 v11, 0x3fb8aa3b, v39
	v_mul_f32_e32 v12, 0x3fb8aa3b, v40
	v_mul_f32_e32 v13, 0x3fb8aa3b, v41
	s_add_u32 s16, s27, s16
	v_exp_f32_e32 v10, v10
	v_exp_f32_e32 v11, v11
	v_exp_f32_e32 v12, v12
	v_exp_f32_e32 v13, v13
	v_mul_f32_e32 v14, 0x3fb8aa3b, v34
	v_mul_f32_e32 v15, 0x3fb8aa3b, v35
	v_mul_f32_e32 v16, 0x3fb8aa3b, v36
	v_mul_f32_e32 v17, 0x3fb8aa3b, v37
	s_addc_u32 s17, s28, s17
	v_exp_f32_e32 v14, v14
	v_exp_f32_e32 v15, v15
	v_exp_f32_e32 v16, v16
	v_exp_f32_e32 v17, v17
	global_store_dwordx4 v67, v[2:5], s[16:17]
	global_store_dwordx4 v67, v[6:9], s[16:17] offset:16
	global_store_dwordx4 v67, v[10:13], s[16:17] offset:32
	global_store_dwordx4 v67, v[14:17], s[16:17] offset:48
	v_mul_f32_e32 v2, 0x3fb8aa3b, v30
	v_mul_f32_e32 v3, 0x3fb8aa3b, v31
	v_mul_f32_e32 v4, 0x3fb8aa3b, v32
	v_mul_f32_e32 v5, 0x3fb8aa3b, v33
	v_exp_f32_e32 v2, v2
	v_exp_f32_e32 v3, v3
	v_exp_f32_e32 v4, v4
	v_exp_f32_e32 v5, v5
	v_mul_f32_e32 v6, 0x3fb8aa3b, v26
	v_mul_f32_e32 v7, 0x3fb8aa3b, v27
	v_mul_f32_e32 v8, 0x3fb8aa3b, v28
	v_mul_f32_e32 v9, 0x3fb8aa3b, v29
	v_exp_f32_e32 v6, v6
	v_exp_f32_e32 v7, v7
	v_exp_f32_e32 v8, v8
	v_exp_f32_e32 v9, v9
	v_mul_f32_e32 v10, 0x3fb8aa3b, v22
	v_mul_f32_e32 v11, 0x3fb8aa3b, v23
	v_mul_f32_e32 v12, 0x3fb8aa3b, v24
	v_mul_f32_e32 v13, 0x3fb8aa3b, v25
	v_exp_f32_e32 v10, v10
	v_exp_f32_e32 v11, v11
	v_exp_f32_e32 v12, v12
	v_exp_f32_e32 v13, v13
	v_mul_f32_e32 v14, 0x3fb8aa3b, v18
	v_mul_f32_e32 v15, 0x3fb8aa3b, v19
	v_mul_f32_e32 v16, 0x3fb8aa3b, v20
	v_mul_f32_e32 v17, 0x3fb8aa3b, v21
	v_exp_f32_e32 v14, v14
	v_exp_f32_e32 v15, v15
	v_exp_f32_e32 v16, v16
	v_exp_f32_e32 v17, v17
	global_store_dwordx4 v67, v[2:5], s[16:17] offset:64
	global_store_dwordx4 v67, v[6:9], s[16:17] offset:80
	global_store_dwordx4 v67, v[10:13], s[16:17] offset:96
	global_store_dwordx4 v67, v[14:17], s[16:17] offset:112
	s_branch .LBB0_1942

.LBB0_1954:
	s_mul_hi_u32 s0, s37, s35
	s_mul_i32 s0, s0, s26
	s_sub_i32 s0, s37, s0
	s_sub_i32 s1, s0, s26
	s_cmp_ge_u32 s0, s26
	s_cselect_b32 s0, s1, s0
	s_sub_i32 s1, s0, s26
	s_cmp_ge_u32 s0, s26
	s_cselect_b32 s0, s1, s0
	s_cmp_lg_u32 s0, s24
	s_cbranch_scc1 .LBB0_1953
	s_bfe_u32 s39, s38, 0x20003
	s_lshr_b32 s41, s38, 5
	s_lshl_b32 s1, s41, 8
	s_lshl_b32 s2, s39, 6
	s_bfe_u32 s40, s38, 0x20001
	s_or_b32 s33, s1, s2
	s_and_b32 s0, s38, 1
	s_add_i32 s33, s33, 0x8000
	s_lshl_b32 s6, s40, 6
	s_cmp_eq_u32 s0, 0
	s_mov_b64 s[0:1], -1
	s_cbranch_scc1 .LBB0_1959
	v_mov_b32_e32 v68, v109
	v_mov_b64_e32 v[2:3], s[22:23]
	v_add_u32_e32 v4, s33, v68
	v_mad_i64_i32 v[70:71], s[0:1], v4, s28, v[2:3]
	s_lshl_b32 s0, s6, 1
	s_mov_b32 s1, s7
	v_lshl_add_u64 v[30:31], v[70:71], 0, s[0:1]
	global_load_dwordx4 v[2:5], v[30:31], off offset:512
	global_load_dwordx4 v[6:9], v[30:31], off offset:528
	global_load_dwordx4 v[10:13], v[30:31], off offset:544
	global_load_dwordx4 v[14:17], v[30:31], off offset:560
	global_load_dwordx4 v[18:21], v[30:31], off offset:576
	global_load_dwordx4 v[22:25], v[30:31], off offset:592
	global_load_dwordx4 v[26:29], v[30:31], off offset:608
	s_nop 0
	global_load_dwordx4 v[30:33], v[30:31], off offset:624
	v_readlane_b32 s44, v239, 33
	global_load_dwordx4 v[34:37], v[70:71], off offset:1568
	s_lshl_b32 s0, s40, 7
	v_readlane_b32 s48, v239, 37
	v_readlane_b32 s49, v239, 38
	v_readlane_b32 s50, v239, 39
	v_readlane_b32 s51, v239, 40
	v_readlane_b32 s56, v239, 45
	v_readlane_b32 s57, v239, 46
	s_add_u32 s12, s4, s0
	v_mov_b32_e32 v123, s0
	v_readlane_b32 s58, v239, 47
	v_readlane_b32 s59, v239, 48
	s_mov_b64 s[48:49], s[56:57]
	s_addc_u32 s13, s5, 0
	global_load_dwordx4 v[38:41], v123, s[48:49] offset:512
	global_load_dwordx4 v[42:45], v123, s[4:5]
	global_load_dwordx4 v[46:49], v123, s[4:5] offset:512
	global_load_dwordx4 v[50:53], v123, s[4:5] offset:1024
	global_load_dwordx4 v[54:57], v123, s[4:5] offset:1536
	global_load_dwordx4 v[58:61], v123, s[4:5] offset:2048
	global_load_dwordx4 v[62:65], v123, s[4:5] offset:2560
	global_load_dwordx4 v[74:77], v123, s[4:5] offset:3072
	global_load_dwordx4 v[78:81], v123, s[4:5] offset:3584
	global_load_dwordx4 v[82:85], v111, s[12:13]
	global_load_dwordx4 v[86:89], v111, s[12:13] offset:512
	global_load_dwordx4 v[90:93], v[70:71], off offset:1584
	v_lshl_add_u32 v66, v68, 1, s25
	v_lshl_add_u64 v[70:71], v[70:71], 0, s[6:7]
	v_ashrrev_i32_e32 v69, 31, v68
	v_readlane_b32 s45, v239, 34
	v_readlane_b32 s46, v239, 35
	v_readlane_b32 s47, v239, 36
	v_readlane_b32 s52, v239, 41
	v_readlane_b32 s53, v239, 42
	v_readlane_b32 s54, v239, 43
	v_readlane_b32 s55, v239, 44
	s_mov_b64 s[50:51], s[58:59]
	s_waitcnt vmcnt(20)
	ds_write_b16 v66, v2
	ds_write_b16_d16_hi v66, v2 offset:128
	ds_write_b16 v66, v3 offset:256
	ds_write_b16_d16_hi v66, v3 offset:384
	ds_write_b16 v66, v4 offset:512
	ds_write_b16_d16_hi v66, v4 offset:640
	ds_write_b16 v66, v5 offset:768
	ds_write_b16_d16_hi v66, v5 offset:896
	s_waitcnt vmcnt(19)
	ds_write_b16 v66, v6 offset:1024
	ds_write_b16_d16_hi v66, v6 offset:1152
	ds_write_b16 v66, v7 offset:1280
	ds_write_b16_d16_hi v66, v7 offset:1408
	ds_write_b16 v66, v8 offset:1536
	ds_write_b16_d16_hi v66, v8 offset:1664
	ds_write_b16 v66, v9 offset:1792
	ds_write_b16_d16_hi v66, v9 offset:1920
	s_waitcnt vmcnt(18)
	ds_write_b16 v66, v10 offset:2048
	ds_write_b16_d16_hi v66, v10 offset:2176
	ds_write_b16 v66, v11 offset:2304
	ds_write_b16_d16_hi v66, v11 offset:2432
	ds_write_b16 v66, v12 offset:2560
	ds_write_b16_d16_hi v66, v12 offset:2688
	ds_write_b16 v66, v13 offset:2816
	ds_write_b16_d16_hi v66, v13 offset:2944
	s_waitcnt vmcnt(17)
	ds_write_b16 v66, v14 offset:3072
	ds_write_b16_d16_hi v66, v14 offset:3200
	ds_write_b16 v66, v15 offset:3328
	ds_write_b16_d16_hi v66, v15 offset:3456
	ds_write_b16 v66, v16 offset:3584
	ds_write_b16_d16_hi v66, v16 offset:3712
	ds_write_b16 v66, v17 offset:3840
	ds_write_b16_d16_hi v66, v17 offset:3968
	s_waitcnt vmcnt(16)
	ds_write_b16 v66, v18 offset:4096
	ds_write_b16_d16_hi v66, v18 offset:4224
	ds_write_b16 v66, v19 offset:4352
	ds_write_b16_d16_hi v66, v19 offset:4480
	ds_write_b16 v66, v20 offset:4608
	ds_write_b16_d16_hi v66, v20 offset:4736
	ds_write_b16 v66, v21 offset:4864
	ds_write_b16_d16_hi v66, v21 offset:4992
	s_waitcnt vmcnt(15)
	ds_write_b16 v66, v22 offset:5120
	ds_write_b16_d16_hi v66, v22 offset:5248
	ds_write_b16 v66, v23 offset:5376
	ds_write_b16_d16_hi v66, v23 offset:5504
	ds_write_b16 v66, v24 offset:5632
	ds_write_b16_d16_hi v66, v24 offset:5760
	ds_write_b16 v66, v25 offset:5888
	ds_write_b16_d16_hi v66, v25 offset:6016
	s_waitcnt vmcnt(14)
	ds_write_b16 v66, v26 offset:6144
	ds_write_b16_d16_hi v66, v26 offset:6272
	ds_write_b16 v66, v27 offset:6400
	ds_write_b16_d16_hi v66, v27 offset:6528
	ds_write_b16 v66, v28 offset:6656
	ds_write_b16_d16_hi v66, v28 offset:6784
	ds_write_b16 v66, v29 offset:6912
	ds_write_b16_d16_hi v66, v29 offset:7040
	s_waitcnt vmcnt(13)
	ds_write_b16 v66, v30 offset:7168
	ds_write_b16_d16_hi v66, v30 offset:7296
	ds_write_b16 v66, v31 offset:7424
	ds_write_b16_d16_hi v66, v31 offset:7552
	ds_write_b16 v66, v32 offset:7680
	ds_write_b16_d16_hi v66, v32 offset:7808
	ds_write_b16 v66, v33 offset:7936
	ds_write_b16_d16_hi v66, v33 offset:8064
	global_load_dwordx4 v[18:21], v111, s[12:13] offset:1024
	global_load_dwordx4 v[22:25], v111, s[12:13] offset:1536
	global_load_dwordx4 v[14:17], v[70:71], off offset:256
	global_load_dwordx4 v[10:13], v[70:71], off offset:272
	global_load_dwordx4 v[6:9], v[70:71], off offset:288
	global_load_dwordx4 v[2:5], v[70:71], off offset:304
	global_load_dwordx4 v[26:29], v111, s[12:13] offset:2048
	global_load_dwordx4 v[30:33], v111, s[12:13] offset:2560
	global_load_dwordx4 v[94:97], v111, s[12:13] offset:3072
	global_load_dwordx4 v[98:101], v111, s[12:13] offset:3584
	s_waitcnt vmcnt(22)
	v_lshlrev_b32_e32 v118, 16, v34
	v_and_b32_e32 v117, 0xffff0000, v34
	v_lshlrev_b32_e32 v120, 16, v36
	v_and_b32_e32 v119, 0xffff0000, v36
	s_waitcnt vmcnt(20)
	v_fma_f32 v36, v42, v118, v38
	v_lshlrev_b32_e32 v122, 16, v35
	s_waitcnt vmcnt(19)
	v_fmac_f32_e32 v36, v46, v117
	v_and_b32_e32 v121, 0xffff0000, v35
	s_waitcnt vmcnt(18)
	v_fmac_f32_e32 v36, v50, v122
	v_fma_f32 v38, v43, v118, v39
	s_waitcnt vmcnt(17)
	v_fmac_f32_e32 v36, v54, v121
	v_fmac_f32_e32 v38, v47, v117
	s_waitcnt vmcnt(16)
	v_fmac_f32_e32 v36, v58, v120
	v_fmac_f32_e32 v38, v51, v122
	v_and_b32_e32 v73, 0xffff0000, v37
	v_lshlrev_b32_e32 v72, 16, v37
	s_waitcnt vmcnt(14)
	v_mov_b32_e32 v34, v74
	s_waitcnt vmcnt(13)
	v_mov_b32_e32 v35, v78
	v_fmac_f32_e32 v36, v62, v119
	v_fmac_f32_e32 v38, v55, v121
	v_fma_f32 v39, v44, v118, v40
	v_pk_mul_f32 v[34:35], v[34:35], v[72:73]
	v_fmac_f32_e32 v38, v59, v120
	v_fmac_f32_e32 v39, v48, v117
	v_add_f32_e32 v34, v36, v34
	v_mov_b32_e32 v78, v75
	v_fmac_f32_e32 v38, v63, v119
	v_fmac_f32_e32 v39, v52, v122
	v_fmac_f32_e32 v41, v45, v118
	v_add_f32_e32 v36, v34, v35
	v_pk_mul_f32 v[34:35], v[78:79], v[72:73]
	v_fmac_f32_e32 v39, v56, v121
	v_fmac_f32_e32 v41, v49, v117
	v_add_f32_e32 v34, v34, v38
	v_fmac_f32_e32 v39, v60, v120
	v_fmac_f32_e32 v41, v53, v122
	v_add_f32_e32 v37, v35, v34
	v_mov_b32_e32 v34, v76
	v_mov_b32_e32 v35, v80
	v_fmac_f32_e32 v39, v64, v119
	v_fmac_f32_e32 v41, v57, v121
	v_pk_mul_f32 v[34:35], v[34:35], v[72:73]
	v_fmac_f32_e32 v41, v61, v120
	v_add_f32_e32 v34, v34, v39
	v_mov_b32_e32 v80, v77
	v_fmac_f32_e32 v41, v65, v119
	v_add_f32_e32 v38, v35, v34
	v_pk_mul_f32 v[34:35], v[80:81], v[72:73]
	s_waitcnt vmcnt(10)
	v_and_b32_e32 v75, 0xffff0000, v90
	v_add_f32_e32 v34, v34, v41
	v_add_f32_e32 v39, v35, v34
	v_lshlrev_b32_e32 v74, 16, v90
	v_mov_b32_e32 v34, v82
	v_mov_b32_e32 v35, v86
	v_pk_mul_f32 v[34:35], v[34:35], v[74:75]
	v_mov_b32_e32 v86, v83
	v_add_f32_e32 v34, v36, v34
	v_add_f32_e32 v36, v34, v35
	v_pk_mul_f32 v[34:35], v[86:87], v[74:75]
	v_and_b32_e32 v79, 0xffff0000, v91
	v_add_f32_e32 v34, v34, v37
	v_add_f32_e32 v37, v35, v34
	v_mov_b32_e32 v34, v84
	v_mov_b32_e32 v35, v88
	v_pk_mul_f32 v[34:35], v[34:35], v[74:75]
	v_mov_b32_e32 v88, v85
	v_add_f32_e32 v34, v34, v38
	v_add_f32_e32 v38, v35, v34
	v_pk_mul_f32 v[34:35], v[88:89], v[74:75]
	v_lshlrev_b32_e32 v78, 16, v91
	v_add_f32_e32 v34, v34, v39
	v_add_f32_e32 v39, v35, v34
	v_and_b32_e32 v81, 0xffff0000, v92
	v_lshlrev_b32_e32 v80, 16, v92
	v_and_b32_e32 v83, 0xffff0000, v93
	v_lshlrev_b32_e32 v82, 16, v93
	s_waitcnt vmcnt(9)
	v_mov_b32_e32 v34, v18
	s_waitcnt vmcnt(8)
	v_mov_b32_e32 v35, v22
	v_pk_mul_f32 v[34:35], v[34:35], v[78:79]
	v_mov_b32_e32 v22, v19
	v_add_f32_e32 v18, v36, v34
	v_add_f32_e32 v34, v18, v35
	v_pk_mul_f32 v[18:19], v[22:23], v[78:79]
	s_nop 0
	v_add_f32_e32 v18, v18, v37
	v_add_f32_e32 v22, v19, v18
	v_mov_b32_e32 v18, v20
	v_mov_b32_e32 v19, v24
	v_pk_mul_f32 v[18:19], v[18:19], v[78:79]
	v_mov_b32_e32 v24, v21
	v_add_f32_e32 v18, v18, v38
	v_add_f32_e32 v20, v19, v18
	v_pk_mul_f32 v[18:19], v[24:25], v[78:79]
	s_waitcnt vmcnt(0)
	v_mov_b32_e32 v21, v98
	v_add_f32_e32 v18, v18, v39
	v_add_f32_e32 v23, v19, v18
	v_mov_b32_e32 v18, v26
	v_mov_b32_e32 v19, v30
	v_pk_mul_f32 v[18:19], v[18:19], v[80:81]
	v_mov_b32_e32 v30, v27
	v_add_f32_e32 v18, v34, v18
	v_add_f32_e32 v24, v18, v19
	v_pk_mul_f32 v[18:19], v[30:31], v[80:81]
	v_mov_b32_e32 v98, v95
	v_add_f32_e32 v18, v18, v22
	v_add_f32_e32 v22, v19, v18
	v_mov_b32_e32 v18, v28
	v_mov_b32_e32 v19, v32
	v_pk_mul_f32 v[18:19], v[18:19], v[80:81]
	v_mov_b32_e32 v32, v29
	v_add_f32_e32 v18, v18, v20
	v_mov_b32_e32 v20, v94
	v_pk_mul_f32 v[20:21], v[20:21], v[82:83]
	s_nop 0
	v_add_f32_e32 v20, v24, v20
	v_add_f32_e32 v20, v20, v21
	v_mul_f32_e64 v21, |v20|, s29
	v_exp_f32_e32 v21, v21
	v_add_f32_e32 v24, v19, v18
	v_pk_mul_f32 v[18:19], v[32:33], v[80:81]
	v_add_f32_e32 v21, 1.0, v21
	v_cmp_gt_f32_e32 vcc, s30, v21
	v_add_f32_e32 v18, v18, v23
	v_add_f32_e32 v26, v19, v18
	v_cndmask_b32_e64 v25, 0, 32, vcc
	v_ldexp_f32 v21, v21, v25
	v_log_f32_e32 v25, v21
	v_min_f32_e32 v18, 0, v20
	v_pk_mul_f32 v[20:21], v[98:99], v[82:83]
	v_mov_b32_e32 v23, v100
	v_add_f32_e32 v20, v20, v22
	v_add_f32_e32 v21, v21, v20
	v_mul_f32_e64 v20, |v21|, s29
	v_exp_f32_e32 v20, v20
	v_mul_f32_e32 v19, 0x3f317217, v25
	v_fma_f32 v19, v25, s31, -v19
	v_fmac_f32_e32 v19, 0x3377d1cf, v25
	v_fmac_f32_e32 v19, 0x3f317217, v25
	v_cmp_lt_f32_e64 s[0:1], |v25|, s34
	v_add_f32_e32 v20, 1.0, v20
	v_mov_b32_e32 v100, v97
	v_cndmask_b32_e64 v19, v25, v19, s[0:1]
	v_cmp_gt_f32_e64 s[0:1], s30, v20
	s_nop 1
	v_cndmask_b32_e64 v22, 0, 32, s[0:1]
	v_ldexp_f32 v20, v20, v22
	v_mov_b32_e32 v22, v96
	v_pk_mul_f32 v[22:23], v[22:23], v[82:83]
	v_log_f32_e32 v25, v20
	v_add_f32_e32 v22, v22, v24
	v_add_f32_e32 v22, v23, v22
	v_mul_f32_e64 v23, |v22|, s29
	v_cndmask_b32_e32 v20, 0, v112, vcc
	v_exp_f32_e32 v23, v23
	v_sub_f32_e32 v20, v19, v20
	v_min_f32_e32 v19, 0, v21
	v_mul_f32_e32 v21, 0x3f317217, v25
	v_fma_f32 v21, v25, s31, -v21
	v_fmac_f32_e32 v21, 0x3377d1cf, v25
	v_fmac_f32_e32 v21, 0x3f317217, v25
	v_cmp_lt_f32_e64 vcc, |v25|, s34
	v_add_f32_e32 v23, 1.0, v23
	v_cndmask_b32_e64 v24, 0, v112, s[0:1]
	v_cndmask_b32_e32 v21, v25, v21, vcc
	v_cmp_gt_f32_e32 vcc, s30, v23
	v_sub_f32_e32 v21, v21, v24
	v_pk_add_f32 v[18:19], v[18:19], v[20:21] neg_lo:[0,1] neg_hi:[0,1]
	v_cndmask_b32_e64 v24, 0, 32, vcc
	v_ldexp_f32 v23, v23, v24
	v_pk_mul_f32 v[20:21], v[100:101], v[82:83]
	v_log_f32_e32 v23, v23
	v_add_f32_e32 v20, v20, v26
	v_add_f32_e32 v21, v21, v20
	v_mul_f32_e64 v20, |v21|, s29
	v_exp_f32_e32 v20, v20
	v_pk_mul_f32 v[70:71], v[18:19], s[10:11] op_sel_hi:[1,0]
	v_mul_f32_e32 v19, 0x3f317217, v23
	v_fma_f32 v19, v23, s31, -v19
	v_fmac_f32_e32 v19, 0x3377d1cf, v23
	v_fmac_f32_e32 v19, 0x3f317217, v23
	v_cmp_lt_f32_e64 s[0:1], |v23|, s34
	v_add_f32_e32 v20, 1.0, v20
	v_min_f32_e32 v18, 0, v22
	v_cndmask_b32_e64 v19, v23, v19, s[0:1]
	v_cmp_gt_f32_e64 s[0:1], s30, v20
	s_nop 1
	v_cndmask_b32_e64 v22, 0, 32, s[0:1]
	v_ldexp_f32 v20, v20, v22
	v_log_f32_e32 v22, v20
	v_cndmask_b32_e32 v20, 0, v112, vcc
	v_sub_f32_e32 v20, v19, v20
	v_min_f32_e32 v19, 0, v21
	v_mul_f32_e32 v21, 0x3f317217, v22
	v_fma_f32 v21, v22, s31, -v21
	v_fmac_f32_e32 v21, 0x3377d1cf, v22
	v_fmac_f32_e32 v21, 0x3f317217, v22
	v_cmp_lt_f32_e64 vcc, |v22|, s34
	s_nop 1
	v_cndmask_b32_e32 v21, v22, v21, vcc
	v_cndmask_b32_e64 v22, 0, v112, s[0:1]
	v_sub_f32_e32 v21, v21, v22
	v_pk_add_f32 v[18:19], v[18:19], v[20:21] neg_lo:[0,1] neg_hi:[0,1]
	s_nop 0
	v_pk_mul_f32 v[76:77], v[18:19], s[10:11] op_sel_hi:[1,0]
	global_load_dwordx4 v[18:21], v123, s[48:49] offset:528
	global_load_dwordx4 v[22:25], v123, s[4:5] offset:16
	global_load_dwordx4 v[26:29], v123, s[4:5] offset:3088
	global_load_dwordx4 v[30:33], v123, s[4:5] offset:3600
	global_load_dwordx4 v[34:37], v111, s[12:13] offset:16
	global_load_dwordx4 v[38:41], v111, s[12:13] offset:528
	global_load_dwordx4 v[42:45], v111, s[12:13] offset:1040
	global_load_dwordx4 v[46:49], v111, s[12:13] offset:1552
	global_load_dwordx4 v[50:53], v111, s[12:13] offset:2064
	global_load_dwordx4 v[54:57], v111, s[12:13] offset:2576
	global_load_dwordx4 v[58:61], v111, s[12:13] offset:3088
	global_load_dwordx4 v[62:65], v111, s[12:13] offset:3600
	global_load_dwordx4 v[84:87], v123, s[4:5] offset:528
	global_load_dwordx4 v[88:91], v123, s[4:5] offset:1040
	global_load_dwordx4 v[92:95], v123, s[4:5] offset:1552
	global_load_dwordx4 v[96:99], v123, s[4:5] offset:2064
	global_load_dwordx4 v[100:103], v123, s[4:5] offset:2576
	s_waitcnt vmcnt(15)
	v_fma_f32 v130, v22, v118, v18
	v_fma_f32 v20, v24, v118, v20
	s_waitcnt vmcnt(14)
	v_mov_b32_e32 v104, v26
	s_waitcnt vmcnt(13)
	v_mov_b32_e32 v105, v30
	v_fma_f32 v23, v23, v118, v19
	v_mov_b32_e32 v30, v27
	v_mov_b32_e32 v18, v28
	v_mov_b32_e32 v19, v32
	v_pk_mul_f32 v[26:27], v[104:105], v[72:73]
	s_waitcnt vmcnt(12)
	v_mov_b32_e32 v106, v34
	s_waitcnt vmcnt(11)
	v_mov_b32_e32 v107, v38
	s_waitcnt vmcnt(4)
	v_fmac_f32_e32 v130, v84, v117
	v_fmac_f32_e32 v20, v86, v117
	s_waitcnt vmcnt(3)
	v_fmac_f32_e32 v130, v88, v122
	v_fmac_f32_e32 v20, v90, v122
	s_waitcnt vmcnt(2)
	v_fmac_f32_e32 v130, v92, v121
	v_fmac_f32_e32 v20, v94, v121
	s_waitcnt vmcnt(1)
	v_fmac_f32_e32 v130, v96, v120
	v_fmac_f32_e32 v20, v98, v120
	s_waitcnt vmcnt(0)
	v_fmac_f32_e32 v130, v100, v119
	v_fmac_f32_e32 v23, v85, v117
	v_pk_mul_f32 v[18:19], v[18:19], v[72:73]
	v_fmac_f32_e32 v20, v102, v119
	v_add_f32_e32 v24, v130, v26
	v_mov_b32_e32 v38, v35
	v_pk_mul_f32 v[34:35], v[106:107], v[74:75]
	v_fmac_f32_e32 v23, v89, v122
	v_add_f32_e32 v18, v18, v20
	v_add_f32_e32 v20, v24, v27
	v_mov_b32_e32 v124, v42
	v_mov_b32_e32 v125, v46
	v_fmac_f32_e32 v23, v93, v121
	v_add_f32_e32 v20, v20, v34
	v_mov_b32_e32 v46, v43
	v_pk_mul_f32 v[42:43], v[124:125], v[78:79]
	v_fmac_f32_e32 v23, v97, v120
	v_add_f32_e32 v20, v20, v35
	v_mov_b32_e32 v126, v50
	v_mov_b32_e32 v127, v54
	v_pk_mul_f32 v[30:31], v[30:31], v[72:73]
	v_fmac_f32_e32 v23, v101, v119
	v_add_f32_e32 v20, v20, v42
	v_mov_b32_e32 v54, v51
	v_pk_mul_f32 v[50:51], v[126:127], v[80:81]
	v_add_f32_e32 v23, v30, v23
	v_add_f32_e32 v20, v20, v43
	v_mov_b32_e32 v128, v58
	v_mov_b32_e32 v129, v62
	v_pk_mul_f32 v[38:39], v[38:39], v[74:75]
	v_add_f32_e32 v23, v31, v23
	v_add_f32_e32 v20, v20, v50
	v_mov_b32_e32 v62, v59
	v_pk_mul_f32 v[58:59], v[128:129], v[82:83]
	v_add_f32_e32 v23, v38, v23
	v_add_f32_e32 v20, v20, v51
	v_pk_mul_f32 v[46:47], v[46:47], v[78:79]
	v_add_f32_e32 v23, v39, v23
	v_add_f32_e32 v20, v20, v58
	v_add_f32_e32 v23, v46, v23
	v_add_f32_e32 v20, v20, v59
	v_pk_mul_f32 v[54:55], v[54:55], v[80:81]
	v_add_f32_e32 v23, v47, v23
	v_mul_f32_e64 v24, |v20|, s29
	v_add_f32_e32 v23, v54, v23
	v_exp_f32_e32 v24, v24
	v_pk_mul_f32 v[62:63], v[62:63], v[82:83]
	v_add_f32_e32 v23, v55, v23
	v_add_f32_e32 v23, v62, v23
	v_add_f32_e32 v23, v63, v23
	v_mul_f32_e64 v26, |v23|, s29
	v_add_f32_e32 v27, v19, v18
	v_add_f32_e32 v19, 1.0, v24
	v_exp_f32_e32 v26, v26
	v_cmp_gt_f32_e32 vcc, s30, v19
	v_min_f32_e32 v18, 0, v20
	v_mov_b32_e32 v22, v36
	v_cndmask_b32_e64 v24, 0, 32, vcc
	v_ldexp_f32 v19, v19, v24
	v_log_f32_e32 v24, v19
	v_add_f32_e32 v20, 1.0, v26
	v_cmp_gt_f32_e64 s[0:1], s30, v20
	v_min_f32_e32 v19, 0, v23
	v_cndmask_b32_e32 v23, 0, v112, vcc
	v_cndmask_b32_e64 v26, 0, 32, s[0:1]
	v_ldexp_f32 v20, v20, v26
	v_mul_f32_e32 v26, 0x3f317217, v24
	v_fma_f32 v26, v24, s31, -v26
	v_fmac_f32_e32 v26, 0x3377d1cf, v24
	v_fmac_f32_e32 v26, 0x3f317217, v24
	v_cmp_lt_f32_e64 vcc, |v24|, s34
	v_log_f32_e32 v20, v20
	v_fmac_f32_e32 v21, v25, v118
	v_cndmask_b32_e32 v24, v24, v26, vcc
	v_sub_f32_e32 v26, v24, v23
	v_mov_b32_e32 v23, v40
	v_pk_mul_f32 v[22:23], v[22:23], v[74:75]
	v_mul_f32_e32 v28, 0x3f317217, v20
	v_add_f32_e32 v22, v22, v27
	v_add_f32_e32 v24, v23, v22
	v_mov_b32_e32 v22, v44
	v_mov_b32_e32 v23, v48
	v_pk_mul_f32 v[22:23], v[22:23], v[78:79]
	v_fma_f32 v28, v20, s31, -v28
	v_add_f32_e32 v22, v22, v24
	v_add_f32_e32 v24, v23, v22
	v_mov_b32_e32 v22, v52
	v_mov_b32_e32 v23, v56
	v_pk_mul_f32 v[22:23], v[22:23], v[80:81]
	v_fmac_f32_e32 v28, 0x3377d1cf, v20
	v_add_f32_e32 v22, v22, v24
	v_add_f32_e32 v24, v23, v22
	v_mov_b32_e32 v22, v60
	v_mov_b32_e32 v23, v64
	v_pk_mul_f32 v[22:23], v[22:23], v[82:83]
	v_fmac_f32_e32 v28, 0x3f317217, v20
	v_add_f32_e32 v22, v22, v24
	v_add_f32_e32 v22, v23, v22
	v_mul_f32_e64 v23, |v22|, s29
	v_exp_f32_e32 v23, v23
	v_cmp_lt_f32_e64 vcc, |v20|, s34
	v_cndmask_b32_e64 v24, 0, v112, s[0:1]
	v_fmac_f32_e32 v21, v87, v117
	v_cndmask_b32_e32 v20, v20, v28, vcc
	v_sub_f32_e32 v27, v20, v24
	v_add_f32_e32 v20, 1.0, v23
	v_fmac_f32_e32 v21, v91, v122
	v_cmp_gt_f32_e32 vcc, s30, v20
	v_fmac_f32_e32 v21, v95, v121
	v_pk_add_f32 v[18:19], v[18:19], v[26:27] neg_lo:[0,1] neg_hi:[0,1]
	v_cndmask_b32_e64 v23, 0, 32, vcc
	v_fmac_f32_e32 v21, v99, v120
	v_mov_b32_e32 v32, v29
	v_ldexp_f32 v20, v20, v23
	v_pk_mul_f32 v[84:85], v[18:19], s[10:11] op_sel_hi:[1,0]
	v_min_f32_e32 v18, 0, v22
	v_fmac_f32_e32 v21, v103, v119
	v_pk_mul_f32 v[22:23], v[32:33], v[72:73]
	v_log_f32_e32 v24, v20
	v_add_f32_e32 v20, v22, v21
	v_mov_b32_e32 v40, v37
	v_add_f32_e32 v22, v23, v20
	v_pk_mul_f32 v[20:21], v[40:41], v[74:75]
	v_mov_b32_e32 v48, v45
	v_add_f32_e32 v20, v20, v22
	v_add_f32_e32 v22, v21, v20
	v_pk_mul_f32 v[20:21], v[48:49], v[78:79]
	v_mov_b32_e32 v56, v53
	v_add_f32_e32 v20, v20, v22
	v_add_f32_e32 v22, v21, v20
	v_pk_mul_f32 v[20:21], v[56:57], v[80:81]
	v_mov_b32_e32 v64, v61
	v_add_f32_e32 v20, v20, v22
	v_add_f32_e32 v22, v21, v20
	v_pk_mul_f32 v[20:21], v[64:65], v[82:83]
	v_mul_f32_e32 v19, 0x3f317217, v24
	v_add_f32_e32 v20, v20, v22
	v_add_f32_e32 v21, v21, v20
	v_mul_f32_e64 v20, |v21|, s29
	v_exp_f32_e32 v20, v20
	v_fma_f32 v19, v24, s31, -v19
	v_fmac_f32_e32 v19, 0x3377d1cf, v24
	v_fmac_f32_e32 v19, 0x3f317217, v24
	v_cmp_lt_f32_e64 s[0:1], |v24|, s34
	v_add_f32_e32 v20, 1.0, v20
	s_nop 0
	v_cndmask_b32_e64 v19, v24, v19, s[0:1]
	v_cmp_gt_f32_e64 s[0:1], s30, v20
	s_nop 1
	v_cndmask_b32_e64 v22, 0, 32, s[0:1]
	v_ldexp_f32 v20, v20, v22
	v_log_f32_e32 v22, v20
	v_cndmask_b32_e32 v20, 0, v112, vcc
	v_sub_f32_e32 v20, v19, v20
	v_min_f32_e32 v19, 0, v21
	v_mul_f32_e32 v21, 0x3f317217, v22
	v_fma_f32 v21, v22, s31, -v21
	v_fmac_f32_e32 v21, 0x3377d1cf, v22
	v_fmac_f32_e32 v21, 0x3f317217, v22
	v_cmp_lt_f32_e64 vcc, |v22|, s34
	s_nop 1
	v_cndmask_b32_e32 v21, v22, v21, vcc
	v_cndmask_b32_e64 v22, 0, v112, s[0:1]
	v_sub_f32_e32 v21, v21, v22
	v_pk_add_f32 v[18:19], v[18:19], v[20:21] neg_lo:[0,1] neg_hi:[0,1]
	s_nop 0
	v_pk_mul_f32 v[86:87], v[18:19], s[10:11] op_sel_hi:[1,0]
	global_load_dwordx4 v[18:21], v123, s[48:49] offset:544
	global_load_dwordx4 v[22:25], v123, s[4:5] offset:32
	global_load_dwordx4 v[26:29], v123, s[4:5] offset:3104
	global_load_dwordx4 v[30:33], v123, s[4:5] offset:3616
	global_load_dwordx4 v[34:37], v111, s[12:13] offset:32
	global_load_dwordx4 v[38:41], v111, s[12:13] offset:544
	global_load_dwordx4 v[42:45], v111, s[12:13] offset:1056
	global_load_dwordx4 v[46:49], v111, s[12:13] offset:1568
	global_load_dwordx4 v[50:53], v111, s[12:13] offset:2080
	global_load_dwordx4 v[54:57], v111, s[12:13] offset:2592
	global_load_dwordx4 v[58:61], v111, s[12:13] offset:3104
	global_load_dwordx4 v[62:65], v111, s[12:13] offset:3616
	global_load_dwordx4 v[88:91], v123, s[4:5] offset:544
	global_load_dwordx4 v[92:95], v123, s[4:5] offset:1056
	global_load_dwordx4 v[96:99], v123, s[4:5] offset:1568
	global_load_dwordx4 v[100:103], v123, s[4:5] offset:2080
	global_load_dwordx4 v[104:107], v123, s[4:5] offset:2592
	s_waitcnt vmcnt(15)
	v_fma_f32 v134, v22, v118, v18
	v_fma_f32 v20, v24, v118, v20
	s_waitcnt vmcnt(14)
	v_mov_b32_e32 v124, v26
	s_waitcnt vmcnt(13)
	v_mov_b32_e32 v125, v30
	v_fma_f32 v23, v23, v118, v19
	v_mov_b32_e32 v30, v27
	v_mov_b32_e32 v18, v28
	v_mov_b32_e32 v19, v32
	v_pk_mul_f32 v[26:27], v[124:125], v[72:73]
	s_waitcnt vmcnt(12)
	v_mov_b32_e32 v126, v34
	s_waitcnt vmcnt(11)
	v_mov_b32_e32 v127, v38
	s_waitcnt vmcnt(4)
	v_fmac_f32_e32 v134, v88, v117
	v_fmac_f32_e32 v20, v90, v117
	s_waitcnt vmcnt(3)
	v_fmac_f32_e32 v134, v92, v122
	v_fmac_f32_e32 v20, v94, v122
	s_waitcnt vmcnt(2)
	v_fmac_f32_e32 v134, v96, v121
	v_fmac_f32_e32 v20, v98, v121
	s_waitcnt vmcnt(1)
	v_fmac_f32_e32 v134, v100, v120
	v_fmac_f32_e32 v20, v102, v120
	s_waitcnt vmcnt(0)
	v_fmac_f32_e32 v134, v104, v119
	v_fmac_f32_e32 v23, v89, v117
	v_pk_mul_f32 v[18:19], v[18:19], v[72:73]
	v_fmac_f32_e32 v20, v106, v119
	v_add_f32_e32 v24, v134, v26
	v_mov_b32_e32 v38, v35
	v_pk_mul_f32 v[34:35], v[126:127], v[74:75]
	v_fmac_f32_e32 v23, v93, v122
	v_add_f32_e32 v18, v18, v20
	v_add_f32_e32 v20, v24, v27
	v_mov_b32_e32 v128, v42
	v_mov_b32_e32 v129, v46
	v_fmac_f32_e32 v23, v97, v121
	v_add_f32_e32 v20, v20, v34
	v_mov_b32_e32 v46, v43
	v_pk_mul_f32 v[42:43], v[128:129], v[78:79]
	v_fmac_f32_e32 v23, v101, v120
	v_add_f32_e32 v20, v20, v35
	v_mov_b32_e32 v130, v50
	v_mov_b32_e32 v131, v54
	v_pk_mul_f32 v[30:31], v[30:31], v[72:73]
	v_fmac_f32_e32 v23, v105, v119
	v_add_f32_e32 v20, v20, v42
	v_mov_b32_e32 v54, v51
	v_pk_mul_f32 v[50:51], v[130:131], v[80:81]
	v_add_f32_e32 v23, v30, v23
	v_add_f32_e32 v20, v20, v43
	v_mov_b32_e32 v132, v58
	v_mov_b32_e32 v133, v62
	v_pk_mul_f32 v[38:39], v[38:39], v[74:75]
	v_add_f32_e32 v23, v31, v23
	v_add_f32_e32 v20, v20, v50
	v_mov_b32_e32 v62, v59
	v_pk_mul_f32 v[58:59], v[132:133], v[82:83]
	v_add_f32_e32 v23, v38, v23
	v_add_f32_e32 v20, v20, v51
	v_pk_mul_f32 v[46:47], v[46:47], v[78:79]
	v_add_f32_e32 v23, v39, v23
	v_add_f32_e32 v20, v20, v58
	v_add_f32_e32 v23, v46, v23
	v_add_f32_e32 v20, v20, v59
	v_pk_mul_f32 v[54:55], v[54:55], v[80:81]
	v_add_f32_e32 v23, v47, v23
	v_mul_f32_e64 v24, |v20|, s29
	v_add_f32_e32 v23, v54, v23
	v_exp_f32_e32 v24, v24
	v_pk_mul_f32 v[62:63], v[62:63], v[82:83]
	v_add_f32_e32 v23, v55, v23
	v_add_f32_e32 v23, v62, v23
	v_add_f32_e32 v23, v63, v23
	v_mul_f32_e64 v26, |v23|, s29
	v_add_f32_e32 v27, v19, v18
	v_add_f32_e32 v19, 1.0, v24
	v_exp_f32_e32 v26, v26
	v_cmp_gt_f32_e32 vcc, s30, v19
	v_min_f32_e32 v18, 0, v20
	v_mov_b32_e32 v22, v36
	v_cndmask_b32_e64 v24, 0, 32, vcc
	v_ldexp_f32 v19, v19, v24
	v_log_f32_e32 v24, v19
	v_add_f32_e32 v20, 1.0, v26
	v_cmp_gt_f32_e64 s[0:1], s30, v20
	v_min_f32_e32 v19, 0, v23
	v_cndmask_b32_e32 v23, 0, v112, vcc
	v_cndmask_b32_e64 v26, 0, 32, s[0:1]
	v_ldexp_f32 v20, v20, v26
	v_mul_f32_e32 v26, 0x3f317217, v24
	v_fma_f32 v26, v24, s31, -v26
	v_fmac_f32_e32 v26, 0x3377d1cf, v24
	v_fmac_f32_e32 v26, 0x3f317217, v24
	v_cmp_lt_f32_e64 vcc, |v24|, s34
	v_log_f32_e32 v20, v20
	v_fmac_f32_e32 v21, v25, v118
	v_cndmask_b32_e32 v24, v24, v26, vcc
	v_sub_f32_e32 v26, v24, v23
	v_mov_b32_e32 v23, v40
	v_pk_mul_f32 v[22:23], v[22:23], v[74:75]
	v_mul_f32_e32 v28, 0x3f317217, v20
	v_add_f32_e32 v22, v22, v27
	v_add_f32_e32 v24, v23, v22
	v_mov_b32_e32 v22, v44
	v_mov_b32_e32 v23, v48
	v_pk_mul_f32 v[22:23], v[22:23], v[78:79]
	v_fma_f32 v28, v20, s31, -v28
	v_add_f32_e32 v22, v22, v24
	v_add_f32_e32 v24, v23, v22
	v_mov_b32_e32 v22, v52
	v_mov_b32_e32 v23, v56
	v_pk_mul_f32 v[22:23], v[22:23], v[80:81]
	v_fmac_f32_e32 v28, 0x3377d1cf, v20
	v_add_f32_e32 v22, v22, v24
	v_add_f32_e32 v24, v23, v22
	v_mov_b32_e32 v22, v60
	v_mov_b32_e32 v23, v64
	v_pk_mul_f32 v[22:23], v[22:23], v[82:83]
	v_fmac_f32_e32 v28, 0x3f317217, v20
	v_add_f32_e32 v22, v22, v24
	v_add_f32_e32 v22, v23, v22
	v_mul_f32_e64 v23, |v22|, s29
	v_exp_f32_e32 v23, v23
	v_cmp_lt_f32_e64 vcc, |v20|, s34
	v_cndmask_b32_e64 v24, 0, v112, s[0:1]
	v_fmac_f32_e32 v21, v91, v117
	v_cndmask_b32_e32 v20, v20, v28, vcc
	v_sub_f32_e32 v27, v20, v24
	v_add_f32_e32 v20, 1.0, v23
	v_fmac_f32_e32 v21, v95, v122
	v_cmp_gt_f32_e32 vcc, s30, v20
	v_fmac_f32_e32 v21, v99, v121
	v_pk_add_f32 v[18:19], v[18:19], v[26:27] neg_lo:[0,1] neg_hi:[0,1]
	v_cndmask_b32_e64 v23, 0, 32, vcc
	v_fmac_f32_e32 v21, v103, v120
	v_mov_b32_e32 v32, v29
	v_ldexp_f32 v20, v20, v23
	v_pk_mul_f32 v[88:89], v[18:19], s[10:11] op_sel_hi:[1,0]
	v_min_f32_e32 v18, 0, v22
	v_fmac_f32_e32 v21, v107, v119
	v_pk_mul_f32 v[22:23], v[32:33], v[72:73]
	v_log_f32_e32 v24, v20
	v_add_f32_e32 v20, v22, v21
	v_mov_b32_e32 v40, v37
	v_add_f32_e32 v22, v23, v20
	v_pk_mul_f32 v[20:21], v[40:41], v[74:75]
	v_mov_b32_e32 v48, v45
	v_add_f32_e32 v20, v20, v22
	v_add_f32_e32 v22, v21, v20
	v_pk_mul_f32 v[20:21], v[48:49], v[78:79]
	v_mov_b32_e32 v56, v53
	v_add_f32_e32 v20, v20, v22
	v_add_f32_e32 v22, v21, v20
	v_pk_mul_f32 v[20:21], v[56:57], v[80:81]
	v_mov_b32_e32 v64, v61
	v_add_f32_e32 v20, v20, v22
	v_add_f32_e32 v22, v21, v20
	v_pk_mul_f32 v[20:21], v[64:65], v[82:83]
	v_mul_f32_e32 v19, 0x3f317217, v24
	v_add_f32_e32 v20, v20, v22
	v_add_f32_e32 v21, v21, v20
	v_mul_f32_e64 v20, |v21|, s29
	v_exp_f32_e32 v20, v20
	v_fma_f32 v19, v24, s31, -v19
	v_fmac_f32_e32 v19, 0x3377d1cf, v24
	v_fmac_f32_e32 v19, 0x3f317217, v24
	v_cmp_lt_f32_e64 s[0:1], |v24|, s34
	v_add_f32_e32 v20, 1.0, v20
	s_nop 0
	v_cndmask_b32_e64 v19, v24, v19, s[0:1]
	v_cmp_gt_f32_e64 s[0:1], s30, v20
	s_nop 1
	v_cndmask_b32_e64 v22, 0, 32, s[0:1]
	v_ldexp_f32 v20, v20, v22
	v_log_f32_e32 v22, v20
	v_cndmask_b32_e32 v20, 0, v112, vcc
	v_sub_f32_e32 v20, v19, v20
	v_min_f32_e32 v19, 0, v21
	v_mul_f32_e32 v21, 0x3f317217, v22
	v_fma_f32 v21, v22, s31, -v21
	v_fmac_f32_e32 v21, 0x3377d1cf, v22
	v_fmac_f32_e32 v21, 0x3f317217, v22
	v_cmp_lt_f32_e64 vcc, |v22|, s34
	s_nop 1
	v_cndmask_b32_e32 v21, v22, v21, vcc
	v_cndmask_b32_e64 v22, 0, v112, s[0:1]
	v_sub_f32_e32 v21, v21, v22
	v_pk_add_f32 v[18:19], v[18:19], v[20:21] neg_lo:[0,1] neg_hi:[0,1]
	s_nop 0
	v_pk_mul_f32 v[90:91], v[18:19], s[10:11] op_sel_hi:[1,0]
	global_load_dwordx4 v[18:21], v123, s[48:49] offset:560
	global_load_dwordx4 v[22:25], v123, s[4:5] offset:48
	global_load_dwordx4 v[26:29], v123, s[4:5] offset:3120
	global_load_dwordx4 v[30:33], v123, s[4:5] offset:3632
	global_load_dwordx4 v[34:37], v111, s[12:13] offset:48
	global_load_dwordx4 v[38:41], v111, s[12:13] offset:560
	global_load_dwordx4 v[42:45], v111, s[12:13] offset:1072
	global_load_dwordx4 v[46:49], v111, s[12:13] offset:1584
	global_load_dwordx4 v[50:53], v111, s[12:13] offset:2096
	global_load_dwordx4 v[54:57], v111, s[12:13] offset:2608
	global_load_dwordx4 v[58:61], v111, s[12:13] offset:3120
	global_load_dwordx4 v[62:65], v111, s[12:13] offset:3632
	global_load_dwordx4 v[92:95], v123, s[4:5] offset:560
	global_load_dwordx4 v[96:99], v123, s[4:5] offset:1072
	global_load_dwordx4 v[100:103], v123, s[4:5] offset:1584
	global_load_dwordx4 v[104:107], v123, s[4:5] offset:2096
	global_load_dwordx4 v[124:127], v123, s[4:5] offset:2608
	s_waitcnt vmcnt(15)
	v_fma_f32 v138, v22, v118, v18
	v_fma_f32 v20, v24, v118, v20
	s_waitcnt vmcnt(14)
	v_mov_b32_e32 v128, v26
	s_waitcnt vmcnt(13)
	v_mov_b32_e32 v129, v30
	v_fma_f32 v23, v23, v118, v19
	v_mov_b32_e32 v30, v27
	v_mov_b32_e32 v18, v28
	v_mov_b32_e32 v19, v32
	v_pk_mul_f32 v[26:27], v[128:129], v[72:73]
	s_waitcnt vmcnt(12)
	v_mov_b32_e32 v130, v34
	s_waitcnt vmcnt(11)
	v_mov_b32_e32 v131, v38
	s_waitcnt vmcnt(4)
	v_fmac_f32_e32 v138, v92, v117
	v_fmac_f32_e32 v20, v94, v117
	s_waitcnt vmcnt(3)
	v_fmac_f32_e32 v138, v96, v122
	v_fmac_f32_e32 v20, v98, v122
	s_waitcnt vmcnt(2)
	v_fmac_f32_e32 v138, v100, v121
	v_fmac_f32_e32 v20, v102, v121
	s_waitcnt vmcnt(1)
	v_fmac_f32_e32 v138, v104, v120
	v_fmac_f32_e32 v20, v106, v120
	s_waitcnt vmcnt(0)
	v_fmac_f32_e32 v138, v124, v119
	v_fmac_f32_e32 v23, v93, v117
	v_pk_mul_f32 v[18:19], v[18:19], v[72:73]
	v_fmac_f32_e32 v20, v126, v119
	v_add_f32_e32 v24, v138, v26
	v_mov_b32_e32 v38, v35
	v_pk_mul_f32 v[34:35], v[130:131], v[74:75]
	v_fmac_f32_e32 v23, v97, v122
	v_add_f32_e32 v18, v18, v20
	v_add_f32_e32 v20, v24, v27
	v_mov_b32_e32 v132, v42
	v_mov_b32_e32 v133, v46
	v_fmac_f32_e32 v23, v101, v121
	v_add_f32_e32 v20, v20, v34
	v_mov_b32_e32 v46, v43
	v_pk_mul_f32 v[42:43], v[132:133], v[78:79]
	v_fmac_f32_e32 v23, v105, v120
	v_add_f32_e32 v20, v20, v35
	v_mov_b32_e32 v134, v50
	v_mov_b32_e32 v135, v54
	v_pk_mul_f32 v[30:31], v[30:31], v[72:73]
	v_fmac_f32_e32 v23, v125, v119
	v_add_f32_e32 v20, v20, v42
	v_mov_b32_e32 v54, v51
	v_pk_mul_f32 v[50:51], v[134:135], v[80:81]
	v_add_f32_e32 v23, v30, v23
	v_add_f32_e32 v20, v20, v43
	v_mov_b32_e32 v136, v58
	v_mov_b32_e32 v137, v62
	v_pk_mul_f32 v[38:39], v[38:39], v[74:75]
	v_add_f32_e32 v23, v31, v23
	v_add_f32_e32 v20, v20, v50
	v_mov_b32_e32 v62, v59
	v_pk_mul_f32 v[58:59], v[136:137], v[82:83]
	v_add_f32_e32 v23, v38, v23
	v_add_f32_e32 v20, v20, v51
	v_pk_mul_f32 v[46:47], v[46:47], v[78:79]
	v_add_f32_e32 v23, v39, v23
	v_add_f32_e32 v20, v20, v58
	v_add_f32_e32 v23, v46, v23
	v_add_f32_e32 v20, v20, v59
	v_pk_mul_f32 v[54:55], v[54:55], v[80:81]
	v_add_f32_e32 v23, v47, v23
	v_mul_f32_e64 v24, |v20|, s29
	v_add_f32_e32 v23, v54, v23
	v_exp_f32_e32 v24, v24
	v_pk_mul_f32 v[62:63], v[62:63], v[82:83]
	v_add_f32_e32 v23, v55, v23
	v_add_f32_e32 v23, v62, v23
	v_add_f32_e32 v23, v63, v23
	v_mul_f32_e64 v26, |v23|, s29
	v_add_f32_e32 v27, v19, v18
	v_add_f32_e32 v19, 1.0, v24
	v_exp_f32_e32 v26, v26
	v_cmp_gt_f32_e32 vcc, s30, v19
	v_min_f32_e32 v18, 0, v20
	v_mov_b32_e32 v22, v36
	v_cndmask_b32_e64 v24, 0, 32, vcc
	v_ldexp_f32 v19, v19, v24
	v_log_f32_e32 v24, v19
	v_add_f32_e32 v20, 1.0, v26
	v_cmp_gt_f32_e64 s[0:1], s30, v20
	v_min_f32_e32 v19, 0, v23
	v_cndmask_b32_e32 v23, 0, v112, vcc
	v_cndmask_b32_e64 v26, 0, 32, s[0:1]
	v_ldexp_f32 v20, v20, v26
	v_mul_f32_e32 v26, 0x3f317217, v24
	v_fma_f32 v26, v24, s31, -v26
	v_fmac_f32_e32 v26, 0x3377d1cf, v24
	v_fmac_f32_e32 v26, 0x3f317217, v24
	v_cmp_lt_f32_e64 vcc, |v24|, s34
	v_log_f32_e32 v20, v20
	v_fmac_f32_e32 v21, v25, v118
	v_cndmask_b32_e32 v24, v24, v26, vcc
	v_sub_f32_e32 v26, v24, v23
	v_mov_b32_e32 v23, v40
	v_pk_mul_f32 v[22:23], v[22:23], v[74:75]
	v_mul_f32_e32 v28, 0x3f317217, v20
	v_add_f32_e32 v22, v22, v27
	v_add_f32_e32 v24, v23, v22
	v_mov_b32_e32 v22, v44
	v_mov_b32_e32 v23, v48
	v_pk_mul_f32 v[22:23], v[22:23], v[78:79]
	v_fma_f32 v28, v20, s31, -v28
	v_add_f32_e32 v22, v22, v24
	v_add_f32_e32 v24, v23, v22
	v_mov_b32_e32 v22, v52
	v_mov_b32_e32 v23, v56
	v_pk_mul_f32 v[22:23], v[22:23], v[80:81]
	v_fmac_f32_e32 v28, 0x3377d1cf, v20
	v_add_f32_e32 v22, v22, v24
	v_add_f32_e32 v24, v23, v22
	v_mov_b32_e32 v22, v60
	v_mov_b32_e32 v23, v64
	v_pk_mul_f32 v[22:23], v[22:23], v[82:83]
	v_fmac_f32_e32 v28, 0x3f317217, v20
	v_add_f32_e32 v22, v22, v24
	v_add_f32_e32 v22, v23, v22
	v_mul_f32_e64 v23, |v22|, s29
	v_exp_f32_e32 v23, v23
	v_cmp_lt_f32_e64 vcc, |v20|, s34
	v_cndmask_b32_e64 v24, 0, v112, s[0:1]
	v_fmac_f32_e32 v21, v95, v117
	v_cndmask_b32_e32 v20, v20, v28, vcc
	v_sub_f32_e32 v27, v20, v24
	v_add_f32_e32 v20, 1.0, v23
	v_fmac_f32_e32 v21, v99, v122
	v_cmp_gt_f32_e32 vcc, s30, v20
	v_fmac_f32_e32 v21, v103, v121
	v_pk_add_f32 v[18:19], v[18:19], v[26:27] neg_lo:[0,1] neg_hi:[0,1]
	v_cndmask_b32_e64 v23, 0, 32, vcc
	v_fmac_f32_e32 v21, v107, v120
	v_mov_b32_e32 v32, v29
	v_ldexp_f32 v20, v20, v23
	v_pk_mul_f32 v[92:93], v[18:19], s[10:11] op_sel_hi:[1,0]
	v_min_f32_e32 v18, 0, v22
	v_fmac_f32_e32 v21, v127, v119
	v_pk_mul_f32 v[22:23], v[32:33], v[72:73]
	v_log_f32_e32 v24, v20
	v_add_f32_e32 v20, v22, v21
	v_mov_b32_e32 v40, v37
	v_add_f32_e32 v22, v23, v20
	v_pk_mul_f32 v[20:21], v[40:41], v[74:75]
	v_mov_b32_e32 v48, v45
	v_add_f32_e32 v20, v20, v22
	v_add_f32_e32 v22, v21, v20
	v_pk_mul_f32 v[20:21], v[48:49], v[78:79]
	v_mov_b32_e32 v56, v53
	v_add_f32_e32 v20, v20, v22
	v_add_f32_e32 v22, v21, v20
	v_pk_mul_f32 v[20:21], v[56:57], v[80:81]
	v_mov_b32_e32 v64, v61
	v_add_f32_e32 v20, v20, v22
	v_add_f32_e32 v22, v21, v20
	v_pk_mul_f32 v[20:21], v[64:65], v[82:83]
	v_mul_f32_e32 v19, 0x3f317217, v24
	v_add_f32_e32 v20, v20, v22
	v_add_f32_e32 v21, v21, v20
	v_mul_f32_e64 v20, |v21|, s29
	v_exp_f32_e32 v20, v20
	v_fma_f32 v19, v24, s31, -v19
	v_fmac_f32_e32 v19, 0x3377d1cf, v24
	v_fmac_f32_e32 v19, 0x3f317217, v24
	v_cmp_lt_f32_e64 s[0:1], |v24|, s34
	v_add_f32_e32 v20, 1.0, v20
	s_nop 0
	v_cndmask_b32_e64 v19, v24, v19, s[0:1]
	v_cmp_gt_f32_e64 s[0:1], s30, v20
	s_nop 1
	v_cndmask_b32_e64 v22, 0, 32, s[0:1]
	v_ldexp_f32 v20, v20, v22
	v_log_f32_e32 v22, v20
	v_cndmask_b32_e32 v20, 0, v112, vcc
	v_sub_f32_e32 v20, v19, v20
	v_min_f32_e32 v19, 0, v21
	v_mul_f32_e32 v21, 0x3f317217, v22
	v_fma_f32 v21, v22, s31, -v21
	v_fmac_f32_e32 v21, 0x3377d1cf, v22
	v_fmac_f32_e32 v21, 0x3f317217, v22
	v_cmp_lt_f32_e64 vcc, |v22|, s34
	s_nop 1
	v_cndmask_b32_e32 v21, v22, v21, vcc
	v_cndmask_b32_e64 v22, 0, v112, s[0:1]
	v_sub_f32_e32 v21, v21, v22
	v_pk_add_f32 v[18:19], v[18:19], v[20:21] neg_lo:[0,1] neg_hi:[0,1]
	s_nop 0
	v_pk_mul_f32 v[94:95], v[18:19], s[10:11] op_sel_hi:[1,0]
	global_load_dwordx4 v[18:21], v123, s[48:49] offset:576
	global_load_dwordx4 v[22:25], v123, s[4:5] offset:64
	global_load_dwordx4 v[26:29], v123, s[4:5] offset:3136
	global_load_dwordx4 v[30:33], v123, s[4:5] offset:3648
	global_load_dwordx4 v[34:37], v111, s[12:13] offset:64
	global_load_dwordx4 v[38:41], v111, s[12:13] offset:576
	global_load_dwordx4 v[42:45], v111, s[12:13] offset:1088
	global_load_dwordx4 v[46:49], v111, s[12:13] offset:1600
	global_load_dwordx4 v[50:53], v111, s[12:13] offset:2112
	global_load_dwordx4 v[54:57], v111, s[12:13] offset:2624
	global_load_dwordx4 v[58:61], v111, s[12:13] offset:3136
	global_load_dwordx4 v[62:65], v111, s[12:13] offset:3648
	global_load_dwordx4 v[96:99], v123, s[4:5] offset:576
	global_load_dwordx4 v[100:103], v123, s[4:5] offset:1088
	global_load_dwordx4 v[104:107], v123, s[4:5] offset:1600
	global_load_dwordx4 v[124:127], v123, s[4:5] offset:2112
	global_load_dwordx4 v[128:131], v123, s[4:5] offset:2624
	s_waitcnt vmcnt(15)
	v_fma_f32 v142, v22, v118, v18
	v_fma_f32 v20, v24, v118, v20
	s_waitcnt vmcnt(14)
	v_mov_b32_e32 v132, v26
	s_waitcnt vmcnt(13)
	v_mov_b32_e32 v133, v30
	v_fma_f32 v23, v23, v118, v19
	v_mov_b32_e32 v30, v27
	v_mov_b32_e32 v18, v28
	v_mov_b32_e32 v19, v32
	v_pk_mul_f32 v[26:27], v[132:133], v[72:73]
	s_waitcnt vmcnt(12)
	v_mov_b32_e32 v134, v34
	s_waitcnt vmcnt(11)
	v_mov_b32_e32 v135, v38
	s_waitcnt vmcnt(4)
	v_fmac_f32_e32 v142, v96, v117
	v_fmac_f32_e32 v20, v98, v117
	s_waitcnt vmcnt(3)
	v_fmac_f32_e32 v142, v100, v122
	v_fmac_f32_e32 v20, v102, v122
	s_waitcnt vmcnt(2)
	v_fmac_f32_e32 v142, v104, v121
	v_fmac_f32_e32 v20, v106, v121
	s_waitcnt vmcnt(1)
	v_fmac_f32_e32 v142, v124, v120
	v_fmac_f32_e32 v20, v126, v120
	s_waitcnt vmcnt(0)
	v_fmac_f32_e32 v142, v128, v119
	v_fmac_f32_e32 v23, v97, v117
	v_pk_mul_f32 v[18:19], v[18:19], v[72:73]
	v_fmac_f32_e32 v20, v130, v119
	v_add_f32_e32 v24, v142, v26
	v_mov_b32_e32 v38, v35
	v_pk_mul_f32 v[34:35], v[134:135], v[74:75]
	v_fmac_f32_e32 v23, v101, v122
	v_add_f32_e32 v18, v18, v20
	v_add_f32_e32 v20, v24, v27
	v_mov_b32_e32 v136, v42
	v_mov_b32_e32 v137, v46
	v_fmac_f32_e32 v23, v105, v121
	v_add_f32_e32 v20, v20, v34
	v_mov_b32_e32 v46, v43
	v_pk_mul_f32 v[42:43], v[136:137], v[78:79]
	v_fmac_f32_e32 v23, v125, v120
	v_add_f32_e32 v20, v20, v35
	v_mov_b32_e32 v138, v50
	v_mov_b32_e32 v139, v54
	v_pk_mul_f32 v[30:31], v[30:31], v[72:73]
	v_fmac_f32_e32 v23, v129, v119
	v_add_f32_e32 v20, v20, v42
	v_mov_b32_e32 v54, v51
	v_pk_mul_f32 v[50:51], v[138:139], v[80:81]
	v_add_f32_e32 v23, v30, v23
	v_add_f32_e32 v20, v20, v43
	v_mov_b32_e32 v140, v58
	v_mov_b32_e32 v141, v62
	v_pk_mul_f32 v[38:39], v[38:39], v[74:75]
	v_add_f32_e32 v23, v31, v23
	v_add_f32_e32 v20, v20, v50
	v_mov_b32_e32 v62, v59
	v_pk_mul_f32 v[58:59], v[140:141], v[82:83]
	v_add_f32_e32 v23, v38, v23
	v_add_f32_e32 v20, v20, v51
	v_pk_mul_f32 v[46:47], v[46:47], v[78:79]
	v_add_f32_e32 v23, v39, v23
	v_add_f32_e32 v20, v20, v58
	v_add_f32_e32 v23, v46, v23
	v_add_f32_e32 v20, v20, v59
	v_pk_mul_f32 v[54:55], v[54:55], v[80:81]
	v_add_f32_e32 v23, v47, v23
	v_mul_f32_e64 v24, |v20|, s29
	v_add_f32_e32 v23, v54, v23
	v_exp_f32_e32 v24, v24
	v_pk_mul_f32 v[62:63], v[62:63], v[82:83]
	v_add_f32_e32 v23, v55, v23
	v_add_f32_e32 v23, v62, v23
	v_add_f32_e32 v23, v63, v23
	v_mul_f32_e64 v26, |v23|, s29
	v_add_f32_e32 v27, v19, v18
	v_add_f32_e32 v19, 1.0, v24
	v_exp_f32_e32 v26, v26
	v_cmp_gt_f32_e32 vcc, s30, v19
	v_min_f32_e32 v18, 0, v20
	v_mov_b32_e32 v22, v36
	v_cndmask_b32_e64 v24, 0, 32, vcc
	v_ldexp_f32 v19, v19, v24
	v_log_f32_e32 v24, v19
	v_add_f32_e32 v20, 1.0, v26
	v_cmp_gt_f32_e64 s[0:1], s30, v20
	v_min_f32_e32 v19, 0, v23
	v_cndmask_b32_e32 v23, 0, v112, vcc
	v_cndmask_b32_e64 v26, 0, 32, s[0:1]
	v_ldexp_f32 v20, v20, v26
	v_mul_f32_e32 v26, 0x3f317217, v24
	v_fma_f32 v26, v24, s31, -v26
	v_fmac_f32_e32 v26, 0x3377d1cf, v24
	v_fmac_f32_e32 v26, 0x3f317217, v24
	v_cmp_lt_f32_e64 vcc, |v24|, s34
	v_log_f32_e32 v20, v20
	v_fmac_f32_e32 v21, v25, v118
	v_cndmask_b32_e32 v24, v24, v26, vcc
	v_sub_f32_e32 v26, v24, v23
	v_mov_b32_e32 v23, v40
	v_pk_mul_f32 v[22:23], v[22:23], v[74:75]
	v_mul_f32_e32 v28, 0x3f317217, v20
	v_add_f32_e32 v22, v22, v27
	v_add_f32_e32 v24, v23, v22
	v_mov_b32_e32 v22, v44
	v_mov_b32_e32 v23, v48
	v_pk_mul_f32 v[22:23], v[22:23], v[78:79]
	v_fma_f32 v28, v20, s31, -v28
	v_add_f32_e32 v22, v22, v24
	v_add_f32_e32 v24, v23, v22
	v_mov_b32_e32 v22, v52
	v_mov_b32_e32 v23, v56
	v_pk_mul_f32 v[22:23], v[22:23], v[80:81]
	v_fmac_f32_e32 v28, 0x3377d1cf, v20
	v_add_f32_e32 v22, v22, v24
	v_add_f32_e32 v24, v23, v22
	v_mov_b32_e32 v22, v60
	v_mov_b32_e32 v23, v64
	v_pk_mul_f32 v[22:23], v[22:23], v[82:83]
	v_fmac_f32_e32 v28, 0x3f317217, v20
	v_add_f32_e32 v22, v22, v24
	v_add_f32_e32 v22, v23, v22
	v_mul_f32_e64 v23, |v22|, s29
	v_exp_f32_e32 v23, v23
	v_cmp_lt_f32_e64 vcc, |v20|, s34
	v_cndmask_b32_e64 v24, 0, v112, s[0:1]
	v_fmac_f32_e32 v21, v99, v117
	v_cndmask_b32_e32 v20, v20, v28, vcc
	v_sub_f32_e32 v27, v20, v24
	v_add_f32_e32 v20, 1.0, v23
	v_fmac_f32_e32 v21, v103, v122
	v_cmp_gt_f32_e32 vcc, s30, v20
	v_fmac_f32_e32 v21, v107, v121
	v_pk_add_f32 v[18:19], v[18:19], v[26:27] neg_lo:[0,1] neg_hi:[0,1]
	v_cndmask_b32_e64 v23, 0, 32, vcc
	v_fmac_f32_e32 v21, v127, v120
	v_mov_b32_e32 v32, v29
	v_ldexp_f32 v20, v20, v23
	v_pk_mul_f32 v[96:97], v[18:19], s[10:11] op_sel_hi:[1,0]
	v_min_f32_e32 v18, 0, v22
	v_fmac_f32_e32 v21, v131, v119
	v_pk_mul_f32 v[22:23], v[32:33], v[72:73]
	v_log_f32_e32 v24, v20
	v_add_f32_e32 v20, v22, v21
	v_mov_b32_e32 v40, v37
	v_add_f32_e32 v22, v23, v20
	v_pk_mul_f32 v[20:21], v[40:41], v[74:75]
	v_mov_b32_e32 v48, v45
	v_add_f32_e32 v20, v20, v22
	v_add_f32_e32 v22, v21, v20
	v_pk_mul_f32 v[20:21], v[48:49], v[78:79]
	v_mov_b32_e32 v56, v53
	v_add_f32_e32 v20, v20, v22
	v_add_f32_e32 v22, v21, v20
	v_pk_mul_f32 v[20:21], v[56:57], v[80:81]
	v_mov_b32_e32 v64, v61
	v_add_f32_e32 v20, v20, v22
	v_add_f32_e32 v22, v21, v20
	v_pk_mul_f32 v[20:21], v[64:65], v[82:83]
	v_mul_f32_e32 v19, 0x3f317217, v24
	v_add_f32_e32 v20, v20, v22
	v_add_f32_e32 v21, v21, v20
	v_mul_f32_e64 v20, |v21|, s29
	v_exp_f32_e32 v20, v20
	v_fma_f32 v19, v24, s31, -v19
	v_fmac_f32_e32 v19, 0x3377d1cf, v24
	v_fmac_f32_e32 v19, 0x3f317217, v24
	v_cmp_lt_f32_e64 s[0:1], |v24|, s34
	v_add_f32_e32 v20, 1.0, v20
	s_nop 0
	v_cndmask_b32_e64 v19, v24, v19, s[0:1]
	v_cmp_gt_f32_e64 s[0:1], s30, v20
	s_nop 1
	v_cndmask_b32_e64 v22, 0, 32, s[0:1]
	v_ldexp_f32 v20, v20, v22
	v_log_f32_e32 v22, v20
	v_cndmask_b32_e32 v20, 0, v112, vcc
	v_sub_f32_e32 v20, v19, v20
	v_min_f32_e32 v19, 0, v21
	v_mul_f32_e32 v21, 0x3f317217, v22
	v_fma_f32 v21, v22, s31, -v21
	v_fmac_f32_e32 v21, 0x3377d1cf, v22
	v_fmac_f32_e32 v21, 0x3f317217, v22
	v_cmp_lt_f32_e64 vcc, |v22|, s34
	s_nop 1
	v_cndmask_b32_e32 v21, v22, v21, vcc
	v_cndmask_b32_e64 v22, 0, v112, s[0:1]
	v_sub_f32_e32 v21, v21, v22
	v_pk_add_f32 v[18:19], v[18:19], v[20:21] neg_lo:[0,1] neg_hi:[0,1]
	s_nop 0
	v_pk_mul_f32 v[98:99], v[18:19], s[10:11] op_sel_hi:[1,0]
	global_load_dwordx4 v[18:21], v123, s[48:49] offset:592
	global_load_dwordx4 v[22:25], v123, s[4:5] offset:80
	global_load_dwordx4 v[26:29], v123, s[4:5] offset:3152
	global_load_dwordx4 v[30:33], v123, s[4:5] offset:3664
	global_load_dwordx4 v[34:37], v111, s[12:13] offset:80
	global_load_dwordx4 v[38:41], v111, s[12:13] offset:592
	global_load_dwordx4 v[42:45], v111, s[12:13] offset:1104
	global_load_dwordx4 v[46:49], v111, s[12:13] offset:1616
	global_load_dwordx4 v[50:53], v111, s[12:13] offset:2128
	global_load_dwordx4 v[54:57], v111, s[12:13] offset:2640
	global_load_dwordx4 v[58:61], v111, s[12:13] offset:3152
	global_load_dwordx4 v[62:65], v111, s[12:13] offset:3664
	global_load_dwordx4 v[100:103], v123, s[4:5] offset:592
	global_load_dwordx4 v[104:107], v123, s[4:5] offset:1104
	global_load_dwordx4 v[124:127], v123, s[4:5] offset:1616
	global_load_dwordx4 v[128:131], v123, s[4:5] offset:2128
	global_load_dwordx4 v[132:135], v123, s[4:5] offset:2640
	s_waitcnt vmcnt(15)
	v_fma_f32 v146, v22, v118, v18
	v_fma_f32 v20, v24, v118, v20
	s_waitcnt vmcnt(14)
	v_mov_b32_e32 v136, v26
	s_waitcnt vmcnt(13)
	v_mov_b32_e32 v137, v30
	v_fma_f32 v23, v23, v118, v19
	v_mov_b32_e32 v30, v27
	v_mov_b32_e32 v18, v28
	v_mov_b32_e32 v19, v32
	v_pk_mul_f32 v[26:27], v[136:137], v[72:73]
	s_waitcnt vmcnt(12)
	v_mov_b32_e32 v138, v34
	s_waitcnt vmcnt(11)
	v_mov_b32_e32 v139, v38
	s_waitcnt vmcnt(4)
	v_fmac_f32_e32 v146, v100, v117
	v_fmac_f32_e32 v20, v102, v117
	s_waitcnt vmcnt(3)
	v_fmac_f32_e32 v146, v104, v122
	v_fmac_f32_e32 v20, v106, v122
	s_waitcnt vmcnt(2)
	v_fmac_f32_e32 v146, v124, v121
	v_fmac_f32_e32 v20, v126, v121
	s_waitcnt vmcnt(1)
	v_fmac_f32_e32 v146, v128, v120
	v_fmac_f32_e32 v20, v130, v120
	s_waitcnt vmcnt(0)
	v_fmac_f32_e32 v146, v132, v119
	v_fmac_f32_e32 v23, v101, v117
	v_pk_mul_f32 v[18:19], v[18:19], v[72:73]
	v_fmac_f32_e32 v20, v134, v119
	v_add_f32_e32 v24, v146, v26
	v_mov_b32_e32 v38, v35
	v_pk_mul_f32 v[34:35], v[138:139], v[74:75]
	v_fmac_f32_e32 v23, v105, v122
	v_add_f32_e32 v18, v18, v20
	v_add_f32_e32 v20, v24, v27
	v_mov_b32_e32 v140, v42
	v_mov_b32_e32 v141, v46
	v_fmac_f32_e32 v23, v125, v121
	v_add_f32_e32 v20, v20, v34
	v_mov_b32_e32 v46, v43
	v_pk_mul_f32 v[42:43], v[140:141], v[78:79]
	v_fmac_f32_e32 v23, v129, v120
	v_add_f32_e32 v20, v20, v35
	v_mov_b32_e32 v142, v50
	v_mov_b32_e32 v143, v54
	v_pk_mul_f32 v[30:31], v[30:31], v[72:73]
	v_fmac_f32_e32 v23, v133, v119
	v_add_f32_e32 v20, v20, v42
	v_mov_b32_e32 v54, v51
	v_pk_mul_f32 v[50:51], v[142:143], v[80:81]
	v_add_f32_e32 v23, v30, v23
	v_add_f32_e32 v20, v20, v43
	v_mov_b32_e32 v144, v58
	v_mov_b32_e32 v145, v62
	v_pk_mul_f32 v[38:39], v[38:39], v[74:75]
	v_add_f32_e32 v23, v31, v23
	v_add_f32_e32 v20, v20, v50
	v_mov_b32_e32 v62, v59
	v_pk_mul_f32 v[58:59], v[144:145], v[82:83]
	v_add_f32_e32 v23, v38, v23
	v_add_f32_e32 v20, v20, v51
	v_pk_mul_f32 v[46:47], v[46:47], v[78:79]
	v_add_f32_e32 v23, v39, v23
	v_add_f32_e32 v20, v20, v58
	v_add_f32_e32 v23, v46, v23
	v_add_f32_e32 v20, v20, v59
	v_pk_mul_f32 v[54:55], v[54:55], v[80:81]
	v_add_f32_e32 v23, v47, v23
	v_mul_f32_e64 v24, |v20|, s29
	v_add_f32_e32 v23, v54, v23
	v_exp_f32_e32 v24, v24
	v_pk_mul_f32 v[62:63], v[62:63], v[82:83]
	v_add_f32_e32 v23, v55, v23
	v_add_f32_e32 v23, v62, v23
	v_add_f32_e32 v23, v63, v23
	v_mul_f32_e64 v26, |v23|, s29
	v_add_f32_e32 v27, v19, v18
	v_add_f32_e32 v19, 1.0, v24
	v_exp_f32_e32 v26, v26
	v_cmp_gt_f32_e32 vcc, s30, v19
	v_min_f32_e32 v18, 0, v20
	v_mov_b32_e32 v22, v36
	v_cndmask_b32_e64 v24, 0, 32, vcc
	v_ldexp_f32 v19, v19, v24
	v_log_f32_e32 v24, v19
	v_add_f32_e32 v20, 1.0, v26
	v_cmp_gt_f32_e64 s[0:1], s30, v20
	v_min_f32_e32 v19, 0, v23
	v_cndmask_b32_e32 v23, 0, v112, vcc
	v_cndmask_b32_e64 v26, 0, 32, s[0:1]
	v_ldexp_f32 v20, v20, v26
	v_mul_f32_e32 v26, 0x3f317217, v24
	v_fma_f32 v26, v24, s31, -v26
	v_fmac_f32_e32 v26, 0x3377d1cf, v24
	v_fmac_f32_e32 v26, 0x3f317217, v24
	v_cmp_lt_f32_e64 vcc, |v24|, s34
	v_log_f32_e32 v20, v20
	v_fmac_f32_e32 v21, v25, v118
	v_cndmask_b32_e32 v24, v24, v26, vcc
	v_sub_f32_e32 v26, v24, v23
	v_mov_b32_e32 v23, v40
	v_pk_mul_f32 v[22:23], v[22:23], v[74:75]
	v_mul_f32_e32 v28, 0x3f317217, v20
	v_add_f32_e32 v22, v22, v27
	v_add_f32_e32 v24, v23, v22
	v_mov_b32_e32 v22, v44
	v_mov_b32_e32 v23, v48
	v_pk_mul_f32 v[22:23], v[22:23], v[78:79]
	v_fma_f32 v28, v20, s31, -v28
	v_add_f32_e32 v22, v22, v24
	v_add_f32_e32 v24, v23, v22
	v_mov_b32_e32 v22, v52
	v_mov_b32_e32 v23, v56
	v_pk_mul_f32 v[22:23], v[22:23], v[80:81]
	v_fmac_f32_e32 v28, 0x3377d1cf, v20
	v_add_f32_e32 v22, v22, v24
	v_add_f32_e32 v24, v23, v22
	v_mov_b32_e32 v22, v60
	v_mov_b32_e32 v23, v64
	v_pk_mul_f32 v[22:23], v[22:23], v[82:83]
	v_fmac_f32_e32 v28, 0x3f317217, v20
	v_add_f32_e32 v22, v22, v24
	v_add_f32_e32 v22, v23, v22
	v_mul_f32_e64 v23, |v22|, s29
	v_exp_f32_e32 v23, v23
	v_cmp_lt_f32_e64 vcc, |v20|, s34
	v_cndmask_b32_e64 v24, 0, v112, s[0:1]
	v_fmac_f32_e32 v21, v103, v117
	v_cndmask_b32_e32 v20, v20, v28, vcc
	v_sub_f32_e32 v27, v20, v24
	v_add_f32_e32 v20, 1.0, v23
	v_fmac_f32_e32 v21, v107, v122
	v_cmp_gt_f32_e32 vcc, s30, v20
	v_fmac_f32_e32 v21, v127, v121
	v_pk_add_f32 v[18:19], v[18:19], v[26:27] neg_lo:[0,1] neg_hi:[0,1]
	v_cndmask_b32_e64 v23, 0, 32, vcc
	v_fmac_f32_e32 v21, v131, v120
	v_mov_b32_e32 v32, v29
	v_ldexp_f32 v20, v20, v23
	v_pk_mul_f32 v[100:101], v[18:19], s[10:11] op_sel_hi:[1,0]
	v_min_f32_e32 v18, 0, v22
	v_fmac_f32_e32 v21, v135, v119
	v_pk_mul_f32 v[22:23], v[32:33], v[72:73]
	v_log_f32_e32 v24, v20
	v_add_f32_e32 v20, v22, v21
	v_mov_b32_e32 v40, v37
	v_add_f32_e32 v22, v23, v20
	v_pk_mul_f32 v[20:21], v[40:41], v[74:75]
	v_mov_b32_e32 v48, v45
	v_add_f32_e32 v20, v20, v22
	v_add_f32_e32 v22, v21, v20
	v_pk_mul_f32 v[20:21], v[48:49], v[78:79]
	v_mov_b32_e32 v56, v53
	v_add_f32_e32 v20, v20, v22
	v_add_f32_e32 v22, v21, v20
	v_pk_mul_f32 v[20:21], v[56:57], v[80:81]
	v_mov_b32_e32 v64, v61
	v_add_f32_e32 v20, v20, v22
	v_add_f32_e32 v22, v21, v20
	v_pk_mul_f32 v[20:21], v[64:65], v[82:83]
	v_mul_f32_e32 v19, 0x3f317217, v24
	v_add_f32_e32 v20, v20, v22
	v_add_f32_e32 v21, v21, v20
	v_mul_f32_e64 v20, |v21|, s29
	v_exp_f32_e32 v20, v20
	v_fma_f32 v19, v24, s31, -v19
	v_fmac_f32_e32 v19, 0x3377d1cf, v24
	v_fmac_f32_e32 v19, 0x3f317217, v24
	v_cmp_lt_f32_e64 s[0:1], |v24|, s34
	v_add_f32_e32 v20, 1.0, v20
	s_nop 0
	v_cndmask_b32_e64 v19, v24, v19, s[0:1]
	v_cmp_gt_f32_e64 s[0:1], s30, v20
	s_nop 1
	v_cndmask_b32_e64 v22, 0, 32, s[0:1]
	v_ldexp_f32 v20, v20, v22
	v_log_f32_e32 v22, v20
	v_cndmask_b32_e32 v20, 0, v112, vcc
	v_sub_f32_e32 v20, v19, v20
	v_min_f32_e32 v19, 0, v21
	v_mul_f32_e32 v21, 0x3f317217, v22
	v_fma_f32 v21, v22, s31, -v21
	v_fmac_f32_e32 v21, 0x3377d1cf, v22
	v_fmac_f32_e32 v21, 0x3f317217, v22
	v_cmp_lt_f32_e64 vcc, |v22|, s34
	s_nop 1
	v_cndmask_b32_e32 v21, v22, v21, vcc
	v_cndmask_b32_e64 v22, 0, v112, s[0:1]
	v_sub_f32_e32 v21, v21, v22
	v_pk_add_f32 v[18:19], v[18:19], v[20:21] neg_lo:[0,1] neg_hi:[0,1]
	s_nop 0
	v_pk_mul_f32 v[102:103], v[18:19], s[10:11] op_sel_hi:[1,0]
	global_load_dwordx4 v[18:21], v123, s[48:49] offset:608
	global_load_dwordx4 v[22:25], v123, s[4:5] offset:96
	global_load_dwordx4 v[26:29], v123, s[4:5] offset:3168
	global_load_dwordx4 v[30:33], v123, s[4:5] offset:3680
	global_load_dwordx4 v[34:37], v111, s[12:13] offset:96
	global_load_dwordx4 v[38:41], v111, s[12:13] offset:608
	global_load_dwordx4 v[42:45], v111, s[12:13] offset:1120
	global_load_dwordx4 v[46:49], v111, s[12:13] offset:1632
	global_load_dwordx4 v[50:53], v111, s[12:13] offset:2144
	global_load_dwordx4 v[54:57], v111, s[12:13] offset:2656
	global_load_dwordx4 v[58:61], v111, s[12:13] offset:3168
	global_load_dwordx4 v[62:65], v111, s[12:13] offset:3680
	global_load_dwordx4 v[104:107], v123, s[4:5] offset:608
	global_load_dwordx4 v[124:127], v123, s[4:5] offset:1120
	global_load_dwordx4 v[128:131], v123, s[4:5] offset:1632
	global_load_dwordx4 v[132:135], v123, s[4:5] offset:2144
	global_load_dwordx4 v[136:139], v123, s[4:5] offset:2656
	s_waitcnt vmcnt(15)
	v_fma_f32 v150, v22, v118, v18
	v_fma_f32 v20, v24, v118, v20
	s_waitcnt vmcnt(14)
	v_mov_b32_e32 v140, v26
	s_waitcnt vmcnt(13)
	v_mov_b32_e32 v141, v30
	v_fma_f32 v23, v23, v118, v19
	v_mov_b32_e32 v30, v27
	v_mov_b32_e32 v18, v28
	v_mov_b32_e32 v19, v32
	v_pk_mul_f32 v[26:27], v[140:141], v[72:73]
	s_waitcnt vmcnt(12)
	v_mov_b32_e32 v142, v34
	s_waitcnt vmcnt(11)
	v_mov_b32_e32 v143, v38
	s_waitcnt vmcnt(4)
	v_fmac_f32_e32 v150, v104, v117
	v_fmac_f32_e32 v20, v106, v117
	s_waitcnt vmcnt(3)
	v_fmac_f32_e32 v150, v124, v122
	v_fmac_f32_e32 v20, v126, v122
	s_waitcnt vmcnt(2)
	v_fmac_f32_e32 v150, v128, v121
	v_fmac_f32_e32 v20, v130, v121
	s_waitcnt vmcnt(1)
	v_fmac_f32_e32 v150, v132, v120
	v_fmac_f32_e32 v20, v134, v120
	s_waitcnt vmcnt(0)
	v_fmac_f32_e32 v150, v136, v119
	v_fmac_f32_e32 v23, v105, v117
	v_pk_mul_f32 v[18:19], v[18:19], v[72:73]
	v_fmac_f32_e32 v20, v138, v119
	v_add_f32_e32 v24, v150, v26
	v_mov_b32_e32 v38, v35
	v_pk_mul_f32 v[34:35], v[142:143], v[74:75]
	v_fmac_f32_e32 v23, v125, v122
	v_add_f32_e32 v18, v18, v20
	v_add_f32_e32 v20, v24, v27
	v_mov_b32_e32 v144, v42
	v_mov_b32_e32 v145, v46
	v_fmac_f32_e32 v23, v129, v121
	v_add_f32_e32 v20, v20, v34
	v_mov_b32_e32 v46, v43
	v_pk_mul_f32 v[42:43], v[144:145], v[78:79]
	v_fmac_f32_e32 v23, v133, v120
	v_add_f32_e32 v20, v20, v35
	v_mov_b32_e32 v146, v50
	v_mov_b32_e32 v147, v54
	v_pk_mul_f32 v[30:31], v[30:31], v[72:73]
	v_fmac_f32_e32 v23, v137, v119
	v_add_f32_e32 v20, v20, v42
	v_mov_b32_e32 v54, v51
	v_pk_mul_f32 v[50:51], v[146:147], v[80:81]
	v_add_f32_e32 v23, v30, v23
	v_add_f32_e32 v20, v20, v43
	v_mov_b32_e32 v148, v58
	v_mov_b32_e32 v149, v62
	v_pk_mul_f32 v[38:39], v[38:39], v[74:75]
	v_add_f32_e32 v23, v31, v23
	v_add_f32_e32 v20, v20, v50
	v_mov_b32_e32 v62, v59
	v_pk_mul_f32 v[58:59], v[148:149], v[82:83]
	v_add_f32_e32 v23, v38, v23
	v_add_f32_e32 v20, v20, v51
	v_pk_mul_f32 v[46:47], v[46:47], v[78:79]
	v_add_f32_e32 v23, v39, v23
	v_add_f32_e32 v20, v20, v58
	v_add_f32_e32 v23, v46, v23
	v_add_f32_e32 v20, v20, v59
	v_pk_mul_f32 v[54:55], v[54:55], v[80:81]
	v_add_f32_e32 v23, v47, v23
	v_mul_f32_e64 v24, |v20|, s29
	v_add_f32_e32 v23, v54, v23
	v_exp_f32_e32 v24, v24
	v_pk_mul_f32 v[62:63], v[62:63], v[82:83]
	v_add_f32_e32 v23, v55, v23
	v_add_f32_e32 v23, v62, v23
	v_add_f32_e32 v23, v63, v23
	v_mul_f32_e64 v26, |v23|, s29
	v_add_f32_e32 v27, v19, v18
	v_add_f32_e32 v19, 1.0, v24
	v_exp_f32_e32 v26, v26
	v_cmp_gt_f32_e32 vcc, s30, v19
	v_min_f32_e32 v18, 0, v20
	v_mov_b32_e32 v22, v36
	v_cndmask_b32_e64 v24, 0, 32, vcc
	v_ldexp_f32 v19, v19, v24
	v_log_f32_e32 v24, v19
	v_add_f32_e32 v20, 1.0, v26
	v_cmp_gt_f32_e64 s[0:1], s30, v20
	v_min_f32_e32 v19, 0, v23
	v_cndmask_b32_e32 v23, 0, v112, vcc
	v_cndmask_b32_e64 v26, 0, 32, s[0:1]
	v_ldexp_f32 v20, v20, v26
	v_mul_f32_e32 v26, 0x3f317217, v24
	v_fma_f32 v26, v24, s31, -v26
	v_fmac_f32_e32 v26, 0x3377d1cf, v24
	v_fmac_f32_e32 v26, 0x3f317217, v24
	v_cmp_lt_f32_e64 vcc, |v24|, s34
	v_log_f32_e32 v20, v20
	v_fmac_f32_e32 v21, v25, v118
	v_cndmask_b32_e32 v24, v24, v26, vcc
	v_sub_f32_e32 v26, v24, v23
	v_mov_b32_e32 v23, v40
	v_pk_mul_f32 v[22:23], v[22:23], v[74:75]
	v_mul_f32_e32 v28, 0x3f317217, v20
	v_add_f32_e32 v22, v22, v27
	v_add_f32_e32 v24, v23, v22
	v_mov_b32_e32 v22, v44
	v_mov_b32_e32 v23, v48
	v_pk_mul_f32 v[22:23], v[22:23], v[78:79]
	v_fma_f32 v28, v20, s31, -v28
	v_add_f32_e32 v22, v22, v24
	v_add_f32_e32 v24, v23, v22
	v_mov_b32_e32 v22, v52
	v_mov_b32_e32 v23, v56
	v_pk_mul_f32 v[22:23], v[22:23], v[80:81]
	v_fmac_f32_e32 v28, 0x3377d1cf, v20
	v_add_f32_e32 v22, v22, v24
	v_add_f32_e32 v24, v23, v22
	v_mov_b32_e32 v22, v60
	v_mov_b32_e32 v23, v64
	v_pk_mul_f32 v[22:23], v[22:23], v[82:83]
	v_fmac_f32_e32 v28, 0x3f317217, v20
	v_add_f32_e32 v22, v22, v24
	v_add_f32_e32 v22, v23, v22
	v_mul_f32_e64 v23, |v22|, s29
	v_exp_f32_e32 v23, v23
	v_cmp_lt_f32_e64 vcc, |v20|, s34
	v_cndmask_b32_e64 v24, 0, v112, s[0:1]
	v_fmac_f32_e32 v21, v107, v117
	v_cndmask_b32_e32 v20, v20, v28, vcc
	v_sub_f32_e32 v27, v20, v24
	v_add_f32_e32 v20, 1.0, v23
	v_fmac_f32_e32 v21, v127, v122
	v_cmp_gt_f32_e32 vcc, s30, v20
	v_fmac_f32_e32 v21, v131, v121
	v_pk_add_f32 v[18:19], v[18:19], v[26:27] neg_lo:[0,1] neg_hi:[0,1]
	v_cndmask_b32_e64 v23, 0, 32, vcc
	v_fmac_f32_e32 v21, v135, v120
	v_mov_b32_e32 v32, v29
	v_ldexp_f32 v20, v20, v23
	v_pk_mul_f32 v[104:105], v[18:19], s[10:11] op_sel_hi:[1,0]
	v_min_f32_e32 v18, 0, v22
	v_fmac_f32_e32 v21, v139, v119
	v_pk_mul_f32 v[22:23], v[32:33], v[72:73]
	v_log_f32_e32 v24, v20
	v_add_f32_e32 v20, v22, v21
	v_mov_b32_e32 v40, v37
	v_add_f32_e32 v22, v23, v20
	v_pk_mul_f32 v[20:21], v[40:41], v[74:75]
	v_mov_b32_e32 v48, v45
	v_add_f32_e32 v20, v20, v22
	v_add_f32_e32 v22, v21, v20
	v_pk_mul_f32 v[20:21], v[48:49], v[78:79]
	v_mov_b32_e32 v56, v53
	v_add_f32_e32 v20, v20, v22
	v_add_f32_e32 v22, v21, v20
	v_pk_mul_f32 v[20:21], v[56:57], v[80:81]
	v_mov_b32_e32 v64, v61
	v_add_f32_e32 v20, v20, v22
	v_add_f32_e32 v22, v21, v20
	v_pk_mul_f32 v[20:21], v[64:65], v[82:83]
	v_mul_f32_e32 v19, 0x3f317217, v24
	v_add_f32_e32 v20, v20, v22
	v_add_f32_e32 v21, v21, v20
	v_mul_f32_e64 v20, |v21|, s29
	v_exp_f32_e32 v20, v20
	v_fma_f32 v19, v24, s31, -v19
	v_fmac_f32_e32 v19, 0x3377d1cf, v24
	v_fmac_f32_e32 v19, 0x3f317217, v24
	v_cmp_lt_f32_e64 s[0:1], |v24|, s34
	v_add_f32_e32 v20, 1.0, v20
	s_nop 0
	v_cndmask_b32_e64 v19, v24, v19, s[0:1]
	v_cmp_gt_f32_e64 s[0:1], s30, v20
	s_nop 1
	v_cndmask_b32_e64 v22, 0, 32, s[0:1]
	v_ldexp_f32 v20, v20, v22
	v_log_f32_e32 v22, v20
	v_cndmask_b32_e32 v20, 0, v112, vcc
	v_sub_f32_e32 v20, v19, v20
	v_min_f32_e32 v19, 0, v21
	v_mul_f32_e32 v21, 0x3f317217, v22
	v_fma_f32 v21, v22, s31, -v21
	v_fmac_f32_e32 v21, 0x3377d1cf, v22
	v_fmac_f32_e32 v21, 0x3f317217, v22
	v_cmp_lt_f32_e64 vcc, |v22|, s34
	s_nop 1
	v_cndmask_b32_e32 v21, v22, v21, vcc
	v_cndmask_b32_e64 v22, 0, v112, s[0:1]
	v_sub_f32_e32 v21, v21, v22
	v_pk_add_f32 v[18:19], v[18:19], v[20:21] neg_lo:[0,1] neg_hi:[0,1]
	s_nop 0
	v_pk_mul_f32 v[106:107], v[18:19], s[10:11] op_sel_hi:[1,0]
	global_load_dwordx4 v[18:21], v123, s[48:49] offset:624
	global_load_dwordx4 v[22:25], v123, s[4:5] offset:112
	global_load_dwordx4 v[26:29], v123, s[4:5] offset:3184
	global_load_dwordx4 v[30:33], v123, s[4:5] offset:3696
	global_load_dwordx4 v[34:37], v111, s[12:13] offset:112
	global_load_dwordx4 v[38:41], v111, s[12:13] offset:624
	global_load_dwordx4 v[42:45], v111, s[12:13] offset:1136
	global_load_dwordx4 v[46:49], v111, s[12:13] offset:1648
	global_load_dwordx4 v[50:53], v111, s[12:13] offset:2160
	global_load_dwordx4 v[54:57], v111, s[12:13] offset:2672
	global_load_dwordx4 v[58:61], v111, s[12:13] offset:3184
	global_load_dwordx4 v[62:65], v111, s[12:13] offset:3696
	global_load_dwordx4 v[124:127], v123, s[4:5] offset:624
	global_load_dwordx4 v[128:131], v123, s[4:5] offset:1136
	global_load_dwordx4 v[132:135], v123, s[4:5] offset:1648
	global_load_dwordx4 v[136:139], v123, s[4:5] offset:2160
	global_load_dwordx4 v[140:143], v123, s[4:5] offset:2672
	s_waitcnt vmcnt(15)
	v_fma_f32 v123, v22, v118, v18
	v_fma_f32 v20, v24, v118, v20
	s_waitcnt vmcnt(14)
	v_mov_b32_e32 v144, v26
	s_waitcnt vmcnt(13)
	v_mov_b32_e32 v145, v30
	v_fma_f32 v23, v23, v118, v19
	v_mov_b32_e32 v30, v27
	v_mov_b32_e32 v18, v28
	v_mov_b32_e32 v19, v32
	v_pk_mul_f32 v[26:27], v[144:145], v[72:73]
	s_waitcnt vmcnt(12)
	v_mov_b32_e32 v146, v34
	s_waitcnt vmcnt(11)
	v_mov_b32_e32 v147, v38
	s_waitcnt vmcnt(4)
	v_fmac_f32_e32 v123, v124, v117
	v_fmac_f32_e32 v20, v126, v117
	s_waitcnt vmcnt(3)
	v_fmac_f32_e32 v123, v128, v122
	v_fmac_f32_e32 v20, v130, v122
	s_waitcnt vmcnt(2)
	v_fmac_f32_e32 v123, v132, v121
	v_fmac_f32_e32 v20, v134, v121
	s_waitcnt vmcnt(1)
	v_fmac_f32_e32 v123, v136, v120
	v_fmac_f32_e32 v20, v138, v120
	s_waitcnt vmcnt(0)
	v_fmac_f32_e32 v123, v140, v119
	v_fmac_f32_e32 v23, v125, v117
	v_pk_mul_f32 v[18:19], v[18:19], v[72:73]
	v_fmac_f32_e32 v20, v142, v119
	v_add_f32_e32 v24, v123, v26
	v_mov_b32_e32 v38, v35
	v_pk_mul_f32 v[34:35], v[146:147], v[74:75]
	v_fmac_f32_e32 v23, v129, v122
	v_add_f32_e32 v18, v18, v20
	v_add_f32_e32 v20, v24, v27
	v_mov_b32_e32 v148, v42
	v_mov_b32_e32 v149, v46
	v_fmac_f32_e32 v23, v133, v121
	v_add_f32_e32 v20, v20, v34
	v_mov_b32_e32 v46, v43
	v_pk_mul_f32 v[42:43], v[148:149], v[78:79]
	v_fmac_f32_e32 v23, v137, v120
	v_add_f32_e32 v20, v20, v35
	v_mov_b32_e32 v150, v50
	v_mov_b32_e32 v151, v54
	v_pk_mul_f32 v[30:31], v[30:31], v[72:73]
	v_fmac_f32_e32 v23, v141, v119
	v_add_f32_e32 v20, v20, v42
	v_mov_b32_e32 v54, v51
	v_pk_mul_f32 v[50:51], v[150:151], v[80:81]
	v_add_f32_e32 v23, v30, v23
	v_add_f32_e32 v20, v20, v43
	v_mov_b32_e32 v152, v58
	v_mov_b32_e32 v153, v62
	v_pk_mul_f32 v[38:39], v[38:39], v[74:75]
	v_add_f32_e32 v23, v31, v23
	v_add_f32_e32 v20, v20, v50
	v_mov_b32_e32 v62, v59
	v_pk_mul_f32 v[58:59], v[152:153], v[82:83]
	v_add_f32_e32 v23, v38, v23
	v_add_f32_e32 v20, v20, v51
	v_pk_mul_f32 v[46:47], v[46:47], v[78:79]
	v_add_f32_e32 v23, v39, v23
	v_add_f32_e32 v20, v20, v58
	v_add_f32_e32 v23, v46, v23
	v_add_f32_e32 v20, v20, v59
	v_pk_mul_f32 v[54:55], v[54:55], v[80:81]
	v_add_f32_e32 v23, v47, v23
	v_mul_f32_e64 v24, |v20|, s29
	v_add_f32_e32 v23, v54, v23
	v_exp_f32_e32 v24, v24
	v_pk_mul_f32 v[62:63], v[62:63], v[82:83]
	v_add_f32_e32 v23, v55, v23
	v_add_f32_e32 v23, v62, v23
	v_add_f32_e32 v23, v63, v23
	v_mul_f32_e64 v26, |v23|, s29
	v_add_f32_e32 v27, v19, v18
	v_add_f32_e32 v19, 1.0, v24
	v_exp_f32_e32 v26, v26
	v_cmp_gt_f32_e32 vcc, s30, v19
	v_min_f32_e32 v18, 0, v20
	v_mov_b32_e32 v22, v36
	v_cndmask_b32_e64 v24, 0, 32, vcc
	v_ldexp_f32 v19, v19, v24
	v_log_f32_e32 v24, v19
	v_add_f32_e32 v20, 1.0, v26
	v_cmp_gt_f32_e64 s[0:1], s30, v20
	v_min_f32_e32 v19, 0, v23
	v_cndmask_b32_e32 v23, 0, v112, vcc
	v_cndmask_b32_e64 v26, 0, 32, s[0:1]
	v_ldexp_f32 v20, v20, v26
	v_mul_f32_e32 v26, 0x3f317217, v24
	v_fma_f32 v26, v24, s31, -v26
	v_fmac_f32_e32 v26, 0x3377d1cf, v24
	v_fmac_f32_e32 v26, 0x3f317217, v24
	v_cmp_lt_f32_e64 vcc, |v24|, s34
	v_log_f32_e32 v20, v20
	v_fmac_f32_e32 v21, v25, v118
	v_cndmask_b32_e32 v24, v24, v26, vcc
	v_sub_f32_e32 v26, v24, v23
	v_mov_b32_e32 v23, v40
	v_pk_mul_f32 v[22:23], v[22:23], v[74:75]
	v_mul_f32_e32 v28, 0x3f317217, v20
	v_add_f32_e32 v22, v22, v27
	v_add_f32_e32 v24, v23, v22
	v_mov_b32_e32 v22, v44
	v_mov_b32_e32 v23, v48
	v_pk_mul_f32 v[22:23], v[22:23], v[78:79]
	v_fma_f32 v28, v20, s31, -v28
	v_add_f32_e32 v22, v22, v24
	v_add_f32_e32 v24, v23, v22
	v_mov_b32_e32 v22, v52
	v_mov_b32_e32 v23, v56
	v_pk_mul_f32 v[22:23], v[22:23], v[80:81]
	v_fmac_f32_e32 v28, 0x3377d1cf, v20
	v_add_f32_e32 v22, v22, v24
	v_add_f32_e32 v24, v23, v22
	v_mov_b32_e32 v22, v60
	v_mov_b32_e32 v23, v64
	v_pk_mul_f32 v[22:23], v[22:23], v[82:83]
	v_fmac_f32_e32 v28, 0x3f317217, v20
	v_add_f32_e32 v22, v22, v24
	v_add_f32_e32 v22, v23, v22
	v_mul_f32_e64 v23, |v22|, s29
	v_exp_f32_e32 v23, v23
	v_cmp_lt_f32_e64 vcc, |v20|, s34
	v_cndmask_b32_e64 v24, 0, v112, s[0:1]
	v_fmac_f32_e32 v21, v127, v117
	v_cndmask_b32_e32 v20, v20, v28, vcc
	v_sub_f32_e32 v27, v20, v24
	v_add_f32_e32 v20, 1.0, v23
	v_cmp_gt_f32_e32 vcc, s30, v20
	v_fmac_f32_e32 v21, v131, v122
	v_fmac_f32_e32 v21, v135, v121
	v_cndmask_b32_e64 v23, 0, 32, vcc
	v_ldexp_f32 v20, v20, v23
	v_log_f32_e32 v24, v20
	v_min_f32_e32 v20, 0, v22
	v_fmac_f32_e32 v21, v139, v120
	v_mov_b32_e32 v32, v29
	v_mul_f32_e32 v22, 0x3f317217, v24
	v_pk_add_f32 v[18:19], v[18:19], v[26:27] neg_lo:[0,1] neg_hi:[0,1]
	v_fma_f32 v26, v24, s31, -v22
	v_fmac_f32_e32 v21, v143, v119
	v_pk_mul_f32 v[22:23], v[32:33], v[72:73]
	v_mov_b32_e32 v40, v37
	v_add_f32_e32 v21, v22, v21
	v_add_f32_e32 v21, v23, v21
	v_pk_mul_f32 v[22:23], v[40:41], v[74:75]
	v_mov_b32_e32 v48, v45
	v_add_f32_e32 v21, v22, v21
	v_add_f32_e32 v21, v23, v21
	v_pk_mul_f32 v[22:23], v[48:49], v[78:79]
	v_mov_b32_e32 v56, v53
	v_add_f32_e32 v21, v22, v21
	v_add_f32_e32 v21, v23, v21
	v_pk_mul_f32 v[22:23], v[56:57], v[80:81]
	v_mov_b32_e32 v64, v61
	v_add_f32_e32 v21, v22, v21
	v_add_f32_e32 v21, v23, v21
	v_pk_mul_f32 v[22:23], v[64:65], v[82:83]
	v_fmac_f32_e32 v26, 0x3377d1cf, v24
	v_add_f32_e32 v21, v22, v21
	v_add_f32_e32 v21, v23, v21
	v_mul_f32_e64 v22, |v21|, s29
	v_exp_f32_e32 v22, v22
	v_fmac_f32_e32 v26, 0x3f317217, v24
	v_cmp_lt_f32_e64 s[0:1], |v24|, s34
	v_min_f32_e32 v21, 0, v21
	v_add_f32_e32 v22, 1.0, v22
	v_cndmask_b32_e64 v23, v24, v26, s[0:1]
	v_cmp_gt_f32_e64 s[0:1], s30, v22
	v_pk_mul_f32 v[18:19], v[18:19], s[10:11] op_sel_hi:[1,0]
	s_nop 0
	v_cndmask_b32_e64 v24, 0, 32, s[0:1]
	v_ldexp_f32 v22, v22, v24
	v_log_f32_e32 v24, v22
	v_cndmask_b32_e32 v22, 0, v112, vcc
	v_sub_f32_e32 v22, v23, v22
	v_mul_f32_e32 v23, 0x3f317217, v24
	v_fma_f32 v23, v24, s31, -v23
	v_fmac_f32_e32 v23, 0x3377d1cf, v24
	v_fmac_f32_e32 v23, 0x3f317217, v24
	v_cmp_lt_f32_e64 vcc, |v24|, s34
	s_nop 1
	v_cndmask_b32_e32 v23, v24, v23, vcc
	v_cndmask_b32_e64 v24, 0, v112, s[0:1]
	v_sub_f32_e32 v23, v23, v24
	v_pk_add_f32 v[20:21], v[20:21], v[22:23] neg_lo:[0,1] neg_hi:[0,1]
	s_nop 0
	v_pk_mul_f32 v[20:21], v[20:21], s[10:11] op_sel_hi:[1,0]
	v_cmp_ne_u32_e32 vcc, 63, v113
	v_cmp_gt_u32_e64 s[0:1], 62, v113
	s_nop 0
	v_addc_co_u32_e32 v22, vcc, 0, v110, vcc
	v_lshlrev_b32_e32 v22, 2, v22
	ds_bpermute_b32 v23, v22, v70
	ds_bpermute_b32 v24, v22, v71
	ds_bpermute_b32 v25, v22, v76
	ds_bpermute_b32 v26, v22, v77
	ds_bpermute_b32 v27, v22, v84
	ds_bpermute_b32 v28, v22, v85
	ds_bpermute_b32 v29, v22, v86
	ds_bpermute_b32 v30, v22, v87
	ds_bpermute_b32 v31, v22, v88
	ds_bpermute_b32 v32, v22, v89
	ds_bpermute_b32 v33, v22, v90
	ds_bpermute_b32 v34, v22, v91
	ds_bpermute_b32 v35, v22, v92
	ds_bpermute_b32 v36, v22, v93
	ds_bpermute_b32 v37, v22, v94
	ds_bpermute_b32 v38, v22, v95
	ds_bpermute_b32 v39, v22, v96
	ds_bpermute_b32 v40, v22, v97
	ds_bpermute_b32 v41, v22, v98
	ds_bpermute_b32 v42, v22, v99
	ds_bpermute_b32 v43, v22, v100
	ds_bpermute_b32 v44, v22, v101
	ds_bpermute_b32 v45, v22, v102
	ds_bpermute_b32 v46, v22, v103
	ds_bpermute_b32 v47, v22, v104
	ds_bpermute_b32 v48, v22, v105
	ds_bpermute_b32 v49, v22, v106
	ds_bpermute_b32 v50, v22, v107
	ds_bpermute_b32 v51, v22, v18
	ds_bpermute_b32 v52, v22, v19
	ds_bpermute_b32 v53, v22, v20
	ds_bpermute_b32 v22, v22, v21
	v_cmp_gt_i32_e32 vcc, 63, v68
	s_waitcnt lgkmcnt(6)
	v_add_f32_e32 v48, v105, v48
	v_add_f32_e32 v23, v70, v23
	v_add_f32_e32 v24, v71, v24
	s_waitcnt lgkmcnt(0)
	v_add_f32_e32 v22, v21, v22
	v_add_f32_e32 v25, v76, v25
	v_add_f32_e32 v26, v77, v26
	v_add_f32_e32 v27, v84, v27
	v_add_f32_e32 v28, v85, v28
	v_add_f32_e32 v29, v86, v29
	v_add_f32_e32 v30, v87, v30
	v_add_f32_e32 v31, v88, v31
	v_add_f32_e32 v32, v89, v32
	v_add_f32_e32 v33, v90, v33
	v_add_f32_e32 v34, v91, v34
	v_add_f32_e32 v35, v92, v35
	v_add_f32_e32 v36, v93, v36
	v_add_f32_e32 v37, v94, v37
	v_add_f32_e32 v38, v95, v38
	v_add_f32_e32 v39, v96, v39
	v_add_f32_e32 v40, v97, v40
	v_add_f32_e32 v41, v98, v41
	v_add_f32_e32 v42, v99, v42
	v_add_f32_e32 v43, v100, v43
	v_add_f32_e32 v44, v101, v44
	v_add_f32_e32 v45, v102, v45
	v_add_f32_e32 v46, v103, v46
	v_add_f32_e32 v47, v104, v47
	v_add_f32_e32 v49, v106, v49
	v_add_f32_e32 v50, v107, v50
	v_add_f32_e32 v51, v18, v51
	v_add_f32_e32 v52, v19, v52
	v_add_f32_e32 v53, v20, v53
	v_cndmask_b32_e32 v21, v21, v22, vcc
	v_cndmask_b32_e32 v22, v105, v48, vcc
	v_cndmask_b32_e64 v48, 0, 2, s[0:1]
	v_cndmask_b32_e32 v23, v70, v23, vcc
	v_cndmask_b32_e32 v25, v76, v25, vcc
	v_cndmask_b32_e32 v26, v77, v26, vcc
	v_cndmask_b32_e32 v28, v85, v28, vcc
	v_cndmask_b32_e32 v29, v86, v29, vcc
	v_cndmask_b32_e32 v31, v88, v31, vcc
	v_cndmask_b32_e32 v32, v89, v32, vcc
	v_cndmask_b32_e32 v34, v91, v34, vcc
	v_cndmask_b32_e32 v35, v92, v35, vcc
	v_cndmask_b32_e32 v37, v94, v37, vcc
	v_cndmask_b32_e32 v38, v95, v38, vcc
	v_cndmask_b32_e32 v40, v97, v40, vcc
	v_cndmask_b32_e32 v41, v98, v41, vcc
	v_cndmask_b32_e32 v43, v100, v43, vcc
	v_cndmask_b32_e32 v44, v101, v44, vcc
	v_cndmask_b32_e32 v46, v103, v46, vcc
	v_cndmask_b32_e32 v47, v104, v47, vcc
	v_cndmask_b32_e32 v49, v106, v49, vcc
	v_cndmask_b32_e32 v50, v107, v50, vcc
	v_cndmask_b32_e32 v52, v19, v52, vcc
	v_cndmask_b32_e32 v53, v20, v53, vcc
	v_cndmask_b32_e32 v18, v18, v51, vcc
	v_cndmask_b32_e32 v45, v102, v45, vcc
	v_cndmask_b32_e32 v42, v99, v42, vcc
	v_cndmask_b32_e32 v39, v96, v39, vcc
	v_cndmask_b32_e32 v36, v93, v36, vcc
	v_cndmask_b32_e32 v33, v90, v33, vcc
	v_add_lshl_u32 v48, v48, v110, 2
	v_cndmask_b32_e32 v30, v87, v30, vcc
	v_cndmask_b32_e32 v27, v84, v27, vcc
	v_cndmask_b32_e32 v24, v71, v24, vcc
	v_cndmask_b32_e32 v54, v70, v23, vcc
	v_cndmask_b32_e32 v55, v76, v25, vcc
	v_cndmask_b32_e32 v57, v85, v28, vcc
	v_cndmask_b32_e32 v58, v86, v29, vcc
	v_cndmask_b32_e32 v59, v88, v31, vcc
	v_cndmask_b32_e32 v60, v89, v32, vcc
	v_cndmask_b32_e32 v61, v91, v34, vcc
	v_cndmask_b32_e32 v62, v92, v35, vcc
	v_cndmask_b32_e32 v63, v94, v37, vcc
	v_cndmask_b32_e32 v64, v95, v38, vcc
	v_cndmask_b32_e32 v65, v97, v40, vcc
	v_cndmask_b32_e32 v70, v98, v41, vcc
	v_cndmask_b32_e32 v72, v100, v43, vcc
	v_cndmask_b32_e32 v73, v101, v44, vcc
	v_cndmask_b32_e32 v74, v103, v46, vcc
	v_cndmask_b32_e32 v75, v104, v47, vcc
	v_cndmask_b32_e32 v76, v106, v49, vcc
	ds_bpermute_b32 v51, v48, v23
	ds_bpermute_b32 v71, v48, v24
	ds_bpermute_b32 v78, v48, v25
	ds_bpermute_b32 v79, v48, v26
	ds_bpermute_b32 v80, v48, v27
	ds_bpermute_b32 v81, v48, v28
	ds_bpermute_b32 v82, v48, v29
	ds_bpermute_b32 v83, v48, v30
	ds_bpermute_b32 v84, v48, v31
	ds_bpermute_b32 v85, v48, v32
	ds_bpermute_b32 v86, v48, v33
	ds_bpermute_b32 v87, v48, v34
	ds_bpermute_b32 v88, v48, v35
	ds_bpermute_b32 v89, v48, v36
	ds_bpermute_b32 v90, v48, v37
	ds_bpermute_b32 v91, v48, v38
	ds_bpermute_b32 v92, v48, v39
	ds_bpermute_b32 v93, v48, v40
	ds_bpermute_b32 v94, v48, v41
	ds_bpermute_b32 v95, v48, v42
	ds_bpermute_b32 v96, v48, v43
	ds_bpermute_b32 v97, v48, v44
	ds_bpermute_b32 v98, v48, v45
	ds_bpermute_b32 v99, v48, v46
	ds_bpermute_b32 v100, v48, v47
	ds_bpermute_b32 v101, v48, v22
	ds_bpermute_b32 v102, v48, v49
	ds_bpermute_b32 v103, v48, v50
	ds_bpermute_b32 v104, v48, v18
	ds_bpermute_b32 v105, v48, v52
	ds_bpermute_b32 v106, v48, v53
	ds_bpermute_b32 v48, v48, v21
	v_cndmask_b32_e32 v56, v77, v26, vcc
	v_cndmask_b32_e32 v77, v107, v50, vcc
	v_cndmask_b32_e32 v19, v19, v52, vcc
	v_cndmask_b32_e32 v20, v20, v53, vcc
	v_cmp_gt_i32_e32 vcc, 62, v68
	s_waitcnt lgkmcnt(0)
	v_add_f32_e32 v48, v21, v48
	v_cmp_gt_u32_e64 s[0:1], 60, v113
	v_add_f32_e32 v51, v23, v51
	v_add_f32_e32 v71, v24, v71
	v_add_f32_e32 v78, v25, v78
	v_add_f32_e32 v79, v26, v79
	v_add_f32_e32 v80, v27, v80
	v_add_f32_e32 v81, v28, v81
	v_add_f32_e32 v82, v29, v82
	v_add_f32_e32 v83, v30, v83
	v_add_f32_e32 v84, v31, v84
	v_add_f32_e32 v85, v32, v85
	v_add_f32_e32 v86, v33, v86
	v_add_f32_e32 v87, v34, v87
	v_add_f32_e32 v88, v35, v88
	v_add_f32_e32 v89, v36, v89
	v_add_f32_e32 v90, v37, v90
	v_add_f32_e32 v91, v38, v91
	v_add_f32_e32 v92, v39, v92
	v_add_f32_e32 v93, v40, v93
	v_add_f32_e32 v94, v41, v94
	v_add_f32_e32 v95, v42, v95
	v_add_f32_e32 v96, v43, v96
	v_add_f32_e32 v97, v44, v97
	v_add_f32_e32 v98, v45, v98
	v_add_f32_e32 v99, v46, v99
	v_add_f32_e32 v100, v47, v100
	v_add_f32_e32 v101, v22, v101
	v_add_f32_e32 v102, v49, v102
	v_add_f32_e32 v103, v50, v103
	v_add_f32_e32 v104, v18, v104
	v_add_f32_e32 v105, v52, v105
	v_add_f32_e32 v106, v53, v106
	v_cndmask_b32_e32 v21, v21, v48, vcc
	v_cndmask_b32_e64 v48, 0, 4, s[0:1]
	v_cndmask_b32_e32 v23, v23, v51, vcc
	v_cndmask_b32_e32 v25, v25, v78, vcc
	v_cndmask_b32_e32 v26, v26, v79, vcc
	v_cndmask_b32_e32 v28, v28, v81, vcc
	v_cndmask_b32_e32 v29, v29, v82, vcc
	v_cndmask_b32_e32 v31, v31, v84, vcc
	v_cndmask_b32_e32 v32, v32, v85, vcc
	v_cndmask_b32_e32 v34, v34, v87, vcc
	v_cndmask_b32_e32 v35, v35, v88, vcc
	v_cndmask_b32_e32 v37, v37, v90, vcc
	v_cndmask_b32_e32 v38, v38, v91, vcc
	v_cndmask_b32_e32 v40, v40, v93, vcc
	v_cndmask_b32_e32 v41, v41, v94, vcc
	v_cndmask_b32_e32 v43, v43, v96, vcc
	v_cndmask_b32_e32 v44, v44, v97, vcc
	v_cndmask_b32_e32 v46, v46, v99, vcc
	v_cndmask_b32_e32 v47, v47, v100, vcc
	v_cndmask_b32_e32 v49, v49, v102, vcc
	v_cndmask_b32_e32 v50, v50, v103, vcc
	v_cndmask_b32_e32 v52, v52, v105, vcc
	v_cndmask_b32_e32 v53, v53, v106, vcc
	v_cndmask_b32_e32 v18, v18, v104, vcc
	v_cndmask_b32_e32 v22, v22, v101, vcc
	v_cndmask_b32_e32 v45, v45, v98, vcc
	v_cndmask_b32_e32 v42, v42, v95, vcc
	v_cndmask_b32_e32 v39, v39, v92, vcc
	v_cndmask_b32_e32 v36, v36, v89, vcc
	v_cndmask_b32_e32 v33, v33, v86, vcc
	v_add_lshl_u32 v48, v48, v110, 2
	v_cndmask_b32_e32 v30, v30, v83, vcc
	v_cndmask_b32_e32 v27, v27, v80, vcc
	v_cndmask_b32_e32 v24, v24, v71, vcc
	v_cndmask_b32_e32 v20, v20, v106, vcc
	v_cndmask_b32_e32 v19, v19, v105, vcc
	v_cndmask_b32_e32 v77, v77, v103, vcc
	v_cndmask_b32_e32 v76, v76, v102, vcc
	v_cndmask_b32_e32 v75, v75, v100, vcc
	v_cndmask_b32_e32 v74, v74, v99, vcc
	v_cndmask_b32_e32 v73, v73, v97, vcc
	v_cndmask_b32_e32 v72, v72, v96, vcc
	v_cndmask_b32_e32 v70, v70, v94, vcc
	v_cndmask_b32_e32 v65, v65, v93, vcc
	v_cndmask_b32_e32 v64, v64, v91, vcc
	v_cndmask_b32_e32 v63, v63, v90, vcc
	v_cndmask_b32_e32 v62, v62, v88, vcc
	v_cndmask_b32_e32 v61, v61, v87, vcc
	v_cndmask_b32_e32 v60, v60, v85, vcc
	v_cndmask_b32_e32 v59, v59, v84, vcc
	v_cndmask_b32_e32 v58, v58, v82, vcc
	v_cndmask_b32_e32 v57, v57, v81, vcc
	v_cndmask_b32_e32 v56, v56, v79, vcc
	v_cndmask_b32_e32 v55, v55, v78, vcc
	v_cndmask_b32_e32 v51, v54, v51, vcc
	ds_bpermute_b32 v54, v48, v23
	ds_bpermute_b32 v71, v48, v24
	ds_bpermute_b32 v78, v48, v25
	ds_bpermute_b32 v79, v48, v26
	ds_bpermute_b32 v80, v48, v27
	ds_bpermute_b32 v81, v48, v28
	ds_bpermute_b32 v82, v48, v29
	ds_bpermute_b32 v83, v48, v30
	ds_bpermute_b32 v84, v48, v31
	ds_bpermute_b32 v85, v48, v32
	ds_bpermute_b32 v86, v48, v33
	ds_bpermute_b32 v87, v48, v34
	ds_bpermute_b32 v88, v48, v35
	ds_bpermute_b32 v89, v48, v36
	ds_bpermute_b32 v90, v48, v37
	ds_bpermute_b32 v91, v48, v38
	ds_bpermute_b32 v92, v48, v39
	ds_bpermute_b32 v93, v48, v40
	ds_bpermute_b32 v94, v48, v41
	ds_bpermute_b32 v95, v48, v42
	ds_bpermute_b32 v96, v48, v43
	ds_bpermute_b32 v97, v48, v44
	ds_bpermute_b32 v98, v48, v45
	ds_bpermute_b32 v99, v48, v46
	ds_bpermute_b32 v100, v48, v47
	ds_bpermute_b32 v101, v48, v22
	ds_bpermute_b32 v102, v48, v49
	ds_bpermute_b32 v103, v48, v50
	ds_bpermute_b32 v104, v48, v18
	ds_bpermute_b32 v105, v48, v52
	ds_bpermute_b32 v106, v48, v53
	ds_bpermute_b32 v48, v48, v21
	v_cmp_gt_i32_e32 vcc, 60, v68
	v_cmp_gt_u32_e64 s[0:1], 56, v113
	s_waitcnt lgkmcnt(14)
	v_add_f32_e32 v54, v23, v54
	v_add_f32_e32 v71, v24, v71
	s_waitcnt lgkmcnt(0)
	v_add_f32_e32 v48, v21, v48
	v_cndmask_b32_e32 v21, v21, v48, vcc
	v_cndmask_b32_e64 v48, 0, 8, s[0:1]
	v_cndmask_b32_e32 v23, v23, v54, vcc
	v_add_f32_e32 v78, v25, v78
	v_add_f32_e32 v79, v26, v79
	v_add_f32_e32 v81, v28, v81
	v_add_f32_e32 v82, v29, v82
	v_add_f32_e32 v84, v31, v84
	v_add_f32_e32 v85, v32, v85
	v_add_f32_e32 v87, v34, v87
	v_add_f32_e32 v88, v35, v88
	v_add_f32_e32 v90, v37, v90
	v_add_f32_e32 v91, v38, v91
	v_add_f32_e32 v93, v40, v93
	v_add_f32_e32 v94, v41, v94
	v_add_f32_e32 v96, v43, v96
	v_add_f32_e32 v97, v44, v97
	v_add_f32_e32 v99, v46, v99
	v_add_f32_e32 v100, v47, v100
	v_add_f32_e32 v102, v49, v102
	v_add_f32_e32 v103, v50, v103
	v_cndmask_b32_e32 v24, v24, v71, vcc
	v_add_lshl_u32 v48, v48, v110, 2
	v_cndmask_b32_e32 v51, v51, v54, vcc
	v_cndmask_b32_e32 v54, v55, v78, vcc
	v_cndmask_b32_e32 v55, v56, v79, vcc
	v_cndmask_b32_e32 v56, v57, v81, vcc
	v_cndmask_b32_e32 v57, v58, v82, vcc
	v_cndmask_b32_e32 v58, v59, v84, vcc
	v_cndmask_b32_e32 v59, v60, v85, vcc
	v_cndmask_b32_e32 v60, v61, v87, vcc
	v_cndmask_b32_e32 v61, v62, v88, vcc
	v_cndmask_b32_e32 v62, v63, v90, vcc
	v_cndmask_b32_e32 v63, v64, v91, vcc
	v_cndmask_b32_e32 v64, v65, v93, vcc
	v_cndmask_b32_e32 v65, v70, v94, vcc
	v_cndmask_b32_e32 v70, v72, v96, vcc
	v_cndmask_b32_e32 v72, v73, v97, vcc
	v_cndmask_b32_e32 v73, v74, v99, vcc
	v_cndmask_b32_e32 v74, v75, v100, vcc
	v_cndmask_b32_e32 v75, v76, v102, vcc
	v_cndmask_b32_e32 v76, v77, v103, vcc
	ds_bpermute_b32 v71, v48, v23
	ds_bpermute_b32 v77, v48, v24
	v_add_f32_e32 v80, v27, v80
	v_cndmask_b32_e32 v25, v25, v78, vcc
	v_cndmask_b32_e32 v28, v28, v81, vcc
	v_cndmask_b32_e32 v29, v29, v82, vcc
	v_cndmask_b32_e32 v27, v27, v80, vcc
	v_cndmask_b32_e32 v26, v26, v79, vcc
	s_waitcnt lgkmcnt(1)
	v_add_f32_e32 v23, v23, v71
	s_waitcnt lgkmcnt(0)
	v_add_f32_e32 v71, v24, v77
	ds_bpermute_b32 v77, v48, v25
	ds_bpermute_b32 v79, v48, v27
	ds_bpermute_b32 v80, v48, v28
	ds_bpermute_b32 v81, v48, v29
	v_add_f32_e32 v86, v33, v86
	v_cndmask_b32_e32 v31, v31, v84, vcc
	v_cndmask_b32_e32 v32, v32, v85, vcc
	v_cndmask_b32_e32 v34, v34, v87, vcc
	v_cndmask_b32_e32 v33, v33, v86, vcc
	s_waitcnt lgkmcnt(3)
	v_add_f32_e32 v25, v25, v77
	s_waitcnt lgkmcnt(2)
	v_add_f32_e32 v77, v27, v79
	s_waitcnt lgkmcnt(1)
	v_add_f32_e32 v28, v28, v80
	s_waitcnt lgkmcnt(0)
	v_add_f32_e32 v29, v29, v81
	ds_bpermute_b32 v79, v48, v31
	ds_bpermute_b32 v80, v48, v32
	ds_bpermute_b32 v81, v48, v33
	ds_bpermute_b32 v82, v48, v34
	v_add_f32_e32 v89, v36, v89
	v_add_f32_e32 v92, v39, v92
	v_cndmask_b32_e32 v35, v35, v88, vcc
	v_cndmask_b32_e32 v37, v37, v90, vcc
	v_cndmask_b32_e32 v39, v39, v92, vcc
	v_cndmask_b32_e32 v36, v36, v89, vcc
	s_waitcnt lgkmcnt(3)
	v_add_f32_e32 v31, v31, v79
	s_waitcnt lgkmcnt(2)
	v_add_f32_e32 v32, v32, v80
	s_waitcnt lgkmcnt(1)
	v_add_f32_e32 v79, v33, v81
	s_waitcnt lgkmcnt(0)
	v_add_f32_e32 v34, v34, v82
	ds_bpermute_b32 v80, v48, v35
	ds_bpermute_b32 v81, v48, v36
	ds_bpermute_b32 v82, v48, v37
	ds_bpermute_b32 v84, v48, v39
	v_add_f32_e32 v95, v42, v95
	v_add_f32_e32 v83, v30, v83
	v_cndmask_b32_e32 v38, v38, v91, vcc
	v_cndmask_b32_e32 v40, v40, v93, vcc
	v_cndmask_b32_e32 v43, v43, v96, vcc
	v_cndmask_b32_e32 v44, v44, v97, vcc
	v_cndmask_b32_e32 v42, v42, v95, vcc
	v_cndmask_b32_e32 v30, v30, v83, vcc
	ds_bpermute_b32 v83, v48, v38
	s_waitcnt lgkmcnt(4)
	v_add_f32_e32 v35, v35, v80
	s_waitcnt lgkmcnt(3)
	v_add_f32_e32 v80, v36, v81
	s_waitcnt lgkmcnt(2)
	v_add_f32_e32 v37, v37, v82
	s_waitcnt lgkmcnt(1)
	v_add_f32_e32 v81, v39, v84
	ds_bpermute_b32 v82, v48, v40
	ds_bpermute_b32 v84, v48, v42
	ds_bpermute_b32 v85, v48, v43
	ds_bpermute_b32 v86, v48, v44
	v_add_f32_e32 v101, v22, v101
	v_cndmask_b32_e32 v41, v41, v94, vcc
	v_cndmask_b32_e32 v46, v46, v99, vcc
	v_cndmask_b32_e32 v47, v47, v100, vcc
	v_cndmask_b32_e32 v49, v49, v102, vcc
	v_cndmask_b32_e32 v22, v22, v101, vcc
	ds_bpermute_b32 v78, v48, v26
	s_waitcnt lgkmcnt(5)
	v_add_f32_e32 v38, v38, v83
	ds_bpermute_b32 v83, v48, v41
	s_waitcnt lgkmcnt(5)
	v_add_f32_e32 v40, v40, v82
	s_waitcnt lgkmcnt(4)
	v_add_f32_e32 v82, v42, v84
	s_waitcnt lgkmcnt(3)
	v_add_f32_e32 v43, v43, v85
	s_waitcnt lgkmcnt(2)
	v_add_f32_e32 v44, v44, v86
	ds_bpermute_b32 v84, v48, v46
	ds_bpermute_b32 v85, v48, v47
	ds_bpermute_b32 v86, v48, v22
	ds_bpermute_b32 v87, v48, v49
	v_add_f32_e32 v98, v45, v98
	v_add_f32_e32 v104, v18, v104
	v_add_f32_e32 v105, v52, v105
	v_add_f32_e32 v106, v53, v106
	v_cndmask_b32_e32 v50, v50, v103, vcc
	v_cndmask_b32_e32 v52, v52, v105, vcc
	v_cndmask_b32_e32 v53, v53, v106, vcc
	v_cndmask_b32_e32 v18, v18, v104, vcc
	v_cndmask_b32_e32 v45, v45, v98, vcc
	s_waitcnt lgkmcnt(5)
	v_add_f32_e32 v26, v26, v78
	ds_bpermute_b32 v78, v48, v30
	s_waitcnt lgkmcnt(5)
	v_add_f32_e32 v41, v41, v83
	ds_bpermute_b32 v83, v48, v45
	s_waitcnt lgkmcnt(5)
	v_add_f32_e32 v46, v46, v84
	s_waitcnt lgkmcnt(4)
	v_add_f32_e32 v47, v47, v85
	s_waitcnt lgkmcnt(3)
	v_add_f32_e32 v84, v22, v86
	s_waitcnt lgkmcnt(2)
	v_add_f32_e32 v49, v49, v87
	ds_bpermute_b32 v85, v48, v50
	ds_bpermute_b32 v86, v48, v18
	ds_bpermute_b32 v87, v48, v52
	ds_bpermute_b32 v88, v48, v53
	ds_bpermute_b32 v48, v48, v21
	v_cndmask_b32_e32 v19, v19, v105, vcc
	v_cndmask_b32_e32 v20, v20, v106, vcc
	s_waitcnt lgkmcnt(4)
	v_add_f32_e32 v50, v50, v85
	v_cmp_gt_i32_e32 vcc, 56, v68
	v_lshrrev_b32_e32 v255, 2, v115
	s_nop 0
	v_readfirstlane_b32 s101, v255
	s_nop 3
	s_waitcnt lgkmcnt(0)
	v_add_f32_e32 v48, v21, v48
	v_cmp_gt_u32_e64 s[0:1], 48, v113
	v_cndmask_b32_e32 v21, v21, v48, vcc
	v_cndmask_b32_e32 v48, v76, v50, vcc
	v_cndmask_b32_e64 v50, 0, 16, s[0:1]
	v_cndmask_b32_e32 v47, v74, v47, vcc
	v_cndmask_b32_e32 v40, v64, v40, vcc
	v_cndmask_b32_e32 v31, v58, v31, vcc
	v_cndmask_b32_e32 v23, v51, v23, vcc
	v_add_lshl_u32 v50, v50, v110, 2
	v_add_f32_e32 v52, v52, v87
	v_cndmask_b32_e32 v22, v22, v84, vcc
	v_cndmask_b32_e32 v44, v72, v44, vcc
	v_cndmask_b32_e32 v33, v33, v79, vcc
	v_cndmask_b32_e32 v32, v59, v32, vcc
	ds_bpermute_b32 v51, v50, v23
	v_cndmask_b32_e32 v24, v24, v71, vcc
	ds_bpermute_b32 v59, v50, v31
	ds_bpermute_b32 v72, v50, v40
	ds_bpermute_b32 v79, v50, v47
	v_cndmask_b32_e32 v19, v19, v52, vcc
	v_cndmask_b32_e32 v36, v36, v80, vcc
	ds_bpermute_b32 v52, v50, v24
	ds_bpermute_b32 v80, v50, v22
	v_cndmask_b32_e32 v28, v56, v28, vcc
	v_add_f32_e32 v78, v30, v78
	v_add_f32_e32 v83, v45, v83
	v_add_f32_e32 v85, v18, v86
	v_add_f32_e32 v53, v53, v88
	v_cndmask_b32_e32 v46, v73, v46, vcc
	v_cndmask_b32_e32 v43, v70, v43, vcc
	v_cndmask_b32_e32 v41, v65, v41, vcc
	v_cndmask_b32_e32 v29, v57, v29, vcc
	v_cndmask_b32_e32 v27, v27, v77, vcc
	v_cndmask_b32_e32 v26, v55, v26, vcc
	v_cndmask_b32_e32 v25, v54, v25, vcc
	ds_bpermute_b32 v56, v50, v28
	ds_bpermute_b32 v76, v50, v44
	v_cndmask_b32_e32 v20, v20, v53, vcc
	v_cndmask_b32_e32 v18, v18, v85, vcc
	v_cndmask_b32_e32 v49, v75, v49, vcc
	v_cndmask_b32_e32 v45, v45, v83, vcc
	v_cndmask_b32_e32 v42, v42, v82, vcc
	v_cndmask_b32_e32 v39, v39, v81, vcc
	v_cndmask_b32_e32 v38, v63, v38, vcc
	v_cndmask_b32_e32 v37, v62, v37, vcc
	v_cndmask_b32_e32 v35, v61, v35, vcc
	v_cndmask_b32_e32 v34, v60, v34, vcc
	v_cndmask_b32_e32 v30, v30, v78, vcc
	s_waitcnt lgkmcnt(7)
	v_add_f32_e32 v51, v23, v51
	ds_bpermute_b32 v53, v50, v25
	v_cmp_gt_i32_e32 vcc, 48, v68
	ds_bpermute_b32 v54, v50, v26
	ds_bpermute_b32 v55, v50, v27
	ds_bpermute_b32 v57, v50, v29
	ds_bpermute_b32 v60, v50, v32
	s_waitcnt lgkmcnt(11)
	v_add_f32_e32 v59, v31, v59
	ds_bpermute_b32 v73, v50, v41
	s_waitcnt lgkmcnt(11)
	v_add_f32_e32 v72, v40, v72
	ds_bpermute_b32 v75, v50, v43
	ds_bpermute_b32 v78, v50, v46
	s_waitcnt lgkmcnt(12)
	v_add_f32_e32 v79, v47, v79
	v_cndmask_b32_e32 v51, v23, v51, vcc
	s_waitcnt lgkmcnt(11)
	v_add_f32_e32 v52, v24, v52
	ds_bpermute_b32 v58, v50, v30
	ds_bpermute_b32 v61, v50, v33
	v_cndmask_b32_e32 v59, v31, v59, vcc
	v_cndmask_b32_e32 v72, v40, v72, vcc
	ds_bpermute_b32 v77, v50, v45
	v_cndmask_b32_e32 v79, v47, v79, vcc
	ds_bpermute_b32 v82, v50, v48
	s_waitcnt lgkmcnt(14)
	v_add_f32_e32 v80, v22, v80
	v_cndmask_b32_e32 v88, v23, v51, vcc
	v_cndmask_b32_e32 v93, v31, v59, vcc
	v_cndmask_b32_e32 v31, v40, v72, vcc
	v_cndmask_b32_e32 v23, v47, v79, vcc
	v_cndmask_b32_e32 v40, v22, v80, vcc
	v_cndmask_b32_e32 v47, v24, v52, vcc
	ds_bpermute_b32 v22, v114, v51
	ds_bpermute_b32 v24, v114, v47
	s_waitcnt lgkmcnt(15)
	v_add_f32_e32 v56, v28, v56
	s_waitcnt lgkmcnt(14)
	v_add_f32_e32 v76, v44, v76
	s_waitcnt lgkmcnt(13)
	v_add_f32_e32 v53, v25, v53
	s_waitcnt lgkmcnt(12)
	v_add_f32_e32 v54, v26, v54
	s_waitcnt lgkmcnt(11)
	v_add_f32_e32 v55, v27, v55
	v_cndmask_b32_e32 v56, v28, v56, vcc
	s_waitcnt lgkmcnt(10)
	v_add_f32_e32 v57, v29, v57
	ds_bpermute_b32 v62, v50, v34
	s_waitcnt lgkmcnt(10)
	v_add_f32_e32 v60, v32, v60
	ds_bpermute_b32 v63, v50, v35
	s_waitcnt lgkmcnt(10)
	v_add_f32_e32 v73, v41, v73
	s_waitcnt lgkmcnt(9)
	v_add_f32_e32 v75, v43, v75
	v_cndmask_b32_e32 v76, v44, v76, vcc
	s_waitcnt lgkmcnt(8)
	v_add_f32_e32 v78, v46, v78
	ds_bpermute_b32 v81, v50, v49
	v_cndmask_b32_e32 v53, v25, v53, vcc
	v_cndmask_b32_e32 v54, v26, v54, vcc
	v_cndmask_b32_e32 v57, v29, v57, vcc
	s_waitcnt lgkmcnt(8)
	v_add_f32_e32 v58, v30, v58
	v_cndmask_b32_e32 v60, v32, v60, vcc
	s_waitcnt lgkmcnt(7)
	v_add_f32_e32 v61, v33, v61
	v_cndmask_b32_e32 v73, v41, v73, vcc
	v_cndmask_b32_e32 v75, v43, v75, vcc
	s_waitcnt lgkmcnt(6)
	v_add_f32_e32 v77, v45, v77
	v_cndmask_b32_e32 v78, v46, v78, vcc
	s_waitcnt lgkmcnt(5)
	v_add_f32_e32 v82, v48, v82
	v_cndmask_b32_e32 v90, v28, v56, vcc
	v_cndmask_b32_e32 v28, v44, v76, vcc
	v_cndmask_b32_e32 v44, v27, v55, vcc
	ds_bpermute_b32 v64, v50, v36
	ds_bpermute_b32 v65, v50, v37
	ds_bpermute_b32 v70, v50, v38
	ds_bpermute_b32 v71, v50, v39
	ds_bpermute_b32 v74, v50, v42
	ds_bpermute_b32 v83, v50, v18
	ds_bpermute_b32 v84, v50, v19
	v_cndmask_b32_e32 v82, v48, v82, vcc
	ds_bpermute_b32 v85, v50, v20
	ds_bpermute_b32 v50, v50, v21
	v_cndmask_b32_e32 v86, v26, v54, vcc
	v_cndmask_b32_e32 v89, v29, v57, vcc
	v_cndmask_b32_e32 v92, v32, v60, vcc
	v_cndmask_b32_e32 v32, v41, v73, vcc
	v_cndmask_b32_e32 v29, v46, v78, vcc
	v_cndmask_b32_e32 v26, v43, v75, vcc
	v_cndmask_b32_e32 v41, v45, v77, vcc
	v_cndmask_b32_e32 v43, v33, v61, vcc
	v_cndmask_b32_e32 v45, v30, v58, vcc
	s_waitcnt lgkmcnt(13)
	v_add_f32_e32 v46, v51, v22
	ds_bpermute_b32 v22, v114, v53
	ds_bpermute_b32 v27, v114, v44
	ds_bpermute_b32 v30, v114, v56
	ds_bpermute_b32 v33, v114, v57
	v_cndmask_b32_e32 v87, v25, v53, vcc
	v_cndmask_b32_e32 v25, v48, v82, vcc
	s_waitcnt lgkmcnt(15)
	v_add_f32_e32 v48, v47, v24
	ds_bpermute_b32 v24, v114, v54
	s_waitcnt lgkmcnt(15)
	v_add_f32_e32 v62, v34, v62
	s_waitcnt lgkmcnt(15)
	v_add_f32_e32 v63, v35, v63
	s_waitcnt lgkmcnt(14)
	v_add_f32_e32 v81, v49, v81
	v_cndmask_b32_e32 v62, v34, v62, vcc
	v_cndmask_b32_e32 v63, v35, v63, vcc
	v_cndmask_b32_e32 v81, v49, v81, vcc
	s_waitcnt lgkmcnt(5)
	v_add_f32_e32 v50, v21, v50
	v_cndmask_b32_e32 v91, v34, v62, vcc
	v_cndmask_b32_e32 v34, v35, v63, vcc
	v_cndmask_b32_e32 v35, v49, v81, vcc
	s_waitcnt lgkmcnt(4)
	v_add_f32_e32 v49, v53, v22
	s_waitcnt lgkmcnt(3)
	v_add_f32_e32 v51, v44, v27
	s_waitcnt lgkmcnt(2)
	v_add_f32_e32 v52, v56, v30
	s_waitcnt lgkmcnt(1)
	v_add_f32_e32 v53, v57, v33
	ds_bpermute_b32 v22, v114, v45
	ds_bpermute_b32 v27, v114, v60
	ds_bpermute_b32 v30, v114, v43
	ds_bpermute_b32 v33, v114, v62
	v_cndmask_b32_e32 v21, v21, v50, vcc
	s_waitcnt lgkmcnt(4)
	v_add_f32_e32 v50, v54, v24
	ds_bpermute_b32 v24, v114, v59
	v_add_f32_e32 v65, v37, v65
	v_add_f32_e32 v70, v38, v70
	v_add_f32_e32 v71, v39, v71
	v_add_f32_e32 v64, v36, v64
	v_cndmask_b32_e32 v65, v37, v65, vcc
	v_cndmask_b32_e32 v70, v38, v70, vcc
	v_cndmask_b32_e32 v39, v39, v71, vcc
	v_cndmask_b32_e32 v36, v36, v64, vcc
	s_waitcnt lgkmcnt(4)
	v_add_f32_e32 v54, v45, v22
	s_waitcnt lgkmcnt(3)
	v_add_f32_e32 v56, v60, v27
	s_waitcnt lgkmcnt(2)
	v_add_f32_e32 v57, v43, v30
	s_waitcnt lgkmcnt(1)
	v_add_f32_e32 v58, v62, v33
	ds_bpermute_b32 v22, v114, v63
	ds_bpermute_b32 v27, v114, v65
	ds_bpermute_b32 v30, v114, v70
	ds_bpermute_b32 v33, v114, v39
	s_waitcnt lgkmcnt(4)
	v_add_f32_e32 v55, v59, v24
	ds_bpermute_b32 v24, v114, v36
	v_add_f32_e32 v74, v42, v74
	v_cndmask_b32_e32 v42, v42, v74, vcc
	s_waitcnt lgkmcnt(4)
	v_add_f32_e32 v59, v63, v22
	s_waitcnt lgkmcnt(3)
	v_add_f32_e32 v61, v65, v27
	s_waitcnt lgkmcnt(2)
	v_add_f32_e32 v62, v70, v30
	s_waitcnt lgkmcnt(1)
	v_add_f32_e32 v30, v39, v33
	ds_bpermute_b32 v22, v114, v72
	ds_bpermute_b32 v27, v114, v42
	ds_bpermute_b32 v33, v114, v75
	ds_bpermute_b32 v63, v114, v76
	s_waitcnt lgkmcnt(4)
	v_add_f32_e32 v60, v36, v24
	ds_bpermute_b32 v24, v114, v73
	v_cndmask_b32_e32 v38, v38, v70, vcc
	s_waitcnt lgkmcnt(4)
	v_add_f32_e32 v64, v72, v22
	s_waitcnt lgkmcnt(3)
	v_add_f32_e32 v70, v42, v27
	s_waitcnt lgkmcnt(2)
	v_add_f32_e32 v27, v75, v33
	s_waitcnt lgkmcnt(1)
	v_add_f32_e32 v33, v76, v63
	ds_bpermute_b32 v22, v114, v41
	ds_bpermute_b32 v63, v114, v79
	ds_bpermute_b32 v72, v114, v81
	v_cndmask_b32_e32 v37, v37, v65, vcc
	s_waitcnt lgkmcnt(3)
	v_add_f32_e32 v65, v73, v24
	ds_bpermute_b32 v24, v114, v78
	ds_bpermute_b32 v71, v114, v40
	v_add_f32_e32 v83, v18, v83
	v_add_f32_e32 v84, v19, v84
	v_add_f32_e32 v85, v20, v85
	s_lshl_b32 s0, s41, 3
	v_cndmask_b32_e32 v84, v19, v84, vcc
	v_cndmask_b32_e32 v85, v20, v85, vcc
	v_cndmask_b32_e32 v18, v18, v83, vcc
	s_or_b32 s0, s40, s0
	v_cndmask_b32_e32 v20, v20, v85, vcc
	v_cndmask_b32_e32 v19, v19, v84, vcc
	s_waitcnt lgkmcnt(4)
	v_add_f32_e32 v73, v41, v22
	s_waitcnt lgkmcnt(3)
	v_add_f32_e32 v22, v79, v63
	s_waitcnt lgkmcnt(2)
	v_add_f32_e32 v63, v81, v72
	ds_bpermute_b32 v72, v114, v18
	ds_bpermute_b32 v75, v114, v84
	ds_bpermute_b32 v76, v114, v85
	ds_bpermute_b32 v77, v114, v21
	v_cmp_gt_i32_e32 vcc, 32, v68
	s_mulk_i32 s0, 0x104
	s_waitcnt lgkmcnt(5)
	v_add_f32_e32 v74, v78, v24
	s_waitcnt lgkmcnt(4)
	v_add_f32_e32 v24, v40, v71
	ds_bpermute_b32 v71, v114, v82
	v_cndmask_b32_e32 v46, v88, v46, vcc
	s_or_b32 s0, s0, s39
	v_cndmask_b32_e32 v22, v23, v22, vcc
	v_cndmask_b32_e32 v23, v40, v24, vcc
	v_cndmask_b32_e32 v40, v43, v57, vcc
	v_cndmask_b32_e32 v43, v90, v52, vcc
	s_addk_i32 s0, 0x410
	s_mov_b32 s1, s7
	v_readlane_b32 s98, v46, s101
	s_lshl_b64 s[12:13], s[0:1], 13
	s_add_u32 s12, s11, s12
	s_waitcnt lgkmcnt(4)
	v_add_f32_e32 v72, v18, v72
	s_waitcnt lgkmcnt(3)
	v_add_f32_e32 v75, v84, v75
	s_waitcnt lgkmcnt(2)
	v_add_f32_e32 v76, v85, v76
	s_waitcnt lgkmcnt(1)
	v_add_f32_e32 v77, v21, v77
	v_cndmask_b32_e32 v26, v26, v27, vcc
	v_cndmask_b32_e32 v27, v28, v33, vcc
	v_cndmask_b32_e32 v33, v42, v70, vcc
	v_cndmask_b32_e32 v42, v44, v51, vcc
	v_cndmask_b32_e32 v47, v47, v48, vcc
	v_cndmask_b32_e32 v48, v87, v49, vcc
	v_cndmask_b32_e32 v49, v86, v50, vcc
	s_addc_u32 s13, s16, s13
	v_lshlrev_b64 v[50:51], 7, v[68:69]
	s_waitcnt lgkmcnt(0)
	v_add_f32_e32 v71, v82, v71
	v_cndmask_b32_e32 v18, v18, v72, vcc
	v_cndmask_b32_e32 v19, v19, v75, vcc
	v_cndmask_b32_e32 v20, v20, v76, vcc
	v_cndmask_b32_e32 v21, v21, v77, vcc
	v_cndmask_b32_e32 v24, v35, v63, vcc
	v_cndmask_b32_e32 v34, v34, v59, vcc
	v_cndmask_b32_e32 v35, v36, v60, vcc
	v_cndmask_b32_e32 v36, v37, v61, vcc
	v_cndmask_b32_e32 v37, v38, v62, vcc
	v_lshl_add_u64 v[50:51], s[12:13], 0, v[50:51]
	v_cndmask_b32_e32 v25, v25, v71, vcc
	v_cndmask_b32_e32 v28, v41, v73, vcc
	v_cndmask_b32_e32 v29, v29, v74, vcc
	v_cndmask_b32_e32 v30, v39, v30, vcc
	v_cndmask_b32_e32 v31, v31, v64, vcc
	v_cndmask_b32_e32 v32, v32, v65, vcc
	v_cndmask_b32_e32 v38, v93, v55, vcc
	v_cndmask_b32_e32 v39, v92, v56, vcc
	v_cndmask_b32_e32 v41, v91, v58, vcc
	v_cndmask_b32_e32 v44, v89, v53, vcc
	v_cndmask_b32_e32 v45, v45, v54, vcc
	global_store_dwordx4 v[50:51], v[46:49], off
	global_store_dwordx4 v[50:51], v[42:45], off offset:16
	global_store_dwordx4 v[50:51], v[38:41], off offset:32
	global_store_dwordx4 v[50:51], v[34:37], off offset:48
	global_store_dwordx4 v[50:51], v[30:33], off offset:64
	global_store_dwordx4 v[50:51], v[26:29], off offset:80
	global_store_dwordx4 v[50:51], v[22:25], off offset:96
	v_sub_f32_e32 v52, s98, v46
	global_store_dwordx4 v[50:51], v[18:21], off offset:112
	v_readlane_b32 s98, v47, s101
	v_mul_f32_e32 v52, 0x3fb8aa3b, v52
	v_exp_f32_e32 v52, v52
	v_lshlrev_b32_e32 v51, 16, v14
	v_and_b32_e32 v14, 0xffff0000, v14
	v_sub_f32_e32 v50, s98, v47
	v_mul_f32_e32 v51, v52, v51
	v_mul_f32_e32 v50, 0x3fb8aa3b, v50
	v_bfe_u32 v52, v51, 16, 1
	v_exp_f32_e32 v50, v50
	v_add3_u32 v51, v51, v52, s36
	ds_write_b16_d16_hi v66, v51 offset:8192
	v_readlane_b32 s98, v48, s101
	v_mul_f32_e32 v14, v50, v14
	v_bfe_u32 v50, v14, 16, 1
	v_add3_u32 v14, v14, v50, s36
	ds_write_b16_d16_hi v66, v14 offset:8320
	v_sub_f32_e32 v50, s98, v48
	v_readlane_b32 s98, v49, s101
	v_mul_f32_e32 v50, 0x3fb8aa3b, v50
	v_exp_f32_e32 v50, v50
	v_lshlrev_b32_e32 v51, 16, v15
	v_and_b32_e32 v15, 0xffff0000, v15
	v_sub_f32_e32 v14, s98, v49
	v_mul_f32_e32 v50, v50, v51
	v_mul_f32_e32 v14, 0x3fb8aa3b, v14
	v_bfe_u32 v51, v50, 16, 1
	v_exp_f32_e32 v14, v14
	v_add3_u32 v50, v50, v51, s36
	ds_write_b16_d16_hi v66, v50 offset:8448
	v_readlane_b32 s98, v42, s101
	v_mul_f32_e32 v14, v14, v15
	v_bfe_u32 v15, v14, 16, 1
	v_add3_u32 v14, v14, v15, s36
	ds_write_b16_d16_hi v66, v14 offset:8576
	v_sub_f32_e32 v15, s98, v42
	v_readlane_b32 s98, v43, s101
	v_mul_f32_e32 v15, 0x3fb8aa3b, v15
	v_exp_f32_e32 v15, v15
	v_lshlrev_b32_e32 v50, 16, v16
	v_and_b32_e32 v16, 0xffff0000, v16
	v_sub_f32_e32 v14, s98, v43
	v_mul_f32_e32 v15, v15, v50
	v_mul_f32_e32 v14, 0x3fb8aa3b, v14
	v_bfe_u32 v50, v15, 16, 1
	v_exp_f32_e32 v14, v14
	v_add3_u32 v15, v15, v50, s36
	ds_write_b16_d16_hi v66, v15 offset:8704
	v_readlane_b32 s98, v44, s101
	v_mul_f32_e32 v14, v14, v16
	v_bfe_u32 v16, v14, 16, 1
	v_add3_u32 v14, v14, v16, s36
	ds_write_b16_d16_hi v66, v14 offset:8832
	v_sub_f32_e32 v15, s98, v44
	v_readlane_b32 s98, v45, s101
	v_mul_f32_e32 v15, 0x3fb8aa3b, v15
	v_exp_f32_e32 v15, v15
	v_lshlrev_b32_e32 v16, 16, v17
	s_xor_b32 s0, s0, 3
	v_sub_f32_e32 v14, s98, v45
	v_mul_f32_e32 v15, v15, v16
	v_mul_f32_e32 v14, 0x3fb8aa3b, v14
	v_bfe_u32 v16, v15, 16, 1
	v_exp_f32_e32 v14, v14
	v_add3_u32 v15, v15, v16, s36
	ds_write_b16_d16_hi v66, v15 offset:8960
	v_readlane_b32 s98, v38, s101
	v_and_b32_e32 v16, 0xffff0000, v17
	v_mul_f32_e32 v14, v14, v16
	v_bfe_u32 v16, v14, 16, 1
	v_add3_u32 v14, v14, v16, s36
	v_sub_f32_e32 v15, s98, v38
	ds_write_b16_d16_hi v66, v14 offset:9088
	v_readlane_b32 s98, v39, s101
	v_mul_f32_e32 v15, 0x3fb8aa3b, v15
	v_exp_f32_e32 v15, v15
	v_lshlrev_b32_e32 v16, 16, v10
	v_and_b32_e32 v10, 0xffff0000, v10
	v_sub_f32_e32 v14, s98, v39
	v_mul_f32_e32 v15, v15, v16
	v_mul_f32_e32 v14, 0x3fb8aa3b, v14
	v_bfe_u32 v16, v15, 16, 1
	v_exp_f32_e32 v14, v14
	v_add3_u32 v15, v15, v16, s36
	ds_write_b16_d16_hi v66, v15 offset:9216
	v_readlane_b32 s98, v40, s101
	v_mul_f32_e32 v10, v14, v10
	v_bfe_u32 v14, v10, 16, 1
	v_add3_u32 v10, v10, v14, s36
	ds_write_b16_d16_hi v66, v10 offset:9344
	v_sub_f32_e32 v14, s98, v40
	v_readlane_b32 s98, v41, s101
	v_mul_f32_e32 v14, 0x3fb8aa3b, v14
	v_exp_f32_e32 v14, v14
	v_lshlrev_b32_e32 v15, 16, v11
	v_and_b32_e32 v11, 0xffff0000, v11
	v_sub_f32_e32 v10, s98, v41
	v_mul_f32_e32 v14, v14, v15
	v_mul_f32_e32 v10, 0x3fb8aa3b, v10
	v_bfe_u32 v15, v14, 16, 1
	v_exp_f32_e32 v10, v10
	v_add3_u32 v14, v14, v15, s36
	ds_write_b16_d16_hi v66, v14 offset:9472
	v_readlane_b32 s98, v34, s101
	v_mul_f32_e32 v10, v10, v11
	v_bfe_u32 v11, v10, 16, 1
	v_add3_u32 v10, v10, v11, s36
	ds_write_b16_d16_hi v66, v10 offset:9600
	v_sub_f32_e32 v11, s98, v34
	v_readlane_b32 s98, v35, s101
	v_mul_f32_e32 v11, 0x3fb8aa3b, v11
	v_exp_f32_e32 v11, v11
	v_lshlrev_b32_e32 v14, 16, v12
	v_and_b32_e32 v12, 0xffff0000, v12
	v_sub_f32_e32 v10, s98, v35
	v_mul_f32_e32 v11, v11, v14
	v_mul_f32_e32 v10, 0x3fb8aa3b, v10
	v_bfe_u32 v14, v11, 16, 1
	v_exp_f32_e32 v10, v10
	v_add3_u32 v11, v11, v14, s36
	ds_write_b16_d16_hi v66, v11 offset:9728
	v_readlane_b32 s98, v36, s101
	v_mul_f32_e32 v10, v10, v12
	v_bfe_u32 v12, v10, 16, 1
	v_add3_u32 v10, v10, v12, s36
	ds_write_b16_d16_hi v66, v10 offset:9856
	v_sub_f32_e32 v11, s98, v36
	v_readlane_b32 s98, v37, s101
	v_mul_f32_e32 v11, 0x3fb8aa3b, v11
	v_exp_f32_e32 v11, v11
	v_lshlrev_b32_e32 v12, 16, v13
	v_cmp_eq_u32_e32 vcc, 0, v68
	v_sub_f32_e32 v10, s98, v37
	v_mul_f32_e32 v11, v11, v12
	v_mul_f32_e32 v10, 0x3fb8aa3b, v10
	v_bfe_u32 v12, v11, 16, 1
	v_exp_f32_e32 v10, v10
	v_add3_u32 v11, v11, v12, s36
	ds_write_b16_d16_hi v66, v11 offset:9984
	v_readlane_b32 s98, v30, s101
	v_and_b32_e32 v12, 0xffff0000, v13
	v_mul_f32_e32 v10, v10, v12
	v_bfe_u32 v12, v10, 16, 1
	v_add3_u32 v10, v10, v12, s36
	v_sub_f32_e32 v11, s98, v30
	ds_write_b16_d16_hi v66, v10 offset:10112
	v_readlane_b32 s98, v31, s101
	v_mul_f32_e32 v11, 0x3fb8aa3b, v11
	v_exp_f32_e32 v11, v11
	v_lshlrev_b32_e32 v12, 16, v6
	v_and_b32_e32 v6, 0xffff0000, v6
	v_sub_f32_e32 v10, s98, v31
	v_mul_f32_e32 v11, v11, v12
	v_mul_f32_e32 v10, 0x3fb8aa3b, v10
	v_bfe_u32 v12, v11, 16, 1
	v_exp_f32_e32 v10, v10
	v_add3_u32 v11, v11, v12, s36
	ds_write_b16_d16_hi v66, v11 offset:10240
	v_readlane_b32 s98, v32, s101
	v_mul_f32_e32 v6, v10, v6
	v_bfe_u32 v10, v6, 16, 1
	v_add3_u32 v6, v6, v10, s36
	ds_write_b16_d16_hi v66, v6 offset:10368
	v_sub_f32_e32 v10, s98, v32
	v_readlane_b32 s98, v33, s101
	v_mul_f32_e32 v10, 0x3fb8aa3b, v10
	v_exp_f32_e32 v10, v10
	v_lshlrev_b32_e32 v11, 16, v7
	v_and_b32_e32 v7, 0xffff0000, v7
	v_sub_f32_e32 v6, s98, v33
	v_mul_f32_e32 v10, v10, v11
	v_mul_f32_e32 v6, 0x3fb8aa3b, v6
	v_bfe_u32 v11, v10, 16, 1
	v_exp_f32_e32 v6, v6
	v_add3_u32 v10, v10, v11, s36
	ds_write_b16_d16_hi v66, v10 offset:10496
	v_readlane_b32 s98, v26, s101
	v_mul_f32_e32 v6, v6, v7
	v_bfe_u32 v7, v6, 16, 1
	v_add3_u32 v6, v6, v7, s36
	ds_write_b16_d16_hi v66, v6 offset:10624
	v_sub_f32_e32 v7, s98, v26
	v_readlane_b32 s98, v27, s101
	v_mul_f32_e32 v7, 0x3fb8aa3b, v7
	v_exp_f32_e32 v7, v7
	v_lshlrev_b32_e32 v10, 16, v8
	v_and_b32_e32 v8, 0xffff0000, v8
	v_sub_f32_e32 v6, s98, v27
	v_mul_f32_e32 v7, v7, v10
	v_mul_f32_e32 v6, 0x3fb8aa3b, v6
	v_bfe_u32 v10, v7, 16, 1
	v_exp_f32_e32 v6, v6
	v_add3_u32 v7, v7, v10, s36
	ds_write_b16_d16_hi v66, v7 offset:10752
	v_readlane_b32 s98, v28, s101
	v_mul_f32_e32 v6, v6, v8
	v_bfe_u32 v8, v6, 16, 1
	v_add3_u32 v6, v6, v8, s36
	ds_write_b16_d16_hi v66, v6 offset:10880
	v_sub_f32_e32 v7, s98, v28
	v_readlane_b32 s98, v29, s101
	v_mul_f32_e32 v7, 0x3fb8aa3b, v7
	v_exp_f32_e32 v7, v7
	v_lshlrev_b32_e32 v8, 16, v9
	v_sub_f32_e32 v6, s98, v29
	v_mul_f32_e32 v7, v7, v8
	v_mul_f32_e32 v6, 0x3fb8aa3b, v6
	v_bfe_u32 v8, v7, 16, 1
	v_exp_f32_e32 v6, v6
	v_add3_u32 v7, v7, v8, s36
	ds_write_b16_d16_hi v66, v7 offset:11008
	v_readlane_b32 s98, v22, s101
	v_and_b32_e32 v8, 0xffff0000, v9
	v_mul_f32_e32 v6, v6, v8
	v_bfe_u32 v8, v6, 16, 1
	v_add3_u32 v6, v6, v8, s36
	v_sub_f32_e32 v7, s98, v22
	ds_write_b16_d16_hi v66, v6 offset:11136
	v_readlane_b32 s98, v23, s101
	v_mul_f32_e32 v7, 0x3fb8aa3b, v7
	v_exp_f32_e32 v7, v7
	v_lshlrev_b32_e32 v8, 16, v2
	v_and_b32_e32 v2, 0xffff0000, v2
	v_sub_f32_e32 v6, s98, v23
	v_mul_f32_e32 v7, v7, v8
	v_mul_f32_e32 v6, 0x3fb8aa3b, v6
	v_bfe_u32 v8, v7, 16, 1
	v_exp_f32_e32 v6, v6
	v_add3_u32 v7, v7, v8, s36
	ds_write_b16_d16_hi v66, v7 offset:11264
	v_readlane_b32 s98, v24, s101
	v_mul_f32_e32 v2, v6, v2
	v_bfe_u32 v6, v2, 16, 1
	v_add3_u32 v2, v2, v6, s36
	ds_write_b16_d16_hi v66, v2 offset:11392
	v_sub_f32_e32 v6, s98, v24
	v_readlane_b32 s98, v25, s101
	v_mul_f32_e32 v6, 0x3fb8aa3b, v6
	v_exp_f32_e32 v6, v6
	v_lshlrev_b32_e32 v7, 16, v3
	v_and_b32_e32 v3, 0xffff0000, v3
	v_sub_f32_e32 v2, s98, v25
	v_mul_f32_e32 v6, v6, v7
	v_mul_f32_e32 v2, 0x3fb8aa3b, v2
	v_bfe_u32 v7, v6, 16, 1
	v_exp_f32_e32 v2, v2
	v_add3_u32 v6, v6, v7, s36
	ds_write_b16_d16_hi v66, v6 offset:11520
	v_readlane_b32 s98, v18, s101
	v_mul_f32_e32 v2, v2, v3
	v_bfe_u32 v3, v2, 16, 1
	v_add3_u32 v2, v2, v3, s36
	ds_write_b16_d16_hi v66, v2 offset:11648
	v_sub_f32_e32 v3, s98, v18
	v_readlane_b32 s98, v19, s101
	v_mul_f32_e32 v3, 0x3fb8aa3b, v3
	v_exp_f32_e32 v3, v3
	v_lshlrev_b32_e32 v6, 16, v4
	v_and_b32_e32 v4, 0xffff0000, v4
	v_sub_f32_e32 v2, s98, v19
	v_mul_f32_e32 v3, v3, v6
	v_mul_f32_e32 v2, 0x3fb8aa3b, v2
	v_bfe_u32 v6, v3, 16, 1
	v_exp_f32_e32 v2, v2
	v_add3_u32 v3, v3, v6, s36
	ds_write_b16_d16_hi v66, v3 offset:11776
	v_readlane_b32 s98, v20, s101
	v_mul_f32_e32 v2, v2, v4
	v_bfe_u32 v4, v2, 16, 1
	v_add3_u32 v2, v2, v4, s36
	v_readlane_b32 s99, v21, s101
	v_sub_f32_e32 v3, s98, v20
	v_mul_f32_e32 v3, 0x3fb8aa3b, v3
	v_exp_f32_e32 v3, v3
	ds_write_b16_d16_hi v66, v2 offset:11904
	v_sub_f32_e32 v4, s99, v21
	v_lshlrev_b32_e32 v2, 16, v5
	v_mul_f32_e32 v4, 0x3fb8aa3b, v4
	v_mul_f32_e32 v2, v3, v2
	v_exp_f32_e32 v4, v4
	v_bfe_u32 v3, v2, 16, 1
	v_add3_u32 v2, v2, v3, s36
	ds_write_b16_d16_hi v66, v2 offset:12032
	v_and_b32_e32 v2, 0xffff0000, v5
	v_mul_f32_e32 v2, v4, v2
	v_bfe_u32 v3, v2, 16, 1
	v_add3_u32 v2, v2, v3, s36
	ds_write_b16_d16_hi v66, v2 offset:12160
	s_and_saveexec_b64 s[12:13], vcc
	s_cbranch_execz .LBB0_1958
	v_mul_f32_e32 v2, 0x3fb8aa3b, v46
	v_mul_f32_e32 v3, 0x3fb8aa3b, v47
	v_mul_f32_e32 v4, 0x3fb8aa3b, v48
	v_mul_f32_e32 v5, 0x3fb8aa3b, v49
	v_exp_f32_e32 v2, v2
	v_exp_f32_e32 v3, v3
	v_exp_f32_e32 v4, v4
	v_exp_f32_e32 v5, v5
	v_mul_f32_e32 v6, 0x3fb8aa3b, v42
	v_mul_f32_e32 v7, 0x3fb8aa3b, v43
	v_mul_f32_e32 v8, 0x3fb8aa3b, v44
	v_mul_f32_e32 v9, 0x3fb8aa3b, v45
	s_lshl_b64 s[14:15], s[0:1], 7
	v_exp_f32_e32 v6, v6
	v_exp_f32_e32 v7, v7
	v_exp_f32_e32 v8, v8
	v_exp_f32_e32 v9, v9
	v_mul_f32_e32 v10, 0x3fb8aa3b, v38
	v_mul_f32_e32 v11, 0x3fb8aa3b, v39
	v_mul_f32_e32 v12, 0x3fb8aa3b, v40
	v_mul_f32_e32 v13, 0x3fb8aa3b, v41
	s_add_u32 s14, s17, s14
	v_exp_f32_e32 v10, v10
	v_exp_f32_e32 v11, v11
	v_exp_f32_e32 v12, v12
	v_exp_f32_e32 v13, v13
	v_mul_f32_e32 v14, 0x3fb8aa3b, v34
	v_mul_f32_e32 v15, 0x3fb8aa3b, v35
	v_mul_f32_e32 v16, 0x3fb8aa3b, v36
	v_mul_f32_e32 v17, 0x3fb8aa3b, v37
	s_addc_u32 s15, s18, s15
	v_exp_f32_e32 v14, v14
	v_exp_f32_e32 v15, v15
	v_exp_f32_e32 v16, v16
	v_exp_f32_e32 v17, v17
	global_store_dwordx4 v67, v[2:5], s[14:15]
	global_store_dwordx4 v67, v[6:9], s[14:15] offset:16
	global_store_dwordx4 v67, v[10:13], s[14:15] offset:32
	global_store_dwordx4 v67, v[14:17], s[14:15] offset:48
	v_mul_f32_e32 v2, 0x3fb8aa3b, v30
	v_mul_f32_e32 v3, 0x3fb8aa3b, v31
	v_mul_f32_e32 v4, 0x3fb8aa3b, v32
	v_mul_f32_e32 v5, 0x3fb8aa3b, v33
	v_exp_f32_e32 v2, v2
	v_exp_f32_e32 v3, v3
	v_exp_f32_e32 v4, v4
	v_exp_f32_e32 v5, v5
	v_mul_f32_e32 v6, 0x3fb8aa3b, v26
	v_mul_f32_e32 v7, 0x3fb8aa3b, v27
	v_mul_f32_e32 v8, 0x3fb8aa3b, v28
	v_mul_f32_e32 v9, 0x3fb8aa3b, v29
	v_exp_f32_e32 v6, v6
	v_exp_f32_e32 v7, v7
	v_exp_f32_e32 v8, v8
	v_exp_f32_e32 v9, v9
	v_mul_f32_e32 v10, 0x3fb8aa3b, v22
	v_mul_f32_e32 v11, 0x3fb8aa3b, v23
	v_mul_f32_e32 v12, 0x3fb8aa3b, v24
	v_mul_f32_e32 v13, 0x3fb8aa3b, v25
	v_exp_f32_e32 v10, v10
	v_exp_f32_e32 v11, v11
	v_exp_f32_e32 v12, v12
	v_exp_f32_e32 v13, v13
	v_mul_f32_e32 v14, 0x3fb8aa3b, v18
	v_mul_f32_e32 v15, 0x3fb8aa3b, v19
	v_mul_f32_e32 v16, 0x3fb8aa3b, v20
	v_mul_f32_e32 v17, 0x3fb8aa3b, v21
	v_exp_f32_e32 v14, v14
	v_exp_f32_e32 v15, v15
	v_exp_f32_e32 v16, v16
	v_exp_f32_e32 v17, v17
	global_store_dwordx4 v67, v[2:5], s[14:15] offset:64
	global_store_dwordx4 v67, v[6:9], s[14:15] offset:80
	global_store_dwordx4 v67, v[10:13], s[14:15] offset:96
	global_store_dwordx4 v67, v[14:17], s[14:15] offset:112

.LBB0_1959:
	s_and_b64 vcc, exec, s[0:1]
	s_cbranch_vccz .LBB0_1953
	v_mov_b32_e32 v68, v109
	v_mov_b64_e32 v[2:3], s[22:23]
	v_add_u32_e32 v4, s33, v68
	v_mad_i64_i32 v[70:71], s[0:1], v4, s28, v[2:3]
	s_lshl_b32 s0, s6, 1
	s_mov_b32 s1, s7
	v_lshl_add_u64 v[30:31], v[70:71], 0, s[0:1]
	global_load_dwordx4 v[2:5], v[30:31], off offset:512
	global_load_dwordx4 v[6:9], v[30:31], off offset:528
	global_load_dwordx4 v[10:13], v[30:31], off offset:544
	global_load_dwordx4 v[14:17], v[30:31], off offset:560
	global_load_dwordx4 v[18:21], v[30:31], off offset:576
	global_load_dwordx4 v[22:25], v[30:31], off offset:592
	global_load_dwordx4 v[26:29], v[30:31], off offset:608
	s_nop 0
	global_load_dwordx4 v[30:33], v[30:31], off offset:624
	s_lshl_b32 s0, s40, 7
	global_load_dwordx4 v[34:37], v[70:71], off offset:1536
	v_readlane_b32 s44, v239, 33
	s_add_u32 s12, s8, s0
	v_mov_b32_e32 v123, s0
	v_readlane_b32 s52, v239, 41
	v_readlane_b32 s53, v239, 42
	s_addc_u32 s13, s9, 0
	s_nop 3
	global_load_dwordx4 v[38:41], v123, s[52:53] offset:512
	global_load_dwordx4 v[42:45], v123, s[8:9]
	global_load_dwordx4 v[46:49], v123, s[8:9] offset:512
	global_load_dwordx4 v[50:53], v123, s[8:9] offset:1024
	global_load_dwordx4 v[54:57], v123, s[8:9] offset:1536
	global_load_dwordx4 v[58:61], v123, s[8:9] offset:2048
	global_load_dwordx4 v[62:65], v123, s[8:9] offset:2560
	global_load_dwordx4 v[74:77], v123, s[8:9] offset:3072
	global_load_dwordx4 v[78:81], v123, s[8:9] offset:3584
	global_load_dwordx4 v[82:85], v111, s[12:13]
	global_load_dwordx4 v[86:89], v111, s[12:13] offset:512
	global_load_dwordx4 v[90:93], v[70:71], off offset:1552
	v_lshl_add_u32 v66, v68, 1, s25
	v_lshl_add_u64 v[70:71], v[70:71], 0, s[6:7]
	v_ashrrev_i32_e32 v69, 31, v68
	v_readlane_b32 s45, v239, 34
	v_readlane_b32 s46, v239, 35
	v_readlane_b32 s47, v239, 36
	v_readlane_b32 s48, v239, 37
	v_readlane_b32 s49, v239, 38
	v_readlane_b32 s50, v239, 39
	v_readlane_b32 s51, v239, 40
	v_readlane_b32 s54, v239, 43
	v_readlane_b32 s55, v239, 44
	v_readlane_b32 s56, v239, 45
	v_readlane_b32 s57, v239, 46
	v_readlane_b32 s58, v239, 47
	v_readlane_b32 s59, v239, 48
	s_waitcnt vmcnt(20)
	ds_write_b16 v66, v2
	ds_write_b16_d16_hi v66, v2 offset:128
	ds_write_b16 v66, v3 offset:256
	ds_write_b16_d16_hi v66, v3 offset:384
	ds_write_b16 v66, v4 offset:512
	ds_write_b16_d16_hi v66, v4 offset:640
	ds_write_b16 v66, v5 offset:768
	ds_write_b16_d16_hi v66, v5 offset:896
	s_waitcnt vmcnt(19)
	ds_write_b16 v66, v6 offset:1024
	ds_write_b16_d16_hi v66, v6 offset:1152
	ds_write_b16 v66, v7 offset:1280
	ds_write_b16_d16_hi v66, v7 offset:1408
	ds_write_b16 v66, v8 offset:1536
	ds_write_b16_d16_hi v66, v8 offset:1664
	ds_write_b16 v66, v9 offset:1792
	ds_write_b16_d16_hi v66, v9 offset:1920
	s_waitcnt vmcnt(18)
	ds_write_b16 v66, v10 offset:2048
	ds_write_b16_d16_hi v66, v10 offset:2176
	ds_write_b16 v66, v11 offset:2304
	ds_write_b16_d16_hi v66, v11 offset:2432
	ds_write_b16 v66, v12 offset:2560
	ds_write_b16_d16_hi v66, v12 offset:2688
	ds_write_b16 v66, v13 offset:2816
	ds_write_b16_d16_hi v66, v13 offset:2944
	s_waitcnt vmcnt(17)
	ds_write_b16 v66, v14 offset:3072
	ds_write_b16_d16_hi v66, v14 offset:3200
	ds_write_b16 v66, v15 offset:3328
	ds_write_b16_d16_hi v66, v15 offset:3456
	ds_write_b16 v66, v16 offset:3584
	ds_write_b16_d16_hi v66, v16 offset:3712
	ds_write_b16 v66, v17 offset:3840
	ds_write_b16_d16_hi v66, v17 offset:3968
	s_waitcnt vmcnt(16)
	ds_write_b16 v66, v18 offset:4096
	ds_write_b16_d16_hi v66, v18 offset:4224
	ds_write_b16 v66, v19 offset:4352
	ds_write_b16_d16_hi v66, v19 offset:4480
	ds_write_b16 v66, v20 offset:4608
	ds_write_b16_d16_hi v66, v20 offset:4736
	ds_write_b16 v66, v21 offset:4864
	ds_write_b16_d16_hi v66, v21 offset:4992
	s_waitcnt vmcnt(15)
	ds_write_b16 v66, v22 offset:5120
	ds_write_b16_d16_hi v66, v22 offset:5248
	ds_write_b16 v66, v23 offset:5376
	ds_write_b16_d16_hi v66, v23 offset:5504
	ds_write_b16 v66, v24 offset:5632
	ds_write_b16_d16_hi v66, v24 offset:5760
	ds_write_b16 v66, v25 offset:5888
	ds_write_b16_d16_hi v66, v25 offset:6016
	s_waitcnt vmcnt(14)
	ds_write_b16 v66, v26 offset:6144
	ds_write_b16_d16_hi v66, v26 offset:6272
	ds_write_b16 v66, v27 offset:6400
	ds_write_b16_d16_hi v66, v27 offset:6528
	ds_write_b16 v66, v28 offset:6656
	ds_write_b16_d16_hi v66, v28 offset:6784
	ds_write_b16 v66, v29 offset:6912
	ds_write_b16_d16_hi v66, v29 offset:7040
	s_waitcnt vmcnt(13)
	ds_write_b16 v66, v30 offset:7168
	ds_write_b16_d16_hi v66, v30 offset:7296
	ds_write_b16 v66, v31 offset:7424
	ds_write_b16_d16_hi v66, v31 offset:7552
	ds_write_b16 v66, v32 offset:7680
	ds_write_b16_d16_hi v66, v32 offset:7808
	ds_write_b16 v66, v33 offset:7936
	ds_write_b16_d16_hi v66, v33 offset:8064
	global_load_dwordx4 v[18:21], v111, s[12:13] offset:1024
	global_load_dwordx4 v[22:25], v111, s[12:13] offset:1536
	global_load_dwordx4 v[14:17], v[70:71], off offset:256
	global_load_dwordx4 v[10:13], v[70:71], off offset:272
	global_load_dwordx4 v[6:9], v[70:71], off offset:288
	global_load_dwordx4 v[2:5], v[70:71], off offset:304
	global_load_dwordx4 v[26:29], v111, s[12:13] offset:2048
	global_load_dwordx4 v[30:33], v111, s[12:13] offset:2560
	global_load_dwordx4 v[94:97], v111, s[12:13] offset:3072
	global_load_dwordx4 v[98:101], v111, s[12:13] offset:3584
	s_waitcnt vmcnt(22)
	v_lshlrev_b32_e32 v118, 16, v34
	v_and_b32_e32 v117, 0xffff0000, v34
	v_lshlrev_b32_e32 v120, 16, v36
	v_and_b32_e32 v119, 0xffff0000, v36
	s_waitcnt vmcnt(20)
	v_fma_f32 v36, v42, v118, v38
	v_lshlrev_b32_e32 v122, 16, v35
	s_waitcnt vmcnt(19)
	v_fmac_f32_e32 v36, v46, v117
	v_and_b32_e32 v121, 0xffff0000, v35
	s_waitcnt vmcnt(18)
	v_fmac_f32_e32 v36, v50, v122
	v_fma_f32 v38, v43, v118, v39
	s_waitcnt vmcnt(17)
	v_fmac_f32_e32 v36, v54, v121
	v_fmac_f32_e32 v38, v47, v117
	s_waitcnt vmcnt(16)
	v_fmac_f32_e32 v36, v58, v120
	v_fmac_f32_e32 v38, v51, v122
	v_and_b32_e32 v73, 0xffff0000, v37
	v_lshlrev_b32_e32 v72, 16, v37
	s_waitcnt vmcnt(14)
	v_mov_b32_e32 v34, v74
	s_waitcnt vmcnt(13)
	v_mov_b32_e32 v35, v78
	v_fmac_f32_e32 v36, v62, v119
	v_fmac_f32_e32 v38, v55, v121
	v_fma_f32 v39, v44, v118, v40
	v_pk_mul_f32 v[34:35], v[34:35], v[72:73]
	v_fmac_f32_e32 v38, v59, v120
	v_fmac_f32_e32 v39, v48, v117
	v_add_f32_e32 v34, v36, v34
	v_mov_b32_e32 v78, v75
	v_fmac_f32_e32 v38, v63, v119
	v_fmac_f32_e32 v39, v52, v122
	v_fmac_f32_e32 v41, v45, v118
	v_add_f32_e32 v36, v34, v35
	v_pk_mul_f32 v[34:35], v[78:79], v[72:73]
	v_fmac_f32_e32 v39, v56, v121
	v_fmac_f32_e32 v41, v49, v117
	v_add_f32_e32 v34, v34, v38
	v_fmac_f32_e32 v39, v60, v120
	v_fmac_f32_e32 v41, v53, v122
	v_add_f32_e32 v37, v35, v34
	v_mov_b32_e32 v34, v76
	v_mov_b32_e32 v35, v80
	v_fmac_f32_e32 v39, v64, v119
	v_fmac_f32_e32 v41, v57, v121
	v_pk_mul_f32 v[34:35], v[34:35], v[72:73]
	v_fmac_f32_e32 v41, v61, v120
	v_add_f32_e32 v34, v34, v39
	v_mov_b32_e32 v80, v77
	v_fmac_f32_e32 v41, v65, v119
	v_add_f32_e32 v38, v35, v34
	v_pk_mul_f32 v[34:35], v[80:81], v[72:73]
	s_waitcnt vmcnt(10)
	v_and_b32_e32 v75, 0xffff0000, v90
	v_add_f32_e32 v34, v34, v41
	v_add_f32_e32 v39, v35, v34
	v_lshlrev_b32_e32 v74, 16, v90
	v_mov_b32_e32 v34, v82
	v_mov_b32_e32 v35, v86
	v_pk_mul_f32 v[34:35], v[34:35], v[74:75]
	v_mov_b32_e32 v86, v83
	v_add_f32_e32 v34, v36, v34
	v_add_f32_e32 v36, v34, v35
	v_pk_mul_f32 v[34:35], v[86:87], v[74:75]
	v_and_b32_e32 v79, 0xffff0000, v91
	v_add_f32_e32 v34, v34, v37
	v_add_f32_e32 v37, v35, v34
	v_mov_b32_e32 v34, v84
	v_mov_b32_e32 v35, v88
	v_pk_mul_f32 v[34:35], v[34:35], v[74:75]
	v_mov_b32_e32 v88, v85
	v_add_f32_e32 v34, v34, v38
	v_add_f32_e32 v38, v35, v34
	v_pk_mul_f32 v[34:35], v[88:89], v[74:75]
	v_lshlrev_b32_e32 v78, 16, v91
	v_add_f32_e32 v34, v34, v39
	v_add_f32_e32 v39, v35, v34
	v_and_b32_e32 v81, 0xffff0000, v92
	v_lshlrev_b32_e32 v80, 16, v92
	v_and_b32_e32 v83, 0xffff0000, v93
	v_lshlrev_b32_e32 v82, 16, v93
	s_waitcnt vmcnt(9)
	v_mov_b32_e32 v34, v18
	s_waitcnt vmcnt(8)
	v_mov_b32_e32 v35, v22
	v_pk_mul_f32 v[34:35], v[34:35], v[78:79]
	v_mov_b32_e32 v22, v19
	v_add_f32_e32 v18, v36, v34
	v_add_f32_e32 v34, v18, v35
	v_pk_mul_f32 v[18:19], v[22:23], v[78:79]
	s_nop 0
	v_add_f32_e32 v18, v18, v37
	v_add_f32_e32 v22, v19, v18
	v_mov_b32_e32 v18, v20
	v_mov_b32_e32 v19, v24
	v_pk_mul_f32 v[18:19], v[18:19], v[78:79]
	v_mov_b32_e32 v24, v21
	v_add_f32_e32 v18, v18, v38
	v_add_f32_e32 v20, v19, v18
	v_pk_mul_f32 v[18:19], v[24:25], v[78:79]
	s_waitcnt vmcnt(0)
	v_mov_b32_e32 v21, v98
	v_add_f32_e32 v18, v18, v39
	v_add_f32_e32 v23, v19, v18
	v_mov_b32_e32 v18, v26
	v_mov_b32_e32 v19, v30
	v_pk_mul_f32 v[18:19], v[18:19], v[80:81]
	v_mov_b32_e32 v30, v27
	v_add_f32_e32 v18, v34, v18
	v_add_f32_e32 v24, v18, v19
	v_pk_mul_f32 v[18:19], v[30:31], v[80:81]
	v_mov_b32_e32 v98, v95
	v_add_f32_e32 v18, v18, v22
	v_add_f32_e32 v22, v19, v18
	v_mov_b32_e32 v18, v28
	v_mov_b32_e32 v19, v32
	v_pk_mul_f32 v[18:19], v[18:19], v[80:81]
	v_mov_b32_e32 v32, v29
	v_add_f32_e32 v18, v18, v20
	v_mov_b32_e32 v20, v94
	v_pk_mul_f32 v[20:21], v[20:21], v[82:83]
	s_nop 0
	v_add_f32_e32 v20, v24, v20
	v_add_f32_e32 v20, v20, v21
	v_mul_f32_e64 v21, |v20|, s29
	v_exp_f32_e32 v21, v21
	v_add_f32_e32 v24, v19, v18
	v_pk_mul_f32 v[18:19], v[32:33], v[80:81]
	v_add_f32_e32 v21, 1.0, v21
	v_cmp_gt_f32_e32 vcc, s30, v21
	v_add_f32_e32 v18, v18, v23
	v_add_f32_e32 v26, v19, v18
	v_cndmask_b32_e64 v25, 0, 32, vcc
	v_ldexp_f32 v21, v21, v25
	v_log_f32_e32 v25, v21
	v_min_f32_e32 v18, 0, v20
	v_pk_mul_f32 v[20:21], v[98:99], v[82:83]
	v_mov_b32_e32 v23, v100
	v_add_f32_e32 v20, v20, v22
	v_add_f32_e32 v21, v21, v20
	v_mul_f32_e64 v20, |v21|, s29
	v_exp_f32_e32 v20, v20
	v_mul_f32_e32 v19, 0x3f317217, v25
	v_fma_f32 v19, v25, s31, -v19
	v_fmac_f32_e32 v19, 0x3377d1cf, v25
	v_fmac_f32_e32 v19, 0x3f317217, v25
	v_cmp_lt_f32_e64 s[0:1], |v25|, s34
	v_add_f32_e32 v20, 1.0, v20
	v_mov_b32_e32 v100, v97
	v_cndmask_b32_e64 v19, v25, v19, s[0:1]
	v_cmp_gt_f32_e64 s[0:1], s30, v20
	s_nop 1
	v_cndmask_b32_e64 v22, 0, 32, s[0:1]
	v_ldexp_f32 v20, v20, v22
	v_mov_b32_e32 v22, v96
	v_pk_mul_f32 v[22:23], v[22:23], v[82:83]
	v_log_f32_e32 v25, v20
	v_add_f32_e32 v22, v22, v24
	v_add_f32_e32 v22, v23, v22
	v_mul_f32_e64 v23, |v22|, s29
	v_cndmask_b32_e32 v20, 0, v112, vcc
	v_exp_f32_e32 v23, v23
	v_sub_f32_e32 v20, v19, v20
	v_min_f32_e32 v19, 0, v21
	v_mul_f32_e32 v21, 0x3f317217, v25
	v_fma_f32 v21, v25, s31, -v21
	v_fmac_f32_e32 v21, 0x3377d1cf, v25
	v_fmac_f32_e32 v21, 0x3f317217, v25
	v_cmp_lt_f32_e64 vcc, |v25|, s34
	v_add_f32_e32 v23, 1.0, v23
	v_cndmask_b32_e64 v24, 0, v112, s[0:1]
	v_cndmask_b32_e32 v21, v25, v21, vcc
	v_cmp_gt_f32_e32 vcc, s30, v23
	v_sub_f32_e32 v21, v21, v24
	v_pk_add_f32 v[18:19], v[18:19], v[20:21] neg_lo:[0,1] neg_hi:[0,1]
	v_cndmask_b32_e64 v24, 0, 32, vcc
	v_ldexp_f32 v23, v23, v24
	v_pk_mul_f32 v[20:21], v[100:101], v[82:83]
	v_log_f32_e32 v23, v23
	v_add_f32_e32 v20, v20, v26
	v_add_f32_e32 v21, v21, v20
	v_mul_f32_e64 v20, |v21|, s29
	v_exp_f32_e32 v20, v20
	v_pk_mul_f32 v[70:71], v[18:19], s[10:11] op_sel_hi:[1,0]
	v_mul_f32_e32 v19, 0x3f317217, v23
	v_fma_f32 v19, v23, s31, -v19
	v_fmac_f32_e32 v19, 0x3377d1cf, v23
	v_fmac_f32_e32 v19, 0x3f317217, v23
	v_cmp_lt_f32_e64 s[0:1], |v23|, s34
	v_add_f32_e32 v20, 1.0, v20
	v_min_f32_e32 v18, 0, v22
	v_cndmask_b32_e64 v19, v23, v19, s[0:1]
	v_cmp_gt_f32_e64 s[0:1], s30, v20
	s_nop 1
	v_cndmask_b32_e64 v22, 0, 32, s[0:1]
	v_ldexp_f32 v20, v20, v22
	v_log_f32_e32 v22, v20
	v_cndmask_b32_e32 v20, 0, v112, vcc
	v_sub_f32_e32 v20, v19, v20
	v_min_f32_e32 v19, 0, v21
	v_mul_f32_e32 v21, 0x3f317217, v22
	v_fma_f32 v21, v22, s31, -v21
	v_fmac_f32_e32 v21, 0x3377d1cf, v22
	v_fmac_f32_e32 v21, 0x3f317217, v22
	v_cmp_lt_f32_e64 vcc, |v22|, s34
	s_nop 1
	v_cndmask_b32_e32 v21, v22, v21, vcc
	v_cndmask_b32_e64 v22, 0, v112, s[0:1]
	v_sub_f32_e32 v21, v21, v22
	v_pk_add_f32 v[18:19], v[18:19], v[20:21] neg_lo:[0,1] neg_hi:[0,1]
	s_nop 0
	v_pk_mul_f32 v[76:77], v[18:19], s[10:11] op_sel_hi:[1,0]
	global_load_dwordx4 v[18:21], v123, s[52:53] offset:528
	global_load_dwordx4 v[22:25], v123, s[8:9] offset:16
	global_load_dwordx4 v[26:29], v123, s[8:9] offset:3088
	global_load_dwordx4 v[30:33], v123, s[8:9] offset:3600
	global_load_dwordx4 v[34:37], v111, s[12:13] offset:16
	global_load_dwordx4 v[38:41], v111, s[12:13] offset:528
	global_load_dwordx4 v[42:45], v111, s[12:13] offset:1040
	global_load_dwordx4 v[46:49], v111, s[12:13] offset:1552
	global_load_dwordx4 v[50:53], v111, s[12:13] offset:2064
	global_load_dwordx4 v[54:57], v111, s[12:13] offset:2576
	global_load_dwordx4 v[58:61], v111, s[12:13] offset:3088
	global_load_dwordx4 v[62:65], v111, s[12:13] offset:3600
	global_load_dwordx4 v[84:87], v123, s[8:9] offset:528
	global_load_dwordx4 v[88:91], v123, s[8:9] offset:1040
	global_load_dwordx4 v[92:95], v123, s[8:9] offset:1552
	global_load_dwordx4 v[96:99], v123, s[8:9] offset:2064
	global_load_dwordx4 v[100:103], v123, s[8:9] offset:2576
	s_waitcnt vmcnt(15)
	v_fma_f32 v130, v22, v118, v18
	v_fma_f32 v20, v24, v118, v20
	s_waitcnt vmcnt(14)
	v_mov_b32_e32 v104, v26
	s_waitcnt vmcnt(13)
	v_mov_b32_e32 v105, v30
	v_fma_f32 v23, v23, v118, v19
	v_mov_b32_e32 v30, v27
	v_mov_b32_e32 v18, v28
	v_mov_b32_e32 v19, v32
	v_pk_mul_f32 v[26:27], v[104:105], v[72:73]
	s_waitcnt vmcnt(12)
	v_mov_b32_e32 v106, v34
	s_waitcnt vmcnt(11)
	v_mov_b32_e32 v107, v38
	s_waitcnt vmcnt(4)
	v_fmac_f32_e32 v130, v84, v117
	v_fmac_f32_e32 v20, v86, v117
	s_waitcnt vmcnt(3)
	v_fmac_f32_e32 v130, v88, v122
	v_fmac_f32_e32 v20, v90, v122
	s_waitcnt vmcnt(2)
	v_fmac_f32_e32 v130, v92, v121
	v_fmac_f32_e32 v20, v94, v121
	s_waitcnt vmcnt(1)
	v_fmac_f32_e32 v130, v96, v120
	v_fmac_f32_e32 v20, v98, v120
	s_waitcnt vmcnt(0)
	v_fmac_f32_e32 v130, v100, v119
	v_fmac_f32_e32 v23, v85, v117
	v_pk_mul_f32 v[18:19], v[18:19], v[72:73]
	v_fmac_f32_e32 v20, v102, v119
	v_add_f32_e32 v24, v130, v26
	v_mov_b32_e32 v38, v35
	v_pk_mul_f32 v[34:35], v[106:107], v[74:75]
	v_fmac_f32_e32 v23, v89, v122
	v_add_f32_e32 v18, v18, v20
	v_add_f32_e32 v20, v24, v27
	v_mov_b32_e32 v124, v42
	v_mov_b32_e32 v125, v46
	v_fmac_f32_e32 v23, v93, v121
	v_add_f32_e32 v20, v20, v34
	v_mov_b32_e32 v46, v43
	v_pk_mul_f32 v[42:43], v[124:125], v[78:79]
	v_fmac_f32_e32 v23, v97, v120
	v_add_f32_e32 v20, v20, v35
	v_mov_b32_e32 v126, v50
	v_mov_b32_e32 v127, v54
	v_pk_mul_f32 v[30:31], v[30:31], v[72:73]
	v_fmac_f32_e32 v23, v101, v119
	v_add_f32_e32 v20, v20, v42
	v_mov_b32_e32 v54, v51
	v_pk_mul_f32 v[50:51], v[126:127], v[80:81]
	v_add_f32_e32 v23, v30, v23
	v_add_f32_e32 v20, v20, v43
	v_mov_b32_e32 v128, v58
	v_mov_b32_e32 v129, v62
	v_pk_mul_f32 v[38:39], v[38:39], v[74:75]
	v_add_f32_e32 v23, v31, v23
	v_add_f32_e32 v20, v20, v50
	v_mov_b32_e32 v62, v59
	v_pk_mul_f32 v[58:59], v[128:129], v[82:83]
	v_add_f32_e32 v23, v38, v23
	v_add_f32_e32 v20, v20, v51
	v_pk_mul_f32 v[46:47], v[46:47], v[78:79]
	v_add_f32_e32 v23, v39, v23
	v_add_f32_e32 v20, v20, v58
	v_add_f32_e32 v23, v46, v23
	v_add_f32_e32 v20, v20, v59
	v_pk_mul_f32 v[54:55], v[54:55], v[80:81]
	v_add_f32_e32 v23, v47, v23
	v_mul_f32_e64 v24, |v20|, s29
	v_add_f32_e32 v23, v54, v23
	v_exp_f32_e32 v24, v24
	v_pk_mul_f32 v[62:63], v[62:63], v[82:83]
	v_add_f32_e32 v23, v55, v23
	v_add_f32_e32 v23, v62, v23
	v_add_f32_e32 v23, v63, v23
	v_mul_f32_e64 v26, |v23|, s29
	v_add_f32_e32 v27, v19, v18
	v_add_f32_e32 v19, 1.0, v24
	v_exp_f32_e32 v26, v26
	v_cmp_gt_f32_e32 vcc, s30, v19
	v_min_f32_e32 v18, 0, v20
	v_mov_b32_e32 v22, v36
	v_cndmask_b32_e64 v24, 0, 32, vcc
	v_ldexp_f32 v19, v19, v24
	v_log_f32_e32 v24, v19
	v_add_f32_e32 v20, 1.0, v26
	v_cmp_gt_f32_e64 s[0:1], s30, v20
	v_min_f32_e32 v19, 0, v23
	v_cndmask_b32_e32 v23, 0, v112, vcc
	v_cndmask_b32_e64 v26, 0, 32, s[0:1]
	v_ldexp_f32 v20, v20, v26
	v_mul_f32_e32 v26, 0x3f317217, v24
	v_fma_f32 v26, v24, s31, -v26
	v_fmac_f32_e32 v26, 0x3377d1cf, v24
	v_fmac_f32_e32 v26, 0x3f317217, v24
	v_cmp_lt_f32_e64 vcc, |v24|, s34
	v_log_f32_e32 v20, v20
	v_fmac_f32_e32 v21, v25, v118
	v_cndmask_b32_e32 v24, v24, v26, vcc
	v_sub_f32_e32 v26, v24, v23
	v_mov_b32_e32 v23, v40
	v_pk_mul_f32 v[22:23], v[22:23], v[74:75]
	v_mul_f32_e32 v28, 0x3f317217, v20
	v_add_f32_e32 v22, v22, v27
	v_add_f32_e32 v24, v23, v22
	v_mov_b32_e32 v22, v44
	v_mov_b32_e32 v23, v48
	v_pk_mul_f32 v[22:23], v[22:23], v[78:79]
	v_fma_f32 v28, v20, s31, -v28
	v_add_f32_e32 v22, v22, v24
	v_add_f32_e32 v24, v23, v22
	v_mov_b32_e32 v22, v52
	v_mov_b32_e32 v23, v56
	v_pk_mul_f32 v[22:23], v[22:23], v[80:81]
	v_fmac_f32_e32 v28, 0x3377d1cf, v20
	v_add_f32_e32 v22, v22, v24
	v_add_f32_e32 v24, v23, v22
	v_mov_b32_e32 v22, v60
	v_mov_b32_e32 v23, v64
	v_pk_mul_f32 v[22:23], v[22:23], v[82:83]
	v_fmac_f32_e32 v28, 0x3f317217, v20
	v_add_f32_e32 v22, v22, v24
	v_add_f32_e32 v22, v23, v22
	v_mul_f32_e64 v23, |v22|, s29
	v_exp_f32_e32 v23, v23
	v_cmp_lt_f32_e64 vcc, |v20|, s34
	v_cndmask_b32_e64 v24, 0, v112, s[0:1]
	v_fmac_f32_e32 v21, v87, v117
	v_cndmask_b32_e32 v20, v20, v28, vcc
	v_sub_f32_e32 v27, v20, v24
	v_add_f32_e32 v20, 1.0, v23
	v_fmac_f32_e32 v21, v91, v122
	v_cmp_gt_f32_e32 vcc, s30, v20
	v_fmac_f32_e32 v21, v95, v121
	v_pk_add_f32 v[18:19], v[18:19], v[26:27] neg_lo:[0,1] neg_hi:[0,1]
	v_cndmask_b32_e64 v23, 0, 32, vcc
	v_fmac_f32_e32 v21, v99, v120
	v_mov_b32_e32 v32, v29
	v_ldexp_f32 v20, v20, v23
	v_pk_mul_f32 v[84:85], v[18:19], s[10:11] op_sel_hi:[1,0]
	v_min_f32_e32 v18, 0, v22
	v_fmac_f32_e32 v21, v103, v119
	v_pk_mul_f32 v[22:23], v[32:33], v[72:73]
	v_log_f32_e32 v24, v20
	v_add_f32_e32 v20, v22, v21
	v_mov_b32_e32 v40, v37
	v_add_f32_e32 v22, v23, v20
	v_pk_mul_f32 v[20:21], v[40:41], v[74:75]
	v_mov_b32_e32 v48, v45
	v_add_f32_e32 v20, v20, v22
	v_add_f32_e32 v22, v21, v20
	v_pk_mul_f32 v[20:21], v[48:49], v[78:79]
	v_mov_b32_e32 v56, v53
	v_add_f32_e32 v20, v20, v22
	v_add_f32_e32 v22, v21, v20
	v_pk_mul_f32 v[20:21], v[56:57], v[80:81]
	v_mov_b32_e32 v64, v61
	v_add_f32_e32 v20, v20, v22
	v_add_f32_e32 v22, v21, v20
	v_pk_mul_f32 v[20:21], v[64:65], v[82:83]
	v_mul_f32_e32 v19, 0x3f317217, v24
	v_add_f32_e32 v20, v20, v22
	v_add_f32_e32 v21, v21, v20
	v_mul_f32_e64 v20, |v21|, s29
	v_exp_f32_e32 v20, v20
	v_fma_f32 v19, v24, s31, -v19
	v_fmac_f32_e32 v19, 0x3377d1cf, v24
	v_fmac_f32_e32 v19, 0x3f317217, v24
	v_cmp_lt_f32_e64 s[0:1], |v24|, s34
	v_add_f32_e32 v20, 1.0, v20
	s_nop 0
	v_cndmask_b32_e64 v19, v24, v19, s[0:1]
	v_cmp_gt_f32_e64 s[0:1], s30, v20
	s_nop 1
	v_cndmask_b32_e64 v22, 0, 32, s[0:1]
	v_ldexp_f32 v20, v20, v22
	v_log_f32_e32 v22, v20
	v_cndmask_b32_e32 v20, 0, v112, vcc
	v_sub_f32_e32 v20, v19, v20
	v_min_f32_e32 v19, 0, v21
	v_mul_f32_e32 v21, 0x3f317217, v22
	v_fma_f32 v21, v22, s31, -v21
	v_fmac_f32_e32 v21, 0x3377d1cf, v22
	v_fmac_f32_e32 v21, 0x3f317217, v22
	v_cmp_lt_f32_e64 vcc, |v22|, s34
	s_nop 1
	v_cndmask_b32_e32 v21, v22, v21, vcc
	v_cndmask_b32_e64 v22, 0, v112, s[0:1]
	v_sub_f32_e32 v21, v21, v22
	v_pk_add_f32 v[18:19], v[18:19], v[20:21] neg_lo:[0,1] neg_hi:[0,1]
	s_nop 0
	v_pk_mul_f32 v[86:87], v[18:19], s[10:11] op_sel_hi:[1,0]
	global_load_dwordx4 v[18:21], v123, s[52:53] offset:544
	global_load_dwordx4 v[22:25], v123, s[8:9] offset:32
	global_load_dwordx4 v[26:29], v123, s[8:9] offset:3104
	global_load_dwordx4 v[30:33], v123, s[8:9] offset:3616
	global_load_dwordx4 v[34:37], v111, s[12:13] offset:32
	global_load_dwordx4 v[38:41], v111, s[12:13] offset:544
	global_load_dwordx4 v[42:45], v111, s[12:13] offset:1056
	global_load_dwordx4 v[46:49], v111, s[12:13] offset:1568
	global_load_dwordx4 v[50:53], v111, s[12:13] offset:2080
	global_load_dwordx4 v[54:57], v111, s[12:13] offset:2592
	global_load_dwordx4 v[58:61], v111, s[12:13] offset:3104
	global_load_dwordx4 v[62:65], v111, s[12:13] offset:3616
	global_load_dwordx4 v[88:91], v123, s[8:9] offset:544
	global_load_dwordx4 v[92:95], v123, s[8:9] offset:1056
	global_load_dwordx4 v[96:99], v123, s[8:9] offset:1568
	global_load_dwordx4 v[100:103], v123, s[8:9] offset:2080
	global_load_dwordx4 v[104:107], v123, s[8:9] offset:2592
	s_waitcnt vmcnt(15)
	v_fma_f32 v134, v22, v118, v18
	v_fma_f32 v20, v24, v118, v20
	s_waitcnt vmcnt(14)
	v_mov_b32_e32 v124, v26
	s_waitcnt vmcnt(13)
	v_mov_b32_e32 v125, v30
	v_fma_f32 v23, v23, v118, v19
	v_mov_b32_e32 v30, v27
	v_mov_b32_e32 v18, v28
	v_mov_b32_e32 v19, v32
	v_pk_mul_f32 v[26:27], v[124:125], v[72:73]
	s_waitcnt vmcnt(12)
	v_mov_b32_e32 v126, v34
	s_waitcnt vmcnt(11)
	v_mov_b32_e32 v127, v38
	s_waitcnt vmcnt(4)
	v_fmac_f32_e32 v134, v88, v117
	v_fmac_f32_e32 v20, v90, v117
	s_waitcnt vmcnt(3)
	v_fmac_f32_e32 v134, v92, v122
	v_fmac_f32_e32 v20, v94, v122
	s_waitcnt vmcnt(2)
	v_fmac_f32_e32 v134, v96, v121
	v_fmac_f32_e32 v20, v98, v121
	s_waitcnt vmcnt(1)
	v_fmac_f32_e32 v134, v100, v120
	v_fmac_f32_e32 v20, v102, v120
	s_waitcnt vmcnt(0)
	v_fmac_f32_e32 v134, v104, v119
	v_fmac_f32_e32 v23, v89, v117
	v_pk_mul_f32 v[18:19], v[18:19], v[72:73]
	v_fmac_f32_e32 v20, v106, v119
	v_add_f32_e32 v24, v134, v26
	v_mov_b32_e32 v38, v35
	v_pk_mul_f32 v[34:35], v[126:127], v[74:75]
	v_fmac_f32_e32 v23, v93, v122
	v_add_f32_e32 v18, v18, v20
	v_add_f32_e32 v20, v24, v27
	v_mov_b32_e32 v128, v42
	v_mov_b32_e32 v129, v46
	v_fmac_f32_e32 v23, v97, v121
	v_add_f32_e32 v20, v20, v34
	v_mov_b32_e32 v46, v43
	v_pk_mul_f32 v[42:43], v[128:129], v[78:79]
	v_fmac_f32_e32 v23, v101, v120
	v_add_f32_e32 v20, v20, v35
	v_mov_b32_e32 v130, v50
	v_mov_b32_e32 v131, v54
	v_pk_mul_f32 v[30:31], v[30:31], v[72:73]
	v_fmac_f32_e32 v23, v105, v119
	v_add_f32_e32 v20, v20, v42
	v_mov_b32_e32 v54, v51
	v_pk_mul_f32 v[50:51], v[130:131], v[80:81]
	v_add_f32_e32 v23, v30, v23
	v_add_f32_e32 v20, v20, v43
	v_mov_b32_e32 v132, v58
	v_mov_b32_e32 v133, v62
	v_pk_mul_f32 v[38:39], v[38:39], v[74:75]
	v_add_f32_e32 v23, v31, v23
	v_add_f32_e32 v20, v20, v50
	v_mov_b32_e32 v62, v59
	v_pk_mul_f32 v[58:59], v[132:133], v[82:83]
	v_add_f32_e32 v23, v38, v23
	v_add_f32_e32 v20, v20, v51
	v_pk_mul_f32 v[46:47], v[46:47], v[78:79]
	v_add_f32_e32 v23, v39, v23
	v_add_f32_e32 v20, v20, v58
	v_add_f32_e32 v23, v46, v23
	v_add_f32_e32 v20, v20, v59
	v_pk_mul_f32 v[54:55], v[54:55], v[80:81]
	v_add_f32_e32 v23, v47, v23
	v_mul_f32_e64 v24, |v20|, s29
	v_add_f32_e32 v23, v54, v23
	v_exp_f32_e32 v24, v24
	v_pk_mul_f32 v[62:63], v[62:63], v[82:83]
	v_add_f32_e32 v23, v55, v23
	v_add_f32_e32 v23, v62, v23
	v_add_f32_e32 v23, v63, v23
	v_mul_f32_e64 v26, |v23|, s29
	v_add_f32_e32 v27, v19, v18
	v_add_f32_e32 v19, 1.0, v24
	v_exp_f32_e32 v26, v26
	v_cmp_gt_f32_e32 vcc, s30, v19
	v_min_f32_e32 v18, 0, v20
	v_mov_b32_e32 v22, v36
	v_cndmask_b32_e64 v24, 0, 32, vcc
	v_ldexp_f32 v19, v19, v24
	v_log_f32_e32 v24, v19
	v_add_f32_e32 v20, 1.0, v26
	v_cmp_gt_f32_e64 s[0:1], s30, v20
	v_min_f32_e32 v19, 0, v23
	v_cndmask_b32_e32 v23, 0, v112, vcc
	v_cndmask_b32_e64 v26, 0, 32, s[0:1]
	v_ldexp_f32 v20, v20, v26
	v_mul_f32_e32 v26, 0x3f317217, v24
	v_fma_f32 v26, v24, s31, -v26
	v_fmac_f32_e32 v26, 0x3377d1cf, v24
	v_fmac_f32_e32 v26, 0x3f317217, v24
	v_cmp_lt_f32_e64 vcc, |v24|, s34
	v_log_f32_e32 v20, v20
	v_fmac_f32_e32 v21, v25, v118
	v_cndmask_b32_e32 v24, v24, v26, vcc
	v_sub_f32_e32 v26, v24, v23
	v_mov_b32_e32 v23, v40
	v_pk_mul_f32 v[22:23], v[22:23], v[74:75]
	v_mul_f32_e32 v28, 0x3f317217, v20
	v_add_f32_e32 v22, v22, v27
	v_add_f32_e32 v24, v23, v22
	v_mov_b32_e32 v22, v44
	v_mov_b32_e32 v23, v48
	v_pk_mul_f32 v[22:23], v[22:23], v[78:79]
	v_fma_f32 v28, v20, s31, -v28
	v_add_f32_e32 v22, v22, v24
	v_add_f32_e32 v24, v23, v22
	v_mov_b32_e32 v22, v52
	v_mov_b32_e32 v23, v56
	v_pk_mul_f32 v[22:23], v[22:23], v[80:81]
	v_fmac_f32_e32 v28, 0x3377d1cf, v20
	v_add_f32_e32 v22, v22, v24
	v_add_f32_e32 v24, v23, v22
	v_mov_b32_e32 v22, v60
	v_mov_b32_e32 v23, v64
	v_pk_mul_f32 v[22:23], v[22:23], v[82:83]
	v_fmac_f32_e32 v28, 0x3f317217, v20
	v_add_f32_e32 v22, v22, v24
	v_add_f32_e32 v22, v23, v22
	v_mul_f32_e64 v23, |v22|, s29
	v_exp_f32_e32 v23, v23
	v_cmp_lt_f32_e64 vcc, |v20|, s34
	v_cndmask_b32_e64 v24, 0, v112, s[0:1]
	v_fmac_f32_e32 v21, v91, v117
	v_cndmask_b32_e32 v20, v20, v28, vcc
	v_sub_f32_e32 v27, v20, v24
	v_add_f32_e32 v20, 1.0, v23
	v_fmac_f32_e32 v21, v95, v122
	v_cmp_gt_f32_e32 vcc, s30, v20
	v_fmac_f32_e32 v21, v99, v121
	v_pk_add_f32 v[18:19], v[18:19], v[26:27] neg_lo:[0,1] neg_hi:[0,1]
	v_cndmask_b32_e64 v23, 0, 32, vcc
	v_fmac_f32_e32 v21, v103, v120
	v_mov_b32_e32 v32, v29
	v_ldexp_f32 v20, v20, v23
	v_pk_mul_f32 v[88:89], v[18:19], s[10:11] op_sel_hi:[1,0]
	v_min_f32_e32 v18, 0, v22
	v_fmac_f32_e32 v21, v107, v119
	v_pk_mul_f32 v[22:23], v[32:33], v[72:73]
	v_log_f32_e32 v24, v20
	v_add_f32_e32 v20, v22, v21
	v_mov_b32_e32 v40, v37
	v_add_f32_e32 v22, v23, v20
	v_pk_mul_f32 v[20:21], v[40:41], v[74:75]
	v_mov_b32_e32 v48, v45
	v_add_f32_e32 v20, v20, v22
	v_add_f32_e32 v22, v21, v20
	v_pk_mul_f32 v[20:21], v[48:49], v[78:79]
	v_mov_b32_e32 v56, v53
	v_add_f32_e32 v20, v20, v22
	v_add_f32_e32 v22, v21, v20
	v_pk_mul_f32 v[20:21], v[56:57], v[80:81]
	v_mov_b32_e32 v64, v61
	v_add_f32_e32 v20, v20, v22
	v_add_f32_e32 v22, v21, v20
	v_pk_mul_f32 v[20:21], v[64:65], v[82:83]
	v_mul_f32_e32 v19, 0x3f317217, v24
	v_add_f32_e32 v20, v20, v22
	v_add_f32_e32 v21, v21, v20
	v_mul_f32_e64 v20, |v21|, s29
	v_exp_f32_e32 v20, v20
	v_fma_f32 v19, v24, s31, -v19
	v_fmac_f32_e32 v19, 0x3377d1cf, v24
	v_fmac_f32_e32 v19, 0x3f317217, v24
	v_cmp_lt_f32_e64 s[0:1], |v24|, s34
	v_add_f32_e32 v20, 1.0, v20
	s_nop 0
	v_cndmask_b32_e64 v19, v24, v19, s[0:1]
	v_cmp_gt_f32_e64 s[0:1], s30, v20
	s_nop 1
	v_cndmask_b32_e64 v22, 0, 32, s[0:1]
	v_ldexp_f32 v20, v20, v22
	v_log_f32_e32 v22, v20
	v_cndmask_b32_e32 v20, 0, v112, vcc
	v_sub_f32_e32 v20, v19, v20
	v_min_f32_e32 v19, 0, v21
	v_mul_f32_e32 v21, 0x3f317217, v22
	v_fma_f32 v21, v22, s31, -v21
	v_fmac_f32_e32 v21, 0x3377d1cf, v22
	v_fmac_f32_e32 v21, 0x3f317217, v22
	v_cmp_lt_f32_e64 vcc, |v22|, s34
	s_nop 1
	v_cndmask_b32_e32 v21, v22, v21, vcc
	v_cndmask_b32_e64 v22, 0, v112, s[0:1]
	v_sub_f32_e32 v21, v21, v22
	v_pk_add_f32 v[18:19], v[18:19], v[20:21] neg_lo:[0,1] neg_hi:[0,1]
	s_nop 0
	v_pk_mul_f32 v[90:91], v[18:19], s[10:11] op_sel_hi:[1,0]
	global_load_dwordx4 v[18:21], v123, s[52:53] offset:560
	global_load_dwordx4 v[22:25], v123, s[8:9] offset:48
	global_load_dwordx4 v[26:29], v123, s[8:9] offset:3120
	global_load_dwordx4 v[30:33], v123, s[8:9] offset:3632
	global_load_dwordx4 v[34:37], v111, s[12:13] offset:48
	global_load_dwordx4 v[38:41], v111, s[12:13] offset:560
	global_load_dwordx4 v[42:45], v111, s[12:13] offset:1072
	global_load_dwordx4 v[46:49], v111, s[12:13] offset:1584
	global_load_dwordx4 v[50:53], v111, s[12:13] offset:2096
	global_load_dwordx4 v[54:57], v111, s[12:13] offset:2608
	global_load_dwordx4 v[58:61], v111, s[12:13] offset:3120
	global_load_dwordx4 v[62:65], v111, s[12:13] offset:3632
	global_load_dwordx4 v[92:95], v123, s[8:9] offset:560
	global_load_dwordx4 v[96:99], v123, s[8:9] offset:1072
	global_load_dwordx4 v[100:103], v123, s[8:9] offset:1584
	global_load_dwordx4 v[104:107], v123, s[8:9] offset:2096
	global_load_dwordx4 v[124:127], v123, s[8:9] offset:2608
	s_waitcnt vmcnt(15)
	v_fma_f32 v138, v22, v118, v18
	v_fma_f32 v20, v24, v118, v20
	s_waitcnt vmcnt(14)
	v_mov_b32_e32 v128, v26
	s_waitcnt vmcnt(13)
	v_mov_b32_e32 v129, v30
	v_fma_f32 v23, v23, v118, v19
	v_mov_b32_e32 v30, v27
	v_mov_b32_e32 v18, v28
	v_mov_b32_e32 v19, v32
	v_pk_mul_f32 v[26:27], v[128:129], v[72:73]
	s_waitcnt vmcnt(12)
	v_mov_b32_e32 v130, v34
	s_waitcnt vmcnt(11)
	v_mov_b32_e32 v131, v38
	s_waitcnt vmcnt(4)
	v_fmac_f32_e32 v138, v92, v117
	v_fmac_f32_e32 v20, v94, v117
	s_waitcnt vmcnt(3)
	v_fmac_f32_e32 v138, v96, v122
	v_fmac_f32_e32 v20, v98, v122
	s_waitcnt vmcnt(2)
	v_fmac_f32_e32 v138, v100, v121
	v_fmac_f32_e32 v20, v102, v121
	s_waitcnt vmcnt(1)
	v_fmac_f32_e32 v138, v104, v120
	v_fmac_f32_e32 v20, v106, v120
	s_waitcnt vmcnt(0)
	v_fmac_f32_e32 v138, v124, v119
	v_fmac_f32_e32 v23, v93, v117
	v_pk_mul_f32 v[18:19], v[18:19], v[72:73]
	v_fmac_f32_e32 v20, v126, v119
	v_add_f32_e32 v24, v138, v26
	v_mov_b32_e32 v38, v35
	v_pk_mul_f32 v[34:35], v[130:131], v[74:75]
	v_fmac_f32_e32 v23, v97, v122
	v_add_f32_e32 v18, v18, v20
	v_add_f32_e32 v20, v24, v27
	v_mov_b32_e32 v132, v42
	v_mov_b32_e32 v133, v46
	v_fmac_f32_e32 v23, v101, v121
	v_add_f32_e32 v20, v20, v34
	v_mov_b32_e32 v46, v43
	v_pk_mul_f32 v[42:43], v[132:133], v[78:79]
	v_fmac_f32_e32 v23, v105, v120
	v_add_f32_e32 v20, v20, v35
	v_mov_b32_e32 v134, v50
	v_mov_b32_e32 v135, v54
	v_pk_mul_f32 v[30:31], v[30:31], v[72:73]
	v_fmac_f32_e32 v23, v125, v119
	v_add_f32_e32 v20, v20, v42
	v_mov_b32_e32 v54, v51
	v_pk_mul_f32 v[50:51], v[134:135], v[80:81]
	v_add_f32_e32 v23, v30, v23
	v_add_f32_e32 v20, v20, v43
	v_mov_b32_e32 v136, v58
	v_mov_b32_e32 v137, v62
	v_pk_mul_f32 v[38:39], v[38:39], v[74:75]
	v_add_f32_e32 v23, v31, v23
	v_add_f32_e32 v20, v20, v50
	v_mov_b32_e32 v62, v59
	v_pk_mul_f32 v[58:59], v[136:137], v[82:83]
	v_add_f32_e32 v23, v38, v23
	v_add_f32_e32 v20, v20, v51
	v_pk_mul_f32 v[46:47], v[46:47], v[78:79]
	v_add_f32_e32 v23, v39, v23
	v_add_f32_e32 v20, v20, v58
	v_add_f32_e32 v23, v46, v23
	v_add_f32_e32 v20, v20, v59
	v_pk_mul_f32 v[54:55], v[54:55], v[80:81]
	v_add_f32_e32 v23, v47, v23
	v_mul_f32_e64 v24, |v20|, s29
	v_add_f32_e32 v23, v54, v23
	v_exp_f32_e32 v24, v24
	v_pk_mul_f32 v[62:63], v[62:63], v[82:83]
	v_add_f32_e32 v23, v55, v23
	v_add_f32_e32 v23, v62, v23
	v_add_f32_e32 v23, v63, v23
	v_mul_f32_e64 v26, |v23|, s29
	v_add_f32_e32 v27, v19, v18
	v_add_f32_e32 v19, 1.0, v24
	v_exp_f32_e32 v26, v26
	v_cmp_gt_f32_e32 vcc, s30, v19
	v_min_f32_e32 v18, 0, v20
	v_mov_b32_e32 v22, v36
	v_cndmask_b32_e64 v24, 0, 32, vcc
	v_ldexp_f32 v19, v19, v24
	v_log_f32_e32 v24, v19
	v_add_f32_e32 v20, 1.0, v26
	v_cmp_gt_f32_e64 s[0:1], s30, v20
	v_min_f32_e32 v19, 0, v23
	v_cndmask_b32_e32 v23, 0, v112, vcc
	v_cndmask_b32_e64 v26, 0, 32, s[0:1]
	v_ldexp_f32 v20, v20, v26
	v_mul_f32_e32 v26, 0x3f317217, v24
	v_fma_f32 v26, v24, s31, -v26
	v_fmac_f32_e32 v26, 0x3377d1cf, v24
	v_fmac_f32_e32 v26, 0x3f317217, v24
	v_cmp_lt_f32_e64 vcc, |v24|, s34
	v_log_f32_e32 v20, v20
	v_fmac_f32_e32 v21, v25, v118
	v_cndmask_b32_e32 v24, v24, v26, vcc
	v_sub_f32_e32 v26, v24, v23
	v_mov_b32_e32 v23, v40
	v_pk_mul_f32 v[22:23], v[22:23], v[74:75]
	v_mul_f32_e32 v28, 0x3f317217, v20
	v_add_f32_e32 v22, v22, v27
	v_add_f32_e32 v24, v23, v22
	v_mov_b32_e32 v22, v44
	v_mov_b32_e32 v23, v48
	v_pk_mul_f32 v[22:23], v[22:23], v[78:79]
	v_fma_f32 v28, v20, s31, -v28
	v_add_f32_e32 v22, v22, v24
	v_add_f32_e32 v24, v23, v22
	v_mov_b32_e32 v22, v52
	v_mov_b32_e32 v23, v56
	v_pk_mul_f32 v[22:23], v[22:23], v[80:81]
	v_fmac_f32_e32 v28, 0x3377d1cf, v20
	v_add_f32_e32 v22, v22, v24
	v_add_f32_e32 v24, v23, v22
	v_mov_b32_e32 v22, v60
	v_mov_b32_e32 v23, v64
	v_pk_mul_f32 v[22:23], v[22:23], v[82:83]
	v_fmac_f32_e32 v28, 0x3f317217, v20
	v_add_f32_e32 v22, v22, v24
	v_add_f32_e32 v22, v23, v22
	v_mul_f32_e64 v23, |v22|, s29
	v_exp_f32_e32 v23, v23
	v_cmp_lt_f32_e64 vcc, |v20|, s34
	v_cndmask_b32_e64 v24, 0, v112, s[0:1]
	v_fmac_f32_e32 v21, v95, v117
	v_cndmask_b32_e32 v20, v20, v28, vcc
	v_sub_f32_e32 v27, v20, v24
	v_add_f32_e32 v20, 1.0, v23
	v_fmac_f32_e32 v21, v99, v122
	v_cmp_gt_f32_e32 vcc, s30, v20
	v_fmac_f32_e32 v21, v103, v121
	v_pk_add_f32 v[18:19], v[18:19], v[26:27] neg_lo:[0,1] neg_hi:[0,1]
	v_cndmask_b32_e64 v23, 0, 32, vcc
	v_fmac_f32_e32 v21, v107, v120
	v_mov_b32_e32 v32, v29
	v_ldexp_f32 v20, v20, v23
	v_pk_mul_f32 v[92:93], v[18:19], s[10:11] op_sel_hi:[1,0]
	v_min_f32_e32 v18, 0, v22
	v_fmac_f32_e32 v21, v127, v119
	v_pk_mul_f32 v[22:23], v[32:33], v[72:73]
	v_log_f32_e32 v24, v20
	v_add_f32_e32 v20, v22, v21
	v_mov_b32_e32 v40, v37
	v_add_f32_e32 v22, v23, v20
	v_pk_mul_f32 v[20:21], v[40:41], v[74:75]
	v_mov_b32_e32 v48, v45
	v_add_f32_e32 v20, v20, v22
	v_add_f32_e32 v22, v21, v20
	v_pk_mul_f32 v[20:21], v[48:49], v[78:79]
	v_mov_b32_e32 v56, v53
	v_add_f32_e32 v20, v20, v22
	v_add_f32_e32 v22, v21, v20
	v_pk_mul_f32 v[20:21], v[56:57], v[80:81]
	v_mov_b32_e32 v64, v61
	v_add_f32_e32 v20, v20, v22
	v_add_f32_e32 v22, v21, v20
	v_pk_mul_f32 v[20:21], v[64:65], v[82:83]
	v_mul_f32_e32 v19, 0x3f317217, v24
	v_add_f32_e32 v20, v20, v22
	v_add_f32_e32 v21, v21, v20
	v_mul_f32_e64 v20, |v21|, s29
	v_exp_f32_e32 v20, v20
	v_fma_f32 v19, v24, s31, -v19
	v_fmac_f32_e32 v19, 0x3377d1cf, v24
	v_fmac_f32_e32 v19, 0x3f317217, v24
	v_cmp_lt_f32_e64 s[0:1], |v24|, s34
	v_add_f32_e32 v20, 1.0, v20
	s_nop 0
	v_cndmask_b32_e64 v19, v24, v19, s[0:1]
	v_cmp_gt_f32_e64 s[0:1], s30, v20
	s_nop 1
	v_cndmask_b32_e64 v22, 0, 32, s[0:1]
	v_ldexp_f32 v20, v20, v22
	v_log_f32_e32 v22, v20
	v_cndmask_b32_e32 v20, 0, v112, vcc
	v_sub_f32_e32 v20, v19, v20
	v_min_f32_e32 v19, 0, v21
	v_mul_f32_e32 v21, 0x3f317217, v22
	v_fma_f32 v21, v22, s31, -v21
	v_fmac_f32_e32 v21, 0x3377d1cf, v22
	v_fmac_f32_e32 v21, 0x3f317217, v22
	v_cmp_lt_f32_e64 vcc, |v22|, s34
	s_nop 1
	v_cndmask_b32_e32 v21, v22, v21, vcc
	v_cndmask_b32_e64 v22, 0, v112, s[0:1]
	v_sub_f32_e32 v21, v21, v22
	v_pk_add_f32 v[18:19], v[18:19], v[20:21] neg_lo:[0,1] neg_hi:[0,1]
	s_nop 0
	v_pk_mul_f32 v[94:95], v[18:19], s[10:11] op_sel_hi:[1,0]
	global_load_dwordx4 v[18:21], v123, s[52:53] offset:576
	global_load_dwordx4 v[22:25], v123, s[8:9] offset:64
	global_load_dwordx4 v[26:29], v123, s[8:9] offset:3136
	global_load_dwordx4 v[30:33], v123, s[8:9] offset:3648
	global_load_dwordx4 v[34:37], v111, s[12:13] offset:64
	global_load_dwordx4 v[38:41], v111, s[12:13] offset:576
	global_load_dwordx4 v[42:45], v111, s[12:13] offset:1088
	global_load_dwordx4 v[46:49], v111, s[12:13] offset:1600
	global_load_dwordx4 v[50:53], v111, s[12:13] offset:2112
	global_load_dwordx4 v[54:57], v111, s[12:13] offset:2624
	global_load_dwordx4 v[58:61], v111, s[12:13] offset:3136
	global_load_dwordx4 v[62:65], v111, s[12:13] offset:3648
	global_load_dwordx4 v[96:99], v123, s[8:9] offset:576
	global_load_dwordx4 v[100:103], v123, s[8:9] offset:1088
	global_load_dwordx4 v[104:107], v123, s[8:9] offset:1600
	global_load_dwordx4 v[124:127], v123, s[8:9] offset:2112
	global_load_dwordx4 v[128:131], v123, s[8:9] offset:2624
	s_waitcnt vmcnt(15)
	v_fma_f32 v142, v22, v118, v18
	v_fma_f32 v20, v24, v118, v20
	s_waitcnt vmcnt(14)
	v_mov_b32_e32 v132, v26
	s_waitcnt vmcnt(13)
	v_mov_b32_e32 v133, v30
	v_fma_f32 v23, v23, v118, v19
	v_mov_b32_e32 v30, v27
	v_mov_b32_e32 v18, v28
	v_mov_b32_e32 v19, v32
	v_pk_mul_f32 v[26:27], v[132:133], v[72:73]
	s_waitcnt vmcnt(12)
	v_mov_b32_e32 v134, v34
	s_waitcnt vmcnt(11)
	v_mov_b32_e32 v135, v38
	s_waitcnt vmcnt(4)
	v_fmac_f32_e32 v142, v96, v117
	v_fmac_f32_e32 v20, v98, v117
	s_waitcnt vmcnt(3)
	v_fmac_f32_e32 v142, v100, v122
	v_fmac_f32_e32 v20, v102, v122
	s_waitcnt vmcnt(2)
	v_fmac_f32_e32 v142, v104, v121
	v_fmac_f32_e32 v20, v106, v121
	s_waitcnt vmcnt(1)
	v_fmac_f32_e32 v142, v124, v120
	v_fmac_f32_e32 v20, v126, v120
	s_waitcnt vmcnt(0)
	v_fmac_f32_e32 v142, v128, v119
	v_fmac_f32_e32 v23, v97, v117
	v_pk_mul_f32 v[18:19], v[18:19], v[72:73]
	v_fmac_f32_e32 v20, v130, v119
	v_add_f32_e32 v24, v142, v26
	v_mov_b32_e32 v38, v35
	v_pk_mul_f32 v[34:35], v[134:135], v[74:75]
	v_fmac_f32_e32 v23, v101, v122
	v_add_f32_e32 v18, v18, v20
	v_add_f32_e32 v20, v24, v27
	v_mov_b32_e32 v136, v42
	v_mov_b32_e32 v137, v46
	v_fmac_f32_e32 v23, v105, v121
	v_add_f32_e32 v20, v20, v34
	v_mov_b32_e32 v46, v43
	v_pk_mul_f32 v[42:43], v[136:137], v[78:79]
	v_fmac_f32_e32 v23, v125, v120
	v_add_f32_e32 v20, v20, v35
	v_mov_b32_e32 v138, v50
	v_mov_b32_e32 v139, v54
	v_pk_mul_f32 v[30:31], v[30:31], v[72:73]
	v_fmac_f32_e32 v23, v129, v119
	v_add_f32_e32 v20, v20, v42
	v_mov_b32_e32 v54, v51
	v_pk_mul_f32 v[50:51], v[138:139], v[80:81]
	v_add_f32_e32 v23, v30, v23
	v_add_f32_e32 v20, v20, v43
	v_mov_b32_e32 v140, v58
	v_mov_b32_e32 v141, v62
	v_pk_mul_f32 v[38:39], v[38:39], v[74:75]
	v_add_f32_e32 v23, v31, v23
	v_add_f32_e32 v20, v20, v50
	v_mov_b32_e32 v62, v59
	v_pk_mul_f32 v[58:59], v[140:141], v[82:83]
	v_add_f32_e32 v23, v38, v23
	v_add_f32_e32 v20, v20, v51
	v_pk_mul_f32 v[46:47], v[46:47], v[78:79]
	v_add_f32_e32 v23, v39, v23
	v_add_f32_e32 v20, v20, v58
	v_add_f32_e32 v23, v46, v23
	v_add_f32_e32 v20, v20, v59
	v_pk_mul_f32 v[54:55], v[54:55], v[80:81]
	v_add_f32_e32 v23, v47, v23
	v_mul_f32_e64 v24, |v20|, s29
	v_add_f32_e32 v23, v54, v23
	v_exp_f32_e32 v24, v24
	v_pk_mul_f32 v[62:63], v[62:63], v[82:83]
	v_add_f32_e32 v23, v55, v23
	v_add_f32_e32 v23, v62, v23
	v_add_f32_e32 v23, v63, v23
	v_mul_f32_e64 v26, |v23|, s29
	v_add_f32_e32 v27, v19, v18
	v_add_f32_e32 v19, 1.0, v24
	v_exp_f32_e32 v26, v26
	v_cmp_gt_f32_e32 vcc, s30, v19
	v_min_f32_e32 v18, 0, v20
	v_mov_b32_e32 v22, v36
	v_cndmask_b32_e64 v24, 0, 32, vcc
	v_ldexp_f32 v19, v19, v24
	v_log_f32_e32 v24, v19
	v_add_f32_e32 v20, 1.0, v26
	v_cmp_gt_f32_e64 s[0:1], s30, v20
	v_min_f32_e32 v19, 0, v23
	v_cndmask_b32_e32 v23, 0, v112, vcc
	v_cndmask_b32_e64 v26, 0, 32, s[0:1]
	v_ldexp_f32 v20, v20, v26
	v_mul_f32_e32 v26, 0x3f317217, v24
	v_fma_f32 v26, v24, s31, -v26
	v_fmac_f32_e32 v26, 0x3377d1cf, v24
	v_fmac_f32_e32 v26, 0x3f317217, v24
	v_cmp_lt_f32_e64 vcc, |v24|, s34
	v_log_f32_e32 v20, v20
	v_fmac_f32_e32 v21, v25, v118
	v_cndmask_b32_e32 v24, v24, v26, vcc
	v_sub_f32_e32 v26, v24, v23
	v_mov_b32_e32 v23, v40
	v_pk_mul_f32 v[22:23], v[22:23], v[74:75]
	v_mul_f32_e32 v28, 0x3f317217, v20
	v_add_f32_e32 v22, v22, v27
	v_add_f32_e32 v24, v23, v22
	v_mov_b32_e32 v22, v44
	v_mov_b32_e32 v23, v48
	v_pk_mul_f32 v[22:23], v[22:23], v[78:79]
	v_fma_f32 v28, v20, s31, -v28
	v_add_f32_e32 v22, v22, v24
	v_add_f32_e32 v24, v23, v22
	v_mov_b32_e32 v22, v52
	v_mov_b32_e32 v23, v56
	v_pk_mul_f32 v[22:23], v[22:23], v[80:81]
	v_fmac_f32_e32 v28, 0x3377d1cf, v20
	v_add_f32_e32 v22, v22, v24
	v_add_f32_e32 v24, v23, v22
	v_mov_b32_e32 v22, v60
	v_mov_b32_e32 v23, v64
	v_pk_mul_f32 v[22:23], v[22:23], v[82:83]
	v_fmac_f32_e32 v28, 0x3f317217, v20
	v_add_f32_e32 v22, v22, v24
	v_add_f32_e32 v22, v23, v22
	v_mul_f32_e64 v23, |v22|, s29
	v_exp_f32_e32 v23, v23
	v_cmp_lt_f32_e64 vcc, |v20|, s34
	v_cndmask_b32_e64 v24, 0, v112, s[0:1]
	v_fmac_f32_e32 v21, v99, v117
	v_cndmask_b32_e32 v20, v20, v28, vcc
	v_sub_f32_e32 v27, v20, v24
	v_add_f32_e32 v20, 1.0, v23
	v_fmac_f32_e32 v21, v103, v122
	v_cmp_gt_f32_e32 vcc, s30, v20
	v_fmac_f32_e32 v21, v107, v121
	v_pk_add_f32 v[18:19], v[18:19], v[26:27] neg_lo:[0,1] neg_hi:[0,1]
	v_cndmask_b32_e64 v23, 0, 32, vcc
	v_fmac_f32_e32 v21, v127, v120
	v_mov_b32_e32 v32, v29
	v_ldexp_f32 v20, v20, v23
	v_pk_mul_f32 v[96:97], v[18:19], s[10:11] op_sel_hi:[1,0]
	v_min_f32_e32 v18, 0, v22
	v_fmac_f32_e32 v21, v131, v119
	v_pk_mul_f32 v[22:23], v[32:33], v[72:73]
	v_log_f32_e32 v24, v20
	v_add_f32_e32 v20, v22, v21
	v_mov_b32_e32 v40, v37
	v_add_f32_e32 v22, v23, v20
	v_pk_mul_f32 v[20:21], v[40:41], v[74:75]
	v_mov_b32_e32 v48, v45
	v_add_f32_e32 v20, v20, v22
	v_add_f32_e32 v22, v21, v20
	v_pk_mul_f32 v[20:21], v[48:49], v[78:79]
	v_mov_b32_e32 v56, v53
	v_add_f32_e32 v20, v20, v22
	v_add_f32_e32 v22, v21, v20
	v_pk_mul_f32 v[20:21], v[56:57], v[80:81]
	v_mov_b32_e32 v64, v61
	v_add_f32_e32 v20, v20, v22
	v_add_f32_e32 v22, v21, v20
	v_pk_mul_f32 v[20:21], v[64:65], v[82:83]
	v_mul_f32_e32 v19, 0x3f317217, v24
	v_add_f32_e32 v20, v20, v22
	v_add_f32_e32 v21, v21, v20
	v_mul_f32_e64 v20, |v21|, s29
	v_exp_f32_e32 v20, v20
	v_fma_f32 v19, v24, s31, -v19
	v_fmac_f32_e32 v19, 0x3377d1cf, v24
	v_fmac_f32_e32 v19, 0x3f317217, v24
	v_cmp_lt_f32_e64 s[0:1], |v24|, s34
	v_add_f32_e32 v20, 1.0, v20
	s_nop 0
	v_cndmask_b32_e64 v19, v24, v19, s[0:1]
	v_cmp_gt_f32_e64 s[0:1], s30, v20
	s_nop 1
	v_cndmask_b32_e64 v22, 0, 32, s[0:1]
	v_ldexp_f32 v20, v20, v22
	v_log_f32_e32 v22, v20
	v_cndmask_b32_e32 v20, 0, v112, vcc
	v_sub_f32_e32 v20, v19, v20
	v_min_f32_e32 v19, 0, v21
	v_mul_f32_e32 v21, 0x3f317217, v22
	v_fma_f32 v21, v22, s31, -v21
	v_fmac_f32_e32 v21, 0x3377d1cf, v22
	v_fmac_f32_e32 v21, 0x3f317217, v22
	v_cmp_lt_f32_e64 vcc, |v22|, s34
	s_nop 1
	v_cndmask_b32_e32 v21, v22, v21, vcc
	v_cndmask_b32_e64 v22, 0, v112, s[0:1]
	v_sub_f32_e32 v21, v21, v22
	v_pk_add_f32 v[18:19], v[18:19], v[20:21] neg_lo:[0,1] neg_hi:[0,1]
	s_nop 0
	v_pk_mul_f32 v[98:99], v[18:19], s[10:11] op_sel_hi:[1,0]
	global_load_dwordx4 v[18:21], v123, s[52:53] offset:592
	global_load_dwordx4 v[22:25], v123, s[8:9] offset:80
	global_load_dwordx4 v[26:29], v123, s[8:9] offset:3152
	global_load_dwordx4 v[30:33], v123, s[8:9] offset:3664
	global_load_dwordx4 v[34:37], v111, s[12:13] offset:80
	global_load_dwordx4 v[38:41], v111, s[12:13] offset:592
	global_load_dwordx4 v[42:45], v111, s[12:13] offset:1104
	global_load_dwordx4 v[46:49], v111, s[12:13] offset:1616
	global_load_dwordx4 v[50:53], v111, s[12:13] offset:2128
	global_load_dwordx4 v[54:57], v111, s[12:13] offset:2640
	global_load_dwordx4 v[58:61], v111, s[12:13] offset:3152
	global_load_dwordx4 v[62:65], v111, s[12:13] offset:3664
	global_load_dwordx4 v[100:103], v123, s[8:9] offset:592
	global_load_dwordx4 v[104:107], v123, s[8:9] offset:1104
	global_load_dwordx4 v[124:127], v123, s[8:9] offset:1616
	global_load_dwordx4 v[128:131], v123, s[8:9] offset:2128
	global_load_dwordx4 v[132:135], v123, s[8:9] offset:2640
	s_waitcnt vmcnt(15)
	v_fma_f32 v146, v22, v118, v18
	v_fma_f32 v20, v24, v118, v20
	s_waitcnt vmcnt(14)
	v_mov_b32_e32 v136, v26
	s_waitcnt vmcnt(13)
	v_mov_b32_e32 v137, v30
	v_fma_f32 v23, v23, v118, v19
	v_mov_b32_e32 v30, v27
	v_mov_b32_e32 v18, v28
	v_mov_b32_e32 v19, v32
	v_pk_mul_f32 v[26:27], v[136:137], v[72:73]
	s_waitcnt vmcnt(12)
	v_mov_b32_e32 v138, v34
	s_waitcnt vmcnt(11)
	v_mov_b32_e32 v139, v38
	s_waitcnt vmcnt(4)
	v_fmac_f32_e32 v146, v100, v117
	v_fmac_f32_e32 v20, v102, v117
	s_waitcnt vmcnt(3)
	v_fmac_f32_e32 v146, v104, v122
	v_fmac_f32_e32 v20, v106, v122
	s_waitcnt vmcnt(2)
	v_fmac_f32_e32 v146, v124, v121
	v_fmac_f32_e32 v20, v126, v121
	s_waitcnt vmcnt(1)
	v_fmac_f32_e32 v146, v128, v120
	v_fmac_f32_e32 v20, v130, v120
	s_waitcnt vmcnt(0)
	v_fmac_f32_e32 v146, v132, v119
	v_fmac_f32_e32 v23, v101, v117
	v_pk_mul_f32 v[18:19], v[18:19], v[72:73]
	v_fmac_f32_e32 v20, v134, v119
	v_add_f32_e32 v24, v146, v26
	v_mov_b32_e32 v38, v35
	v_pk_mul_f32 v[34:35], v[138:139], v[74:75]
	v_fmac_f32_e32 v23, v105, v122
	v_add_f32_e32 v18, v18, v20
	v_add_f32_e32 v20, v24, v27
	v_mov_b32_e32 v140, v42
	v_mov_b32_e32 v141, v46
	v_fmac_f32_e32 v23, v125, v121
	v_add_f32_e32 v20, v20, v34
	v_mov_b32_e32 v46, v43
	v_pk_mul_f32 v[42:43], v[140:141], v[78:79]
	v_fmac_f32_e32 v23, v129, v120
	v_add_f32_e32 v20, v20, v35
	v_mov_b32_e32 v142, v50
	v_mov_b32_e32 v143, v54
	v_pk_mul_f32 v[30:31], v[30:31], v[72:73]
	v_fmac_f32_e32 v23, v133, v119
	v_add_f32_e32 v20, v20, v42
	v_mov_b32_e32 v54, v51
	v_pk_mul_f32 v[50:51], v[142:143], v[80:81]
	v_add_f32_e32 v23, v30, v23
	v_add_f32_e32 v20, v20, v43
	v_mov_b32_e32 v144, v58
	v_mov_b32_e32 v145, v62
	v_pk_mul_f32 v[38:39], v[38:39], v[74:75]
	v_add_f32_e32 v23, v31, v23
	v_add_f32_e32 v20, v20, v50
	v_mov_b32_e32 v62, v59
	v_pk_mul_f32 v[58:59], v[144:145], v[82:83]
	v_add_f32_e32 v23, v38, v23
	v_add_f32_e32 v20, v20, v51
	v_pk_mul_f32 v[46:47], v[46:47], v[78:79]
	v_add_f32_e32 v23, v39, v23
	v_add_f32_e32 v20, v20, v58
	v_add_f32_e32 v23, v46, v23
	v_add_f32_e32 v20, v20, v59
	v_pk_mul_f32 v[54:55], v[54:55], v[80:81]
	v_add_f32_e32 v23, v47, v23
	v_mul_f32_e64 v24, |v20|, s29
	v_add_f32_e32 v23, v54, v23
	v_exp_f32_e32 v24, v24
	v_pk_mul_f32 v[62:63], v[62:63], v[82:83]
	v_add_f32_e32 v23, v55, v23
	v_add_f32_e32 v23, v62, v23
	v_add_f32_e32 v23, v63, v23
	v_mul_f32_e64 v26, |v23|, s29
	v_add_f32_e32 v27, v19, v18
	v_add_f32_e32 v19, 1.0, v24
	v_exp_f32_e32 v26, v26
	v_cmp_gt_f32_e32 vcc, s30, v19
	v_min_f32_e32 v18, 0, v20
	v_mov_b32_e32 v22, v36
	v_cndmask_b32_e64 v24, 0, 32, vcc
	v_ldexp_f32 v19, v19, v24
	v_log_f32_e32 v24, v19
	v_add_f32_e32 v20, 1.0, v26
	v_cmp_gt_f32_e64 s[0:1], s30, v20
	v_min_f32_e32 v19, 0, v23
	v_cndmask_b32_e32 v23, 0, v112, vcc
	v_cndmask_b32_e64 v26, 0, 32, s[0:1]
	v_ldexp_f32 v20, v20, v26
	v_mul_f32_e32 v26, 0x3f317217, v24
	v_fma_f32 v26, v24, s31, -v26
	v_fmac_f32_e32 v26, 0x3377d1cf, v24
	v_fmac_f32_e32 v26, 0x3f317217, v24
	v_cmp_lt_f32_e64 vcc, |v24|, s34
	v_log_f32_e32 v20, v20
	v_fmac_f32_e32 v21, v25, v118
	v_cndmask_b32_e32 v24, v24, v26, vcc
	v_sub_f32_e32 v26, v24, v23
	v_mov_b32_e32 v23, v40
	v_pk_mul_f32 v[22:23], v[22:23], v[74:75]
	v_mul_f32_e32 v28, 0x3f317217, v20
	v_add_f32_e32 v22, v22, v27
	v_add_f32_e32 v24, v23, v22
	v_mov_b32_e32 v22, v44
	v_mov_b32_e32 v23, v48
	v_pk_mul_f32 v[22:23], v[22:23], v[78:79]
	v_fma_f32 v28, v20, s31, -v28
	v_add_f32_e32 v22, v22, v24
	v_add_f32_e32 v24, v23, v22
	v_mov_b32_e32 v22, v52
	v_mov_b32_e32 v23, v56
	v_pk_mul_f32 v[22:23], v[22:23], v[80:81]
	v_fmac_f32_e32 v28, 0x3377d1cf, v20
	v_add_f32_e32 v22, v22, v24
	v_add_f32_e32 v24, v23, v22
	v_mov_b32_e32 v22, v60
	v_mov_b32_e32 v23, v64
	v_pk_mul_f32 v[22:23], v[22:23], v[82:83]
	v_fmac_f32_e32 v28, 0x3f317217, v20
	v_add_f32_e32 v22, v22, v24
	v_add_f32_e32 v22, v23, v22
	v_mul_f32_e64 v23, |v22|, s29
	v_exp_f32_e32 v23, v23
	v_cmp_lt_f32_e64 vcc, |v20|, s34
	v_cndmask_b32_e64 v24, 0, v112, s[0:1]
	v_fmac_f32_e32 v21, v103, v117
	v_cndmask_b32_e32 v20, v20, v28, vcc
	v_sub_f32_e32 v27, v20, v24
	v_add_f32_e32 v20, 1.0, v23
	v_fmac_f32_e32 v21, v107, v122
	v_cmp_gt_f32_e32 vcc, s30, v20
	v_fmac_f32_e32 v21, v127, v121
	v_pk_add_f32 v[18:19], v[18:19], v[26:27] neg_lo:[0,1] neg_hi:[0,1]
	v_cndmask_b32_e64 v23, 0, 32, vcc
	v_fmac_f32_e32 v21, v131, v120
	v_mov_b32_e32 v32, v29
	v_ldexp_f32 v20, v20, v23
	v_pk_mul_f32 v[100:101], v[18:19], s[10:11] op_sel_hi:[1,0]
	v_min_f32_e32 v18, 0, v22
	v_fmac_f32_e32 v21, v135, v119
	v_pk_mul_f32 v[22:23], v[32:33], v[72:73]
	v_log_f32_e32 v24, v20
	v_add_f32_e32 v20, v22, v21
	v_mov_b32_e32 v40, v37
	v_add_f32_e32 v22, v23, v20
	v_pk_mul_f32 v[20:21], v[40:41], v[74:75]
	v_mov_b32_e32 v48, v45
	v_add_f32_e32 v20, v20, v22
	v_add_f32_e32 v22, v21, v20
	v_pk_mul_f32 v[20:21], v[48:49], v[78:79]
	v_mov_b32_e32 v56, v53
	v_add_f32_e32 v20, v20, v22
	v_add_f32_e32 v22, v21, v20
	v_pk_mul_f32 v[20:21], v[56:57], v[80:81]
	v_mov_b32_e32 v64, v61
	v_add_f32_e32 v20, v20, v22
	v_add_f32_e32 v22, v21, v20
	v_pk_mul_f32 v[20:21], v[64:65], v[82:83]
	v_mul_f32_e32 v19, 0x3f317217, v24
	v_add_f32_e32 v20, v20, v22
	v_add_f32_e32 v21, v21, v20
	v_mul_f32_e64 v20, |v21|, s29
	v_exp_f32_e32 v20, v20
	v_fma_f32 v19, v24, s31, -v19
	v_fmac_f32_e32 v19, 0x3377d1cf, v24
	v_fmac_f32_e32 v19, 0x3f317217, v24
	v_cmp_lt_f32_e64 s[0:1], |v24|, s34
	v_add_f32_e32 v20, 1.0, v20
	s_nop 0
	v_cndmask_b32_e64 v19, v24, v19, s[0:1]
	v_cmp_gt_f32_e64 s[0:1], s30, v20
	s_nop 1
	v_cndmask_b32_e64 v22, 0, 32, s[0:1]
	v_ldexp_f32 v20, v20, v22
	v_log_f32_e32 v22, v20
	v_cndmask_b32_e32 v20, 0, v112, vcc
	v_sub_f32_e32 v20, v19, v20
	v_min_f32_e32 v19, 0, v21
	v_mul_f32_e32 v21, 0x3f317217, v22
	v_fma_f32 v21, v22, s31, -v21
	v_fmac_f32_e32 v21, 0x3377d1cf, v22
	v_fmac_f32_e32 v21, 0x3f317217, v22
	v_cmp_lt_f32_e64 vcc, |v22|, s34
	s_nop 1
	v_cndmask_b32_e32 v21, v22, v21, vcc
	v_cndmask_b32_e64 v22, 0, v112, s[0:1]
	v_sub_f32_e32 v21, v21, v22
	v_pk_add_f32 v[18:19], v[18:19], v[20:21] neg_lo:[0,1] neg_hi:[0,1]
	s_nop 0
	v_pk_mul_f32 v[102:103], v[18:19], s[10:11] op_sel_hi:[1,0]
	global_load_dwordx4 v[18:21], v123, s[52:53] offset:608
	global_load_dwordx4 v[22:25], v123, s[8:9] offset:96
	global_load_dwordx4 v[26:29], v123, s[8:9] offset:3168
	global_load_dwordx4 v[30:33], v123, s[8:9] offset:3680
	global_load_dwordx4 v[34:37], v111, s[12:13] offset:96
	global_load_dwordx4 v[38:41], v111, s[12:13] offset:608
	global_load_dwordx4 v[42:45], v111, s[12:13] offset:1120
	global_load_dwordx4 v[46:49], v111, s[12:13] offset:1632
	global_load_dwordx4 v[50:53], v111, s[12:13] offset:2144
	global_load_dwordx4 v[54:57], v111, s[12:13] offset:2656
	global_load_dwordx4 v[58:61], v111, s[12:13] offset:3168
	global_load_dwordx4 v[62:65], v111, s[12:13] offset:3680
	global_load_dwordx4 v[104:107], v123, s[8:9] offset:608
	global_load_dwordx4 v[124:127], v123, s[8:9] offset:1120
	global_load_dwordx4 v[128:131], v123, s[8:9] offset:1632
	global_load_dwordx4 v[132:135], v123, s[8:9] offset:2144
	global_load_dwordx4 v[136:139], v123, s[8:9] offset:2656
	s_waitcnt vmcnt(15)
	v_fma_f32 v150, v22, v118, v18
	v_fma_f32 v20, v24, v118, v20
	s_waitcnt vmcnt(14)
	v_mov_b32_e32 v140, v26
	s_waitcnt vmcnt(13)
	v_mov_b32_e32 v141, v30
	v_fma_f32 v23, v23, v118, v19
	v_mov_b32_e32 v30, v27
	v_mov_b32_e32 v18, v28
	v_mov_b32_e32 v19, v32
	v_pk_mul_f32 v[26:27], v[140:141], v[72:73]
	s_waitcnt vmcnt(12)
	v_mov_b32_e32 v142, v34
	s_waitcnt vmcnt(11)
	v_mov_b32_e32 v143, v38
	s_waitcnt vmcnt(4)
	v_fmac_f32_e32 v150, v104, v117
	v_fmac_f32_e32 v20, v106, v117
	s_waitcnt vmcnt(3)
	v_fmac_f32_e32 v150, v124, v122
	v_fmac_f32_e32 v20, v126, v122
	s_waitcnt vmcnt(2)
	v_fmac_f32_e32 v150, v128, v121
	v_fmac_f32_e32 v20, v130, v121
	s_waitcnt vmcnt(1)
	v_fmac_f32_e32 v150, v132, v120
	v_fmac_f32_e32 v20, v134, v120
	s_waitcnt vmcnt(0)
	v_fmac_f32_e32 v150, v136, v119
	v_fmac_f32_e32 v23, v105, v117
	v_pk_mul_f32 v[18:19], v[18:19], v[72:73]
	v_fmac_f32_e32 v20, v138, v119
	v_add_f32_e32 v24, v150, v26
	v_mov_b32_e32 v38, v35
	v_pk_mul_f32 v[34:35], v[142:143], v[74:75]
	v_fmac_f32_e32 v23, v125, v122
	v_add_f32_e32 v18, v18, v20
	v_add_f32_e32 v20, v24, v27
	v_mov_b32_e32 v144, v42
	v_mov_b32_e32 v145, v46
	v_fmac_f32_e32 v23, v129, v121
	v_add_f32_e32 v20, v20, v34
	v_mov_b32_e32 v46, v43
	v_pk_mul_f32 v[42:43], v[144:145], v[78:79]
	v_fmac_f32_e32 v23, v133, v120
	v_add_f32_e32 v20, v20, v35
	v_mov_b32_e32 v146, v50
	v_mov_b32_e32 v147, v54
	v_pk_mul_f32 v[30:31], v[30:31], v[72:73]
	v_fmac_f32_e32 v23, v137, v119
	v_add_f32_e32 v20, v20, v42
	v_mov_b32_e32 v54, v51
	v_pk_mul_f32 v[50:51], v[146:147], v[80:81]
	v_add_f32_e32 v23, v30, v23
	v_add_f32_e32 v20, v20, v43
	v_mov_b32_e32 v148, v58
	v_mov_b32_e32 v149, v62
	v_pk_mul_f32 v[38:39], v[38:39], v[74:75]
	v_add_f32_e32 v23, v31, v23
	v_add_f32_e32 v20, v20, v50
	v_mov_b32_e32 v62, v59
	v_pk_mul_f32 v[58:59], v[148:149], v[82:83]
	v_add_f32_e32 v23, v38, v23
	v_add_f32_e32 v20, v20, v51
	v_pk_mul_f32 v[46:47], v[46:47], v[78:79]
	v_add_f32_e32 v23, v39, v23
	v_add_f32_e32 v20, v20, v58
	v_add_f32_e32 v23, v46, v23
	v_add_f32_e32 v20, v20, v59
	v_pk_mul_f32 v[54:55], v[54:55], v[80:81]
	v_add_f32_e32 v23, v47, v23
	v_mul_f32_e64 v24, |v20|, s29
	v_add_f32_e32 v23, v54, v23
	v_exp_f32_e32 v24, v24
	v_pk_mul_f32 v[62:63], v[62:63], v[82:83]
	v_add_f32_e32 v23, v55, v23
	v_add_f32_e32 v23, v62, v23
	v_add_f32_e32 v23, v63, v23
	v_mul_f32_e64 v26, |v23|, s29
	v_add_f32_e32 v27, v19, v18
	v_add_f32_e32 v19, 1.0, v24
	v_exp_f32_e32 v26, v26
	v_cmp_gt_f32_e32 vcc, s30, v19
	v_min_f32_e32 v18, 0, v20
	v_mov_b32_e32 v22, v36
	v_cndmask_b32_e64 v24, 0, 32, vcc
	v_ldexp_f32 v19, v19, v24
	v_log_f32_e32 v24, v19
	v_add_f32_e32 v20, 1.0, v26
	v_cmp_gt_f32_e64 s[0:1], s30, v20
	v_min_f32_e32 v19, 0, v23
	v_cndmask_b32_e32 v23, 0, v112, vcc
	v_cndmask_b32_e64 v26, 0, 32, s[0:1]
	v_ldexp_f32 v20, v20, v26
	v_mul_f32_e32 v26, 0x3f317217, v24
	v_fma_f32 v26, v24, s31, -v26
	v_fmac_f32_e32 v26, 0x3377d1cf, v24
	v_fmac_f32_e32 v26, 0x3f317217, v24
	v_cmp_lt_f32_e64 vcc, |v24|, s34
	v_log_f32_e32 v20, v20
	v_fmac_f32_e32 v21, v25, v118
	v_cndmask_b32_e32 v24, v24, v26, vcc
	v_sub_f32_e32 v26, v24, v23
	v_mov_b32_e32 v23, v40
	v_pk_mul_f32 v[22:23], v[22:23], v[74:75]
	v_mul_f32_e32 v28, 0x3f317217, v20
	v_add_f32_e32 v22, v22, v27
	v_add_f32_e32 v24, v23, v22
	v_mov_b32_e32 v22, v44
	v_mov_b32_e32 v23, v48
	v_pk_mul_f32 v[22:23], v[22:23], v[78:79]
	v_fma_f32 v28, v20, s31, -v28
	v_add_f32_e32 v22, v22, v24
	v_add_f32_e32 v24, v23, v22
	v_mov_b32_e32 v22, v52
	v_mov_b32_e32 v23, v56
	v_pk_mul_f32 v[22:23], v[22:23], v[80:81]
	v_fmac_f32_e32 v28, 0x3377d1cf, v20
	v_add_f32_e32 v22, v22, v24
	v_add_f32_e32 v24, v23, v22
	v_mov_b32_e32 v22, v60
	v_mov_b32_e32 v23, v64
	v_pk_mul_f32 v[22:23], v[22:23], v[82:83]
	v_fmac_f32_e32 v28, 0x3f317217, v20
	v_add_f32_e32 v22, v22, v24
	v_add_f32_e32 v22, v23, v22
	v_mul_f32_e64 v23, |v22|, s29
	v_exp_f32_e32 v23, v23
	v_cmp_lt_f32_e64 vcc, |v20|, s34
	v_cndmask_b32_e64 v24, 0, v112, s[0:1]
	v_fmac_f32_e32 v21, v107, v117
	v_cndmask_b32_e32 v20, v20, v28, vcc
	v_sub_f32_e32 v27, v20, v24
	v_add_f32_e32 v20, 1.0, v23
	v_fmac_f32_e32 v21, v127, v122
	v_cmp_gt_f32_e32 vcc, s30, v20
	v_fmac_f32_e32 v21, v131, v121
	v_pk_add_f32 v[18:19], v[18:19], v[26:27] neg_lo:[0,1] neg_hi:[0,1]
	v_cndmask_b32_e64 v23, 0, 32, vcc
	v_fmac_f32_e32 v21, v135, v120
	v_mov_b32_e32 v32, v29
	v_ldexp_f32 v20, v20, v23
	v_pk_mul_f32 v[104:105], v[18:19], s[10:11] op_sel_hi:[1,0]
	v_min_f32_e32 v18, 0, v22
	v_fmac_f32_e32 v21, v139, v119
	v_pk_mul_f32 v[22:23], v[32:33], v[72:73]
	v_log_f32_e32 v24, v20
	v_add_f32_e32 v20, v22, v21
	v_mov_b32_e32 v40, v37
	v_add_f32_e32 v22, v23, v20
	v_pk_mul_f32 v[20:21], v[40:41], v[74:75]
	v_mov_b32_e32 v48, v45
	v_add_f32_e32 v20, v20, v22
	v_add_f32_e32 v22, v21, v20
	v_pk_mul_f32 v[20:21], v[48:49], v[78:79]
	v_mov_b32_e32 v56, v53
	v_add_f32_e32 v20, v20, v22
	v_add_f32_e32 v22, v21, v20
	v_pk_mul_f32 v[20:21], v[56:57], v[80:81]
	v_mov_b32_e32 v64, v61
	v_add_f32_e32 v20, v20, v22
	v_add_f32_e32 v22, v21, v20
	v_pk_mul_f32 v[20:21], v[64:65], v[82:83]
	v_mul_f32_e32 v19, 0x3f317217, v24
	v_add_f32_e32 v20, v20, v22
	v_add_f32_e32 v21, v21, v20
	v_mul_f32_e64 v20, |v21|, s29
	v_exp_f32_e32 v20, v20
	v_fma_f32 v19, v24, s31, -v19
	v_fmac_f32_e32 v19, 0x3377d1cf, v24
	v_fmac_f32_e32 v19, 0x3f317217, v24
	v_cmp_lt_f32_e64 s[0:1], |v24|, s34
	v_add_f32_e32 v20, 1.0, v20
	s_nop 0
	v_cndmask_b32_e64 v19, v24, v19, s[0:1]
	v_cmp_gt_f32_e64 s[0:1], s30, v20
	s_nop 1
	v_cndmask_b32_e64 v22, 0, 32, s[0:1]
	v_ldexp_f32 v20, v20, v22
	v_log_f32_e32 v22, v20
	v_cndmask_b32_e32 v20, 0, v112, vcc
	v_sub_f32_e32 v20, v19, v20
	v_min_f32_e32 v19, 0, v21
	v_mul_f32_e32 v21, 0x3f317217, v22
	v_fma_f32 v21, v22, s31, -v21
	v_fmac_f32_e32 v21, 0x3377d1cf, v22
	v_fmac_f32_e32 v21, 0x3f317217, v22
	v_cmp_lt_f32_e64 vcc, |v22|, s34
	s_nop 1
	v_cndmask_b32_e32 v21, v22, v21, vcc
	v_cndmask_b32_e64 v22, 0, v112, s[0:1]
	v_sub_f32_e32 v21, v21, v22
	v_pk_add_f32 v[18:19], v[18:19], v[20:21] neg_lo:[0,1] neg_hi:[0,1]
	s_nop 0
	v_pk_mul_f32 v[106:107], v[18:19], s[10:11] op_sel_hi:[1,0]
	global_load_dwordx4 v[18:21], v123, s[52:53] offset:624
	global_load_dwordx4 v[22:25], v123, s[8:9] offset:112
	global_load_dwordx4 v[26:29], v123, s[8:9] offset:3184
	global_load_dwordx4 v[30:33], v123, s[8:9] offset:3696
	global_load_dwordx4 v[34:37], v111, s[12:13] offset:112
	global_load_dwordx4 v[38:41], v111, s[12:13] offset:624
	global_load_dwordx4 v[42:45], v111, s[12:13] offset:1136
	global_load_dwordx4 v[46:49], v111, s[12:13] offset:1648
	global_load_dwordx4 v[50:53], v111, s[12:13] offset:2160
	global_load_dwordx4 v[54:57], v111, s[12:13] offset:2672
	global_load_dwordx4 v[58:61], v111, s[12:13] offset:3184
	global_load_dwordx4 v[62:65], v111, s[12:13] offset:3696
	global_load_dwordx4 v[124:127], v123, s[8:9] offset:624
	global_load_dwordx4 v[128:131], v123, s[8:9] offset:1136
	global_load_dwordx4 v[132:135], v123, s[8:9] offset:1648
	global_load_dwordx4 v[136:139], v123, s[8:9] offset:2160
	global_load_dwordx4 v[140:143], v123, s[8:9] offset:2672
	s_waitcnt vmcnt(15)
	v_fma_f32 v123, v22, v118, v18
	v_fma_f32 v20, v24, v118, v20
	s_waitcnt vmcnt(14)
	v_mov_b32_e32 v144, v26
	s_waitcnt vmcnt(13)
	v_mov_b32_e32 v145, v30
	v_fma_f32 v23, v23, v118, v19
	v_mov_b32_e32 v30, v27
	v_mov_b32_e32 v18, v28
	v_mov_b32_e32 v19, v32
	v_pk_mul_f32 v[26:27], v[144:145], v[72:73]
	s_waitcnt vmcnt(12)
	v_mov_b32_e32 v146, v34
	s_waitcnt vmcnt(11)
	v_mov_b32_e32 v147, v38
	s_waitcnt vmcnt(4)
	v_fmac_f32_e32 v123, v124, v117
	v_fmac_f32_e32 v20, v126, v117
	s_waitcnt vmcnt(3)
	v_fmac_f32_e32 v123, v128, v122
	v_fmac_f32_e32 v20, v130, v122
	s_waitcnt vmcnt(2)
	v_fmac_f32_e32 v123, v132, v121
	v_fmac_f32_e32 v20, v134, v121
	s_waitcnt vmcnt(1)
	v_fmac_f32_e32 v123, v136, v120
	v_fmac_f32_e32 v20, v138, v120
	s_waitcnt vmcnt(0)
	v_fmac_f32_e32 v123, v140, v119
	v_fmac_f32_e32 v23, v125, v117
	v_pk_mul_f32 v[18:19], v[18:19], v[72:73]
	v_fmac_f32_e32 v20, v142, v119
	v_add_f32_e32 v24, v123, v26
	v_mov_b32_e32 v38, v35
	v_pk_mul_f32 v[34:35], v[146:147], v[74:75]
	v_fmac_f32_e32 v23, v129, v122
	v_add_f32_e32 v18, v18, v20
	v_add_f32_e32 v20, v24, v27
	v_mov_b32_e32 v148, v42
	v_mov_b32_e32 v149, v46
	v_fmac_f32_e32 v23, v133, v121
	v_add_f32_e32 v20, v20, v34
	v_mov_b32_e32 v46, v43
	v_pk_mul_f32 v[42:43], v[148:149], v[78:79]
	v_fmac_f32_e32 v23, v137, v120
	v_add_f32_e32 v20, v20, v35
	v_mov_b32_e32 v150, v50
	v_mov_b32_e32 v151, v54
	v_pk_mul_f32 v[30:31], v[30:31], v[72:73]
	v_fmac_f32_e32 v23, v141, v119
	v_add_f32_e32 v20, v20, v42
	v_mov_b32_e32 v54, v51
	v_pk_mul_f32 v[50:51], v[150:151], v[80:81]
	v_add_f32_e32 v23, v30, v23
	v_add_f32_e32 v20, v20, v43
	v_mov_b32_e32 v152, v58
	v_mov_b32_e32 v153, v62
	v_pk_mul_f32 v[38:39], v[38:39], v[74:75]
	v_add_f32_e32 v23, v31, v23
	v_add_f32_e32 v20, v20, v50
	v_mov_b32_e32 v62, v59
	v_pk_mul_f32 v[58:59], v[152:153], v[82:83]
	v_add_f32_e32 v23, v38, v23
	v_add_f32_e32 v20, v20, v51
	v_pk_mul_f32 v[46:47], v[46:47], v[78:79]
	v_add_f32_e32 v23, v39, v23
	v_add_f32_e32 v20, v20, v58
	v_add_f32_e32 v23, v46, v23
	v_add_f32_e32 v20, v20, v59
	v_pk_mul_f32 v[54:55], v[54:55], v[80:81]
	v_add_f32_e32 v23, v47, v23
	v_mul_f32_e64 v24, |v20|, s29
	v_add_f32_e32 v23, v54, v23
	v_exp_f32_e32 v24, v24
	v_pk_mul_f32 v[62:63], v[62:63], v[82:83]
	v_add_f32_e32 v23, v55, v23
	v_add_f32_e32 v23, v62, v23
	v_add_f32_e32 v23, v63, v23
	v_mul_f32_e64 v26, |v23|, s29
	v_add_f32_e32 v27, v19, v18
	v_add_f32_e32 v19, 1.0, v24
	v_exp_f32_e32 v26, v26
	v_cmp_gt_f32_e32 vcc, s30, v19
	v_min_f32_e32 v18, 0, v20
	v_mov_b32_e32 v22, v36
	v_cndmask_b32_e64 v24, 0, 32, vcc
	v_ldexp_f32 v19, v19, v24
	v_log_f32_e32 v24, v19
	v_add_f32_e32 v20, 1.0, v26
	v_cmp_gt_f32_e64 s[0:1], s30, v20
	v_min_f32_e32 v19, 0, v23
	v_cndmask_b32_e32 v23, 0, v112, vcc
	v_cndmask_b32_e64 v26, 0, 32, s[0:1]
	v_ldexp_f32 v20, v20, v26
	v_mul_f32_e32 v26, 0x3f317217, v24
	v_fma_f32 v26, v24, s31, -v26
	v_fmac_f32_e32 v26, 0x3377d1cf, v24
	v_fmac_f32_e32 v26, 0x3f317217, v24
	v_cmp_lt_f32_e64 vcc, |v24|, s34
	v_log_f32_e32 v20, v20
	v_fmac_f32_e32 v21, v25, v118
	v_cndmask_b32_e32 v24, v24, v26, vcc
	v_sub_f32_e32 v26, v24, v23
	v_mov_b32_e32 v23, v40
	v_pk_mul_f32 v[22:23], v[22:23], v[74:75]
	v_mul_f32_e32 v28, 0x3f317217, v20
	v_add_f32_e32 v22, v22, v27
	v_add_f32_e32 v24, v23, v22
	v_mov_b32_e32 v22, v44
	v_mov_b32_e32 v23, v48
	v_pk_mul_f32 v[22:23], v[22:23], v[78:79]
	v_fma_f32 v28, v20, s31, -v28
	v_add_f32_e32 v22, v22, v24
	v_add_f32_e32 v24, v23, v22
	v_mov_b32_e32 v22, v52
	v_mov_b32_e32 v23, v56
	v_pk_mul_f32 v[22:23], v[22:23], v[80:81]
	v_fmac_f32_e32 v28, 0x3377d1cf, v20
	v_add_f32_e32 v22, v22, v24
	v_add_f32_e32 v24, v23, v22
	v_mov_b32_e32 v22, v60
	v_mov_b32_e32 v23, v64
	v_pk_mul_f32 v[22:23], v[22:23], v[82:83]
	v_fmac_f32_e32 v28, 0x3f317217, v20
	v_add_f32_e32 v22, v22, v24
	v_add_f32_e32 v24, v23, v22
	v_mul_f32_e64 v22, |v24|, s29
	v_exp_f32_e32 v22, v22
	v_cmp_lt_f32_e64 vcc, |v20|, s34
	v_cndmask_b32_e64 v23, 0, v112, s[0:1]
	v_fmac_f32_e32 v21, v127, v117
	v_cndmask_b32_e32 v20, v20, v28, vcc
	v_sub_f32_e32 v27, v20, v23
	v_add_f32_e32 v20, 1.0, v22
	v_fmac_f32_e32 v21, v131, v122
	v_cmp_gt_f32_e32 vcc, s30, v20
	v_fmac_f32_e32 v21, v135, v121
	v_pk_add_f32 v[18:19], v[18:19], v[26:27] neg_lo:[0,1] neg_hi:[0,1]
	v_cndmask_b32_e64 v22, 0, 32, vcc
	v_fmac_f32_e32 v21, v139, v120
	v_mov_b32_e32 v32, v29
	v_ldexp_f32 v20, v20, v22
	v_pk_mul_f32 v[22:23], v[18:19], s[10:11] op_sel_hi:[1,0]
	v_min_f32_e32 v18, 0, v24
	v_fmac_f32_e32 v21, v143, v119
	v_pk_mul_f32 v[24:25], v[32:33], v[72:73]
	v_log_f32_e32 v28, v20
	v_add_f32_e32 v20, v24, v21
	v_mov_b32_e32 v40, v37
	v_add_f32_e32 v24, v25, v20
	v_pk_mul_f32 v[20:21], v[40:41], v[74:75]
	v_mov_b32_e32 v48, v45
	v_add_f32_e32 v20, v20, v24
	v_add_f32_e32 v24, v21, v20
	v_pk_mul_f32 v[20:21], v[48:49], v[78:79]
	v_mov_b32_e32 v56, v53
	v_add_f32_e32 v20, v20, v24
	v_add_f32_e32 v24, v21, v20
	v_pk_mul_f32 v[20:21], v[56:57], v[80:81]
	v_mov_b32_e32 v64, v61
	v_add_f32_e32 v20, v20, v24
	v_add_f32_e32 v24, v21, v20
	v_pk_mul_f32 v[20:21], v[64:65], v[82:83]
	v_mul_f32_e32 v19, 0x3f317217, v28
	v_add_f32_e32 v20, v20, v24
	v_add_f32_e32 v21, v21, v20
	v_mul_f32_e64 v20, |v21|, s29
	v_exp_f32_e32 v20, v20
	v_fma_f32 v19, v28, s31, -v19
	v_fmac_f32_e32 v19, 0x3377d1cf, v28
	v_fmac_f32_e32 v19, 0x3f317217, v28
	v_cmp_lt_f32_e64 s[0:1], |v28|, s34
	v_add_f32_e32 v20, 1.0, v20
	s_nop 0
	v_cndmask_b32_e64 v19, v28, v19, s[0:1]
	v_cmp_gt_f32_e64 s[0:1], s30, v20
	s_nop 1
	v_cndmask_b32_e64 v24, 0, 32, s[0:1]
	v_ldexp_f32 v20, v20, v24
	v_log_f32_e32 v24, v20
	v_cndmask_b32_e32 v20, 0, v112, vcc
	v_sub_f32_e32 v20, v19, v20
	v_min_f32_e32 v19, 0, v21
	v_mul_f32_e32 v21, 0x3f317217, v24
	v_fma_f32 v21, v24, s31, -v21
	v_fmac_f32_e32 v21, 0x3377d1cf, v24
	v_fmac_f32_e32 v21, 0x3f317217, v24
	v_cmp_lt_f32_e64 vcc, |v24|, s34
	s_nop 1
	v_cndmask_b32_e32 v21, v24, v21, vcc
	v_cndmask_b32_e64 v24, 0, v112, s[0:1]
	v_sub_f32_e32 v21, v21, v24
	v_pk_add_f32 v[18:19], v[18:19], v[20:21] neg_lo:[0,1] neg_hi:[0,1]
	s_nop 0
	v_pk_mul_f32 v[20:21], v[18:19], s[10:11] op_sel_hi:[1,0]
	v_and_b32_e32 v18, 64, v110
	v_add_u32_e32 v19, -1, v110
	v_cmp_lt_i32_e32 vcc, v19, v18
	s_nop 1
	v_cndmask_b32_e32 v19, v19, v110, vcc
	v_lshlrev_b32_e32 v19, 2, v19
	ds_bpermute_b32 v24, v19, v70
	ds_bpermute_b32 v25, v19, v71
	ds_bpermute_b32 v26, v19, v76
	ds_bpermute_b32 v27, v19, v77
	ds_bpermute_b32 v28, v19, v84
	ds_bpermute_b32 v29, v19, v85
	ds_bpermute_b32 v30, v19, v86
	ds_bpermute_b32 v31, v19, v87
	ds_bpermute_b32 v32, v19, v88
	ds_bpermute_b32 v33, v19, v89
	ds_bpermute_b32 v34, v19, v90
	ds_bpermute_b32 v35, v19, v91
	ds_bpermute_b32 v36, v19, v92
	ds_bpermute_b32 v37, v19, v93
	ds_bpermute_b32 v38, v19, v94
	ds_bpermute_b32 v39, v19, v95
	ds_bpermute_b32 v40, v19, v96
	ds_bpermute_b32 v41, v19, v97
	ds_bpermute_b32 v42, v19, v98
	ds_bpermute_b32 v43, v19, v99
	ds_bpermute_b32 v44, v19, v100
	ds_bpermute_b32 v45, v19, v101
	ds_bpermute_b32 v46, v19, v102
	ds_bpermute_b32 v47, v19, v103
	ds_bpermute_b32 v48, v19, v104
	ds_bpermute_b32 v49, v19, v105
	ds_bpermute_b32 v50, v19, v106
	ds_bpermute_b32 v51, v19, v107
	ds_bpermute_b32 v52, v19, v22
	ds_bpermute_b32 v53, v19, v23
	ds_bpermute_b32 v54, v19, v20
	ds_bpermute_b32 v19, v19, v21
	v_cmp_gt_i32_e32 vcc, 1, v68
	s_waitcnt lgkmcnt(6)
	v_add_f32_e32 v49, v105, v49
	s_waitcnt lgkmcnt(3)
	v_add_f32_e32 v52, v22, v52
	v_add_f32_e32 v24, v70, v24
	s_waitcnt lgkmcnt(0)
	v_add_f32_e32 v19, v21, v19
	v_cndmask_b32_e32 v19, v19, v21, vcc
	v_cndmask_b32_e32 v21, v52, v22, vcc
	v_cndmask_b32_e32 v22, v49, v105, vcc
	v_add_u32_e32 v49, -2, v110
	v_cmp_lt_i32_e64 s[0:1], v49, v18
	v_add_f32_e32 v25, v71, v25
	v_add_f32_e32 v26, v76, v26
	v_add_f32_e32 v27, v77, v27
	v_add_f32_e32 v28, v84, v28
	v_add_f32_e32 v29, v85, v29
	v_add_f32_e32 v30, v86, v30
	v_add_f32_e32 v31, v87, v31
	v_add_f32_e32 v32, v88, v32
	v_add_f32_e32 v33, v89, v33
	v_add_f32_e32 v34, v90, v34
	v_add_f32_e32 v35, v91, v35
	v_add_f32_e32 v36, v92, v36
	v_add_f32_e32 v37, v93, v37
	v_add_f32_e32 v38, v94, v38
	v_add_f32_e32 v39, v95, v39
	v_add_f32_e32 v40, v96, v40
	v_add_f32_e32 v41, v97, v41
	v_add_f32_e32 v42, v98, v42
	v_add_f32_e32 v43, v99, v43
	v_add_f32_e32 v44, v100, v44
	v_add_f32_e32 v45, v101, v45
	v_add_f32_e32 v46, v102, v46
	v_add_f32_e32 v47, v103, v47
	v_add_f32_e32 v48, v104, v48
	v_add_f32_e32 v50, v106, v50
	v_add_f32_e32 v51, v107, v51
	v_add_f32_e32 v53, v23, v53
	v_add_f32_e32 v54, v20, v54
	v_cndmask_b32_e64 v49, v49, v110, s[0:1]
	v_cndmask_b32_e32 v24, v24, v70, vcc
	v_cndmask_b32_e32 v26, v26, v76, vcc
	v_cndmask_b32_e32 v27, v27, v77, vcc
	v_cndmask_b32_e32 v29, v29, v85, vcc
	v_cndmask_b32_e32 v30, v30, v86, vcc
	v_cndmask_b32_e32 v32, v32, v88, vcc
	v_cndmask_b32_e32 v33, v33, v89, vcc
	v_cndmask_b32_e32 v35, v35, v91, vcc
	v_cndmask_b32_e32 v36, v36, v92, vcc
	v_cndmask_b32_e32 v38, v38, v94, vcc
	v_cndmask_b32_e32 v39, v39, v95, vcc
	v_cndmask_b32_e32 v41, v41, v97, vcc
	v_cndmask_b32_e32 v42, v42, v98, vcc
	v_cndmask_b32_e32 v44, v44, v100, vcc
	v_cndmask_b32_e32 v45, v45, v101, vcc
	v_cndmask_b32_e32 v47, v47, v103, vcc
	v_cndmask_b32_e32 v48, v48, v104, vcc
	v_cndmask_b32_e32 v50, v50, v106, vcc
	v_cndmask_b32_e32 v51, v51, v107, vcc
	v_cndmask_b32_e32 v53, v53, v23, vcc
	v_cndmask_b32_e32 v54, v54, v20, vcc
	v_cndmask_b32_e32 v46, v46, v102, vcc
	v_cndmask_b32_e32 v43, v43, v99, vcc
	v_cndmask_b32_e32 v40, v40, v96, vcc
	v_cndmask_b32_e32 v37, v37, v93, vcc
	v_cndmask_b32_e32 v34, v34, v90, vcc
	v_lshlrev_b32_e32 v49, 2, v49
	v_cndmask_b32_e32 v31, v31, v87, vcc
	v_cndmask_b32_e32 v28, v28, v84, vcc
	v_cndmask_b32_e32 v25, v25, v71, vcc
	v_cndmask_b32_e32 v55, v24, v70, vcc
	v_cndmask_b32_e32 v56, v26, v76, vcc
	v_cndmask_b32_e32 v57, v27, v77, vcc
	v_cndmask_b32_e32 v58, v29, v85, vcc
	v_cndmask_b32_e32 v59, v30, v86, vcc
	v_cndmask_b32_e32 v60, v32, v88, vcc
	v_cndmask_b32_e32 v61, v33, v89, vcc
	v_cndmask_b32_e32 v62, v35, v91, vcc
	v_cndmask_b32_e32 v63, v36, v92, vcc
	v_cndmask_b32_e32 v64, v38, v94, vcc
	v_cndmask_b32_e32 v65, v39, v95, vcc
	v_cndmask_b32_e32 v70, v41, v97, vcc
	v_cndmask_b32_e32 v72, v42, v98, vcc
	v_cndmask_b32_e32 v73, v44, v100, vcc
	v_cndmask_b32_e32 v74, v45, v101, vcc
	v_cndmask_b32_e32 v75, v47, v103, vcc
	v_cndmask_b32_e32 v76, v48, v104, vcc
	v_cndmask_b32_e32 v77, v50, v106, vcc
	v_cndmask_b32_e32 v78, v51, v107, vcc
	ds_bpermute_b32 v52, v49, v24
	ds_bpermute_b32 v71, v49, v25
	ds_bpermute_b32 v79, v49, v26
	ds_bpermute_b32 v80, v49, v27
	ds_bpermute_b32 v81, v49, v28
	ds_bpermute_b32 v82, v49, v29
	ds_bpermute_b32 v83, v49, v30
	ds_bpermute_b32 v84, v49, v31
	ds_bpermute_b32 v85, v49, v32
	ds_bpermute_b32 v86, v49, v33
	ds_bpermute_b32 v87, v49, v34
	ds_bpermute_b32 v88, v49, v35
	ds_bpermute_b32 v89, v49, v36
	ds_bpermute_b32 v90, v49, v37
	ds_bpermute_b32 v91, v49, v38
	ds_bpermute_b32 v92, v49, v39
	ds_bpermute_b32 v93, v49, v40
	ds_bpermute_b32 v94, v49, v41
	ds_bpermute_b32 v95, v49, v42
	ds_bpermute_b32 v96, v49, v43
	ds_bpermute_b32 v97, v49, v44
	ds_bpermute_b32 v98, v49, v45
	ds_bpermute_b32 v99, v49, v46
	ds_bpermute_b32 v100, v49, v47
	ds_bpermute_b32 v101, v49, v48
	ds_bpermute_b32 v102, v49, v22
	ds_bpermute_b32 v103, v49, v50
	ds_bpermute_b32 v104, v49, v51
	ds_bpermute_b32 v105, v49, v21
	ds_bpermute_b32 v106, v49, v53
	ds_bpermute_b32 v107, v49, v54
	ds_bpermute_b32 v49, v49, v19
	v_cndmask_b32_e32 v23, v53, v23, vcc
	v_cndmask_b32_e32 v20, v54, v20, vcc
	v_cmp_gt_i32_e32 vcc, 2, v68
	s_waitcnt lgkmcnt(14)
	v_add_f32_e32 v52, v24, v52
	s_waitcnt lgkmcnt(0)
	v_add_f32_e32 v49, v19, v49
	v_cndmask_b32_e32 v19, v49, v19, vcc
	v_add_u32_e32 v49, -4, v110
	v_cmp_lt_i32_e64 s[0:1], v49, v18
	v_add_f32_e32 v71, v25, v71
	v_add_f32_e32 v79, v26, v79
	v_add_f32_e32 v80, v27, v80
	v_add_f32_e32 v81, v28, v81
	v_add_f32_e32 v82, v29, v82
	v_add_f32_e32 v83, v30, v83
	v_add_f32_e32 v84, v31, v84
	v_add_f32_e32 v85, v32, v85
	v_add_f32_e32 v86, v33, v86
	v_add_f32_e32 v87, v34, v87
	v_add_f32_e32 v88, v35, v88
	v_add_f32_e32 v89, v36, v89
	v_add_f32_e32 v90, v37, v90
	v_add_f32_e32 v91, v38, v91
	v_add_f32_e32 v92, v39, v92
	v_add_f32_e32 v93, v40, v93
	v_add_f32_e32 v94, v41, v94
	v_add_f32_e32 v95, v42, v95
	v_add_f32_e32 v96, v43, v96
	v_add_f32_e32 v97, v44, v97
	v_add_f32_e32 v98, v45, v98
	v_add_f32_e32 v99, v46, v99
	v_add_f32_e32 v100, v47, v100
	v_add_f32_e32 v101, v48, v101
	v_add_f32_e32 v102, v22, v102
	v_add_f32_e32 v103, v50, v103
	v_add_f32_e32 v104, v51, v104
	v_add_f32_e32 v105, v21, v105
	v_add_f32_e32 v106, v53, v106
	v_add_f32_e32 v107, v54, v107
	v_cndmask_b32_e64 v49, v49, v110, s[0:1]
	v_cndmask_b32_e32 v24, v52, v24, vcc
	v_cndmask_b32_e32 v26, v79, v26, vcc
	v_cndmask_b32_e32 v27, v80, v27, vcc
	v_cndmask_b32_e32 v29, v82, v29, vcc
	v_cndmask_b32_e32 v30, v83, v30, vcc
	v_cndmask_b32_e32 v32, v85, v32, vcc
	v_cndmask_b32_e32 v33, v86, v33, vcc
	v_cndmask_b32_e32 v35, v88, v35, vcc
	v_cndmask_b32_e32 v36, v89, v36, vcc
	v_cndmask_b32_e32 v38, v91, v38, vcc
	v_cndmask_b32_e32 v39, v92, v39, vcc
	v_cndmask_b32_e32 v41, v94, v41, vcc
	v_cndmask_b32_e32 v42, v95, v42, vcc
	v_cndmask_b32_e32 v44, v97, v44, vcc
	v_cndmask_b32_e32 v45, v98, v45, vcc
	v_cndmask_b32_e32 v47, v100, v47, vcc
	v_cndmask_b32_e32 v48, v101, v48, vcc
	v_cndmask_b32_e32 v50, v103, v50, vcc
	v_cndmask_b32_e32 v51, v104, v51, vcc
	v_cndmask_b32_e32 v53, v106, v53, vcc
	v_cndmask_b32_e32 v54, v107, v54, vcc
	v_cndmask_b32_e32 v21, v105, v21, vcc
	v_cndmask_b32_e32 v22, v102, v22, vcc
	v_cndmask_b32_e32 v46, v99, v46, vcc
	v_cndmask_b32_e32 v43, v96, v43, vcc
	v_cndmask_b32_e32 v40, v93, v40, vcc
	v_cndmask_b32_e32 v37, v90, v37, vcc
	v_cndmask_b32_e32 v34, v87, v34, vcc
	v_lshlrev_b32_e32 v49, 2, v49
	v_cndmask_b32_e32 v31, v84, v31, vcc
	v_cndmask_b32_e32 v28, v81, v28, vcc
	v_cndmask_b32_e32 v25, v71, v25, vcc
	v_cndmask_b32_e32 v20, v107, v20, vcc
	v_cndmask_b32_e32 v23, v106, v23, vcc
	v_cndmask_b32_e32 v78, v104, v78, vcc
	v_cndmask_b32_e32 v77, v103, v77, vcc
	v_cndmask_b32_e32 v76, v101, v76, vcc
	v_cndmask_b32_e32 v75, v100, v75, vcc
	v_cndmask_b32_e32 v74, v98, v74, vcc
	v_cndmask_b32_e32 v73, v97, v73, vcc
	v_cndmask_b32_e32 v72, v95, v72, vcc
	v_cndmask_b32_e32 v70, v94, v70, vcc
	v_cndmask_b32_e32 v65, v92, v65, vcc
	v_cndmask_b32_e32 v64, v91, v64, vcc
	v_cndmask_b32_e32 v63, v89, v63, vcc
	v_cndmask_b32_e32 v62, v88, v62, vcc
	v_cndmask_b32_e32 v61, v86, v61, vcc
	v_cndmask_b32_e32 v60, v85, v60, vcc
	v_cndmask_b32_e32 v59, v83, v59, vcc
	v_cndmask_b32_e32 v58, v82, v58, vcc
	v_cndmask_b32_e32 v57, v80, v57, vcc
	v_cndmask_b32_e32 v56, v79, v56, vcc
	v_cndmask_b32_e32 v52, v52, v55, vcc
	ds_bpermute_b32 v55, v49, v24
	ds_bpermute_b32 v71, v49, v25
	ds_bpermute_b32 v79, v49, v26
	ds_bpermute_b32 v80, v49, v27
	ds_bpermute_b32 v81, v49, v28
	ds_bpermute_b32 v82, v49, v29
	ds_bpermute_b32 v83, v49, v30
	ds_bpermute_b32 v84, v49, v31
	ds_bpermute_b32 v85, v49, v32
	ds_bpermute_b32 v86, v49, v33
	ds_bpermute_b32 v87, v49, v34
	ds_bpermute_b32 v88, v49, v35
	ds_bpermute_b32 v89, v49, v36
	ds_bpermute_b32 v90, v49, v37
	ds_bpermute_b32 v91, v49, v38
	ds_bpermute_b32 v92, v49, v39
	ds_bpermute_b32 v93, v49, v40
	ds_bpermute_b32 v94, v49, v41
	ds_bpermute_b32 v95, v49, v42
	ds_bpermute_b32 v96, v49, v43
	ds_bpermute_b32 v97, v49, v44
	ds_bpermute_b32 v98, v49, v45
	ds_bpermute_b32 v99, v49, v46
	ds_bpermute_b32 v100, v49, v47
	ds_bpermute_b32 v101, v49, v48
	ds_bpermute_b32 v102, v49, v22
	ds_bpermute_b32 v103, v49, v50
	ds_bpermute_b32 v104, v49, v51
	ds_bpermute_b32 v105, v49, v21
	ds_bpermute_b32 v106, v49, v53
	ds_bpermute_b32 v107, v49, v54
	ds_bpermute_b32 v49, v49, v19
	v_cmp_gt_i32_e32 vcc, 4, v68
	s_waitcnt lgkmcnt(14)
	v_add_f32_e32 v55, v24, v55
	v_add_f32_e32 v71, v25, v71
	v_cndmask_b32_e32 v24, v55, v24, vcc
	s_waitcnt lgkmcnt(0)
	v_add_f32_e32 v49, v19, v49
	v_cndmask_b32_e32 v19, v49, v19, vcc
	v_add_u32_e32 v49, -8, v110
	v_cmp_lt_i32_e64 s[0:1], v49, v18
	v_add_f32_e32 v79, v26, v79
	v_add_f32_e32 v80, v27, v80
	v_cndmask_b32_e64 v49, v49, v110, s[0:1]
	v_add_f32_e32 v82, v29, v82
	v_add_f32_e32 v83, v30, v83
	v_add_f32_e32 v85, v32, v85
	v_add_f32_e32 v86, v33, v86
	v_add_f32_e32 v88, v35, v88
	v_add_f32_e32 v89, v36, v89
	v_add_f32_e32 v91, v38, v91
	v_add_f32_e32 v92, v39, v92
	v_add_f32_e32 v94, v41, v94
	v_add_f32_e32 v95, v42, v95
	v_add_f32_e32 v97, v44, v97
	v_add_f32_e32 v98, v45, v98
	v_add_f32_e32 v100, v47, v100
	v_add_f32_e32 v101, v48, v101
	v_add_f32_e32 v103, v50, v103
	v_add_f32_e32 v104, v51, v104
	v_cndmask_b32_e32 v25, v71, v25, vcc
	v_lshlrev_b32_e32 v49, 2, v49
	v_cndmask_b32_e32 v52, v55, v52, vcc
	v_cndmask_b32_e32 v55, v79, v56, vcc
	v_cndmask_b32_e32 v56, v80, v57, vcc
	v_cndmask_b32_e32 v57, v82, v58, vcc
	v_cndmask_b32_e32 v58, v83, v59, vcc
	v_cndmask_b32_e32 v59, v85, v60, vcc
	v_cndmask_b32_e32 v60, v86, v61, vcc
	v_cndmask_b32_e32 v61, v88, v62, vcc
	v_cndmask_b32_e32 v62, v89, v63, vcc
	v_cndmask_b32_e32 v63, v91, v64, vcc
	v_cndmask_b32_e32 v64, v92, v65, vcc
	v_cndmask_b32_e32 v65, v94, v70, vcc
	v_cndmask_b32_e32 v70, v95, v72, vcc
	v_cndmask_b32_e32 v72, v97, v73, vcc
	v_cndmask_b32_e32 v73, v98, v74, vcc
	v_cndmask_b32_e32 v74, v100, v75, vcc
	v_cndmask_b32_e32 v75, v101, v76, vcc
	v_cndmask_b32_e32 v76, v103, v77, vcc
	v_cndmask_b32_e32 v77, v104, v78, vcc
	ds_bpermute_b32 v71, v49, v24
	ds_bpermute_b32 v78, v49, v25
	v_add_f32_e32 v81, v28, v81
	v_cndmask_b32_e32 v26, v79, v26, vcc
	v_cndmask_b32_e32 v29, v82, v29, vcc
	v_cndmask_b32_e32 v30, v83, v30, vcc
	v_cndmask_b32_e32 v28, v81, v28, vcc
	v_cndmask_b32_e32 v27, v80, v27, vcc
	s_waitcnt lgkmcnt(1)
	v_add_f32_e32 v24, v24, v71
	s_waitcnt lgkmcnt(0)
	v_add_f32_e32 v71, v25, v78
	ds_bpermute_b32 v78, v49, v26
	ds_bpermute_b32 v80, v49, v28
	ds_bpermute_b32 v81, v49, v29
	ds_bpermute_b32 v82, v49, v30
	v_add_f32_e32 v87, v34, v87
	v_cndmask_b32_e32 v32, v85, v32, vcc
	v_cndmask_b32_e32 v33, v86, v33, vcc
	v_cndmask_b32_e32 v35, v88, v35, vcc
	v_cndmask_b32_e32 v34, v87, v34, vcc
	s_waitcnt lgkmcnt(3)
	v_add_f32_e32 v26, v26, v78
	s_waitcnt lgkmcnt(2)
	v_add_f32_e32 v78, v28, v80
	s_waitcnt lgkmcnt(1)
	v_add_f32_e32 v29, v29, v81
	s_waitcnt lgkmcnt(0)
	v_add_f32_e32 v30, v30, v82
	ds_bpermute_b32 v80, v49, v32
	ds_bpermute_b32 v81, v49, v33
	ds_bpermute_b32 v82, v49, v34
	ds_bpermute_b32 v83, v49, v35
	v_add_f32_e32 v90, v37, v90
	v_add_f32_e32 v93, v40, v93
	v_cndmask_b32_e32 v36, v89, v36, vcc
	v_cndmask_b32_e32 v38, v91, v38, vcc
	v_cndmask_b32_e32 v40, v93, v40, vcc
	v_cndmask_b32_e32 v37, v90, v37, vcc
	s_waitcnt lgkmcnt(3)
	v_add_f32_e32 v32, v32, v80
	s_waitcnt lgkmcnt(2)
	v_add_f32_e32 v33, v33, v81
	s_waitcnt lgkmcnt(1)
	v_add_f32_e32 v80, v34, v82
	s_waitcnt lgkmcnt(0)
	v_add_f32_e32 v35, v35, v83
	ds_bpermute_b32 v81, v49, v36
	ds_bpermute_b32 v82, v49, v37
	ds_bpermute_b32 v83, v49, v38
	ds_bpermute_b32 v85, v49, v40
	v_add_f32_e32 v96, v43, v96
	v_add_f32_e32 v84, v31, v84
	v_cndmask_b32_e32 v39, v92, v39, vcc
	v_cndmask_b32_e32 v41, v94, v41, vcc
	v_cndmask_b32_e32 v44, v97, v44, vcc
	v_cndmask_b32_e32 v45, v98, v45, vcc
	v_cndmask_b32_e32 v43, v96, v43, vcc
	v_cndmask_b32_e32 v31, v84, v31, vcc
	ds_bpermute_b32 v84, v49, v39
	s_waitcnt lgkmcnt(4)
	v_add_f32_e32 v36, v36, v81
	s_waitcnt lgkmcnt(3)
	v_add_f32_e32 v81, v37, v82
	s_waitcnt lgkmcnt(2)
	v_add_f32_e32 v38, v38, v83
	s_waitcnt lgkmcnt(1)
	v_add_f32_e32 v82, v40, v85
	ds_bpermute_b32 v83, v49, v41
	ds_bpermute_b32 v85, v49, v43
	ds_bpermute_b32 v86, v49, v44
	ds_bpermute_b32 v87, v49, v45
	v_add_f32_e32 v102, v22, v102
	v_cndmask_b32_e32 v42, v95, v42, vcc
	v_cndmask_b32_e32 v47, v100, v47, vcc
	v_cndmask_b32_e32 v48, v101, v48, vcc
	v_cndmask_b32_e32 v50, v103, v50, vcc
	v_cndmask_b32_e32 v22, v102, v22, vcc
	ds_bpermute_b32 v79, v49, v27
	s_waitcnt lgkmcnt(5)
	v_add_f32_e32 v39, v39, v84
	ds_bpermute_b32 v84, v49, v42
	s_waitcnt lgkmcnt(5)
	v_add_f32_e32 v41, v41, v83
	s_waitcnt lgkmcnt(4)
	v_add_f32_e32 v83, v43, v85
	s_waitcnt lgkmcnt(3)
	v_add_f32_e32 v44, v44, v86
	s_waitcnt lgkmcnt(2)
	v_add_f32_e32 v45, v45, v87
	ds_bpermute_b32 v85, v49, v47
	ds_bpermute_b32 v86, v49, v48
	ds_bpermute_b32 v87, v49, v22
	ds_bpermute_b32 v88, v49, v50
	v_add_f32_e32 v99, v46, v99
	v_add_f32_e32 v105, v21, v105
	v_add_f32_e32 v106, v53, v106
	v_add_f32_e32 v107, v54, v107
	v_cndmask_b32_e32 v51, v104, v51, vcc
	v_cndmask_b32_e32 v53, v106, v53, vcc
	v_cndmask_b32_e32 v54, v107, v54, vcc
	v_cndmask_b32_e32 v21, v105, v21, vcc
	v_cndmask_b32_e32 v46, v99, v46, vcc
	s_waitcnt lgkmcnt(5)
	v_add_f32_e32 v27, v27, v79
	ds_bpermute_b32 v79, v49, v31
	s_waitcnt lgkmcnt(5)
	v_add_f32_e32 v42, v42, v84
	ds_bpermute_b32 v84, v49, v46
	s_waitcnt lgkmcnt(5)
	v_add_f32_e32 v47, v47, v85
	s_waitcnt lgkmcnt(4)
	v_add_f32_e32 v48, v48, v86
	s_waitcnt lgkmcnt(3)
	v_add_f32_e32 v85, v22, v87
	s_waitcnt lgkmcnt(2)
	v_add_f32_e32 v50, v50, v88
	ds_bpermute_b32 v86, v49, v51
	ds_bpermute_b32 v87, v49, v21
	ds_bpermute_b32 v88, v49, v53
	ds_bpermute_b32 v89, v49, v54
	ds_bpermute_b32 v49, v49, v19
	v_cndmask_b32_e32 v23, v106, v23, vcc
	v_cndmask_b32_e32 v20, v107, v20, vcc
	s_waitcnt lgkmcnt(4)
	v_add_f32_e32 v51, v51, v86
	v_cmp_gt_i32_e32 vcc, 8, v68
	s_waitcnt lgkmcnt(0)
	v_add_f32_e32 v49, v19, v49
	v_add_f32_e32 v79, v31, v79
	v_cndmask_b32_e32 v19, v49, v19, vcc
	v_cndmask_b32_e32 v49, v51, v77, vcc
	v_add_u32_e32 v51, -16, v110
	v_cmp_lt_i32_e64 s[0:1], v51, v18
	v_add_f32_e32 v84, v46, v84
	v_add_f32_e32 v86, v21, v87
	v_cndmask_b32_e64 v51, v51, v110, s[0:1]
	v_add_f32_e32 v53, v53, v88
	v_add_f32_e32 v54, v54, v89
	v_cndmask_b32_e32 v41, v41, v65, vcc
	v_cndmask_b32_e32 v33, v33, v60, vcc
	v_lshlrev_b32_e32 v51, 2, v51
	v_cndmask_b32_e32 v20, v54, v20, vcc
	v_cndmask_b32_e32 v23, v53, v23, vcc
	v_cndmask_b32_e32 v21, v86, v21, vcc
	v_cndmask_b32_e32 v50, v50, v76, vcc
	v_cndmask_b32_e32 v22, v85, v22, vcc
	v_cndmask_b32_e32 v48, v48, v75, vcc
	v_cndmask_b32_e32 v47, v47, v74, vcc
	v_cndmask_b32_e32 v46, v84, v46, vcc
	v_cndmask_b32_e32 v45, v45, v73, vcc
	v_cndmask_b32_e32 v44, v44, v72, vcc
	v_cndmask_b32_e32 v43, v83, v43, vcc
	v_cndmask_b32_e32 v42, v42, v70, vcc
	v_cndmask_b32_e32 v40, v82, v40, vcc
	v_cndmask_b32_e32 v39, v39, v64, vcc
	v_cndmask_b32_e32 v38, v38, v63, vcc
	v_cndmask_b32_e32 v37, v81, v37, vcc
	v_cndmask_b32_e32 v36, v36, v62, vcc
	v_cndmask_b32_e32 v35, v35, v61, vcc
	v_cndmask_b32_e32 v34, v80, v34, vcc
	v_cndmask_b32_e32 v32, v32, v59, vcc
	v_cndmask_b32_e32 v31, v79, v31, vcc
	v_cndmask_b32_e32 v30, v30, v58, vcc
	v_cndmask_b32_e32 v29, v29, v57, vcc
	v_cndmask_b32_e32 v28, v78, v28, vcc
	v_cndmask_b32_e32 v24, v24, v52, vcc
	v_cndmask_b32_e32 v27, v27, v56, vcc
	v_cndmask_b32_e32 v26, v26, v55, vcc
	v_cndmask_b32_e32 v25, v71, v25, vcc
	ds_bpermute_b32 v61, v51, v33
	ds_bpermute_b32 v73, v51, v41
	ds_bpermute_b32 v52, v51, v24
	ds_bpermute_b32 v53, v51, v25
	ds_bpermute_b32 v54, v51, v26
	ds_bpermute_b32 v55, v51, v27
	ds_bpermute_b32 v56, v51, v28
	ds_bpermute_b32 v57, v51, v29
	ds_bpermute_b32 v58, v51, v30
	ds_bpermute_b32 v59, v51, v31
	ds_bpermute_b32 v60, v51, v32
	ds_bpermute_b32 v62, v51, v34
	ds_bpermute_b32 v63, v51, v35
	ds_bpermute_b32 v64, v51, v36
	ds_bpermute_b32 v65, v51, v37
	ds_bpermute_b32 v70, v51, v38
	ds_bpermute_b32 v71, v51, v39
	ds_bpermute_b32 v72, v51, v40
	ds_bpermute_b32 v74, v51, v42
	ds_bpermute_b32 v75, v51, v43
	ds_bpermute_b32 v76, v51, v44
	ds_bpermute_b32 v77, v51, v45
	ds_bpermute_b32 v78, v51, v46
	ds_bpermute_b32 v79, v51, v47
	ds_bpermute_b32 v80, v51, v48
	ds_bpermute_b32 v81, v51, v22
	ds_bpermute_b32 v82, v51, v50
	ds_bpermute_b32 v83, v51, v49
	ds_bpermute_b32 v84, v51, v21
	ds_bpermute_b32 v85, v51, v23
	ds_bpermute_b32 v86, v51, v20
	ds_bpermute_b32 v51, v51, v19
	v_cmp_gt_i32_e32 vcc, 16, v68
	s_waitcnt lgkmcnt(14)
	v_add_f32_e32 v61, v33, v61
	v_add_f32_e32 v73, v41, v73
	v_cndmask_b32_e32 v61, v61, v33, vcc
	v_cndmask_b32_e32 v73, v73, v41, vcc
	s_waitcnt lgkmcnt(3)
	v_add_f32_e32 v84, v21, v84
	s_waitcnt lgkmcnt(0)
	v_add_f32_e32 v51, v19, v51
	v_cndmask_b32_e32 v93, v61, v33, vcc
	v_cndmask_b32_e32 v33, v73, v41, vcc
	v_cndmask_b32_e32 v41, v51, v19, vcc
	v_cndmask_b32_e32 v19, v84, v21, vcc
	v_subrev_u32_e32 v21, 32, v110
	v_add_f32_e32 v57, v29, v57
	v_add_f32_e32 v79, v47, v79
	v_cmp_lt_i32_e64 s[0:1], v21, v18
	v_add_f32_e32 v52, v24, v52
	v_add_f32_e32 v53, v25, v53
	v_cndmask_b32_e32 v57, v57, v29, vcc
	v_add_f32_e32 v60, v32, v60
	v_add_f32_e32 v74, v42, v74
	v_cndmask_b32_e32 v79, v79, v47, vcc
	v_cndmask_b32_e64 v18, v21, v110, s[0:1]
	v_cndmask_b32_e32 v52, v52, v24, vcc
	v_cndmask_b32_e32 v60, v60, v32, vcc
	v_cndmask_b32_e32 v74, v74, v42, vcc
	v_add_f32_e32 v81, v22, v81
	v_cndmask_b32_e32 v91, v57, v29, vcc
	v_cndmask_b32_e32 v29, v79, v47, vcc
	v_cndmask_b32_e32 v47, v53, v25, vcc
	v_lshlrev_b32_e32 v18, 2, v18
	v_cndmask_b32_e32 v94, v60, v32, vcc
	v_cndmask_b32_e32 v32, v74, v42, vcc
	v_cndmask_b32_e32 v42, v81, v22, vcc
	ds_bpermute_b32 v21, v18, v52
	ds_bpermute_b32 v22, v18, v47
	v_add_f32_e32 v63, v35, v63
	v_add_f32_e32 v64, v36, v64
	v_add_f32_e32 v80, v48, v80
	v_add_f32_e32 v54, v26, v54
	v_add_f32_e32 v55, v27, v55
	v_add_f32_e32 v56, v28, v56
	v_add_f32_e32 v58, v30, v58
	v_cndmask_b32_e32 v63, v63, v35, vcc
	v_cndmask_b32_e32 v64, v64, v36, vcc
	v_cndmask_b32_e32 v80, v80, v48, vcc
	v_add_f32_e32 v82, v50, v82
	v_add_f32_e32 v83, v49, v83
	v_cndmask_b32_e32 v54, v54, v26, vcc
	v_cndmask_b32_e32 v55, v55, v27, vcc
	v_cndmask_b32_e32 v58, v58, v30, vcc
	v_cndmask_b32_e32 v82, v82, v50, vcc
	v_cndmask_b32_e32 v83, v83, v49, vcc
	v_cndmask_b32_e32 v92, v63, v35, vcc
	v_cndmask_b32_e32 v35, v64, v36, vcc
	v_cndmask_b32_e32 v36, v80, v48, vcc
	v_cndmask_b32_e32 v48, v56, v28, vcc
	v_cndmask_b32_e32 v89, v52, v24, vcc
	v_cndmask_b32_e32 v90, v58, v30, vcc
	v_cndmask_b32_e32 v30, v83, v49, vcc
	v_cndmask_b32_e32 v24, v82, v50, vcc
	s_waitcnt lgkmcnt(1)
	v_add_f32_e32 v49, v52, v21
	s_waitcnt lgkmcnt(0)
	v_add_f32_e32 v50, v47, v22
	ds_bpermute_b32 v21, v18, v54
	ds_bpermute_b32 v22, v18, v55
	ds_bpermute_b32 v25, v18, v48
	v_add_f32_e32 v76, v44, v76
	v_add_f32_e32 v59, v31, v59
	v_cndmask_b32_e32 v76, v76, v44, vcc
	v_add_f32_e32 v78, v46, v78
	v_cndmask_b32_e32 v88, v54, v26, vcc
	v_cndmask_b32_e32 v26, v76, v44, vcc
	v_cndmask_b32_e32 v44, v78, v46, vcc
	v_cndmask_b32_e32 v46, v59, v31, vcc
	ds_bpermute_b32 v28, v18, v57
	ds_bpermute_b32 v31, v18, v58
	s_waitcnt lgkmcnt(4)
	v_add_f32_e32 v51, v54, v21
	s_waitcnt lgkmcnt(3)
	v_add_f32_e32 v52, v55, v22
	s_waitcnt lgkmcnt(2)
	v_add_f32_e32 v53, v48, v25
	ds_bpermute_b32 v21, v18, v46
	ds_bpermute_b32 v22, v18, v60
	ds_bpermute_b32 v25, v18, v61
	v_add_f32_e32 v77, v45, v77
	v_add_f32_e32 v62, v34, v62
	v_add_f32_e32 v65, v37, v65
	v_add_f32_e32 v70, v38, v70
	v_cndmask_b32_e32 v77, v77, v45, vcc
	v_cndmask_b32_e32 v70, v70, v38, vcc
	v_cndmask_b32_e32 v87, v55, v27, vcc
	v_cndmask_b32_e32 v27, v77, v45, vcc
	v_cndmask_b32_e32 v37, v65, v37, vcc
	v_cndmask_b32_e32 v45, v62, v34, vcc
	s_waitcnt lgkmcnt(4)
	v_add_f32_e32 v54, v57, v28
	s_waitcnt lgkmcnt(3)
	v_add_f32_e32 v55, v58, v31
	ds_bpermute_b32 v28, v18, v45
	s_waitcnt lgkmcnt(3)
	v_add_f32_e32 v56, v46, v21
	s_waitcnt lgkmcnt(2)
	v_add_f32_e32 v57, v60, v22
	s_waitcnt lgkmcnt(1)
	v_add_f32_e32 v58, v61, v25
	ds_bpermute_b32 v21, v18, v64
	ds_bpermute_b32 v22, v18, v37
	ds_bpermute_b32 v25, v18, v70
	v_add_f32_e32 v71, v39, v71
	v_add_f32_e32 v75, v43, v75
	v_cndmask_b32_e32 v71, v71, v39, vcc
	v_cndmask_b32_e32 v43, v75, v43, vcc
	ds_bpermute_b32 v31, v18, v63
	s_waitcnt lgkmcnt(4)
	v_add_f32_e32 v59, v45, v28
	ds_bpermute_b32 v28, v18, v71
	s_waitcnt lgkmcnt(4)
	v_add_f32_e32 v34, v64, v21
	s_waitcnt lgkmcnt(3)
	v_add_f32_e32 v61, v37, v22
	s_waitcnt lgkmcnt(2)
	v_add_f32_e32 v62, v70, v25
	ds_bpermute_b32 v21, v18, v73
	ds_bpermute_b32 v22, v18, v74
	ds_bpermute_b32 v25, v18, v43
	v_add_f32_e32 v72, v40, v72
	v_cndmask_b32_e32 v39, v71, v39, vcc
	v_cndmask_b32_e32 v38, v70, v38, vcc
	v_cndmask_b32_e32 v40, v72, v40, vcc
	s_waitcnt lgkmcnt(4)
	v_add_f32_e32 v60, v63, v31
	s_waitcnt lgkmcnt(3)
	v_add_f32_e32 v63, v71, v28
	ds_bpermute_b32 v28, v18, v76
	s_waitcnt lgkmcnt(3)
	v_add_f32_e32 v65, v73, v21
	s_waitcnt lgkmcnt(2)
	v_add_f32_e32 v70, v74, v22
	s_waitcnt lgkmcnt(1)
	v_add_f32_e32 v71, v43, v25
	ds_bpermute_b32 v21, v18, v44
	ds_bpermute_b32 v22, v18, v79
	ds_bpermute_b32 v25, v18, v80
	ds_bpermute_b32 v72, v18, v42
	ds_bpermute_b32 v73, v18, v82
	ds_bpermute_b32 v64, v18, v77
	v_add_f32_e32 v85, v23, v85
	v_cndmask_b32_e32 v85, v85, v23, vcc
	v_add_f32_e32 v86, v20, v86
	v_cndmask_b32_e32 v86, v86, v20, vcc
	ds_bpermute_b32 v31, v18, v40
	s_waitcnt lgkmcnt(7)
	v_add_f32_e32 v28, v76, v28
	s_waitcnt lgkmcnt(6)
	v_add_f32_e32 v74, v44, v21
	s_waitcnt lgkmcnt(5)
	v_add_f32_e32 v75, v79, v22
	s_waitcnt lgkmcnt(4)
	v_add_f32_e32 v22, v80, v25
	s_waitcnt lgkmcnt(3)
	v_add_f32_e32 v25, v42, v72
	s_waitcnt lgkmcnt(2)
	v_add_f32_e32 v72, v82, v73
	ds_bpermute_b32 v21, v18, v83
	ds_bpermute_b32 v73, v18, v19
	ds_bpermute_b32 v76, v18, v85
	s_waitcnt lgkmcnt(4)
	v_add_f32_e32 v64, v77, v64
	ds_bpermute_b32 v77, v18, v86
	ds_bpermute_b32 v18, v18, v41
	s_lshl_b32 s0, s41, 3
	v_cndmask_b32_e32 v20, v86, v20, vcc
	v_cndmask_b32_e32 v23, v85, v23, vcc
	s_waitcnt lgkmcnt(5)
	v_add_f32_e32 v31, v40, v31
	s_waitcnt lgkmcnt(4)
	v_add_f32_e32 v78, v83, v21
	s_waitcnt lgkmcnt(3)
	v_add_f32_e32 v21, v19, v73
	s_waitcnt lgkmcnt(2)
	v_add_f32_e32 v73, v85, v76
	v_cmp_gt_i32_e32 vcc, 32, v68
	s_or_b32 s0, s40, s0
	s_waitcnt lgkmcnt(1)
	v_add_f32_e32 v76, v86, v77
	s_waitcnt lgkmcnt(0)
	v_add_f32_e32 v77, v41, v18
	v_cndmask_b32_e32 v18, v21, v19, vcc
	v_cndmask_b32_e32 v19, v73, v23, vcc
	v_cndmask_b32_e32 v23, v25, v42, vcc
	v_cndmask_b32_e32 v25, v78, v30, vcc
	v_cndmask_b32_e32 v30, v31, v40, vcc
	v_cndmask_b32_e32 v40, v59, v45, vcc
	v_cndmask_b32_e32 v45, v56, v46, vcc
	v_cndmask_b32_e32 v46, v49, v89, vcc
	v_cndmask_b32_e32 v49, v52, v87, vcc
	s_mulk_i32 s0, 0x104
	v_lshl_or_b32 v52, v110, 2, v116
	v_lshrrev_b32_e32 v255, 2, v52
	s_nop 0
	v_readfirstlane_b32 s101, v255
	s_nop 3
	v_cndmask_b32_e32 v42, v53, v48, vcc
	s_or_b32 s6, s0, s39
	v_readlane_b32 s98, v46, s101
	s_lshl_b64 s[0:1], s[6:7], 13
	s_add_u32 s12, s11, s0
	v_cndmask_b32_e32 v47, v50, v47, vcc
	v_cndmask_b32_e32 v48, v51, v88, vcc
	s_addc_u32 s13, s16, s1
	v_lshlrev_b64 v[50:51], 7, v[68:69]
	v_cndmask_b32_e32 v20, v76, v20, vcc
	v_cndmask_b32_e32 v21, v77, v41, vcc
	v_cndmask_b32_e32 v22, v22, v36, vcc
	v_cndmask_b32_e32 v34, v34, v35, vcc
	v_cndmask_b32_e32 v35, v61, v37, vcc
	v_cndmask_b32_e32 v36, v62, v38, vcc
	v_cndmask_b32_e32 v37, v63, v39, vcc
	v_lshl_add_u64 v[50:51], s[12:13], 0, v[50:51]
	v_cndmask_b32_e32 v24, v72, v24, vcc
	v_cndmask_b32_e32 v26, v28, v26, vcc
	v_cndmask_b32_e32 v27, v64, v27, vcc
	v_cndmask_b32_e32 v28, v74, v44, vcc
	v_cndmask_b32_e32 v29, v75, v29, vcc
	v_cndmask_b32_e32 v31, v65, v33, vcc
	v_cndmask_b32_e32 v32, v70, v32, vcc
	v_cndmask_b32_e32 v33, v71, v43, vcc
	v_cndmask_b32_e32 v38, v57, v94, vcc
	v_cndmask_b32_e32 v39, v58, v93, vcc
	v_cndmask_b32_e32 v41, v60, v92, vcc
	v_cndmask_b32_e32 v43, v54, v91, vcc
	v_cndmask_b32_e32 v44, v55, v90, vcc
	global_store_dwordx4 v[50:51], v[46:49], off
	global_store_dwordx4 v[50:51], v[42:45], off offset:16
	global_store_dwordx4 v[50:51], v[38:41], off offset:32
	global_store_dwordx4 v[50:51], v[34:37], off offset:48
	global_store_dwordx4 v[50:51], v[30:33], off offset:64
	global_store_dwordx4 v[50:51], v[26:29], off offset:80
	global_store_dwordx4 v[50:51], v[22:25], off offset:96
	v_sub_f32_e32 v53, s98, v46
	global_store_dwordx4 v[50:51], v[18:21], off offset:112
	v_readlane_b32 s98, v47, s101
	v_mul_f32_e32 v53, 0x3fb8aa3b, v53
	v_exp_f32_e32 v53, v53
	v_lshlrev_b32_e32 v51, 16, v14
	v_and_b32_e32 v14, 0xffff0000, v14
	v_sub_f32_e32 v50, s98, v47
	v_mul_f32_e32 v51, v53, v51
	v_mul_f32_e32 v50, 0x3fb8aa3b, v50
	v_bfe_u32 v53, v51, 16, 1
	v_exp_f32_e32 v50, v50
	v_add3_u32 v51, v51, v53, s36
	ds_write_b16_d16_hi v66, v51 offset:8192
	v_readlane_b32 s98, v48, s101
	v_mul_f32_e32 v14, v50, v14
	v_bfe_u32 v50, v14, 16, 1
	v_add3_u32 v14, v14, v50, s36
	ds_write_b16_d16_hi v66, v14 offset:8320
	v_sub_f32_e32 v50, s98, v48
	v_readlane_b32 s98, v49, s101
	v_mul_f32_e32 v50, 0x3fb8aa3b, v50
	v_exp_f32_e32 v50, v50
	v_lshlrev_b32_e32 v51, 16, v15
	v_and_b32_e32 v15, 0xffff0000, v15
	v_sub_f32_e32 v14, s98, v49
	v_mul_f32_e32 v50, v50, v51
	v_mul_f32_e32 v14, 0x3fb8aa3b, v14
	v_bfe_u32 v51, v50, 16, 1
	v_exp_f32_e32 v14, v14
	v_add3_u32 v50, v50, v51, s36
	ds_write_b16_d16_hi v66, v50 offset:8448
	v_readlane_b32 s98, v42, s101
	v_mul_f32_e32 v14, v14, v15
	v_bfe_u32 v15, v14, 16, 1
	v_add3_u32 v14, v14, v15, s36
	ds_write_b16_d16_hi v66, v14 offset:8576
	v_sub_f32_e32 v15, s98, v42
	v_readlane_b32 s98, v43, s101
	v_mul_f32_e32 v15, 0x3fb8aa3b, v15
	v_exp_f32_e32 v15, v15
	v_lshlrev_b32_e32 v50, 16, v16
	v_and_b32_e32 v16, 0xffff0000, v16
	v_sub_f32_e32 v14, s98, v43
	v_mul_f32_e32 v15, v15, v50
	v_mul_f32_e32 v14, 0x3fb8aa3b, v14
	v_bfe_u32 v50, v15, 16, 1
	v_exp_f32_e32 v14, v14
	v_add3_u32 v15, v15, v50, s36
	ds_write_b16_d16_hi v66, v15 offset:8704
	v_readlane_b32 s98, v44, s101
	v_mul_f32_e32 v14, v14, v16
	v_bfe_u32 v16, v14, 16, 1
	v_add3_u32 v14, v14, v16, s36
	ds_write_b16_d16_hi v66, v14 offset:8832
	v_sub_f32_e32 v15, s98, v44
	v_readlane_b32 s98, v45, s101
	v_mul_f32_e32 v15, 0x3fb8aa3b, v15
	v_exp_f32_e32 v15, v15
	v_lshlrev_b32_e32 v16, 16, v17
	v_cmp_eq_u32_e32 vcc, 63, v68
	v_sub_f32_e32 v14, s98, v45
	v_mul_f32_e32 v15, v15, v16
	v_mul_f32_e32 v14, 0x3fb8aa3b, v14
	v_bfe_u32 v16, v15, 16, 1
	v_exp_f32_e32 v14, v14
	v_add3_u32 v15, v15, v16, s36
	ds_write_b16_d16_hi v66, v15 offset:8960
	v_readlane_b32 s98, v38, s101
	v_and_b32_e32 v16, 0xffff0000, v17
	v_mul_f32_e32 v14, v14, v16
	v_bfe_u32 v16, v14, 16, 1
	v_add3_u32 v14, v14, v16, s36
	v_sub_f32_e32 v15, s98, v38
	ds_write_b16_d16_hi v66, v14 offset:9088
	v_readlane_b32 s98, v39, s101
	v_mul_f32_e32 v15, 0x3fb8aa3b, v15
	v_exp_f32_e32 v15, v15
	v_lshlrev_b32_e32 v16, 16, v10
	v_and_b32_e32 v10, 0xffff0000, v10
	v_sub_f32_e32 v14, s98, v39
	v_mul_f32_e32 v15, v15, v16
	v_mul_f32_e32 v14, 0x3fb8aa3b, v14
	v_bfe_u32 v16, v15, 16, 1
	v_exp_f32_e32 v14, v14
	v_add3_u32 v15, v15, v16, s36
	ds_write_b16_d16_hi v66, v15 offset:9216
	v_readlane_b32 s98, v40, s101
	v_mul_f32_e32 v10, v14, v10
	v_bfe_u32 v14, v10, 16, 1
	v_add3_u32 v10, v10, v14, s36
	ds_write_b16_d16_hi v66, v10 offset:9344
	v_sub_f32_e32 v14, s98, v40
	v_readlane_b32 s98, v41, s101
	v_mul_f32_e32 v14, 0x3fb8aa3b, v14
	v_exp_f32_e32 v14, v14
	v_lshlrev_b32_e32 v15, 16, v11
	v_and_b32_e32 v11, 0xffff0000, v11
	v_sub_f32_e32 v10, s98, v41
	v_mul_f32_e32 v14, v14, v15
	v_mul_f32_e32 v10, 0x3fb8aa3b, v10
	v_bfe_u32 v15, v14, 16, 1
	v_exp_f32_e32 v10, v10
	v_add3_u32 v14, v14, v15, s36
	ds_write_b16_d16_hi v66, v14 offset:9472
	v_readlane_b32 s98, v34, s101
	v_mul_f32_e32 v10, v10, v11
	v_bfe_u32 v11, v10, 16, 1
	v_add3_u32 v10, v10, v11, s36
	ds_write_b16_d16_hi v66, v10 offset:9600
	v_sub_f32_e32 v11, s98, v34
	v_readlane_b32 s98, v35, s101
	v_mul_f32_e32 v11, 0x3fb8aa3b, v11
	v_exp_f32_e32 v11, v11
	v_lshlrev_b32_e32 v14, 16, v12
	v_and_b32_e32 v12, 0xffff0000, v12
	v_sub_f32_e32 v10, s98, v35
	v_mul_f32_e32 v11, v11, v14
	v_mul_f32_e32 v10, 0x3fb8aa3b, v10
	v_bfe_u32 v14, v11, 16, 1
	v_exp_f32_e32 v10, v10
	v_add3_u32 v11, v11, v14, s36
	ds_write_b16_d16_hi v66, v11 offset:9728
	v_readlane_b32 s98, v36, s101
	v_mul_f32_e32 v10, v10, v12
	v_bfe_u32 v12, v10, 16, 1
	v_add3_u32 v10, v10, v12, s36
	ds_write_b16_d16_hi v66, v10 offset:9856
	v_sub_f32_e32 v11, s98, v36
	v_readlane_b32 s98, v37, s101
	v_mul_f32_e32 v11, 0x3fb8aa3b, v11
	v_exp_f32_e32 v11, v11
	v_lshlrev_b32_e32 v12, 16, v13
	v_sub_f32_e32 v10, s98, v37
	v_mul_f32_e32 v11, v11, v12
	v_mul_f32_e32 v10, 0x3fb8aa3b, v10
	v_bfe_u32 v12, v11, 16, 1
	v_exp_f32_e32 v10, v10
	v_add3_u32 v11, v11, v12, s36
	ds_write_b16_d16_hi v66, v11 offset:9984
	v_readlane_b32 s98, v30, s101
	v_and_b32_e32 v12, 0xffff0000, v13
	v_mul_f32_e32 v10, v10, v12
	v_bfe_u32 v12, v10, 16, 1
	v_add3_u32 v10, v10, v12, s36
	v_sub_f32_e32 v11, s98, v30
	ds_write_b16_d16_hi v66, v10 offset:10112
	v_readlane_b32 s98, v31, s101
	v_mul_f32_e32 v11, 0x3fb8aa3b, v11
	v_exp_f32_e32 v11, v11
	v_lshlrev_b32_e32 v12, 16, v6
	v_and_b32_e32 v6, 0xffff0000, v6
	v_sub_f32_e32 v10, s98, v31
	v_mul_f32_e32 v11, v11, v12
	v_mul_f32_e32 v10, 0x3fb8aa3b, v10
	v_bfe_u32 v12, v11, 16, 1
	v_exp_f32_e32 v10, v10
	v_add3_u32 v11, v11, v12, s36
	ds_write_b16_d16_hi v66, v11 offset:10240
	v_readlane_b32 s98, v32, s101
	v_mul_f32_e32 v6, v10, v6
	v_bfe_u32 v10, v6, 16, 1
	v_add3_u32 v6, v6, v10, s36
	ds_write_b16_d16_hi v66, v6 offset:10368
	v_sub_f32_e32 v10, s98, v32
	v_readlane_b32 s98, v33, s101
	v_mul_f32_e32 v10, 0x3fb8aa3b, v10
	v_exp_f32_e32 v10, v10
	v_lshlrev_b32_e32 v11, 16, v7
	v_and_b32_e32 v7, 0xffff0000, v7
	v_sub_f32_e32 v6, s98, v33
	v_mul_f32_e32 v10, v10, v11
	v_mul_f32_e32 v6, 0x3fb8aa3b, v6
	v_bfe_u32 v11, v10, 16, 1
	v_exp_f32_e32 v6, v6
	v_add3_u32 v10, v10, v11, s36
	ds_write_b16_d16_hi v66, v10 offset:10496
	v_readlane_b32 s98, v26, s101
	v_mul_f32_e32 v6, v6, v7
	v_bfe_u32 v7, v6, 16, 1
	v_add3_u32 v6, v6, v7, s36
	ds_write_b16_d16_hi v66, v6 offset:10624
	v_sub_f32_e32 v7, s98, v26
	v_readlane_b32 s98, v27, s101
	v_mul_f32_e32 v7, 0x3fb8aa3b, v7
	v_exp_f32_e32 v7, v7
	v_lshlrev_b32_e32 v10, 16, v8
	v_and_b32_e32 v8, 0xffff0000, v8
	v_sub_f32_e32 v6, s98, v27
	v_mul_f32_e32 v7, v7, v10
	v_mul_f32_e32 v6, 0x3fb8aa3b, v6
	v_bfe_u32 v10, v7, 16, 1
	v_exp_f32_e32 v6, v6
	v_add3_u32 v7, v7, v10, s36
	ds_write_b16_d16_hi v66, v7 offset:10752
	v_readlane_b32 s98, v28, s101
	v_mul_f32_e32 v6, v6, v8
	v_bfe_u32 v8, v6, 16, 1
	v_add3_u32 v6, v6, v8, s36
	ds_write_b16_d16_hi v66, v6 offset:10880
	v_sub_f32_e32 v7, s98, v28
	v_readlane_b32 s98, v29, s101
	v_mul_f32_e32 v7, 0x3fb8aa3b, v7
	v_exp_f32_e32 v7, v7
	v_lshlrev_b32_e32 v8, 16, v9
	v_sub_f32_e32 v6, s98, v29
	v_mul_f32_e32 v7, v7, v8
	v_mul_f32_e32 v6, 0x3fb8aa3b, v6
	v_bfe_u32 v8, v7, 16, 1
	v_exp_f32_e32 v6, v6
	v_add3_u32 v7, v7, v8, s36
	ds_write_b16_d16_hi v66, v7 offset:11008
	v_readlane_b32 s98, v22, s101
	v_and_b32_e32 v8, 0xffff0000, v9
	v_mul_f32_e32 v6, v6, v8
	v_bfe_u32 v8, v6, 16, 1
	v_add3_u32 v6, v6, v8, s36
	v_sub_f32_e32 v7, s98, v22
	ds_write_b16_d16_hi v66, v6 offset:11136
	v_readlane_b32 s98, v23, s101
	v_mul_f32_e32 v7, 0x3fb8aa3b, v7
	v_exp_f32_e32 v7, v7
	v_lshlrev_b32_e32 v8, 16, v2
	v_and_b32_e32 v2, 0xffff0000, v2
	v_sub_f32_e32 v6, s98, v23
	v_mul_f32_e32 v7, v7, v8
	v_mul_f32_e32 v6, 0x3fb8aa3b, v6
	v_bfe_u32 v8, v7, 16, 1
	v_exp_f32_e32 v6, v6
	v_add3_u32 v7, v7, v8, s36
	ds_write_b16_d16_hi v66, v7 offset:11264
	v_readlane_b32 s98, v24, s101
	v_mul_f32_e32 v2, v6, v2
	v_bfe_u32 v6, v2, 16, 1
	v_add3_u32 v2, v2, v6, s36
	ds_write_b16_d16_hi v66, v2 offset:11392
	v_sub_f32_e32 v6, s98, v24
	v_readlane_b32 s98, v25, s101
	v_mul_f32_e32 v6, 0x3fb8aa3b, v6
	v_exp_f32_e32 v6, v6
	v_lshlrev_b32_e32 v7, 16, v3
	v_and_b32_e32 v3, 0xffff0000, v3
	v_sub_f32_e32 v2, s98, v25
	v_mul_f32_e32 v6, v6, v7
	v_mul_f32_e32 v2, 0x3fb8aa3b, v2
	v_bfe_u32 v7, v6, 16, 1
	v_exp_f32_e32 v2, v2
	v_add3_u32 v6, v6, v7, s36
	ds_write_b16_d16_hi v66, v6 offset:11520
	v_readlane_b32 s98, v18, s101
	v_mul_f32_e32 v2, v2, v3
	v_bfe_u32 v3, v2, 16, 1
	v_add3_u32 v2, v2, v3, s36
	ds_write_b16_d16_hi v66, v2 offset:11648
	v_sub_f32_e32 v3, s98, v18
	v_readlane_b32 s98, v19, s101
	v_mul_f32_e32 v3, 0x3fb8aa3b, v3
	v_exp_f32_e32 v3, v3
	v_lshlrev_b32_e32 v6, 16, v4
	v_and_b32_e32 v4, 0xffff0000, v4
	v_sub_f32_e32 v2, s98, v19
	v_mul_f32_e32 v3, v3, v6
	v_mul_f32_e32 v2, 0x3fb8aa3b, v2
	v_bfe_u32 v6, v3, 16, 1
	v_exp_f32_e32 v2, v2
	v_add3_u32 v3, v3, v6, s36
	ds_write_b16_d16_hi v66, v3 offset:11776
	v_readlane_b32 s98, v20, s101
	v_mul_f32_e32 v2, v2, v4
	v_bfe_u32 v4, v2, 16, 1
	v_add3_u32 v2, v2, v4, s36
	v_readlane_b32 s99, v21, s101
	v_sub_f32_e32 v3, s98, v20
	v_mul_f32_e32 v3, 0x3fb8aa3b, v3
	v_exp_f32_e32 v3, v3
	ds_write_b16_d16_hi v66, v2 offset:11904
	v_sub_f32_e32 v4, s99, v21
	v_lshlrev_b32_e32 v2, 16, v5
	v_mul_f32_e32 v4, 0x3fb8aa3b, v4
	v_mul_f32_e32 v2, v3, v2
	v_exp_f32_e32 v4, v4
	v_bfe_u32 v3, v2, 16, 1
	v_add3_u32 v2, v2, v3, s36
	ds_write_b16_d16_hi v66, v2 offset:12032
	v_and_b32_e32 v2, 0xffff0000, v5
	v_mul_f32_e32 v2, v4, v2
	v_bfe_u32 v3, v2, 16, 1
	v_add3_u32 v2, v2, v3, s36
	ds_write_b16_d16_hi v66, v2 offset:12160
	s_and_saveexec_b64 s[12:13], vcc
	s_cbranch_execz .LBB0_1952
	v_mul_f32_e32 v2, 0x3fb8aa3b, v46
	v_mul_f32_e32 v3, 0x3fb8aa3b, v47
	v_mul_f32_e32 v4, 0x3fb8aa3b, v48
	v_mul_f32_e32 v5, 0x3fb8aa3b, v49
	v_exp_f32_e32 v2, v2
	v_exp_f32_e32 v3, v3
	v_exp_f32_e32 v4, v4
	v_exp_f32_e32 v5, v5
	v_mul_f32_e32 v6, 0x3fb8aa3b, v42
	v_mul_f32_e32 v7, 0x3fb8aa3b, v43
	v_mul_f32_e32 v8, 0x3fb8aa3b, v44
	v_mul_f32_e32 v9, 0x3fb8aa3b, v45
	s_lshl_b64 s[14:15], s[6:7], 7
	v_exp_f32_e32 v6, v6
	v_exp_f32_e32 v7, v7
	v_exp_f32_e32 v8, v8
	v_exp_f32_e32 v9, v9
	v_mul_f32_e32 v10, 0x3fb8aa3b, v38
	v_mul_f32_e32 v11, 0x3fb8aa3b, v39
	v_mul_f32_e32 v12, 0x3fb8aa3b, v40
	v_mul_f32_e32 v13, 0x3fb8aa3b, v41
	s_add_u32 s14, s17, s14
	v_exp_f32_e32 v10, v10
	v_exp_f32_e32 v11, v11
	v_exp_f32_e32 v12, v12
	v_exp_f32_e32 v13, v13
	v_mul_f32_e32 v14, 0x3fb8aa3b, v34
	v_mul_f32_e32 v15, 0x3fb8aa3b, v35
	v_mul_f32_e32 v16, 0x3fb8aa3b, v36
	v_mul_f32_e32 v17, 0x3fb8aa3b, v37
	s_addc_u32 s15, s18, s15
	v_exp_f32_e32 v14, v14
	v_exp_f32_e32 v15, v15
	v_exp_f32_e32 v16, v16
	v_exp_f32_e32 v17, v17
	global_store_dwordx4 v67, v[2:5], s[14:15]
	global_store_dwordx4 v67, v[6:9], s[14:15] offset:16
	global_store_dwordx4 v67, v[10:13], s[14:15] offset:32
	global_store_dwordx4 v67, v[14:17], s[14:15] offset:48
	v_mul_f32_e32 v2, 0x3fb8aa3b, v30
	v_mul_f32_e32 v3, 0x3fb8aa3b, v31
	v_mul_f32_e32 v4, 0x3fb8aa3b, v32
	v_mul_f32_e32 v5, 0x3fb8aa3b, v33
	v_exp_f32_e32 v2, v2
	v_exp_f32_e32 v3, v3
	v_exp_f32_e32 v4, v4
	v_exp_f32_e32 v5, v5
	v_mul_f32_e32 v6, 0x3fb8aa3b, v26
	v_mul_f32_e32 v7, 0x3fb8aa3b, v27
	v_mul_f32_e32 v8, 0x3fb8aa3b, v28
	v_mul_f32_e32 v9, 0x3fb8aa3b, v29
	v_exp_f32_e32 v6, v6
	v_exp_f32_e32 v7, v7
	v_exp_f32_e32 v8, v8
	v_exp_f32_e32 v9, v9
	v_mul_f32_e32 v10, 0x3fb8aa3b, v22
	v_mul_f32_e32 v11, 0x3fb8aa3b, v23
	v_mul_f32_e32 v12, 0x3fb8aa3b, v24
	v_mul_f32_e32 v13, 0x3fb8aa3b, v25
	v_exp_f32_e32 v10, v10
	v_exp_f32_e32 v11, v11
	v_exp_f32_e32 v12, v12
	v_exp_f32_e32 v13, v13
	v_mul_f32_e32 v14, 0x3fb8aa3b, v18
	v_mul_f32_e32 v15, 0x3fb8aa3b, v19
	v_mul_f32_e32 v16, 0x3fb8aa3b, v20
	v_mul_f32_e32 v17, 0x3fb8aa3b, v21
	v_exp_f32_e32 v14, v14
	v_exp_f32_e32 v15, v15
	v_exp_f32_e32 v16, v16
	v_exp_f32_e32 v17, v17
	global_store_dwordx4 v67, v[2:5], s[14:15] offset:64
	global_store_dwordx4 v67, v[6:9], s[14:15] offset:80
	global_store_dwordx4 v67, v[10:13], s[14:15] offset:96
	global_store_dwordx4 v67, v[14:17], s[14:15] offset:112
	s_branch .LBB0_1952
